# all flat memory ops converted to global ops (vmcnt only, no LDS-path dispatch)
# speedup vs baseline: 1.0192x; 1.0192x over previous
.LBB0_62:
	s_waitcnt lgkmcnt(3)
	v_bfe_u32 v23, v16, 16, 1
	v_add3_u32 v16, v16, v23, s39
	v_bfe_u32 v23, v17, 16, 1
	v_lshrrev_b32_e32 v16, 16, v16
	v_add3_u32 v17, v17, v23, s39
	v_and_or_b32 v24, v17, s40, v16
	s_waitcnt lgkmcnt(2)
	v_bfe_u32 v16, v14, 16, 1
	v_add3_u32 v14, v14, v16, s39
	v_bfe_u32 v16, v15, 16, 1
	v_lshrrev_b32_e32 v14, 16, v14
	v_add3_u32 v15, v15, v16, s39
	v_and_or_b32 v25, v15, s40, v14
	s_waitcnt lgkmcnt(1)
	v_bfe_u32 v14, v4, 16, 1
	v_add3_u32 v4, v4, v14, s39
	v_bfe_u32 v14, v5, 16, 1
	v_lshrrev_b32_e32 v4, 16, v4
	v_add3_u32 v5, v5, v14, s39
	v_and_or_b32 v26, v5, s40, v4
	s_waitcnt lgkmcnt(0)
	v_bfe_u32 v4, v2, 16, 1
	v_add3_u32 v2, v2, v4, s39
	v_bfe_u32 v4, v3, 16, 1
	v_lshrrev_b32_e32 v2, 16, v2
	v_add3_u32 v3, v3, v4, s39
	v_and_or_b32 v27, v3, s40, v2
	v_mad_u64_u32 v[2:3], s[4:5], v8, s35, 0
	v_ashrrev_i32_e32 v5, 31, v8
	v_mov_b32_e32 v4, v3
	v_mad_u64_u32 v[4:5], s[4:5], v5, s35, v[4:5]
	v_mov_b32_e32 v3, v4
	s_ashr_i32 s15, s14, 31
	v_lshl_add_u64 v[2:3], v[2:3], 1, s[10:11]
	v_lshl_add_u64 v[2:3], s[14:15], 1, v[2:3]
	v_lshlrev_b32_e32 v8, 1, v10
	v_lshl_add_u64 v[2:3], v[2:3], 0, v[8:9]
	global_store_dwordx4 v[2:3], v[24:27], off
	ds_read2_b32 v[16:17], v20 offset0:32 offset1:161
	ds_read2_b32 v[14:15], v13 offset0:34 offset1:163
	ds_read2_b32 v[4:5], v19 offset0:36 offset1:165
	ds_read2_b32 v[2:3], v22 offset0:38 offset1:167
	v_cndmask_b32_e64 v23, 0, 1, s[16:17]
	v_cmp_ne_u32_e64 s[4:5], 1, v23
	s_andn2_b64 vcc, exec, s[16:17]
	v_add_u32_e32 v23, 32, v18
	s_cbranch_vccnz .LBB0_64
	v_mul_hi_i32 v24, v23, s37
	v_lshrrev_b32_e32 v25, 31, v24
	v_ashrrev_i32_e32 v24, 9, v24
	v_add_u32_e32 v24, v24, v25
	v_mul_i32_i24_e32 v25, 0xc00, v24
	v_sub_u32_e32 v23, v23, v25
	v_lshlrev_b32_e32 v25, 1, v23
	v_and_b32_e32 v25, 0xffffff00, v25
	v_lshl_add_u32 v24, v24, 7, v25
	v_and_or_b32 v23, v23, s38, v24
.LBB0_64:
	s_waitcnt lgkmcnt(0)
	v_bfe_u32 v24, v16, 16, 1
	v_add3_u32 v16, v16, v24, s39
	v_bfe_u32 v24, v17, 16, 1
	v_lshrrev_b32_e32 v16, 16, v16
	v_add3_u32 v17, v17, v24, s39
	v_and_or_b32 v24, v17, s40, v16
	v_bfe_u32 v16, v14, 16, 1
	v_add3_u32 v14, v14, v16, s39
	v_bfe_u32 v16, v15, 16, 1
	v_lshrrev_b32_e32 v14, 16, v14
	v_add3_u32 v15, v15, v16, s39
	v_and_or_b32 v25, v15, s40, v14
	v_bfe_u32 v14, v4, 16, 1
	v_add3_u32 v4, v4, v14, s39
	v_bfe_u32 v14, v5, 16, 1
	v_lshrrev_b32_e32 v4, 16, v4
	v_add3_u32 v5, v5, v14, s39
	v_and_or_b32 v26, v5, s40, v4
	v_bfe_u32 v4, v2, 16, 1
	v_add3_u32 v2, v2, v4, s39
	v_bfe_u32 v4, v3, 16, 1
	v_lshrrev_b32_e32 v2, 16, v2
	v_add3_u32 v3, v3, v4, s39
	v_and_or_b32 v27, v3, s40, v2
	v_mad_u64_u32 v[2:3], s[16:17], v23, s35, 0
	v_ashrrev_i32_e32 v5, 31, v23
	v_mov_b32_e32 v4, v3
	v_mad_u64_u32 v[4:5], s[16:17], v5, s35, v[4:5]
	v_mov_b32_e32 v3, v4
	v_lshl_add_u64 v[2:3], v[2:3], 1, s[10:11]
	v_lshl_add_u64 v[2:3], s[14:15], 1, v[2:3]
	v_lshl_add_u64 v[2:3], v[2:3], 0, v[8:9]
	global_store_dwordx4 v[2:3], v[24:27], off
	ds_read2_b32 v[16:17], v20 offset0:64 offset1:193
	ds_read2_b32 v[14:15], v13 offset0:66 offset1:195
	ds_read2_b32 v[4:5], v19 offset0:68 offset1:197
	ds_read2_b32 v[2:3], v22 offset0:70 offset1:199
	s_and_b64 vcc, exec, s[4:5]
	v_add_u32_e32 v23, 64, v18
	s_cbranch_vccnz .LBB0_66
	v_mul_hi_i32 v24, v23, s37
	v_lshrrev_b32_e32 v25, 31, v24
	v_ashrrev_i32_e32 v24, 9, v24
	v_add_u32_e32 v24, v24, v25
	v_mul_i32_i24_e32 v25, 0xc00, v24
	v_sub_u32_e32 v23, v23, v25
	v_lshlrev_b32_e32 v25, 1, v23
	v_and_b32_e32 v25, 0xffffff00, v25
	v_lshl_add_u32 v24, v24, 7, v25
	v_and_or_b32 v23, v23, s38, v24
.LBB0_66:
	s_waitcnt lgkmcnt(0)
	v_bfe_u32 v24, v16, 16, 1
	v_add3_u32 v16, v16, v24, s39
	v_bfe_u32 v24, v17, 16, 1
	v_lshrrev_b32_e32 v16, 16, v16
	v_add3_u32 v17, v17, v24, s39
	v_and_or_b32 v24, v17, s40, v16
	v_bfe_u32 v16, v14, 16, 1
	v_add3_u32 v14, v14, v16, s39
	v_bfe_u32 v16, v15, 16, 1
	v_lshrrev_b32_e32 v14, 16, v14
	v_add3_u32 v15, v15, v16, s39
	v_and_or_b32 v25, v15, s40, v14
	v_bfe_u32 v14, v4, 16, 1
	v_add3_u32 v4, v4, v14, s39
	v_bfe_u32 v14, v5, 16, 1
	v_lshrrev_b32_e32 v4, 16, v4
	v_add3_u32 v5, v5, v14, s39
	v_and_or_b32 v26, v5, s40, v4
	v_bfe_u32 v4, v2, 16, 1
	v_add3_u32 v2, v2, v4, s39
	v_bfe_u32 v4, v3, 16, 1
	v_lshrrev_b32_e32 v2, 16, v2
	v_add3_u32 v3, v3, v4, s39
	v_and_or_b32 v27, v3, s40, v2
	v_mad_u64_u32 v[2:3], s[16:17], v23, s35, 0
	v_ashrrev_i32_e32 v5, 31, v23
	v_mov_b32_e32 v4, v3
	v_mad_u64_u32 v[4:5], s[16:17], v5, s35, v[4:5]
	v_mov_b32_e32 v3, v4
	v_lshl_add_u64 v[2:3], v[2:3], 1, s[10:11]
	v_lshl_add_u64 v[2:3], s[14:15], 1, v[2:3]
	v_lshl_add_u64 v[2:3], v[2:3], 0, v[8:9]
	global_store_dwordx4 v[2:3], v[24:27], off
	ds_read2_b32 v[16:17], v20 offset0:96 offset1:225
	ds_read2_b32 v[14:15], v13 offset0:98 offset1:227
	ds_read2_b32 v[4:5], v19 offset0:100 offset1:229
	ds_read2_b32 v[2:3], v22 offset0:102 offset1:231
	s_and_b64 vcc, exec, s[4:5]
	v_add_u32_e32 v13, 0x60, v18
	s_cbranch_vccnz .LBB0_68
	v_mul_hi_i32 v18, v13, s37
	v_lshrrev_b32_e32 v19, 31, v18
	v_ashrrev_i32_e32 v18, 9, v18
	v_add_u32_e32 v18, v18, v19
	v_mul_i32_i24_e32 v19, 0xc00, v18
	v_sub_u32_e32 v13, v13, v19
	v_lshlrev_b32_e32 v19, 1, v13
	v_and_b32_e32 v19, 0xffffff00, v19
	v_lshl_add_u32 v18, v18, 7, v19
	v_and_or_b32 v13, v13, s38, v18
.LBB0_68:
	s_waitcnt lgkmcnt(0)
	v_bfe_u32 v18, v17, 16, 1
	v_add3_u32 v17, v17, v18, s39
	v_bfe_u32 v18, v16, 16, 1
	v_add3_u32 v16, v16, v18, s39
	v_lshrrev_b32_e32 v16, 16, v16
	v_and_or_b32 v16, v17, s40, v16
	v_bfe_u32 v17, v15, 16, 1
	v_add3_u32 v15, v15, v17, s39
	v_bfe_u32 v17, v14, 16, 1
	v_add3_u32 v14, v14, v17, s39
	v_lshrrev_b32_e32 v14, 16, v14
	v_and_or_b32 v17, v15, s40, v14
	v_bfe_u32 v14, v5, 16, 1
	v_add3_u32 v5, v5, v14, s39
	v_bfe_u32 v14, v4, 16, 1
	v_add3_u32 v4, v4, v14, s39
	v_lshrrev_b32_e32 v4, 16, v4
	v_and_or_b32 v18, v5, s40, v4
	v_bfe_u32 v4, v3, 16, 1
	v_add3_u32 v3, v3, v4, s39
	v_bfe_u32 v4, v2, 16, 1
	v_add3_u32 v2, v2, v4, s39
	v_lshrrev_b32_e32 v2, 16, v2
	v_and_or_b32 v19, v3, s40, v2
	v_mad_u64_u32 v[2:3], s[4:5], v13, s35, 0
	v_ashrrev_i32_e32 v5, 31, v13
	v_mov_b32_e32 v4, v3
	v_mad_u64_u32 v[4:5], s[4:5], v5, s35, v[4:5]
	v_mov_b32_e32 v3, v4
	v_lshl_add_u64 v[2:3], v[2:3], 1, s[10:11]
	v_lshl_add_u64 v[2:3], s[14:15], 1, v[2:3]
	v_lshl_add_u64 v[2:3], v[2:3], 0, v[8:9]
	s_add_i32 s23, s23, s27
	global_store_dwordx4 v[2:3], v[16:19], off
	s_waitcnt lgkmcnt(0)
	s_barrier
	s_cmp_lt_i32 s41, 21
	s_cbranch_scc1 .LBB0_10

.LBB0_73:
	s_cmpk_gt_i32 s34, 0x3fff
	s_mov_b64 s[24:25], -1
	s_cbranch_scc0 .LBB0_83
	s_cmpk_gt_u32 s34, 0x407f
	s_cbranch_scc0 .LBB0_78
	v_mov_b32_e32 v27, s3
	s_waitcnt lgkmcnt(0)
	ds_read_b64 v[28:29], v27
	s_add_i32 s12, s34, 0xffffbf80
	s_lshl_b64 s[24:25], s[12:13], 12
	v_cmp_lt_i32_e32 vcc, v21, v20
	s_waitcnt lgkmcnt(0)
	v_readfirstlane_b32 s17, v28
	v_readfirstlane_b32 s35, v29
	s_add_u32 s24, s17, s24
	s_addc_u32 s25, s35, s25
	v_lshl_add_u64 v[40:41], s[24:25], 0, v[2:3]
	global_load_dwordx4 v[28:31], v[40:41], off
	s_lshl_b64 s[24:25], s[12:13], 11
	v_lshl_add_u64 v[44:45], v[4:5], 0, s[24:25]
	s_waitcnt vmcnt(0) lgkmcnt(0)
	v_bfe_u32 v27, v28, 16, 1
	v_bfe_u32 v33, v30, 16, 1
	v_bfe_u32 v32, v29, 16, 1
	v_bfe_u32 v34, v31, 16, 1
	v_add3_u32 v27, v28, v27, s15
	v_add3_u32 v33, v30, v33, s15
	v_add3_u32 v32, v29, v32, s15
	v_add3_u32 v34, v31, v34, s15
	v_lshrrev_b32_e32 v27, 16, v27
	v_lshrrev_b32_e32 v33, 16, v33
	v_and_or_b32 v32, v32, s29, v27
	v_and_or_b32 v33, v34, s29, v33
	global_store_dwordx2 v[44:45], v[32:33], off
	global_load_dwordx4 v[32:35], v[40:41], off offset:1024
	v_mul_f32_e32 v29, v29, v29
	v_mul_f32_e32 v31, v31, v31
	v_fmac_f32_e32 v29, v28, v28
	v_fmac_f32_e32 v31, v30, v30
	v_add_f32_e32 v28, v29, v31
	s_waitcnt vmcnt(0) lgkmcnt(0)
	v_bfe_u32 v27, v32, 16, 1
	v_bfe_u32 v37, v34, 16, 1
	v_bfe_u32 v36, v33, 16, 1
	v_bfe_u32 v38, v35, 16, 1
	v_add3_u32 v27, v32, v27, s15
	v_add3_u32 v37, v34, v37, s15
	v_add3_u32 v36, v33, v36, s15
	v_add3_u32 v38, v35, v38, s15
	v_lshrrev_b32_e32 v27, 16, v27
	v_lshrrev_b32_e32 v37, 16, v37
	v_and_or_b32 v36, v36, s29, v27
	v_and_or_b32 v37, v38, s29, v37
	global_store_dwordx2 v[44:45], v[36:37], off offset:512
	global_load_dwordx4 v[36:39], v[40:41], off offset:2048
	v_mul_f32_e32 v29, v33, v33
	v_mul_f32_e32 v30, v35, v35
	v_fmac_f32_e32 v29, v32, v32
	v_fmac_f32_e32 v30, v34, v34
	v_add_f32_e32 v29, v29, v30
	v_add_f32_e32 v28, v28, v29
	s_waitcnt vmcnt(0) lgkmcnt(0)
	v_bfe_u32 v27, v36, 16, 1
	v_bfe_u32 v43, v38, 16, 1
	v_bfe_u32 v42, v37, 16, 1
	v_bfe_u32 v46, v39, 16, 1
	v_add3_u32 v27, v36, v27, s15
	v_add3_u32 v43, v38, v43, s15
	v_add3_u32 v42, v37, v42, s15
	v_add3_u32 v46, v39, v46, s15
	v_lshrrev_b32_e32 v27, 16, v27
	v_lshrrev_b32_e32 v43, 16, v43
	v_and_or_b32 v42, v42, s29, v27
	v_and_or_b32 v43, v46, s29, v43
	global_store_dwordx2 v[44:45], v[42:43], off offset:1024
	global_load_dwordx4 v[40:43], v[40:41], off offset:3072
	v_mul_f32_e32 v29, v37, v37
	v_mul_f32_e32 v30, v39, v39
	v_fmac_f32_e32 v29, v36, v36
	v_fmac_f32_e32 v30, v38, v38
	v_add_f32_e32 v29, v29, v30
	v_add_f32_e32 v28, v28, v29
	v_cndmask_b32_e32 v27, v7, v21, vcc
	v_lshlrev_b32_e32 v27, 2, v27
	v_cmp_lt_i32_e32 vcc, v22, v20
	s_waitcnt vmcnt(0) lgkmcnt(0)
	v_mul_f32_e32 v29, v41, v41
	v_mul_f32_e32 v30, v43, v43
	v_fmac_f32_e32 v29, v40, v40
	v_fmac_f32_e32 v30, v42, v42
	v_add_f32_e32 v29, v29, v30
	v_add_f32_e32 v28, v28, v29
	ds_bpermute_b32 v27, v27, v28
	v_cndmask_b32_e32 v29, v7, v22, vcc
	v_lshlrev_b32_e32 v29, 2, v29
	v_cmp_lt_i32_e32 vcc, v23, v20
	v_bfe_u32 v33, v42, 16, 1
	s_waitcnt lgkmcnt(0)
	v_add_f32_e32 v27, v28, v27
	ds_bpermute_b32 v28, v29, v27
	v_cndmask_b32_e32 v30, v7, v23, vcc
	v_lshlrev_b32_e32 v30, 2, v30
	v_cmp_lt_i32_e32 vcc, v24, v20
	s_waitcnt lgkmcnt(0)
	v_add_f32_e32 v27, v27, v28
	ds_bpermute_b32 v28, v30, v27
	v_cndmask_b32_e32 v29, v7, v24, vcc
	v_lshlrev_b32_e32 v29, 2, v29
	v_cmp_lt_i32_e32 vcc, v25, v20
	s_waitcnt lgkmcnt(0)
	v_add_f32_e32 v27, v27, v28
	ds_bpermute_b32 v28, v29, v27
	v_cndmask_b32_e32 v31, v7, v25, vcc
	v_lshlrev_b32_e32 v30, 2, v31
	v_cmp_lt_i32_e32 vcc, v26, v20
	v_bfe_u32 v31, v40, 16, 1
	s_waitcnt lgkmcnt(0)
	v_add_f32_e32 v27, v27, v28
	ds_bpermute_b32 v28, v30, v27
	v_cndmask_b32_e32 v32, v7, v26, vcc
	v_bfe_u32 v29, v41, 16, 1
	v_add3_u32 v31, v40, v31, s15
	v_add3_u32 v29, v41, v29, s15
	s_waitcnt lgkmcnt(0)
	v_add_f32_e32 v27, v27, v28
	v_lshlrev_b32_e32 v28, 2, v32
	ds_bpermute_b32 v28, v28, v27
	v_add3_u32 v30, v42, v33, s15
	v_lshrrev_b32_e32 v31, 16, v31
	v_lshrrev_b32_e32 v33, 16, v30
	v_and_or_b32 v30, v29, s29, v31
	v_bfe_u32 v29, v43, 16, 1
	v_add3_u32 v29, v43, v29, s15
	v_and_or_b32 v31, v29, s29, v33
	global_store_dwordx2 v[44:45], v[30:31], off offset:1536
	s_and_saveexec_b64 s[24:25], s[8:9]
	s_cbranch_execz .LBB0_77
	s_lshl_b64 s[36:37], s[12:13], 6
	s_waitcnt lgkmcnt(0)
	v_add_f32_e32 v27, v27, v28
	v_lshl_add_u64 v[30:31], v[8:9], 0, s[36:37]
	v_cndmask_b32_e64 v27, 0, v27, s[4:5]
	global_store_dword v[30:31], v27, off

.LBB0_78:
	s_andn2_b64 vcc, exec, s[24:25]
	s_cbranch_vccnz .LBB0_82
	v_mov_b32_e32 v27, s30
	s_waitcnt lgkmcnt(0)
	ds_read_b64 v[28:29], v27
	s_add_i32 s12, s34, 0xffffc000
	s_lshl_b64 s[24:25], s[12:13], 12
	v_cmp_lt_i32_e32 vcc, v21, v20
	s_waitcnt lgkmcnt(0)
	v_readfirstlane_b32 s17, v28
	v_readfirstlane_b32 s35, v29
	s_add_u32 s24, s17, s24
	s_addc_u32 s25, s35, s25
	v_lshl_add_u64 v[40:41], s[24:25], 0, v[2:3]
	global_load_dwordx4 v[28:31], v[40:41], off
	s_mov_b32 s17, s13
	v_lshl_add_u64 v[44:45], v[10:11], 0, s[16:17]
	s_waitcnt vmcnt(0) lgkmcnt(0)
	v_bfe_u32 v27, v28, 16, 1
	v_bfe_u32 v33, v30, 16, 1
	v_bfe_u32 v32, v29, 16, 1
	v_bfe_u32 v34, v31, 16, 1
	v_add3_u32 v27, v28, v27, s15
	v_add3_u32 v33, v30, v33, s15
	v_add3_u32 v32, v29, v32, s15
	v_add3_u32 v34, v31, v34, s15
	v_lshrrev_b32_e32 v27, 16, v27
	v_lshrrev_b32_e32 v33, 16, v33
	v_and_or_b32 v32, v32, s29, v27
	v_and_or_b32 v33, v34, s29, v33
	global_store_dwordx2 v[44:45], v[32:33], off
	global_load_dwordx4 v[32:35], v[40:41], off offset:1024
	v_mul_f32_e32 v29, v29, v29
	v_mul_f32_e32 v31, v31, v31
	v_fmac_f32_e32 v29, v28, v28
	v_fmac_f32_e32 v31, v30, v30
	v_add_f32_e32 v28, v29, v31
	s_waitcnt vmcnt(0) lgkmcnt(0)
	v_bfe_u32 v27, v32, 16, 1
	v_bfe_u32 v37, v34, 16, 1
	v_bfe_u32 v36, v33, 16, 1
	v_bfe_u32 v38, v35, 16, 1
	v_add3_u32 v27, v32, v27, s15
	v_add3_u32 v37, v34, v37, s15
	v_add3_u32 v36, v33, v36, s15
	v_add3_u32 v38, v35, v38, s15
	v_lshrrev_b32_e32 v27, 16, v27
	v_lshrrev_b32_e32 v37, 16, v37
	v_and_or_b32 v36, v36, s29, v27
	v_and_or_b32 v37, v38, s29, v37
	global_store_dwordx2 v[44:45], v[36:37], off offset:512
	global_load_dwordx4 v[36:39], v[40:41], off offset:2048
	v_mul_f32_e32 v29, v33, v33
	v_mul_f32_e32 v30, v35, v35
	v_fmac_f32_e32 v29, v32, v32
	v_fmac_f32_e32 v30, v34, v34
	v_add_f32_e32 v29, v29, v30
	v_add_f32_e32 v28, v28, v29
	s_waitcnt vmcnt(0) lgkmcnt(0)
	v_bfe_u32 v27, v36, 16, 1
	v_bfe_u32 v43, v38, 16, 1
	v_bfe_u32 v42, v37, 16, 1
	v_bfe_u32 v46, v39, 16, 1
	v_add3_u32 v27, v36, v27, s15
	v_add3_u32 v43, v38, v43, s15
	v_add3_u32 v42, v37, v42, s15
	v_add3_u32 v46, v39, v46, s15
	v_lshrrev_b32_e32 v27, 16, v27
	v_lshrrev_b32_e32 v43, 16, v43
	v_and_or_b32 v42, v42, s29, v27
	v_and_or_b32 v43, v46, s29, v43
	global_store_dwordx2 v[44:45], v[42:43], off offset:1024
	global_load_dwordx4 v[40:43], v[40:41], off offset:3072
	v_mul_f32_e32 v29, v37, v37
	v_mul_f32_e32 v30, v39, v39
	v_fmac_f32_e32 v29, v36, v36
	v_fmac_f32_e32 v30, v38, v38
	v_add_f32_e32 v29, v29, v30
	v_add_f32_e32 v28, v28, v29
	v_cndmask_b32_e32 v27, v7, v21, vcc
	v_lshlrev_b32_e32 v27, 2, v27
	v_cmp_lt_i32_e32 vcc, v22, v20
	s_waitcnt vmcnt(0) lgkmcnt(0)
	v_mul_f32_e32 v29, v41, v41
	v_mul_f32_e32 v30, v43, v43
	v_fmac_f32_e32 v29, v40, v40
	v_fmac_f32_e32 v30, v42, v42
	v_add_f32_e32 v29, v29, v30
	v_add_f32_e32 v28, v28, v29
	ds_bpermute_b32 v27, v27, v28
	v_cndmask_b32_e32 v29, v7, v22, vcc
	v_lshlrev_b32_e32 v29, 2, v29
	v_cmp_lt_i32_e32 vcc, v23, v20
	v_bfe_u32 v33, v42, 16, 1
	s_waitcnt lgkmcnt(0)
	v_add_f32_e32 v27, v28, v27
	ds_bpermute_b32 v28, v29, v27
	v_cndmask_b32_e32 v30, v7, v23, vcc
	v_lshlrev_b32_e32 v30, 2, v30
	v_cmp_lt_i32_e32 vcc, v24, v20
	s_waitcnt lgkmcnt(0)
	v_add_f32_e32 v27, v27, v28
	ds_bpermute_b32 v28, v30, v27
	v_cndmask_b32_e32 v29, v7, v24, vcc
	v_lshlrev_b32_e32 v29, 2, v29
	v_cmp_lt_i32_e32 vcc, v25, v20
	s_waitcnt lgkmcnt(0)
	v_add_f32_e32 v27, v27, v28
	ds_bpermute_b32 v28, v29, v27
	v_cndmask_b32_e32 v31, v7, v25, vcc
	v_lshlrev_b32_e32 v30, 2, v31
	v_cmp_lt_i32_e32 vcc, v26, v20
	v_bfe_u32 v31, v40, 16, 1
	s_waitcnt lgkmcnt(0)
	v_add_f32_e32 v27, v27, v28
	ds_bpermute_b32 v28, v30, v27
	v_cndmask_b32_e32 v32, v7, v26, vcc
	v_bfe_u32 v29, v41, 16, 1
	v_add3_u32 v31, v40, v31, s15
	v_add3_u32 v29, v41, v29, s15
	s_waitcnt lgkmcnt(0)
	v_add_f32_e32 v27, v27, v28
	v_lshlrev_b32_e32 v28, 2, v32
	ds_bpermute_b32 v28, v28, v27
	v_add3_u32 v30, v42, v33, s15
	v_lshrrev_b32_e32 v31, 16, v31
	v_lshrrev_b32_e32 v33, 16, v30
	v_and_or_b32 v30, v29, s29, v31
	v_bfe_u32 v29, v43, 16, 1
	v_add3_u32 v29, v43, v29, s15
	v_and_or_b32 v31, v29, s29, v33
	global_store_dwordx2 v[44:45], v[30:31], off offset:1536
	s_and_saveexec_b64 s[24:25], s[6:7]
	s_cbranch_execz .LBB0_81
	s_lshl_b64 s[36:37], s[12:13], 7
	s_waitcnt lgkmcnt(0)
	v_add_f32_e32 v27, v27, v28
	v_lshl_add_u64 v[30:31], v[12:13], 0, s[36:37]
	v_cndmask_b32_e64 v27, 0, v27, s[4:5]
	global_store_dword v[30:31], v27, off

.LBB0_83:
	s_andn2_b64 vcc, exec, s[24:25]
	s_cbranch_vccnz .LBB0_72
	v_mov_b32_e32 v27, s31
	s_waitcnt lgkmcnt(0)
	ds_read_b64 v[28:29], v27
	v_lshl_add_u64 v[32:33], s[10:11], 0, v[16:17]
	v_add_co_u32_e32 v44, vcc, s33, v32
	s_waitcnt lgkmcnt(0)
	v_readfirstlane_b32 s24, v28
	v_readfirstlane_b32 s25, v29
	v_addc_co_u32_e32 v45, vcc, 0, v33, vcc
	s_nop 0
	v_lshl_add_u64 v[40:41], s[24:25], 0, v[18:19]
	global_load_dwordx4 v[28:31], v[40:41], off
	v_cmp_lt_i32_e32 vcc, v21, v20
	s_waitcnt vmcnt(0) lgkmcnt(0)
	v_bfe_u32 v27, v28, 16, 1
	v_bfe_u32 v33, v30, 16, 1
	v_bfe_u32 v32, v29, 16, 1
	v_bfe_u32 v34, v31, 16, 1
	v_add3_u32 v27, v28, v27, s15
	v_add3_u32 v33, v30, v33, s15
	v_add3_u32 v32, v29, v32, s15
	v_add3_u32 v34, v31, v34, s15
	v_lshrrev_b32_e32 v27, 16, v27
	v_lshrrev_b32_e32 v33, 16, v33
	v_and_or_b32 v32, v32, s29, v27
	v_and_or_b32 v33, v34, s29, v33
	global_store_dwordx2 v[44:45], v[32:33], off
	global_load_dwordx4 v[32:35], v[40:41], off offset:1024
	v_mul_f32_e32 v29, v29, v29
	v_mul_f32_e32 v31, v31, v31
	v_fmac_f32_e32 v29, v28, v28
	v_fmac_f32_e32 v31, v30, v30
	v_add_f32_e32 v28, v29, v31
	s_waitcnt vmcnt(0) lgkmcnt(0)
	v_bfe_u32 v27, v32, 16, 1
	v_bfe_u32 v37, v34, 16, 1
	v_bfe_u32 v36, v33, 16, 1
	v_bfe_u32 v38, v35, 16, 1
	v_add3_u32 v27, v32, v27, s15
	v_add3_u32 v37, v34, v37, s15
	v_add3_u32 v36, v33, v36, s15
	v_add3_u32 v38, v35, v38, s15
	v_lshrrev_b32_e32 v27, 16, v27
	v_lshrrev_b32_e32 v37, 16, v37
	v_and_or_b32 v36, v36, s29, v27
	v_and_or_b32 v37, v38, s29, v37
	global_store_dwordx2 v[44:45], v[36:37], off offset:512
	global_load_dwordx4 v[36:39], v[40:41], off offset:2048
	v_mul_f32_e32 v29, v33, v33
	v_mul_f32_e32 v30, v35, v35
	v_fmac_f32_e32 v29, v32, v32
	v_fmac_f32_e32 v30, v34, v34
	v_add_f32_e32 v29, v29, v30
	v_add_f32_e32 v28, v28, v29
	s_waitcnt vmcnt(0) lgkmcnt(0)
	v_bfe_u32 v27, v36, 16, 1
	v_bfe_u32 v43, v38, 16, 1
	v_bfe_u32 v42, v37, 16, 1
	v_bfe_u32 v46, v39, 16, 1
	v_add3_u32 v27, v36, v27, s15
	v_add3_u32 v43, v38, v43, s15
	v_add3_u32 v42, v37, v42, s15
	v_add3_u32 v46, v39, v46, s15
	v_lshrrev_b32_e32 v27, 16, v27
	v_lshrrev_b32_e32 v43, 16, v43
	v_and_or_b32 v42, v42, s29, v27
	v_and_or_b32 v43, v46, s29, v43
	global_store_dwordx2 v[44:45], v[42:43], off offset:1024
	global_load_dwordx4 v[40:43], v[40:41], off offset:3072
	v_mul_f32_e32 v29, v37, v37
	v_mul_f32_e32 v30, v39, v39
	v_fmac_f32_e32 v29, v36, v36
	v_fmac_f32_e32 v30, v38, v38
	v_add_f32_e32 v29, v29, v30
	v_add_f32_e32 v28, v28, v29
	v_cndmask_b32_e32 v27, v7, v21, vcc
	v_lshlrev_b32_e32 v27, 2, v27
	v_cmp_lt_i32_e32 vcc, v22, v20
	s_waitcnt vmcnt(0) lgkmcnt(0)
	v_mul_f32_e32 v29, v41, v41
	v_mul_f32_e32 v30, v43, v43
	v_fmac_f32_e32 v29, v40, v40
	v_fmac_f32_e32 v30, v42, v42
	v_add_f32_e32 v29, v29, v30
	v_add_f32_e32 v28, v28, v29
	ds_bpermute_b32 v27, v27, v28
	v_cndmask_b32_e32 v29, v7, v22, vcc
	v_lshlrev_b32_e32 v29, 2, v29
	v_cmp_lt_i32_e32 vcc, v23, v20
	v_bfe_u32 v33, v42, 16, 1
	s_waitcnt lgkmcnt(0)
	v_add_f32_e32 v27, v28, v27
	ds_bpermute_b32 v28, v29, v27
	v_cndmask_b32_e32 v30, v7, v23, vcc
	v_lshlrev_b32_e32 v30, 2, v30
	v_cmp_lt_i32_e32 vcc, v24, v20
	s_waitcnt lgkmcnt(0)
	v_add_f32_e32 v27, v27, v28
	ds_bpermute_b32 v28, v30, v27
	v_cndmask_b32_e32 v29, v7, v24, vcc
	v_lshlrev_b32_e32 v29, 2, v29
	v_cmp_lt_i32_e32 vcc, v25, v20
	s_waitcnt lgkmcnt(0)
	v_add_f32_e32 v27, v27, v28
	ds_bpermute_b32 v28, v29, v27
	v_cndmask_b32_e32 v31, v7, v25, vcc
	v_lshlrev_b32_e32 v30, 2, v31
	v_cmp_lt_i32_e32 vcc, v26, v20
	v_bfe_u32 v31, v40, 16, 1
	s_waitcnt lgkmcnt(0)
	v_add_f32_e32 v27, v27, v28
	ds_bpermute_b32 v28, v30, v27
	v_cndmask_b32_e32 v32, v7, v26, vcc
	v_bfe_u32 v29, v41, 16, 1
	v_add3_u32 v31, v40, v31, s15
	v_add3_u32 v29, v41, v29, s15
	s_waitcnt lgkmcnt(0)
	v_add_f32_e32 v27, v27, v28
	v_lshlrev_b32_e32 v28, 2, v32
	ds_bpermute_b32 v28, v28, v27
	v_add3_u32 v30, v42, v33, s15
	v_lshrrev_b32_e32 v31, 16, v31
	v_lshrrev_b32_e32 v33, 16, v30
	v_and_or_b32 v30, v29, s29, v31
	v_bfe_u32 v29, v43, 16, 1
	v_add3_u32 v29, v43, v29, s15
	v_and_or_b32 v31, v29, s29, v33
	global_store_dwordx2 v[44:45], v[30:31], off offset:1536
	s_and_saveexec_b64 s[24:25], s[8:9]
	s_cbranch_execz .LBB0_71
	s_waitcnt lgkmcnt(0)
	v_add_f32_e32 v27, v27, v28
	v_lshl_add_u64 v[30:31], s[10:11], 0, v[14:15]
	v_cndmask_b32_e64 v27, 0, v27, s[4:5]
	global_store_dword v[30:31], v27, off
	s_branch .LBB0_71

.LBB0_88:
	s_or_b64 exec, exec, s[12:13]
	v_ashrrev_i32_e32 v12, 13, v10
	v_bfe_u32 v6, v10, 6, 6
	v_ashrrev_i32_e32 v13, 31, v12
	v_lshlrev_b64 v[12:13], 14, v[12:13]
	v_and_or_b32 v6, v3, s16, v6
	v_lshl_add_u64 v[8:9], v[8:9], 0, v[12:13]
	v_lshlrev_b32_e32 v6, 2, v6
	v_lshl_add_u64 v[8:9], v[8:9], 0, v[6:7]
	global_load_dword v6, v[8:9], off
	v_add_u32_e32 v10, s6, v10
	v_cmp_lt_i32_e32 vcc, s18, v10
	s_or_b64 s[2:3], vcc, s[2:3]
	v_add_u32_e32 v3, s7, v3
	s_waitcnt vmcnt(0) lgkmcnt(0)
	v_bfe_u32 v8, v6, 16, 1
	v_add3_u32 v6, v6, v8, s17
	global_store_short_d16_hi v[4:5], v6, off
	v_lshl_add_u64 v[4:5], v[4:5], 0, s[8:9]
	s_andn2_b64 exec, exec, s[2:3]
	s_cbranch_execz .LBB0_93

.LBB0_96:
	s_or_b64 exec, exec, s[22:23]
	v_ashrrev_i32_e32 v3, 31, v2
	v_cvt_f32_f64_e32 v26, v[18:19]
	v_lshlrev_b64 v[18:19], 2, v[2:3]
	v_add_u32_e32 v2, s27, v2
	v_cmp_lt_i32_e64 s[4:5], s29, v2
	v_lshl_add_u64 v[20:21], s[6:7], 0, v[18:19]
	v_cvt_f32_f64_e32 v3, v[22:23]
	v_lshl_add_u64 v[18:19], s[8:9], 0, v[18:19]
	s_or_b64 s[10:11], s[4:5], s[10:11]
	global_store_dword v[20:21], v26, off
	global_store_dword v[18:19], v3, off
	s_andn2_b64 exec, exec, s[10:11]
	s_cbranch_execz .LBB0_108

.LBB0_132:
	global_load_dword v49, v[2:3], off sc1
	global_load_dword v0, v[6:7], off sc1
	global_load_dword v5, v[8:9], off sc1
	global_load_dword v36, v[10:11], off sc1
	global_load_dword v37, v[12:13], off sc1
	global_load_dword v38, v[14:15], off sc1
	global_load_dword v39, v[16:17], off sc1
	global_load_dword v40, v[18:19], off sc1
	global_load_dword v41, v[20:21], off sc1
	global_load_dword v42, v[22:23], off sc1
	global_load_dword v43, v[24:25], off sc1
	global_load_dword v44, v[26:27], off sc1
	global_load_dword v45, v[28:29], off sc1
	global_load_dword v46, v[30:31], off sc1
	global_load_dword v47, v[32:33], off sc1
	global_load_dword v48, v[34:35], off sc1
	s_or_b64 s[10:11], s[10:11], exec
	s_or_b64 s[8:9], s[8:9], exec
	s_waitcnt vmcnt(0) lgkmcnt(0)
	v_add_u32_e32 v50, v0, v49
	v_add_u32_e32 v50, v50, v5
	v_add_u32_e32 v50, v50, v36
	v_add_u32_e32 v50, v50, v37
	v_add_u32_e32 v50, v50, v38
	v_add_u32_e32 v50, v50, v39
	v_add_u32_e32 v50, v50, v40
	v_add_u32_e32 v50, v50, v41
	v_add_u32_e32 v50, v50, v42
	v_add_u32_e32 v50, v50, v43
	v_add_u32_e32 v50, v50, v44
	v_add_u32_e32 v50, v50, v45
	v_add_u32_e32 v50, v50, v46
	v_add_u32_e32 v50, v50, v47
	v_add_u32_e32 v50, v50, v48
	v_cmp_ne_u32_e32 vcc, s22, v50
	s_and_saveexec_b64 s[12:13], vcc
	s_cbranch_execz .LBB0_131
	s_and_b32 s16, s23, 0xff
	s_mov_b64 s[14:15], -1
	s_cmp_eq_u32 s16, 0
	s_mov_b64 s[18:19], -1
	s_mov_b64 s[16:17], -1
	s_sleep 1
	s_cbranch_scc1 .LBB0_135
	s_and_saveexec_b64 s[20:21], s[18:19]
	s_cbranch_execz .LBB0_130
	s_branch .LBB0_138
.LBB0_135:
	v_mov_b64_e32 v[50:51], s[2:3]
	global_load_dword v50, v[50:51], off sc1
	s_mov_b64 s[18:19], 0
	s_waitcnt vmcnt(0) lgkmcnt(0)
	v_cmp_eq_u32_e32 vcc, 0, v50
	s_and_saveexec_b64 s[20:21], vcc
	s_cmp_lt_u32 s23, 0x40001
	s_cselect_b64 s[18:19], -1, 0
	s_xor_b64 s[16:17], exec, -1
	s_and_b64 s[18:19], s[18:19], exec
	s_or_b64 exec, exec, s[20:21]
	s_and_saveexec_b64 s[20:21], s[18:19]
	s_cbranch_execz .LBB0_130

.LBB0_139:
	s_or_b64 exec, exec, s[4:5]
	s_xor_b64 s[4:5], s[6:7], -1
	s_and_saveexec_b64 s[6:7], s[4:5]
	s_xor_b64 s[4:5], exec, s[6:7]
	s_cbranch_execz .LBB0_141
	v_mov_b64_e32 v[2:3], s[2:3]
	global_atomic_add v[2:3], v218, off

.LBB0_142:
	s_lshl_b32 s2, s38, 8
	s_add_u32 s2, s36, s2
	s_addc_u32 s3, s37, 0
	v_mov_b32_e32 v3, s2
	v_add_co_u32_e32 v6, vcc, 0x8d41000, v3
	v_mov_b32_e32 v3, s3
	s_nop 0
	v_addc_co_u32_e32 v7, vcc, 0, v3, vcc
	global_atomic_add v3, v[6:7], v218, off offset:1024 sc0
	v_cvt_f32_u32_e32 v5, v2
	v_sub_u32_e32 v6, 0, v2
	s_add_u32 s25, s2, 0x8d40000
	s_addc_u32 s24, s3, 0
	v_rcp_iflag_f32_e32 v5, v5
	s_waitcnt vmcnt(0) lgkmcnt(0)
	v_add_u32_e32 v8, 1, v3
	v_mul_f32_e32 v5, 0x4f7ffffe, v5
	v_cvt_u32_f32_e32 v5, v5
	v_mul_lo_u32 v6, v6, v5
	v_mul_hi_u32 v6, v5, v6
	v_add_u32_e32 v5, v5, v6
	v_mul_hi_u32 v5, v3, v5
	v_mul_lo_u32 v6, v5, v2
	v_sub_u32_e32 v3, v3, v6
	v_add_u32_e32 v7, 1, v5
	v_cmp_ge_u32_e32 vcc, v3, v2
	v_sub_u32_e32 v6, v3, v2
	s_nop 0
	v_cndmask_b32_e32 v5, v5, v7, vcc
	v_cndmask_b32_e32 v3, v3, v6, vcc
	v_add_u32_e32 v6, 1, v5
	v_cmp_ge_u32_e32 vcc, v3, v2
	s_nop 1
	v_cndmask_b32_e32 v3, v5, v6, vcc
	v_mad_u64_u32 v[6:7], s[2:3], v2, v3, v[2:3]
	v_cmp_ne_u32_e32 vcc, v8, v6
	s_and_saveexec_b64 s[2:3], vcc
	s_xor_b64 s[2:3], exec, s[2:3]
	s_cbranch_execz .LBB0_155
	v_mov_b32_e32 v0, s25
	v_add_co_u32_e32 v6, vcc, 0x2000, v0
	v_mov_b32_e32 v0, s24
	s_nop 0
	v_addc_co_u32_e32 v7, vcc, 0, v0, vcc
	global_load_dword v0, v[6:7], off offset:1024 sc1
	s_add_u32 s6, s25, 0x2400
	s_addc_u32 s7, s24, 0
	s_waitcnt vmcnt(0) lgkmcnt(0)
	v_cmp_eq_u32_e32 vcc, v0, v3
	s_and_saveexec_b64 s[4:5], vcc
	s_cbranch_execz .LBB0_154
	s_add_u32 s8, s36, 0x8d40200
	s_addc_u32 s9, s37, 0
	s_mov_b32 s26, 1
	s_mov_b64 s[10:11], 0
	s_branch .LBB0_146

.LBB0_146:
	s_and_b32 s18, s26, 0xff
	s_mov_b64 s[16:17], -1
	s_cmp_lg_u32 s18, 0
	s_mov_b64 s[18:19], -1
	s_sleep 1
	s_cbranch_scc1 .LBB0_150
	v_mov_b64_e32 v[6:7], s[8:9]
	global_load_dword v0, v[6:7], off sc1
	s_mov_b64 s[18:19], 0
	s_mov_b64 s[20:21], -1
	s_waitcnt vmcnt(0) lgkmcnt(0)
	v_cmp_eq_u32_e32 vcc, 0, v0
	s_and_saveexec_b64 s[22:23], vcc
	s_cmp_lt_u32 s26, 0x40001
	s_cselect_b64 s[18:19], -1, 0
	s_xor_b64 s[20:21], exec, -1
	s_and_b64 s[18:19], s[18:19], exec
	s_or_b64 exec, exec, s[22:23]
.LBB0_150:
	s_andn2_b64 s[14:15], s[14:15], exec
	s_and_b64 s[20:21], s[20:21], exec
	s_or_b64 s[14:15], s[14:15], s[20:21]
	s_and_saveexec_b64 s[20:21], s[18:19]
	s_cbranch_execz .LBB0_145
	v_mov_b64_e32 v[6:7], s[6:7]
	global_load_dword v0, v[6:7], off sc1
	s_add_i32 s26, s26, 1
	s_or_b64 s[14:15], s[14:15], exec
	s_waitcnt vmcnt(0) lgkmcnt(0)
	v_cmp_ne_u32_e32 vcc, v0, v3
	s_orn2_b64 s[16:17], vcc, exec
	s_branch .LBB0_145
.LBB0_152:
	s_or_b64 exec, exec, s[10:11]
	s_xor_b64 s[6:7], s[12:13], -1
	s_and_saveexec_b64 s[10:11], s[6:7]
	s_xor_b64 s[10:11], exec, s[10:11]
	s_cbranch_execz .LBB0_154
	v_mov_b64_e32 v[2:3], s[8:9]
	global_atomic_add v[2:3], v218, off

.LBB0_155:
	s_andn2_saveexec_b64 s[2:3], s[2:3]
	s_cbranch_execz .LBB0_171
	v_mov_b32_e32 v2, s36
	v_add_co_u32_e32 v2, vcc, 0x8d43000, v2
	v_mov_b32_e32 v3, s37
	buffer_wbl2 sc1
	s_waitcnt vmcnt(0)
	v_addc_co_u32_e32 v3, vcc, 0, v3, vcc
	global_atomic_add v2, v[2:3], v218, off offset:1024 sc0
	v_cvt_f32_u32_e32 v3, v0
	v_sub_u32_e32 v5, 0, v0
	s_add_u32 s2, s36, 0x8d43500
	s_addc_u32 s3, s37, 0
	v_rcp_iflag_f32_e32 v3, v3
	s_mov_b64 s[6:7], -1
	v_mul_f32_e32 v3, 0x4f7ffffe, v3
	v_cvt_u32_f32_e32 v3, v3
	v_mul_lo_u32 v5, v5, v3
	v_mul_hi_u32 v5, v3, v5
	v_add_u32_e32 v3, v3, v5
	s_waitcnt vmcnt(0) lgkmcnt(0)
	v_mul_hi_u32 v3, v2, v3
	v_mul_lo_u32 v5, v3, v0
	v_add_u32_e32 v6, 1, v2
	v_sub_u32_e32 v2, v2, v5
	v_add_u32_e32 v7, 1, v3
	v_cmp_ge_u32_e32 vcc, v2, v0
	v_sub_u32_e32 v5, v2, v0
	s_nop 0
	v_cndmask_b32_e32 v3, v3, v7, vcc
	v_cndmask_b32_e32 v2, v2, v5, vcc
	v_add_u32_e32 v5, 1, v3
	v_cmp_ge_u32_e32 vcc, v2, v0
	s_nop 1
	v_cndmask_b32_e32 v5, v3, v5, vcc
	v_mad_u64_u32 v[2:3], s[4:5], v0, v5, v[0:1]
	v_cmp_ne_u32_e32 vcc, v6, v2
	v_mov_b64_e32 v[2:3], s[2:3]
	s_and_saveexec_b64 s[4:5], vcc
	s_cbranch_execz .LBB0_168
	v_mov_b64_e32 v[2:3], s[2:3]
	global_load_dword v0, v[2:3], off sc1
	s_mov_b64 s[10:11], 0
	s_waitcnt vmcnt(0) lgkmcnt(0)
	v_cmp_eq_u32_e32 vcc, v0, v5
	s_and_saveexec_b64 s[8:9], vcc
	s_cbranch_execz .LBB0_167
	s_add_u32 s6, s36, 0x8d40200
	s_addc_u32 s7, s37, 0
	s_mov_b32 s22, 1
	s_branch .LBB0_160

.LBB0_162:
	v_mov_b64_e32 v[2:3], s[6:7]
	global_load_dword v0, v[2:3], off sc1
	s_mov_b64 s[18:19], 0
	s_mov_b64 s[16:17], -1
	s_waitcnt vmcnt(0) lgkmcnt(0)
	v_cmp_eq_u32_e32 vcc, 0, v0
	s_and_saveexec_b64 s[20:21], vcc
	s_cmp_lt_u32 s22, 0x40001
	s_cselect_b64 s[18:19], -1, 0
	s_xor_b64 s[16:17], exec, -1
	s_and_b64 s[18:19], s[18:19], exec
	s_or_b64 exec, exec, s[20:21]
	s_and_saveexec_b64 s[20:21], s[18:19]
	s_cbranch_execz .LBB0_159
.LBB0_165:
	v_mov_b64_e32 v[2:3], s[2:3]
	global_load_dword v0, v[2:3], off sc1
	s_add_i32 s22, s22, 1
	s_or_b64 s[16:17], s[16:17], exec
	s_waitcnt vmcnt(0) lgkmcnt(0)
	v_cmp_ne_u32_e32 vcc, v0, v5
	s_orn2_b64 s[14:15], vcc, exec
	s_branch .LBB0_159

.LBB0_168:
	s_or_b64 exec, exec, s[4:5]
	s_and_saveexec_b64 s[2:3], s[6:7]
	s_cbranch_execz .LBB0_170
	global_atomic_add v[2:3], v218, off
.LBB0_170:
	s_or_b64 exec, exec, s[2:3]
	v_mov_b32_e32 v0, s25
	v_add_co_u32_e32 v2, vcc, 0x2000, v0
	v_mov_b32_e32 v0, s24
	s_nop 0
	v_addc_co_u32_e32 v3, vcc, 0, v0, vcc
	s_waitcnt vmcnt(0) lgkmcnt(0)
	buffer_inv sc1
	global_atomic_add v[2:3], v218, off offset:1024
	s_waitcnt vmcnt(0)

.LBB0_216:
	s_lshl_b32 s23, s34, 8
	s_add_i32 s23, s23, s54
	v_or_b32_e32 v237, s23, v231
	v_lshl_or_b32 v0, v237, 6, v193
	v_or_b32_e32 v240, 1, v237
	v_lshl_add_u64 v[70:71], s[10:11], 0, v[0:1]
	v_lshl_or_b32 v72, v240, 6, v193
	v_mov_b32_e32 v73, v1
	v_lshl_add_u64 v[72:73], s[10:11], 0, v[72:73]
	global_load_dwordx4 v[166:169], v[70:71], off
	global_load_dwordx4 v[170:173], v[72:73], off
	v_or_b32_e32 v239, 2, v237
	v_lshl_or_b32 v70, v239, 6, v193
	v_mov_b32_e32 v71, v1
	v_lshl_add_u64 v[70:71], s[10:11], 0, v[70:71]
	global_load_dwordx4 v[174:177], v[70:71], off
	v_or_b32_e32 v70, 0xc0, v0
	v_mov_b32_e32 v71, v1
	v_lshl_add_u64 v[70:71], s[10:11], 0, v[70:71]
	global_load_dwordx4 v[178:181], v[70:71], off
	v_add_u32_e32 v238, 0x80, v237
	v_mov_b32_e32 v71, v1
	v_lshl_or_b32 v70, v238, 6, v193
	v_lshl_add_u64 v[70:71], s[10:11], 0, v[70:71]
	global_load_dwordx4 v[242:245], v[70:71], off
	v_mov_b32_e32 v73, v1
	v_mov_b32_e32 v75, v1
	v_lshl_or_b32 v192, s30, 7, v235
	v_add_u32_e32 v72, 0x2040, v0
	v_add_u32_e32 v74, 0x2080, v0
	v_add_u32_e32 v0, 0x20c0, v0
	v_lshl_add_u64 v[72:73], s[10:11], 0, v[72:73]
	v_lshl_add_u64 v[70:71], s[10:11], 0, v[74:75]
	v_lshl_add_u64 v[74:75], s[10:11], 0, v[0:1]
	v_lshlrev_b32_e32 v0, 2, v192
	global_load_dwordx4 v[246:249], v[72:73], off
	global_load_dwordx4 v[250:253], v[70:71], off
	global_load_dwordx4 v[194:197], v[74:75], off
	v_lshl_add_u64 v[206:207], s[12:13], 0, v[0:1]
	s_movk_i32 s25, 0x6000
	v_add_co_u32_e32 v202, vcc, s25, v206
	s_mov_b32 s25, 0xc000
	s_nop 0
	v_addc_co_u32_e32 v203, vcc, 0, v207, vcc
	v_add_co_u32_e32 v208, vcc, s25, v206
	s_movk_i32 s25, 0x3000
	s_nop 0
	v_addc_co_u32_e32 v209, vcc, 0, v207, vcc
	v_add_co_u32_e32 v204, vcc, s25, v206
	s_mov_b32 s30, 0x9000
	s_nop 0
	v_addc_co_u32_e32 v205, vcc, 0, v207, vcc
	v_add_co_u32_e32 v210, vcc, s30, v206
	s_mov_b32 s30, 0xf000
	s_nop 0
	v_addc_co_u32_e32 v211, vcc, 0, v207, vcc
	v_add_co_u32_e32 v212, vcc, s30, v206
	v_lshl_add_u64 v[200:201], s[14:15], 0, v[0:1]
	s_nop 0
	v_addc_co_u32_e32 v213, vcc, 0, v207, vcc
	v_add_co_u32_e32 v214, vcc, s25, v200
	global_load_dwordx4 v[74:77], v[206:207], off
	global_load_dwordx4 v[78:81], v[200:201], off
	v_addc_co_u32_e32 v215, vcc, 0, v201, vcc
	global_load_dwordx4 v[98:101], v[202:203], off
	global_load_dwordx4 v[94:97], v[208:209], off
	global_load_dwordx4 v[86:89], v[204:205], off
	global_load_dwordx4 v[82:85], v[210:211], off
	global_load_dwordx4 v[70:73], v[212:213], off
	global_load_dwordx4 v[90:93], v[214:215], off
	s_waitcnt vmcnt(0) lgkmcnt(0)
	v_mov_b32_e32 v216, v167
	v_mov_b32_e32 v217, v168
	v_mov_b32_e32 v167, v169
	v_pk_add_f32 v[166:167], v[216:217], v[166:167]
	v_mov_b32_e32 v168, v171
	v_mov_b32_e32 v169, v172
	v_mov_b32_e32 v171, v173
	v_add_f32_e32 v0, v166, v167
	v_pk_add_f32 v[166:167], v[168:169], v[170:171]
	ds_bpermute_b32 v170, v233, v0
	v_mov_b32_e32 v172, v175
	v_mov_b32_e32 v173, v176
	v_mov_b32_e32 v175, v177
	v_mov_b32_e32 v176, v179
	v_mov_b32_e32 v177, v180
	v_pk_add_f32 v[168:169], v[172:173], v[174:175]
	v_mov_b32_e32 v179, v181
	v_add_f32_e32 v173, v168, v169
	v_pk_add_f32 v[168:169], v[176:177], v[178:179]
	v_add_f32_e32 v171, v166, v167
	s_waitcnt lgkmcnt(0)
	v_add_f32_e32 v166, v0, v170
	v_add_f32_e32 v0, v168, v169
	ds_bpermute_b32 v174, v233, v173
	ds_bpermute_b32 v175, v233, v0
	v_mov_b32_e32 v168, v243
	v_mov_b32_e32 v169, v244
	v_mov_b32_e32 v243, v245
	v_pk_add_f32 v[168:169], v[168:169], v[242:243]
	s_waitcnt lgkmcnt(0)
	v_add_f32_e32 v0, v0, v175
	v_add_f32_e32 v176, v168, v169
	ds_bpermute_b32 v177, v233, v176
	v_add_f32_e32 v169, v173, v174
	v_mov_b32_e32 v174, v247
	v_mov_b32_e32 v175, v248
	v_mov_b32_e32 v247, v249
	v_pk_add_f32 v[174:175], v[174:175], v[246:247]
	s_waitcnt lgkmcnt(0)
	v_add_f32_e32 v243, v176, v177
	v_add_f32_e32 v173, v174, v175
	v_mov_b32_e32 v174, v251
	v_mov_b32_e32 v175, v252
	v_mov_b32_e32 v251, v253
	v_pk_add_f32 v[174:175], v[174:175], v[250:251]
	ds_bpermute_b32 v172, v233, v171
	v_add_f32_e32 v177, v174, v175
	v_mov_b32_e32 v174, v195
	v_mov_b32_e32 v175, v196
	v_mov_b32_e32 v195, v197
	v_pk_add_f32 v[174:175], v[174:175], v[194:195]
	ds_bpermute_b32 v176, v233, v173
	v_add_f32_e32 v174, v174, v175
	ds_bpermute_b32 v178, v233, v177
	ds_bpermute_b32 v175, v233, v174
	s_waitcnt lgkmcnt(3)
	v_add_f32_e32 v170, v171, v172
	s_waitcnt lgkmcnt(2)
	v_add_f32_e32 v241, v173, v176
	ds_bpermute_b32 v167, v234, v166
	s_waitcnt lgkmcnt(2)
	v_add_f32_e32 v247, v177, v178
	s_waitcnt lgkmcnt(1)
	v_add_f32_e32 v245, v174, v175
	ds_bpermute_b32 v171, v234, v170
	ds_bpermute_b32 v244, v234, v243
	ds_bpermute_b32 v242, v234, v241
	ds_bpermute_b32 v248, v234, v247
	ds_bpermute_b32 v246, v234, v245
	ds_bpermute_b32 v172, v234, v169
	ds_bpermute_b32 v168, v234, v0
	s_waitcnt lgkmcnt(1)
	v_add_f32_e32 v169, v169, v172
	s_waitcnt lgkmcnt(0)
	v_add_f32_e32 v0, v0, v168
	v_fmamk_f32 v169, v169, 0x3a800000, v219
	v_fmamk_f32 v0, v0, 0x3a800000, v219
	v_rsq_f32_e32 v172, v169
	v_rsq_f32_e32 v0, v0
	s_lshr_b32 s25, s23, 4
	v_cmp_lt_i32_e32 vcc, 14, v5
	v_pk_mul_f32 v[152:153], v[152:153], v[172:173] op_sel_hi:[1,0]
	v_pk_mul_f32 v[150:151], v[150:151], v[172:173] op_sel_hi:[1,0]
	v_pk_mul_f32 v[24:25], v[24:25], v[172:173] op_sel_hi:[1,0]
	v_pk_mul_f32 v[22:23], v[22:23], v[172:173] op_sel_hi:[1,0]
	v_pk_mul_f32 v[148:149], v[148:149], v[172:173] op_sel_hi:[1,0]
	v_pk_mul_f32 v[146:147], v[146:147], v[172:173] op_sel_hi:[1,0]
	v_pk_mul_f32 v[20:21], v[20:21], v[172:173] op_sel_hi:[1,0]
	v_pk_mul_f32 v[18:19], v[18:19], v[172:173] op_sel_hi:[1,0]
	v_pk_mul_f32 v[164:165], v[164:165], v[0:1] op_sel_hi:[1,0]
	v_pk_mul_f32 v[162:163], v[162:163], v[0:1] op_sel_hi:[1,0]
	v_pk_mul_f32 v[36:37], v[36:37], v[0:1] op_sel_hi:[1,0]
	v_pk_mul_f32 v[34:35], v[34:35], v[0:1] op_sel_hi:[1,0]
	v_pk_mul_f32 v[160:161], v[160:161], v[0:1] op_sel_hi:[1,0]
	v_pk_mul_f32 v[158:159], v[158:159], v[0:1] op_sel_hi:[1,0]
	v_pk_mul_f32 v[32:33], v[32:33], v[0:1] op_sel_hi:[1,0]
	v_pk_mul_f32 v[30:31], v[30:31], v[0:1] op_sel_hi:[1,0]
	s_mov_b64 s[30:31], 0
	s_and_saveexec_b64 s[34:35], vcc
	s_xor_b64 s[34:35], exec, s[34:35]
	v_readlane_b32 s43, v254, 41
	v_readlane_b32 s42, v254, 42
	s_cbranch_execz .LBB0_222
	s_and_b32 s37, s23, 0xfc0
	s_cmpk_eq_i32 s37, 0xfc0
	s_cselect_b64 s[30:31], -1, 0
	s_lshr_b32 s36, s23, 11
	s_cmpk_lg_i32 s37, 0xfc0
	s_mul_i32 s37, s25, 0x1800
	v_add_u32_e32 v168, s37, v192
	v_lshl_add_u32 v0, v168, 2, v225
	v_lshl_add_u64 v[172:173], s[16:17], 0, v[0:1]
	global_store_dwordx4 v[172:173], v[150:153], off
	global_store_dwordx4 v[172:173], v[22:25], off offset:16
	v_add_co_u32_e32 v172, vcc, 0x3000, v172
	s_nop 1
	v_addc_co_u32_e32 v173, vcc, 0, v173, vcc
	global_store_dwordx4 v[172:173], v[146:149], off
	global_store_dwordx4 v[172:173], v[18:21], off offset:16
	s_cbranch_scc1 .LBB0_219
	s_and_b32 s37, s36, 0x1ffffe
	s_mulk_i32 s37, 0x1800
	v_add_lshl_u32 v0, s37, v192, 2
	v_lshl_add_u64 v[172:173], s[18:19], 0, v[0:1]
	global_store_dwordx4 v[172:173], v[150:153], off
	global_store_dwordx4 v[172:173], v[22:25], off offset:16
	v_add_co_u32_e32 v172, vcc, 0x3000, v172
	s_nop 1
	v_addc_co_u32_e32 v173, vcc, 0, v173, vcc
	global_store_dwordx4 v[172:173], v[146:149], off
	global_store_dwordx4 v[172:173], v[18:21], off offset:16
.LBB0_219:
	v_lshl_add_u32 v0, v168, 2, v226
	v_lshl_add_u64 v[168:169], s[16:17], 0, v[0:1]
	global_store_dwordx4 v[168:169], v[162:165], off
	global_store_dwordx4 v[168:169], v[34:37], off offset:16
	v_add_co_u32_e32 v168, vcc, 0x3000, v168
	s_nop 1
	v_addc_co_u32_e32 v169, vcc, 0, v169, vcc
	s_andn2_b64 vcc, exec, s[30:31]
	s_mov_b64 s[30:31], 0
	global_store_dwordx4 v[168:169], v[158:161], off
	global_store_dwordx4 v[168:169], v[30:33], off offset:16
	s_cbranch_vccnz .LBB0_221
	s_mulk_i32 s36, 0x1800
	v_add_u32_e32 v0, s36, v192
	s_mov_b64 s[30:31], -1

.LBB0_222:
	s_or_saveexec_b64 s[34:35], s[34:35]
	v_add_f32_e32 v166, v166, v167
	v_fmamk_f32 v166, v166, 0x3a800000, v219
	v_rsq_f32_e32 v172, v166
	v_mov_b64_e32 v[176:177], v[36:37]
	v_mov_b64_e32 v[180:181], v[164:165]
	v_mov_b64_e32 v[216:217], s[18:19]
	v_pk_mul_f32 v[168:169], v[156:157], v[172:173] op_sel_hi:[1,0]
	v_pk_mul_f32 v[156:157], v[68:69], v[172:173] op_sel_hi:[1,0]
	v_add_f32_e32 v68, v170, v171
	v_fmamk_f32 v68, v68, 0x3a800000, v219
	v_rsq_f32_e32 v170, v68
	v_pk_mul_f32 v[166:167], v[154:155], v[172:173] op_sel_hi:[1,0]
	v_pk_mul_f32 v[60:61], v[60:61], v[172:173] op_sel_hi:[1,0]
	v_pk_mul_f32 v[58:59], v[58:59], v[172:173] op_sel_hi:[1,0]
	v_pk_mul_f32 v[154:155], v[66:67], v[172:173] op_sel_hi:[1,0]
	v_pk_mul_f32 v[56:57], v[56:57], v[172:173] op_sel_hi:[1,0]
	v_pk_mul_f32 v[54:55], v[54:55], v[172:173] op_sel_hi:[1,0]
	v_pk_mul_f32 v[144:145], v[144:145], v[170:171] op_sel_hi:[1,0]
	v_pk_mul_f32 v[142:143], v[142:143], v[170:171] op_sel_hi:[1,0]
	v_pk_mul_f32 v[68:69], v[140:141], v[170:171] op_sel_hi:[1,0]
	v_pk_mul_f32 v[66:67], v[138:139], v[170:171] op_sel_hi:[1,0]
	v_pk_mul_f32 v[140:141], v[136:137], v[170:171] op_sel_hi:[1,0]
	v_pk_mul_f32 v[138:139], v[134:135], v[170:171] op_sel_hi:[1,0]
	v_pk_mul_f32 v[64:65], v[64:65], v[170:171] op_sel_hi:[1,0]
	v_pk_mul_f32 v[62:63], v[62:63], v[170:171] op_sel_hi:[1,0]
	v_mov_b64_e32 v[136:137], v[32:33]
	v_mov_b64_e32 v[172:173], v[160:161]
	v_mov_b64_e32 v[134:135], v[30:31]
	v_mov_b64_e32 v[170:171], v[158:159]
	v_mov_b64_e32 v[174:175], v[34:35]
	v_mov_b64_e32 v[178:179], v[162:163]
	s_xor_b64 exec, exec, s[34:35]
	s_cbranch_execz .LBB0_226
	v_cmp_eq_u32_e32 vcc, 0, v5
	s_mov_b64 s[38:39], s[30:31]
	s_and_saveexec_b64 s[36:37], vcc
	s_cbranch_execz .LBB0_225
	s_mulk_i32 s25, 0x1800
	v_add_u32_e32 v136, s25, v192
	v_lshlrev_b32_e32 v0, 2, v136
	v_lshl_add_u64 v[134:135], s[16:17], 0, v[0:1]
	global_store_dwordx4 v[134:135], v[166:169], off
	global_store_dwordx4 v[134:135], v[58:61], off offset:16
	v_add_co_u32_e32 v134, vcc, 0x3000, v134
	v_add_u32_e32 v0, 0x1800, v136
	s_nop 0
	v_addc_co_u32_e32 v135, vcc, 0, v135, vcc
	s_or_b64 s[38:39], s[30:31], exec
	global_store_dwordx4 v[134:135], v[154:157], off
	global_store_dwordx4 v[134:135], v[54:57], off offset:16

.LBB0_226:
	s_or_b64 exec, exec, s[34:35]
	s_and_saveexec_b64 s[34:35], s[30:31]
	s_cbranch_execz .LBB0_228
	v_lshlrev_b32_e32 v0, 2, v0
	v_lshl_add_u64 v[194:195], v[216:217], 0, v[0:1]
	global_store_dwordx4 v[194:195], v[178:181], off
	global_store_dwordx4 v[194:195], v[174:177], off offset:16
	s_nop 1
	v_add_co_u32_e32 v174, vcc, 0x3000, v194
	s_nop 1
	v_addc_co_u32_e32 v175, vcc, 0, v195, vcc
	global_store_dwordx4 v[174:175], v[170:173], off
	global_store_dwordx4 v[174:175], v[134:137], off offset:16
.LBB0_228:
	s_or_b64 exec, exec, s[34:35]
	v_add_f32_e32 v0, v247, v248
	v_fmamk_f32 v0, v0, 0x3a800000, v219
	v_rsq_f32_e32 v0, v0
	s_add_i32 s25, s23, 0x80
	s_lshr_b32 s23, s25, 4
	v_cmp_lt_i32_e32 vcc, 14, v5
	v_pk_mul_f32 v[132:133], v[132:133], v[0:1] op_sel_hi:[1,0]
	v_pk_mul_f32 v[130:131], v[130:131], v[0:1] op_sel_hi:[1,0]
	v_pk_mul_f32 v[8:9], v[8:9], v[0:1] op_sel_hi:[1,0]
	v_pk_mul_f32 v[6:7], v[6:7], v[0:1] op_sel_hi:[1,0]
	v_pk_mul_f32 v[128:129], v[128:129], v[0:1] op_sel_hi:[1,0]
	v_pk_mul_f32 v[126:127], v[126:127], v[0:1] op_sel_hi:[1,0]
	v_pk_mul_f32 v[12:13], v[12:13], v[0:1] op_sel_hi:[1,0]
	v_pk_mul_f32 v[10:11], v[10:11], v[0:1] op_sel_hi:[1,0]
	v_add_f32_e32 v0, v245, v246
	v_fmamk_f32 v0, v0, 0x3a800000, v219
	v_rsq_f32_e32 v0, v0
	s_mov_b64 s[30:31], 0
	v_pk_mul_f32 v[124:125], v[124:125], v[0:1] op_sel_hi:[1,0]
	v_pk_mul_f32 v[122:123], v[122:123], v[0:1] op_sel_hi:[1,0]
	v_pk_mul_f32 v[16:17], v[16:17], v[0:1] op_sel_hi:[1,0]
	v_pk_mul_f32 v[14:15], v[14:15], v[0:1] op_sel_hi:[1,0]
	v_pk_mul_f32 v[120:121], v[120:121], v[0:1] op_sel_hi:[1,0]
	v_pk_mul_f32 v[118:119], v[118:119], v[0:1] op_sel_hi:[1,0]
	v_pk_mul_f32 v[28:29], v[28:29], v[0:1] op_sel_hi:[1,0]
	v_pk_mul_f32 v[26:27], v[26:27], v[0:1] op_sel_hi:[1,0]
	s_and_saveexec_b64 s[34:35], vcc
	s_xor_b64 s[34:35], exec, s[34:35]
	s_cbranch_execz .LBB0_234
	s_and_b32 s36, s25, 0xfc0
	s_cmpk_eq_i32 s36, 0xfc0
	s_cselect_b64 s[30:31], -1, 0
	s_lshr_b32 s25, s25, 11
	s_cmpk_lg_i32 s36, 0xfc0
	s_mul_i32 s36, s23, 0x1800
	v_add_u32_e32 v134, s36, v192
	v_lshl_add_u32 v0, v134, 2, v225
	v_lshl_add_u64 v[136:137], s[16:17], 0, v[0:1]
	global_store_dwordx4 v[136:137], v[130:133], off
	global_store_dwordx4 v[136:137], v[6:9], off offset:16
	v_add_co_u32_e32 v136, vcc, 0x3000, v136
	s_nop 1
	v_addc_co_u32_e32 v137, vcc, 0, v137, vcc
	global_store_dwordx4 v[136:137], v[126:129], off
	global_store_dwordx4 v[136:137], v[10:13], off offset:16
	s_cbranch_scc1 .LBB0_231
	s_and_b32 s36, s25, 0x1ffffe
	s_mulk_i32 s36, 0x1800
	v_add_lshl_u32 v0, s36, v192, 2
	v_lshl_add_u64 v[136:137], s[18:19], 0, v[0:1]
	global_store_dwordx4 v[136:137], v[130:133], off
	global_store_dwordx4 v[136:137], v[6:9], off offset:16
	v_add_co_u32_e32 v136, vcc, 0x3000, v136
	s_nop 1
	v_addc_co_u32_e32 v137, vcc, 0, v137, vcc
	global_store_dwordx4 v[136:137], v[126:129], off
	global_store_dwordx4 v[136:137], v[10:13], off offset:16
.LBB0_231:
	v_lshl_add_u32 v0, v134, 2, v226
	v_lshl_add_u64 v[134:135], s[16:17], 0, v[0:1]
	global_store_dwordx4 v[134:135], v[122:125], off
	global_store_dwordx4 v[134:135], v[14:17], off offset:16
	v_add_co_u32_e32 v134, vcc, 0x3000, v134
	s_nop 1
	v_addc_co_u32_e32 v135, vcc, 0, v135, vcc
	s_andn2_b64 vcc, exec, s[30:31]
	s_mov_b64 s[30:31], 0
	global_store_dwordx4 v[134:135], v[118:121], off
	global_store_dwordx4 v[134:135], v[26:29], off offset:16
	s_cbranch_vccnz .LBB0_233
	s_mulk_i32 s25, 0x1800
	v_add_u32_e32 v0, s25, v192
	s_mov_b64 s[30:31], -1

.LBB0_234:
	s_or_saveexec_b64 s[34:35], s[34:35]
	v_add_f32_e32 v134, v243, v244
	v_fmamk_f32 v134, v134, 0x3a800000, v219
	v_rsq_f32_e32 v170, v134
	v_mov_b64_e32 v[176:177], v[16:17]
	v_mov_b64_e32 v[180:181], v[124:125]
	v_mov_b64_e32 v[216:217], s[18:19]
	v_pk_mul_f32 v[136:137], v[116:117], v[170:171] op_sel_hi:[1,0]
	v_pk_mul_f32 v[116:117], v[48:49], v[170:171] op_sel_hi:[1,0]
	v_add_f32_e32 v48, v241, v242
	v_fmamk_f32 v48, v48, 0x3a800000, v219
	v_rsq_f32_e32 v172, v48
	v_pk_mul_f32 v[134:135], v[114:115], v[170:171] op_sel_hi:[1,0]
	v_pk_mul_f32 v[40:41], v[40:41], v[170:171] op_sel_hi:[1,0]
	v_pk_mul_f32 v[38:39], v[38:39], v[170:171] op_sel_hi:[1,0]
	v_pk_mul_f32 v[114:115], v[46:47], v[170:171] op_sel_hi:[1,0]
	v_pk_mul_f32 v[48:49], v[44:45], v[170:171] op_sel_hi:[1,0]
	v_pk_mul_f32 v[46:47], v[42:43], v[170:171] op_sel_hi:[1,0]
	v_pk_mul_f32 v[112:113], v[112:113], v[172:173] op_sel_hi:[1,0]
	v_pk_mul_f32 v[110:111], v[110:111], v[172:173] op_sel_hi:[1,0]
	v_pk_mul_f32 v[44:45], v[108:109], v[172:173] op_sel_hi:[1,0]
	v_pk_mul_f32 v[42:43], v[106:107], v[172:173] op_sel_hi:[1,0]
	v_pk_mul_f32 v[104:105], v[104:105], v[172:173] op_sel_hi:[1,0]
	v_pk_mul_f32 v[102:103], v[102:103], v[172:173] op_sel_hi:[1,0]
	v_pk_mul_f32 v[52:53], v[52:53], v[172:173] op_sel_hi:[1,0]
	v_pk_mul_f32 v[50:51], v[50:51], v[172:173] op_sel_hi:[1,0]
	v_mov_b64_e32 v[108:109], v[28:29]
	v_mov_b64_e32 v[172:173], v[120:121]
	v_mov_b64_e32 v[106:107], v[26:27]
	v_mov_b64_e32 v[170:171], v[118:119]
	v_mov_b64_e32 v[174:175], v[14:15]
	v_mov_b64_e32 v[178:179], v[122:123]
	s_xor_b64 exec, exec, s[34:35]
	s_cbranch_execz .LBB0_238
	v_cmp_eq_u32_e32 vcc, 0, v5
	s_mov_b64 s[38:39], s[30:31]
	s_and_saveexec_b64 s[36:37], vcc
	s_cbranch_execz .LBB0_237
	s_mulk_i32 s23, 0x1800
	v_add_u32_e32 v108, s23, v192
	v_lshlrev_b32_e32 v0, 2, v108
	v_lshl_add_u64 v[106:107], s[16:17], 0, v[0:1]
	global_store_dwordx4 v[106:107], v[134:137], off
	global_store_dwordx4 v[106:107], v[38:41], off offset:16
	v_add_co_u32_e32 v106, vcc, 0x3000, v106
	v_add_u32_e32 v0, 0x1800, v108
	s_nop 0
	v_addc_co_u32_e32 v107, vcc, 0, v107, vcc
	s_or_b64 s[38:39], s[30:31], exec
	global_store_dwordx4 v[106:107], v[114:117], off
	global_store_dwordx4 v[106:107], v[46:49], off offset:16

.LBB0_238:
	s_or_b64 exec, exec, s[34:35]
	s_and_saveexec_b64 s[34:35], s[30:31]
	s_cbranch_execz .LBB0_240
	v_lshlrev_b32_e32 v0, 2, v0
	v_lshl_add_u64 v[194:195], v[216:217], 0, v[0:1]
	global_store_dwordx4 v[194:195], v[178:181], off
	global_store_dwordx4 v[194:195], v[174:177], off offset:16
	s_nop 1
	v_add_co_u32_e32 v174, vcc, 0x3000, v194
	s_nop 1
	v_addc_co_u32_e32 v175, vcc, 0, v195, vcc
	global_store_dwordx4 v[174:175], v[170:173], off
	global_store_dwordx4 v[174:175], v[106:109], off offset:16
.LBB0_240:
	s_or_b64 exec, exec, s[34:35]
	v_mov_b32_e32 v170, v1
	v_mov_b32_e32 v171, v1
	v_mov_b32_e32 v106, v1
	v_mov_b32_dpp v170, v150 row_shr:1 row_mask:0xf bank_mask:0xf
	v_mov_b32_e32 v107, v1
	v_mov_b32_dpp v171, v151 row_shr:1 row_mask:0xf bank_mask:0xf
	v_mov_b32_dpp v106, v162 row_shr:1 row_mask:0xf bank_mask:0xf
	v_mov_b32_dpp v107, v163 row_shr:1 row_mask:0xf bank_mask:0xf
	v_pk_fma_f32 v[170:171], v[74:75], v[170:171], v[78:79]
	v_mov_b32_e32 v172, v1
	v_pk_fma_f32 v[170:171], v[98:99], v[106:107], v[170:171]
	v_mov_b32_e32 v173, v1
	v_pk_fma_f32 v[174:175], v[94:95], v[166:167], v[170:171]
	v_mov_b32_e32 v178, v1
	v_mul_f32_e32 v0, v174, v174
	v_fmamk_f32 v0, v0, 0xbdd2d3e2, v220
	v_mul_f32_e32 v0, v174, v0
	v_exp_f32_e32 v0, v0
	v_mov_b32_e32 v179, v1
	v_mov_b32_e32 v108, v1
	v_mov_b32_dpp v172, v152 row_shr:1 row_mask:0xf bank_mask:0xf
	v_add_f32_e32 v0, 1.0, v0
	v_rcp_f32_e32 v0, v0
	v_mov_b32_e32 v109, v1
	v_mov_b32_dpp v173, v153 row_shr:1 row_mask:0xf bank_mask:0xf
	v_mov_b32_e32 v170, v1
	v_mul_f32_e32 v0, v174, v0
	v_mul_f32_e32 v174, v175, v175
	v_fmamk_f32 v174, v174, 0xbdd2d3e2, v220
	v_mul_f32_e32 v174, v175, v174
	v_exp_f32_e32 v174, v174
	v_mov_b32_dpp v178, v146 row_shr:1 row_mask:0xf bank_mask:0xf
	v_mov_b32_e32 v171, v1
	v_mov_b32_dpp v179, v147 row_shr:1 row_mask:0xf bank_mask:0xf
	v_add_f32_e32 v174, 1.0, v174
	v_rcp_f32_e32 v174, v174
	v_mov_b32_dpp v108, v164 row_shr:1 row_mask:0xf bank_mask:0xf
	v_mov_b32_dpp v109, v165 row_shr:1 row_mask:0xf bank_mask:0xf
	v_pk_fma_f32 v[172:173], v[76:77], v[172:173], v[80:81]
	v_mov_b32_dpp v170, v158 row_shr:1 row_mask:0xf bank_mask:0xf
	v_mov_b32_dpp v171, v159 row_shr:1 row_mask:0xf bank_mask:0xf
	v_pk_fma_f32 v[178:179], v[86:87], v[178:179], v[90:91]
	v_pk_fma_f32 v[172:173], v[100:101], v[108:109], v[172:173]
	v_pk_fma_f32 v[178:179], v[82:83], v[170:171], v[178:179]
	v_pk_fma_f32 v[176:177], v[96:97], v[168:169], v[172:173]
	v_pk_fma_f32 v[178:179], v[70:71], v[154:155], v[178:179]
	v_mul_f32_e32 v174, v175, v174
	v_mul_f32_e32 v0, v0, v178
	v_mul_f32_e32 v174, v174, v179
	v_mul_f32_e32 v175, v177, v177
	v_cvt_pk_bf16_f32 v174, v0, v174
	v_mul_f32_e32 v0, v176, v176
	v_fmamk_f32 v175, v175, 0xbdd2d3e2, v220
	v_fmamk_f32 v0, v0, 0xbdd2d3e2, v220
	v_mul_f32_e32 v175, v177, v175
	v_mul_f32_e32 v0, v176, v0
	v_exp_f32_e32 v175, v175
	v_exp_f32_e32 v0, v0
	v_mov_b32_e32 v180, v1
	v_mov_b32_e32 v181, v1
	v_add_f32_e32 v175, 1.0, v175
	v_add_f32_e32 v0, 1.0, v0
	v_rcp_f32_e32 v175, v175
	v_mov_b32_e32 v172, v1
	v_mov_b32_dpp v180, v148 row_shr:1 row_mask:0xf bank_mask:0xf
	v_mov_b32_e32 v173, v1
	v_mov_b32_dpp v181, v149 row_shr:1 row_mask:0xf bank_mask:0xf
	v_rcp_f32_e32 v0, v0
	v_mov_b32_dpp v172, v160 row_shr:1 row_mask:0xf bank_mask:0xf
	v_mov_b32_dpp v173, v161 row_shr:1 row_mask:0xf bank_mask:0xf
	v_pk_fma_f32 v[180:181], v[88:89], v[180:181], v[92:93]
	v_mul_f32_e32 v175, v177, v175
	v_pk_fma_f32 v[180:181], v[84:85], v[172:173], v[180:181]
	v_mul_f32_e32 v0, v176, v0
	v_pk_fma_f32 v[180:181], v[72:73], v[156:157], v[180:181]
	s_nop 0
	v_mul_f32_e32 v175, v175, v181
	v_mul_f32_e32 v0, v0, v180
	v_cvt_pk_bf16_f32 v175, v0, v175
	s_and_saveexec_b64 s[30:31], s[4:5]
	s_cbranch_execz .LBB0_242
	s_movk_i32 s23, 0xc00
	v_mul_lo_u32 v0, v237, s23
	v_add_lshl_u32 v0, v0, v192, 1
	v_lshl_add_u64 v[176:177], s[8:9], 0, v[0:1]
	global_store_dwordx2 v[176:177], v[174:175], off
.LBB0_242:
	s_or_b64 exec, exec, s[30:31]
	v_pk_fma_f32 v[106:107], v[74:75], v[106:107], v[78:79]
	v_pk_fma_f32 v[108:109], v[76:77], v[108:109], v[80:81]
	v_pk_fma_f32 v[106:107], v[98:99], v[166:167], v[106:107]
	v_pk_fma_f32 v[170:171], v[86:87], v[170:171], v[90:91]
	v_pk_fma_f32 v[106:107], v[94:95], v[142:143], v[106:107]
	v_pk_fma_f32 v[108:109], v[100:101], v[168:169], v[108:109]
	v_mul_f32_e32 v0, v106, v106
	v_fmamk_f32 v0, v0, 0xbdd2d3e2, v220
	v_mul_f32_e32 v0, v106, v0
	v_exp_f32_e32 v0, v0
	v_pk_fma_f32 v[170:171], v[82:83], v[154:155], v[170:171]
	v_pk_fma_f32 v[108:109], v[96:97], v[144:145], v[108:109]
	v_pk_fma_f32 v[170:171], v[70:71], v[138:139], v[170:171]
	v_add_f32_e32 v0, 1.0, v0
	v_rcp_f32_e32 v0, v0
	v_pk_fma_f32 v[172:173], v[88:89], v[172:173], v[92:93]
	v_mul_f32_e32 v0, v106, v0
	v_mul_f32_e32 v106, v107, v107
	v_fmamk_f32 v106, v106, 0xbdd2d3e2, v220
	v_mul_f32_e32 v106, v107, v106
	v_exp_f32_e32 v106, v106
	v_mul_f32_e32 v0, v0, v170
	v_pk_fma_f32 v[172:173], v[84:85], v[156:157], v[172:173]
	v_add_f32_e32 v106, 1.0, v106
	v_rcp_f32_e32 v106, v106
	v_pk_fma_f32 v[172:173], v[72:73], v[140:141], v[172:173]
	v_mul_f32_e32 v106, v107, v106
	v_mul_f32_e32 v106, v106, v171
	v_mul_f32_e32 v107, v109, v109
	v_cvt_pk_bf16_f32 v106, v0, v106
	v_mul_f32_e32 v0, v108, v108
	v_fmamk_f32 v107, v107, 0xbdd2d3e2, v220
	v_fmamk_f32 v0, v0, 0xbdd2d3e2, v220
	v_mul_f32_e32 v107, v109, v107
	v_mul_f32_e32 v0, v108, v0
	v_exp_f32_e32 v107, v107
	v_exp_f32_e32 v0, v0
	v_add_f32_e32 v107, 1.0, v107
	v_add_f32_e32 v0, 1.0, v0
	v_rcp_f32_e32 v107, v107
	v_rcp_f32_e32 v0, v0
	v_mul_f32_e32 v107, v109, v107
	v_mul_f32_e32 v0, v108, v0
	v_mul_f32_e32 v107, v107, v173
	v_mul_f32_e32 v0, v0, v172
	v_cvt_pk_bf16_f32 v107, v0, v107
	s_and_saveexec_b64 s[30:31], s[4:5]
	s_cbranch_execz .LBB0_244
	s_movk_i32 s23, 0xc00
	v_mul_lo_u32 v0, v240, s23
	v_add_lshl_u32 v0, v0, v192, 1
	v_lshl_add_u64 v[108:109], s[8:9], 0, v[0:1]
	global_store_dwordx2 v[108:109], v[106:107], off
.LBB0_244:
	s_or_b64 exec, exec, s[30:31]
	v_pk_fma_f32 v[106:107], v[76:77], v[168:169], v[80:81]
	v_pk_fma_f32 v[108:109], v[74:75], v[166:167], v[78:79]
	v_pk_fma_f32 v[106:107], v[100:101], v[144:145], v[106:107]
	v_pk_fma_f32 v[144:145], v[76:77], v[144:145], v[80:81]
	v_pk_fma_f32 v[108:109], v[98:99], v[142:143], v[108:109]
	v_pk_fma_f32 v[106:107], v[96:97], v[152:153], v[106:107]
	v_pk_fma_f32 v[144:145], v[100:101], v[152:153], v[144:145]
	v_pk_fma_f32 v[152:153], v[86:87], v[154:155], v[90:91]
	v_pk_fma_f32 v[108:109], v[94:95], v[150:151], v[108:109]
	v_pk_fma_f32 v[152:153], v[82:83], v[138:139], v[152:153]
	v_pk_fma_f32 v[138:139], v[86:87], v[138:139], v[90:91]
	v_pk_fma_f32 v[152:153], v[70:71], v[146:147], v[152:153]
	v_pk_fma_f32 v[138:139], v[82:83], v[146:147], v[138:139]
	v_mul_f32_e32 v0, v108, v108
	v_mul_f32_e32 v146, v109, v109
	v_fmamk_f32 v0, v0, 0xbdd2d3e2, v220
	v_fmamk_f32 v146, v146, 0xbdd2d3e2, v220
	v_mul_f32_e32 v0, v108, v0
	v_mul_f32_e32 v146, v109, v146
	v_exp_f32_e32 v0, v0
	v_exp_f32_e32 v146, v146
	v_pk_fma_f32 v[142:143], v[74:75], v[142:143], v[78:79]
	s_movk_i32 s23, 0xc00
	v_add_f32_e32 v0, 1.0, v0
	v_add_f32_e32 v146, 1.0, v146
	v_rcp_f32_e32 v0, v0
	v_rcp_f32_e32 v146, v146
	v_pk_fma_f32 v[142:143], v[98:99], v[150:151], v[142:143]
	v_pk_fma_f32 v[150:151], v[88:89], v[156:157], v[92:93]
	v_mul_f32_e32 v0, v108, v0
	v_mul_f32_e32 v108, v109, v146
	v_mul_f32_e32 v109, v106, v106
	v_mul_f32_e32 v146, v107, v107
	v_fmamk_f32 v109, v109, 0xbdd2d3e2, v220
	v_fmamk_f32 v146, v146, 0xbdd2d3e2, v220
	v_mul_f32_e32 v109, v106, v109
	v_mul_f32_e32 v146, v107, v146
	v_exp_f32_e32 v109, v109
	v_exp_f32_e32 v146, v146
	v_pk_fma_f32 v[150:151], v[84:85], v[140:141], v[150:151]
	v_mul_f32_e32 v0, v152, v0
	v_add_f32_e32 v109, 1.0, v109
	v_add_f32_e32 v146, 1.0, v146
	v_rcp_f32_e32 v109, v109
	v_rcp_f32_e32 v146, v146
	v_mul_f32_e32 v108, v153, v108
	v_pk_fma_f32 v[150:151], v[72:73], v[148:149], v[150:151]
	v_cvt_pk_bf16_f32 v108, v0, v108
	v_mul_f32_e32 v0, v106, v109
	v_mul_f32_e32 v106, v107, v146
	v_mul_f32_e32 v106, v151, v106
	v_pk_fma_f32 v[142:143], v[94:95], v[162:163], v[142:143]
	v_mul_f32_e32 v0, v150, v0
	v_cvt_pk_bf16_f32 v109, v0, v106
	v_mad_u64_u32 v[106:107], s[30:31], v239, s23, v[192:193]
	v_mul_f32_e32 v107, v142, v142
	v_fmamk_f32 v107, v107, 0xbdd2d3e2, v220
	v_mul_f32_e32 v107, v142, v107
	v_exp_f32_e32 v107, v107
	v_mul_f32_e32 v146, v143, v143
	v_fmamk_f32 v146, v146, 0xbdd2d3e2, v220
	v_pk_fma_f32 v[140:141], v[88:89], v[140:141], v[92:93]
	v_add_f32_e32 v107, 1.0, v107
	v_rcp_f32_e32 v107, v107
	v_lshlrev_b32_e32 v0, 1, v106
	v_mul_f32_e32 v146, v143, v146
	v_pk_fma_f32 v[144:145], v[96:97], v[164:165], v[144:145]
	v_pk_fma_f32 v[140:141], v[84:85], v[148:149], v[140:141]
	v_pk_fma_f32 v[138:139], v[70:71], v[158:159], v[138:139]
	v_exp_f32_e32 v148, v146
	v_lshl_add_u64 v[146:147], s[8:9], 0, v[0:1]
	v_mul_f32_e32 v107, v142, v107
	global_store_dwordx2 v[146:147], v[108:109], off
	v_mul_f32_e32 v107, v138, v107
	v_mul_f32_e32 v109, v144, v144
	v_mul_f32_e32 v138, v145, v145
	v_fmamk_f32 v109, v109, 0xbdd2d3e2, v220
	v_fmamk_f32 v138, v138, 0xbdd2d3e2, v220
	v_mul_f32_e32 v109, v144, v109
	v_mul_f32_e32 v138, v145, v138
	v_exp_f32_e32 v109, v109
	v_exp_f32_e32 v138, v138
	v_add_f32_e32 v148, 1.0, v148
	v_rcp_f32_e32 v148, v148
	v_add_f32_e32 v109, 1.0, v109
	v_add_f32_e32 v138, 1.0, v138
	v_rcp_f32_e32 v109, v109
	v_rcp_f32_e32 v138, v138
	v_mul_f32_e32 v108, v143, v148
	v_mul_f32_e32 v108, v139, v108
	v_pk_fma_f32 v[140:141], v[72:73], v[160:161], v[140:141]
	v_cvt_pk_bf16_f32 v108, v107, v108
	v_mul_f32_e32 v107, v144, v109
	v_mul_f32_e32 v109, v145, v138
	v_mul_f32_e32 v107, v140, v107
	v_mul_f32_e32 v109, v141, v109
	v_add_u32_e32 v146, 0xc00, v106
	v_cvt_pk_bf16_f32 v109, v107, v109
	v_lshlrev_b32_e32 v106, 1, v146
	v_mov_b32_e32 v107, v1
	v_lshl_add_u64 v[138:139], s[8:9], 0, v[106:107]
	v_mov_b32_e32 v140, v1
	v_mov_b32_e32 v141, v1
	global_store_dwordx2 v[138:139], v[108:109], off
	v_mov_b32_e32 v108, v1
	v_mov_b32_dpp v140, v130 row_shr:1 row_mask:0xf bank_mask:0xf
	v_mov_b32_e32 v109, v1
	v_mov_b32_dpp v141, v131 row_shr:1 row_mask:0xf bank_mask:0xf
	v_mov_b32_dpp v108, v122 row_shr:1 row_mask:0xf bank_mask:0xf
	v_mov_b32_dpp v109, v123 row_shr:1 row_mask:0xf bank_mask:0xf
	v_pk_fma_f32 v[140:141], v[74:75], v[140:141], v[78:79]
	v_mov_b32_e32 v142, v1
	v_pk_fma_f32 v[140:141], v[98:99], v[108:109], v[140:141]
	v_mov_b32_e32 v143, v1
	v_pk_fma_f32 v[144:145], v[94:95], v[134:135], v[140:141]
	v_mov_b32_e32 v138, v1
	v_mul_f32_e32 v107, v144, v144
	v_mul_f32_e32 v147, v145, v145
	v_fmamk_f32 v107, v107, 0xbdd2d3e2, v220
	v_fmamk_f32 v147, v147, 0xbdd2d3e2, v220
	v_mul_f32_e32 v107, v144, v107
	v_mul_f32_e32 v147, v145, v147
	v_exp_f32_e32 v107, v107
	v_exp_f32_e32 v147, v147
	v_mov_b32_dpp v142, v132 row_shr:1 row_mask:0xf bank_mask:0xf
	v_mov_b32_e32 v139, v1
	v_add_f32_e32 v107, 1.0, v107
	v_add_f32_e32 v147, 1.0, v147
	v_mov_b32_dpp v143, v133 row_shr:1 row_mask:0xf bank_mask:0xf
	v_rcp_f32_e32 v107, v107
	v_rcp_f32_e32 v147, v147
	v_mov_b32_dpp v138, v124 row_shr:1 row_mask:0xf bank_mask:0xf
	v_mov_b32_dpp v139, v125 row_shr:1 row_mask:0xf bank_mask:0xf
	v_pk_fma_f32 v[142:143], v[76:77], v[142:143], v[80:81]
	v_mul_f32_e32 v107, v144, v107
	v_pk_fma_f32 v[142:143], v[100:101], v[138:139], v[142:143]
	v_mul_f32_e32 v144, v145, v147
	v_pk_fma_f32 v[148:149], v[96:97], v[136:137], v[142:143]
	v_mov_b32_e32 v150, v1
	v_mul_f32_e32 v145, v148, v148
	v_mul_f32_e32 v147, v149, v149
	v_fmamk_f32 v145, v145, 0xbdd2d3e2, v220
	v_fmamk_f32 v147, v147, 0xbdd2d3e2, v220
	v_mul_f32_e32 v145, v148, v145
	v_mul_f32_e32 v147, v149, v147
	v_exp_f32_e32 v145, v145
	v_exp_f32_e32 v147, v147
	v_mov_b32_e32 v151, v1
	v_mov_b32_e32 v140, v1
	v_mov_b32_dpp v150, v126 row_shr:1 row_mask:0xf bank_mask:0xf
	v_mov_b32_e32 v141, v1
	v_mov_b32_dpp v151, v127 row_shr:1 row_mask:0xf bank_mask:0xf
	v_add_f32_e32 v145, 1.0, v145
	v_add_f32_e32 v147, 1.0, v147
	v_mov_b32_dpp v140, v118 row_shr:1 row_mask:0xf bank_mask:0xf
	v_mov_b32_dpp v141, v119 row_shr:1 row_mask:0xf bank_mask:0xf
	v_mov_b32_e32 v152, v1
	v_mov_b32_e32 v153, v1
	v_pk_fma_f32 v[150:151], v[86:87], v[150:151], v[90:91]
	v_rcp_f32_e32 v145, v145
	v_rcp_f32_e32 v147, v147
	v_mov_b32_e32 v142, v1
	v_mov_b32_dpp v152, v128 row_shr:1 row_mask:0xf bank_mask:0xf
	v_mov_b32_e32 v143, v1
	v_mov_b32_dpp v153, v129 row_shr:1 row_mask:0xf bank_mask:0xf
	v_pk_fma_f32 v[150:151], v[82:83], v[140:141], v[150:151]
	v_mov_b32_dpp v142, v120 row_shr:1 row_mask:0xf bank_mask:0xf
	v_mov_b32_dpp v143, v121 row_shr:1 row_mask:0xf bank_mask:0xf
	v_pk_fma_f32 v[152:153], v[88:89], v[152:153], v[92:93]
	v_pk_fma_f32 v[150:151], v[70:71], v[114:115], v[150:151]
	v_pk_fma_f32 v[152:153], v[84:85], v[142:143], v[152:153]
	v_mul_f32_e32 v107, v107, v150
	v_mul_f32_e32 v144, v144, v151
	v_pk_fma_f32 v[152:153], v[72:73], v[116:117], v[152:153]
	v_cvt_pk_bf16_f32 v144, v107, v144
	v_mul_f32_e32 v107, v148, v145
	v_mul_f32_e32 v145, v149, v147
	v_mul_f32_e32 v145, v145, v153
	v_mul_f32_e32 v107, v107, v152
	v_cvt_pk_bf16_f32 v145, v107, v145
	s_and_saveexec_b64 s[30:31], s[4:5]
	s_cbranch_execz .LBB0_246
	v_mul_lo_u32 v107, v238, s23
	v_add_lshl_u32 v148, v107, v192, 1
	v_mov_b32_e32 v149, v1
	v_lshl_add_u64 v[148:149], s[8:9], 0, v[148:149]
	global_store_dwordx2 v[148:149], v[144:145], off
.LBB0_246:
	s_or_b64 exec, exec, s[30:31]
	v_pk_fma_f32 v[108:109], v[74:75], v[108:109], v[78:79]
	v_pk_fma_f32 v[138:139], v[76:77], v[138:139], v[80:81]
	v_pk_fma_f32 v[108:109], v[98:99], v[134:135], v[108:109]
	v_pk_fma_f32 v[140:141], v[86:87], v[140:141], v[90:91]
	v_pk_fma_f32 v[108:109], v[94:95], v[110:111], v[108:109]
	v_pk_fma_f32 v[138:139], v[100:101], v[136:137], v[138:139]
	v_mul_f32_e32 v107, v108, v108
	v_fmamk_f32 v107, v107, 0xbdd2d3e2, v220
	v_mul_f32_e32 v107, v108, v107
	v_exp_f32_e32 v107, v107
	v_pk_fma_f32 v[140:141], v[82:83], v[114:115], v[140:141]
	v_pk_fma_f32 v[138:139], v[96:97], v[112:113], v[138:139]
	v_pk_fma_f32 v[140:141], v[70:71], v[102:103], v[140:141]
	v_add_f32_e32 v107, 1.0, v107
	v_rcp_f32_e32 v107, v107
	v_pk_fma_f32 v[142:143], v[88:89], v[142:143], v[92:93]
	v_mul_f32_e32 v107, v108, v107
	v_mul_f32_e32 v108, v109, v109
	v_fmamk_f32 v108, v108, 0xbdd2d3e2, v220
	v_mul_f32_e32 v108, v109, v108
	v_exp_f32_e32 v108, v108
	v_mul_f32_e32 v107, v107, v140
	v_pk_fma_f32 v[142:143], v[84:85], v[116:117], v[142:143]
	v_add_f32_e32 v108, 1.0, v108
	v_rcp_f32_e32 v108, v108
	v_pk_fma_f32 v[142:143], v[72:73], v[104:105], v[142:143]
	v_mul_f32_e32 v108, v109, v108
	v_mul_f32_e32 v108, v108, v141
	v_mul_f32_e32 v109, v139, v139
	v_cvt_pk_bf16_f32 v108, v107, v108
	v_mul_f32_e32 v107, v138, v138
	v_fmamk_f32 v109, v109, 0xbdd2d3e2, v220
	v_fmamk_f32 v107, v107, 0xbdd2d3e2, v220
	v_mul_f32_e32 v109, v139, v109
	v_mul_f32_e32 v107, v138, v107
	v_exp_f32_e32 v109, v109
	v_exp_f32_e32 v107, v107
	v_add_f32_e32 v109, 1.0, v109
	v_add_f32_e32 v107, 1.0, v107
	v_rcp_f32_e32 v109, v109
	v_rcp_f32_e32 v107, v107
	v_mul_f32_e32 v109, v139, v109
	v_mul_f32_e32 v107, v138, v107
	v_mul_f32_e32 v109, v109, v143
	v_mul_f32_e32 v107, v107, v142
	v_cvt_pk_bf16_f32 v109, v107, v109
	s_and_saveexec_b64 s[30:31], s[4:5]
	s_cbranch_execz .LBB0_248
	v_mov_b32_e32 v107, 0xbd000
	v_lshl_add_u32 v138, v146, 1, v107
	v_mov_b32_e32 v139, v1
	v_lshl_add_u64 v[138:139], s[8:9], 0, v[138:139]
	global_store_dwordx2 v[138:139], v[108:109], off
.LBB0_248:
	s_or_b64 exec, exec, s[30:31]
	v_pk_fma_f32 v[134:135], v[74:75], v[134:135], v[78:79]
	v_pk_fma_f32 v[108:109], v[76:77], v[136:137], v[80:81]
	v_pk_fma_f32 v[134:135], v[98:99], v[110:111], v[134:135]
	v_pk_fma_f32 v[76:77], v[76:77], v[112:113], v[80:81]
	v_pk_fma_f32 v[134:135], v[94:95], v[130:131], v[134:135]
	v_pk_fma_f32 v[80:81], v[86:87], v[114:115], v[90:91]
	v_pk_fma_f32 v[86:87], v[86:87], v[102:103], v[90:91]
	v_pk_fma_f32 v[80:81], v[82:83], v[102:103], v[80:81]
	v_pk_fma_f32 v[82:83], v[82:83], v[126:127], v[86:87]
	v_mul_f32_e32 v86, v134, v134
	v_fmamk_f32 v86, v86, 0xbdd2d3e2, v220
	v_mul_f32_e32 v86, v134, v86
	v_exp_f32_e32 v86, v86
	v_pk_fma_f32 v[74:75], v[74:75], v[110:111], v[78:79]
	v_pk_fma_f32 v[78:79], v[88:89], v[116:117], v[92:93]
	v_pk_fma_f32 v[88:89], v[88:89], v[104:105], v[92:93]
	v_mul_f32_e32 v87, v135, v135
	v_pk_fma_f32 v[78:79], v[84:85], v[104:105], v[78:79]
	v_pk_fma_f32 v[84:85], v[84:85], v[128:129], v[88:89]
	v_fmamk_f32 v87, v87, 0xbdd2d3e2, v220
	v_pk_fma_f32 v[78:79], v[72:73], v[128:129], v[78:79]
	v_mul_f32_e32 v87, v135, v87
	v_pk_fma_f32 v[72:73], v[72:73], v[120:121], v[84:85]
	v_add_f32_e32 v84, 1.0, v86
	v_exp_f32_e32 v87, v87
	v_rcp_f32_e32 v84, v84
	v_pk_fma_f32 v[108:109], v[100:101], v[112:113], v[108:109]
	v_pk_fma_f32 v[80:81], v[70:71], v[126:127], v[80:81]
	v_pk_fma_f32 v[108:109], v[96:97], v[132:133], v[108:109]
	v_pk_fma_f32 v[70:71], v[70:71], v[118:119], v[82:83]
	v_mul_f32_e32 v83, v108, v108
	v_add_f32_e32 v85, 1.0, v87
	v_mul_f32_e32 v82, v134, v84
	v_fmamk_f32 v83, v83, 0xbdd2d3e2, v220
	v_mul_f32_e32 v84, v109, v109
	v_rcp_f32_e32 v85, v85
	v_mul_f32_e32 v83, v108, v83
	v_fmamk_f32 v84, v84, 0xbdd2d3e2, v220
	v_exp_f32_e32 v83, v83
	v_mul_f32_e32 v84, v109, v84
	v_exp_f32_e32 v84, v84
	v_mul_f32_e32 v80, v80, v82
	v_mul_f32_e32 v82, v135, v85
	v_mul_f32_e32 v81, v81, v82
	v_add_f32_e32 v82, 1.0, v83
	v_rcp_f32_e32 v82, v82
	v_add_f32_e32 v83, 1.0, v84
	v_rcp_f32_e32 v83, v83
	v_cvt_pk_bf16_f32 v80, v80, v81
	v_mul_f32_e32 v81, v108, v82
	v_pk_fma_f32 v[74:75], v[98:99], v[130:131], v[74:75]
	v_mul_f32_e32 v78, v78, v81
	v_mul_f32_e32 v81, v109, v83
	v_pk_fma_f32 v[74:75], v[94:95], v[122:123], v[74:75]
	v_mul_f32_e32 v79, v79, v81
	v_cvt_pk_bf16_f32 v81, v78, v79
	v_mov_b32_e32 v78, 0xbe800
	v_lshl_add_u32 v102, v146, 1, v78
	v_mul_f32_e32 v78, v74, v74
	v_fmamk_f32 v78, v78, 0xbdd2d3e2, v220
	v_mul_f32_e32 v78, v74, v78
	v_exp_f32_e32 v82, v78
	v_mul_f32_e32 v78, v75, v75
	v_fmamk_f32 v78, v78, 0xbdd2d3e2, v220
	v_mul_f32_e32 v78, v75, v78
	v_exp_f32_e32 v83, v78
	v_add_f32_e32 v82, 1.0, v82
	v_rcp_f32_e32 v82, v82
	v_pk_fma_f32 v[76:77], v[100:101], v[132:133], v[76:77]
	v_add_f32_e32 v83, 1.0, v83
	v_rcp_f32_e32 v83, v83
	v_pk_fma_f32 v[76:77], v[96:97], v[124:125], v[76:77]
	v_mov_b32_e32 v103, v1
	v_mul_f32_e32 v74, v74, v82
	v_lshl_add_u64 v[78:79], s[8:9], 0, v[102:103]
	v_mul_f32_e32 v70, v70, v74
	v_mul_f32_e32 v74, v75, v83
	v_mul_f32_e32 v75, v76, v76
	global_store_dwordx2 v[78:79], v[80:81], off
	v_fmamk_f32 v75, v75, 0xbdd2d3e2, v220
	v_mul_f32_e32 v78, v77, v77
	v_mul_f32_e32 v75, v76, v75
	v_fmamk_f32 v78, v78, 0xbdd2d3e2, v220
	v_exp_f32_e32 v75, v75
	v_mul_f32_e32 v78, v77, v78
	v_exp_f32_e32 v78, v78
	v_mul_f32_e32 v71, v71, v74
	v_add_f32_e32 v74, 1.0, v75
	v_rcp_f32_e32 v74, v74
	v_add_f32_e32 v75, 1.0, v78
	v_rcp_f32_e32 v75, v75
	v_cvt_pk_bf16_f32 v70, v70, v71
	v_mul_f32_e32 v71, v76, v74
	v_mul_f32_e32 v71, v72, v71
	v_mul_f32_e32 v72, v77, v75
	v_add_u32_e32 v103, 0x60000, v146
	v_mul_f32_e32 v72, v73, v72
	v_lshlrev_b32_e32 v104, 1, v103
	v_mov_b32_e32 v105, v1
	v_cvt_pk_bf16_f32 v71, v71, v72
	v_lshl_add_u64 v[72:73], s[8:9], 0, v[104:105]
	global_store_dwordx2 v[72:73], v[70:71], off
	global_load_dwordx4 v[78:81], v[206:207], off offset:16
	global_load_dwordx4 v[82:85], v[200:201], off offset:16
	global_load_dwordx4 v[74:77], v[202:203], off offset:16
	s_nop 0
	global_load_dwordx4 v[70:73], v[208:209], off offset:16
	global_load_dwordx4 v[94:97], v[214:215], off offset:16
	global_load_dwordx4 v[98:101], v[204:205], off offset:16
	global_load_dwordx4 v[90:93], v[210:211], off offset:16
	global_load_dwordx4 v[86:89], v[212:213], off offset:16
	v_mov_b32_e32 v112, v1
	v_mov_b32_e32 v113, v1
	v_mov_b32_e32 v108, v1
	v_mov_b32_dpp v112, v22 row_shr:1 row_mask:0xf bank_mask:0xf
	v_mov_b32_e32 v109, v1
	v_mov_b32_dpp v113, v23 row_shr:1 row_mask:0xf bank_mask:0xf
	v_mov_b32_dpp v108, v34 row_shr:1 row_mask:0xf bank_mask:0xf
	v_mov_b32_dpp v109, v35 row_shr:1 row_mask:0xf bank_mask:0xf
	v_mov_b32_e32 v114, v1
	v_mov_b32_e32 v115, v1
	v_mov_b32_e32 v110, v1
	v_mov_b32_dpp v114, v24 row_shr:1 row_mask:0xf bank_mask:0xf
	v_mov_b32_e32 v111, v1
	v_mov_b32_dpp v115, v25 row_shr:1 row_mask:0xf bank_mask:0xf
	v_mov_b32_dpp v110, v36 row_shr:1 row_mask:0xf bank_mask:0xf
	v_mov_b32_dpp v111, v37 row_shr:1 row_mask:0xf bank_mask:0xf
	v_mov_b32_e32 v120, v1
	v_mov_b32_e32 v121, v1
	v_mov_b32_e32 v122, v1
	v_mov_b32_dpp v120, v18 row_shr:1 row_mask:0xf bank_mask:0xf
	v_mov_b32_dpp v121, v19 row_shr:1 row_mask:0xf bank_mask:0xf
	v_mov_b32_e32 v123, v1
	v_mov_b32_dpp v122, v20 row_shr:1 row_mask:0xf bank_mask:0xf
	s_waitcnt vmcnt(0) lgkmcnt(0)
	v_pk_fma_f32 v[112:113], v[78:79], v[112:113], v[82:83]
	s_nop 0
	v_pk_fma_f32 v[112:113], v[74:75], v[108:109], v[112:113]
	v_pk_fma_f32 v[114:115], v[80:81], v[114:115], v[84:85]
	v_pk_fma_f32 v[116:117], v[58:59], v[70:71], v[112:113]
	v_pk_fma_f32 v[114:115], v[76:77], v[110:111], v[114:115]
	v_mul_f32_e32 v105, v116, v116
	v_fmamk_f32 v105, v105, 0xbdd2d3e2, v220
	v_mul_f32_e32 v107, v117, v117
	v_mul_f32_e32 v105, v116, v105
	v_fmamk_f32 v107, v107, 0xbdd2d3e2, v220
	v_exp_f32_e32 v105, v105
	v_mul_f32_e32 v107, v117, v107
	v_exp_f32_e32 v107, v107
	v_pk_fma_f32 v[118:119], v[60:61], v[72:73], v[114:115]
	v_add_f32_e32 v105, 1.0, v105
	v_rcp_f32_e32 v105, v105
	v_add_f32_e32 v107, 1.0, v107
	v_rcp_f32_e32 v107, v107
	v_mov_b32_e32 v112, v1
	v_mul_f32_e32 v105, v116, v105
	v_mul_f32_e32 v116, v118, v118
	v_mul_f32_e32 v107, v117, v107
	v_fmamk_f32 v116, v116, 0xbdd2d3e2, v220
	v_mul_f32_e32 v117, v119, v119
	v_mul_f32_e32 v116, v118, v116
	v_fmamk_f32 v117, v117, 0xbdd2d3e2, v220
	v_exp_f32_e32 v116, v116
	v_mul_f32_e32 v117, v119, v117
	v_mov_b32_e32 v113, v1
	v_exp_f32_e32 v117, v117
	v_mov_b32_dpp v112, v30 row_shr:1 row_mask:0xf bank_mask:0xf
	v_mov_b32_dpp v113, v31 row_shr:1 row_mask:0xf bank_mask:0xf
	v_pk_fma_f32 v[120:121], v[98:99], v[120:121], v[94:95]
	v_add_f32_e32 v116, 1.0, v116
	v_pk_fma_f32 v[120:121], v[90:91], v[112:113], v[120:121]
	v_mov_b32_e32 v114, v1
	v_pk_fma_f32 v[120:121], v[54:55], v[86:87], v[120:121]
	v_mov_b32_e32 v115, v1
	v_mul_f32_e32 v105, v105, v120
	v_rcp_f32_e32 v120, v116
	v_add_f32_e32 v116, 1.0, v117
	v_rcp_f32_e32 v117, v116
	v_mov_b32_dpp v123, v21 row_shr:1 row_mask:0xf bank_mask:0xf
	v_mov_b32_dpp v114, v32 row_shr:1 row_mask:0xf bank_mask:0xf
	v_mov_b32_dpp v115, v33 row_shr:1 row_mask:0xf bank_mask:0xf
	v_pk_fma_f32 v[122:123], v[100:101], v[122:123], v[96:97]
	v_mul_f32_e32 v107, v107, v121
	v_pk_fma_f32 v[122:123], v[92:93], v[114:115], v[122:123]
	v_cvt_pk_bf16_f32 v116, v105, v107
	v_mul_f32_e32 v105, v118, v120
	v_pk_fma_f32 v[122:123], v[56:57], v[88:89], v[122:123]
	v_mul_f32_e32 v107, v119, v117
	v_mul_f32_e32 v105, v105, v122
	v_mul_f32_e32 v107, v107, v123
	v_cvt_pk_bf16_f32 v117, v105, v107
	s_and_saveexec_b64 s[30:31], s[4:5]
	s_cbranch_execz .LBB0_250
	v_mad_u64_u32 v[118:119], s[34:35], v237, s23, v[192:193]
	v_lshl_or_b32 v118, v118, 1, 8
	v_mov_b32_e32 v119, v1
	v_lshl_add_u64 v[118:119], s[8:9], 0, v[118:119]
	global_store_dwordx2 v[118:119], v[116:117], off
.LBB0_250:
	s_or_b64 exec, exec, s[30:31]
	v_pk_fma_f32 v[108:109], v[78:79], v[108:109], v[82:83]
	v_pk_fma_f32 v[112:113], v[98:99], v[112:113], v[94:95]
	v_pk_fma_f32 v[108:109], v[58:59], v[74:75], v[108:109]
	v_pk_fma_f32 v[110:111], v[80:81], v[110:111], v[84:85]
	v_pk_fma_f32 v[108:109], v[66:67], v[70:71], v[108:109]
	v_pk_fma_f32 v[112:113], v[54:55], v[90:91], v[112:113]
	v_mul_f32_e32 v105, v108, v108
	v_mul_f32_e32 v107, v109, v109
	v_fmamk_f32 v105, v105, 0xbdd2d3e2, v220
	v_fmamk_f32 v107, v107, 0xbdd2d3e2, v220
	v_mul_f32_e32 v105, v108, v105
	v_mul_f32_e32 v107, v109, v107
	v_exp_f32_e32 v105, v105
	v_exp_f32_e32 v107, v107
	v_pk_fma_f32 v[110:111], v[60:61], v[76:77], v[110:111]
	v_pk_fma_f32 v[112:113], v[62:63], v[86:87], v[112:113]
	v_add_f32_e32 v105, 1.0, v105
	v_add_f32_e32 v107, 1.0, v107
	v_rcp_f32_e32 v105, v105
	v_rcp_f32_e32 v107, v107
	v_pk_fma_f32 v[110:111], v[68:69], v[72:73], v[110:111]
	v_pk_fma_f32 v[114:115], v[100:101], v[114:115], v[96:97]
	v_mul_f32_e32 v105, v108, v105
	v_mul_f32_e32 v107, v109, v107
	v_mul_f32_e32 v105, v105, v112
	v_mul_f32_e32 v107, v107, v113
	v_cvt_pk_bf16_f32 v108, v105, v107
	v_mul_f32_e32 v105, v110, v110
	v_mul_f32_e32 v107, v111, v111
	v_fmamk_f32 v105, v105, 0xbdd2d3e2, v220
	v_fmamk_f32 v107, v107, 0xbdd2d3e2, v220
	v_mul_f32_e32 v105, v110, v105
	v_mul_f32_e32 v107, v111, v107
	v_exp_f32_e32 v105, v105
	v_exp_f32_e32 v107, v107
	v_pk_fma_f32 v[114:115], v[56:57], v[92:93], v[114:115]
	v_add_f32_e32 v105, 1.0, v105
	v_add_f32_e32 v107, 1.0, v107
	v_rcp_f32_e32 v105, v105
	v_rcp_f32_e32 v107, v107
	v_pk_fma_f32 v[114:115], v[64:65], v[88:89], v[114:115]
	v_mul_f32_e32 v105, v110, v105
	v_mul_f32_e32 v107, v111, v107
	v_mul_f32_e32 v105, v105, v114
	v_mul_f32_e32 v107, v107, v115
	v_cvt_pk_bf16_f32 v109, v105, v107
	s_and_saveexec_b64 s[30:31], s[4:5]
	s_cbranch_execz .LBB0_252
	v_mov_b32_e32 v105, 0xfff3d008
	v_lshl_add_u32 v110, v103, 1, v105
	v_mov_b32_e32 v111, v1
	v_lshl_add_u64 v[110:111], s[8:9], 0, v[110:111]
	global_store_dwordx2 v[110:111], v[108:109], off
.LBB0_252:
	s_or_b64 exec, exec, s[30:31]
	v_pk_fma_f32 v[58:59], v[58:59], v[78:79], v[82:83]
	v_pk_fma_f32 v[60:61], v[60:61], v[80:81], v[84:85]
	v_pk_fma_f32 v[58:59], v[66:67], v[74:75], v[58:59]
	v_pk_fma_f32 v[66:67], v[66:67], v[78:79], v[82:83]
	v_pk_fma_f32 v[60:61], v[68:69], v[76:77], v[60:61]
	v_pk_fma_f32 v[58:59], v[22:23], v[70:71], v[58:59]
	v_pk_fma_f32 v[68:69], v[68:69], v[80:81], v[84:85]
	v_pk_fma_f32 v[22:23], v[22:23], v[74:75], v[66:67]
	v_pk_fma_f32 v[60:61], v[24:25], v[72:73], v[60:61]
	v_pk_fma_f32 v[24:25], v[24:25], v[76:77], v[68:69]
	v_pk_fma_f32 v[22:23], v[34:35], v[70:71], v[22:23]
	v_pk_fma_f32 v[34:35], v[56:57], v[100:101], v[96:97]
	v_pk_fma_f32 v[24:25], v[36:37], v[72:73], v[24:25]
	v_pk_fma_f32 v[36:37], v[54:55], v[98:99], v[94:95]
	v_pk_fma_f32 v[34:35], v[64:65], v[92:93], v[34:35]
	v_pk_fma_f32 v[54:55], v[64:65], v[100:101], v[96:97]
	v_pk_fma_f32 v[34:35], v[20:21], v[88:89], v[34:35]
	v_pk_fma_f32 v[20:21], v[20:21], v[92:93], v[54:55]
	v_mul_f32_e32 v54, v58, v58
	v_mul_f32_e32 v55, v59, v59
	v_fmamk_f32 v54, v54, 0xbdd2d3e2, v220
	v_fmamk_f32 v55, v55, 0xbdd2d3e2, v220
	v_mul_f32_e32 v54, v58, v54
	v_mul_f32_e32 v55, v59, v55
	v_exp_f32_e32 v54, v54
	v_exp_f32_e32 v55, v55
	v_pk_fma_f32 v[20:21], v[32:33], v[88:89], v[20:21]
	v_pk_fma_f32 v[36:37], v[62:63], v[90:91], v[36:37]
	v_add_f32_e32 v32, 1.0, v54
	v_add_f32_e32 v33, 1.0, v55
	v_rcp_f32_e32 v32, v32
	v_rcp_f32_e32 v33, v33
	v_pk_fma_f32 v[56:57], v[62:63], v[98:99], v[94:95]
	v_pk_fma_f32 v[36:37], v[18:19], v[86:87], v[36:37]
	v_pk_fma_f32 v[18:19], v[18:19], v[90:91], v[56:57]
	v_or_b32_e32 v0, 8, v0
	v_pk_fma_f32 v[18:19], v[30:31], v[86:87], v[18:19]
	v_mul_f32_e32 v30, v58, v32
	v_mul_f32_e32 v31, v59, v33
	v_mul_f32_e32 v32, v60, v60
	v_mul_f32_e32 v33, v61, v61
	v_fmamk_f32 v32, v32, 0xbdd2d3e2, v220
	v_fmamk_f32 v33, v33, 0xbdd2d3e2, v220
	v_mul_f32_e32 v32, v60, v32
	v_mul_f32_e32 v33, v61, v33
	v_exp_f32_e32 v32, v32
	v_exp_f32_e32 v33, v33
	v_mul_f32_e32 v30, v36, v30
	v_mul_f32_e32 v31, v37, v31
	v_add_f32_e32 v32, 1.0, v32
	v_add_f32_e32 v33, 1.0, v33
	v_rcp_f32_e32 v32, v32
	v_rcp_f32_e32 v33, v33
	v_cvt_pk_bf16_f32 v30, v30, v31
	v_mov_b32_e32 v36, v1
	v_mul_f32_e32 v31, v60, v32
	v_mul_f32_e32 v32, v61, v33
	v_mul_f32_e32 v31, v34, v31
	v_mul_f32_e32 v32, v35, v32
	v_cvt_pk_bf16_f32 v31, v31, v32
	v_mul_f32_e32 v32, v22, v22
	v_fmamk_f32 v32, v32, 0xbdd2d3e2, v220
	v_mul_f32_e32 v32, v22, v32
	v_exp_f32_e32 v34, v32
	v_mul_f32_e32 v32, v23, v23
	v_fmamk_f32 v32, v32, 0xbdd2d3e2, v220
	v_mul_f32_e32 v32, v23, v32
	v_exp_f32_e32 v35, v32
	v_lshl_add_u64 v[32:33], s[8:9], 0, v[0:1]
	v_add_f32_e32 v0, 1.0, v34
	v_rcp_f32_e32 v0, v0
	v_add_f32_e32 v34, 1.0, v35
	v_rcp_f32_e32 v34, v34
	global_store_dwordx2 v[32:33], v[30:31], off
	v_mul_f32_e32 v0, v22, v0
	v_mul_f32_e32 v0, v18, v0
	v_mul_f32_e32 v18, v23, v34
	v_mul_f32_e32 v22, v24, v24
	v_mul_f32_e32 v23, v25, v25
	v_fmamk_f32 v22, v22, 0xbdd2d3e2, v220
	v_fmamk_f32 v23, v23, 0xbdd2d3e2, v220
	v_mul_f32_e32 v22, v24, v22
	v_mul_f32_e32 v23, v25, v23
	v_exp_f32_e32 v22, v22
	v_exp_f32_e32 v23, v23
	v_mul_f32_e32 v18, v19, v18
	v_cvt_pk_bf16_f32 v18, v0, v18
	v_add_f32_e32 v19, 1.0, v22
	v_add_f32_e32 v22, 1.0, v23
	v_rcp_f32_e32 v19, v19
	v_rcp_f32_e32 v22, v22
	v_mov_b32_e32 v23, v1
	v_mov_b32_e32 v34, v1
	v_mul_f32_e32 v0, v24, v19
	v_mul_f32_e32 v19, v25, v22
	v_mul_f32_e32 v0, v20, v0
	v_mul_f32_e32 v19, v21, v19
	v_cvt_pk_bf16_f32 v19, v0, v19
	v_or_b32_e32 v0, 8, v106
	v_lshl_add_u64 v[20:21], s[8:9], 0, v[0:1]
	v_mov_b32_e32 v22, v1
	global_store_dwordx2 v[20:21], v[18:19], off
	v_mov_b32_e32 v18, v1
	v_mov_b32_dpp v22, v6 row_shr:1 row_mask:0xf bank_mask:0xf
	v_mov_b32_e32 v19, v1
	v_mov_b32_dpp v23, v7 row_shr:1 row_mask:0xf bank_mask:0xf
	v_mov_b32_dpp v18, v14 row_shr:1 row_mask:0xf bank_mask:0xf
	v_mov_b32_dpp v19, v15 row_shr:1 row_mask:0xf bank_mask:0xf
	v_pk_fma_f32 v[22:23], v[78:79], v[22:23], v[82:83]
	v_mov_b32_e32 v24, v1
	v_pk_fma_f32 v[22:23], v[74:75], v[18:19], v[22:23]
	v_mov_b32_e32 v25, v1
	v_pk_fma_f32 v[30:31], v[38:39], v[70:71], v[22:23]
	v_mov_b32_e32 v35, v1
	v_mul_f32_e32 v0, v30, v30
	v_fmamk_f32 v0, v0, 0xbdd2d3e2, v220
	v_mul_f32_e32 v54, v31, v31
	v_mul_f32_e32 v0, v30, v0
	v_fmamk_f32 v54, v54, 0xbdd2d3e2, v220
	v_exp_f32_e32 v0, v0
	v_mul_f32_e32 v54, v31, v54
	v_exp_f32_e32 v54, v54
	v_mov_b32_e32 v20, v1
	v_add_f32_e32 v0, 1.0, v0
	v_rcp_f32_e32 v0, v0
	v_add_f32_e32 v54, 1.0, v54
	v_mov_b32_dpp v24, v8 row_shr:1 row_mask:0xf bank_mask:0xf
	v_mov_b32_e32 v21, v1
	v_mov_b32_dpp v25, v9 row_shr:1 row_mask:0xf bank_mask:0xf
	v_mov_b32_e32 v22, v1
	v_mov_b32_dpp v34, v10 row_shr:1 row_mask:0xf bank_mask:0xf
	v_mov_b32_e32 v23, v1
	v_mov_b32_dpp v35, v11 row_shr:1 row_mask:0xf bank_mask:0xf
	v_rcp_f32_e32 v54, v54
	v_mov_b32_dpp v20, v16 row_shr:1 row_mask:0xf bank_mask:0xf
	v_mov_b32_dpp v21, v17 row_shr:1 row_mask:0xf bank_mask:0xf
	v_pk_fma_f32 v[24:25], v[80:81], v[24:25], v[84:85]
	v_mov_b32_dpp v22, v26 row_shr:1 row_mask:0xf bank_mask:0xf
	v_mov_b32_dpp v23, v27 row_shr:1 row_mask:0xf bank_mask:0xf
	v_pk_fma_f32 v[34:35], v[98:99], v[34:35], v[94:95]
	v_pk_fma_f32 v[24:25], v[76:77], v[20:21], v[24:25]
	v_pk_fma_f32 v[34:35], v[90:91], v[22:23], v[34:35]
	v_pk_fma_f32 v[32:33], v[40:41], v[72:73], v[24:25]
	v_pk_fma_f32 v[34:35], v[46:47], v[86:87], v[34:35]
	v_mul_f32_e32 v0, v30, v0
	v_mul_f32_e32 v0, v0, v34
	v_mul_f32_e32 v30, v31, v54
	v_mul_f32_e32 v31, v32, v32
	v_mul_f32_e32 v34, v33, v33
	v_fmamk_f32 v31, v31, 0xbdd2d3e2, v220
	v_fmamk_f32 v34, v34, 0xbdd2d3e2, v220
	v_mul_f32_e32 v31, v32, v31
	v_mul_f32_e32 v34, v33, v34
	v_exp_f32_e32 v31, v31
	v_exp_f32_e32 v34, v34
	v_mov_b32_e32 v37, v1
	v_mov_b32_e32 v24, v1
	v_add_f32_e32 v31, 1.0, v31
	v_add_f32_e32 v34, 1.0, v34
	v_rcp_f32_e32 v31, v31
	v_rcp_f32_e32 v34, v34
	v_mov_b32_dpp v36, v12 row_shr:1 row_mask:0xf bank_mask:0xf
	v_mov_b32_e32 v25, v1
	v_mov_b32_dpp v37, v13 row_shr:1 row_mask:0xf bank_mask:0xf
	v_mov_b32_dpp v24, v28 row_shr:1 row_mask:0xf bank_mask:0xf
	v_mov_b32_dpp v25, v29 row_shr:1 row_mask:0xf bank_mask:0xf
	v_pk_fma_f32 v[36:37], v[100:101], v[36:37], v[96:97]
	v_mul_f32_e32 v30, v30, v35
	v_pk_fma_f32 v[36:37], v[92:93], v[24:25], v[36:37]
	v_cvt_pk_bf16_f32 v30, v0, v30
	v_mul_f32_e32 v0, v32, v31
	v_pk_fma_f32 v[36:37], v[48:49], v[88:89], v[36:37]
	v_mul_f32_e32 v31, v33, v34
	v_mul_f32_e32 v31, v31, v37
	v_mul_f32_e32 v0, v0, v36
	v_cvt_pk_bf16_f32 v31, v0, v31
	s_and_saveexec_b64 s[30:31], s[4:5]
	s_cbranch_execz .LBB0_254
	v_mov_b32_e32 v0, 0xffffb808
	v_lshl_add_u32 v0, v103, 1, v0
	v_lshl_add_u64 v[32:33], s[8:9], 0, v[0:1]
	global_store_dwordx2 v[32:33], v[30:31], off
.LBB0_254:
	s_or_b64 exec, exec, s[30:31]
	v_pk_fma_f32 v[18:19], v[78:79], v[18:19], v[82:83]
	v_pk_fma_f32 v[20:21], v[80:81], v[20:21], v[84:85]
	v_pk_fma_f32 v[18:19], v[38:39], v[74:75], v[18:19]
	v_pk_fma_f32 v[22:23], v[98:99], v[22:23], v[94:95]
	v_pk_fma_f32 v[18:19], v[42:43], v[70:71], v[18:19]
	v_pk_fma_f32 v[20:21], v[40:41], v[76:77], v[20:21]
	v_mul_f32_e32 v0, v18, v18
	v_fmamk_f32 v0, v0, 0xbdd2d3e2, v220
	v_mul_f32_e32 v0, v18, v0
	v_exp_f32_e32 v0, v0
	v_pk_fma_f32 v[22:23], v[46:47], v[90:91], v[22:23]
	v_pk_fma_f32 v[20:21], v[44:45], v[72:73], v[20:21]
	v_pk_fma_f32 v[22:23], v[50:51], v[86:87], v[22:23]
	v_add_f32_e32 v0, 1.0, v0
	v_rcp_f32_e32 v0, v0
	v_pk_fma_f32 v[24:25], v[100:101], v[24:25], v[96:97]
	v_mul_f32_e32 v0, v18, v0
	v_mul_f32_e32 v18, v19, v19
	v_fmamk_f32 v18, v18, 0xbdd2d3e2, v220
	v_mul_f32_e32 v18, v19, v18
	v_exp_f32_e32 v18, v18
	v_mul_f32_e32 v0, v0, v22
	v_pk_fma_f32 v[24:25], v[48:49], v[92:93], v[24:25]
	v_add_f32_e32 v18, 1.0, v18
	v_rcp_f32_e32 v18, v18
	v_pk_fma_f32 v[24:25], v[52:53], v[88:89], v[24:25]
	v_mul_f32_e32 v18, v19, v18
	v_mul_f32_e32 v18, v18, v23
	v_mul_f32_e32 v19, v21, v21
	v_cvt_pk_bf16_f32 v18, v0, v18
	v_mul_f32_e32 v0, v20, v20
	v_fmamk_f32 v19, v19, 0xbdd2d3e2, v220
	v_fmamk_f32 v0, v0, 0xbdd2d3e2, v220
	v_mul_f32_e32 v19, v21, v19
	v_mul_f32_e32 v0, v20, v0
	v_exp_f32_e32 v19, v19
	v_exp_f32_e32 v0, v0
	v_add_f32_e32 v19, 1.0, v19
	v_add_f32_e32 v0, 1.0, v0
	v_rcp_f32_e32 v19, v19
	v_rcp_f32_e32 v0, v0
	v_mul_f32_e32 v19, v21, v19
	v_mul_f32_e32 v0, v20, v0
	v_mul_f32_e32 v19, v19, v25
	v_mul_f32_e32 v0, v0, v24
	v_cvt_pk_bf16_f32 v19, v0, v19
	s_and_saveexec_b64 s[30:31], s[4:5]
	s_cbranch_execz .LBB0_256
	v_mov_b32_e32 v0, 0xffffd008
	v_lshl_add_u32 v0, v103, 1, v0
	v_lshl_add_u64 v[20:21], s[8:9], 0, v[0:1]
	global_store_dwordx2 v[20:21], v[18:19], off
.LBB0_256:
	s_or_b64 exec, exec, s[30:31]
	v_pk_fma_f32 v[24:25], v[46:47], v[98:99], v[94:95]
	v_pk_fma_f32 v[20:21], v[50:51], v[98:99], v[94:95]
	v_pk_fma_f32 v[24:25], v[50:51], v[90:91], v[24:25]
	v_pk_fma_f32 v[20:21], v[10:11], v[90:91], v[20:21]
	v_pk_fma_f32 v[10:11], v[10:11], v[86:87], v[24:25]
	v_pk_fma_f32 v[24:25], v[42:43], v[78:79], v[82:83]
	v_pk_fma_f32 v[22:23], v[48:49], v[100:101], v[96:97]
	v_pk_fma_f32 v[24:25], v[6:7], v[74:75], v[24:25]
	v_pk_fma_f32 v[18:19], v[52:53], v[100:101], v[96:97]
	v_pk_fma_f32 v[14:15], v[14:15], v[70:71], v[24:25]
	v_pk_fma_f32 v[24:25], v[38:39], v[78:79], v[82:83]
	v_pk_fma_f32 v[22:23], v[52:53], v[92:93], v[22:23]
	v_pk_fma_f32 v[24:25], v[42:43], v[74:75], v[24:25]
	v_pk_fma_f32 v[18:19], v[12:13], v[92:93], v[18:19]
	v_pk_fma_f32 v[6:7], v[6:7], v[70:71], v[24:25]
	v_pk_fma_f32 v[12:13], v[12:13], v[88:89], v[22:23]
	v_mul_f32_e32 v0, v6, v6
	v_mul_f32_e32 v24, v7, v7
	v_fmamk_f32 v0, v0, 0xbdd2d3e2, v220
	v_fmamk_f32 v24, v24, 0xbdd2d3e2, v220
	v_mul_f32_e32 v0, v6, v0
	v_mul_f32_e32 v24, v7, v24
	v_exp_f32_e32 v0, v0
	v_exp_f32_e32 v24, v24
	v_pk_fma_f32 v[22:23], v[44:45], v[80:81], v[84:85]
	v_pk_fma_f32 v[20:21], v[26:27], v[86:87], v[20:21]
	v_add_f32_e32 v0, 1.0, v0
	v_add_f32_e32 v24, 1.0, v24
	v_pk_fma_f32 v[22:23], v[8:9], v[76:77], v[22:23]
	v_rcp_f32_e32 v0, v0
	v_rcp_f32_e32 v24, v24
	v_pk_fma_f32 v[16:17], v[16:17], v[72:73], v[22:23]
	v_pk_fma_f32 v[22:23], v[40:41], v[80:81], v[84:85]
	v_mul_f32_e32 v0, v6, v0
	v_pk_fma_f32 v[22:23], v[44:45], v[76:77], v[22:23]
	v_mul_f32_e32 v6, v7, v24
	v_pk_fma_f32 v[8:9], v[8:9], v[72:73], v[22:23]
	v_mul_f32_e32 v0, v10, v0
	v_mul_f32_e32 v7, v8, v8
	v_fmamk_f32 v7, v7, 0xbdd2d3e2, v220
	v_mul_f32_e32 v7, v8, v7
	v_exp_f32_e32 v7, v7
	v_mul_f32_e32 v10, v9, v9
	v_fmamk_f32 v10, v10, 0xbdd2d3e2, v220
	v_mul_f32_e32 v10, v9, v10
	v_exp_f32_e32 v10, v10
	v_add_f32_e32 v7, 1.0, v7
	v_rcp_f32_e32 v7, v7
	v_mul_f32_e32 v6, v11, v6
	v_add_f32_e32 v10, 1.0, v10
	v_rcp_f32_e32 v10, v10
	v_cvt_pk_bf16_f32 v6, v0, v6
	v_mul_f32_e32 v0, v8, v7
	v_mul_f32_e32 v8, v14, v14
	v_fmamk_f32 v8, v8, 0xbdd2d3e2, v220
	v_mul_f32_e32 v8, v14, v8
	v_mul_f32_e32 v7, v9, v10
	v_exp_f32_e32 v10, v8
	v_mul_f32_e32 v8, v15, v15
	v_mul_f32_e32 v0, v12, v0
	v_mul_f32_e32 v7, v13, v7
	v_fmamk_f32 v8, v8, 0xbdd2d3e2, v220
	v_cvt_pk_bf16_f32 v7, v0, v7
	v_or_b32_e32 v0, 8, v102
	v_mul_f32_e32 v8, v15, v8
	v_exp_f32_e32 v11, v8
	v_lshl_add_u64 v[8:9], s[8:9], 0, v[0:1]
	global_store_dwordx2 v[8:9], v[6:7], off
	v_mul_f32_e32 v7, v16, v16
	v_mul_f32_e32 v8, v17, v17
	v_fmamk_f32 v7, v7, 0xbdd2d3e2, v220
	v_fmamk_f32 v8, v8, 0xbdd2d3e2, v220
	v_mul_f32_e32 v7, v16, v7
	v_mul_f32_e32 v8, v17, v8
	v_exp_f32_e32 v7, v7
	v_exp_f32_e32 v8, v8
	v_add_f32_e32 v0, 1.0, v10
	v_add_f32_e32 v10, 1.0, v11
	v_rcp_f32_e32 v0, v0
	v_rcp_f32_e32 v10, v10
	v_add_f32_e32 v7, 1.0, v7
	v_add_f32_e32 v8, 1.0, v8
	v_rcp_f32_e32 v7, v7
	v_rcp_f32_e32 v8, v8
	v_mul_f32_e32 v0, v14, v0
	v_mul_f32_e32 v6, v15, v10
	v_mul_f32_e32 v0, v20, v0
	v_mul_f32_e32 v6, v21, v6
	v_pk_fma_f32 v[18:19], v[28:29], v[88:89], v[18:19]
	v_cvt_pk_bf16_f32 v6, v0, v6
	v_mul_f32_e32 v0, v16, v7
	v_mul_f32_e32 v7, v17, v8
	v_mul_f32_e32 v0, v18, v0
	v_mul_f32_e32 v7, v19, v7
	v_cvt_pk_bf16_f32 v7, v0, v7
	v_or_b32_e32 v0, 8, v104
	v_lshl_add_u64 v[8:9], s[8:9], 0, v[0:1]
	s_andn2_b64 vcc, exec, s[6:7]
	s_mov_b64 s[6:7], -1
	global_store_dwordx2 v[8:9], v[6:7], off
	s_cbranch_vccnz .LBB0_209
	s_andn2_b64 vcc, exec, s[2:3]
	s_cbranch_vccnz .LBB0_208
	s_barrier
	s_branch .LBB0_208

.LBB0_262:
	s_and_b32 s4, s14, 0xffffff00
	s_and_b32 s5, s12, 0x70
	s_or_b32 s4, s4, s5
	v_or_b32_e32 v22, s4, v5
	v_ashrrev_i32_e32 v23, 31, v22
	v_lshlrev_b64 v[22:23], 11, v[22:23]
	v_lshl_add_u64 v[150:151], v[58:59], 0, v[22:23]
	v_add_co_u32_e32 v120, vcc, 0x40000, v150
	global_load_dwordx4 v[6:9], v[60:61], off
	global_load_dwordx4 v[10:13], v[62:63], off
	global_load_dwordx4 v[14:17], v[2:3], off
	global_load_dwordx4 v[18:21], v[2:3], off offset:64
	global_load_dwordx4 v[22:25], v[150:151], off
	global_load_dwordx4 v[26:29], v[150:151], off offset:64
	global_load_dwordx4 v[34:37], v[64:65], off
	global_load_dwordx4 v[42:45], v[66:67], off
	v_addc_co_u32_e32 v121, vcc, 0, v151, vcc
	global_load_dwordx4 v[50:53], v[120:121], off
	global_load_dwordx4 v[54:57], v[120:121], off offset:64
	s_add_i32 s16, s16, s90
	s_add_i32 s14, s14, s15
	s_waitcnt vmcnt(0) lgkmcnt(0)
	v_mfma_f32_16x16x32_bf16 v[30:33], v[22:25], v[14:17], 0
	global_load_dwordx4 v[126:129], v[70:71], off
	v_mfma_f32_16x16x32_bf16 v[38:41], v[22:25], v[6:9], 0
	v_mfma_f32_16x16x32_bf16 v[46:49], v[22:25], v[10:13], 0
	v_mfma_f32_16x16x32_bf16 v[22:25], v[22:25], v[34:37], 0
	v_mfma_f32_16x16x32_bf16 v[14:17], v[50:53], v[14:17], 0
	v_mfma_f32_16x16x32_bf16 v[6:9], v[50:53], v[6:9], 0
	v_mfma_f32_16x16x32_bf16 v[10:13], v[50:53], v[10:13], 0
	v_mfma_f32_16x16x32_bf16 v[34:37], v[50:53], v[34:37], 0
	global_load_dwordx4 v[50:53], v[68:69], off
	v_mfma_f32_16x16x32_bf16 v[30:33], v[26:29], v[18:21], v[30:33]
	v_mfma_f32_16x16x32_bf16 v[38:41], v[26:29], v[42:45], v[38:41]
	v_mfma_f32_16x16x32_bf16 v[14:17], v[54:57], v[18:21], v[14:17]
	v_mfma_f32_16x16x32_bf16 v[6:9], v[54:57], v[42:45], v[6:9]
	s_waitcnt vmcnt(0) lgkmcnt(0)
	v_mfma_f32_16x16x32_bf16 v[46:49], v[26:29], v[50:53], v[46:49]
	v_mfma_f32_16x16x32_bf16 v[22:25], v[26:29], v[126:129], v[22:25]
	global_load_dwordx4 v[18:21], v[72:73], off
	global_load_dwordx4 v[26:29], v[2:3], off offset:128
	global_load_dwordx4 v[42:45], v[2:3], off offset:192
	v_mfma_f32_16x16x32_bf16 v[10:13], v[54:57], v[50:53], v[10:13]
	v_mfma_f32_16x16x32_bf16 v[34:37], v[54:57], v[126:129], v[34:37]
	global_load_dwordx4 v[50:53], v[150:151], off offset:128
	global_load_dwordx4 v[54:57], v[150:151], off offset:192
	global_load_dwordx4 v[126:129], v[74:75], off
	global_load_dwordx4 v[130:133], v[76:77], off
	global_load_dwordx4 v[134:137], v[78:79], off
	s_waitcnt vmcnt(0) lgkmcnt(0)
	v_mfma_f32_16x16x32_bf16 v[30:33], v[50:53], v[26:29], v[30:33]
	v_mfma_f32_16x16x32_bf16 v[38:41], v[50:53], v[18:21], v[38:41]
	v_mfma_f32_16x16x32_bf16 v[46:49], v[50:53], v[126:129], v[46:49]
	v_mfma_f32_16x16x32_bf16 v[22:25], v[50:53], v[130:133], v[22:25]
	global_load_dwordx4 v[50:53], v[120:121], off offset:128
	global_load_dwordx4 v[138:141], v[120:121], off offset:192
	s_waitcnt vmcnt(0) lgkmcnt(0)
	v_mfma_f32_16x16x32_bf16 v[14:17], v[50:53], v[26:29], v[14:17]
	v_mfma_f32_16x16x32_bf16 v[6:9], v[50:53], v[18:21], v[6:9]
	v_mfma_f32_16x16x32_bf16 v[18:21], v[50:53], v[130:133], v[34:37]
	v_mfma_f32_16x16x32_bf16 v[26:29], v[54:57], v[42:45], v[30:33]
	s_nop 2
	global_load_dwordx4 v[30:33], v[80:81], off
	v_mfma_f32_16x16x32_bf16 v[34:37], v[54:57], v[134:137], v[38:41]
	s_nop 2
	global_load_dwordx4 v[38:41], v[82:83], off
	v_mfma_f32_16x16x32_bf16 v[10:13], v[50:53], v[126:129], v[10:13]
	s_waitcnt vmcnt(0) lgkmcnt(0)
	v_mfma_f32_16x16x32_bf16 v[46:49], v[54:57], v[30:33], v[46:49]
	v_mfma_f32_16x16x32_bf16 v[22:25], v[54:57], v[38:41], v[22:25]
	v_mfma_f32_16x16x32_bf16 v[14:17], v[138:141], v[42:45], v[14:17]
	v_mfma_f32_16x16x32_bf16 v[10:13], v[138:141], v[30:33], v[10:13]
	global_load_dwordx4 v[30:33], v[84:85], off
	global_load_dwordx4 v[42:45], v[2:3], off offset:256
	global_load_dwordx4 v[50:53], v[2:3], off offset:320
	v_mfma_f32_16x16x32_bf16 v[18:21], v[138:141], v[38:41], v[18:21]
	global_load_dwordx4 v[38:41], v[150:151], off offset:256
	global_load_dwordx4 v[54:57], v[150:151], off offset:320
	global_load_dwordx4 v[126:129], v[86:87], off
	v_mfma_f32_16x16x32_bf16 v[6:9], v[138:141], v[134:137], v[6:9]
	global_load_dwordx4 v[130:133], v[88:89], off
	global_load_dwordx4 v[134:137], v[90:91], off
	s_waitcnt vmcnt(0) lgkmcnt(0)
	v_mfma_f32_16x16x32_bf16 v[26:29], v[38:41], v[42:45], v[26:29]
	v_mfma_f32_16x16x32_bf16 v[34:37], v[38:41], v[30:33], v[34:37]
	v_mfma_f32_16x16x32_bf16 v[46:49], v[38:41], v[126:129], v[46:49]
	v_mfma_f32_16x16x32_bf16 v[22:25], v[38:41], v[130:133], v[22:25]
	global_load_dwordx4 v[38:41], v[120:121], off offset:256
	global_load_dwordx4 v[138:141], v[120:121], off offset:320
	s_waitcnt vmcnt(0) lgkmcnt(0)
	v_mfma_f32_16x16x32_bf16 v[6:9], v[38:41], v[30:33], v[6:9]
	global_load_dwordx4 v[30:33], v[92:93], off
	v_mfma_f32_16x16x32_bf16 v[10:13], v[38:41], v[126:129], v[10:13]
	global_load_dwordx4 v[126:129], v[94:95], off
	v_mfma_f32_16x16x32_bf16 v[14:17], v[38:41], v[42:45], v[14:17]
	v_mfma_f32_16x16x32_bf16 v[18:21], v[38:41], v[130:133], v[18:21]
	v_mfma_f32_16x16x32_bf16 v[26:29], v[54:57], v[50:53], v[26:29]
	v_mfma_f32_16x16x32_bf16 v[42:45], v[54:57], v[134:137], v[34:37]
	s_waitcnt vmcnt(0) lgkmcnt(0)
	v_mfma_f32_16x16x32_bf16 v[130:133], v[54:57], v[30:33], v[46:49]
	v_mfma_f32_16x16x32_bf16 v[142:145], v[54:57], v[126:129], v[22:25]
	global_load_dwordx4 v[54:57], v[96:97], off
	v_mfma_f32_16x16x32_bf16 v[146:149], v[138:141], v[50:53], v[14:17]
	v_mfma_f32_16x16x32_bf16 v[50:53], v[138:141], v[134:137], v[6:9]
	v_mfma_f32_16x16x32_bf16 v[34:37], v[138:141], v[30:33], v[10:13]
	global_load_dwordx4 v[38:41], v[98:99], off
	global_load_dwordx4 v[134:137], v[2:3], off offset:384
	s_nop 0
	global_load_dwordx4 v[10:13], v[2:3], off offset:448
	v_mfma_f32_16x16x32_bf16 v[30:33], v[138:141], v[126:129], v[18:21]
	global_load_dwordx4 v[126:129], v[150:151], off offset:384
	global_load_dwordx4 v[22:25], v[150:151], off offset:448
	global_load_dwordx4 v[46:49], v[100:101], off
	global_load_dwordx4 v[18:21], v[102:103], off
	global_load_dwordx4 v[14:17], v[104:105], off
	global_load_dwordx4 v[6:9], v[106:107], off
	global_load_dwordx4 v[138:141], v[120:121], off offset:384
	s_waitcnt vmcnt(0) lgkmcnt(0)
	v_mfma_f32_16x16x32_bf16 v[26:29], v[126:129], v[134:137], v[26:29]
	v_add_u32_e32 v150, s12, v124
	v_ashrrev_i32_e32 v151, 31, v150
	s_add_i32 s12, s12, s13
	v_mfma_f32_16x16x32_bf16 v[42:45], v[126:129], v[54:57], v[42:45]
	s_cmpk_gt_i32 s16, 0xbf
	v_mfma_f32_16x16x32_bf16 v[130:133], v[126:129], v[38:41], v[130:133]
	v_mfma_f32_16x16x32_bf16 v[126:129], v[126:129], v[46:49], v[142:145]
	s_nop 2
	global_load_dwordx4 v[142:145], v[120:121], off offset:448
	v_mfma_f32_16x16x32_bf16 v[134:137], v[138:141], v[134:137], v[146:149]
	v_lshl_add_u64 v[120:121], v[150:151], 1, v[118:119]
	v_mfma_f32_16x16x32_bf16 v[50:53], v[138:141], v[54:57], v[50:53]
	v_lshlrev_b64 v[54:55], 2, v[150:151]
	v_lshl_add_u64 v[56:57], v[110:111], 0, v[54:55]
	v_lshl_add_u64 v[146:147], v[112:113], 0, v[54:55]
	v_mfma_f32_16x16x32_bf16 v[34:37], v[138:141], v[38:41], v[34:37]
	v_add_co_u32_e32 v156, vcc, s19, v56
	v_lshl_add_u64 v[148:149], s[10:11], 0, v[54:55]
	v_mfma_f32_16x16x32_bf16 v[30:33], v[138:141], v[46:49], v[30:33]
	v_addc_co_u32_e32 v157, vcc, 0, v57, vcc
	v_add_co_u32_e32 v158, vcc, s19, v146
	v_mfma_f32_16x16x32_bf16 v[26:29], v[22:25], v[10:13], v[26:29]
	v_lshl_add_u64 v[138:139], s[2:3], 0, v[54:55]
	v_addc_co_u32_e32 v159, vcc, 0, v147, vcc
	v_mfma_f32_16x16x32_bf16 v[38:41], v[22:25], v[18:21], v[42:45]
	v_add_co_u32_e32 v160, vcc, s19, v138
	v_lshl_add_u64 v[140:141], s[8:9], 0, v[54:55]
	v_mfma_f32_16x16x32_bf16 v[42:45], v[22:25], v[14:17], v[130:133]
	v_addc_co_u32_e32 v161, vcc, 0, v139, vcc
	v_add_co_u32_e32 v162, vcc, s19, v140
	v_mfma_f32_16x16x32_bf16 v[22:25], v[22:25], v[6:9], v[126:129]
	s_nop 0
	v_addc_co_u32_e32 v163, vcc, 0, v141, vcc
	v_add_co_u32_e32 v164, vcc, s19, v148
	s_waitcnt vmcnt(0) lgkmcnt(0)
	v_mfma_f32_16x16x32_bf16 v[10:13], v[142:145], v[10:13], v[134:137]
	v_lshl_add_u64 v[150:151], s[6:7], 0, v[54:55]
	v_addc_co_u32_e32 v165, vcc, 0, v149, vcc
	v_mfma_f32_16x16x32_bf16 v[18:21], v[142:145], v[18:21], v[50:53]
	v_add_co_u32_e32 v166, vcc, s19, v150
	v_lshl_add_u64 v[152:153], v[114:115], 0, v[54:55]
	v_mfma_f32_16x16x32_bf16 v[14:17], v[142:145], v[14:17], v[34:37]
	v_addc_co_u32_e32 v167, vcc, 0, v151, vcc
	v_lshl_add_u64 v[154:155], v[116:117], 0, v[54:55]
	v_mfma_f32_16x16x32_bf16 v[6:9], v[142:145], v[6:9], v[30:33]
	ds_write_b128 v0, v[26:29]
	ds_write_b128 v0, v[38:41] offset:2048
	ds_write_b128 v0, v[42:45] offset:4096
	ds_write_b128 v0, v[22:25] offset:6144
	ds_write_b128 v0, v[10:13] offset:1024
	ds_write_b128 v0, v[18:21] offset:3072
	ds_write_b128 v0, v[14:17] offset:5120
	s_nop 0
	ds_write_b128 v0, v[6:9] offset:7168
	s_waitcnt lgkmcnt(0)
	s_barrier
	global_load_dwordx4 v[6:9], v[108:109], off
	global_load_dwordx4 v[10:13], v[108:109], off offset:16
	global_load_dwordx4 v[14:17], v[146:147], off nt
	global_load_dwordx4 v[18:21], v[56:57], off nt
	ds_read_b128 v[22:25], v125
	ds_read_b128 v[26:29], v125 offset:1024
	ds_read_b128 v[30:33], v125 offset:8192
	ds_read_b128 v[34:37], v125 offset:9216
	ds_read_b128 v[38:41], v125 offset:16384
	ds_read_b128 v[42:45], v125 offset:17408
	ds_read_b128 v[46:49], v125 offset:24576
	ds_read_b128 v[50:53], v125 offset:25600
	s_waitcnt lgkmcnt(0)
	v_pk_add_f32 v[22:23], v[22:23], 0 op_sel_hi:[1,0]
	global_load_dwordx4 v[54:57], v[138:139], off
	global_load_dwordx4 v[126:129], v[140:141], off
	global_load_dwordx4 v[130:133], v[148:149], off
	global_load_dwordx4 v[134:137], v[150:151], off
	v_pk_add_f32 v[22:23], v[22:23], v[30:31]
	v_pk_add_f32 v[24:25], v[24:25], 0 op_sel_hi:[1,0]
	v_pk_add_f32 v[22:23], v[22:23], v[38:39]
	v_pk_add_f32 v[24:25], v[24:25], v[32:33]
	v_pk_add_f32 v[22:23], v[22:23], v[46:47]
	v_pk_add_f32 v[24:25], v[24:25], v[40:41]
	v_pk_add_f32 v[26:27], v[26:27], 0 op_sel_hi:[1,0]
	v_pk_add_f32 v[24:25], v[24:25], v[48:49]
	v_pk_add_f32 v[26:27], v[26:27], v[34:35]
	v_pk_add_f32 v[28:29], v[28:29], 0 op_sel_hi:[1,0]
	v_pk_add_f32 v[26:27], v[26:27], v[42:43]
	v_pk_add_f32 v[28:29], v[28:29], v[36:37]
	v_pk_add_f32 v[26:27], v[26:27], v[50:51]
	v_pk_add_f32 v[28:29], v[28:29], v[44:45]
	s_waitcnt vmcnt(0)
	v_mov_b32_e32 v30, v6
	v_mov_b32_e32 v31, v10
	v_mov_b32_e32 v10, v7
	v_mov_b32_e32 v6, v8
	v_mov_b32_e32 v7, v12
	v_mov_b32_e32 v12, v9
	v_pk_add_f32 v[8:9], v[30:31], v[10:11]
	v_pk_add_f32 v[6:7], v[6:7], v[12:13]
	global_store_dwordx4 v[152:153], v[14:17], off
	v_pk_add_f32 v[6:7], v[8:9], v[6:7]
	v_pk_add_f32 v[28:29], v[28:29], v[52:53]
	v_add_f32_e32 v6, v6, v7
	ds_bpermute_b32 v7, v122, v6
	s_waitcnt lgkmcnt(0)
	v_pk_mul_f32 v[16:17], v[16:17], v[128:129]
	v_pk_mul_f32 v[14:15], v[14:15], v[126:127]
	v_pk_fma_f32 v[20:21], v[20:21], v[56:57], v[16:17]
	v_pk_fma_f32 v[18:19], v[18:19], v[54:55], v[14:15]
	v_add_f32_e32 v6, v6, v7
	ds_bpermute_b32 v7, v123, v6
	s_waitcnt lgkmcnt(0)
	v_add_f32_e32 v6, v6, v7
	v_fmamk_f32 v6, v6, 0x3a800000, v219
	v_mul_f32_e32 v7, 0x4f800000, v6
	v_cmp_gt_f32_e32 vcc, s85, v6
	s_nop 1
	v_cndmask_b32_e32 v6, v6, v7, vcc
	v_sqrt_f32_e32 v7, v6
	s_nop 0
	v_add_u32_e32 v8, -1, v7
	v_add_u32_e32 v9, 1, v7
	v_fma_f32 v10, -v8, v7, v6
	v_fma_f32 v11, -v9, v7, v6
	v_cmp_ge_f32_e64 s[4:5], 0, v10
	s_nop 1
	v_cndmask_b32_e64 v7, v7, v8, s[4:5]
	v_cmp_lt_f32_e64 s[4:5], 0, v11
	s_nop 1
	v_cndmask_b32_e64 v7, v7, v9, s[4:5]
	v_mul_f32_e32 v8, 0x37800000, v7
	v_cndmask_b32_e32 v7, v7, v8, vcc
	v_cmp_class_f32_e32 vcc, v6, v221
	s_nop 1
	v_cndmask_b32_e32 v6, v7, v6, vcc
	v_div_scale_f32 v7, s[4:5], v6, v6, 1.0
	v_rcp_f32_e32 v9, v7
	v_div_scale_f32 v8, vcc, 1.0, v6, 1.0
	v_fma_f32 v10, -v7, v9, 1.0
	v_fmac_f32_e32 v9, v10, v9
	v_mul_f32_e32 v10, v8, v9
	v_fma_f32 v11, -v7, v10, v8
	v_fmac_f32_e32 v10, v11, v9
	v_fma_f32 v7, -v7, v10, v8
	v_div_fmas_f32 v7, v7, v9, v10
	v_div_fixup_f32 v142, v7, v6, 1.0
	v_pk_mul_f32 v[8:9], v[24:25], v[142:143] op_sel_hi:[1,0]
	v_pk_mul_f32 v[6:7], v[22:23], v[142:143] op_sel_hi:[1,0]
	global_store_dwordx4 v[154:155], v[6:9], off
	global_load_dwordx4 v[10:13], v[162:163], off
	global_load_dwordx4 v[22:25], v[158:159], off nt
	global_load_dwordx4 v[30:33], v[156:157], off nt
	global_load_dwordx4 v[38:41], v[160:161], off
	global_load_dwordx4 v[46:49], v[164:165], off
	global_load_dwordx4 v[138:141], v[166:167], off
	v_pk_fma_f32 v[6:7], v[130:131], v[6:7], v[18:19]
	v_pk_fma_f32 v[8:9], v[132:133], v[8:9], v[20:21]
	v_pk_add_f32 v[6:7], v[134:135], v[6:7]
	v_pk_add_f32 v[8:9], v[136:137], v[8:9]
	v_pk_mul_f32 v[14:15], v[26:27], v[142:143] op_sel_hi:[1,0]
	v_mul_f32_e32 v20, v6, v6
	v_mul_f32_e32 v21, v7, v7
	v_mul_f32_e32 v26, v8, v8
	v_mul_f32_e32 v27, v9, v9
	v_fmamk_f32 v20, v20, 0xbdd2d3e2, v220
	v_fmamk_f32 v21, v21, 0xbdd2d3e2, v220
	v_fmamk_f32 v26, v26, 0xbdd2d3e2, v220
	v_fmamk_f32 v27, v27, 0xbdd2d3e2, v220
	v_mov_b32_e32 v18, v6
	v_mul_f32_e32 v6, v6, v20
	v_mul_f32_e32 v20, v7, v21
	v_mul_f32_e32 v21, v8, v26
	v_mul_f32_e32 v26, v9, v27
	v_mov_b32_e32 v19, v8
	v_mov_b32_e32 v8, v7
	v_exp_f32_e32 v7, v20
	v_exp_f32_e32 v20, v21
	v_exp_f32_e32 v21, v26
	v_exp_f32_e32 v6, v6
	v_add_f32_e32 v7, 1.0, v7
	v_add_co_u32_e32 v144, vcc, s19, v152
	v_add_f32_e32 v21, 1.0, v21
	v_add_f32_e32 v6, 1.0, v6
	v_add_f32_e32 v26, 1.0, v20
	v_rcp_f32_e32 v20, v7
	v_rcp_f32_e32 v21, v21
	v_addc_co_u32_e32 v145, vcc, 0, v153, vcc
	v_pk_mul_f32 v[16:17], v[28:29], v[142:143] op_sel_hi:[1,0]
	v_rcp_f32_e32 v6, v6
	v_rcp_f32_e32 v7, v26
	v_add_co_u32_e32 v146, vcc, s19, v154
	v_pk_mul_f32 v[8:9], v[8:9], v[20:21]
	s_nop 0
	v_addc_co_u32_e32 v147, vcc, 0, v155, vcc
	global_store_dwordx4 v[146:147], v[14:17], off
	v_pk_mul_f32 v[6:7], v[18:19], v[6:7]
	s_waitcnt vmcnt(0) lgkmcnt(0)
	v_pk_mul_f32 v[12:13], v[24:25], v[12:13]
	v_pk_mul_f32 v[10:11], v[22:23], v[10:11]
	v_pk_fma_f32 v[12:13], v[32:33], v[40:41], v[12:13]
	v_pk_fma_f32 v[10:11], v[30:31], v[38:39], v[10:11]
	v_pk_fma_f32 v[12:13], v[16:17], v[48:49], v[12:13]
	v_pk_fma_f32 v[10:11], v[14:15], v[46:47], v[10:11]
	v_pk_add_f32 v[12:13], v[140:141], v[12:13]
	v_pk_add_f32 v[10:11], v[138:139], v[10:11]
	v_mov_b32_e32 v15, v12
	v_mov_b32_e32 v12, v11
	v_mov_b32_e32 v14, v10
	v_pk_mul_f32 v[8:9], v[12:13], v[8:9]
	v_pk_mul_f32 v[6:7], v[14:15], v[6:7]
	v_and_b32_sdwa v12, v9, v218 dst_sel:DWORD dst_unused:UNUSED_PAD src0_sel:WORD_1 src1_sel:DWORD
	v_and_b32_sdwa v13, v8, v218 dst_sel:DWORD dst_unused:UNUSED_PAD src0_sel:WORD_1 src1_sel:DWORD
	v_and_b32_sdwa v10, v7, v218 dst_sel:DWORD dst_unused:UNUSED_PAD src0_sel:WORD_1 src1_sel:DWORD
	v_and_b32_sdwa v11, v6, v218 dst_sel:DWORD dst_unused:UNUSED_PAD src0_sel:WORD_1 src1_sel:DWORD
	v_add3_u32 v9, v9, v12, s91
	v_add3_u32 v8, v8, v13, s91
	v_add3_u32 v6, v6, v11, s91
	v_add3_u32 v7, v7, v10, s91
	v_and_b32_e32 v9, 0xffff0000, v9
	v_and_b32_e32 v8, 0xffff0000, v8
	v_or_b32_sdwa v7, v9, v7 dst_sel:DWORD dst_unused:UNUSED_PAD src0_sel:DWORD src1_sel:WORD_1
	v_or_b32_sdwa v6, v8, v6 dst_sel:DWORD dst_unused:UNUSED_PAD src0_sel:DWORD src1_sel:WORD_1
	global_store_dwordx4 v[144:145], v[22:25], off
	global_store_dwordx2 v[120:121], v[6:7], off
	s_waitcnt lgkmcnt(0)
	s_barrier
	s_cbranch_scc0 .LBB0_262

.LBB0_289:
	v_add_co_u32_e32 v42, vcc, 0x3000, v40
	s_mov_b32 s13, 0xc000
	s_nop 0
	v_addc_co_u32_e32 v43, vcc, 0, v41, vcc
	v_add_co_u32_e32 v44, vcc, 0x9000, v40
	s_mov_b32 s4, 0x12000
	s_nop 0
	v_addc_co_u32_e32 v45, vcc, 0, v41, vcc
	global_load_dwordx4 v[160:163], v[42:43], off
	global_load_dwordx4 v[164:167], v[44:45], off
	v_add_co_u32_e32 v44, vcc, s13, v40
	v_lshl_add_u64 v[42:43], s[34:35], 0, v[38:39]
	s_nop 0
	v_addc_co_u32_e32 v45, vcc, 0, v41, vcc
	v_add_co_u32_e32 v46, vcc, s4, v40
	s_movk_i32 s5, 0x6000
	s_nop 0
	v_addc_co_u32_e32 v47, vcc, 0, v41, vcc
	global_load_dwordx4 v[114:117], v[44:45], off
	global_load_dwordx4 v[102:105], v[42:43], off
	v_add_co_u32_e32 v44, vcc, s5, v42
	s_mov_b32 s59, 0xf000
	s_nop 0
	v_addc_co_u32_e32 v45, vcc, 0, v43, vcc
	global_load_dwordx4 v[110:113], v[46:47], off
	global_load_dwordx4 v[106:109], v[44:45], off
	v_add_co_u32_e32 v44, vcc, s59, v40
	s_mov_b32 s60, 0x15000
	s_nop 0
	v_addc_co_u32_e32 v45, vcc, 0, v41, vcc
	v_add_co_u32_e32 v40, vcc, s60, v40
	s_movk_i32 s57, 0x3000
	s_nop 0
	v_addc_co_u32_e32 v41, vcc, 0, v41, vcc
	global_load_dwordx4 v[126:129], v[44:45], off
	global_load_dwordx4 v[118:121], v[40:41], off
	v_add_co_u32_e32 v40, vcc, s57, v42
	s_mov_b32 s58, 0x9000
	s_nop 0
	v_addc_co_u32_e32 v41, vcc, 0, v43, vcc
	v_add_co_u32_e32 v44, vcc, s58, v42
	s_waitcnt vmcnt(0) lgkmcnt(0)
	v_pk_fma_f32 v[142:143], v[26:27], v[142:143], v[30:31]
	v_addc_co_u32_e32 v45, vcc, 0, v43, vcc
	global_load_dwordx4 v[130:133], v[40:41], off
	global_load_dwordx4 v[122:125], v[44:45], off
	v_pk_fma_f32 v[142:143], v[22:23], v[138:139], v[142:143]
	v_lshl_add_u64 v[158:159], v[2:3], 1, s[10:11]
	v_pk_fma_f32 v[142:143], v[18:19], v[154:155], v[142:143]
	v_pk_fma_f32 v[144:145], v[28:29], v[144:145], v[32:33]
	v_mul_f32_e32 v3, v142, v142
	v_fmamk_f32 v3, v3, 0xbdd2d3e2, v220
	v_mul_f32_e32 v5, v143, v143
	v_mul_f32_e32 v3, v142, v3
	v_fmamk_f32 v5, v5, 0xbdd2d3e2, v220
	v_exp_f32_e32 v3, v3
	v_mul_f32_e32 v5, v143, v5
	v_exp_f32_e32 v5, v5
	v_add_co_u32_e32 v44, vcc, s13, v42
	v_pk_fma_f32 v[144:145], v[24:25], v[140:141], v[144:145]
	v_pk_fma_f32 v[138:139], v[26:27], v[138:139], v[30:31]
	v_addc_co_u32_e32 v45, vcc, 0, v43, vcc
	v_pk_fma_f32 v[144:145], v[20:21], v[156:157], v[144:145]
	v_pk_fma_f32 v[138:139], v[22:23], v[154:155], v[138:139]
	v_add_f32_e32 v3, 1.0, v3
	v_add_co_u32_e32 v46, vcc, s4, v42
	v_pk_fma_f32 v[138:139], v[18:19], v[150:151], v[138:139]
	v_rcp_f32_e32 v150, v3
	v_add_f32_e32 v3, 1.0, v5
	v_mul_f32_e32 v5, v144, v144
	v_lshl_add_u64 v[40:41], s[24:25], 0, v[38:39]
	v_addc_co_u32_e32 v47, vcc, 0, v43, vcc
	v_fmamk_f32 v5, v5, 0xbdd2d3e2, v220
	v_mul_f32_e32 v151, v145, v145
	global_load_dwordx4 v[98:101], v[44:45], off
	global_load_dwordx4 v[78:81], v[40:41], off
	v_add_co_u32_e32 v44, vcc, s5, v40
	v_pk_fma_f32 v[140:141], v[28:29], v[140:141], v[32:33]
	v_mul_f32_e32 v5, v144, v5
	v_fmamk_f32 v151, v151, 0xbdd2d3e2, v220
	v_addc_co_u32_e32 v45, vcc, 0, v41, vcc
	v_pk_fma_f32 v[140:141], v[24:25], v[156:157], v[140:141]
	v_exp_f32_e32 v5, v5
	v_mul_f32_e32 v151, v145, v151
	global_load_dwordx4 v[94:97], v[46:47], off
	global_load_dwordx4 v[82:85], v[44:45], off
	v_add_co_u32_e32 v44, vcc, s59, v42
	v_pk_fma_f32 v[140:141], v[20:21], v[152:153], v[140:141]
	v_exp_f32_e32 v153, v151
	v_addc_co_u32_e32 v45, vcc, 0, v43, vcc
	v_add_co_u32_e32 v42, vcc, s60, v42
	v_rcp_f32_e32 v152, v3
	s_nop 0
	v_addc_co_u32_e32 v43, vcc, 0, v43, vcc
	v_add_f32_e32 v3, 1.0, v5
	global_load_dwordx4 v[90:93], v[44:45], off
	global_load_dwordx4 v[74:77], v[42:43], off
	v_add_co_u32_e32 v42, vcc, s57, v40
	v_rcp_f32_e32 v151, v3
	v_add_f32_e32 v3, 1.0, v153
	v_addc_co_u32_e32 v43, vcc, 0, v41, vcc
	v_rcp_f32_e32 v153, v3
	v_add_co_u32_e32 v44, vcc, s58, v40
	v_pk_fma_f32 v[136:137], v[12:13], v[136:137], v[36:37]
	v_pk_fma_f32 v[134:135], v[10:11], v[134:135], v[34:35]
	v_addc_co_u32_e32 v45, vcc, 0, v41, vcc
	v_pk_fma_f32 v[136:137], v[16:17], v[148:149], v[136:137]
	v_pk_fma_f32 v[134:135], v[14:15], v[146:147], v[134:135]
	global_load_dwordx4 v[86:89], v[42:43], off
	global_load_dwordx4 v[70:73], v[44:45], off
	v_add_co_u32_e32 v42, vcc, s13, v40
	v_pk_fma_f32 v[136:137], v[8:9], v[162:163], v[136:137]
	v_pk_fma_f32 v[134:135], v[6:7], v[160:161], v[134:135]
	v_mov_b32_e32 v154, v142
	v_mov_b32_e32 v155, v144
	v_mov_b32_e32 v144, v143
	v_addc_co_u32_e32 v43, vcc, 0, v41, vcc
	v_pk_mul_f32 v[150:151], v[154:155], v[150:151]
	v_mov_b32_e32 v155, v136
	v_pk_mul_f32 v[142:143], v[144:145], v[152:153]
	v_mov_b32_e32 v136, v135
	v_add_co_u32_e32 v44, vcc, s4, v40
	v_mov_b32_e32 v154, v134
	v_pk_mul_f32 v[134:135], v[142:143], v[136:137]
	v_lshl_add_u64 v[38:39], s[36:37], 0, v[38:39]
	v_addc_co_u32_e32 v45, vcc, 0, v41, vcc
	v_pk_mul_f32 v[150:151], v[150:151], v[154:155]
	v_and_b32_sdwa v136, v135, v218 dst_sel:DWORD dst_unused:UNUSED_PAD src0_sel:WORD_1 src1_sel:DWORD
	global_load_dwordx4 v[62:65], v[42:43], off
	global_load_dwordx4 v[46:49], v[38:39], off
	v_add_co_u32_e32 v42, vcc, s5, v38
	v_and_b32_sdwa v3, v151, v218 dst_sel:DWORD dst_unused:UNUSED_PAD src0_sel:WORD_1 src1_sel:DWORD
	v_and_b32_sdwa v137, v134, v218 dst_sel:DWORD dst_unused:UNUSED_PAD src0_sel:WORD_1 src1_sel:DWORD
	v_add3_u32 v135, v135, v136, s91
	v_addc_co_u32_e32 v43, vcc, 0, v39, vcc
	v_and_b32_sdwa v5, v150, v218 dst_sel:DWORD dst_unused:UNUSED_PAD src0_sel:WORD_1 src1_sel:DWORD
	v_add3_u32 v3, v151, v3, s91
	v_add3_u32 v134, v134, v137, s91
	v_and_b32_e32 v135, 0xffff0000, v135
	global_load_dwordx4 v[54:57], v[44:45], off
	global_load_dwordx4 v[50:53], v[42:43], off
	v_add_co_u32_e32 v42, vcc, s60, v40
	v_add3_u32 v5, v150, v5, s91
	v_and_b32_e32 v134, 0xffff0000, v134
	v_or_b32_sdwa v135, v135, v3 dst_sel:DWORD dst_unused:UNUSED_PAD src0_sel:DWORD src1_sel:WORD_1
	v_mul_f32_e32 v3, v138, v138
	v_addc_co_u32_e32 v43, vcc, 0, v41, vcc
	v_or_b32_sdwa v134, v134, v5 dst_sel:DWORD dst_unused:UNUSED_PAD src0_sel:DWORD src1_sel:WORD_1
	v_fmamk_f32 v3, v3, 0xbdd2d3e2, v220
	v_mul_f32_e32 v5, v139, v139
	v_add_co_u32_e32 v40, vcc, s59, v40
	v_mul_f32_e32 v3, v138, v3
	v_fmamk_f32 v5, v5, 0xbdd2d3e2, v220
	v_addc_co_u32_e32 v41, vcc, 0, v41, vcc
	v_exp_f32_e32 v3, v3
	v_mul_f32_e32 v5, v139, v5
	global_load_dwordx4 v[42:45], v[42:43], off
	s_nop 0
	global_load_dwordx4 v[66:69], v[40:41], off
	v_add_co_u32_e32 v40, vcc, s57, v38
	v_exp_f32_e32 v5, v5
	s_nop 0
	v_addc_co_u32_e32 v41, vcc, 0, v39, vcc
	v_add_co_u32_e32 v38, vcc, s58, v38
	v_lshl_add_u64 v[136:137], v[158:159], 0, s[38:39]
	s_nop 0
	v_addc_co_u32_e32 v39, vcc, 0, v39, vcc
	v_add_f32_e32 v3, 1.0, v3
	global_load_dwordx4 v[58:61], v[40:41], off
	s_nop 0
	global_load_dwordx4 v[38:41], v[38:39], off
	v_pk_fma_f32 v[148:149], v[12:13], v[148:149], v[36:37]
	global_store_dwordx2 v[136:137], v[134:135], off
	v_rcp_f32_e32 v134, v3
	v_add_f32_e32 v3, 1.0, v5
	v_mul_f32_e32 v5, v140, v140
	v_fmamk_f32 v5, v5, 0xbdd2d3e2, v220
	v_mul_f32_e32 v135, v141, v141
	v_mul_f32_e32 v5, v140, v5
	v_fmamk_f32 v135, v135, 0xbdd2d3e2, v220
	v_exp_f32_e32 v5, v5
	v_mul_f32_e32 v135, v141, v135
	v_exp_f32_e32 v137, v135
	v_rcp_f32_e32 v136, v3
	v_add_f32_e32 v3, 1.0, v5
	v_rcp_f32_e32 v135, v3
	v_add_f32_e32 v3, 1.0, v137
	v_pk_fma_f32 v[146:147], v[10:11], v[146:147], v[34:35]
	v_rcp_f32_e32 v137, v3
	v_pk_fma_f32 v[148:149], v[16:17], v[162:163], v[148:149]
	v_pk_fma_f32 v[146:147], v[14:15], v[160:161], v[146:147]
	v_pk_fma_f32 v[148:149], v[8:9], v[166:167], v[148:149]
	v_pk_fma_f32 v[146:147], v[6:7], v[164:165], v[146:147]
	v_mov_b32_e32 v142, v138
	v_mov_b32_e32 v143, v140
	v_pk_mul_f32 v[134:135], v[142:143], v[134:135]
	v_mov_b32_e32 v142, v146
	v_mov_b32_e32 v143, v148
	v_mov_b32_e32 v140, v139
	v_pk_mul_f32 v[134:135], v[134:135], v[142:143]
	v_pk_mul_f32 v[136:137], v[140:141], v[136:137]
	v_mov_b32_e32 v148, v147
	v_pk_mul_f32 v[136:137], v[136:137], v[148:149]
	v_and_b32_sdwa v5, v134, v218 dst_sel:DWORD dst_unused:UNUSED_PAD src0_sel:WORD_1 src1_sel:DWORD
	v_and_b32_sdwa v3, v135, v218 dst_sel:DWORD dst_unused:UNUSED_PAD src0_sel:WORD_1 src1_sel:DWORD
	v_add3_u32 v5, v134, v5, s91
	v_and_b32_sdwa v134, v137, v218 dst_sel:DWORD dst_unused:UNUSED_PAD src0_sel:WORD_1 src1_sel:DWORD
	v_pk_fma_f32 v[114:115], v[26:27], v[114:115], v[30:31]
	v_add3_u32 v3, v135, v3, s91
	v_and_b32_sdwa v135, v136, v218 dst_sel:DWORD dst_unused:UNUSED_PAD src0_sel:WORD_1 src1_sel:DWORD
	v_add3_u32 v134, v137, v134, s91
	v_pk_fma_f32 v[114:115], v[22:23], v[110:111], v[114:115]
	v_add3_u32 v135, v136, v135, s91
	v_and_b32_e32 v134, 0xffff0000, v134
	v_pk_fma_f32 v[114:115], v[18:19], v[102:103], v[114:115]
	v_and_b32_e32 v136, 0xffff0000, v135
	v_or_b32_sdwa v135, v134, v3 dst_sel:DWORD dst_unused:UNUSED_PAD src0_sel:DWORD src1_sel:WORD_1
	v_mul_f32_e32 v3, v114, v114
	v_or_b32_sdwa v134, v136, v5 dst_sel:DWORD dst_unused:UNUSED_PAD src0_sel:DWORD src1_sel:WORD_1
	v_fmamk_f32 v3, v3, 0xbdd2d3e2, v220
	v_mul_f32_e32 v5, v115, v115
	v_mul_f32_e32 v3, v114, v3
	v_fmamk_f32 v5, v5, 0xbdd2d3e2, v220
	v_exp_f32_e32 v3, v3
	v_mul_f32_e32 v5, v115, v5
	v_pk_fma_f32 v[116:117], v[28:29], v[116:117], v[32:33]
	v_exp_f32_e32 v5, v5
	v_pk_fma_f32 v[116:117], v[24:25], v[112:113], v[116:117]
	v_pk_fma_f32 v[112:113], v[28:29], v[112:113], v[32:33]
	v_pk_fma_f32 v[116:117], v[20:21], v[104:105], v[116:117]
	v_pk_fma_f32 v[104:105], v[24:25], v[104:105], v[112:113]
	v_add_f32_e32 v3, 1.0, v3
	v_pk_fma_f32 v[104:105], v[20:21], v[108:109], v[104:105]
	v_pk_fma_f32 v[108:109], v[10:11], v[126:127], v[34:35]
	v_pk_fma_f32 v[112:113], v[10:11], v[118:119], v[34:35]
	v_pk_fma_f32 v[108:109], v[14:15], v[118:119], v[108:109]
	v_rcp_f32_e32 v118, v3
	v_add_f32_e32 v3, 1.0, v5
	v_mul_f32_e32 v5, v116, v116
	v_pk_fma_f32 v[110:111], v[26:27], v[110:111], v[30:31]
	v_fmamk_f32 v5, v5, 0xbdd2d3e2, v220
	v_mul_f32_e32 v119, v117, v117
	v_pk_fma_f32 v[102:103], v[22:23], v[102:103], v[110:111]
	v_mul_f32_e32 v5, v116, v5
	v_fmamk_f32 v119, v119, 0xbdd2d3e2, v220
	v_pk_fma_f32 v[102:103], v[18:19], v[106:107], v[102:103]
	v_pk_fma_f32 v[106:107], v[12:13], v[128:129], v[36:37]
	v_exp_f32_e32 v5, v5
	v_mul_f32_e32 v119, v117, v119
	v_pk_fma_f32 v[106:107], v[16:17], v[120:121], v[106:107]
	v_pk_fma_f32 v[110:111], v[12:13], v[120:121], v[36:37]
	v_exp_f32_e32 v121, v119
	v_rcp_f32_e32 v120, v3
	v_add_f32_e32 v3, 1.0, v5
	v_rcp_f32_e32 v119, v3
	v_add_f32_e32 v3, 1.0, v121
	v_rcp_f32_e32 v121, v3
	s_waitcnt vmcnt(0) lgkmcnt(0)
	v_pk_fma_f32 v[112:113], v[14:15], v[130:131], v[112:113]
	v_pk_fma_f32 v[106:107], v[8:9], v[132:133], v[106:107]
	v_pk_fma_f32 v[108:109], v[6:7], v[130:131], v[108:109]
	v_pk_fma_f32 v[112:113], v[6:7], v[122:123], v[112:113]
	v_mov_b32_e32 v122, v114
	v_mov_b32_e32 v123, v116
	v_mov_b32_e32 v116, v115
	v_pk_mul_f32 v[118:119], v[122:123], v[118:119]
	v_mov_b32_e32 v123, v106
	v_pk_mul_f32 v[114:115], v[116:117], v[120:121]
	v_mov_b32_e32 v106, v109
	v_mov_b32_e32 v122, v108
	v_pk_mul_f32 v[106:107], v[106:107], v[114:115]
	v_pk_mul_f32 v[118:119], v[122:123], v[118:119]
	v_and_b32_sdwa v108, v107, v218 dst_sel:DWORD dst_unused:UNUSED_PAD src0_sel:WORD_1 src1_sel:DWORD
	v_and_b32_sdwa v3, v119, v218 dst_sel:DWORD dst_unused:UNUSED_PAD src0_sel:WORD_1 src1_sel:DWORD
	v_and_b32_sdwa v109, v106, v218 dst_sel:DWORD dst_unused:UNUSED_PAD src0_sel:WORD_1 src1_sel:DWORD
	v_add3_u32 v107, v107, v108, s91
	v_and_b32_sdwa v5, v118, v218 dst_sel:DWORD dst_unused:UNUSED_PAD src0_sel:WORD_1 src1_sel:DWORD
	v_add3_u32 v3, v119, v3, s91
	v_add3_u32 v106, v106, v109, s91
	v_and_b32_e32 v107, 0xffff0000, v107
	v_add3_u32 v5, v118, v5, s91
	v_and_b32_e32 v106, 0xffff0000, v106
	v_or_b32_sdwa v107, v107, v3 dst_sel:DWORD dst_unused:UNUSED_PAD src0_sel:DWORD src1_sel:WORD_1
	v_mul_f32_e32 v3, v102, v102
	v_or_b32_sdwa v106, v106, v5 dst_sel:DWORD dst_unused:UNUSED_PAD src0_sel:DWORD src1_sel:WORD_1
	v_fmamk_f32 v3, v3, 0xbdd2d3e2, v220
	v_mul_f32_e32 v5, v103, v103
	v_mul_f32_e32 v3, v102, v3
	v_fmamk_f32 v5, v5, 0xbdd2d3e2, v220
	v_exp_f32_e32 v3, v3
	v_mul_f32_e32 v5, v103, v5
	v_exp_f32_e32 v5, v5
	v_lshl_add_u64 v[108:109], v[158:159], 0, s[42:43]
	v_add_f32_e32 v3, 1.0, v3
	global_store_dwordx2 v[108:109], v[106:107], off
	v_rcp_f32_e32 v106, v3
	v_add_f32_e32 v3, 1.0, v5
	v_mul_f32_e32 v5, v104, v104
	v_fmamk_f32 v5, v5, 0xbdd2d3e2, v220
	v_mul_f32_e32 v107, v105, v105
	v_mul_f32_e32 v5, v104, v5
	v_fmamk_f32 v107, v107, 0xbdd2d3e2, v220
	v_exp_f32_e32 v5, v5
	v_mul_f32_e32 v107, v105, v107
	v_exp_f32_e32 v109, v107
	v_rcp_f32_e32 v108, v3
	v_add_f32_e32 v3, 1.0, v5
	v_rcp_f32_e32 v107, v3
	v_add_f32_e32 v3, 1.0, v109
	v_rcp_f32_e32 v109, v3
	v_pk_fma_f32 v[110:111], v[16:17], v[132:133], v[110:111]
	v_mov_b32_e32 v114, v102
	v_pk_fma_f32 v[110:111], v[8:9], v[124:125], v[110:111]
	v_mov_b32_e32 v115, v104
	v_mov_b32_e32 v104, v103
	v_pk_mul_f32 v[106:107], v[114:115], v[106:107]
	v_mov_b32_e32 v115, v110
	v_pk_mul_f32 v[102:103], v[104:105], v[108:109]
	v_mov_b32_e32 v110, v113
	v_mov_b32_e32 v114, v112
	v_pk_mul_f32 v[102:103], v[110:111], v[102:103]
	v_pk_mul_f32 v[106:107], v[114:115], v[106:107]
	v_and_b32_sdwa v104, v103, v218 dst_sel:DWORD dst_unused:UNUSED_PAD src0_sel:WORD_1 src1_sel:DWORD
	v_pk_fma_f32 v[98:99], v[26:27], v[98:99], v[30:31]
	v_and_b32_sdwa v3, v107, v218 dst_sel:DWORD dst_unused:UNUSED_PAD src0_sel:WORD_1 src1_sel:DWORD
	v_and_b32_sdwa v105, v102, v218 dst_sel:DWORD dst_unused:UNUSED_PAD src0_sel:WORD_1 src1_sel:DWORD
	v_add3_u32 v103, v103, v104, s91
	v_pk_fma_f32 v[98:99], v[22:23], v[94:95], v[98:99]
	v_and_b32_sdwa v5, v106, v218 dst_sel:DWORD dst_unused:UNUSED_PAD src0_sel:WORD_1 src1_sel:DWORD
	v_add3_u32 v3, v107, v3, s91
	v_add3_u32 v102, v102, v105, s91
	v_and_b32_e32 v103, 0xffff0000, v103
	v_pk_fma_f32 v[98:99], v[18:19], v[78:79], v[98:99]
	v_add3_u32 v5, v106, v5, s91
	v_and_b32_e32 v102, 0xffff0000, v102
	v_or_b32_sdwa v103, v103, v3 dst_sel:DWORD dst_unused:UNUSED_PAD src0_sel:DWORD src1_sel:WORD_1
	v_mul_f32_e32 v3, v98, v98
	v_or_b32_sdwa v102, v102, v5 dst_sel:DWORD dst_unused:UNUSED_PAD src0_sel:DWORD src1_sel:WORD_1
	v_fmamk_f32 v3, v3, 0xbdd2d3e2, v220
	v_mul_f32_e32 v5, v99, v99
	v_pk_fma_f32 v[100:101], v[28:29], v[100:101], v[32:33]
	v_mul_f32_e32 v3, v98, v3
	v_fmamk_f32 v5, v5, 0xbdd2d3e2, v220
	v_pk_fma_f32 v[100:101], v[24:25], v[96:97], v[100:101]
	v_pk_fma_f32 v[96:97], v[28:29], v[96:97], v[32:33]
	v_exp_f32_e32 v3, v3
	v_mul_f32_e32 v5, v99, v5
	v_pk_fma_f32 v[100:101], v[20:21], v[80:81], v[100:101]
	v_pk_fma_f32 v[80:81], v[24:25], v[80:81], v[96:97]
	v_exp_f32_e32 v5, v5
	v_pk_fma_f32 v[80:81], v[20:21], v[84:85], v[80:81]
	v_pk_fma_f32 v[84:85], v[10:11], v[90:91], v[34:35]
	v_pk_fma_f32 v[94:95], v[26:27], v[94:95], v[30:31]
	v_pk_fma_f32 v[84:85], v[14:15], v[74:75], v[84:85]
	v_pk_fma_f32 v[74:75], v[10:11], v[74:75], v[34:35]
	v_add_f32_e32 v3, 1.0, v3
	v_pk_fma_f32 v[74:75], v[14:15], v[86:87], v[74:75]
	v_pk_fma_f32 v[78:79], v[22:23], v[78:79], v[94:95]
	v_pk_fma_f32 v[70:71], v[6:7], v[70:71], v[74:75]
	v_rcp_f32_e32 v74, v3
	v_add_f32_e32 v3, 1.0, v5
	v_mul_f32_e32 v5, v100, v100
	v_pk_fma_f32 v[78:79], v[18:19], v[82:83], v[78:79]
	v_pk_fma_f32 v[82:83], v[12:13], v[92:93], v[36:37]
	v_fmamk_f32 v5, v5, 0xbdd2d3e2, v220
	v_mul_f32_e32 v75, v101, v101
	v_pk_fma_f32 v[82:83], v[16:17], v[76:77], v[82:83]
	v_pk_fma_f32 v[76:77], v[12:13], v[76:77], v[36:37]
	v_mul_f32_e32 v5, v100, v5
	v_fmamk_f32 v75, v75, 0xbdd2d3e2, v220
	v_pk_fma_f32 v[76:77], v[16:17], v[88:89], v[76:77]
	v_exp_f32_e32 v5, v5
	v_mul_f32_e32 v75, v101, v75
	v_pk_fma_f32 v[72:73], v[8:9], v[72:73], v[76:77]
	v_exp_f32_e32 v77, v75
	v_rcp_f32_e32 v76, v3
	v_add_f32_e32 v3, 1.0, v5
	v_rcp_f32_e32 v75, v3
	v_add_f32_e32 v3, 1.0, v77
	v_rcp_f32_e32 v77, v3
	v_pk_fma_f32 v[82:83], v[8:9], v[88:89], v[82:83]
	v_pk_fma_f32 v[84:85], v[6:7], v[86:87], v[84:85]
	v_mov_b32_e32 v86, v98
	v_mov_b32_e32 v87, v100
	v_pk_mul_f32 v[74:75], v[86:87], v[74:75]
	v_mov_b32_e32 v86, v84
	v_mov_b32_e32 v87, v82
	v_mov_b32_e32 v100, v99
	v_pk_mul_f32 v[74:75], v[86:87], v[74:75]
	v_pk_mul_f32 v[76:77], v[100:101], v[76:77]
	v_mov_b32_e32 v82, v85
	v_pk_mul_f32 v[76:77], v[82:83], v[76:77]
	v_and_b32_sdwa v5, v74, v218 dst_sel:DWORD dst_unused:UNUSED_PAD src0_sel:WORD_1 src1_sel:DWORD
	v_and_b32_sdwa v3, v75, v218 dst_sel:DWORD dst_unused:UNUSED_PAD src0_sel:WORD_1 src1_sel:DWORD
	v_add3_u32 v5, v74, v5, s91
	v_and_b32_sdwa v74, v77, v218 dst_sel:DWORD dst_unused:UNUSED_PAD src0_sel:WORD_1 src1_sel:DWORD
	v_add3_u32 v3, v75, v3, s91
	v_and_b32_sdwa v75, v76, v218 dst_sel:DWORD dst_unused:UNUSED_PAD src0_sel:WORD_1 src1_sel:DWORD
	v_add3_u32 v74, v77, v74, s91
	v_add3_u32 v75, v76, v75, s91
	v_and_b32_e32 v74, 0xffff0000, v74
	v_and_b32_e32 v76, 0xffff0000, v75
	v_or_b32_sdwa v75, v74, v3 dst_sel:DWORD dst_unused:UNUSED_PAD src0_sel:DWORD src1_sel:WORD_1
	v_mul_f32_e32 v3, v78, v78
	v_or_b32_sdwa v74, v76, v5 dst_sel:DWORD dst_unused:UNUSED_PAD src0_sel:DWORD src1_sel:WORD_1
	v_fmamk_f32 v3, v3, 0xbdd2d3e2, v220
	v_mul_f32_e32 v5, v79, v79
	v_mul_f32_e32 v3, v78, v3
	v_fmamk_f32 v5, v5, 0xbdd2d3e2, v220
	v_exp_f32_e32 v3, v3
	v_mul_f32_e32 v5, v79, v5
	v_exp_f32_e32 v5, v5
	v_lshl_add_u64 v[76:77], v[158:159], 0, s[46:47]
	v_add_f32_e32 v3, 1.0, v3
	global_store_dwordx2 v[76:77], v[74:75], off
	v_rcp_f32_e32 v74, v3
	v_add_f32_e32 v3, 1.0, v5
	v_mul_f32_e32 v5, v80, v80
	v_fmamk_f32 v5, v5, 0xbdd2d3e2, v220
	v_mul_f32_e32 v75, v81, v81
	v_mul_f32_e32 v5, v80, v5
	v_fmamk_f32 v75, v75, 0xbdd2d3e2, v220
	v_exp_f32_e32 v5, v5
	v_mul_f32_e32 v75, v81, v75
	v_exp_f32_e32 v77, v75
	v_rcp_f32_e32 v76, v3
	v_add_f32_e32 v3, 1.0, v5
	v_rcp_f32_e32 v75, v3
	v_add_f32_e32 v3, 1.0, v77
	v_rcp_f32_e32 v77, v3
	v_mov_b32_e32 v82, v78
	v_mov_b32_e32 v83, v80
	v_mov_b32_e32 v80, v79
	v_pk_mul_f32 v[74:75], v[82:83], v[74:75]
	v_mov_b32_e32 v83, v72
	v_pk_mul_f32 v[76:77], v[80:81], v[76:77]
	v_mov_b32_e32 v72, v71
	v_mov_b32_e32 v82, v70
	v_pk_mul_f32 v[70:71], v[72:73], v[76:77]
	v_pk_mul_f32 v[74:75], v[82:83], v[74:75]
	v_and_b32_sdwa v72, v71, v218 dst_sel:DWORD dst_unused:UNUSED_PAD src0_sel:WORD_1 src1_sel:DWORD
	v_pk_fma_f32 v[62:63], v[26:27], v[62:63], v[30:31]
	v_and_b32_sdwa v3, v75, v218 dst_sel:DWORD dst_unused:UNUSED_PAD src0_sel:WORD_1 src1_sel:DWORD
	v_and_b32_sdwa v73, v70, v218 dst_sel:DWORD dst_unused:UNUSED_PAD src0_sel:WORD_1 src1_sel:DWORD
	v_add3_u32 v71, v71, v72, s91
	v_pk_fma_f32 v[62:63], v[22:23], v[54:55], v[62:63]
	v_and_b32_sdwa v5, v74, v218 dst_sel:DWORD dst_unused:UNUSED_PAD src0_sel:WORD_1 src1_sel:DWORD
	v_add3_u32 v3, v75, v3, s91
	v_add3_u32 v70, v70, v73, s91
	v_and_b32_e32 v71, 0xffff0000, v71
	v_pk_fma_f32 v[62:63], v[18:19], v[46:47], v[62:63]
	v_add3_u32 v5, v74, v5, s91
	v_and_b32_e32 v70, 0xffff0000, v70
	v_or_b32_sdwa v71, v71, v3 dst_sel:DWORD dst_unused:UNUSED_PAD src0_sel:DWORD src1_sel:WORD_1
	v_mul_f32_e32 v3, v62, v62
	v_or_b32_sdwa v70, v70, v5 dst_sel:DWORD dst_unused:UNUSED_PAD src0_sel:DWORD src1_sel:WORD_1
	v_fmamk_f32 v3, v3, 0xbdd2d3e2, v220
	v_mul_f32_e32 v5, v63, v63
	v_mul_f32_e32 v3, v62, v3
	v_fmamk_f32 v5, v5, 0xbdd2d3e2, v220
	v_exp_f32_e32 v3, v3
	v_mul_f32_e32 v5, v63, v5
	v_pk_fma_f32 v[64:65], v[28:29], v[64:65], v[32:33]
	v_pk_fma_f32 v[28:29], v[28:29], v[56:57], v[32:33]
	v_exp_f32_e32 v5, v5
	v_pk_fma_f32 v[64:65], v[24:25], v[56:57], v[64:65]
	v_pk_fma_f32 v[24:25], v[24:25], v[48:49], v[28:29]
	v_pk_fma_f32 v[64:65], v[20:21], v[48:49], v[64:65]
	v_pk_fma_f32 v[20:21], v[20:21], v[52:53], v[24:25]
	v_pk_fma_f32 v[24:25], v[10:11], v[66:67], v[34:35]
	v_pk_fma_f32 v[10:11], v[10:11], v[42:43], v[34:35]
	v_pk_fma_f32 v[24:25], v[14:15], v[42:43], v[24:25]
	v_pk_fma_f32 v[10:11], v[14:15], v[58:59], v[10:11]
	v_add_f32_e32 v3, 1.0, v3
	v_pk_fma_f32 v[26:27], v[26:27], v[54:55], v[30:31]
	v_pk_fma_f32 v[24:25], v[6:7], v[58:59], v[24:25]
	v_pk_fma_f32 v[6:7], v[6:7], v[38:39], v[10:11]
	v_rcp_f32_e32 v10, v3
	v_add_f32_e32 v3, 1.0, v5
	v_mul_f32_e32 v5, v64, v64
	v_pk_fma_f32 v[22:23], v[22:23], v[46:47], v[26:27]
	v_fmamk_f32 v5, v5, 0xbdd2d3e2, v220
	v_mul_f32_e32 v11, v65, v65
	v_pk_fma_f32 v[18:19], v[18:19], v[50:51], v[22:23]
	v_pk_fma_f32 v[22:23], v[12:13], v[68:69], v[36:37]
	v_pk_fma_f32 v[12:13], v[12:13], v[44:45], v[36:37]
	v_mul_f32_e32 v5, v64, v5
	v_fmamk_f32 v11, v11, 0xbdd2d3e2, v220
	v_pk_fma_f32 v[22:23], v[16:17], v[44:45], v[22:23]
	v_pk_fma_f32 v[12:13], v[16:17], v[60:61], v[12:13]
	v_exp_f32_e32 v5, v5
	v_mul_f32_e32 v11, v65, v11
	v_pk_fma_f32 v[22:23], v[8:9], v[60:61], v[22:23]
	v_pk_fma_f32 v[8:9], v[8:9], v[40:41], v[12:13]
	v_exp_f32_e32 v13, v11
	v_rcp_f32_e32 v12, v3
	v_add_f32_e32 v3, 1.0, v5
	v_rcp_f32_e32 v11, v3
	v_add_f32_e32 v3, 1.0, v13
	v_rcp_f32_e32 v13, v3
	v_mov_b32_e32 v14, v62
	v_mov_b32_e32 v15, v64
	v_pk_mul_f32 v[10:11], v[14:15], v[10:11]
	v_mov_b32_e32 v14, v24
	v_mov_b32_e32 v15, v22
	v_mov_b32_e32 v64, v63
	v_pk_mul_f32 v[10:11], v[14:15], v[10:11]
	v_pk_mul_f32 v[12:13], v[64:65], v[12:13]
	v_mov_b32_e32 v22, v25
	v_pk_mul_f32 v[12:13], v[22:23], v[12:13]
	v_and_b32_sdwa v5, v10, v218 dst_sel:DWORD dst_unused:UNUSED_PAD src0_sel:WORD_1 src1_sel:DWORD
	v_and_b32_sdwa v3, v11, v218 dst_sel:DWORD dst_unused:UNUSED_PAD src0_sel:WORD_1 src1_sel:DWORD
	v_add3_u32 v5, v10, v5, s91
	v_and_b32_sdwa v10, v13, v218 dst_sel:DWORD dst_unused:UNUSED_PAD src0_sel:WORD_1 src1_sel:DWORD
	v_add3_u32 v3, v11, v3, s91
	v_and_b32_sdwa v11, v12, v218 dst_sel:DWORD dst_unused:UNUSED_PAD src0_sel:WORD_1 src1_sel:DWORD
	v_add3_u32 v10, v13, v10, s91
	v_add3_u32 v11, v12, v11, s91
	v_and_b32_e32 v10, 0xffff0000, v10
	v_and_b32_e32 v12, 0xffff0000, v11
	v_or_b32_sdwa v11, v10, v3 dst_sel:DWORD dst_unused:UNUSED_PAD src0_sel:DWORD src1_sel:WORD_1
	v_mul_f32_e32 v3, v18, v18
	v_or_b32_sdwa v10, v12, v5 dst_sel:DWORD dst_unused:UNUSED_PAD src0_sel:DWORD src1_sel:WORD_1
	v_fmamk_f32 v3, v3, 0xbdd2d3e2, v220
	v_mul_f32_e32 v5, v19, v19
	v_mul_f32_e32 v3, v18, v3
	v_fmamk_f32 v5, v5, 0xbdd2d3e2, v220
	v_exp_f32_e32 v3, v3
	v_mul_f32_e32 v5, v19, v5
	v_exp_f32_e32 v5, v5
	v_lshl_add_u64 v[12:13], v[158:159], 0, s[50:51]
	v_add_f32_e32 v3, 1.0, v3
	global_store_dwordx2 v[12:13], v[10:11], off
	v_rcp_f32_e32 v10, v3
	v_add_f32_e32 v3, 1.0, v5
	v_mul_f32_e32 v5, v20, v20
	v_fmamk_f32 v5, v5, 0xbdd2d3e2, v220
	v_mul_f32_e32 v11, v21, v21
	v_mul_f32_e32 v5, v20, v5
	v_fmamk_f32 v11, v11, 0xbdd2d3e2, v220
	v_exp_f32_e32 v5, v5
	v_mul_f32_e32 v11, v21, v11
	v_exp_f32_e32 v13, v11
	v_rcp_f32_e32 v12, v3
	v_add_f32_e32 v3, 1.0, v5
	v_rcp_f32_e32 v11, v3
	v_add_f32_e32 v3, 1.0, v13
	v_rcp_f32_e32 v13, v3
	v_mov_b32_e32 v14, v18
	v_mov_b32_e32 v15, v20
	v_mov_b32_e32 v20, v19
	v_pk_mul_f32 v[10:11], v[14:15], v[10:11]
	v_mov_b32_e32 v15, v8
	v_pk_mul_f32 v[12:13], v[20:21], v[12:13]
	v_mov_b32_e32 v8, v7
	v_mov_b32_e32 v14, v6
	v_pk_mul_f32 v[6:7], v[8:9], v[12:13]
	v_pk_mul_f32 v[10:11], v[14:15], v[10:11]
	v_and_b32_sdwa v8, v7, v218 dst_sel:DWORD dst_unused:UNUSED_PAD src0_sel:WORD_1 src1_sel:DWORD
	v_and_b32_sdwa v9, v6, v218 dst_sel:DWORD dst_unused:UNUSED_PAD src0_sel:WORD_1 src1_sel:DWORD
	v_and_b32_sdwa v3, v11, v218 dst_sel:DWORD dst_unused:UNUSED_PAD src0_sel:WORD_1 src1_sel:DWORD
	v_and_b32_sdwa v5, v10, v218 dst_sel:DWORD dst_unused:UNUSED_PAD src0_sel:WORD_1 src1_sel:DWORD
	v_add3_u32 v7, v7, v8, s91
	v_add3_u32 v6, v6, v9, s91
	v_add_u32_e32 v0, 0x200, v0
	v_add3_u32 v5, v10, v5, s91
	v_add3_u32 v3, v11, v3, s91
	v_and_b32_e32 v7, 0xffff0000, v7
	v_and_b32_e32 v6, 0xffff0000, v6
	v_cmp_lt_i32_e32 vcc, s66, v0
	v_lshl_add_u64 v[136:137], v[158:159], 0, s[40:41]
	v_lshl_add_u64 v[104:105], v[158:159], 0, s[44:45]
	v_lshl_add_u64 v[72:73], v[158:159], 0, s[48:49]
	v_or_b32_sdwa v7, v7, v3 dst_sel:DWORD dst_unused:UNUSED_PAD src0_sel:DWORD src1_sel:WORD_1
	v_or_b32_sdwa v6, v6, v5 dst_sel:DWORD dst_unused:UNUSED_PAD src0_sel:DWORD src1_sel:WORD_1
	v_lshl_add_u64 v[8:9], v[158:159], 0, s[52:53]
	s_or_b64 s[54:55], vcc, s[54:55]
	v_add_u32_e32 v2, 0x800, v2
	global_store_dwordx2 v[136:137], v[134:135], off
	global_store_dwordx2 v[104:105], v[102:103], off
	global_store_dwordx2 v[72:73], v[70:71], off
	global_store_dwordx2 v[8:9], v[6:7], off
	s_andn2_b64 exec, exec, s[54:55]
	s_cbranch_execz .LBB0_294
.LBB0_290:
	v_ashrrev_i32_e32 v3, 31, v2
	v_lshlrev_b64 v[38:39], 2, v[2:3]
	v_lshl_add_u64 v[6:7], s[16:17], 0, v[38:39]
	v_lshl_add_u64 v[8:9], s[20:21], 0, v[38:39]
	global_load_dwordx4 v[26:29], v[6:7], off
	global_load_dwordx4 v[22:25], v[8:9], off
	v_add_co_u32_e32 v6, vcc, 0x3000, v6
	v_lshl_add_u64 v[34:35], s[22:23], 0, v[38:39]
	s_nop 0
	v_addc_co_u32_e32 v7, vcc, 0, v7, vcc
	v_add_co_u32_e32 v8, vcc, 0x3000, v8
	v_lshl_add_u64 v[36:37], s[18:19], 0, v[38:39]
	s_nop 0
	v_addc_co_u32_e32 v9, vcc, 0, v9, vcc
	global_load_dwordx4 v[18:21], v[34:35], off
	global_load_dwordx4 v[30:33], v[36:37], off
	global_load_dwordx4 v[10:13], v[6:7], off
	global_load_dwordx4 v[14:17], v[8:9], off
	v_add_co_u32_e32 v6, vcc, 0x3000, v34
	v_cndmask_b32_e64 v5, 0, 1, s[26:27]
	s_nop 0
	v_addc_co_u32_e32 v7, vcc, 0, v35, vcc
	v_add_co_u32_e32 v34, vcc, 0x3000, v36
	global_load_dwordx4 v[6:9], v[6:7], off
	s_nop 0
	v_addc_co_u32_e32 v35, vcc, 0, v37, vcc
	global_load_dwordx4 v[34:37], v[34:35], off
	v_mov_b32_e32 v134, 0
	v_cmp_ne_u32_e64 s[4:5], 1, v5
	s_andn2_b64 vcc, exec, s[26:27]
	v_mov_b32_e32 v142, 0
	v_mov_b32_e32 v143, 0
	v_mov_b32_e32 v144, 0
	v_mov_b32_e32 v145, 0
	v_mov_b32_e32 v138, 0
	v_mov_b32_e32 v139, 0
	v_mov_b32_e32 v140, 0
	v_mov_b32_e32 v141, 0
	s_cbranch_vccnz .LBB0_292
	v_lshl_add_u64 v[40:41], v[2:3], 2, s[28:29]
	v_add_co_u32_e32 v42, vcc, 0xc000, v40
	s_nop 1
	v_addc_co_u32_e32 v43, vcc, 0, v41, vcc
	v_add_co_u32_e32 v40, vcc, 0x12000, v40
	s_nop 1
	v_addc_co_u32_e32 v41, vcc, 0, v41, vcc
	global_load_dwordx4 v[142:145], v[42:43], off
	global_load_dwordx4 v[138:141], v[40:41], off
.LBB0_292:
	v_lshl_add_u64 v[40:41], v[2:3], 2, s[30:31]
	v_add_co_u32_e32 v42, vcc, 0x6000, v40
	v_mov_b32_e32 v135, 0
	s_nop 0
	v_addc_co_u32_e32 v43, vcc, 0, v41, vcc
	global_load_dwordx4 v[154:157], v[40:41], off
	global_load_dwordx4 v[150:153], v[42:43], off
	s_and_b64 vcc, exec, s[4:5]
	v_mov_b32_e32 v136, 0
	v_mov_b32_e32 v137, 0
	v_mov_b32_e32 v146, 0
	v_mov_b32_e32 v147, 0
	v_mov_b32_e32 v148, 0
	v_mov_b32_e32 v149, 0
	s_cbranch_vccnz .LBB0_289
	v_add_u32_e32 v42, 0xc00, v2
	v_ashrrev_i32_e32 v43, 31, v42
	v_lshl_add_u64 v[42:43], v[42:43], 2, s[28:29]
	v_add_co_u32_e32 v44, vcc, 0xc000, v42
	s_nop 1
	v_addc_co_u32_e32 v45, vcc, 0, v43, vcc
	v_add_co_u32_e32 v42, vcc, 0x12000, v42
	s_nop 1
	v_addc_co_u32_e32 v43, vcc, 0, v43, vcc
	global_load_dwordx4 v[134:137], v[44:45], off
	global_load_dwordx4 v[146:149], v[42:43], off
	s_branch .LBB0_289

.LBB0_323:
	v_lshl_or_b32 v231, s59, 8, v214
	v_lshl_add_u32 v210, s60, 8, v212
	v_lshlrev_b32_e32 v0, 1, v231
	v_lshl_add_u32 v0, v210, 11, v0
	v_lshl_add_u64 v[86:87], s[22:23], 0, v[0:1]
	global_load_dwordx4 v[194:197], v[86:87], off
	v_or_b32_e32 v86, 0x100, v0
	v_mov_b32_e32 v87, v1
	v_lshl_add_u64 v[86:87], s[22:23], 0, v[86:87]
	global_load_dwordx4 v[190:193], v[86:87], off
	v_add_u32_e32 v86, 0x8000, v0
	v_mov_b32_e32 v87, v1
	v_lshl_add_u64 v[86:87], s[22:23], 0, v[86:87]
	global_load_dwordx4 v[186:189], v[86:87], off
	v_add_u32_e32 v86, 0x8100, v0
	v_mov_b32_e32 v87, v1
	v_lshl_add_u64 v[86:87], s[22:23], 0, v[86:87]
	global_load_dwordx4 v[182:185], v[86:87], off
	v_add_u32_e32 v86, 0x10000, v0
	v_mov_b32_e32 v87, v1
	v_lshl_add_u64 v[86:87], s[22:23], 0, v[86:87]
	global_load_dwordx4 v[178:181], v[86:87], off
	v_add_u32_e32 v86, 0x10100, v0
	v_mov_b32_e32 v87, v1
	v_lshl_add_u64 v[86:87], s[22:23], 0, v[86:87]
	global_load_dwordx4 v[174:177], v[86:87], off
	v_add_u32_e32 v86, 0x18000, v0
	v_mov_b32_e32 v87, v1
	v_lshl_add_u64 v[86:87], s[22:23], 0, v[86:87]
	global_load_dwordx4 v[170:173], v[86:87], off
	v_add_u32_e32 v86, 0x18100, v0
	v_mov_b32_e32 v87, v1
	v_lshl_add_u64 v[86:87], s[22:23], 0, v[86:87]
	global_load_dwordx4 v[158:161], v[86:87], off
	v_add_u32_e32 v86, 0x40000, v0
	v_mov_b32_e32 v87, v1
	v_lshl_add_u64 v[86:87], s[22:23], 0, v[86:87]
	global_load_dwordx4 v[154:157], v[86:87], off
	v_add_u32_e32 v86, 0x40100, v0
	v_mov_b32_e32 v87, v1
	v_lshl_add_u64 v[86:87], s[22:23], 0, v[86:87]
	global_load_dwordx4 v[150:153], v[86:87], off
	v_add_u32_e32 v86, 0x48000, v0
	v_mov_b32_e32 v87, v1
	v_lshl_add_u64 v[86:87], s[22:23], 0, v[86:87]
	global_load_dwordx4 v[138:141], v[86:87], off
	v_add_u32_e32 v86, 0x48100, v0
	v_mov_b32_e32 v87, v1
	v_lshl_add_u64 v[86:87], s[22:23], 0, v[86:87]
	global_load_dwordx4 v[134:137], v[86:87], off
	v_add_u32_e32 v86, 0x50000, v0
	v_mov_b32_e32 v87, v1
	v_lshl_add_u64 v[86:87], s[22:23], 0, v[86:87]
	global_load_dwordx4 v[118:121], v[86:87], off
	v_add_u32_e32 v86, 0x50100, v0
	v_mov_b32_e32 v87, v1
	v_lshl_add_u64 v[86:87], s[22:23], 0, v[86:87]
	global_load_dwordx4 v[110:113], v[86:87], off
	v_add_u32_e32 v86, 0x58000, v0
	v_mov_b32_e32 v87, v1
	v_lshl_add_u64 v[86:87], s[22:23], 0, v[86:87]
	v_add_u32_e32 v0, 0x58100, v0
	global_load_dwordx4 v[98:101], v[86:87], off
	v_lshl_add_u64 v[86:87], s[22:23], 0, v[0:1]
	global_load_dwordx4 v[86:89], v[86:87], off
	v_lshl_add_u32 v211, v210, 10, v231
	v_lshlrev_b32_e32 v0, 1, v211
	s_andn2_b64 vcc, exec, s[28:29]
	s_waitcnt vmcnt(0) lgkmcnt(0)
	v_lshlrev_b32_e32 v232, 16, v194
	v_and_b32_e32 v233, 0xffff0000, v194
	v_lshlrev_b32_e32 v194, 16, v195
	v_and_b32_e32 v195, 0xffff0000, v195
	v_pk_add_f32 v[168:169], v[168:169], v[194:195]
	v_lshlrev_b32_e32 v194, 16, v196
	v_and_b32_e32 v195, 0xffff0000, v196
	v_pk_add_f32 v[166:167], v[166:167], v[232:233]
	v_pk_add_f32 v[162:163], v[162:163], v[194:195]
	v_lshlrev_b32_e32 v194, 16, v197
	v_and_b32_e32 v195, 0xffff0000, v197
	v_lshl_add_u64 v[232:233], s[22:23], 0, v[0:1]
	v_cndmask_b32_e64 v0, 0, 1, s[28:29]
	v_pk_add_f32 v[164:165], v[164:165], v[194:195]
	v_cmp_ne_u32_e64 s[10:11], 1, v0
	v_cvt_pk_bf16_f32 v194, v166, v167
	v_cvt_pk_bf16_f32 v195, v168, v169
	v_cvt_pk_bf16_f32 v196, v162, v163
	v_cvt_pk_bf16_f32 v197, v164, v165
	global_store_dwordx4 v[232:233], v[194:197], off
	s_cbranch_vccnz .LBB0_325
	v_lshlrev_b32_e32 v0, 2, v211
	v_lshl_add_u64 v[194:195], s[16:17], 0, v[0:1]
	global_store_dwordx4 v[194:195], v[166:169], off
	global_store_dwordx4 v[194:195], v[162:165], off offset:16
.LBB0_325:
	s_nop 0
	v_lshlrev_b32_e32 v194, 16, v190
	v_and_b32_e32 v195, 0xffff0000, v190
	v_lshlrev_b32_e32 v190, 16, v191
	v_and_b32_e32 v191, 0xffff0000, v191
	v_pk_add_f32 v[148:149], v[148:149], v[190:191]
	v_lshlrev_b32_e32 v190, 16, v192
	v_and_b32_e32 v191, 0xffff0000, v192
	v_pk_add_f32 v[142:143], v[142:143], v[190:191]
	v_lshlrev_b32_e32 v190, 16, v193
	v_and_b32_e32 v191, 0xffff0000, v193
	v_pk_add_f32 v[144:145], v[144:145], v[190:191]
	v_or_b32_e32 v190, 0x80, v211
	v_lshlrev_b32_e32 v0, 1, v190
	v_pk_add_f32 v[146:147], v[146:147], v[194:195]
	v_lshl_add_u64 v[196:197], s[22:23], 0, v[0:1]
	s_and_b64 vcc, exec, s[10:11]
	v_cvt_pk_bf16_f32 v192, v146, v147
	v_cvt_pk_bf16_f32 v193, v148, v149
	v_cvt_pk_bf16_f32 v194, v142, v143
	v_cvt_pk_bf16_f32 v195, v144, v145
	global_store_dwordx4 v[196:197], v[192:195], off
	s_cbranch_vccnz .LBB0_327
	v_lshlrev_b32_e32 v190, 2, v190
	v_mov_b32_e32 v191, v1
	v_or_b32_e32 v0, 16, v190
	v_lshl_add_u64 v[190:191], s[16:17], 0, v[190:191]
	v_lshl_add_u64 v[192:193], s[16:17], 0, v[0:1]
	global_store_dwordx4 v[190:191], v[146:149], off
	global_store_dwordx4 v[192:193], v[142:145], off
.LBB0_327:
	s_nop 1
	v_pk_mul_f32 v[142:143], v[142:143], v[142:143]
	v_pk_mul_f32 v[144:145], v[144:145], v[144:145]
	v_pk_mul_f32 v[146:147], v[146:147], v[146:147]
	v_pk_mul_f32 v[148:149], v[148:149], v[148:149]
	v_add_f32_e32 v0, v144, v145
	v_add_f32_e32 v142, v142, v143
	v_add_f32_e32 v0, v142, v0
	v_add_f32_e32 v142, v148, v149
	v_add_f32_e32 v143, v146, v147
	v_pk_mul_f32 v[162:163], v[162:163], v[162:163]
	v_pk_mul_f32 v[164:165], v[164:165], v[164:165]
	v_add_f32_e32 v142, v143, v142
	v_pk_mul_f32 v[166:167], v[166:167], v[166:167]
	v_pk_mul_f32 v[168:169], v[168:169], v[168:169]
	v_add_f32_e32 v0, v142, v0
	v_add_f32_e32 v142, v164, v165
	v_add_f32_e32 v143, v162, v163
	v_add_f32_e32 v142, v143, v142
	v_add_f32_e32 v143, v168, v169
	v_add_f32_e32 v144, v166, v167
	v_add_f32_e32 v143, v144, v143
	v_add_f32_e32 v142, v143, v142
	v_add_f32_e32 v0, v142, v0
	ds_bpermute_b32 v142, v215, v0
	s_lshl_b32 s36, s59, 2
	s_ashr_i32 s37, s36, 31
	s_waitcnt lgkmcnt(0)
	v_add_f32_e32 v0, v0, v142
	ds_bpermute_b32 v142, v216, v0
	s_and_saveexec_b64 s[38:39], s[6:7]
	s_cbranch_execz .LBB0_329
	v_mov_b32_e32 v211, v1
	v_lshlrev_b64 v[144:145], 6, v[210:211]
	v_lshl_add_u64 v[144:145], s[24:25], 0, v[144:145]
	v_lshl_add_u64 v[144:145], s[36:37], 2, v[144:145]
	s_lshl_b32 s94, s49, 2
	v_lshl_add_u64 v[144:145], v[144:145], 0, s[94:95]
	s_waitcnt lgkmcnt(0)
	v_add_f32_e32 v0, v0, v142
	global_store_dword v[144:145], v0, off
.LBB0_329:
	s_or_b64 exec, exec, s[38:39]
	v_lshlrev_b32_e32 v144, 16, v186
	v_and_b32_e32 v145, 0xffff0000, v186
	s_waitcnt lgkmcnt(0)
	v_or_b32_e32 v142, 16, v210
	v_pk_add_f32 v[130:131], v[130:131], v[144:145]
	v_lshlrev_b32_e32 v144, 16, v187
	v_and_b32_e32 v145, 0xffff0000, v187
	v_lshl_add_u32 v143, v142, 10, v231
	v_pk_add_f32 v[132:133], v[132:133], v[144:145]
	v_lshlrev_b32_e32 v144, 16, v188
	v_and_b32_e32 v145, 0xffff0000, v188
	v_pk_add_f32 v[126:127], v[126:127], v[144:145]
	v_lshlrev_b32_e32 v144, 16, v189
	v_and_b32_e32 v145, 0xffff0000, v189
	v_lshlrev_b32_e32 v0, 1, v143
	v_pk_add_f32 v[128:129], v[128:129], v[144:145]
	v_lshl_add_u64 v[148:149], s[22:23], 0, v[0:1]
	s_and_b64 vcc, exec, s[10:11]
	v_cvt_pk_bf16_f32 v144, v130, v131
	v_cvt_pk_bf16_f32 v145, v132, v133
	v_cvt_pk_bf16_f32 v146, v126, v127
	v_cvt_pk_bf16_f32 v147, v128, v129
	global_store_dwordx4 v[148:149], v[144:147], off
	s_cbranch_vccnz .LBB0_331
	v_lshlrev_b32_e32 v0, 2, v143
	v_lshl_add_u64 v[144:145], s[16:17], 0, v[0:1]
	global_store_dwordx4 v[144:145], v[130:133], off
	global_store_dwordx4 v[144:145], v[126:129], off offset:16
.LBB0_331:
	s_nop 0
	v_lshlrev_b32_e32 v144, 16, v182
	v_and_b32_e32 v145, 0xffff0000, v182
	v_pk_add_f32 v[122:123], v[122:123], v[144:145]
	v_lshlrev_b32_e32 v144, 16, v183
	v_and_b32_e32 v145, 0xffff0000, v183
	v_pk_add_f32 v[124:125], v[124:125], v[144:145]
	v_lshlrev_b32_e32 v144, 16, v184
	v_and_b32_e32 v145, 0xffff0000, v184
	v_or_b32_e32 v143, 0x80, v143
	v_pk_add_f32 v[114:115], v[114:115], v[144:145]
	v_lshlrev_b32_e32 v144, 16, v185
	v_and_b32_e32 v145, 0xffff0000, v185
	v_lshlrev_b32_e32 v0, 1, v143
	v_pk_add_f32 v[116:117], v[116:117], v[144:145]
	v_lshl_add_u64 v[148:149], s[22:23], 0, v[0:1]
	s_and_b64 vcc, exec, s[10:11]
	v_cvt_pk_bf16_f32 v144, v122, v123
	v_cvt_pk_bf16_f32 v145, v124, v125
	v_cvt_pk_bf16_f32 v146, v114, v115
	v_cvt_pk_bf16_f32 v147, v116, v117
	global_store_dwordx4 v[148:149], v[144:147], off
	s_cbranch_vccnz .LBB0_333
	s_nop 0
	v_lshlrev_b32_e32 v144, 2, v143
	v_mov_b32_e32 v145, v1
	v_or_b32_e32 v0, 16, v144
	v_lshl_add_u64 v[144:145], s[16:17], 0, v[144:145]
	v_lshl_add_u64 v[146:147], s[16:17], 0, v[0:1]
	global_store_dwordx4 v[144:145], v[122:125], off
	global_store_dwordx4 v[146:147], v[114:117], off
.LBB0_333:
	s_nop 1
	v_pk_mul_f32 v[114:115], v[114:115], v[114:115]
	v_pk_mul_f32 v[116:117], v[116:117], v[116:117]
	v_pk_mul_f32 v[122:123], v[122:123], v[122:123]
	v_pk_mul_f32 v[124:125], v[124:125], v[124:125]
	v_add_f32_e32 v0, v116, v117
	v_add_f32_e32 v114, v114, v115
	v_add_f32_e32 v0, v114, v0
	v_add_f32_e32 v114, v124, v125
	v_add_f32_e32 v115, v122, v123
	v_pk_mul_f32 v[126:127], v[126:127], v[126:127]
	v_pk_mul_f32 v[128:129], v[128:129], v[128:129]
	v_add_f32_e32 v114, v115, v114
	v_pk_mul_f32 v[130:131], v[130:131], v[130:131]
	v_pk_mul_f32 v[132:133], v[132:133], v[132:133]
	v_add_f32_e32 v0, v114, v0
	v_add_f32_e32 v114, v128, v129
	v_add_f32_e32 v115, v126, v127
	v_add_f32_e32 v114, v115, v114
	v_add_f32_e32 v115, v132, v133
	v_add_f32_e32 v116, v130, v131
	v_add_f32_e32 v115, v116, v115
	v_add_f32_e32 v114, v115, v114
	v_add_f32_e32 v0, v114, v0
	ds_bpermute_b32 v114, v215, v0
	s_waitcnt lgkmcnt(0)
	v_add_f32_e32 v0, v0, v114
	ds_bpermute_b32 v114, v216, v0
	s_and_saveexec_b64 s[38:39], s[6:7]
	s_cbranch_execz .LBB0_335
	v_mov_b32_e32 v143, v1
	v_lshlrev_b64 v[116:117], 6, v[142:143]
	v_lshl_add_u64 v[116:117], s[24:25], 0, v[116:117]
	v_lshl_add_u64 v[116:117], s[36:37], 2, v[116:117]
	s_lshl_b32 s94, s49, 2
	v_lshl_add_u64 v[116:117], v[116:117], 0, s[94:95]
	s_waitcnt lgkmcnt(0)
	v_add_f32_e32 v0, v0, v114
	global_store_dword v[116:117], v0, off
.LBB0_335:
	s_or_b64 exec, exec, s[38:39]
	v_lshlrev_b32_e32 v116, 16, v178
	v_and_b32_e32 v117, 0xffff0000, v178
	s_waitcnt lgkmcnt(0)
	v_or_b32_e32 v114, 32, v210
	v_pk_add_f32 v[106:107], v[106:107], v[116:117]
	v_lshlrev_b32_e32 v116, 16, v179
	v_and_b32_e32 v117, 0xffff0000, v179
	v_lshl_add_u32 v115, v114, 10, v231
	v_pk_add_f32 v[108:109], v[108:109], v[116:117]
	v_lshlrev_b32_e32 v116, 16, v180
	v_and_b32_e32 v117, 0xffff0000, v180
	v_pk_add_f32 v[102:103], v[102:103], v[116:117]
	v_lshlrev_b32_e32 v116, 16, v181
	v_and_b32_e32 v117, 0xffff0000, v181
	v_lshlrev_b32_e32 v0, 1, v115
	v_pk_add_f32 v[104:105], v[104:105], v[116:117]
	v_lshl_add_u64 v[116:117], s[22:23], 0, v[0:1]
	s_and_b64 vcc, exec, s[10:11]
	v_cvt_pk_bf16_f32 v122, v106, v107
	v_cvt_pk_bf16_f32 v123, v108, v109
	v_cvt_pk_bf16_f32 v124, v102, v103
	v_cvt_pk_bf16_f32 v125, v104, v105
	global_store_dwordx4 v[116:117], v[122:125], off
	s_cbranch_vccnz .LBB0_337
	v_lshlrev_b32_e32 v0, 2, v115
	v_lshl_add_u64 v[116:117], s[16:17], 0, v[0:1]
	global_store_dwordx4 v[116:117], v[106:109], off
	global_store_dwordx4 v[116:117], v[102:105], off offset:16
.LBB0_337:
	v_lshlrev_b32_e32 v116, 16, v174
	v_and_b32_e32 v117, 0xffff0000, v174
	v_pk_add_f32 v[94:95], v[94:95], v[116:117]
	v_lshlrev_b32_e32 v116, 16, v175
	v_and_b32_e32 v117, 0xffff0000, v175
	v_pk_add_f32 v[96:97], v[96:97], v[116:117]
	v_lshlrev_b32_e32 v116, 16, v176
	v_and_b32_e32 v117, 0xffff0000, v176
	v_or_b32_e32 v115, 0x80, v115
	v_pk_add_f32 v[90:91], v[90:91], v[116:117]
	v_lshlrev_b32_e32 v116, 16, v177
	v_and_b32_e32 v117, 0xffff0000, v177
	v_lshlrev_b32_e32 v0, 1, v115
	v_pk_add_f32 v[92:93], v[92:93], v[116:117]
	v_lshl_add_u64 v[116:117], s[22:23], 0, v[0:1]
	s_and_b64 vcc, exec, s[10:11]
	v_cvt_pk_bf16_f32 v122, v94, v95
	v_cvt_pk_bf16_f32 v123, v96, v97
	v_cvt_pk_bf16_f32 v124, v90, v91
	v_cvt_pk_bf16_f32 v125, v92, v93
	global_store_dwordx4 v[116:117], v[122:125], off
	s_cbranch_vccnz .LBB0_339
	v_lshlrev_b32_e32 v116, 2, v115
	v_mov_b32_e32 v117, v1
	v_or_b32_e32 v0, 16, v116
	v_lshl_add_u64 v[116:117], s[16:17], 0, v[116:117]
	v_lshl_add_u64 v[122:123], s[16:17], 0, v[0:1]
	global_store_dwordx4 v[116:117], v[94:97], off
	global_store_dwordx4 v[122:123], v[90:93], off
.LBB0_339:
	s_nop 1
	v_pk_mul_f32 v[90:91], v[90:91], v[90:91]
	v_pk_mul_f32 v[92:93], v[92:93], v[92:93]
	v_pk_mul_f32 v[94:95], v[94:95], v[94:95]
	v_pk_mul_f32 v[96:97], v[96:97], v[96:97]
	v_add_f32_e32 v0, v92, v93
	v_add_f32_e32 v90, v90, v91
	v_add_f32_e32 v0, v90, v0
	v_add_f32_e32 v90, v96, v97
	v_add_f32_e32 v91, v94, v95
	v_pk_mul_f32 v[102:103], v[102:103], v[102:103]
	v_pk_mul_f32 v[104:105], v[104:105], v[104:105]
	v_add_f32_e32 v90, v91, v90
	v_pk_mul_f32 v[106:107], v[106:107], v[106:107]
	v_pk_mul_f32 v[108:109], v[108:109], v[108:109]
	v_add_f32_e32 v0, v90, v0
	v_add_f32_e32 v90, v104, v105
	v_add_f32_e32 v91, v102, v103
	v_add_f32_e32 v90, v91, v90
	v_add_f32_e32 v91, v108, v109
	v_add_f32_e32 v92, v106, v107
	v_add_f32_e32 v91, v92, v91
	v_add_f32_e32 v90, v91, v90
	v_add_f32_e32 v0, v90, v0
	ds_bpermute_b32 v90, v215, v0
	s_waitcnt lgkmcnt(0)
	v_add_f32_e32 v0, v0, v90
	ds_bpermute_b32 v90, v216, v0
	s_and_saveexec_b64 s[38:39], s[6:7]
	s_cbranch_execz .LBB0_341
	v_mov_b32_e32 v115, v1
	v_lshlrev_b64 v[92:93], 6, v[114:115]
	v_lshl_add_u64 v[92:93], s[24:25], 0, v[92:93]
	v_lshl_add_u64 v[92:93], s[36:37], 2, v[92:93]
	s_lshl_b32 s94, s49, 2
	v_lshl_add_u64 v[92:93], v[92:93], 0, s[94:95]
	s_waitcnt lgkmcnt(0)
	v_add_f32_e32 v0, v0, v90
	global_store_dword v[92:93], v0, off
.LBB0_341:
	s_or_b64 exec, exec, s[38:39]
	v_lshlrev_b32_e32 v92, 16, v170
	v_and_b32_e32 v93, 0xffff0000, v170
	s_waitcnt lgkmcnt(0)
	v_or_b32_e32 v90, 48, v210
	v_pk_add_f32 v[82:83], v[82:83], v[92:93]
	v_lshlrev_b32_e32 v92, 16, v171
	v_and_b32_e32 v93, 0xffff0000, v171
	v_lshl_add_u32 v91, v90, 10, v231
	v_pk_add_f32 v[84:85], v[84:85], v[92:93]
	v_lshlrev_b32_e32 v92, 16, v172
	v_and_b32_e32 v93, 0xffff0000, v172
	v_pk_add_f32 v[78:79], v[78:79], v[92:93]
	v_lshlrev_b32_e32 v92, 16, v173
	v_and_b32_e32 v93, 0xffff0000, v173
	v_lshlrev_b32_e32 v0, 1, v91
	v_pk_add_f32 v[80:81], v[80:81], v[92:93]
	v_lshl_add_u64 v[96:97], s[22:23], 0, v[0:1]
	s_and_b64 vcc, exec, s[10:11]
	v_cvt_pk_bf16_f32 v92, v82, v83
	v_cvt_pk_bf16_f32 v93, v84, v85
	v_cvt_pk_bf16_f32 v94, v78, v79
	v_cvt_pk_bf16_f32 v95, v80, v81
	global_store_dwordx4 v[96:97], v[92:95], off
	s_cbranch_vccnz .LBB0_343
	v_lshlrev_b32_e32 v0, 2, v91
	v_lshl_add_u64 v[92:93], s[16:17], 0, v[0:1]
	global_store_dwordx4 v[92:93], v[82:85], off
	global_store_dwordx4 v[92:93], v[78:81], off offset:16
.LBB0_343:
	s_nop 0
	v_lshlrev_b32_e32 v92, 16, v158
	v_and_b32_e32 v93, 0xffff0000, v158
	v_pk_add_f32 v[74:75], v[74:75], v[92:93]
	v_lshlrev_b32_e32 v92, 16, v159
	v_and_b32_e32 v93, 0xffff0000, v159
	v_pk_add_f32 v[76:77], v[76:77], v[92:93]
	v_lshlrev_b32_e32 v92, 16, v160
	v_and_b32_e32 v93, 0xffff0000, v160
	v_or_b32_e32 v91, 0x80, v91
	v_pk_add_f32 v[70:71], v[70:71], v[92:93]
	v_lshlrev_b32_e32 v92, 16, v161
	v_and_b32_e32 v93, 0xffff0000, v161
	v_lshlrev_b32_e32 v0, 1, v91
	v_pk_add_f32 v[72:73], v[72:73], v[92:93]
	v_lshl_add_u64 v[96:97], s[22:23], 0, v[0:1]
	s_and_b64 vcc, exec, s[10:11]
	v_cvt_pk_bf16_f32 v92, v74, v75
	v_cvt_pk_bf16_f32 v93, v76, v77
	v_cvt_pk_bf16_f32 v94, v70, v71
	v_cvt_pk_bf16_f32 v95, v72, v73
	global_store_dwordx4 v[96:97], v[92:95], off
	s_cbranch_vccnz .LBB0_345
	s_nop 0
	v_lshlrev_b32_e32 v92, 2, v91
	v_mov_b32_e32 v93, v1
	v_or_b32_e32 v0, 16, v92
	v_lshl_add_u64 v[92:93], s[16:17], 0, v[92:93]
	v_lshl_add_u64 v[94:95], s[16:17], 0, v[0:1]
	global_store_dwordx4 v[92:93], v[74:77], off
	global_store_dwordx4 v[94:95], v[70:73], off
.LBB0_345:
	s_nop 1
	v_pk_mul_f32 v[70:71], v[70:71], v[70:71]
	v_pk_mul_f32 v[72:73], v[72:73], v[72:73]
	v_pk_mul_f32 v[74:75], v[74:75], v[74:75]
	v_pk_mul_f32 v[76:77], v[76:77], v[76:77]
	v_add_f32_e32 v0, v72, v73
	v_add_f32_e32 v70, v70, v71
	v_add_f32_e32 v0, v70, v0
	v_add_f32_e32 v70, v76, v77
	v_add_f32_e32 v71, v74, v75
	v_pk_mul_f32 v[78:79], v[78:79], v[78:79]
	v_pk_mul_f32 v[80:81], v[80:81], v[80:81]
	v_add_f32_e32 v70, v71, v70
	v_pk_mul_f32 v[82:83], v[82:83], v[82:83]
	v_pk_mul_f32 v[84:85], v[84:85], v[84:85]
	v_add_f32_e32 v0, v70, v0
	v_add_f32_e32 v70, v80, v81
	v_add_f32_e32 v71, v78, v79
	v_add_f32_e32 v70, v71, v70
	v_add_f32_e32 v71, v84, v85
	v_add_f32_e32 v72, v82, v83
	v_add_f32_e32 v71, v72, v71
	v_add_f32_e32 v70, v71, v70
	v_add_f32_e32 v0, v70, v0
	ds_bpermute_b32 v70, v215, v0
	s_waitcnt lgkmcnt(0)
	v_add_f32_e32 v0, v0, v70
	ds_bpermute_b32 v70, v216, v0
	s_and_saveexec_b64 s[38:39], s[6:7]
	s_cbranch_execz .LBB0_347
	v_mov_b32_e32 v91, v1
	v_lshlrev_b64 v[72:73], 6, v[90:91]
	v_lshl_add_u64 v[72:73], s[24:25], 0, v[72:73]
	v_lshl_add_u64 v[72:73], s[36:37], 2, v[72:73]
	s_lshl_b32 s94, s49, 2
	v_lshl_add_u64 v[72:73], v[72:73], 0, s[94:95]
	s_waitcnt lgkmcnt(0)
	v_add_f32_e32 v0, v0, v70
	global_store_dword v[72:73], v0, off
.LBB0_347:
	s_or_b64 exec, exec, s[38:39]
	v_lshlrev_b32_e32 v72, 16, v154
	v_and_b32_e32 v73, 0xffff0000, v154
	s_waitcnt lgkmcnt(0)
	v_add_u32_e32 v70, 0x80, v210
	v_pk_add_f32 v[66:67], v[66:67], v[72:73]
	v_lshlrev_b32_e32 v72, 16, v155
	v_and_b32_e32 v73, 0xffff0000, v155
	v_lshl_add_u32 v71, v70, 10, v231
	v_pk_add_f32 v[68:69], v[68:69], v[72:73]
	v_lshlrev_b32_e32 v72, 16, v156
	v_and_b32_e32 v73, 0xffff0000, v156
	v_pk_add_f32 v[62:63], v[62:63], v[72:73]
	v_lshlrev_b32_e32 v72, 16, v157
	v_and_b32_e32 v73, 0xffff0000, v157
	v_lshlrev_b32_e32 v0, 1, v71
	v_pk_add_f32 v[64:65], v[64:65], v[72:73]
	v_lshl_add_u64 v[76:77], s[22:23], 0, v[0:1]
	s_and_b64 vcc, exec, s[10:11]
	v_cvt_pk_bf16_f32 v72, v66, v67
	v_cvt_pk_bf16_f32 v73, v68, v69
	v_cvt_pk_bf16_f32 v74, v62, v63
	v_cvt_pk_bf16_f32 v75, v64, v65
	global_store_dwordx4 v[76:77], v[72:75], off
	s_cbranch_vccnz .LBB0_349
	v_lshlrev_b32_e32 v0, 2, v71
	v_lshl_add_u64 v[72:73], s[16:17], 0, v[0:1]
	global_store_dwordx4 v[72:73], v[66:69], off
	global_store_dwordx4 v[72:73], v[62:65], off offset:16
.LBB0_349:
	s_nop 0
	v_lshlrev_b32_e32 v72, 16, v150
	v_and_b32_e32 v73, 0xffff0000, v150
	v_pk_add_f32 v[58:59], v[58:59], v[72:73]
	v_lshlrev_b32_e32 v72, 16, v151
	v_and_b32_e32 v73, 0xffff0000, v151
	v_pk_add_f32 v[60:61], v[60:61], v[72:73]
	v_lshlrev_b32_e32 v72, 16, v152
	v_and_b32_e32 v73, 0xffff0000, v152
	v_or_b32_e32 v71, 0x80, v71
	v_pk_add_f32 v[54:55], v[54:55], v[72:73]
	v_lshlrev_b32_e32 v72, 16, v153
	v_and_b32_e32 v73, 0xffff0000, v153
	v_lshlrev_b32_e32 v0, 1, v71
	v_pk_add_f32 v[56:57], v[56:57], v[72:73]
	v_lshl_add_u64 v[76:77], s[22:23], 0, v[0:1]
	s_and_b64 vcc, exec, s[10:11]
	v_cvt_pk_bf16_f32 v72, v58, v59
	v_cvt_pk_bf16_f32 v73, v60, v61
	v_cvt_pk_bf16_f32 v74, v54, v55
	v_cvt_pk_bf16_f32 v75, v56, v57
	global_store_dwordx4 v[76:77], v[72:75], off
	s_cbranch_vccnz .LBB0_351
	s_nop 0
	v_lshlrev_b32_e32 v72, 2, v71
	v_mov_b32_e32 v73, v1
	v_or_b32_e32 v0, 16, v72
	v_lshl_add_u64 v[72:73], s[16:17], 0, v[72:73]
	v_lshl_add_u64 v[74:75], s[16:17], 0, v[0:1]
	global_store_dwordx4 v[72:73], v[58:61], off
	global_store_dwordx4 v[74:75], v[54:57], off
.LBB0_351:
	s_nop 1
	v_pk_mul_f32 v[54:55], v[54:55], v[54:55]
	v_pk_mul_f32 v[56:57], v[56:57], v[56:57]
	v_pk_mul_f32 v[58:59], v[58:59], v[58:59]
	v_pk_mul_f32 v[60:61], v[60:61], v[60:61]
	v_add_f32_e32 v0, v56, v57
	v_add_f32_e32 v54, v54, v55
	v_add_f32_e32 v0, v54, v0
	v_add_f32_e32 v54, v60, v61
	v_add_f32_e32 v55, v58, v59
	v_pk_mul_f32 v[62:63], v[62:63], v[62:63]
	v_pk_mul_f32 v[64:65], v[64:65], v[64:65]
	v_add_f32_e32 v54, v55, v54
	v_pk_mul_f32 v[66:67], v[66:67], v[66:67]
	v_pk_mul_f32 v[68:69], v[68:69], v[68:69]
	v_add_f32_e32 v0, v54, v0
	v_add_f32_e32 v54, v64, v65
	v_add_f32_e32 v55, v62, v63
	v_add_f32_e32 v54, v55, v54
	v_add_f32_e32 v55, v68, v69
	v_add_f32_e32 v56, v66, v67
	v_add_f32_e32 v55, v56, v55
	v_add_f32_e32 v54, v55, v54
	v_add_f32_e32 v0, v54, v0
	ds_bpermute_b32 v54, v215, v0
	s_waitcnt lgkmcnt(0)
	v_add_f32_e32 v0, v0, v54
	ds_bpermute_b32 v54, v216, v0
	s_and_saveexec_b64 s[38:39], s[6:7]
	s_cbranch_execz .LBB0_353
	v_mov_b32_e32 v71, v1
	v_lshlrev_b64 v[56:57], 6, v[70:71]
	v_lshl_add_u64 v[56:57], s[24:25], 0, v[56:57]
	v_lshl_add_u64 v[56:57], s[36:37], 2, v[56:57]
	s_lshl_b32 s94, s49, 2
	v_lshl_add_u64 v[56:57], v[56:57], 0, s[94:95]
	s_waitcnt lgkmcnt(0)
	v_add_f32_e32 v0, v0, v54
	global_store_dword v[56:57], v0, off
.LBB0_353:
	s_or_b64 exec, exec, s[38:39]
	v_lshlrev_b32_e32 v56, 16, v138
	v_and_b32_e32 v57, 0xffff0000, v138
	s_waitcnt lgkmcnt(0)
	v_add_u32_e32 v54, 0x90, v210
	v_pk_add_f32 v[50:51], v[50:51], v[56:57]
	v_lshlrev_b32_e32 v56, 16, v139
	v_and_b32_e32 v57, 0xffff0000, v139
	v_lshl_add_u32 v55, v54, 10, v231
	v_pk_add_f32 v[52:53], v[52:53], v[56:57]
	v_lshlrev_b32_e32 v56, 16, v140
	v_and_b32_e32 v57, 0xffff0000, v140
	v_pk_add_f32 v[46:47], v[46:47], v[56:57]
	v_lshlrev_b32_e32 v56, 16, v141
	v_and_b32_e32 v57, 0xffff0000, v141
	v_lshlrev_b32_e32 v0, 1, v55
	v_pk_add_f32 v[48:49], v[48:49], v[56:57]
	v_lshl_add_u64 v[60:61], s[22:23], 0, v[0:1]
	s_and_b64 vcc, exec, s[10:11]
	v_cvt_pk_bf16_f32 v56, v50, v51
	v_cvt_pk_bf16_f32 v57, v52, v53
	v_cvt_pk_bf16_f32 v58, v46, v47
	v_cvt_pk_bf16_f32 v59, v48, v49
	global_store_dwordx4 v[60:61], v[56:59], off
	s_cbranch_vccnz .LBB0_355
	v_lshlrev_b32_e32 v0, 2, v55
	v_lshl_add_u64 v[56:57], s[16:17], 0, v[0:1]
	global_store_dwordx4 v[56:57], v[50:53], off
	global_store_dwordx4 v[56:57], v[46:49], off offset:16
.LBB0_355:
	s_nop 0
	v_lshlrev_b32_e32 v56, 16, v134
	v_and_b32_e32 v57, 0xffff0000, v134
	v_pk_add_f32 v[42:43], v[42:43], v[56:57]
	v_lshlrev_b32_e32 v56, 16, v135
	v_and_b32_e32 v57, 0xffff0000, v135
	v_pk_add_f32 v[44:45], v[44:45], v[56:57]
	v_lshlrev_b32_e32 v56, 16, v136
	v_and_b32_e32 v57, 0xffff0000, v136
	v_or_b32_e32 v55, 0x80, v55
	v_pk_add_f32 v[38:39], v[38:39], v[56:57]
	v_lshlrev_b32_e32 v56, 16, v137
	v_and_b32_e32 v57, 0xffff0000, v137
	v_lshlrev_b32_e32 v0, 1, v55
	v_pk_add_f32 v[40:41], v[40:41], v[56:57]
	v_lshl_add_u64 v[60:61], s[22:23], 0, v[0:1]
	s_and_b64 vcc, exec, s[10:11]
	v_cvt_pk_bf16_f32 v56, v42, v43
	v_cvt_pk_bf16_f32 v57, v44, v45
	v_cvt_pk_bf16_f32 v58, v38, v39
	v_cvt_pk_bf16_f32 v59, v40, v41
	global_store_dwordx4 v[60:61], v[56:59], off
	s_cbranch_vccnz .LBB0_357
	s_nop 0
	v_lshlrev_b32_e32 v56, 2, v55
	v_mov_b32_e32 v57, v1
	v_or_b32_e32 v0, 16, v56
	v_lshl_add_u64 v[56:57], s[16:17], 0, v[56:57]
	v_lshl_add_u64 v[58:59], s[16:17], 0, v[0:1]
	global_store_dwordx4 v[56:57], v[42:45], off
	global_store_dwordx4 v[58:59], v[38:41], off
.LBB0_357:
	s_nop 1
	v_pk_mul_f32 v[38:39], v[38:39], v[38:39]
	v_pk_mul_f32 v[40:41], v[40:41], v[40:41]
	v_pk_mul_f32 v[42:43], v[42:43], v[42:43]
	v_pk_mul_f32 v[44:45], v[44:45], v[44:45]
	v_add_f32_e32 v0, v40, v41
	v_add_f32_e32 v38, v38, v39
	v_add_f32_e32 v0, v38, v0
	v_add_f32_e32 v38, v44, v45
	v_add_f32_e32 v39, v42, v43
	v_pk_mul_f32 v[46:47], v[46:47], v[46:47]
	v_pk_mul_f32 v[48:49], v[48:49], v[48:49]
	v_add_f32_e32 v38, v39, v38
	v_pk_mul_f32 v[50:51], v[50:51], v[50:51]
	v_pk_mul_f32 v[52:53], v[52:53], v[52:53]
	v_add_f32_e32 v0, v38, v0
	v_add_f32_e32 v38, v48, v49
	v_add_f32_e32 v39, v46, v47
	v_add_f32_e32 v38, v39, v38
	v_add_f32_e32 v39, v52, v53
	v_add_f32_e32 v40, v50, v51
	v_add_f32_e32 v39, v40, v39
	v_add_f32_e32 v38, v39, v38
	v_add_f32_e32 v0, v38, v0
	ds_bpermute_b32 v38, v215, v0
	s_waitcnt lgkmcnt(0)
	v_add_f32_e32 v0, v0, v38
	ds_bpermute_b32 v38, v216, v0
	s_and_saveexec_b64 s[38:39], s[6:7]
	s_cbranch_execz .LBB0_359
	v_mov_b32_e32 v55, v1
	v_lshlrev_b64 v[40:41], 6, v[54:55]
	v_lshl_add_u64 v[40:41], s[24:25], 0, v[40:41]
	v_lshl_add_u64 v[40:41], s[36:37], 2, v[40:41]
	s_lshl_b32 s94, s49, 2
	v_lshl_add_u64 v[40:41], v[40:41], 0, s[94:95]
	s_waitcnt lgkmcnt(0)
	v_add_f32_e32 v0, v0, v38
	global_store_dword v[40:41], v0, off
.LBB0_359:
	s_or_b64 exec, exec, s[38:39]
	v_lshlrev_b32_e32 v40, 16, v118
	v_and_b32_e32 v41, 0xffff0000, v118
	s_waitcnt lgkmcnt(0)
	v_add_u32_e32 v38, 0xa0, v210
	v_pk_add_f32 v[34:35], v[34:35], v[40:41]
	v_lshlrev_b32_e32 v40, 16, v119
	v_and_b32_e32 v41, 0xffff0000, v119
	v_lshl_add_u32 v39, v38, 10, v231
	v_pk_add_f32 v[36:37], v[36:37], v[40:41]
	v_lshlrev_b32_e32 v40, 16, v120
	v_and_b32_e32 v41, 0xffff0000, v120
	v_pk_add_f32 v[30:31], v[30:31], v[40:41]
	v_lshlrev_b32_e32 v40, 16, v121
	v_and_b32_e32 v41, 0xffff0000, v121
	v_lshlrev_b32_e32 v0, 1, v39
	v_pk_add_f32 v[32:33], v[32:33], v[40:41]
	v_lshl_add_u64 v[44:45], s[22:23], 0, v[0:1]
	s_and_b64 vcc, exec, s[10:11]
	v_cvt_pk_bf16_f32 v40, v34, v35
	v_cvt_pk_bf16_f32 v41, v36, v37
	v_cvt_pk_bf16_f32 v42, v30, v31
	v_cvt_pk_bf16_f32 v43, v32, v33
	global_store_dwordx4 v[44:45], v[40:43], off
	s_cbranch_vccnz .LBB0_361
	v_lshlrev_b32_e32 v0, 2, v39
	v_lshl_add_u64 v[40:41], s[16:17], 0, v[0:1]
	global_store_dwordx4 v[40:41], v[34:37], off
	global_store_dwordx4 v[40:41], v[30:33], off offset:16
.LBB0_361:
	s_nop 0
	v_lshlrev_b32_e32 v40, 16, v110
	v_and_b32_e32 v41, 0xffff0000, v110
	v_pk_add_f32 v[26:27], v[26:27], v[40:41]
	v_lshlrev_b32_e32 v40, 16, v111
	v_and_b32_e32 v41, 0xffff0000, v111
	v_pk_add_f32 v[28:29], v[28:29], v[40:41]
	v_lshlrev_b32_e32 v40, 16, v112
	v_and_b32_e32 v41, 0xffff0000, v112
	v_or_b32_e32 v39, 0x80, v39
	v_pk_add_f32 v[22:23], v[22:23], v[40:41]
	v_lshlrev_b32_e32 v40, 16, v113
	v_and_b32_e32 v41, 0xffff0000, v113
	v_lshlrev_b32_e32 v0, 1, v39
	v_pk_add_f32 v[24:25], v[24:25], v[40:41]
	v_lshl_add_u64 v[44:45], s[22:23], 0, v[0:1]
	s_and_b64 vcc, exec, s[10:11]
	v_cvt_pk_bf16_f32 v40, v26, v27
	v_cvt_pk_bf16_f32 v41, v28, v29
	v_cvt_pk_bf16_f32 v42, v22, v23
	v_cvt_pk_bf16_f32 v43, v24, v25
	global_store_dwordx4 v[44:45], v[40:43], off
	s_cbranch_vccnz .LBB0_363
	s_nop 0
	v_lshlrev_b32_e32 v40, 2, v39
	v_mov_b32_e32 v41, v1
	v_or_b32_e32 v0, 16, v40
	v_lshl_add_u64 v[40:41], s[16:17], 0, v[40:41]
	v_lshl_add_u64 v[42:43], s[16:17], 0, v[0:1]
	global_store_dwordx4 v[40:41], v[26:29], off
	global_store_dwordx4 v[42:43], v[22:25], off
.LBB0_363:
	s_nop 1
	v_pk_mul_f32 v[22:23], v[22:23], v[22:23]
	v_pk_mul_f32 v[24:25], v[24:25], v[24:25]
	v_pk_mul_f32 v[26:27], v[26:27], v[26:27]
	v_pk_mul_f32 v[28:29], v[28:29], v[28:29]
	v_add_f32_e32 v0, v24, v25
	v_add_f32_e32 v22, v22, v23
	v_add_f32_e32 v0, v22, v0
	v_add_f32_e32 v22, v28, v29
	v_add_f32_e32 v23, v26, v27
	v_pk_mul_f32 v[30:31], v[30:31], v[30:31]
	v_pk_mul_f32 v[32:33], v[32:33], v[32:33]
	v_add_f32_e32 v22, v23, v22
	v_pk_mul_f32 v[34:35], v[34:35], v[34:35]
	v_pk_mul_f32 v[36:37], v[36:37], v[36:37]
	v_add_f32_e32 v0, v22, v0
	v_add_f32_e32 v22, v32, v33
	v_add_f32_e32 v23, v30, v31
	v_add_f32_e32 v22, v23, v22
	v_add_f32_e32 v23, v36, v37
	v_add_f32_e32 v24, v34, v35
	v_add_f32_e32 v23, v24, v23
	v_add_f32_e32 v22, v23, v22
	v_add_f32_e32 v0, v22, v0
	ds_bpermute_b32 v22, v215, v0
	s_waitcnt lgkmcnt(0)
	v_add_f32_e32 v0, v0, v22
	ds_bpermute_b32 v22, v216, v0
	s_and_saveexec_b64 s[38:39], s[6:7]
	s_cbranch_execz .LBB0_365
	v_mov_b32_e32 v39, v1
	v_lshlrev_b64 v[24:25], 6, v[38:39]
	v_lshl_add_u64 v[24:25], s[24:25], 0, v[24:25]
	v_lshl_add_u64 v[24:25], s[36:37], 2, v[24:25]
	s_lshl_b32 s94, s49, 2
	v_lshl_add_u64 v[24:25], v[24:25], 0, s[94:95]
	s_waitcnt lgkmcnt(0)
	v_add_f32_e32 v0, v0, v22
	global_store_dword v[24:25], v0, off
.LBB0_365:
	s_or_b64 exec, exec, s[38:39]
	v_lshlrev_b32_e32 v24, 16, v98
	v_and_b32_e32 v25, 0xffff0000, v98
	s_waitcnt lgkmcnt(0)
	v_add_u32_e32 v22, 0xb0, v210
	v_pk_add_f32 v[18:19], v[18:19], v[24:25]
	v_lshlrev_b32_e32 v24, 16, v99
	v_and_b32_e32 v25, 0xffff0000, v99
	v_lshl_add_u32 v23, v22, 10, v231
	v_pk_add_f32 v[20:21], v[20:21], v[24:25]
	v_lshlrev_b32_e32 v24, 16, v100
	v_and_b32_e32 v25, 0xffff0000, v100
	v_pk_add_f32 v[14:15], v[14:15], v[24:25]
	v_lshlrev_b32_e32 v24, 16, v101
	v_and_b32_e32 v25, 0xffff0000, v101
	v_lshlrev_b32_e32 v0, 1, v23
	v_pk_add_f32 v[16:17], v[16:17], v[24:25]
	v_lshl_add_u64 v[28:29], s[22:23], 0, v[0:1]
	s_and_b64 vcc, exec, s[10:11]
	v_cvt_pk_bf16_f32 v24, v18, v19
	v_cvt_pk_bf16_f32 v25, v20, v21
	v_cvt_pk_bf16_f32 v26, v14, v15
	v_cvt_pk_bf16_f32 v27, v16, v17
	global_store_dwordx4 v[28:29], v[24:27], off
	s_cbranch_vccnz .LBB0_367
	v_lshlrev_b32_e32 v0, 2, v23
	v_lshl_add_u64 v[24:25], s[16:17], 0, v[0:1]
	global_store_dwordx4 v[24:25], v[18:21], off
	global_store_dwordx4 v[24:25], v[14:17], off offset:16
.LBB0_367:
	s_nop 0
	v_lshlrev_b32_e32 v24, 16, v86
	v_and_b32_e32 v25, 0xffff0000, v86
	v_pk_add_f32 v[10:11], v[10:11], v[24:25]
	v_lshlrev_b32_e32 v24, 16, v87
	v_and_b32_e32 v25, 0xffff0000, v87
	v_pk_add_f32 v[12:13], v[12:13], v[24:25]
	v_lshlrev_b32_e32 v24, 16, v88
	v_and_b32_e32 v25, 0xffff0000, v88
	v_or_b32_e32 v23, 0x80, v23
	v_pk_add_f32 v[6:7], v[6:7], v[24:25]
	v_lshlrev_b32_e32 v24, 16, v89
	v_and_b32_e32 v25, 0xffff0000, v89
	v_lshlrev_b32_e32 v0, 1, v23
	v_pk_add_f32 v[8:9], v[8:9], v[24:25]
	v_lshl_add_u64 v[28:29], s[22:23], 0, v[0:1]
	s_and_b64 vcc, exec, s[10:11]
	v_cvt_pk_bf16_f32 v24, v10, v11
	v_cvt_pk_bf16_f32 v25, v12, v13
	v_cvt_pk_bf16_f32 v26, v6, v7
	v_cvt_pk_bf16_f32 v27, v8, v9
	global_store_dwordx4 v[28:29], v[24:27], off
	s_cbranch_vccnz .LBB0_369
	s_nop 0
	v_lshlrev_b32_e32 v24, 2, v23
	v_mov_b32_e32 v25, v1
	v_or_b32_e32 v0, 16, v24
	v_lshl_add_u64 v[24:25], s[16:17], 0, v[24:25]
	v_lshl_add_u64 v[26:27], s[16:17], 0, v[0:1]
	global_store_dwordx4 v[24:25], v[10:13], off
	global_store_dwordx4 v[26:27], v[6:9], off
.LBB0_369:
	s_nop 1
	v_pk_mul_f32 v[6:7], v[6:7], v[6:7]
	v_pk_mul_f32 v[8:9], v[8:9], v[8:9]
	v_pk_mul_f32 v[10:11], v[10:11], v[10:11]
	v_pk_mul_f32 v[12:13], v[12:13], v[12:13]
	v_add_f32_e32 v0, v8, v9
	v_add_f32_e32 v6, v6, v7
	v_add_f32_e32 v0, v6, v0
	v_add_f32_e32 v6, v12, v13
	v_add_f32_e32 v7, v10, v11
	v_pk_mul_f32 v[14:15], v[14:15], v[14:15]
	v_pk_mul_f32 v[16:17], v[16:17], v[16:17]
	v_add_f32_e32 v6, v7, v6
	v_pk_mul_f32 v[18:19], v[18:19], v[18:19]
	v_pk_mul_f32 v[20:21], v[20:21], v[20:21]
	v_add_f32_e32 v0, v6, v0
	v_add_f32_e32 v6, v16, v17
	v_add_f32_e32 v7, v14, v15
	v_add_f32_e32 v6, v7, v6
	v_add_f32_e32 v7, v20, v21
	v_add_f32_e32 v8, v18, v19
	v_add_f32_e32 v7, v8, v7
	v_add_f32_e32 v6, v7, v6
	v_add_f32_e32 v0, v6, v0
	ds_bpermute_b32 v6, v215, v0
	s_waitcnt lgkmcnt(0)
	v_add_f32_e32 v0, v0, v6
	ds_bpermute_b32 v6, v216, v0
	s_and_saveexec_b64 s[10:11], s[6:7]
	s_cbranch_execz .LBB0_371
	v_mov_b32_e32 v23, v1
	v_lshlrev_b64 v[8:9], 6, v[22:23]
	v_lshl_add_u64 v[8:9], s[24:25], 0, v[8:9]
	v_lshl_add_u64 v[8:9], s[36:37], 2, v[8:9]
	s_lshl_b32 s94, s49, 2
	v_lshl_add_u64 v[8:9], v[8:9], 0, s[94:95]
	s_waitcnt lgkmcnt(0)
	v_add_f32_e32 v0, v0, v6
	global_store_dword v[8:9], v0, off

.LBB0_387:
	s_lshl_b32 s15, s23, 4
	s_and_b32 s15, s15, 0x70
	v_or_b32_e32 v30, s15, v5
	s_lshl_b32 s14, s23, 2
	v_mul_u32_u24_e32 v0, s40, v30
	s_andn2_b32 s14, s14, 31
	s_mov_b64 s[16:17], -1
	s_and_b64 vcc, exec, s[0:1]
	v_lshlrev_b32_e32 v0, 1, v0
	s_cbranch_vccz .LBB0_389
	v_or_b32_e32 v6, s14, v5
	v_mad_i64_i32 v[6:7], s[16:17], v6, s40, 0
	v_lshl_add_u64 v[26:27], v[6:7], 1, v[14:15]
	global_load_dwordx4 v[6:9], v[26:27], off
	v_lshl_add_u64 v[44:45], v[2:3], 0, v[0:1]
	v_lshl_add_u64 v[46:47], v[26:27], 0, s[94:95]
	global_load_dwordx4 v[10:13], v[44:45], off
	global_load_dwordx4 v[22:25], v[46:47], off
	global_load_dwordx4 v[32:35], v[26:27], off offset:64
	global_load_dwordx4 v[36:39], v[44:45], off offset:64
	s_mov_b64 s[16:17], 0
	s_waitcnt vmcnt(0) lgkmcnt(0)
	v_mfma_f32_16x16x32_bf16 v[6:9], v[6:9], v[10:13], 0
	v_mfma_f32_16x16x32_bf16 v[10:13], v[22:25], v[10:13], 0
	global_load_dwordx4 v[22:25], v[46:47], off offset:64
	v_mfma_f32_16x16x32_bf16 v[6:9], v[32:35], v[36:39], v[6:9]
	global_load_dwordx4 v[32:35], v[26:27], off offset:128
	global_load_dwordx4 v[40:43], v[44:45], off offset:128
	s_waitcnt vmcnt(0) lgkmcnt(0)
	v_mfma_f32_16x16x32_bf16 v[10:13], v[22:25], v[36:39], v[10:13]
	global_load_dwordx4 v[22:25], v[46:47], off offset:128
	v_mfma_f32_16x16x32_bf16 v[6:9], v[32:35], v[40:43], v[6:9]
	global_load_dwordx4 v[32:35], v[26:27], off offset:192
	global_load_dwordx4 v[36:39], v[44:45], off offset:192
	s_waitcnt vmcnt(0) lgkmcnt(0)
	v_mfma_f32_16x16x32_bf16 v[6:9], v[32:35], v[36:39], v[6:9]
	v_mfma_f32_16x16x32_bf16 v[10:13], v[22:25], v[40:43], v[10:13]
	global_load_dwordx4 v[22:25], v[46:47], off offset:192
	global_load_dwordx4 v[32:35], v[26:27], off offset:256
	global_load_dwordx4 v[40:43], v[44:45], off offset:256
	s_waitcnt vmcnt(0) lgkmcnt(0)
	v_mfma_f32_16x16x32_bf16 v[6:9], v[32:35], v[40:43], v[6:9]
	v_mfma_f32_16x16x32_bf16 v[10:13], v[22:25], v[36:39], v[10:13]
	global_load_dwordx4 v[22:25], v[46:47], off offset:256
	global_load_dwordx4 v[32:35], v[26:27], off offset:320
	global_load_dwordx4 v[36:39], v[44:45], off offset:320
	s_waitcnt vmcnt(0) lgkmcnt(0)
	v_mfma_f32_16x16x32_bf16 v[6:9], v[32:35], v[36:39], v[6:9]
	v_mfma_f32_16x16x32_bf16 v[10:13], v[22:25], v[40:43], v[10:13]
	global_load_dwordx4 v[22:25], v[46:47], off offset:320
	global_load_dwordx4 v[32:35], v[26:27], off offset:384
	global_load_dwordx4 v[40:43], v[44:45], off offset:384
	s_waitcnt vmcnt(0) lgkmcnt(0)
	v_mfma_f32_16x16x32_bf16 v[6:9], v[32:35], v[40:43], v[6:9]
	v_mfma_f32_16x16x32_bf16 v[10:13], v[22:25], v[36:39], v[10:13]
	global_load_dwordx4 v[22:25], v[46:47], off offset:384
	global_load_dwordx4 v[32:35], v[26:27], off offset:448
	global_load_dwordx4 v[36:39], v[44:45], off offset:448
	s_waitcnt vmcnt(0) lgkmcnt(0)
	v_mfma_f32_16x16x32_bf16 v[6:9], v[32:35], v[36:39], v[6:9]
	v_mfma_f32_16x16x32_bf16 v[10:13], v[22:25], v[40:43], v[10:13]
	global_load_dwordx4 v[22:25], v[46:47], off offset:448
	global_load_dwordx4 v[32:35], v[26:27], off offset:512
	global_load_dwordx4 v[40:43], v[44:45], off offset:512
	s_waitcnt vmcnt(0) lgkmcnt(0)
	v_mfma_f32_16x16x32_bf16 v[6:9], v[32:35], v[40:43], v[6:9]
	v_mfma_f32_16x16x32_bf16 v[10:13], v[22:25], v[36:39], v[10:13]
	global_load_dwordx4 v[22:25], v[46:47], off offset:512
	global_load_dwordx4 v[32:35], v[26:27], off offset:576
	global_load_dwordx4 v[36:39], v[44:45], off offset:576
	s_waitcnt vmcnt(0) lgkmcnt(0)
	v_mfma_f32_16x16x32_bf16 v[6:9], v[32:35], v[36:39], v[6:9]
	v_mfma_f32_16x16x32_bf16 v[10:13], v[22:25], v[40:43], v[10:13]
	global_load_dwordx4 v[22:25], v[46:47], off offset:576
	global_load_dwordx4 v[32:35], v[26:27], off offset:640
	global_load_dwordx4 v[40:43], v[44:45], off offset:640
	s_waitcnt vmcnt(0) lgkmcnt(0)
	v_mfma_f32_16x16x32_bf16 v[6:9], v[32:35], v[40:43], v[6:9]
	global_load_dwordx4 v[32:35], v[26:27], off offset:704
	v_mfma_f32_16x16x32_bf16 v[10:13], v[22:25], v[36:39], v[10:13]
	global_load_dwordx4 v[22:25], v[46:47], off offset:640
	s_waitcnt vmcnt(0) lgkmcnt(0)
	v_mfma_f32_16x16x32_bf16 v[10:13], v[22:25], v[40:43], v[10:13]
	global_load_dwordx4 v[22:25], v[44:45], off offset:704
	s_waitcnt vmcnt(0) lgkmcnt(0)
	v_mfma_f32_16x16x32_bf16 v[6:9], v[32:35], v[22:25], v[6:9]
	global_load_dwordx4 v[32:35], v[46:47], off offset:704
	s_waitcnt vmcnt(0) lgkmcnt(0)
	v_mfma_f32_16x16x32_bf16 v[10:13], v[32:35], v[22:25], v[10:13]

.LBB0_391:
	global_load_dwordx4 v[32:35], v[22:23], off
	global_load_dwordx4 v[36:39], v[26:27], off
	global_load_dwordx4 v[40:43], v[24:25], off
	s_addk_i32 s15, 0x80
	s_cmp_lt_u32 s15, s18
	s_waitcnt vmcnt(0) lgkmcnt(0)
	v_mfma_f32_16x16x32_bf16 v[6:9], v[32:35], v[36:39], v[6:9]
	global_load_dwordx4 v[32:35], v[22:23], off offset:64
	global_load_dwordx4 v[44:47], v[26:27], off offset:64
	v_mfma_f32_16x16x32_bf16 v[10:13], v[40:43], v[36:39], v[10:13]
	global_load_dwordx4 v[36:39], v[24:25], off offset:64
	s_waitcnt vmcnt(0) lgkmcnt(0)
	v_mfma_f32_16x16x32_bf16 v[6:9], v[32:35], v[44:47], v[6:9]
	global_load_dwordx4 v[32:35], v[22:23], off offset:128
	global_load_dwordx4 v[40:43], v[26:27], off offset:128
	v_mfma_f32_16x16x32_bf16 v[10:13], v[36:39], v[44:47], v[10:13]
	global_load_dwordx4 v[36:39], v[24:25], off offset:128
	s_waitcnt vmcnt(0) lgkmcnt(0)
	v_mfma_f32_16x16x32_bf16 v[6:9], v[32:35], v[40:43], v[6:9]
	global_load_dwordx4 v[32:35], v[22:23], off offset:192
	v_lshl_add_u64 v[22:23], v[22:23], 0, s[16:17]
	v_mfma_f32_16x16x32_bf16 v[10:13], v[36:39], v[40:43], v[10:13]
	global_load_dwordx4 v[36:39], v[26:27], off offset:192
	v_lshl_add_u64 v[26:27], v[26:27], 0, s[16:17]
	s_waitcnt vmcnt(0) lgkmcnt(0)
	v_mfma_f32_16x16x32_bf16 v[6:9], v[32:35], v[36:39], v[6:9]
	global_load_dwordx4 v[32:35], v[24:25], off offset:192
	v_lshl_add_u64 v[24:25], v[24:25], 0, s[16:17]
	s_waitcnt vmcnt(0) lgkmcnt(0)
	v_mfma_f32_16x16x32_bf16 v[10:13], v[32:35], v[36:39], v[10:13]
	s_cbranch_scc1 .LBB0_391
.LBB0_392:
	v_add_u32_e32 v0, s19, v17
	s_andn2_b64 vcc, exec, s[12:13]
	s_nop 0
	ds_write_b128 v0, v[6:9]
	s_nop 2
	ds_write_b128 v0, v[10:13] offset:1024
	s_waitcnt lgkmcnt(0)
	s_barrier
	s_cbranch_vccnz .LBB0_386
	ds_read_b128 v[22:25], v17 offset:2048
	v_lshlrev_b32_e32 v0, 10, v30
	s_ashr_i32 s15, s14, 31
	v_lshl_add_u64 v[36:37], v[0:1], 0, s[14:15]
	v_or_b32_e32 v36, v36, v16
	s_waitcnt lgkmcnt(0)
	v_pk_add_f32 v[24:25], v[8:9], v[24:25]
	v_pk_add_f32 v[22:23], v[6:7], v[22:23]
	ds_read_b128 v[6:9], v17 offset:3072
	v_lshlrev_b64 v[38:39], 2, v[36:37]
	v_lshl_add_u64 v[40:41], s[2:3], 0, v[38:39]
	s_waitcnt lgkmcnt(0)
	v_pk_add_f32 v[12:13], v[12:13], v[8:9]
	v_pk_add_f32 v[10:11], v[10:11], v[6:7]
	ds_read_b128 v[6:9], v17 offset:4096
	s_waitcnt lgkmcnt(0)
	v_pk_add_f32 v[24:25], v[24:25], v[8:9]
	v_pk_add_f32 v[22:23], v[22:23], v[6:7]
	ds_read_b128 v[6:9], v17 offset:5120
	s_waitcnt lgkmcnt(0)
	v_pk_add_f32 v[12:13], v[12:13], v[8:9]
	v_pk_add_f32 v[10:11], v[10:11], v[6:7]
	ds_read_b128 v[6:9], v17 offset:6144
	s_waitcnt lgkmcnt(0)
	v_pk_add_f32 v[24:25], v[24:25], v[8:9]
	v_pk_add_f32 v[22:23], v[22:23], v[6:7]
	ds_read_b128 v[6:9], v17 offset:7168
	s_waitcnt lgkmcnt(0)
	v_pk_add_f32 v[12:13], v[12:13], v[8:9]
	v_pk_add_f32 v[10:11], v[10:11], v[6:7]
	ds_read_b128 v[6:9], v17 offset:8192
	s_waitcnt lgkmcnt(0)
	v_pk_add_f32 v[24:25], v[24:25], v[8:9]
	v_pk_add_f32 v[22:23], v[22:23], v[6:7]
	ds_read_b128 v[6:9], v17 offset:9216
	s_waitcnt lgkmcnt(0)
	v_pk_add_f32 v[12:13], v[12:13], v[8:9]
	v_pk_add_f32 v[10:11], v[10:11], v[6:7]
	ds_read_b128 v[6:9], v17 offset:10240
	s_waitcnt lgkmcnt(0)
	v_pk_add_f32 v[24:25], v[24:25], v[8:9]
	v_pk_add_f32 v[22:23], v[22:23], v[6:7]
	ds_read_b128 v[6:9], v17 offset:11264
	s_waitcnt lgkmcnt(0)
	v_pk_add_f32 v[12:13], v[12:13], v[8:9]
	v_pk_add_f32 v[10:11], v[10:11], v[6:7]
	ds_read_b128 v[6:9], v17 offset:12288
	s_waitcnt lgkmcnt(0)
	v_pk_add_f32 v[24:25], v[24:25], v[8:9]
	v_pk_add_f32 v[22:23], v[22:23], v[6:7]
	ds_read_b128 v[6:9], v17 offset:13312
	s_waitcnt lgkmcnt(0)
	v_pk_add_f32 v[12:13], v[12:13], v[8:9]
	v_pk_add_f32 v[10:11], v[10:11], v[6:7]
	ds_read_b128 v[6:9], v17 offset:14336
	s_waitcnt lgkmcnt(0)
	v_pk_add_f32 v[24:25], v[24:25], v[8:9]
	v_pk_add_f32 v[26:27], v[22:23], v[6:7]
	ds_read_b128 v[6:9], v17 offset:15360
	v_or_b32_e32 v22, 16, v36
	v_mov_b32_e32 v23, v37
	s_waitcnt lgkmcnt(0)
	v_pk_add_f32 v[32:33], v[12:13], v[8:9]
	v_pk_add_f32 v[34:35], v[10:11], v[6:7]
	global_load_dwordx4 v[6:9], v[40:41], off
	s_waitcnt vmcnt(0) lgkmcnt(0)
	v_pk_add_f32 v[12:13], v[24:25], v[8:9]
	v_pk_add_f32 v[10:11], v[26:27], v[6:7]
	global_load_dwordx4 v[6:9], v[40:41], off offset:64
	v_lshl_add_u64 v[24:25], s[6:7], 0, v[38:39]
	global_store_dwordx4 v[24:25], v[10:13], off
	v_lshl_add_u64 v[24:25], v[22:23], 2, s[6:7]
	v_and_b32_sdwa v26, v11, v218 dst_sel:DWORD dst_unused:UNUSED_PAD src0_sel:WORD_1 src1_sel:DWORD
	v_and_b32_sdwa v0, v12, v218 dst_sel:DWORD dst_unused:UNUSED_PAD src0_sel:WORD_1 src1_sel:DWORD
	v_add3_u32 v26, v11, v26, s91
	v_add3_u32 v0, v12, v0, s91
	v_and_b32_e32 v26, 0xffff0000, v26
	v_lshl_add_u64 v[22:23], v[22:23], 1, s[8:9]
	s_waitcnt vmcnt(0) lgkmcnt(0)
	v_pk_add_f32 v[8:9], v[32:33], v[8:9]
	v_pk_add_f32 v[6:7], v[34:35], v[6:7]
	global_store_dwordx4 v[24:25], v[6:9], off
	v_and_b32_sdwa v25, v13, v218 dst_sel:DWORD dst_unused:UNUSED_PAD src0_sel:WORD_1 src1_sel:DWORD
	v_and_b32_sdwa v24, v10, v218 dst_sel:DWORD dst_unused:UNUSED_PAD src0_sel:WORD_1 src1_sel:DWORD
	v_add3_u32 v25, v13, v25, s91
	v_add3_u32 v24, v10, v24, s91
	v_and_b32_e32 v25, 0xffff0000, v25
	v_or_b32_sdwa v25, v25, v0 dst_sel:DWORD dst_unused:UNUSED_PAD src0_sel:DWORD src1_sel:WORD_1
	v_or_b32_sdwa v24, v26, v24 dst_sel:DWORD dst_unused:UNUSED_PAD src0_sel:DWORD src1_sel:WORD_1
	v_lshl_add_u64 v[26:27], v[36:37], 1, s[8:9]
	global_store_dwordx2 v[26:27], v[24:25], off
	v_and_b32_sdwa v25, v9, v218 dst_sel:DWORD dst_unused:UNUSED_PAD src0_sel:WORD_1 src1_sel:DWORD
	v_and_b32_sdwa v0, v8, v218 dst_sel:DWORD dst_unused:UNUSED_PAD src0_sel:WORD_1 src1_sel:DWORD
	v_add3_u32 v25, v9, v25, s91
	v_add3_u32 v0, v8, v0, s91
	v_and_b32_sdwa v26, v7, v218 dst_sel:DWORD dst_unused:UNUSED_PAD src0_sel:WORD_1 src1_sel:DWORD
	v_and_b32_e32 v25, 0xffff0000, v25
	v_and_b32_sdwa v24, v6, v218 dst_sel:DWORD dst_unused:UNUSED_PAD src0_sel:WORD_1 src1_sel:DWORD
	v_add3_u32 v26, v7, v26, s91
	v_or_b32_sdwa v25, v25, v0 dst_sel:DWORD dst_unused:UNUSED_PAD src0_sel:DWORD src1_sel:WORD_1
	v_mul_f32_e32 v0, v11, v11
	v_mul_f32_e32 v7, v7, v7
	v_add3_u32 v24, v6, v24, s91
	v_fmac_f32_e32 v0, v10, v10
	v_mul_f32_e32 v10, v13, v13
	v_fmac_f32_e32 v7, v6, v6
	v_mul_f32_e32 v6, v9, v9
	v_fmac_f32_e32 v10, v12, v12
	v_fmac_f32_e32 v6, v8, v8
	v_add_f32_e32 v0, v0, v10
	v_add_f32_e32 v6, v7, v6
	v_add_f32_e32 v0, v0, v6
	ds_bpermute_b32 v6, v28, v0
	v_and_b32_e32 v26, 0xffff0000, v26
	v_or_b32_sdwa v24, v26, v24 dst_sel:DWORD dst_unused:UNUSED_PAD src0_sel:DWORD src1_sel:WORD_1
	global_store_dwordx2 v[22:23], v[24:25], off
	s_waitcnt lgkmcnt(0)
	v_add_f32_e32 v0, v0, v6
	ds_bpermute_b32 v6, v29, v0
	s_and_saveexec_b64 s[14:15], s[4:5]
	s_cbranch_execz .LBB0_385
	s_ashr_i32 s16, s23, 3
	v_lshl_add_u32 v8, v30, 5, s16
	v_ashrrev_i32_e32 v9, 31, v8
	v_lshl_add_u64 v[8:9], v[8:9], 2, s[10:11]
	s_waitcnt lgkmcnt(0)
	v_add_f32_e32 v0, v0, v6
	global_store_dword v[8:9], v0, off
	s_branch .LBB0_385

.LBB0_399:
	s_or_b64 exec, exec, s[4:5]
	s_and_b32 s2, s12, -2
	s_cmp_eq_u32 s13, 0
	s_cselect_b64 vcc, -1, 0
	s_lshl_b32 s4, s2, 4
	v_or_b32_e32 v47, s14, v75
	v_lshl_add_u32 v46, v79, 4, 0
	v_or_b32_e32 v48, s4, v75
	v_mad_u64_u32 v[100:101], s[6:7], v48, s88, v[46:47]
	s_or_b32 s6, s4, 16
	s_add_i32 s3, s2, 2
	v_or_b32_e32 v48, s6, v75
	s_lshl_b32 s12, s3, 4
	v_mad_u64_u32 v[98:99], s[8:9], v48, s88, v[46:47]
	v_or_b32_e32 v48, s12, v75
	s_add_i32 s20, s4, 48
	s_add_i32 s49, s2, 4
	v_mad_u64_u32 v[96:97], s[8:9], v48, s88, v[46:47]
	v_or_b32_e32 v48, s20, v75
	s_lshl_b32 s28, s49, 4
	v_mad_u64_u32 v[94:95], s[8:9], v48, s88, v[46:47]
	v_or_b32_e32 v48, s28, v75
	s_add_i32 s38, s4, 0x50
	v_mad_u64_u32 v[92:93], s[8:9], v48, s88, v[46:47]
	v_or_b32_e32 v48, s38, v75
	v_mad_u64_u32 v[90:91], s[8:9], v48, s88, v[46:47]
	s_add_i32 s88, s2, 6
	s_lshl_b32 s54, s88, 4
	s_movk_i32 s5, 0x90
	v_or_b32_e32 v48, s54, v75
	s_add_i32 s62, s4, 0x70
	s_add_i32 s89, s2, 8
	v_mad_u64_u32 v[88:89], s[8:9], v48, s5, v[46:47]
	v_or_b32_e32 v48, s62, v75
	s_lshl_b32 s70, s89, 4
	v_mad_u64_u32 v[86:87], s[8:9], v48, s5, v[46:47]
	v_or_b32_e32 v48, s70, v75
	s_add_i32 s78, s4, 0x90
	v_mad_u64_u32 v[84:85], s[8:9], v48, s5, v[46:47]
	v_or_b32_e32 v48, s78, v75
	v_mad_u64_u32 v[82:83], s[8:9], v48, s5, v[46:47]
	v_max_i32_e32 v46, 0x80, v47
	v_lshlrev_b32_e32 v48, 2, v79
	v_cndmask_b32_e32 v46, v47, v46, vcc
	v_add_u32_e32 v47, 0x80, v47
	v_or_b32_e32 v49, s4, v48
	v_cmp_lt_i32_e32 vcc, v49, v46
	v_cmp_gt_i32_e64 s[4:5], v49, v47
	v_or_b32_e32 v50, 1, v49
	s_or_b64 s[40:41], vcc, s[4:5]
	v_cmp_lt_i32_e32 vcc, v50, v46
	v_cmp_ge_i32_e64 s[4:5], v49, v47
	v_or_b32_e32 v50, 2, v49
	v_writelane_b32 v255, s40, 0
	s_or_b64 s[42:43], vcc, s[4:5]
	v_cmp_lt_i32_e32 vcc, v50, v46
	v_cmp_gt_i32_e64 s[4:5], v50, v47
	v_writelane_b32 v255, s41, 1
	s_or_b64 s[4:5], vcc, s[4:5]
	v_writelane_b32 v255, s4, 2
	v_or_b32_e32 v49, 3, v49
	v_cmp_lt_i32_e32 vcc, v49, v46
	v_writelane_b32 v255, s5, 3
	v_cmp_gt_i32_e64 s[4:5], v49, v47
	s_or_b64 s[4:5], vcc, s[4:5]
	v_or_b32_e32 v49, s6, v48
	v_writelane_b32 v255, s4, 4
	v_cmp_lt_i32_e32 vcc, v49, v46
	v_or_b32_e32 v50, 1, v49
	v_writelane_b32 v255, s5, 5
	v_cmp_gt_i32_e64 s[4:5], v49, v47
	s_or_b64 s[4:5], vcc, s[4:5]
	v_cmp_lt_i32_e32 vcc, v50, v46
	v_writelane_b32 v255, s4, 6
	v_cmp_ge_i32_e64 s[6:7], v49, v47
	v_or_b32_e32 v50, 2, v49
	v_writelane_b32 v255, s5, 7
	s_or_b64 s[6:7], vcc, s[6:7]
	v_cmp_lt_i32_e32 vcc, v50, v46
	v_cmp_gt_i32_e64 s[8:9], v50, v47
	v_or_b32_e32 v49, 3, v49
	v_writelane_b32 v255, s6, 8
	s_or_b64 s[4:5], vcc, s[8:9]
	v_cmp_lt_i32_e32 vcc, v49, v46
	v_cmp_gt_i32_e64 s[10:11], v49, v47
	v_or_b32_e32 v49, s12, v48
	v_writelane_b32 v255, s7, 9
	s_or_b64 s[44:45], vcc, s[10:11]
	v_cmp_lt_i32_e32 vcc, v49, v46
	v_cmp_gt_i32_e64 s[12:13], v49, v47
	v_or_b32_e32 v50, 1, v49
	v_writelane_b32 v255, s4, 10
	s_or_b64 s[8:9], vcc, s[12:13]
	v_cmp_lt_i32_e32 vcc, v50, v46
	v_cmp_ge_i32_e64 s[14:15], v49, v47
	v_or_b32_e32 v50, 2, v49
	v_writelane_b32 v255, s5, 11
	s_or_b64 s[12:13], vcc, s[14:15]
	v_cmp_lt_i32_e32 vcc, v50, v46
	v_cmp_gt_i32_e64 s[16:17], v50, v47
	v_or_b32_e32 v49, 3, v49
	v_writelane_b32 v255, s8, 12
	s_or_b64 s[10:11], vcc, s[16:17]
	v_cmp_lt_i32_e32 vcc, v49, v46
	v_cmp_gt_i32_e64 s[18:19], v49, v47
	v_or_b32_e32 v49, s20, v48
	v_writelane_b32 v255, s9, 13
	s_or_b64 s[8:9], vcc, s[18:19]
	v_cmp_lt_i32_e32 vcc, v49, v46
	v_cmp_gt_i32_e64 s[20:21], v49, v47
	v_or_b32_e32 v50, 1, v49
	s_or_b64 s[20:21], vcc, s[20:21]
	v_cmp_lt_i32_e32 vcc, v50, v46
	v_cmp_ge_i32_e64 s[22:23], v49, v47
	v_or_b32_e32 v50, 2, v49
	s_or_b64 s[18:19], vcc, s[22:23]
	v_cmp_lt_i32_e32 vcc, v50, v46
	v_cmp_gt_i32_e64 s[24:25], v50, v47
	v_or_b32_e32 v49, 3, v49
	s_or_b64 s[16:17], vcc, s[24:25]
	v_cmp_lt_i32_e32 vcc, v49, v46
	v_cmp_gt_i32_e64 s[26:27], v49, v47
	v_or_b32_e32 v49, s28, v48
	s_or_b64 s[14:15], vcc, s[26:27]
	v_cmp_lt_i32_e32 vcc, v49, v46
	v_cmp_gt_i32_e64 s[28:29], v49, v47
	v_or_b32_e32 v50, 1, v49
	s_or_b64 s[28:29], vcc, s[28:29]
	v_cmp_lt_i32_e32 vcc, v50, v46
	v_cmp_ge_i32_e64 s[30:31], v49, v47
	v_or_b32_e32 v50, 2, v49
	s_or_b64 s[24:25], vcc, s[30:31]
	v_cmp_lt_i32_e32 vcc, v50, v46
	v_cmp_gt_i32_e64 s[34:35], v50, v47
	v_or_b32_e32 v49, 3, v49
	s_or_b64 s[22:23], vcc, s[34:35]
	v_cmp_lt_i32_e32 vcc, v49, v46
	v_cmp_gt_i32_e64 s[36:37], v49, v47
	v_or_b32_e32 v49, s38, v48
	s_or_b64 s[26:27], vcc, s[36:37]
	v_cmp_lt_i32_e32 vcc, v49, v46
	v_cmp_gt_i32_e64 s[38:39], v49, v47
	v_or_b32_e32 v50, 1, v49
	s_or_b64 s[38:39], vcc, s[38:39]
	v_cmp_lt_i32_e32 vcc, v50, v46
	v_cmp_ge_i32_e64 s[46:47], v49, v47
	v_or_b32_e32 v50, 2, v49
	s_or_b64 s[30:31], vcc, s[46:47]
	v_cmp_lt_i32_e32 vcc, v50, v46
	v_cmp_gt_i32_e64 s[50:51], v50, v47
	v_or_b32_e32 v49, 3, v49
	s_or_b64 s[34:35], vcc, s[50:51]
	v_cmp_lt_i32_e32 vcc, v49, v46
	v_cmp_gt_i32_e64 s[52:53], v49, v47
	v_or_b32_e32 v49, s54, v48
	s_or_b64 s[36:37], vcc, s[52:53]
	v_cmp_lt_i32_e32 vcc, v49, v46
	v_cmp_gt_i32_e64 s[54:55], v49, v47
	v_or_b32_e32 v50, 1, v49
	s_or_b64 s[54:55], vcc, s[54:55]
	v_cmp_lt_i32_e32 vcc, v50, v46
	v_cmp_ge_i32_e64 s[56:57], v49, v47
	v_or_b32_e32 v50, 2, v49
	s_or_b64 s[46:47], vcc, s[56:57]
	v_cmp_lt_i32_e32 vcc, v50, v46
	v_cmp_gt_i32_e64 s[58:59], v50, v47
	v_or_b32_e32 v49, 3, v49
	s_or_b64 s[50:51], vcc, s[58:59]
	v_cmp_lt_i32_e32 vcc, v49, v46
	v_cmp_gt_i32_e64 s[60:61], v49, v47
	v_or_b32_e32 v49, s62, v48
	s_or_b64 s[52:53], vcc, s[60:61]
	v_cmp_lt_i32_e32 vcc, v49, v46
	v_cmp_gt_i32_e64 s[62:63], v49, v47
	v_or_b32_e32 v50, 1, v49
	s_or_b64 s[62:63], vcc, s[62:63]
	v_cmp_lt_i32_e32 vcc, v50, v46
	v_cmp_ge_i32_e64 s[64:65], v49, v47
	v_or_b32_e32 v50, 2, v49
	s_or_b64 s[56:57], vcc, s[64:65]
	v_cmp_lt_i32_e32 vcc, v50, v46
	v_cmp_gt_i32_e64 s[66:67], v50, v47
	v_or_b32_e32 v49, 3, v49
	s_or_b64 s[58:59], vcc, s[66:67]
	v_cmp_lt_i32_e32 vcc, v49, v46
	v_cmp_gt_i32_e64 s[68:69], v49, v47
	v_or_b32_e32 v49, s70, v48
	s_or_b64 s[60:61], vcc, s[68:69]
	v_cmp_lt_i32_e32 vcc, v49, v46
	v_cmp_gt_i32_e64 s[70:71], v49, v47
	v_or_b32_e32 v50, 1, v49
	v_ashrrev_i32_e32 v3, 31, v2
	s_or_b64 s[70:71], vcc, s[70:71]
	v_cmp_lt_i32_e32 vcc, v50, v46
	v_cmp_ge_i32_e64 s[72:73], v49, v47
	v_or_b32_e32 v50, 2, v49
	s_or_b64 s[64:65], vcc, s[72:73]
	v_cmp_lt_i32_e32 vcc, v50, v46
	v_cmp_gt_i32_e64 s[74:75], v50, v47
	v_or_b32_e32 v49, 3, v49
	v_lshlrev_b64 v[2:3], 11, v[2:3]
	v_lshlrev_b32_e32 v0, 3, v79
	s_or_b64 s[66:67], vcc, s[74:75]
	v_cmp_lt_i32_e32 vcc, v49, v46
	v_cmp_gt_i32_e64 s[76:77], v49, v47
	v_or_b32_e32 v48, s78, v48
	v_lshl_add_u64 v[2:3], s[0:1], 0, v[2:3]
	s_or_b64 s[68:69], vcc, s[76:77]
	v_cmp_lt_i32_e32 vcc, v48, v46
	v_cmp_gt_i32_e64 s[78:79], v48, v47
	v_or_b32_e32 v49, 1, v48
	v_lshl_add_u64 v[2:3], v[2:3], 0, v[0:1]
	s_mov_b64 s[0:1], 0xa000000
	s_or_b64 s[78:79], vcc, s[78:79]
	v_cmp_lt_i32_e32 vcc, v49, v46
	v_cmp_ge_i32_e64 s[80:81], v48, v47
	v_or_b32_e32 v49, 2, v48
	v_lshl_add_u64 v[80:81], v[2:3], 0, s[0:1]
	v_readlane_b32 s0, v254, 14
	s_or_b64 s[76:77], vcc, s[80:81]
	v_cmp_lt_i32_e32 vcc, v49, v46
	v_cmp_gt_i32_e64 s[82:83], v49, v47
	v_or_b32_e32 v48, 3, v48
	v_mov_b32_e32 v79, s0
	s_waitcnt lgkmcnt(0)
	s_barrier
	s_or_b64 s[72:73], vcc, s[82:83]
	v_cmp_lt_i32_e32 vcc, v48, v46
	v_cmp_gt_i32_e64 s[84:85], v48, v47
	v_add_u32_e32 v46, 0, v0
	v_mul_u32_u24_e32 v47, 0x210, v75
	s_lshl_b32 s2, s2, 5
	v_lshlrev_b32_e32 v64, 16, v38
	v_and_b32_e32 v66, 0xffff0000, v38
	v_lshlrev_b32_e32 v65, 16, v39
	v_and_b32_e32 v67, 0xffff0000, v39
	v_lshlrev_b32_e32 v68, 16, v40
	v_and_b32_e32 v70, 0xffff0000, v40
	v_lshlrev_b32_e32 v69, 16, v41
	v_and_b32_e32 v71, 0xffff0000, v41
	ds_read2_b64 v[38:41], v79 offset1:1
	v_add3_u32 v91, v46, s2, v47
	s_lshl_b32 s2, s3, 5
	v_add3_u32 v89, v46, s2, v47
	s_lshl_b32 s2, s49, 5
	v_add3_u32 v87, v46, s2, v47
	s_lshl_b32 s2, s88, 5
	v_readlane_b32 s0, v254, 51
	v_add3_u32 v85, v46, s2, v47
	s_lshl_b32 s2, s89, 5
	v_readlane_b32 s1, v254, 52
	s_or_b64 s[74:75], vcc, s[84:85]
	v_add3_u32 v83, v46, s2, v47
	s_waitcnt lgkmcnt(0)
	v_readfirstlane_b32 s2, v38
	s_lshl_b64 s[0:1], s[0:1], 2
	v_readfirstlane_b32 s3, v39
	s_add_u32 s2, s2, s0
	v_lshlrev_b32_e32 v3, 16, v43
	v_and_b32_e32 v59, 0xffff0000, v43
	v_lshlrev_b32_e32 v60, 16, v44
	v_and_b32_e32 v62, 0xffff0000, v44
	v_lshlrev_b32_e32 v61, 16, v45
	v_and_b32_e32 v63, 0xffff0000, v45
	s_addc_u32 s3, s3, s1
	v_lshlrev_b32_e32 v0, 2, v0
	v_mov_b32_e32 v44, v67
	v_mov_b32_e32 v45, v65
	v_lshlrev_b32_e32 v2, 16, v42
	v_and_b32_e32 v58, 0xffff0000, v42
	v_lshl_add_u64 v[38:39], s[2:3], 0, v[0:1]
	v_mov_b32_e32 v42, v59
	v_mov_b32_e32 v43, v3
	v_pk_mul_f32 v[44:45], v[44:45], v[44:45]
	global_load_dwordx4 v[46:49], v[38:39], off offset:128
	v_pk_fma_f32 v[72:73], v[42:43], v[42:43], v[44:45]
	global_load_dwordx4 v[42:45], v[38:39], off
	global_load_dwordx4 v[50:53], v[38:39], off offset:16
	global_load_dwordx4 v[54:57], v[38:39], off offset:144
	v_mul_f32_e32 v38, v58, v58
	v_mul_f32_e32 v39, v2, v2
	v_fmac_f32_e32 v38, v66, v66
	v_fmac_f32_e32 v39, v64, v64
	v_mov_b32_e32 v104, v18
	v_mov_b32_e32 v105, v20
	v_mov_b32_e32 v20, v19
	v_mov_b32_e32 v18, v70
	v_mov_b32_e32 v19, v68
	v_add_f32_e32 v38, v39, v38
	v_mov_b32_e32 v102, v10
	v_mov_b32_e32 v103, v12
	v_mov_b32_e32 v12, v11
	v_mov_b32_e32 v10, v62
	v_mov_b32_e32 v11, v60
	v_pk_mul_f32 v[18:19], v[18:19], v[18:19]
	v_add_f32_e32 v38, v73, v38
	v_pk_fma_f32 v[10:11], v[10:11], v[10:11], v[18:19]
	v_add_f32_e32 v38, v72, v38
	v_mov_b32_e32 v18, v63
	v_mov_b32_e32 v19, v61
	v_add_f32_e32 v11, v11, v38
	v_add_f32_e32 v10, v10, v11
	s_mov_b32 s2, 0xf800000
	v_readfirstlane_b32 s49, v40
	v_writelane_b32 v255, s12, 14
	s_mov_b32 s94, 0xf149f2ca
	s_mov_b64 s[84:85], s[8:9]
	v_writelane_b32 v255, s13, 15
	v_writelane_b32 v255, s18, 16
	s_mov_b64 s[82:83], s[10:11]
	s_waitcnt vmcnt(0) lgkmcnt(0)
	v_mov_b32_e32 v76, v46
	v_mov_b32_e32 v77, v48
	v_mov_b32_e32 v74, v42
	v_mov_b32_e32 v75, v44
	v_mov_b32_e32 v44, v43
	v_mov_b32_e32 v42, v71
	v_mov_b32_e32 v43, v69
	v_pk_mul_f32 v[42:43], v[42:43], v[42:43]
	v_mov_b32_e32 v48, v47
	v_pk_fma_f32 v[18:19], v[18:19], v[18:19], v[42:43]
	v_writelane_b32 v255, s19, 17
	v_add_f32_e32 v10, v19, v10
	v_add_f32_e32 v10, v18, v10
	ds_bpermute_b32 v11, v109, v10
	v_writelane_b32 v255, s16, 18
	s_waitcnt lgkmcnt(0)
	v_add_f32_e32 v10, v10, v11
	ds_bpermute_b32 v11, v110, v10
	v_writelane_b32 v255, s17, 19
	v_writelane_b32 v255, s70, 20
	s_waitcnt lgkmcnt(0)
	v_add_f32_e32 v10, v10, v11
	v_fmamk_f32 v10, v10, 0x3c800000, v219
	v_cmp_gt_f32_e32 vcc, s2, v10
	v_mul_f32_e32 v11, 0x4f800000, v10
	v_writelane_b32 v255, s71, 21
	v_cndmask_b32_e32 v10, v10, v11, vcc
	v_sqrt_f32_e32 v11, v10
	s_nop 0
	v_add_u32_e32 v18, -1, v11
	v_fma_f32 v19, -v18, v11, v10
	v_cmp_ge_f32_e64 s[88:89], 0, v19
	v_add_u32_e32 v19, 1, v11
	s_nop 0
	v_cndmask_b32_e64 v18, v11, v18, s[88:89]
	v_fma_f32 v11, -v19, v11, v10
	v_cmp_lt_f32_e64 s[88:89], 0, v11
	s_nop 1
	v_cndmask_b32_e64 v11, v18, v19, s[88:89]
	v_mul_f32_e32 v18, 0x37800000, v11
	v_cndmask_b32_e32 v11, v11, v18, vcc
	v_cmp_class_f32_e32 vcc, v10, v221
	v_readfirstlane_b32 s88, v41
	s_nop 0
	v_cndmask_b32_e32 v10, v11, v10, vcc
	v_div_scale_f32 v11, s[2:3], v10, v10, 1.0
	v_rcp_f32_e32 v18, v11
	s_add_i32 s2, s48, s93
	s_ashr_i32 s3, s2, 31
	s_lshl_b64 s[2:3], s[2:3], 2
	v_fma_f32 v19, -v11, v18, 1.0
	v_fmac_f32_e32 v18, v19, v18
	v_div_scale_f32 v19, vcc, 1.0, v10, 1.0
	v_mul_f32_e32 v38, v19, v18
	v_fma_f32 v39, -v11, v38, v19
	v_fmac_f32_e32 v38, v39, v18
	v_fma_f32 v11, -v11, v38, v19
	v_div_fmas_f32 v11, v11, v18, v38
	v_div_fixup_f32 v10, v11, v10, 1.0
	v_pk_mul_f32 v[18:19], v[10:11], v[64:65] op_sel_hi:[0,1]
	v_pk_mul_f32 v[38:39], v[76:77], v[18:19]
	v_pk_mul_f32 v[18:19], v[10:11], v[58:59] op_sel_hi:[0,1]
	v_pk_mul_f32 v[2:3], v[10:11], v[2:3] op_sel_hi:[0,1]
	v_pk_mul_f32 v[42:43], v[18:19], v[44:45]
	v_pk_mul_f32 v[18:19], v[10:11], v[66:67] op_sel_hi:[0,1]
	v_pk_mul_f32 v[2:3], v[74:75], v[2:3]
	v_pk_mul_f32 v[44:45], v[18:19], v[48:49]
	v_pk_mul_f32 v[18:19], v[102:103], v[38:39]
	v_mov_b32_e32 v58, v50
	v_pk_fma_f32 v[18:19], v[104:105], v[2:3], v[18:19]
	v_mov_b32_e32 v59, v52
	v_pk_mul_f32 v[46:47], v[18:19], s[86:87] op_sel_hi:[1,0]
	v_pk_mul_f32 v[18:19], v[12:13], v[44:45]
	v_mov_b32_e32 v52, v51
	v_pk_fma_f32 v[18:19], v[20:21], v[42:43], v[18:19]
	s_add_u32 s48, s49, s2
	v_pk_mul_f32 v[48:49], v[18:19], s[86:87] op_sel_hi:[1,0]
	v_pk_mul_f32 v[18:19], v[10:11], v[60:61] op_sel_hi:[0,1]
	v_pk_mul_f32 v[58:59], v[18:19], v[58:59]
	v_pk_mul_f32 v[18:19], v[10:11], v[68:69] op_sel_hi:[0,1]
	v_mov_b32_e32 v60, v54
	v_mov_b32_e32 v61, v56
	v_pk_mul_f32 v[60:61], v[18:19], v[60:61]
	v_pk_mul_f32 v[18:19], v[10:11], v[62:63] op_sel_hi:[0,1]
	v_pk_mul_f32 v[50:51], v[18:19], v[52:53]
	v_pk_mul_f32 v[10:11], v[10:11], v[70:71] op_sel_hi:[0,1]
	v_mov_b32_e32 v56, v55
	v_mov_b32_e32 v18, v14
	v_mov_b32_e32 v19, v16
	v_mov_b32_e32 v16, v15
	v_pk_mul_f32 v[14:15], v[104:105], v[38:39]
	v_pk_mul_f32 v[52:53], v[10:11], v[56:57]
	v_pk_fma_f32 v[2:3], v[102:103], v[2:3], v[14:15] neg_lo:[0,0,1] neg_hi:[0,0,1]
	v_pk_mul_f32 v[14:15], v[20:21], v[44:45]
	v_mov_b32_e32 v10, v6
	v_mov_b32_e32 v11, v8
	v_mov_b32_e32 v8, v7
	v_pk_fma_f32 v[14:15], v[12:13], v[42:43], v[14:15] neg_lo:[0,0,1] neg_hi:[0,0,1]
	v_pk_mul_f32 v[38:39], v[18:19], v[60:61]
	v_pk_mul_f32 v[42:43], v[16:17], v[52:53]
	v_pk_mul_f32 v[6:7], v[8:9], v[52:53]
	v_pk_mul_f32 v[14:15], v[14:15], s[86:87] op_sel_hi:[1,0]
	v_pk_fma_f32 v[38:39], v[10:11], v[58:59], v[38:39] neg_lo:[0,0,1] neg_hi:[0,0,1]
	v_pk_fma_f32 v[42:43], v[8:9], v[50:51], v[42:43] neg_lo:[0,0,1] neg_hi:[0,0,1]
	v_pk_fma_f32 v[6:7], v[16:17], v[50:51], v[6:7]
	v_pk_mul_f32 v[38:39], v[38:39], s[86:87] op_sel_hi:[1,0]
	v_pk_mul_f32 v[42:43], v[42:43], s[86:87] op_sel_hi:[1,0]
	v_bfe_u32 v50, v15, 16, 1
	v_bfe_u32 v51, v14, 16, 1
	v_pk_mul_f32 v[54:55], v[10:11], v[60:61]
	v_pk_mul_f32 v[2:3], v[2:3], s[86:87] op_sel_hi:[1,0]
	v_bfe_u32 v44, v43, 16, 1
	v_bfe_u32 v45, v42, 16, 1
	v_add3_u32 v14, v14, v51, s91
	v_add3_u32 v15, v15, v50, s91
	v_bfe_u32 v50, v38, 16, 1
	v_bfe_u32 v51, v39, 16, 1
	v_pk_fma_f32 v[54:55], v[18:19], v[58:59], v[54:55]
	v_add3_u32 v42, v42, v45, s91
	v_add3_u32 v43, v43, v44, s91
	v_bfe_u32 v44, v2, 16, 1
	v_bfe_u32 v45, v3, 16, 1
	v_add3_u32 v39, v39, v51, s91
	v_add3_u32 v38, v38, v50, s91
	v_pk_mul_f32 v[54:55], v[54:55], s[86:87] op_sel_hi:[1,0]
	v_add3_u32 v3, v3, v45, s91
	v_add3_u32 v2, v2, v44, s91
	v_lshrrev_b32_e32 v38, 16, v38
	v_lshrrev_b32_e32 v39, 16, v39
	v_pk_mul_f32 v[6:7], v[6:7], s[86:87] op_sel_hi:[1,0]
	v_lshrrev_b32_e32 v2, 16, v2
	v_lshrrev_b32_e32 v3, 16, v3
	v_and_or_b32 v115, v43, s33, v39
	v_and_or_b32 v114, v42, s33, v38
	v_bfe_u32 v38, v54, 16, 1
	v_bfe_u32 v39, v55, 16, 1
	v_and_or_b32 v113, v15, s33, v3
	v_and_or_b32 v112, v14, s33, v2
	v_bfe_u32 v2, v7, 16, 1
	v_bfe_u32 v3, v6, 16, 1
	v_add3_u32 v39, v55, v39, s91
	v_add3_u32 v38, v54, v38, s91
	v_add3_u32 v3, v6, v3, s91
	v_add3_u32 v2, v7, v2, s91
	v_lshrrev_b32_e32 v38, 16, v38
	v_lshrrev_b32_e32 v39, 16, v39
	v_and_or_b32 v119, v2, s33, v39
	v_and_or_b32 v118, v3, s33, v38
	ds_read_b128 v[38:41], v100
	ds_read_b128 v[42:45], v100 offset:64
	v_bfe_u32 v6, v46, 16, 1
	v_bfe_u32 v7, v47, 16, 1
	s_waitcnt lgkmcnt(1)
	v_mfma_f32_16x16x32_bf16 v[38:41], v[38:41], v[112:115], 0
	v_bfe_u32 v14, v49, 16, 1
	v_bfe_u32 v15, v48, 16, 1
	v_add3_u32 v7, v47, v7, s91
	v_add3_u32 v6, v46, v6, s91
	v_add3_u32 v15, v48, v15, s91
	v_add3_u32 v14, v49, v14, s91
	v_lshrrev_b32_e32 v6, 16, v6
	v_lshrrev_b32_e32 v7, 16, v7
	v_and_or_b32 v117, v14, s33, v7
	v_and_or_b32 v116, v15, s33, v6
	s_addc_u32 s49, s88, s3
	s_nop 1
	v_mov_b64_e32 v[148:149], s[48:49]
	global_load_dword v150, v[148:149], off
	v_mov_b64_e32 v[2:3], s[48:49]
	s_waitcnt lgkmcnt(0)
	v_mfma_f32_16x16x32_bf16 v[74:77], v[42:45], v[116:119], v[38:41]
	ds_read_b128 v[42:45], v98 offset:64
	s_waitcnt vmcnt(0)
	s_nop 0
	v_mov_b32_e32 v3, v150
	s_nop 1
	v_mov_b32_e32 v2, s94
	ds_read_b128 v[38:41], v98
	s_waitcnt lgkmcnt(0)
	v_mfma_f32_16x16x32_bf16 v[38:41], v[38:41], v[112:115], 0
	s_nop 1
	v_cndmask_b32_e64 v15, v74, v2, s[40:41]
	s_mov_b64 s[40:41], s[42:43]
	v_mfma_f32_16x16x32_bf16 v[70:73], v[42:45], v[116:119], v[38:41]
	ds_read_b128 v[42:45], v96 offset:64
	v_writelane_b32 v255, s40, 22
	v_cndmask_b32_e64 v14, v75, v227, s[42:43]
	ds_read_b128 v[38:41], v96
	s_waitcnt lgkmcnt(0)
	v_mfma_f32_16x16x32_bf16 v[38:41], v[38:41], v[112:115], 0
	v_writelane_b32 v255, s41, 23
	v_max3_f32 v2, v15, s94, v14
	v_readlane_b32 s80, v255, 2
	v_mfma_f32_16x16x32_bf16 v[66:69], v[42:45], v[116:119], v[38:41]
	ds_read_b128 v[42:45], v94 offset:64
	v_readlane_b32 s42, v255, 4
	v_readlane_b32 s81, v255, 3
	s_nop 0
	ds_read_b128 v[38:41], v94
	s_waitcnt lgkmcnt(0)
	v_mfma_f32_16x16x32_bf16 v[38:41], v[38:41], v[112:115], 0
	v_readlane_b32 s43, v255, 5
	v_cndmask_b32_e64 v7, v76, v227, s[80:81]
	v_mfma_f32_16x16x32_bf16 v[62:65], v[42:45], v[116:119], v[38:41]
	ds_read_b128 v[42:45], v92 offset:64
	v_cndmask_b32_e64 v6, v77, v227, s[42:43]
	v_readlane_b32 s48, v255, 6
	s_nop 1
	ds_read_b128 v[38:41], v92
	s_waitcnt lgkmcnt(0)
	v_mfma_f32_16x16x32_bf16 v[38:41], v[38:41], v[112:115], 0
	v_max3_f32 v76, v2, v7, v6
	v_mov_b32_e32 v2, s94
	v_readlane_b32 s49, v255, 7
	v_mfma_f32_16x16x32_bf16 v[58:61], v[42:45], v[116:119], v[38:41]
	ds_read_b128 v[42:45], v90 offset:64
	v_cndmask_b32_e64 v75, v70, v2, s[48:49]
	v_cndmask_b32_e64 v74, v71, v227, s[6:7]
	s_nop 0
	ds_read_b128 v[38:41], v90
	s_waitcnt lgkmcnt(0)
	v_mfma_f32_16x16x32_bf16 v[38:41], v[38:41], v[112:115], 0
	v_max3_f32 v2, v76, v75, v74
	v_cndmask_b32_e64 v71, v72, v227, s[4:5]
	v_mfma_f32_16x16x32_bf16 v[54:57], v[42:45], v[116:119], v[38:41]
	ds_read_b128 v[42:45], v88 offset:64
	v_cndmask_b32_e64 v70, v73, v227, s[44:45]
	v_readlane_b32 s4, v255, 12
	s_nop 1
	ds_read_b128 v[38:41], v88
	s_waitcnt lgkmcnt(0)
	v_mfma_f32_16x16x32_bf16 v[38:41], v[38:41], v[112:115], 0
	v_max3_f32 v76, v2, v71, v70
	v_mov_b32_e32 v2, s94
	v_readlane_b32 s5, v255, 13
	v_mfma_f32_16x16x32_bf16 v[50:53], v[42:45], v[116:119], v[38:41]
	ds_read_b128 v[42:45], v86 offset:64
	v_cndmask_b32_e64 v73, v66, v2, s[4:5]
	v_cndmask_b32_e64 v72, v67, v227, s[12:13]
	s_nop 0
	ds_read_b128 v[38:41], v86
	s_waitcnt lgkmcnt(0)
	v_mfma_f32_16x16x32_bf16 v[38:41], v[38:41], v[112:115], 0
	v_max3_f32 v2, v76, v73, v72
	v_cndmask_b32_e64 v67, v68, v227, s[10:11]
	v_mfma_f32_16x16x32_bf16 v[46:49], v[42:45], v[116:119], v[38:41]
	ds_read_b128 v[42:45], v84 offset:64
	v_cndmask_b32_e64 v66, v69, v227, s[8:9]
	v_max3_f32 v76, v2, v67, v66
	s_nop 1
	ds_read_b128 v[38:41], v84
	s_waitcnt lgkmcnt(0)
	v_mfma_f32_16x16x32_bf16 v[38:41], v[38:41], v[112:115], 0
	v_mov_b32_e32 v2, s94
	v_cndmask_b32_e64 v69, v62, v2, s[20:21]
	v_cndmask_b32_e64 v68, v63, v227, s[18:19]
	v_mfma_f32_16x16x32_bf16 v[42:45], v[42:45], v[116:119], v[38:41]
	v_max3_f32 v2, v76, v69, v68
	v_cndmask_b32_e64 v63, v64, v227, s[16:17]
	v_cndmask_b32_e64 v62, v65, v227, s[14:15]
	s_nop 0
	ds_read_b128 v[38:41], v82
	v_max3_f32 v76, v2, v63, v62
	v_mov_b32_e32 v2, s94
	v_cndmask_b32_e64 v65, v58, v2, s[28:29]
	v_cndmask_b32_e64 v64, v59, v227, s[24:25]
	v_max3_f32 v2, v76, v65, v64
	v_cndmask_b32_e64 v59, v60, v227, s[22:23]
	v_cndmask_b32_e64 v58, v61, v227, s[26:27]
	s_waitcnt lgkmcnt(0)
	v_mfma_f32_16x16x32_bf16 v[38:41], v[38:41], v[112:115], 0
	ds_read_b128 v[112:115], v82 offset:64
	v_max3_f32 v76, v2, v59, v58
	v_mov_b32_e32 v2, s94
	v_cndmask_b32_e64 v61, v54, v2, s[38:39]
	v_cndmask_b32_e64 v60, v55, v227, s[30:31]
	v_max3_f32 v2, v76, v61, v60
	v_cndmask_b32_e64 v55, v56, v227, s[34:35]
	v_cndmask_b32_e64 v54, v57, v227, s[36:37]
	v_max3_f32 v76, v2, v55, v54
	v_mov_b32_e32 v2, s94
	v_cndmask_b32_e64 v57, v50, v2, s[54:55]
	v_cndmask_b32_e64 v56, v51, v227, s[46:47]
	v_max3_f32 v2, v76, v57, v56
	v_cndmask_b32_e64 v51, v52, v227, s[50:51]
	v_cndmask_b32_e64 v50, v53, v227, s[52:53]
	v_max3_f32 v76, v2, v51, v50
	v_mov_b32_e32 v2, s94
	v_cndmask_b32_e64 v53, v46, v2, s[62:63]
	v_cndmask_b32_e64 v52, v47, v227, s[56:57]
	v_max3_f32 v2, v76, v53, v52
	v_cndmask_b32_e64 v47, v48, v227, s[58:59]
	v_cndmask_b32_e64 v46, v49, v227, s[60:61]
	s_waitcnt lgkmcnt(0)
	v_mfma_f32_16x16x32_bf16 v[38:41], v[112:115], v[116:119], v[38:41]
	v_max3_f32 v76, v2, v47, v46
	v_mov_b32_e32 v2, s94
	v_cndmask_b32_e64 v49, v42, v2, s[70:71]
	v_cndmask_b32_e64 v48, v43, v227, s[64:65]
	v_max3_f32 v2, v76, v49, v48
	v_cndmask_b32_e64 v43, v44, v227, s[66:67]
	v_cndmask_b32_e64 v42, v45, v227, s[68:69]
	s_mov_b64 s[4:5], s[24:25]
	v_max3_f32 v44, v2, v43, v42
	v_mov_b32_e32 v2, s94
	s_mov_b64 s[24:25], s[78:79]
	s_mov_b64 s[70:71], s[76:77]
	v_cndmask_b32_e64 v2, v38, v2, s[24:25]
	v_cndmask_b32_e64 v38, v39, v227, s[70:71]
	v_max3_f32 v39, v44, v2, v38
	v_cndmask_b32_e64 v40, v40, v227, s[72:73]
	v_cndmask_b32_e64 v41, v41, v227, s[74:75]
	v_max3_f32 v39, v39, v40, v41
	ds_bpermute_b32 v44, v109, v39
	s_mov_b32 s93, s95
	s_mov_b32 s6, 0xf800000
	v_readlane_b32 s8, v255, 0
	s_waitcnt lgkmcnt(0)
	v_max_f32_e32 v44, v44, v44
	v_max_f32_e32 v39, v39, v44
	ds_bpermute_b32 v44, v110, v39
	v_readlane_b32 s9, v255, 1
	v_readlane_b32 s18, v255, 6
	v_readlane_b32 s10, v255, 8
	v_readlane_b32 s19, v255, 7
	s_waitcnt vmcnt(0) lgkmcnt(0)
	v_max3_f32 v39, v39, v44, v3
	v_sub_f32_e32 v15, v15, v39
	v_mul_f32_e32 v15, 0x3fb8aa3b, v15
	v_sub_f32_e32 v14, v14, v39
	v_exp_f32_e32 v15, v15
	v_mul_f32_e32 v14, 0x3fb8aa3b, v14
	v_sub_f32_e32 v7, v7, v39
	v_exp_f32_e32 v14, v14
	v_mul_f32_e32 v7, 0x3fb8aa3b, v7
	v_sub_f32_e32 v6, v6, v39
	v_exp_f32_e32 v7, v7
	v_mul_f32_e32 v6, 0x3fb8aa3b, v6
	v_sub_f32_e32 v45, v75, v39
	v_exp_f32_e32 v6, v6
	v_mul_f32_e32 v45, 0x3fb8aa3b, v45
	v_sub_f32_e32 v74, v74, v39
	v_add_f32_e32 v44, 0, v15
	v_exp_f32_e32 v45, v45
	v_mul_f32_e32 v74, 0x3fb8aa3b, v74
	v_sub_f32_e32 v71, v71, v39
	v_add_f32_e32 v44, v14, v44
	v_exp_f32_e32 v74, v74
	v_mul_f32_e32 v71, 0x3fb8aa3b, v71
	v_sub_f32_e32 v70, v70, v39
	v_add_f32_e32 v44, v7, v44
	v_exp_f32_e32 v71, v71
	v_mul_f32_e32 v70, 0x3fb8aa3b, v70
	v_sub_f32_e32 v73, v73, v39
	v_add_f32_e32 v44, v6, v44
	v_exp_f32_e32 v70, v70
	v_mul_f32_e32 v73, 0x3fb8aa3b, v73
	v_sub_f32_e32 v72, v72, v39
	v_add_f32_e32 v44, v45, v44
	v_exp_f32_e32 v75, v73
	v_mul_f32_e32 v72, 0x3fb8aa3b, v72
	v_sub_f32_e32 v67, v67, v39
	v_add_f32_e32 v44, v74, v44
	v_exp_f32_e32 v76, v72
	v_mul_f32_e32 v67, 0x3fb8aa3b, v67
	v_sub_f32_e32 v66, v66, v39
	v_add_f32_e32 v44, v71, v44
	v_exp_f32_e32 v67, v67
	v_mul_f32_e32 v66, 0x3fb8aa3b, v66
	v_sub_f32_e32 v69, v69, v39
	v_add_f32_e32 v44, v70, v44
	v_exp_f32_e32 v66, v66
	v_mul_f32_e32 v69, 0x3fb8aa3b, v69
	v_sub_f32_e32 v68, v68, v39
	v_add_f32_e32 v44, v75, v44
	v_exp_f32_e32 v69, v69
	v_mul_f32_e32 v68, 0x3fb8aa3b, v68
	v_sub_f32_e32 v63, v63, v39
	v_add_f32_e32 v44, v76, v44
	v_exp_f32_e32 v68, v68
	v_mul_f32_e32 v63, 0x3fb8aa3b, v63
	v_sub_f32_e32 v62, v62, v39
	v_add_f32_e32 v44, v67, v44
	v_exp_f32_e32 v63, v63
	v_mul_f32_e32 v62, 0x3fb8aa3b, v62
	v_sub_f32_e32 v65, v65, v39
	v_add_f32_e32 v44, v66, v44
	v_exp_f32_e32 v62, v62
	v_mul_f32_e32 v65, 0x3fb8aa3b, v65
	v_sub_f32_e32 v64, v64, v39
	v_sub_f32_e32 v58, v58, v39
	v_add_f32_e32 v44, v69, v44
	v_exp_f32_e32 v65, v65
	v_mul_f32_e32 v64, 0x3fb8aa3b, v64
	v_sub_f32_e32 v59, v59, v39
	v_mul_f32_e32 v58, 0x3fb8aa3b, v58
	v_add_f32_e32 v44, v68, v44
	v_exp_f32_e32 v64, v64
	v_mul_f32_e32 v59, 0x3fb8aa3b, v59
	v_exp_f32_e32 v93, v58
	v_sub_f32_e32 v58, v61, v39
	v_add_f32_e32 v44, v63, v44
	v_exp_f32_e32 v77, v59
	v_mul_f32_e32 v58, 0x3fb8aa3b, v58
	v_add_f32_e32 v44, v62, v44
	v_exp_f32_e32 v95, v58
	v_sub_f32_e32 v58, v60, v39
	v_sub_f32_e32 v54, v54, v39
	v_add_f32_e32 v44, v65, v44
	v_mul_f32_e32 v58, 0x3fb8aa3b, v58
	v_sub_f32_e32 v55, v55, v39
	v_mul_f32_e32 v54, 0x3fb8aa3b, v54
	v_add_f32_e32 v44, v64, v44
	v_exp_f32_e32 v97, v58
	v_mul_f32_e32 v55, 0x3fb8aa3b, v55
	v_exp_f32_e32 v101, v54
	v_sub_f32_e32 v54, v57, v39
	v_add_f32_e32 v44, v77, v44
	v_exp_f32_e32 v99, v55
	v_mul_f32_e32 v54, 0x3fb8aa3b, v54
	v_add_f32_e32 v44, v93, v44
	v_exp_f32_e32 v111, v54
	v_sub_f32_e32 v54, v56, v39
	v_sub_f32_e32 v50, v50, v39
	v_add_f32_e32 v44, v95, v44
	v_mul_f32_e32 v54, 0x3fb8aa3b, v54
	v_sub_f32_e32 v51, v51, v39
	v_mul_f32_e32 v50, 0x3fb8aa3b, v50
	v_add_f32_e32 v44, v97, v44
	v_exp_f32_e32 v112, v54
	v_mul_f32_e32 v51, 0x3fb8aa3b, v51
	v_exp_f32_e32 v114, v50
	v_sub_f32_e32 v50, v53, v39
	v_add_f32_e32 v44, v99, v44
	v_exp_f32_e32 v113, v51
	v_mul_f32_e32 v50, 0x3fb8aa3b, v50
	v_add_f32_e32 v44, v101, v44
	v_exp_f32_e32 v115, v50
	v_sub_f32_e32 v50, v52, v39
	v_sub_f32_e32 v46, v46, v39
	v_add_f32_e32 v44, v111, v44
	v_mul_f32_e32 v50, 0x3fb8aa3b, v50
	v_sub_f32_e32 v47, v47, v39
	v_mul_f32_e32 v46, 0x3fb8aa3b, v46
	v_add_f32_e32 v44, v112, v44
	v_exp_f32_e32 v116, v50
	v_mul_f32_e32 v47, 0x3fb8aa3b, v47
	v_exp_f32_e32 v118, v46
	v_sub_f32_e32 v46, v49, v39
	v_add_f32_e32 v44, v113, v44
	v_exp_f32_e32 v117, v47
	v_mul_f32_e32 v46, 0x3fb8aa3b, v46
	v_add_f32_e32 v44, v114, v44
	v_exp_f32_e32 v119, v46
	v_sub_f32_e32 v46, v48, v39
	v_add_f32_e32 v44, v115, v44
	v_mul_f32_e32 v46, 0x3fb8aa3b, v46
	v_sub_f32_e32 v43, v43, v39
	v_add_f32_e32 v44, v116, v44
	v_exp_f32_e32 v120, v46
	v_mul_f32_e32 v43, 0x3fb8aa3b, v43
	v_sub_f32_e32 v42, v42, v39
	v_sub_f32_e32 v38, v38, v39
	v_add_f32_e32 v44, v117, v44
	v_exp_f32_e32 v121, v43
	v_mul_f32_e32 v42, 0x3fb8aa3b, v42
	v_sub_f32_e32 v2, v2, v39
	v_mul_f32_e32 v38, 0x3fb8aa3b, v38
	v_add_f32_e32 v44, v118, v44
	v_exp_f32_e32 v122, v42
	v_mul_f32_e32 v2, 0x3fb8aa3b, v2
	v_exp_f32_e32 v124, v38
	v_sub_f32_e32 v38, v40, v39
	v_add_f32_e32 v44, v119, v44
	v_exp_f32_e32 v123, v2
	v_mul_f32_e32 v38, 0x3fb8aa3b, v38
	v_add_f32_e32 v44, v120, v44
	v_exp_f32_e32 v125, v38
	v_sub_f32_e32 v38, v41, v39
	v_add_f32_e32 v43, v121, v44
	v_mul_f32_e32 v38, 0x3fb8aa3b, v38
	v_add_f32_e32 v42, v122, v43
	v_exp_f32_e32 v126, v38
	v_add_f32_e32 v2, v123, v42
	v_add_f32_e32 v2, v124, v2
	v_add_f32_e32 v2, v125, v2
	v_add_f32_e32 v2, v126, v2
	ds_bpermute_b32 v38, v109, v2
	v_sub_f32_e32 v3, v3, v39
	v_mul_f32_e32 v3, 0x3fb8aa3b, v3
	v_exp_f32_e32 v3, v3
	v_bfe_u32 v40, v14, 16, 1
	s_waitcnt lgkmcnt(0)
	v_add_f32_e32 v2, v2, v38
	ds_bpermute_b32 v38, v110, v2
	v_bfe_u32 v42, v71, 16, 1
	v_add3_u32 v14, v14, v40, s91
	v_bfe_u32 v40, v7, 16, 1
	v_bfe_u32 v41, v45, 16, 1
	s_waitcnt lgkmcnt(0)
	v_add_f32_e32 v2, v2, v38
	v_add_f32_e32 v2, v3, v2
	v_bfe_u32 v3, v70, 16, 1
	v_add3_u32 v3, v70, v3, s91
	v_add3_u32 v42, v71, v42, s91
	v_add_u32_e32 v73, 0x9000, v91
	v_add_u32_e32 v72, 0xb000, v91
	v_add_u32_e32 v71, 0xd000, v91
	v_add_u32_e32 v70, 0xf000, v91
	v_add3_u32 v41, v45, v41, s91
	v_add3_u32 v7, v7, v40, s91
	v_lshrrev_b32_e32 v40, 16, v42
	ds_read2_b64 v[42:45], v73 offset1:4
	ds_read2_b64 v[46:49], v72 offset0:32 offset1:36
	ds_read2_b64 v[50:53], v71 offset0:64 offset1:68
	ds_read2_b64 v[54:57], v70 offset0:96 offset1:100
	v_bfe_u32 v39, v6, 16, 1
	v_add3_u32 v6, v6, v39, s91
	v_bfe_u32 v39, v15, 16, 1
	v_bfe_u32 v38, v74, 16, 1
	v_add3_u32 v15, v15, v39, s91
	v_add3_u32 v38, v74, v38, s91
	v_lshrrev_b32_e32 v15, 16, v15
	v_lshrrev_b32_e32 v7, 16, v7
	v_lshrrev_b32_e32 v39, 16, v41
	v_and_or_b32 v41, v3, s33, v40
	v_and_or_b32 v40, v38, s33, v39
	v_and_or_b32 v39, v6, s33, v7
	v_and_or_b32 v38, v14, s33, v15
	v_bfe_u32 v15, v75, 16, 1
	v_bfe_u32 v3, v62, 16, 1
	s_waitcnt lgkmcnt(3)
	v_mfma_f32_16x16x32_bf16 v[42:45], v[42:45], v[38:41], 0
	v_bfe_u32 v6, v68, 16, 1
	v_bfe_u32 v7, v66, 16, 1
	v_bfe_u32 v14, v76, 16, 1
	s_waitcnt lgkmcnt(2)
	v_mfma_f32_16x16x32_bf16 v[46:49], v[46:49], v[38:41], 0
	v_add3_u32 v15, v75, v15, s91
	v_add3_u32 v14, v76, v14, s91
	v_add3_u32 v7, v66, v7, s91
	s_waitcnt lgkmcnt(1)
	v_mfma_f32_16x16x32_bf16 v[50:53], v[50:53], v[38:41], 0
	v_add3_u32 v6, v68, v6, s91
	v_add3_u32 v3, v62, v3, s91
	v_lshrrev_b32_e32 v15, 16, v15
	s_waitcnt lgkmcnt(0)
	v_mfma_f32_16x16x32_bf16 v[38:41], v[54:57], v[38:41], 0
	v_bfe_u32 v55, v69, 16, 1
	v_add3_u32 v55, v69, v55, s91
	v_add_u32_e32 v69, 0x9000, v89
	ds_read2_b64 v[58:61], v69 offset1:4
	v_bfe_u32 v54, v67, 16, 1
	v_bfe_u32 v56, v63, 16, 1
	v_add3_u32 v56, v63, v56, s91
	v_add3_u32 v54, v67, v54, s91
	v_lshrrev_b32_e32 v54, 16, v54
	v_lshrrev_b32_e32 v55, 16, v55
	v_lshrrev_b32_e32 v56, 16, v56
	v_and_or_b32 v57, v3, s33, v56
	v_and_or_b32 v56, v6, s33, v55
	v_and_or_b32 v55, v7, s33, v54
	v_and_or_b32 v54, v14, s33, v15
	v_add_u32_e32 v68, 0xb000, v89
	v_add_u32_e32 v67, 0xd000, v89
	s_waitcnt lgkmcnt(0)
	v_mfma_f32_16x16x32_bf16 v[42:45], v[58:61], v[54:57], v[42:45]
	ds_read2_b64 v[58:61], v68 offset0:32 offset1:36
	v_add_u32_e32 v66, 0xf000, v89
	v_bfe_u32 v15, v65, 16, 1
	s_waitcnt lgkmcnt(0)
	v_mfma_f32_16x16x32_bf16 v[46:49], v[58:61], v[54:57], v[46:49]
	ds_read2_b64 v[58:61], v67 offset0:64 offset1:68
	v_add3_u32 v15, v65, v15, s91
	v_add_u32_e32 v65, 0x9000, v87
	s_waitcnt lgkmcnt(0)
	v_mfma_f32_16x16x32_bf16 v[50:53], v[58:61], v[54:57], v[50:53]
	ds_read2_b64 v[58:61], v66 offset0:96 offset1:100
	v_bfe_u32 v3, v101, 16, 1
	s_waitcnt lgkmcnt(0)
	v_mfma_f32_16x16x32_bf16 v[38:41], v[58:61], v[54:57], v[38:41]
	ds_read2_b64 v[58:61], v65 offset1:4
	v_bfe_u32 v54, v77, 16, 1
	v_bfe_u32 v55, v95, 16, 1
	v_bfe_u32 v56, v99, 16, 1
	v_bfe_u32 v6, v97, 16, 1
	v_bfe_u32 v7, v93, 16, 1
	v_bfe_u32 v14, v64, 16, 1
	v_add3_u32 v56, v99, v56, s91
	v_add3_u32 v55, v95, v55, s91
	v_add3_u32 v54, v77, v54, s91
	v_add3_u32 v14, v64, v14, s91
	v_add3_u32 v7, v93, v7, s91
	v_add3_u32 v6, v97, v6, s91
	v_add3_u32 v3, v101, v3, s91
	v_lshrrev_b32_e32 v15, 16, v15
	v_lshrrev_b32_e32 v54, 16, v54
	v_lshrrev_b32_e32 v55, 16, v55
	v_lshrrev_b32_e32 v56, 16, v56
	v_and_or_b32 v57, v3, s33, v56
	v_and_or_b32 v56, v6, s33, v55
	v_and_or_b32 v55, v7, s33, v54
	v_and_or_b32 v54, v14, s33, v15
	v_add_u32_e32 v64, 0xb000, v87
	v_add_u32_e32 v63, 0xd000, v87
	s_waitcnt lgkmcnt(0)
	v_mfma_f32_16x16x32_bf16 v[42:45], v[58:61], v[54:57], v[42:45]
	ds_read2_b64 v[58:61], v64 offset0:32 offset1:36
	v_add_u32_e32 v62, 0xf000, v87
	v_bfe_u32 v15, v111, 16, 1
	s_waitcnt lgkmcnt(0)
	v_mfma_f32_16x16x32_bf16 v[46:49], v[58:61], v[54:57], v[46:49]
	ds_read2_b64 v[58:61], v63 offset0:64 offset1:68
	v_bfe_u32 v3, v118, 16, 1
	v_bfe_u32 v6, v116, 16, 1
	s_waitcnt lgkmcnt(0)
	v_mfma_f32_16x16x32_bf16 v[50:53], v[58:61], v[54:57], v[50:53]
	ds_read2_b64 v[58:61], v62 offset0:96 offset1:100
	v_bfe_u32 v7, v114, 16, 1
	s_waitcnt lgkmcnt(0)
	v_mfma_f32_16x16x32_bf16 v[38:41], v[58:61], v[54:57], v[38:41]
	v_add_u32_e32 v61, 0x9000, v85
	ds_read2_b64 v[74:77], v61 offset1:4
	v_bfe_u32 v54, v113, 16, 1
	v_bfe_u32 v55, v115, 16, 1
	v_bfe_u32 v56, v117, 16, 1
	v_bfe_u32 v14, v112, 16, 1
	v_add3_u32 v56, v117, v56, s91
	v_add3_u32 v55, v115, v55, s91
	v_add3_u32 v54, v113, v54, s91
	v_add3_u32 v15, v111, v15, s91
	v_add3_u32 v14, v112, v14, s91
	v_add3_u32 v7, v114, v7, s91
	v_add3_u32 v6, v116, v6, s91
	v_add3_u32 v3, v118, v3, s91
	v_lshrrev_b32_e32 v15, 16, v15
	v_lshrrev_b32_e32 v54, 16, v54
	v_lshrrev_b32_e32 v55, 16, v55
	v_lshrrev_b32_e32 v56, 16, v56
	v_and_or_b32 v57, v3, s33, v56
	v_and_or_b32 v56, v6, s33, v55
	v_and_or_b32 v55, v7, s33, v54
	v_and_or_b32 v54, v14, s33, v15
	v_add_u32_e32 v60, 0xb000, v85
	v_add_u32_e32 v59, 0xd000, v85
	s_waitcnt lgkmcnt(0)
	v_mfma_f32_16x16x32_bf16 v[42:45], v[74:77], v[54:57], v[42:45]
	ds_read2_b64 v[74:77], v60 offset0:32 offset1:36
	v_add_u32_e32 v58, 0xf000, v85
	v_bfe_u32 v3, v126, 16, 1
	s_waitcnt lgkmcnt(0)
	v_mfma_f32_16x16x32_bf16 v[46:49], v[74:77], v[54:57], v[46:49]
	ds_read2_b64 v[74:77], v59 offset0:64 offset1:68
	v_bfe_u32 v6, v124, 16, 1
	v_bfe_u32 v7, v122, 16, 1
	s_waitcnt lgkmcnt(0)
	v_mfma_f32_16x16x32_bf16 v[74:77], v[74:77], v[54:57], v[50:53]
	s_nop 2
	ds_read2_b64 v[50:53], v58 offset0:96 offset1:100
	v_add3_u32 v7, v122, v7, s91
	s_waitcnt lgkmcnt(0)
	v_mfma_f32_16x16x32_bf16 v[38:41], v[50:53], v[54:57], v[38:41]
	v_bfe_u32 v50, v121, 16, 1
	v_bfe_u32 v51, v123, 16, 1
	v_bfe_u32 v52, v125, 16, 1
	v_add3_u32 v52, v125, v52, s91
	v_add3_u32 v51, v123, v51, s91
	v_add3_u32 v50, v121, v50, s91
	v_add3_u32 v6, v124, v6, s91
	v_add3_u32 v3, v126, v3, s91
	v_lshrrev_b32_e32 v50, 16, v50
	v_lshrrev_b32_e32 v51, 16, v51
	v_lshrrev_b32_e32 v52, 16, v52
	v_add_u32_e32 v57, 0x9000, v83
	v_and_or_b32 v115, v3, s33, v52
	v_and_or_b32 v114, v6, s33, v51
	v_and_or_b32 v113, v7, s33, v50
	ds_read2_b64 v[50:53], v57 offset1:4
	v_bfe_u32 v15, v119, 16, 1
	v_bfe_u32 v14, v120, 16, 1
	v_add3_u32 v15, v119, v15, s91
	v_add3_u32 v14, v120, v14, s91
	v_lshrrev_b32_e32 v15, 16, v15
	v_and_or_b32 v112, v14, s33, v15
	v_add_u32_e32 v56, 0xb000, v83
	v_div_scale_f32 v3, s[48:49], v2, v2, 1.0
	s_waitcnt lgkmcnt(0)
	v_mfma_f32_16x16x32_bf16 v[50:53], v[50:53], v[112:115], v[42:45]
	v_rcp_f32_e32 v6, v3
	v_add_u32_e32 v55, 0xd000, v83
	v_add_u32_e32 v54, 0xf000, v83
	ds_read2_b64 v[42:45], v56 offset0:32 offset1:36
	v_fma_f32 v7, -v3, v6, 1.0
	v_fmac_f32_e32 v6, v7, v6
	v_div_scale_f32 v7, vcc, 1.0, v2, 1.0
	v_mul_f32_e32 v14, v7, v6
	v_fma_f32 v15, -v3, v14, v7
	v_fmac_f32_e32 v14, v15, v6
	s_waitcnt lgkmcnt(0)
	v_mfma_f32_16x16x32_bf16 v[46:49], v[42:45], v[112:115], v[46:49]
	ds_read2_b64 v[42:45], v55 offset0:64 offset1:68
	v_fma_f32 v3, -v3, v14, v7
	v_div_fmas_f32 v3, v3, v6, v14
	v_div_fixup_f32 v6, v3, v2, 1.0
	v_mov_b32_e32 v14, v50
	v_mov_b32_e32 v15, v52
	v_pk_mul_f32 v[14:15], v[6:7], v[14:15] op_sel_hi:[0,1]
	v_mov_b32_e32 v52, v51
	v_pk_mul_f32 v[50:51], v[6:7], v[52:53] op_sel_hi:[0,1]
	v_and_b32_sdwa v7, v15, v218 dst_sel:DWORD dst_unused:UNUSED_PAD src0_sel:WORD_1 src1_sel:DWORD
	v_and_b32_sdwa v52, v14, v218 dst_sel:DWORD dst_unused:UNUSED_PAD src0_sel:WORD_1 src1_sel:DWORD
	v_add3_u32 v14, v14, v52, s91
	v_add3_u32 v7, v15, v7, s91
	v_and_b32_sdwa v15, v51, v218 dst_sel:DWORD dst_unused:UNUSED_PAD src0_sel:WORD_1 src1_sel:DWORD
	v_and_b32_sdwa v52, v50, v218 dst_sel:DWORD dst_unused:UNUSED_PAD src0_sel:WORD_1 src1_sel:DWORD
	v_add3_u32 v15, v51, v15, s91
	v_add3_u32 v50, v50, v52, s91
	v_and_b32_e32 v15, 0xffff0000, v15
	v_and_b32_e32 v50, 0xffff0000, v50
	v_lshl_add_u64 v[2:3], v[80:81], 0, s[92:93]
	v_or_b32_sdwa v15, v15, v7 dst_sel:DWORD dst_unused:UNUSED_PAD src0_sel:DWORD src1_sel:WORD_1
	v_or_b32_sdwa v14, v50, v14 dst_sel:DWORD dst_unused:UNUSED_PAD src0_sel:DWORD src1_sel:WORD_1
	s_waitcnt lgkmcnt(0)
	v_mfma_f32_16x16x32_bf16 v[42:45], v[42:45], v[112:115], v[74:77]
	s_mov_b64 s[92:93], s[42:43]
	v_readlane_b32 s11, v255, 9
	v_readlane_b32 s12, v255, 10
	ds_read2_b64 v[74:77], v54 offset0:96 offset1:100
	global_store_dwordx2 v[2:3], v[14:15], off
	v_mov_b32_e32 v14, v46
	v_mov_b32_e32 v15, v48
	v_pk_mul_f32 v[14:15], v[6:7], v[14:15] op_sel_hi:[0,1]
	v_mov_b32_e32 v48, v47
	v_pk_mul_f32 v[46:47], v[6:7], v[48:49] op_sel_hi:[0,1]
	v_and_b32_sdwa v7, v15, v218 dst_sel:DWORD dst_unused:UNUSED_PAD src0_sel:WORD_1 src1_sel:DWORD
	v_and_b32_sdwa v48, v14, v218 dst_sel:DWORD dst_unused:UNUSED_PAD src0_sel:WORD_1 src1_sel:DWORD
	v_add3_u32 v14, v14, v48, s91
	v_add3_u32 v7, v15, v7, s91
	v_and_b32_sdwa v15, v47, v218 dst_sel:DWORD dst_unused:UNUSED_PAD src0_sel:WORD_1 src1_sel:DWORD
	v_and_b32_sdwa v48, v46, v218 dst_sel:DWORD dst_unused:UNUSED_PAD src0_sel:WORD_1 src1_sel:DWORD
	v_add3_u32 v15, v47, v15, s91
	v_add3_u32 v46, v46, v48, s91
	v_and_b32_e32 v15, 0xffff0000, v15
	v_and_b32_e32 v46, 0xffff0000, v46
	v_or_b32_sdwa v15, v15, v7 dst_sel:DWORD dst_unused:UNUSED_PAD src0_sel:DWORD src1_sel:WORD_1
	v_or_b32_sdwa v14, v46, v14 dst_sel:DWORD dst_unused:UNUSED_PAD src0_sel:DWORD src1_sel:WORD_1
	global_store_dwordx2 v[2:3], v[14:15], off offset:32
	v_mov_b32_e32 v14, v42
	v_mov_b32_e32 v15, v44
	v_pk_mul_f32 v[14:15], v[6:7], v[14:15] op_sel_hi:[0,1]
	v_mov_b32_e32 v44, v43
	v_pk_mul_f32 v[42:43], v[6:7], v[44:45] op_sel_hi:[0,1]
	v_and_b32_sdwa v7, v15, v218 dst_sel:DWORD dst_unused:UNUSED_PAD src0_sel:WORD_1 src1_sel:DWORD
	v_and_b32_sdwa v44, v14, v218 dst_sel:DWORD dst_unused:UNUSED_PAD src0_sel:WORD_1 src1_sel:DWORD
	s_waitcnt lgkmcnt(0)
	v_mfma_f32_16x16x32_bf16 v[38:41], v[74:77], v[112:115], v[38:41]
	v_add3_u32 v14, v14, v44, s91
	v_add3_u32 v7, v15, v7, s91
	v_and_b32_sdwa v15, v43, v218 dst_sel:DWORD dst_unused:UNUSED_PAD src0_sel:WORD_1 src1_sel:DWORD
	v_and_b32_sdwa v44, v42, v218 dst_sel:DWORD dst_unused:UNUSED_PAD src0_sel:WORD_1 src1_sel:DWORD
	v_add3_u32 v15, v43, v15, s91
	v_add3_u32 v42, v42, v44, s91
	v_and_b32_e32 v15, 0xffff0000, v15
	v_and_b32_e32 v42, 0xffff0000, v42
	v_or_b32_sdwa v15, v15, v7 dst_sel:DWORD dst_unused:UNUSED_PAD src0_sel:DWORD src1_sel:WORD_1
	v_or_b32_sdwa v14, v42, v14 dst_sel:DWORD dst_unused:UNUSED_PAD src0_sel:DWORD src1_sel:WORD_1
	global_store_dwordx2 v[2:3], v[14:15], off offset:64
	v_mov_b32_e32 v14, v38
	v_mov_b32_e32 v15, v40
	v_pk_mul_f32 v[14:15], v[6:7], v[14:15] op_sel_hi:[0,1]
	v_mov_b32_e32 v40, v39
	v_pk_mul_f32 v[6:7], v[6:7], v[40:41] op_sel_hi:[0,1]
	v_and_b32_sdwa v38, v15, v218 dst_sel:DWORD dst_unused:UNUSED_PAD src0_sel:WORD_1 src1_sel:DWORD
	v_and_b32_sdwa v39, v14, v218 dst_sel:DWORD dst_unused:UNUSED_PAD src0_sel:WORD_1 src1_sel:DWORD
	v_add3_u32 v14, v14, v39, s91
	v_add3_u32 v15, v15, v38, s91
	v_and_b32_sdwa v38, v7, v218 dst_sel:DWORD dst_unused:UNUSED_PAD src0_sel:WORD_1 src1_sel:DWORD
	v_and_b32_sdwa v39, v6, v218 dst_sel:DWORD dst_unused:UNUSED_PAD src0_sel:WORD_1 src1_sel:DWORD
	v_add3_u32 v7, v7, v38, s91
	v_add3_u32 v6, v6, v39, s91
	v_and_b32_e32 v7, 0xffff0000, v7
	v_and_b32_e32 v6, 0xffff0000, v6
	v_or_b32_sdwa v7, v7, v15 dst_sel:DWORD dst_unused:UNUSED_PAD src0_sel:DWORD src1_sel:WORD_1
	v_or_b32_sdwa v6, v6, v14 dst_sel:DWORD dst_unused:UNUSED_PAD src0_sel:DWORD src1_sel:WORD_1
	global_store_dwordx2 v[2:3], v[6:7], off offset:96
	v_lshlrev_b32_e32 v14, 16, v36
	v_and_b32_e32 v2, 0xffff0000, v36
	v_lshlrev_b32_e32 v15, 16, v37
	v_and_b32_e32 v3, 0xffff0000, v37
	ds_read2_b64 v[36:39], v79 offset1:1
	v_lshlrev_b32_e32 v45, 16, v31
	v_and_b32_e32 v43, 0xffff0000, v31
	v_lshlrev_b32_e32 v41, 16, v35
	v_and_b32_e32 v35, 0xffff0000, v35
	s_waitcnt lgkmcnt(0)
	v_readfirstlane_b32 s48, v36
	v_readfirstlane_b32 s49, v37
	s_add_u32 s48, s48, s0
	s_addc_u32 s49, s49, s1
	s_nop 1
	v_lshl_add_u64 v[154:155], s[48:49], 0, v[0:1]
	global_load_dwordx4 v[156:159], v[154:155], off offset:144
	s_nop 1
	v_lshl_add_u64 v[148:149], s[48:49], 0, v[0:1]
	global_load_dwordx4 v[150:153], v[148:149], off offset:16
	v_mov_b32_e32 v46, v43
	v_mov_b32_e32 v47, v45
	v_lshlrev_b32_e32 v44, 16, v30
	v_and_b32_e32 v42, 0xffff0000, v30
	v_lshlrev_b32_e32 v30, 16, v32
	v_and_b32_e32 v6, 0xffff0000, v32
	v_lshlrev_b32_e32 v31, 16, v33
	v_and_b32_e32 v7, 0xffff0000, v33
	v_lshl_add_u64 v[32:33], s[48:49], 0, v[0:1]
	v_mov_b32_e32 v36, v35
	v_mov_b32_e32 v37, v41
	v_pk_mul_f32 v[46:47], v[46:47], v[46:47]
	global_load_dwordx4 v[50:53], v[32:33], off offset:128
	v_pk_fma_f32 v[36:37], v[36:37], v[36:37], v[46:47]
	global_load_dwordx4 v[46:49], v[32:33], off
	v_mov_b32_e32 v74, v7
	v_mov_b32_e32 v75, v31
	v_pk_mul_f32 v[74:75], v[74:75], v[74:75]
	v_lshlrev_b32_e32 v40, 16, v34
	v_and_b32_e32 v34, 0xffff0000, v34
	v_readlane_b32 s13, v255, 11
	v_readlane_b32 s16, v255, 12
	v_readlane_b32 s17, v255, 13
	v_readlane_b32 s76, v255, 16
	v_readlane_b32 s77, v255, 17
	v_readlane_b32 s78, v255, 18
	v_readlane_b32 s79, v255, 19
	s_mov_b64 s[42:43], s[4:5]
	v_readlane_b32 s4, v255, 20
	v_readlane_b32 s5, v255, 21
	v_readlane_b32 s7, v254, 62
	s_waitcnt vmcnt(0) lgkmcnt(0)
	v_mov_b32_e32 v118, v50
	v_mov_b32_e32 v119, v52
	v_mov_b32_e32 v52, v51
	v_mov_b32_e32 v50, v6
	v_mov_b32_e32 v51, v30
	v_mov_b32_e32 v116, v46
	v_mov_b32_e32 v117, v48
	v_mov_b32_e32 v48, v47
	v_mov_b32_e32 v46, v2
	v_mov_b32_e32 v47, v14
	v_pk_mul_f32 v[50:51], v[50:51], v[50:51]
	s_nop 0
	v_pk_fma_f32 v[46:47], v[46:47], v[46:47], v[50:51]
	v_mov_b32_e32 v50, v3
	v_mov_b32_e32 v51, v15
	v_pk_fma_f32 v[50:51], v[50:51], v[50:51], v[74:75]
	s_waitcnt vmcnt(0)
	s_nop 0
	v_mov_b32_e32 v74, v150
	v_mov_b32_e32 v75, v151
	v_mov_b32_e32 v76, v152
	v_mov_b32_e32 v77, v153
	s_nop 1
	s_waitcnt vmcnt(0)
	s_nop 0
	v_mov_b32_e32 v112, v156
	v_mov_b32_e32 v113, v157
	v_mov_b32_e32 v114, v158
	v_mov_b32_e32 v115, v159
	s_nop 1
	v_mul_f32_e32 v32, v34, v34
	v_mul_f32_e32 v33, v40, v40
	v_fmac_f32_e32 v32, v42, v42
	v_fmac_f32_e32 v33, v44, v44
	v_add_f32_e32 v32, v33, v32
	v_add_f32_e32 v32, v37, v32
	v_add_f32_e32 v32, v36, v32
	v_add_f32_e32 v32, v47, v32
	v_add_f32_e32 v32, v46, v32
	v_add_f32_e32 v32, v51, v32
	v_add_f32_e32 v32, v50, v32
	ds_bpermute_b32 v33, v109, v32
	s_waitcnt lgkmcnt(0)
	v_add_f32_e32 v32, v32, v33
	ds_bpermute_b32 v33, v110, v32
	s_waitcnt lgkmcnt(0)
	v_add_f32_e32 v32, v32, v33
	v_fmamk_f32 v32, v32, 0x3c800000, v219
	v_cmp_gt_f32_e32 vcc, s6, v32
	v_mul_f32_e32 v33, 0x4f800000, v32
	s_nop 0
	v_cndmask_b32_e32 v32, v32, v33, vcc
	v_sqrt_f32_e32 v33, v32
	s_nop 0
	v_add_u32_e32 v36, -1, v33
	v_fma_f32 v37, -v36, v33, v32
	v_cmp_ge_f32_e64 s[88:89], 0, v37
	v_add_u32_e32 v37, 1, v33
	s_nop 0
	v_cndmask_b32_e64 v36, v33, v36, s[88:89]
	v_fma_f32 v33, -v37, v33, v32
	v_cmp_lt_f32_e64 s[88:89], 0, v33
	s_nop 1
	v_cndmask_b32_e64 v33, v36, v37, s[88:89]
	v_mul_f32_e32 v36, 0x37800000, v33
	v_cndmask_b32_e32 v33, v33, v36, vcc
	v_cmp_class_f32_e32 vcc, v32, v221
	s_nop 1
	v_cndmask_b32_e32 v32, v33, v32, vcc
	v_div_scale_f32 v33, s[48:49], v32, v32, 1.0
	v_rcp_f32_e32 v36, v33
	v_readfirstlane_b32 s48, v38
	v_readfirstlane_b32 s49, v39
	s_add_u32 s48, s48, s2
	v_fma_f32 v37, -v33, v36, 1.0
	v_fmac_f32_e32 v36, v37, v36
	v_div_scale_f32 v37, vcc, 1.0, v32, 1.0
	v_mul_f32_e32 v46, v37, v36
	v_fma_f32 v47, -v33, v46, v37
	v_fmac_f32_e32 v46, v47, v36
	v_fma_f32 v33, -v33, v46, v37
	v_div_fmas_f32 v33, v33, v36, v46
	v_div_fixup_f32 v32, v33, v32, 1.0
	v_pk_mul_f32 v[34:35], v[32:33], v[34:35] op_sel_hi:[0,1]
	v_pk_mul_f32 v[34:35], v[34:35], v[48:49]
	v_pk_mul_f32 v[14:15], v[32:33], v[14:15] op_sel_hi:[0,1]
	v_pk_mul_f32 v[30:31], v[32:33], v[30:31] op_sel_hi:[0,1]
	v_pk_mul_f32 v[36:37], v[32:33], v[40:41] op_sel_hi:[0,1]
	v_pk_mul_f32 v[40:41], v[32:33], v[44:45] op_sel_hi:[0,1]
	v_pk_mul_f32 v[42:43], v[32:33], v[42:43] op_sel_hi:[0,1]
	v_pk_mul_f32 v[2:3], v[32:33], v[2:3] op_sel_hi:[0,1]
	v_pk_mul_f32 v[6:7], v[32:33], v[6:7] op_sel_hi:[0,1]
	v_pk_mul_f32 v[40:41], v[118:119], v[40:41]
	v_pk_mul_f32 v[36:37], v[116:117], v[36:37]
	v_pk_mul_f32 v[42:43], v[42:43], v[52:53]
	v_pk_mul_f32 v[44:45], v[102:103], v[40:41]
	s_waitcnt vmcnt(0)
	v_mov_b32_e32 v48, v74
	v_mov_b32_e32 v49, v76
	v_pk_mul_f32 v[14:15], v[14:15], v[48:49]
	v_mov_b32_e32 v48, v112
	v_mov_b32_e32 v49, v114
	v_pk_mul_f32 v[30:31], v[30:31], v[48:49]
	v_mov_b32_e32 v114, v113
	v_pk_mul_f32 v[32:33], v[10:11], v[30:31]
	v_mov_b32_e32 v76, v75
	v_pk_mul_f32 v[6:7], v[6:7], v[114:115]
	v_pk_fma_f32 v[32:33], v[18:19], v[14:15], v[32:33]
	v_pk_mul_f32 v[2:3], v[2:3], v[76:77]
	v_pk_mul_f32 v[48:49], v[32:33], s[86:87] op_sel_hi:[1,0]
	v_pk_mul_f32 v[32:33], v[8:9], v[6:7]
	v_pk_fma_f32 v[44:45], v[104:105], v[36:37], v[44:45]
	v_pk_fma_f32 v[32:33], v[16:17], v[2:3], v[32:33]
	v_pk_mul_f32 v[46:47], v[12:13], v[42:43]
	v_pk_mul_f32 v[50:51], v[32:33], s[86:87] op_sel_hi:[1,0]
	v_pk_mul_f32 v[32:33], v[104:105], v[40:41]
	v_pk_fma_f32 v[46:47], v[20:21], v[34:35], v[46:47]
	v_pk_fma_f32 v[32:33], v[102:103], v[36:37], v[32:33] neg_lo:[0,0,1] neg_hi:[0,0,1]
	v_pk_mul_f32 v[36:37], v[20:21], v[42:43]
	v_pk_mul_f32 v[30:31], v[18:19], v[30:31]
	v_pk_fma_f32 v[34:35], v[12:13], v[34:35], v[36:37] neg_lo:[0,0,1] neg_hi:[0,0,1]
	v_pk_fma_f32 v[14:15], v[10:11], v[14:15], v[30:31] neg_lo:[0,0,1] neg_hi:[0,0,1]
	v_pk_mul_f32 v[34:35], v[34:35], s[86:87] op_sel_hi:[1,0]
	v_pk_mul_f32 v[6:7], v[16:17], v[6:7]
	v_pk_mul_f32 v[14:15], v[14:15], s[86:87] op_sel_hi:[1,0]
	v_pk_fma_f32 v[2:3], v[8:9], v[2:3], v[6:7] neg_lo:[0,0,1] neg_hi:[0,0,1]
	v_bfe_u32 v30, v35, 16, 1
	v_bfe_u32 v31, v34, 16, 1
	v_pk_mul_f32 v[2:3], v[2:3], s[86:87] op_sel_hi:[1,0]
	v_add3_u32 v34, v34, v31, s91
	v_add3_u32 v30, v35, v30, s91
	v_bfe_u32 v31, v14, 16, 1
	v_bfe_u32 v35, v15, 16, 1
	ds_read_b128 v[38:41], v100
	v_pk_mul_f32 v[32:33], v[32:33], s[86:87] op_sel_hi:[1,0]
	v_bfe_u32 v6, v3, 16, 1
	v_bfe_u32 v7, v2, 16, 1
	v_add3_u32 v15, v15, v35, s91
	v_add3_u32 v14, v14, v31, s91
	v_pk_mul_f32 v[44:45], v[44:45], s[86:87] op_sel_hi:[1,0]
	v_add3_u32 v2, v2, v7, s91
	v_add3_u32 v3, v3, v6, s91
	v_bfe_u32 v6, v32, 16, 1
	v_bfe_u32 v7, v33, 16, 1
	v_lshrrev_b32_e32 v14, 16, v14
	v_lshrrev_b32_e32 v15, 16, v15
	v_add3_u32 v7, v33, v7, s91
	v_add3_u32 v6, v32, v6, s91
	v_and_or_b32 v33, v3, s33, v15
	v_and_or_b32 v32, v2, s33, v14
	v_bfe_u32 v14, v44, 16, 1
	v_bfe_u32 v15, v45, 16, 1
	v_add3_u32 v15, v45, v15, s91
	v_add3_u32 v14, v44, v14, s91
	ds_read_b128 v[42:45], v100 offset:64
	v_lshrrev_b32_e32 v6, 16, v6
	v_lshrrev_b32_e32 v7, 16, v7
	v_and_or_b32 v31, v30, s33, v7
	v_and_or_b32 v30, v34, s33, v6
	v_pk_mul_f32 v[46:47], v[46:47], s[86:87] op_sel_hi:[1,0]
	v_bfe_u32 v34, v48, 16, 1
	v_bfe_u32 v35, v49, 16, 1
	s_waitcnt lgkmcnt(1)
	v_mfma_f32_16x16x32_bf16 v[38:41], v[38:41], v[30:33], 0
	v_bfe_u32 v2, v51, 16, 1
	v_bfe_u32 v3, v50, 16, 1
	v_bfe_u32 v6, v47, 16, 1
	v_bfe_u32 v7, v46, 16, 1
	v_add3_u32 v35, v49, v35, s91
	v_add3_u32 v34, v48, v34, s91
	v_add3_u32 v7, v46, v7, s91
	v_add3_u32 v6, v47, v6, s91
	v_add3_u32 v3, v50, v3, s91
	v_add3_u32 v2, v51, v2, s91
	v_lshrrev_b32_e32 v14, 16, v14
	v_lshrrev_b32_e32 v15, 16, v15
	v_lshrrev_b32_e32 v34, 16, v34
	v_lshrrev_b32_e32 v35, 16, v35
	v_and_or_b32 v37, v2, s33, v35
	v_and_or_b32 v36, v3, s33, v34
	v_and_or_b32 v35, v6, s33, v15
	v_and_or_b32 v34, v7, s33, v14
	ds_read_b128 v[46:49], v98 offset:64
	s_addc_u32 s49, s49, s3
	s_nop 1
	v_mov_b64_e32 v[160:161], s[48:49]
	global_load_dword v162, v[160:161], off offset:4
	s_waitcnt lgkmcnt(1)
	v_mfma_f32_16x16x32_bf16 v[38:41], v[42:45], v[34:37], v[38:41]
	ds_read_b128 v[42:45], v98
	v_mov_b64_e32 v[2:3], s[48:49]
	s_waitcnt vmcnt(0)
	s_nop 0
	v_mov_b32_e32 v2, v162
	s_nop 1
	s_waitcnt lgkmcnt(0)
	v_mfma_f32_16x16x32_bf16 v[42:45], v[42:45], v[30:33], 0
	ds_read_b128 v[50:53], v96 offset:64
	ds_read_b128 v[74:77], v94 offset:64
	v_mfma_f32_16x16x32_bf16 v[42:45], v[46:49], v[34:37], v[42:45]
	ds_read_b128 v[46:49], v96
	v_mov_b32_e32 v6, s94
	v_cndmask_b32_e64 v3, v38, v6, s[8:9]
	s_waitcnt lgkmcnt(0)
	v_mfma_f32_16x16x32_bf16 v[46:49], v[46:49], v[30:33], 0
	v_cndmask_b32_e64 v7, v39, v227, s[40:41]
	s_mov_b64 s[40:41], s[80:81]
	v_max3_f32 v6, v3, s94, v7
	v_mfma_f32_16x16x32_bf16 v[46:49], v[50:53], v[34:37], v[46:49]
	ds_read_b128 v[50:53], v94
	ds_read_b128 v[112:115], v92 offset:64
	s_waitcnt lgkmcnt(0)
	v_mfma_f32_16x16x32_bf16 v[50:53], v[50:53], v[30:33], 0
	ds_read_b128 v[116:119], v90 offset:64
	v_cndmask_b32_e64 v14, v40, v227, s[40:41]
	v_cndmask_b32_e64 v15, v41, v227, s[92:93]
	v_mfma_f32_16x16x32_bf16 v[50:53], v[74:77], v[34:37], v[50:53]
	ds_read_b128 v[74:77], v92
	v_readlane_b32 s80, v255, 14
	v_readlane_b32 s81, v255, 15
	s_waitcnt lgkmcnt(0)
	v_mfma_f32_16x16x32_bf16 v[74:77], v[74:77], v[30:33], 0
	v_cndmask_b32_e64 v40, v47, v227, s[80:81]
	v_cndmask_b32_e64 v41, v49, v227, s[84:85]
	v_mfma_f32_16x16x32_bf16 v[74:77], v[112:115], v[34:37], v[74:77]
	ds_read_b128 v[112:115], v90
	ds_read_b128 v[120:123], v88 offset:64
	s_waitcnt lgkmcnt(0)
	v_mfma_f32_16x16x32_bf16 v[112:115], v[112:115], v[30:33], 0
	ds_read_b128 v[124:127], v86 offset:64
	s_nop 2
	v_cndmask_b32_e64 v49, v77, v227, s[26:27]
	v_mfma_f32_16x16x32_bf16 v[112:115], v[116:119], v[34:37], v[112:115]
	ds_read_b128 v[116:119], v88
	s_waitcnt lgkmcnt(0)
	v_mfma_f32_16x16x32_bf16 v[116:119], v[116:119], v[30:33], 0
	v_mfma_f32_16x16x32_bf16 v[116:119], v[120:123], v[34:37], v[116:119]
	ds_read_b128 v[120:123], v86
	ds_read_b128 v[128:131], v84 offset:64
	s_waitcnt lgkmcnt(0)
	v_mfma_f32_16x16x32_bf16 v[120:123], v[120:123], v[30:33], 0
	s_nop 3
	v_cndmask_b32_e64 v77, v119, v227, s[52:53]
	v_mfma_f32_16x16x32_bf16 v[120:123], v[124:127], v[34:37], v[120:123]
	ds_read_b128 v[124:127], v84
	s_waitcnt lgkmcnt(0)
	v_mfma_f32_16x16x32_bf16 v[124:127], v[124:127], v[30:33], 0
	s_nop 4
	v_cndmask_b32_e64 v87, v121, v227, s[56:57]
	v_cndmask_b32_e64 v89, v123, v227, s[60:61]
	v_mfma_f32_16x16x32_bf16 v[124:127], v[128:131], v[34:37], v[124:127]
	ds_read_b128 v[128:131], v82
	s_waitcnt lgkmcnt(0)
	v_mfma_f32_16x16x32_bf16 v[30:33], v[128:131], v[30:33], 0
	ds_read_b128 v[128:131], v82 offset:64
	s_nop 3
	v_cndmask_b32_e64 v95, v125, v227, s[64:65]
	v_cndmask_b32_e64 v97, v127, v227, s[68:69]
	s_waitcnt lgkmcnt(0)
	v_mfma_f32_16x16x32_bf16 v[30:33], v[128:131], v[34:37], v[30:33]
	v_max3_f32 v34, v6, v14, v15
	v_mov_b32_e32 v6, s94
	v_cndmask_b32_e64 v35, v42, v6, s[18:19]
	v_cndmask_b32_e64 v36, v43, v227, s[10:11]
	v_max3_f32 v6, v34, v35, v36
	v_cndmask_b32_e64 v34, v44, v227, s[12:13]
	v_cndmask_b32_e64 v37, v45, v227, s[44:45]
	v_max3_f32 v38, v6, v34, v37
	v_mov_b32_e32 v6, s94
	v_cndmask_b32_e64 v39, v46, v6, s[16:17]
	v_max3_f32 v6, v38, v39, v40
	v_cndmask_b32_e64 v38, v48, v227, s[82:83]
	v_max3_f32 v42, v6, v38, v41
	v_mov_b32_e32 v6, s94
	v_cndmask_b32_e64 v43, v50, v6, s[20:21]
	v_cndmask_b32_e64 v44, v51, v227, s[76:77]
	v_max3_f32 v6, v42, v43, v44
	v_cndmask_b32_e64 v42, v52, v227, s[78:79]
	v_cndmask_b32_e64 v45, v53, v227, s[14:15]
	v_max3_f32 v46, v6, v42, v45
	v_mov_b32_e32 v6, s94
	v_cndmask_b32_e64 v47, v74, v6, s[28:29]
	v_cndmask_b32_e64 v48, v75, v227, s[42:43]
	v_max3_f32 v6, v46, v47, v48
	v_cndmask_b32_e64 v46, v76, v227, s[22:23]
	v_max3_f32 v50, v6, v46, v49
	v_mov_b32_e32 v6, s94
	v_cndmask_b32_e64 v51, v112, v6, s[38:39]
	v_cndmask_b32_e64 v52, v113, v227, s[30:31]
	v_max3_f32 v6, v50, v51, v52
	v_cndmask_b32_e64 v50, v114, v227, s[34:35]
	v_cndmask_b32_e64 v53, v115, v227, s[36:37]
	v_max3_f32 v74, v6, v50, v53
	v_mov_b32_e32 v6, s94
	v_cndmask_b32_e64 v75, v116, v6, s[54:55]
	v_cndmask_b32_e64 v76, v117, v227, s[46:47]
	v_max3_f32 v6, v74, v75, v76
	v_cndmask_b32_e64 v74, v118, v227, s[50:51]
	v_max3_f32 v83, v6, v74, v77
	v_mov_b32_e32 v6, s94
	v_cndmask_b32_e64 v85, v120, v6, s[62:63]
	v_max3_f32 v6, v83, v85, v87
	v_cndmask_b32_e64 v83, v122, v227, s[58:59]
	v_max3_f32 v91, v6, v83, v89
	v_mov_b32_e32 v6, s94
	v_cndmask_b32_e64 v93, v124, v6, s[4:5]
	v_max3_f32 v6, v91, v93, v95
	v_cndmask_b32_e64 v91, v126, v227, s[66:67]
	v_max3_f32 v99, v6, v91, v97
	v_mov_b32_e32 v6, s94
	v_cndmask_b32_e64 v6, v30, v6, s[24:25]
	v_cndmask_b32_e64 v30, v31, v227, s[70:71]
	v_max3_f32 v31, v99, v6, v30
	v_cndmask_b32_e64 v32, v32, v227, s[72:73]
	v_cndmask_b32_e64 v33, v33, v227, s[74:75]
	v_max3_f32 v31, v31, v32, v33
	ds_bpermute_b32 v99, v109, v31
	s_lshl_b32 s94, s7, 1
	s_waitcnt lgkmcnt(0)
	v_max_f32_e32 v99, v99, v99
	v_max_f32_e32 v31, v31, v99
	ds_bpermute_b32 v99, v110, v31
	s_waitcnt vmcnt(0) lgkmcnt(0)
	v_max3_f32 v31, v31, v99, v2
	v_sub_f32_e32 v3, v3, v31
	v_mul_f32_e32 v3, 0x3fb8aa3b, v3
	v_sub_f32_e32 v7, v7, v31
	v_exp_f32_e32 v3, v3
	v_mul_f32_e32 v7, 0x3fb8aa3b, v7
	v_sub_f32_e32 v14, v14, v31
	v_exp_f32_e32 v7, v7
	v_mul_f32_e32 v14, 0x3fb8aa3b, v14
	v_sub_f32_e32 v15, v15, v31
	v_exp_f32_e32 v14, v14
	v_mul_f32_e32 v15, 0x3fb8aa3b, v15
	v_sub_f32_e32 v35, v35, v31
	v_exp_f32_e32 v15, v15
	v_mul_f32_e32 v35, 0x3fb8aa3b, v35
	v_sub_f32_e32 v36, v36, v31
	v_add_f32_e32 v99, 0, v3
	v_exp_f32_e32 v35, v35
	v_mul_f32_e32 v36, 0x3fb8aa3b, v36
	v_sub_f32_e32 v34, v34, v31
	v_add_f32_e32 v99, v7, v99
	v_exp_f32_e32 v36, v36
	v_mul_f32_e32 v34, 0x3fb8aa3b, v34
	v_sub_f32_e32 v37, v37, v31
	v_add_f32_e32 v99, v14, v99
	v_exp_f32_e32 v34, v34
	v_mul_f32_e32 v37, 0x3fb8aa3b, v37
	v_sub_f32_e32 v39, v39, v31
	v_add_f32_e32 v99, v15, v99
	v_exp_f32_e32 v37, v37
	v_mul_f32_e32 v39, 0x3fb8aa3b, v39
	v_add_f32_e32 v99, v35, v99
	v_exp_f32_e32 v101, v39
	v_add_f32_e32 v99, v36, v99
	v_add_f32_e32 v99, v34, v99
	v_sub_f32_e32 v40, v40, v31
	v_add_f32_e32 v99, v37, v99
	v_mul_f32_e32 v40, 0x3fb8aa3b, v40
	v_sub_f32_e32 v38, v38, v31
	v_add_f32_e32 v39, v101, v99
	v_exp_f32_e32 v99, v40
	v_mul_f32_e32 v38, 0x3fb8aa3b, v38
	v_exp_f32_e32 v111, v38
	v_sub_f32_e32 v6, v6, v31
	v_add_f32_e32 v39, v99, v39
	v_mul_f32_e32 v6, 0x3fb8aa3b, v6
	v_add_f32_e32 v38, v111, v39
	v_sub_f32_e32 v39, v41, v31
	v_mul_f32_e32 v39, 0x3fb8aa3b, v39
	v_exp_f32_e32 v112, v39
	v_sub_f32_e32 v39, v43, v31
	v_mul_f32_e32 v39, 0x3fb8aa3b, v39
	v_exp_f32_e32 v113, v39
	v_sub_f32_e32 v39, v44, v31
	v_mul_f32_e32 v39, 0x3fb8aa3b, v39
	v_exp_f32_e32 v114, v39
	v_sub_f32_e32 v39, v42, v31
	v_mul_f32_e32 v39, 0x3fb8aa3b, v39
	v_exp_f32_e32 v115, v39
	v_sub_f32_e32 v39, v45, v31
	v_mul_f32_e32 v39, 0x3fb8aa3b, v39
	v_exp_f32_e32 v116, v39
	v_sub_f32_e32 v39, v47, v31
	v_mul_f32_e32 v39, 0x3fb8aa3b, v39
	v_exp_f32_e32 v117, v39
	v_sub_f32_e32 v39, v48, v31
	v_mul_f32_e32 v39, 0x3fb8aa3b, v39
	v_exp_f32_e32 v118, v39
	v_sub_f32_e32 v39, v46, v31
	v_mul_f32_e32 v39, 0x3fb8aa3b, v39
	v_exp_f32_e32 v119, v39
	v_sub_f32_e32 v39, v49, v31
	v_mul_f32_e32 v39, 0x3fb8aa3b, v39
	v_exp_f32_e32 v120, v39
	v_sub_f32_e32 v39, v51, v31
	v_mul_f32_e32 v39, 0x3fb8aa3b, v39
	v_exp_f32_e32 v121, v39
	v_sub_f32_e32 v39, v52, v31
	v_mul_f32_e32 v39, 0x3fb8aa3b, v39
	v_exp_f32_e32 v122, v39
	v_sub_f32_e32 v39, v50, v31
	v_mul_f32_e32 v39, 0x3fb8aa3b, v39
	v_exp_f32_e32 v123, v39
	v_sub_f32_e32 v39, v53, v31
	v_mul_f32_e32 v39, 0x3fb8aa3b, v39
	v_exp_f32_e32 v124, v39
	v_sub_f32_e32 v39, v75, v31
	v_mul_f32_e32 v39, 0x3fb8aa3b, v39
	v_exp_f32_e32 v75, v39
	v_sub_f32_e32 v39, v76, v31
	v_mul_f32_e32 v39, 0x3fb8aa3b, v39
	v_add_f32_e32 v38, v112, v38
	v_exp_f32_e32 v76, v39
	v_sub_f32_e32 v39, v74, v31
	v_add_f32_e32 v38, v113, v38
	v_mul_f32_e32 v39, 0x3fb8aa3b, v39
	v_add_f32_e32 v38, v114, v38
	v_exp_f32_e32 v74, v39
	v_sub_f32_e32 v39, v77, v31
	v_add_f32_e32 v38, v115, v38
	v_mul_f32_e32 v39, 0x3fb8aa3b, v39
	v_add_f32_e32 v38, v116, v38
	v_exp_f32_e32 v77, v39
	v_sub_f32_e32 v39, v85, v31
	v_add_f32_e32 v38, v117, v38
	v_mul_f32_e32 v39, 0x3fb8aa3b, v39
	v_add_f32_e32 v38, v118, v38
	v_exp_f32_e32 v85, v39
	v_sub_f32_e32 v39, v87, v31
	v_add_f32_e32 v38, v119, v38
	v_mul_f32_e32 v39, 0x3fb8aa3b, v39
	v_add_f32_e32 v38, v120, v38
	v_exp_f32_e32 v87, v39
	v_sub_f32_e32 v39, v83, v31
	v_add_f32_e32 v38, v121, v38
	v_mul_f32_e32 v39, 0x3fb8aa3b, v39
	v_add_f32_e32 v38, v122, v38
	v_exp_f32_e32 v83, v39
	v_sub_f32_e32 v39, v89, v31
	v_add_f32_e32 v38, v123, v38
	v_mul_f32_e32 v39, 0x3fb8aa3b, v39
	v_add_f32_e32 v38, v124, v38
	v_exp_f32_e32 v89, v39
	v_sub_f32_e32 v39, v93, v31
	v_add_f32_e32 v38, v75, v38
	v_mul_f32_e32 v39, 0x3fb8aa3b, v39
	v_add_f32_e32 v38, v76, v38
	v_exp_f32_e32 v93, v39
	v_sub_f32_e32 v39, v95, v31
	v_add_f32_e32 v38, v74, v38
	v_mul_f32_e32 v39, 0x3fb8aa3b, v39
	v_add_f32_e32 v38, v77, v38
	v_exp_f32_e32 v95, v39
	v_sub_f32_e32 v39, v91, v31
	v_add_f32_e32 v38, v85, v38
	v_mul_f32_e32 v39, 0x3fb8aa3b, v39
	v_add_f32_e32 v38, v87, v38
	v_exp_f32_e32 v91, v39
	v_sub_f32_e32 v39, v97, v31
	v_add_f32_e32 v38, v83, v38
	v_mul_f32_e32 v39, 0x3fb8aa3b, v39
	v_add_f32_e32 v38, v89, v38
	v_exp_f32_e32 v97, v39
	v_sub_f32_e32 v30, v30, v31
	v_sub_f32_e32 v32, v32, v31
	v_add_f32_e32 v38, v93, v38
	v_exp_f32_e32 v6, v6
	v_mul_f32_e32 v30, 0x3fb8aa3b, v30
	v_mul_f32_e32 v32, 0x3fb8aa3b, v32
	v_add_f32_e32 v38, v95, v38
	v_exp_f32_e32 v125, v30
	v_exp_f32_e32 v126, v32
	v_sub_f32_e32 v32, v33, v31
	v_add_f32_e32 v38, v91, v38
	v_mul_f32_e32 v32, 0x3fb8aa3b, v32
	v_add_f32_e32 v38, v97, v38
	v_exp_f32_e32 v127, v32
	v_add_f32_e32 v38, v6, v38
	v_add_f32_e32 v30, v125, v38
	v_add_f32_e32 v30, v126, v30
	v_add_f32_e32 v30, v127, v30
	ds_bpermute_b32 v32, v109, v30
	v_sub_f32_e32 v2, v2, v31
	v_mul_f32_e32 v2, 0x3fb8aa3b, v2
	v_exp_f32_e32 v2, v2
	v_bfe_u32 v31, v36, 16, 1
	s_waitcnt lgkmcnt(0)
	v_add_f32_e32 v30, v30, v32
	ds_bpermute_b32 v32, v110, v30
	v_bfe_u32 v33, v7, 16, 1
	v_add3_u32 v31, v36, v31, s91
	v_bfe_u32 v36, v35, 16, 1
	v_add3_u32 v7, v7, v33, s91
	s_waitcnt lgkmcnt(0)
	v_add_f32_e32 v30, v30, v32
	v_add_f32_e32 v2, v2, v30
	v_bfe_u32 v30, v37, 16, 1
	v_bfe_u32 v32, v15, 16, 1
	v_add3_u32 v30, v37, v30, s91
	v_bfe_u32 v37, v34, 16, 1
	v_add3_u32 v15, v15, v32, s91
	v_bfe_u32 v32, v3, 16, 1
	v_bfe_u32 v33, v14, 16, 1
	v_add3_u32 v34, v34, v37, s91
	v_add3_u32 v35, v35, v36, s91
	v_add3_u32 v14, v14, v33, s91
	v_add3_u32 v3, v3, v32, s91
	v_lshrrev_b32_e32 v32, 16, v35
	v_lshrrev_b32_e32 v33, 16, v34
	ds_read2_b64 v[34:37], v73 offset1:4
	ds_read2_b64 v[38:41], v72 offset0:32 offset1:36
	ds_read2_b64 v[42:45], v71 offset0:64 offset1:68
	ds_read2_b64 v[46:49], v70 offset0:96 offset1:100
	ds_read2_b64 v[50:53], v69 offset1:4
	v_lshrrev_b32_e32 v3, 16, v3
	v_lshrrev_b32_e32 v14, 16, v14
	v_and_or_b32 v33, v30, s33, v33
	v_and_or_b32 v32, v31, s33, v32
	v_and_or_b32 v31, v15, s33, v14
	v_and_or_b32 v30, v7, s33, v3
	v_bfe_u32 v3, v116, 16, 1
	v_bfe_u32 v7, v114, 16, 1
	s_waitcnt lgkmcnt(4)
	v_mfma_f32_16x16x32_bf16 v[34:37], v[34:37], v[30:33], 0
	v_bfe_u32 v14, v112, 16, 1
	v_bfe_u32 v15, v99, 16, 1
	v_add3_u32 v15, v99, v15, s91
	s_waitcnt lgkmcnt(3)
	v_mfma_f32_16x16x32_bf16 v[38:41], v[38:41], v[30:33], 0
	v_add3_u32 v14, v112, v14, s91
	v_add3_u32 v7, v114, v7, s91
	v_add3_u32 v3, v116, v3, s91
	s_waitcnt lgkmcnt(2)
	v_mfma_f32_16x16x32_bf16 v[42:45], v[42:45], v[30:33], 0
	s_waitcnt lgkmcnt(1)
	v_mfma_f32_16x16x32_bf16 v[30:33], v[46:49], v[30:33], 0
	v_bfe_u32 v46, v101, 16, 1
	v_bfe_u32 v47, v111, 16, 1
	v_bfe_u32 v48, v113, 16, 1
	v_bfe_u32 v49, v115, 16, 1
	v_add3_u32 v49, v115, v49, s91
	v_add3_u32 v48, v113, v48, s91
	v_add3_u32 v47, v111, v47, s91
	v_add3_u32 v46, v101, v46, s91
	v_lshrrev_b32_e32 v46, 16, v46
	v_lshrrev_b32_e32 v47, 16, v47
	v_lshrrev_b32_e32 v48, 16, v48
	v_lshrrev_b32_e32 v49, 16, v49
	v_and_or_b32 v49, v3, s33, v49
	v_and_or_b32 v48, v7, s33, v48
	v_and_or_b32 v47, v14, s33, v47
	v_and_or_b32 v46, v15, s33, v46
	v_bfe_u32 v3, v124, 16, 1
	v_bfe_u32 v7, v122, 16, 1
	s_waitcnt lgkmcnt(0)
	v_mfma_f32_16x16x32_bf16 v[34:37], v[50:53], v[46:49], v[34:37]
	ds_read2_b64 v[50:53], v68 offset0:32 offset1:36
	v_bfe_u32 v14, v120, 16, 1
	v_bfe_u32 v15, v118, 16, 1
	s_waitcnt lgkmcnt(0)
	v_mfma_f32_16x16x32_bf16 v[38:41], v[50:53], v[46:49], v[38:41]
	ds_read2_b64 v[50:53], v67 offset0:64 offset1:68
	v_add3_u32 v15, v118, v15, s91
	v_add3_u32 v14, v120, v14, s91
	s_waitcnt lgkmcnt(0)
	v_mfma_f32_16x16x32_bf16 v[42:45], v[50:53], v[46:49], v[42:45]
	ds_read2_b64 v[50:53], v66 offset0:96 offset1:100
	v_add3_u32 v7, v122, v7, s91
	s_waitcnt lgkmcnt(0)
	v_mfma_f32_16x16x32_bf16 v[30:33], v[50:53], v[46:49], v[30:33]
	ds_read2_b64 v[50:53], v65 offset1:4
	v_bfe_u32 v46, v117, 16, 1
	v_bfe_u32 v47, v119, 16, 1
	v_bfe_u32 v48, v121, 16, 1
	v_bfe_u32 v49, v123, 16, 1
	v_add3_u32 v49, v123, v49, s91
	v_add3_u32 v48, v121, v48, s91
	v_add3_u32 v47, v119, v47, s91
	v_add3_u32 v46, v117, v46, s91
	v_add3_u32 v3, v124, v3, s91
	v_lshrrev_b32_e32 v46, 16, v46
	v_lshrrev_b32_e32 v47, 16, v47
	v_lshrrev_b32_e32 v48, 16, v48
	v_lshrrev_b32_e32 v49, 16, v49
	v_and_or_b32 v49, v3, s33, v49
	v_and_or_b32 v48, v7, s33, v48
	v_and_or_b32 v47, v14, s33, v47
	v_and_or_b32 v46, v15, s33, v46
	v_bfe_u32 v3, v89, 16, 1
	v_bfe_u32 v7, v87, 16, 1
	s_waitcnt lgkmcnt(0)
	v_mfma_f32_16x16x32_bf16 v[34:37], v[50:53], v[46:49], v[34:37]
	ds_read2_b64 v[50:53], v64 offset0:32 offset1:36
	v_bfe_u32 v14, v77, 16, 1
	v_bfe_u32 v15, v76, 16, 1
	s_waitcnt lgkmcnt(0)
	v_mfma_f32_16x16x32_bf16 v[38:41], v[50:53], v[46:49], v[38:41]
	ds_read2_b64 v[50:53], v63 offset0:64 offset1:68
	v_add3_u32 v15, v76, v15, s91
	v_add3_u32 v14, v77, v14, s91
	s_waitcnt lgkmcnt(0)
	v_mfma_f32_16x16x32_bf16 v[42:45], v[50:53], v[46:49], v[42:45]
	ds_read2_b64 v[50:53], v62 offset0:96 offset1:100
	v_add3_u32 v7, v87, v7, s91
	s_waitcnt lgkmcnt(0)
	v_mfma_f32_16x16x32_bf16 v[30:33], v[50:53], v[46:49], v[30:33]
	ds_read2_b64 v[50:53], v61 offset1:4
	v_bfe_u32 v46, v75, 16, 1
	v_bfe_u32 v47, v74, 16, 1
	v_bfe_u32 v48, v85, 16, 1
	v_bfe_u32 v49, v83, 16, 1
	v_add3_u32 v49, v83, v49, s91
	v_add3_u32 v48, v85, v48, s91
	v_add3_u32 v47, v74, v47, s91
	v_add3_u32 v46, v75, v46, s91
	v_add3_u32 v3, v89, v3, s91
	v_lshrrev_b32_e32 v46, 16, v46
	v_lshrrev_b32_e32 v47, 16, v47
	v_lshrrev_b32_e32 v48, 16, v48
	v_lshrrev_b32_e32 v49, 16, v49
	v_and_or_b32 v49, v3, s33, v49
	v_and_or_b32 v48, v7, s33, v48
	v_and_or_b32 v47, v14, s33, v47
	v_and_or_b32 v46, v15, s33, v46
	v_bfe_u32 v3, v127, 16, 1
	v_bfe_u32 v14, v97, 16, 1
	s_waitcnt lgkmcnt(0)
	v_mfma_f32_16x16x32_bf16 v[34:37], v[50:53], v[46:49], v[34:37]
	ds_read2_b64 v[50:53], v60 offset0:32 offset1:36
	v_bfe_u32 v15, v95, 16, 1
	v_add3_u32 v15, v95, v15, s91
	s_waitcnt lgkmcnt(0)
	v_mfma_f32_16x16x32_bf16 v[38:41], v[50:53], v[46:49], v[38:41]
	ds_read2_b64 v[50:53], v59 offset0:64 offset1:68
	v_add3_u32 v14, v97, v14, s91
	v_add3_u32 v3, v127, v3, s91
	s_waitcnt lgkmcnt(0)
	v_mfma_f32_16x16x32_bf16 v[50:53], v[50:53], v[46:49], v[42:45]
	s_nop 2
	ds_read2_b64 v[42:45], v58 offset0:96 offset1:100
	v_bfe_u32 v7, v125, 16, 1
	s_waitcnt lgkmcnt(0)
	v_mfma_f32_16x16x32_bf16 v[30:33], v[42:45], v[46:49], v[30:33]
	v_bfe_u32 v42, v93, 16, 1
	v_bfe_u32 v43, v91, 16, 1
	v_bfe_u32 v45, v126, 16, 1
	v_bfe_u32 v44, v6, 16, 1
	v_add3_u32 v45, v126, v45, s91
	v_add3_u32 v43, v91, v43, s91
	v_add3_u32 v42, v93, v42, s91
	v_add3_u32 v6, v6, v44, s91
	v_lshrrev_b32_e32 v42, 16, v42
	v_lshrrev_b32_e32 v43, 16, v43
	v_lshrrev_b32_e32 v44, 16, v45
	v_and_or_b32 v49, v3, s33, v44
	v_and_or_b32 v47, v14, s33, v43
	v_and_or_b32 v46, v15, s33, v42
	ds_read2_b64 v[42:45], v57 offset1:4
	v_add3_u32 v7, v125, v7, s91
	v_lshrrev_b32_e32 v6, 16, v6
	v_and_or_b32 v48, v7, s33, v6
	v_div_scale_f32 v3, s[48:49], v2, v2, 1.0
	s_waitcnt lgkmcnt(0)
	v_mfma_f32_16x16x32_bf16 v[42:45], v[42:45], v[46:49], v[34:37]
	s_nop 2
	ds_read2_b64 v[34:37], v56 offset0:32 offset1:36
	v_rcp_f32_e32 v6, v3
	s_waitcnt lgkmcnt(0)
	v_mfma_f32_16x16x32_bf16 v[38:41], v[34:37], v[46:49], v[38:41]
	v_fma_f32 v7, -v3, v6, 1.0
	v_fmac_f32_e32 v6, v7, v6
	v_div_scale_f32 v7, vcc, 1.0, v2, 1.0
	v_mul_f32_e32 v14, v7, v6
	v_fma_f32 v15, -v3, v14, v7
	v_fmac_f32_e32 v14, v15, v6
	ds_read2_b64 v[34:37], v55 offset0:64 offset1:68
	v_fma_f32 v3, -v3, v14, v7
	v_div_fmas_f32 v3, v3, v6, v14
	v_div_fixup_f32 v2, v3, v2, 1.0
	v_mov_b32_e32 v14, v42
	v_mov_b32_e32 v15, v44
	v_pk_mul_f32 v[14:15], v[2:3], v[14:15] op_sel_hi:[0,1]
	v_mov_b32_e32 v44, v43
	v_pk_mul_f32 v[42:43], v[2:3], v[44:45] op_sel_hi:[0,1]
	v_and_b32_sdwa v3, v15, v218 dst_sel:DWORD dst_unused:UNUSED_PAD src0_sel:WORD_1 src1_sel:DWORD
	v_and_b32_sdwa v44, v14, v218 dst_sel:DWORD dst_unused:UNUSED_PAD src0_sel:WORD_1 src1_sel:DWORD
	v_add3_u32 v14, v14, v44, s91
	v_add3_u32 v3, v15, v3, s91
	v_and_b32_sdwa v15, v43, v218 dst_sel:DWORD dst_unused:UNUSED_PAD src0_sel:WORD_1 src1_sel:DWORD
	v_and_b32_sdwa v44, v42, v218 dst_sel:DWORD dst_unused:UNUSED_PAD src0_sel:WORD_1 src1_sel:DWORD
	v_add3_u32 v15, v43, v15, s91
	v_add3_u32 v42, v42, v44, s91
	v_and_b32_e32 v15, 0xffff0000, v15
	v_and_b32_e32 v42, 0xffff0000, v42
	v_lshl_add_u64 v[6:7], v[80:81], 0, s[94:95]
	v_or_b32_sdwa v15, v15, v3 dst_sel:DWORD dst_unused:UNUSED_PAD src0_sel:DWORD src1_sel:WORD_1
	v_or_b32_sdwa v14, v42, v14 dst_sel:DWORD dst_unused:UNUSED_PAD src0_sel:DWORD src1_sel:WORD_1
	s_waitcnt lgkmcnt(0)
	v_mfma_f32_16x16x32_bf16 v[34:37], v[34:37], v[46:49], v[50:53]
	v_lshlrev_b32_e32 v44, 16, v22
	v_lshlrev_b32_e32 v45, 16, v23
	v_and_b32_e32 v42, 0xffff0000, v28
	ds_read2_b64 v[50:53], v54 offset0:96 offset1:100
	global_store_dwordx2 v[6:7], v[14:15], off
	v_mov_b32_e32 v14, v38
	v_mov_b32_e32 v15, v40
	v_pk_mul_f32 v[14:15], v[2:3], v[14:15] op_sel_hi:[0,1]
	v_mov_b32_e32 v40, v39
	v_pk_mul_f32 v[38:39], v[2:3], v[40:41] op_sel_hi:[0,1]
	v_and_b32_sdwa v3, v15, v218 dst_sel:DWORD dst_unused:UNUSED_PAD src0_sel:WORD_1 src1_sel:DWORD
	v_and_b32_sdwa v40, v14, v218 dst_sel:DWORD dst_unused:UNUSED_PAD src0_sel:WORD_1 src1_sel:DWORD
	v_add3_u32 v14, v14, v40, s91
	v_add3_u32 v3, v15, v3, s91
	v_and_b32_sdwa v15, v39, v218 dst_sel:DWORD dst_unused:UNUSED_PAD src0_sel:WORD_1 src1_sel:DWORD
	v_and_b32_sdwa v40, v38, v218 dst_sel:DWORD dst_unused:UNUSED_PAD src0_sel:WORD_1 src1_sel:DWORD
	v_add3_u32 v15, v39, v15, s91
	v_add3_u32 v38, v38, v40, s91
	v_and_b32_e32 v15, 0xffff0000, v15
	v_and_b32_e32 v38, 0xffff0000, v38
	v_or_b32_sdwa v15, v15, v3 dst_sel:DWORD dst_unused:UNUSED_PAD src0_sel:DWORD src1_sel:WORD_1
	v_or_b32_sdwa v14, v38, v14 dst_sel:DWORD dst_unused:UNUSED_PAD src0_sel:DWORD src1_sel:WORD_1
	global_store_dwordx2 v[6:7], v[14:15], off offset:32
	v_mov_b32_e32 v14, v34
	v_mov_b32_e32 v15, v36
	v_pk_mul_f32 v[14:15], v[2:3], v[14:15] op_sel_hi:[0,1]
	v_mov_b32_e32 v36, v35
	v_pk_mul_f32 v[34:35], v[2:3], v[36:37] op_sel_hi:[0,1]
	v_and_b32_sdwa v3, v15, v218 dst_sel:DWORD dst_unused:UNUSED_PAD src0_sel:WORD_1 src1_sel:DWORD
	v_and_b32_sdwa v36, v14, v218 dst_sel:DWORD dst_unused:UNUSED_PAD src0_sel:WORD_1 src1_sel:DWORD
	s_waitcnt lgkmcnt(0)
	v_mfma_f32_16x16x32_bf16 v[30:33], v[50:53], v[46:49], v[30:33]
	v_add3_u32 v14, v14, v36, s91
	v_add3_u32 v3, v15, v3, s91
	v_and_b32_sdwa v15, v35, v218 dst_sel:DWORD dst_unused:UNUSED_PAD src0_sel:WORD_1 src1_sel:DWORD
	v_and_b32_sdwa v36, v34, v218 dst_sel:DWORD dst_unused:UNUSED_PAD src0_sel:WORD_1 src1_sel:DWORD
	v_add3_u32 v15, v35, v15, s91
	v_add3_u32 v34, v34, v36, s91
	v_and_b32_e32 v15, 0xffff0000, v15
	v_and_b32_e32 v34, 0xffff0000, v34
	v_or_b32_sdwa v15, v15, v3 dst_sel:DWORD dst_unused:UNUSED_PAD src0_sel:DWORD src1_sel:WORD_1
	v_or_b32_sdwa v14, v34, v14 dst_sel:DWORD dst_unused:UNUSED_PAD src0_sel:DWORD src1_sel:WORD_1
	global_store_dwordx2 v[6:7], v[14:15], off offset:64
	v_mov_b32_e32 v14, v30
	v_mov_b32_e32 v15, v32
	v_pk_mul_f32 v[14:15], v[2:3], v[14:15] op_sel_hi:[0,1]
	v_mov_b32_e32 v32, v31
	v_pk_mul_f32 v[2:3], v[2:3], v[32:33] op_sel_hi:[0,1]
	v_and_b32_sdwa v30, v15, v218 dst_sel:DWORD dst_unused:UNUSED_PAD src0_sel:WORD_1 src1_sel:DWORD
	v_and_b32_sdwa v31, v14, v218 dst_sel:DWORD dst_unused:UNUSED_PAD src0_sel:WORD_1 src1_sel:DWORD
	v_add3_u32 v14, v14, v31, s91
	v_add3_u32 v15, v15, v30, s91
	v_and_b32_sdwa v30, v3, v218 dst_sel:DWORD dst_unused:UNUSED_PAD src0_sel:WORD_1 src1_sel:DWORD
	v_and_b32_sdwa v31, v2, v218 dst_sel:DWORD dst_unused:UNUSED_PAD src0_sel:WORD_1 src1_sel:DWORD
	v_add3_u32 v3, v3, v30, s91
	v_add3_u32 v2, v2, v31, s91
	v_and_b32_e32 v3, 0xffff0000, v3
	v_and_b32_e32 v2, 0xffff0000, v2
	v_or_b32_sdwa v3, v3, v15 dst_sel:DWORD dst_unused:UNUSED_PAD src0_sel:DWORD src1_sel:WORD_1
	v_or_b32_sdwa v2, v2, v14 dst_sel:DWORD dst_unused:UNUSED_PAD src0_sel:DWORD src1_sel:WORD_1
	global_store_dwordx2 v[6:7], v[2:3], off offset:96
	v_and_b32_e32 v46, 0xffff0000, v22
	v_and_b32_e32 v47, 0xffff0000, v23
	v_lshlrev_b32_e32 v48, 16, v24
	v_and_b32_e32 v50, 0xffff0000, v24
	v_lshlrev_b32_e32 v49, 16, v25
	v_and_b32_e32 v51, 0xffff0000, v25
	ds_read2_b64 v[22:25], v79 offset1:1
	v_lshlrev_b32_e32 v3, 16, v27
	v_and_b32_e32 v7, 0xffff0000, v27
	v_lshlrev_b32_e32 v14, 16, v28
	v_lshlrev_b32_e32 v15, 16, v29
	s_waitcnt lgkmcnt(0)
	v_readfirstlane_b32 s48, v22
	v_readfirstlane_b32 s49, v23
	s_add_u32 s0, s48, s0
	v_and_b32_e32 v43, 0xffff0000, v29
	s_addc_u32 s1, s49, s1
	s_nop 1
	v_lshl_add_u64 v[154:155], s[0:1], 0, v[0:1]
	global_load_dwordx4 v[156:159], v[154:155], off offset:144
	s_nop 1
	v_lshl_add_u64 v[148:149], s[0:1], 0, v[0:1]
	global_load_dwordx4 v[150:153], v[148:149], off offset:16
	v_mov_b32_e32 v28, v47
	v_mov_b32_e32 v29, v45
	v_lshlrev_b32_e32 v2, 16, v26
	v_and_b32_e32 v6, 0xffff0000, v26
	v_lshl_add_u64 v[22:23], s[0:1], 0, v[0:1]
	v_mov_b32_e32 v26, v7
	v_mov_b32_e32 v27, v3
	v_pk_mul_f32 v[28:29], v[28:29], v[28:29]
	global_load_dwordx4 v[30:33], v[22:23], off offset:128
	v_pk_fma_f32 v[52:53], v[26:27], v[26:27], v[28:29]
	global_load_dwordx4 v[26:29], v[22:23], off
	v_mov_b32_e32 v34, v51
	v_mov_b32_e32 v35, v49
	v_pk_mul_f32 v[34:35], v[34:35], v[34:35]
	v_mul_f32_e32 v0, v6, v6
	v_fmac_f32_e32 v0, v46, v46
	s_waitcnt vmcnt(0) lgkmcnt(0)
	v_mov_b32_e32 v76, v30
	v_mov_b32_e32 v77, v32
	v_mov_b32_e32 v32, v31
	v_mov_b32_e32 v30, v50
	v_mov_b32_e32 v31, v48
	v_mov_b32_e32 v74, v26
	v_mov_b32_e32 v75, v28
	v_mov_b32_e32 v28, v27
	v_mov_b32_e32 v26, v42
	v_mov_b32_e32 v27, v14
	v_pk_mul_f32 v[30:31], v[30:31], v[30:31]
	s_nop 0
	v_pk_fma_f32 v[26:27], v[26:27], v[26:27], v[30:31]
	v_mov_b32_e32 v30, v43
	v_mov_b32_e32 v31, v15
	v_pk_fma_f32 v[30:31], v[30:31], v[30:31], v[34:35]
	s_waitcnt vmcnt(0)
	s_nop 0
	v_mov_b32_e32 v34, v150
	v_mov_b32_e32 v35, v151
	v_mov_b32_e32 v36, v152
	v_mov_b32_e32 v37, v153
	s_nop 1
	s_waitcnt vmcnt(0)
	s_nop 0
	v_mov_b32_e32 v38, v156
	v_mov_b32_e32 v39, v157
	v_mov_b32_e32 v40, v158
	v_mov_b32_e32 v41, v159
	s_nop 1
	v_mul_f32_e32 v22, v2, v2
	v_fmac_f32_e32 v22, v44, v44
	v_add_f32_e32 v0, v22, v0
	v_add_f32_e32 v0, v53, v0
	v_add_f32_e32 v0, v52, v0
	v_add_f32_e32 v0, v27, v0
	v_add_f32_e32 v0, v26, v0
	v_add_f32_e32 v0, v31, v0
	v_add_f32_e32 v0, v30, v0
	ds_bpermute_b32 v22, v109, v0
	s_waitcnt lgkmcnt(0)
	v_add_f32_e32 v0, v0, v22
	ds_bpermute_b32 v22, v110, v0
	s_waitcnt lgkmcnt(0)
	v_add_f32_e32 v0, v0, v22
	v_fmamk_f32 v0, v0, 0x3c800000, v219
	v_cmp_gt_f32_e32 vcc, s6, v0
	v_mul_f32_e32 v22, 0x4f800000, v0
	s_nop 0
	v_cndmask_b32_e32 v0, v0, v22, vcc
	v_sqrt_f32_e32 v22, v0
	s_nop 0
	v_add_u32_e32 v23, -1, v22
	v_fma_f32 v26, -v23, v22, v0
	v_cmp_ge_f32_e64 s[88:89], 0, v26
	v_add_u32_e32 v26, 1, v22
	s_nop 0
	v_cndmask_b32_e64 v23, v22, v23, s[88:89]
	v_fma_f32 v22, -v26, v22, v0
	v_cmp_lt_f32_e64 s[88:89], 0, v22
	s_nop 1
	v_cndmask_b32_e64 v22, v23, v26, s[88:89]
	v_mul_f32_e32 v23, 0x37800000, v22
	v_cndmask_b32_e32 v22, v22, v23, vcc
	v_cmp_class_f32_e32 vcc, v0, v221
	s_mov_b32 s89, 0xf149f2ca
	s_movk_i32 s88, 0x90
	v_cndmask_b32_e32 v0, v22, v0, vcc
	v_div_scale_f32 v22, s[0:1], v0, v0, 1.0
	v_rcp_f32_e32 v23, v22
	v_readfirstlane_b32 s0, v24
	v_readfirstlane_b32 s1, v25
	s_add_u32 s0, s0, s2
	v_fma_f32 v26, -v22, v23, 1.0
	v_fmac_f32_e32 v23, v26, v23
	v_div_scale_f32 v26, vcc, 1.0, v0, 1.0
	v_mul_f32_e32 v27, v26, v23
	v_fma_f32 v30, -v22, v27, v26
	v_fmac_f32_e32 v27, v30, v23
	v_fma_f32 v22, -v22, v27, v26
	v_div_fmas_f32 v22, v22, v23, v27
	v_div_fixup_f32 v0, v22, v0, 1.0
	v_pk_mul_f32 v[26:27], v[0:1], v[46:47] op_sel_hi:[0,1]
	v_pk_mul_f32 v[6:7], v[0:1], v[6:7] op_sel_hi:[0,1]
	v_pk_mul_f32 v[26:27], v[26:27], v[32:33]
	v_pk_mul_f32 v[14:15], v[0:1], v[14:15] op_sel_hi:[0,1]
	v_pk_mul_f32 v[22:23], v[0:1], v[44:45] op_sel_hi:[0,1]
	v_pk_mul_f32 v[6:7], v[6:7], v[28:29]
	v_pk_mul_f32 v[30:31], v[12:13], v[26:27]
	v_pk_mul_f32 v[42:43], v[0:1], v[42:43] op_sel_hi:[0,1]
	v_pk_fma_f32 v[30:31], v[20:21], v[6:7], v[30:31]
	v_pk_mul_f32 v[20:21], v[20:21], v[26:27]
	v_pk_mul_f32 v[2:3], v[0:1], v[2:3] op_sel_hi:[0,1]
	v_pk_fma_f32 v[6:7], v[12:13], v[6:7], v[20:21] neg_lo:[0,0,1] neg_hi:[0,0,1]
	v_pk_mul_f32 v[22:23], v[76:77], v[22:23]
	v_pk_mul_f32 v[2:3], v[74:75], v[2:3]
	v_pk_mul_f32 v[28:29], v[102:103], v[22:23]
	s_waitcnt vmcnt(0)
	v_mov_b32_e32 v32, v34
	v_mov_b32_e32 v33, v36
	v_pk_mul_f32 v[14:15], v[14:15], v[32:33]
	v_pk_mul_f32 v[32:33], v[0:1], v[48:49] op_sel_hi:[0,1]
	v_mov_b32_e32 v44, v38
	v_mov_b32_e32 v45, v40
	v_mov_b32_e32 v36, v35
	v_pk_mul_f32 v[32:33], v[32:33], v[44:45]
	v_pk_mul_f32 v[34:35], v[42:43], v[36:37]
	v_pk_mul_f32 v[36:37], v[0:1], v[50:51] op_sel_hi:[0,1]
	v_mov_b32_e32 v40, v39
	v_pk_mul_f32 v[36:37], v[36:37], v[40:41]
	v_pk_mul_f32 v[12:13], v[18:19], v[32:33]
	v_pk_mul_f32 v[38:39], v[10:11], v[32:33]
	v_pk_fma_f32 v[10:11], v[10:11], v[14:15], v[12:13] neg_lo:[0,0,1] neg_hi:[0,0,1]
	v_pk_mul_f32 v[12:13], v[16:17], v[36:37]
	v_pk_mul_f32 v[40:41], v[8:9], v[36:37]
	v_pk_mul_f32 v[22:23], v[104:105], v[22:23]
	v_pk_mul_f32 v[6:7], v[6:7], s[86:87] op_sel_hi:[1,0]
	v_pk_fma_f32 v[8:9], v[8:9], v[34:35], v[12:13] neg_lo:[0,0,1] neg_hi:[0,0,1]
	v_pk_fma_f32 v[28:29], v[104:105], v[2:3], v[28:29]
	v_pk_fma_f32 v[38:39], v[18:19], v[14:15], v[38:39]
	v_pk_fma_f32 v[2:3], v[102:103], v[2:3], v[22:23] neg_lo:[0,0,1] neg_hi:[0,0,1]
	v_pk_mul_f32 v[10:11], v[10:11], s[86:87] op_sel_hi:[1,0]
	v_pk_mul_f32 v[8:9], v[8:9], s[86:87] op_sel_hi:[1,0]
	v_bfe_u32 v13, v7, 16, 1
	v_bfe_u32 v14, v6, 16, 1
	v_pk_mul_f32 v[2:3], v[2:3], s[86:87] op_sel_hi:[1,0]
	v_bfe_u32 v0, v9, 16, 1
	v_add3_u32 v6, v6, v14, s91
	v_add3_u32 v7, v7, v13, s91
	v_bfe_u32 v13, v10, 16, 1
	v_bfe_u32 v14, v11, 16, 1
	v_pk_mul_f32 v[28:29], v[28:29], s[86:87] op_sel_hi:[1,0]
	v_bfe_u32 v12, v8, 16, 1
	v_add3_u32 v0, v9, v0, s91
	v_bfe_u32 v9, v2, 16, 1
	v_add3_u32 v11, v11, v14, s91
	v_add3_u32 v10, v10, v13, s91
	v_pk_mul_f32 v[30:31], v[30:31], s[86:87] op_sel_hi:[1,0]
	v_pk_mul_f32 v[38:39], v[38:39], s[86:87] op_sel_hi:[1,0]
	v_add3_u32 v8, v8, v12, s91
	v_bfe_u32 v12, v3, 16, 1
	v_add3_u32 v2, v2, v9, s91
	v_lshrrev_b32_e32 v10, 16, v10
	v_lshrrev_b32_e32 v9, 16, v11
	v_bfe_u32 v11, v28, 16, 1
	v_add3_u32 v3, v3, v12, s91
	v_and_or_b32 v8, v8, s33, v10
	v_bfe_u32 v10, v30, 16, 1
	v_bfe_u32 v12, v29, 16, 1
	v_bfe_u32 v13, v38, 16, 1
	v_bfe_u32 v14, v39, 16, 1
	v_add3_u32 v11, v28, v11, s91
	v_add3_u32 v10, v30, v10, s91
	v_add3_u32 v14, v39, v14, s91
	v_add3_u32 v13, v38, v13, s91
	v_add3_u32 v12, v29, v12, s91
	v_lshrrev_b32_e32 v15, 16, v11
	v_pk_fma_f32 v[40:41], v[16:17], v[34:35], v[40:41]
	v_lshrrev_b32_e32 v11, 16, v12
	v_lshrrev_b32_e32 v12, 16, v13
	v_lshrrev_b32_e32 v13, 16, v14
	v_and_or_b32 v10, v10, s33, v15
	ds_read_b128 v[14:17], v100
	ds_read_b128 v[18:21], v100 offset:64
	v_lshrrev_b32_e32 v2, 16, v2
	v_lshrrev_b32_e32 v3, 16, v3
	v_and_or_b32 v9, v0, s33, v9
	v_and_or_b32 v7, v7, s33, v3
	v_and_or_b32 v6, v6, s33, v2
	v_pk_mul_f32 v[40:41], v[40:41], s[86:87] op_sel_hi:[1,0]
	v_bfe_u32 v3, v31, 16, 1
	s_waitcnt lgkmcnt(1)
	v_mfma_f32_16x16x32_bf16 v[14:17], v[14:17], v[6:9], 0
	v_bfe_u32 v0, v41, 16, 1
	v_bfe_u32 v2, v40, 16, 1
	v_add3_u32 v3, v31, v3, s91
	v_add3_u32 v2, v40, v2, s91
	v_add3_u32 v0, v41, v0, s91
	v_and_or_b32 v13, v0, s33, v13
	v_and_or_b32 v12, v2, s33, v12
	v_and_or_b32 v11, v3, s33, v11
	ds_read_b128 v[22:25], v98 offset:64
	s_addc_u32 s1, s1, s3
	s_nop 1
	v_mov_b64_e32 v[160:161], s[0:1]
	global_load_dword v162, v[160:161], off offset:8
	s_waitcnt lgkmcnt(1)
	v_mfma_f32_16x16x32_bf16 v[14:17], v[18:21], v[10:13], v[14:17]
	ds_read_b128 v[18:21], v98
	v_mov_b64_e32 v[2:3], s[0:1]
	s_waitcnt vmcnt(0)
	s_nop 0
	v_mov_b32_e32 v0, v162
	s_nop 1
	s_waitcnt lgkmcnt(0)
	v_mfma_f32_16x16x32_bf16 v[18:21], v[18:21], v[6:9], 0
	ds_read_b128 v[26:29], v96 offset:64
	ds_read_b128 v[30:33], v94 offset:64
	v_mfma_f32_16x16x32_bf16 v[18:21], v[22:25], v[10:13], v[18:21]
	ds_read_b128 v[22:25], v96
	v_readlane_b32 s0, v255, 22
	v_mov_b32_e32 v2, s89
	s_waitcnt lgkmcnt(0)
	v_mfma_f32_16x16x32_bf16 v[22:25], v[22:25], v[6:9], 0
	v_readlane_b32 s1, v255, 23
	v_cndmask_b32_e64 v3, v14, v2, s[8:9]
	v_mfma_f32_16x16x32_bf16 v[22:25], v[26:29], v[10:13], v[22:25]
	ds_read_b128 v[26:29], v94
	ds_read_b128 v[34:37], v92 offset:64
	s_waitcnt lgkmcnt(0)
	v_mfma_f32_16x16x32_bf16 v[26:29], v[26:29], v[6:9], 0
	ds_read_b128 v[38:41], v90 offset:64
	v_mfma_f32_16x16x32_bf16 v[26:29], v[30:33], v[10:13], v[26:29]
	ds_read_b128 v[30:33], v92
	s_waitcnt lgkmcnt(0)
	v_mfma_f32_16x16x32_bf16 v[30:33], v[30:33], v[6:9], 0
	v_mfma_f32_16x16x32_bf16 v[30:33], v[34:37], v[10:13], v[30:33]
	ds_read_b128 v[34:37], v90
	ds_read_b128 v[42:45], v88 offset:64
	s_waitcnt lgkmcnt(0)
	v_mfma_f32_16x16x32_bf16 v[34:37], v[34:37], v[6:9], 0
	ds_read_b128 v[46:49], v86 offset:64
	v_mfma_f32_16x16x32_bf16 v[34:37], v[38:41], v[10:13], v[34:37]
	ds_read_b128 v[38:41], v88
	s_waitcnt lgkmcnt(0)
	v_mfma_f32_16x16x32_bf16 v[38:41], v[38:41], v[6:9], 0
	s_nop 4
	v_cndmask_b32_e64 v37, v37, v227, s[36:37]
	v_mfma_f32_16x16x32_bf16 v[38:41], v[42:45], v[10:13], v[38:41]
	ds_read_b128 v[42:45], v86
	ds_read_b128 v[50:53], v84 offset:64
	s_waitcnt lgkmcnt(0)
	v_mfma_f32_16x16x32_bf16 v[42:45], v[42:45], v[6:9], 0
	s_nop 3
	v_cndmask_b32_e64 v39, v39, v227, s[46:47]
	v_cndmask_b32_e64 v40, v40, v227, s[50:51]
	v_cndmask_b32_e64 v41, v41, v227, s[52:53]
	v_mfma_f32_16x16x32_bf16 v[42:45], v[46:49], v[10:13], v[42:45]
	ds_read_b128 v[46:49], v84
	s_waitcnt lgkmcnt(0)
	v_mfma_f32_16x16x32_bf16 v[46:49], v[46:49], v[6:9], 0
	s_nop 4
	v_cndmask_b32_e64 v43, v43, v227, s[56:57]
	v_cndmask_b32_e64 v44, v44, v227, s[58:59]
	v_cndmask_b32_e64 v45, v45, v227, s[60:61]
	v_mfma_f32_16x16x32_bf16 v[46:49], v[50:53], v[10:13], v[46:49]
	ds_read_b128 v[50:53], v82
	s_waitcnt lgkmcnt(0)
	v_mfma_f32_16x16x32_bf16 v[6:9], v[50:53], v[6:9], 0
	ds_read_b128 v[50:53], v82 offset:64
	s_nop 3
	v_cndmask_b32_e64 v47, v47, v227, s[64:65]
	v_cndmask_b32_e64 v48, v48, v227, s[66:67]
	s_waitcnt lgkmcnt(0)
	v_mfma_f32_16x16x32_bf16 v[6:9], v[50:53], v[10:13], v[6:9]
	v_cndmask_b32_e64 v10, v15, v227, s[0:1]
	v_max3_f32 v2, v3, s89, v10
	v_cndmask_b32_e64 v11, v16, v227, s[40:41]
	v_cndmask_b32_e64 v12, v17, v227, s[92:93]
	v_max3_f32 v13, v2, v11, v12
	v_mov_b32_e32 v2, s89
	v_cndmask_b32_e64 v14, v18, v2, s[18:19]
	v_cndmask_b32_e64 v15, v19, v227, s[10:11]
	v_max3_f32 v2, v13, v14, v15
	v_cndmask_b32_e64 v13, v20, v227, s[12:13]
	v_cndmask_b32_e64 v16, v21, v227, s[44:45]
	v_max3_f32 v17, v2, v13, v16
	v_mov_b32_e32 v2, s89
	v_cndmask_b32_e64 v18, v22, v2, s[16:17]
	v_cndmask_b32_e64 v19, v23, v227, s[80:81]
	v_max3_f32 v2, v17, v18, v19
	v_cndmask_b32_e64 v17, v24, v227, s[82:83]
	v_cndmask_b32_e64 v20, v25, v227, s[84:85]
	v_max3_f32 v21, v2, v17, v20
	v_mov_b32_e32 v2, s89
	v_cndmask_b32_e64 v22, v26, v2, s[20:21]
	v_cndmask_b32_e64 v23, v27, v227, s[76:77]
	v_max3_f32 v2, v21, v22, v23
	v_cndmask_b32_e64 v21, v28, v227, s[78:79]
	v_cndmask_b32_e64 v24, v29, v227, s[14:15]
	v_max3_f32 v25, v2, v21, v24
	v_mov_b32_e32 v2, s89
	v_cndmask_b32_e64 v26, v30, v2, s[28:29]
	v_cndmask_b32_e64 v27, v31, v227, s[42:43]
	v_max3_f32 v2, v25, v26, v27
	v_cndmask_b32_e64 v25, v32, v227, s[22:23]
	v_cndmask_b32_e64 v50, v33, v227, s[26:27]
	v_max3_f32 v28, v2, v25, v50
	v_mov_b32_e32 v2, s89
	v_cndmask_b32_e64 v51, v34, v2, s[38:39]
	v_cndmask_b32_e64 v52, v35, v227, s[30:31]
	v_max3_f32 v2, v28, v51, v52
	v_cndmask_b32_e64 v53, v36, v227, s[34:35]
	v_max3_f32 v28, v2, v53, v37
	v_mov_b32_e32 v2, s89
	v_cndmask_b32_e64 v38, v38, v2, s[54:55]
	v_max3_f32 v2, v28, v38, v39
	v_max3_f32 v28, v2, v40, v41
	v_mov_b32_e32 v2, s89
	v_cndmask_b32_e64 v42, v42, v2, s[62:63]
	v_max3_f32 v2, v28, v42, v43
	v_max3_f32 v28, v2, v44, v45
	v_mov_b32_e32 v2, s89
	v_cndmask_b32_e64 v46, v46, v2, s[4:5]
	v_max3_f32 v2, v28, v46, v47
	v_cndmask_b32_e64 v49, v49, v227, s[68:69]
	v_max3_f32 v28, v2, v48, v49
	v_mov_b32_e32 v2, s89
	v_cndmask_b32_e64 v74, v6, v2, s[24:25]
	v_cndmask_b32_e64 v75, v7, v227, s[70:71]
	v_max3_f32 v2, v28, v74, v75
	v_cndmask_b32_e64 v76, v8, v227, s[72:73]
	v_cndmask_b32_e64 v77, v9, v227, s[74:75]
	v_max3_f32 v2, v2, v76, v77
	ds_bpermute_b32 v6, v109, v2
	v_readlane_b32 s40, v254, 60
	s_mov_b32 s85, 0xf800000
	s_waitcnt lgkmcnt(0)
	v_max_f32_e32 v6, v6, v6
	v_max_f32_e32 v2, v2, v6
	ds_bpermute_b32 v6, v110, v2
	s_waitcnt vmcnt(0) lgkmcnt(0)
	v_max3_f32 v79, v2, v6, v0
	v_sub_f32_e32 v2, v3, v79
	v_sub_f32_e32 v3, v10, v79
	v_mul_f32_e32 v3, 0x3fb8aa3b, v3
	v_exp_f32_e32 v82, v3
	v_sub_f32_e32 v3, v11, v79
	v_mul_f32_e32 v3, 0x3fb8aa3b, v3
	v_exp_f32_e32 v83, v3
	v_sub_f32_e32 v3, v12, v79
	v_mul_f32_e32 v3, 0x3fb8aa3b, v3
	v_exp_f32_e32 v84, v3
	v_sub_f32_e32 v3, v14, v79
	v_mul_f32_e32 v3, 0x3fb8aa3b, v3
	v_exp_f32_e32 v85, v3
	v_sub_f32_e32 v3, v15, v79
	v_mul_f32_e32 v3, 0x3fb8aa3b, v3
	v_exp_f32_e32 v86, v3
	v_sub_f32_e32 v3, v13, v79
	v_mul_f32_e32 v3, 0x3fb8aa3b, v3
	v_exp_f32_e32 v87, v3
	v_sub_f32_e32 v3, v16, v79
	v_mul_f32_e32 v3, 0x3fb8aa3b, v3
	v_exp_f32_e32 v88, v3
	v_sub_f32_e32 v3, v18, v79
	v_mul_f32_e32 v3, 0x3fb8aa3b, v3
	v_exp_f32_e32 v28, v3
	v_sub_f32_e32 v3, v19, v79
	v_mul_f32_e32 v3, 0x3fb8aa3b, v3
	v_exp_f32_e32 v30, v3
	v_sub_f32_e32 v3, v17, v79
	v_mul_f32_e32 v3, 0x3fb8aa3b, v3
	v_exp_f32_e32 v29, v3
	v_sub_f32_e32 v3, v20, v79
	v_mul_f32_e32 v3, 0x3fb8aa3b, v3
	v_exp_f32_e32 v31, v3
	v_sub_f32_e32 v3, v22, v79
	v_mul_f32_e32 v3, 0x3fb8aa3b, v3
	v_exp_f32_e32 v32, v3
	v_sub_f32_e32 v3, v23, v79
	v_mul_f32_e32 v3, 0x3fb8aa3b, v3
	v_exp_f32_e32 v33, v3
	v_sub_f32_e32 v3, v21, v79
	v_mul_f32_e32 v3, 0x3fb8aa3b, v3
	v_exp_f32_e32 v34, v3
	v_sub_f32_e32 v3, v24, v79
	v_mul_f32_e32 v3, 0x3fb8aa3b, v3
	v_mul_f32_e32 v2, 0x3fb8aa3b, v2
	v_exp_f32_e32 v35, v3
	v_sub_f32_e32 v3, v26, v79
	v_exp_f32_e32 v36, v2
	v_mul_f32_e32 v3, 0x3fb8aa3b, v3
	v_exp_f32_e32 v20, v3
	v_sub_f32_e32 v3, v27, v79
	v_mul_f32_e32 v3, 0x3fb8aa3b, v3
	v_exp_f32_e32 v22, v3
	v_sub_f32_e32 v3, v25, v79
	v_add_f32_e32 v2, 0, v36
	v_mul_f32_e32 v3, 0x3fb8aa3b, v3
	v_add_f32_e32 v2, v82, v2
	v_exp_f32_e32 v21, v3
	v_sub_f32_e32 v3, v50, v79
	v_add_f32_e32 v2, v83, v2
	v_mul_f32_e32 v3, 0x3fb8aa3b, v3
	v_add_f32_e32 v2, v84, v2
	v_exp_f32_e32 v23, v3
	v_sub_f32_e32 v3, v51, v79
	v_add_f32_e32 v2, v85, v2
	v_mul_f32_e32 v3, 0x3fb8aa3b, v3
	v_add_f32_e32 v2, v86, v2
	v_exp_f32_e32 v24, v3
	v_sub_f32_e32 v3, v52, v79
	v_add_f32_e32 v2, v87, v2
	v_mul_f32_e32 v3, 0x3fb8aa3b, v3
	v_add_f32_e32 v2, v88, v2
	v_exp_f32_e32 v25, v3
	v_sub_f32_e32 v3, v53, v79
	v_add_f32_e32 v2, v28, v2
	v_mul_f32_e32 v3, 0x3fb8aa3b, v3
	v_add_f32_e32 v2, v30, v2
	v_exp_f32_e32 v26, v3
	v_sub_f32_e32 v3, v37, v79
	v_add_f32_e32 v2, v29, v2
	v_mul_f32_e32 v3, 0x3fb8aa3b, v3
	v_add_f32_e32 v2, v31, v2
	v_exp_f32_e32 v27, v3
	v_sub_f32_e32 v3, v38, v79
	v_add_f32_e32 v2, v32, v2
	v_mul_f32_e32 v3, 0x3fb8aa3b, v3
	v_add_f32_e32 v2, v33, v2
	v_exp_f32_e32 v12, v3
	v_sub_f32_e32 v3, v39, v79
	v_add_f32_e32 v2, v34, v2
	v_mul_f32_e32 v3, 0x3fb8aa3b, v3
	v_add_f32_e32 v2, v35, v2
	v_exp_f32_e32 v14, v3
	v_sub_f32_e32 v3, v40, v79
	v_add_f32_e32 v2, v20, v2
	v_mul_f32_e32 v3, 0x3fb8aa3b, v3
	v_add_f32_e32 v2, v22, v2
	v_exp_f32_e32 v13, v3
	v_sub_f32_e32 v3, v41, v79
	v_add_f32_e32 v2, v21, v2
	v_mul_f32_e32 v3, 0x3fb8aa3b, v3
	v_add_f32_e32 v2, v23, v2
	v_exp_f32_e32 v15, v3
	v_sub_f32_e32 v3, v42, v79
	v_add_f32_e32 v2, v24, v2
	v_mul_f32_e32 v3, 0x3fb8aa3b, v3
	v_add_f32_e32 v2, v25, v2
	v_exp_f32_e32 v16, v3
	v_sub_f32_e32 v3, v43, v79
	v_add_f32_e32 v2, v26, v2
	v_mul_f32_e32 v3, 0x3fb8aa3b, v3
	v_add_f32_e32 v2, v27, v2
	v_exp_f32_e32 v17, v3
	v_sub_f32_e32 v3, v44, v79
	v_add_f32_e32 v2, v12, v2
	v_mul_f32_e32 v3, 0x3fb8aa3b, v3
	v_add_f32_e32 v2, v14, v2
	v_exp_f32_e32 v18, v3
	v_sub_f32_e32 v3, v45, v79
	v_add_f32_e32 v2, v13, v2
	v_mul_f32_e32 v3, 0x3fb8aa3b, v3
	v_add_f32_e32 v2, v15, v2
	v_exp_f32_e32 v19, v3
	v_add_f32_e32 v2, v16, v2
	v_add_f32_e32 v2, v17, v2
	v_add_f32_e32 v2, v18, v2
	v_add_f32_e32 v3, v19, v2
	v_sub_f32_e32 v2, v46, v79
	v_mul_f32_e32 v2, 0x3fb8aa3b, v2
	v_sub_f32_e32 v6, v47, v79
	v_exp_f32_e32 v2, v2
	v_mul_f32_e32 v6, 0x3fb8aa3b, v6
	v_exp_f32_e32 v6, v6
	v_sub_f32_e32 v8, v49, v79
	v_add_f32_e32 v3, v2, v3
	v_mul_f32_e32 v8, 0x3fb8aa3b, v8
	v_add_f32_e32 v7, v6, v3
	v_sub_f32_e32 v3, v48, v79
	v_mul_f32_e32 v3, 0x3fb8aa3b, v3
	v_exp_f32_e32 v3, v3
	v_exp_f32_e32 v8, v8
	v_sub_f32_e32 v10, v75, v79
	v_mul_f32_e32 v10, 0x3fb8aa3b, v10
	v_add_f32_e32 v7, v3, v7
	v_add_f32_e32 v9, v8, v7
	v_sub_f32_e32 v7, v74, v79
	v_mul_f32_e32 v7, 0x3fb8aa3b, v7
	v_exp_f32_e32 v7, v7
	v_exp_f32_e32 v10, v10
	v_sub_f32_e32 v0, v0, v79
	v_mul_f32_e32 v0, 0x3fb8aa3b, v0
	v_add_f32_e32 v9, v7, v9
	v_add_f32_e32 v11, v10, v9
	v_sub_f32_e32 v9, v76, v79
	v_mul_f32_e32 v9, 0x3fb8aa3b, v9
	v_exp_f32_e32 v9, v9
	v_exp_f32_e32 v0, v0
	v_bfe_u32 v39, v84, 16, 1
	v_add3_u32 v41, v84, v39, s91
	v_add_f32_e32 v37, v9, v11
	v_sub_f32_e32 v11, v77, v79
	v_mul_f32_e32 v11, 0x3fb8aa3b, v11
	v_exp_f32_e32 v11, v11
	v_bfe_u32 v39, v36, 16, 1
	v_bfe_u32 v42, v83, 16, 1
	v_bfe_u32 v43, v85, 16, 1
	v_add_f32_e32 v37, v11, v37
	ds_bpermute_b32 v38, v109, v37
	v_bfe_u32 v44, v87, 16, 1
	v_bfe_u32 v40, v82, 16, 1
	v_add3_u32 v44, v87, v44, s91
	v_add3_u32 v43, v85, v43, s91
	s_waitcnt lgkmcnt(0)
	v_add_f32_e32 v37, v37, v38
	ds_bpermute_b32 v38, v110, v37
	v_add3_u32 v42, v83, v42, s91
	v_add3_u32 v36, v36, v39, s91
	v_add3_u32 v40, v82, v40, s91
	v_lshrrev_b32_e32 v36, 16, v36
	s_waitcnt lgkmcnt(0)
	v_add_f32_e32 v37, v37, v38
	v_add_f32_e32 v0, v0, v37
	v_bfe_u32 v37, v88, 16, 1
	v_bfe_u32 v38, v86, 16, 1
	v_add3_u32 v38, v86, v38, s91
	v_add3_u32 v37, v88, v37, s91
	v_lshrrev_b32_e32 v42, 16, v42
	v_lshrrev_b32_e32 v43, 16, v43
	v_lshrrev_b32_e32 v39, 16, v44
	v_and_or_b32 v39, v37, s33, v39
	v_and_or_b32 v38, v38, s33, v43
	v_and_or_b32 v37, v41, s33, v42
	v_and_or_b32 v36, v40, s33, v36
	ds_read2_b64 v[40:43], v73 offset1:4
	ds_read2_b64 v[44:47], v72 offset0:32 offset1:36
	ds_read2_b64 v[48:51], v71 offset0:64 offset1:68
	ds_read2_b64 v[70:73], v70 offset0:96 offset1:100
	s_waitcnt lgkmcnt(3)
	v_mfma_f32_16x16x32_bf16 v[40:43], v[40:43], v[36:39], 0
	v_bfe_u32 v52, v35, 16, 1
	v_bfe_u32 v53, v33, 16, 1
	s_waitcnt lgkmcnt(2)
	v_mfma_f32_16x16x32_bf16 v[44:47], v[44:47], v[36:39], 0
	s_waitcnt lgkmcnt(1)
	v_mfma_f32_16x16x32_bf16 v[48:51], v[48:51], v[36:39], 0
	s_waitcnt lgkmcnt(0)
	v_mfma_f32_16x16x32_bf16 v[36:39], v[70:73], v[36:39], 0
	v_bfe_u32 v70, v31, 16, 1
	v_bfe_u32 v71, v30, 16, 1
	v_add3_u32 v71, v30, v71, s91
	v_add3_u32 v70, v31, v70, s91
	v_add3_u32 v30, v33, v53, s91
	v_add3_u32 v31, v35, v52, s91
	v_bfe_u32 v52, v32, 16, 1
	v_bfe_u32 v53, v34, 16, 1
	v_bfe_u32 v33, v28, 16, 1
	v_add3_u32 v34, v34, v53, s91
	v_add3_u32 v32, v32, v52, s91
	v_bfe_u32 v35, v29, 16, 1
	v_add3_u32 v28, v28, v33, s91
	v_lshrrev_b32_e32 v32, 16, v32
	v_lshrrev_b32_e32 v33, 16, v34
	v_add3_u32 v29, v29, v35, s91
	v_and_or_b32 v31, v31, s33, v33
	v_and_or_b32 v30, v30, s33, v32
	ds_read2_b64 v[32:35], v69 offset1:4
	v_lshrrev_b32_e32 v28, 16, v28
	v_lshrrev_b32_e32 v29, 16, v29
	v_and_or_b32 v29, v70, s33, v29
	v_and_or_b32 v28, v71, s33, v28
	s_waitcnt lgkmcnt(0)
	s_nop 0
	v_mfma_f32_16x16x32_bf16 v[32:35], v[32:35], v[28:31], v[40:43]
	s_nop 2
	ds_read2_b64 v[40:43], v68 offset0:32 offset1:36
	s_waitcnt lgkmcnt(0)
	v_mfma_f32_16x16x32_bf16 v[40:43], v[40:43], v[28:31], v[44:47]
	s_nop 2
	ds_read2_b64 v[44:47], v67 offset0:64 offset1:68
	s_waitcnt lgkmcnt(0)
	v_mfma_f32_16x16x32_bf16 v[44:47], v[44:47], v[28:31], v[48:51]
	s_nop 2
	ds_read2_b64 v[48:51], v66 offset0:96 offset1:100
	s_waitcnt lgkmcnt(0)
	v_mfma_f32_16x16x32_bf16 v[28:31], v[48:51], v[28:31], v[36:39]
	s_nop 2
	v_bfe_u32 v36, v27, 16, 1
	v_bfe_u32 v37, v25, 16, 1
	v_bfe_u32 v38, v23, 16, 1
	v_bfe_u32 v39, v22, 16, 1
	v_add3_u32 v39, v22, v39, s91
	v_add3_u32 v38, v23, v38, s91
	v_add3_u32 v22, v25, v37, s91
	v_add3_u32 v23, v27, v36, s91
	v_bfe_u32 v36, v24, 16, 1
	v_bfe_u32 v37, v26, 16, 1
	v_bfe_u32 v25, v20, 16, 1
	v_add3_u32 v26, v26, v37, s91
	v_add3_u32 v24, v24, v36, s91
	v_bfe_u32 v27, v21, 16, 1
	v_add3_u32 v20, v20, v25, s91
	v_lshrrev_b32_e32 v24, 16, v24
	v_lshrrev_b32_e32 v25, 16, v26
	v_add3_u32 v21, v21, v27, s91
	v_and_or_b32 v23, v23, s33, v25
	v_and_or_b32 v22, v22, s33, v24
	ds_read2_b64 v[24:27], v65 offset1:4
	v_lshrrev_b32_e32 v20, 16, v20
	v_lshrrev_b32_e32 v21, 16, v21
	v_and_or_b32 v21, v38, s33, v21
	v_and_or_b32 v20, v39, s33, v20
	ds_read2_b64 v[36:39], v63 offset0:64 offset1:68
	s_waitcnt lgkmcnt(1)
	v_mfma_f32_16x16x32_bf16 v[24:27], v[24:27], v[20:23], v[32:35]
	s_nop 2
	ds_read2_b64 v[32:35], v64 offset0:32 offset1:36
	s_waitcnt lgkmcnt(0)
	v_mfma_f32_16x16x32_bf16 v[32:35], v[32:35], v[20:23], v[40:43]
	s_nop 2
	ds_read2_b64 v[40:43], v62 offset0:96 offset1:100
	v_mfma_f32_16x16x32_bf16 v[36:39], v[36:39], v[20:23], v[44:47]
	s_waitcnt lgkmcnt(0)
	v_mfma_f32_16x16x32_bf16 v[20:23], v[40:43], v[20:23], v[28:31]
	s_nop 2
	v_bfe_u32 v28, v19, 16, 1
	v_bfe_u32 v29, v17, 16, 1
	v_bfe_u32 v30, v15, 16, 1
	v_bfe_u32 v31, v14, 16, 1
	v_add3_u32 v31, v14, v31, s91
	v_add3_u32 v30, v15, v30, s91
	v_add3_u32 v14, v17, v29, s91
	v_add3_u32 v15, v19, v28, s91
	v_bfe_u32 v28, v16, 16, 1
	v_bfe_u32 v29, v18, 16, 1
	v_bfe_u32 v17, v12, 16, 1
	v_add3_u32 v18, v18, v29, s91
	v_add3_u32 v16, v16, v28, s91
	v_bfe_u32 v19, v13, 16, 1
	v_add3_u32 v12, v12, v17, s91
	v_lshrrev_b32_e32 v16, 16, v16
	v_lshrrev_b32_e32 v17, 16, v18
	v_add3_u32 v13, v13, v19, s91
	v_and_or_b32 v15, v15, s33, v17
	v_and_or_b32 v14, v14, s33, v16
	ds_read2_b64 v[16:19], v61 offset1:4
	v_lshrrev_b32_e32 v12, 16, v12
	v_lshrrev_b32_e32 v13, 16, v13
	v_and_or_b32 v13, v30, s33, v13
	v_and_or_b32 v12, v31, s33, v12
	ds_read2_b64 v[28:31], v59 offset0:64 offset1:68
	s_waitcnt lgkmcnt(1)
	v_mfma_f32_16x16x32_bf16 v[16:19], v[16:19], v[12:15], v[24:27]
	s_nop 2
	ds_read2_b64 v[24:27], v60 offset0:32 offset1:36
	s_waitcnt lgkmcnt(0)
	v_mfma_f32_16x16x32_bf16 v[24:27], v[24:27], v[12:15], v[32:35]
	s_nop 2
	ds_read2_b64 v[32:35], v58 offset0:96 offset1:100
	v_mfma_f32_16x16x32_bf16 v[28:31], v[28:31], v[12:15], v[36:39]
	s_waitcnt lgkmcnt(0)
	v_mfma_f32_16x16x32_bf16 v[12:15], v[32:35], v[12:15], v[20:23]
	s_nop 2
	v_bfe_u32 v20, v11, 16, 1
	v_bfe_u32 v21, v10, 16, 1
	v_bfe_u32 v22, v8, 16, 1
	v_add3_u32 v22, v8, v22, s91
	v_add3_u32 v8, v10, v21, s91
	v_add3_u32 v10, v11, v20, s91
	v_bfe_u32 v20, v3, 16, 1
	v_bfe_u32 v21, v7, 16, 1
	v_bfe_u32 v23, v6, 16, 1
	v_add3_u32 v7, v7, v21, s91
	v_add3_u32 v3, v3, v20, s91
	v_add3_u32 v6, v6, v23, s91
	v_bfe_u32 v23, v9, 16, 1
	v_lshrrev_b32_e32 v3, 16, v3
	v_lshrrev_b32_e32 v7, 16, v7
	v_add3_u32 v9, v9, v23, s91
	v_and_or_b32 v8, v8, s33, v7
	v_and_or_b32 v7, v22, s33, v3
	ds_read2_b64 v[20:23], v57 offset1:4
	v_bfe_u32 v11, v2, 16, 1
	v_add3_u32 v2, v2, v11, s91
	v_lshrrev_b32_e32 v2, 16, v2
	v_lshrrev_b32_e32 v9, 16, v9
	v_and_or_b32 v9, v10, s33, v9
	v_and_or_b32 v6, v6, s33, v2
	v_div_scale_f32 v2, s[0:1], v0, v0, 1.0
	s_waitcnt lgkmcnt(0)
	v_mfma_f32_16x16x32_bf16 v[16:19], v[20:23], v[6:9], v[16:19]
	ds_read2_b64 v[20:23], v56 offset0:32 offset1:36
	v_rcp_f32_e32 v3, v2
	v_readlane_b32 s0, v254, 63
	s_waitcnt lgkmcnt(0)
	v_mfma_f32_16x16x32_bf16 v[20:23], v[20:23], v[6:9], v[24:27]
	s_nop 2
	ds_read2_b64 v[24:27], v55 offset0:64 offset1:68
	v_fma_f32 v10, -v2, v3, 1.0
	v_fmac_f32_e32 v3, v10, v3
	s_waitcnt lgkmcnt(0)
	v_mfma_f32_16x16x32_bf16 v[24:27], v[24:27], v[6:9], v[28:31]
	s_nop 2
	ds_read2_b64 v[28:31], v54 offset0:96 offset1:100
	v_div_scale_f32 v10, vcc, 1.0, v0, 1.0
	v_mul_f32_e32 v11, v10, v3
	s_waitcnt lgkmcnt(0)
	v_mfma_f32_16x16x32_bf16 v[6:9], v[28:31], v[6:9], v[12:15]
	s_nop 2
	v_fma_f32 v12, -v2, v11, v10
	v_fmac_f32_e32 v11, v12, v3
	v_fma_f32 v2, -v2, v11, v10
	v_div_fmas_f32 v2, v2, v3, v11
	v_div_fixup_f32 v0, v2, v0, 1.0
	v_mov_b32_e32 v10, v16
	v_mov_b32_e32 v11, v18
	v_pk_mul_f32 v[10:11], v[0:1], v[10:11] op_sel_hi:[0,1]
	v_mov_b32_e32 v18, v17
	v_pk_mul_f32 v[12:13], v[0:1], v[18:19] op_sel_hi:[0,1]
	v_and_b32_sdwa v14, v11, v218 dst_sel:DWORD dst_unused:UNUSED_PAD src0_sel:WORD_1 src1_sel:DWORD
	v_and_b32_sdwa v15, v10, v218 dst_sel:DWORD dst_unused:UNUSED_PAD src0_sel:WORD_1 src1_sel:DWORD
	v_add3_u32 v10, v10, v15, s91
	v_add3_u32 v11, v11, v14, s91
	v_and_b32_sdwa v14, v13, v218 dst_sel:DWORD dst_unused:UNUSED_PAD src0_sel:WORD_1 src1_sel:DWORD
	v_and_b32_sdwa v15, v12, v218 dst_sel:DWORD dst_unused:UNUSED_PAD src0_sel:WORD_1 src1_sel:DWORD
	v_add3_u32 v13, v13, v14, s91
	v_add3_u32 v12, v12, v15, s91
	s_lshl_b32 s94, s0, 1
	v_and_b32_e32 v13, 0xffff0000, v13
	v_and_b32_e32 v12, 0xffff0000, v12
	v_lshl_add_u64 v[2:3], v[80:81], 0, s[94:95]
	v_or_b32_sdwa v11, v13, v11 dst_sel:DWORD dst_unused:UNUSED_PAD src0_sel:DWORD src1_sel:WORD_1
	v_or_b32_sdwa v10, v12, v10 dst_sel:DWORD dst_unused:UNUSED_PAD src0_sel:DWORD src1_sel:WORD_1
	global_store_dwordx2 v[2:3], v[10:11], off
	v_mov_b32_e32 v10, v20
	v_mov_b32_e32 v11, v22
	v_pk_mul_f32 v[10:11], v[0:1], v[10:11] op_sel_hi:[0,1]
	v_mov_b32_e32 v22, v21
	v_pk_mul_f32 v[12:13], v[0:1], v[22:23] op_sel_hi:[0,1]
	v_and_b32_sdwa v14, v11, v218 dst_sel:DWORD dst_unused:UNUSED_PAD src0_sel:WORD_1 src1_sel:DWORD
	v_and_b32_sdwa v15, v10, v218 dst_sel:DWORD dst_unused:UNUSED_PAD src0_sel:WORD_1 src1_sel:DWORD
	v_add3_u32 v10, v10, v15, s91
	v_add3_u32 v11, v11, v14, s91
	v_and_b32_sdwa v14, v13, v218 dst_sel:DWORD dst_unused:UNUSED_PAD src0_sel:WORD_1 src1_sel:DWORD
	v_and_b32_sdwa v15, v12, v218 dst_sel:DWORD dst_unused:UNUSED_PAD src0_sel:WORD_1 src1_sel:DWORD
	v_add3_u32 v13, v13, v14, s91
	v_add3_u32 v12, v12, v15, s91
	v_and_b32_e32 v13, 0xffff0000, v13
	v_and_b32_e32 v12, 0xffff0000, v12
	v_or_b32_sdwa v11, v13, v11 dst_sel:DWORD dst_unused:UNUSED_PAD src0_sel:DWORD src1_sel:WORD_1
	v_or_b32_sdwa v10, v12, v10 dst_sel:DWORD dst_unused:UNUSED_PAD src0_sel:DWORD src1_sel:WORD_1
	global_store_dwordx2 v[2:3], v[10:11], off offset:32
	v_mov_b32_e32 v10, v24
	v_mov_b32_e32 v11, v26
	v_pk_mul_f32 v[10:11], v[0:1], v[10:11] op_sel_hi:[0,1]
	v_mov_b32_e32 v26, v25
	v_pk_mul_f32 v[12:13], v[0:1], v[26:27] op_sel_hi:[0,1]
	v_and_b32_sdwa v14, v11, v218 dst_sel:DWORD dst_unused:UNUSED_PAD src0_sel:WORD_1 src1_sel:DWORD
	v_and_b32_sdwa v15, v10, v218 dst_sel:DWORD dst_unused:UNUSED_PAD src0_sel:WORD_1 src1_sel:DWORD
	v_add3_u32 v10, v10, v15, s91
	v_add3_u32 v11, v11, v14, s91
	v_and_b32_sdwa v14, v13, v218 dst_sel:DWORD dst_unused:UNUSED_PAD src0_sel:WORD_1 src1_sel:DWORD
	v_and_b32_sdwa v15, v12, v218 dst_sel:DWORD dst_unused:UNUSED_PAD src0_sel:WORD_1 src1_sel:DWORD
	v_add3_u32 v13, v13, v14, s91
	v_add3_u32 v12, v12, v15, s91
	v_and_b32_e32 v13, 0xffff0000, v13
	v_and_b32_e32 v12, 0xffff0000, v12
	v_or_b32_sdwa v11, v13, v11 dst_sel:DWORD dst_unused:UNUSED_PAD src0_sel:DWORD src1_sel:WORD_1
	v_or_b32_sdwa v10, v12, v10 dst_sel:DWORD dst_unused:UNUSED_PAD src0_sel:DWORD src1_sel:WORD_1
	global_store_dwordx2 v[2:3], v[10:11], off offset:64
	v_mov_b32_e32 v10, v6
	v_mov_b32_e32 v11, v8
	v_pk_mul_f32 v[10:11], v[0:1], v[10:11] op_sel_hi:[0,1]
	v_mov_b32_e32 v8, v7
	v_pk_mul_f32 v[6:7], v[0:1], v[8:9] op_sel_hi:[0,1]
	v_and_b32_sdwa v8, v10, v218 dst_sel:DWORD dst_unused:UNUSED_PAD src0_sel:WORD_1 src1_sel:DWORD
	v_add3_u32 v8, v10, v8, s91
	v_and_b32_sdwa v9, v7, v218 dst_sel:DWORD dst_unused:UNUSED_PAD src0_sel:WORD_1 src1_sel:DWORD
	v_and_b32_sdwa v10, v6, v218 dst_sel:DWORD dst_unused:UNUSED_PAD src0_sel:WORD_1 src1_sel:DWORD
	v_and_b32_sdwa v0, v11, v218 dst_sel:DWORD dst_unused:UNUSED_PAD src0_sel:WORD_1 src1_sel:DWORD
	v_add3_u32 v7, v7, v9, s91
	v_add3_u32 v6, v6, v10, s91
	v_add3_u32 v0, v11, v0, s91
	v_and_b32_e32 v7, 0xffff0000, v7
	v_and_b32_e32 v6, 0xffff0000, v6
	v_or_b32_sdwa v7, v7, v0 dst_sel:DWORD dst_unused:UNUSED_PAD src0_sel:DWORD src1_sel:WORD_1
	v_or_b32_sdwa v6, v6, v8 dst_sel:DWORD dst_unused:UNUSED_PAD src0_sel:DWORD src1_sel:WORD_1
	global_store_dwordx2 v[2:3], v[6:7], off offset:96
	s_waitcnt lgkmcnt(0)
	s_barrier

.LBB0_406:
	s_nop 1
	global_load_dword v148, v[8:9], off
	global_load_dword v13, v[10:11], off
	v_add_u32_e32 v7, 8, v7
	s_waitcnt vmcnt(0) lgkmcnt(0)
	v_mul_f32_e32 v14, v13, v13
	ds_bpermute_b32 v14, v5, v14
	s_waitcnt lgkmcnt(0)
	v_fmac_f32_e32 v14, v13, v13
	ds_bpermute_b32 v15, v106, v14
	s_waitcnt lgkmcnt(0)
	v_add_f32_e32 v14, v14, v15
	ds_bpermute_b32 v15, v107, v14
	s_waitcnt lgkmcnt(0)
	v_add_f32_e32 v14, v14, v15
	ds_bpermute_b32 v15, v108, v14
	s_waitcnt lgkmcnt(0)
	v_add_f32_e32 v14, v14, v15
	ds_bpermute_b32 v15, v109, v14
	s_waitcnt lgkmcnt(0)
	v_add_f32_e32 v14, v14, v15
	ds_bpermute_b32 v15, v110, v14
	s_waitcnt lgkmcnt(0)
	v_add_f32_e32 v14, v14, v15
	v_fmamk_f32 v14, v14, 0x3c800000, v219
	v_cmp_gt_f32_e32 vcc, s85, v14
	v_mul_f32_e32 v15, 0x4f800000, v14
	s_nop 0
	v_cndmask_b32_e32 v14, v14, v15, vcc
	v_sqrt_f32_e32 v15, v14
	s_nop 0
	v_add_u32_e32 v16, -1, v15
	v_fma_f32 v17, -v16, v15, v14
	v_cmp_ge_f32_e64 s[6:7], 0, v17
	v_add_u32_e32 v17, 1, v15
	s_nop 0
	v_cndmask_b32_e64 v16, v15, v16, s[6:7]
	v_fma_f32 v15, -v17, v15, v14
	v_cmp_lt_f32_e64 s[6:7], 0, v15
	s_nop 1
	v_cndmask_b32_e64 v15, v16, v17, s[6:7]
	v_mul_f32_e32 v16, 0x37800000, v15
	v_cndmask_b32_e32 v15, v15, v16, vcc
	v_cmp_class_f32_e32 vcc, v14, v221
	s_nop 1
	v_cndmask_b32_e32 v14, v15, v14, vcc
	v_div_scale_f32 v15, s[6:7], v14, v14, 1.0
	v_rcp_f32_e32 v16, v15
	s_mov_b64 s[6:7], 0x800
	v_lshl_add_u64 v[10:11], v[10:11], 0, s[6:7]
	v_fma_f32 v17, -v15, v16, 1.0
	v_fmac_f32_e32 v16, v17, v16
	v_div_scale_f32 v17, vcc, 1.0, v14, 1.0
	v_mul_f32_e32 v18, v17, v16
	v_fma_f32 v19, -v15, v18, v17
	v_fmac_f32_e32 v18, v19, v16
	v_fma_f32 v15, -v15, v18, v17
	v_div_fmas_f32 v15, v15, v16, v18
	v_div_fixup_f32 v14, v15, v14, 1.0
	v_mul_f32_e32 v13, v13, v14
	s_waitcnt vmcnt(0)
	s_nop 0
	v_mov_b32_e32 v14, v148
	s_nop 1
	v_cmp_lt_i32_e32 vcc, -5, v7
	s_or_b64 s[2:3], vcc, s[2:3]
	s_waitcnt vmcnt(0) lgkmcnt(0)
	v_mul_f32_e32 v13, v14, v13
	v_mul_f32_e32 v13, 0x3e000000, v13
	ds_write_b32 v12, v13
	v_add_u32_e32 v12, 0x800, v12
	s_andn2_b64 exec, exec, s[2:3]
	s_cbranch_execnz .LBB0_406

.LBB0_423:
	global_load_dwordx4 v[24:27], v[12:13], off nt
	ds_read_b32 v20, v15
	v_add_co_u32_e32 v17, vcc, 1, v17
	v_add_u32_e32 v16, 4, v16
	v_add_u32_e32 v15, 16, v15
	v_lshl_add_u64 v[12:13], v[12:13], 0, s[4:5]
	s_or_b64 s[2:3], vcc, s[2:3]
	s_waitcnt vmcnt(0) lgkmcnt(0)
	v_pk_fma_f32 v[8:9], v[26:27], v[20:21], v[8:9] op_sel_hi:[1,0,1]
	v_pk_fma_f32 v[10:11], v[24:25], v[20:21], v[10:11] op_sel_hi:[1,0,1]
	s_andn2_b64 exec, exec, s[2:3]
	s_cbranch_execnz .LBB0_423
	s_or_b64 exec, exec, s[2:3]

.LBB0_434:
	v_and_b32_e32 v15, 0xffffffc0, v6
	v_and_b32_e32 v14, 0xffffffc0, v7
	v_lshl_add_u32 v15, v15, 2, v9
	ds_read2st64_b32 v[12:13], v10 offset1:8
	v_lshl_add_u32 v16, v14, 2, v9
	ds_read_b32 v14, v15 offset:20672
	ds_read_b32 v15, v16 offset:20672
	v_add_u32_e32 v11, -2, v11
	v_cmp_eq_u32_e32 vcc, 0, v11
	v_add_u32_e32 v10, 0x1000, v10
	s_or_b64 s[6:7], vcc, s[6:7]
	s_waitcnt lgkmcnt(0)
	v_pk_add_f32 v[12:13], v[12:13], v[14:15]
	s_nop 0
	v_and_b32_sdwa v14, v13, v218 dst_sel:DWORD dst_unused:UNUSED_PAD src0_sel:WORD_1 src1_sel:DWORD
	v_and_b32_sdwa v15, v12, v218 dst_sel:DWORD dst_unused:UNUSED_PAD src0_sel:WORD_1 src1_sel:DWORD
	v_add3_u32 v16, v13, v14, s91
	v_add3_u32 v17, v12, v15, s91
	v_ashrrev_i32_e32 v15, 31, v6
	v_mov_b32_e32 v14, v6
	v_ashrrev_i32_e32 v13, 31, v7
	v_mov_b32_e32 v12, v7
	v_lshl_add_u64 v[14:15], v[14:15], 1, s[4:5]
	v_add_u32_e32 v7, 0x400, v7
	v_add_u32_e32 v6, 0x400, v6
	v_lshl_add_u64 v[12:13], v[12:13], 1, s[4:5]
	global_store_short_d16_hi v[14:15], v17, off
	global_store_short_d16_hi v[12:13], v16, off
	s_andn2_b64 exec, exec, s[6:7]
	s_cbranch_execnz .LBB0_434
	s_or_b64 exec, exec, s[6:7]
	v_cmp_ne_u32_e32 vcc, v3, v8
	v_lshl_add_u32 v6, v8, 9, v78
	s_orn2_b64 s[4:5], vcc, exec

.LBB0_438:
	v_and_b32_e32 v11, 0x3fffffc0, v6
	v_lshl_add_u32 v11, v11, 2, v3
	ds_read_b32 v7, v10
	ds_read_b32 v11, v11 offset:20672
	v_cmp_lt_i32_e32 vcc, s4, v6
	v_add_u32_e32 v10, 0x800, v10
	s_or_b64 s[2:3], vcc, s[2:3]
	s_waitcnt lgkmcnt(0)
	v_add_f32_e32 v7, v7, v11
	v_bfe_u32 v11, v7, 16, 1
	v_add3_u32 v7, v7, v11, s91
	global_store_short_d16_hi v[8:9], v7, off
	v_add_u32_e32 v7, 0x200, v6
	v_lshl_add_u64 v[8:9], v[8:9], 0, s[6:7]
	v_mov_b32_e32 v6, v7
	s_andn2_b64 exec, exec, s[2:3]
	s_cbranch_execnz .LBB0_438

.LBB0_443:
	s_nop 1
	global_load_dword v150, v[12:13], off
	s_nop 1
	global_load_dword v149, v[10:11], off
	s_nop 1
	global_load_dword v148, v[8:9], off
	v_ashrrev_i32_e32 v15, 31, v14
	v_lshl_add_u64 v[18:19], v[14:15], 2, s[10:11]
	global_load_dword v15, v[18:19], off
	v_add_u32_e32 v3, 8, v3
	v_add_u32_e32 v14, 0x200, v14
	s_waitcnt vmcnt(0) lgkmcnt(0)
	v_mul_f32_e32 v17, v15, v15
	ds_bpermute_b32 v17, v5, v17
	s_waitcnt lgkmcnt(0)
	v_fmac_f32_e32 v17, v15, v15
	ds_bpermute_b32 v18, v106, v17
	s_waitcnt lgkmcnt(0)
	v_add_f32_e32 v17, v17, v18
	ds_bpermute_b32 v18, v107, v17
	s_waitcnt lgkmcnt(0)
	v_add_f32_e32 v17, v17, v18
	ds_bpermute_b32 v18, v108, v17
	s_waitcnt lgkmcnt(0)
	v_add_f32_e32 v17, v17, v18
	ds_bpermute_b32 v18, v109, v17
	s_waitcnt lgkmcnt(0)
	v_add_f32_e32 v17, v17, v18
	ds_bpermute_b32 v18, v110, v17
	s_waitcnt lgkmcnt(0)
	v_add_f32_e32 v17, v17, v18
	v_fmamk_f32 v17, v17, 0x3c800000, v219
	v_cmp_gt_f32_e32 vcc, s85, v17
	v_mul_f32_e32 v18, 0x4f800000, v17
	s_nop 0
	v_cndmask_b32_e32 v17, v17, v18, vcc
	v_sqrt_f32_e32 v18, v17
	s_nop 0
	v_add_u32_e32 v19, -1, v18
	v_fma_f32 v20, -v19, v18, v17
	v_cmp_ge_f32_e64 s[8:9], 0, v20
	v_add_u32_e32 v20, 1, v18
	s_nop 0
	v_cndmask_b32_e64 v19, v18, v19, s[8:9]
	v_fma_f32 v18, -v20, v18, v17
	v_cmp_lt_f32_e64 s[8:9], 0, v18
	s_nop 1
	v_cndmask_b32_e64 v18, v19, v20, s[8:9]
	v_mul_f32_e32 v19, 0x37800000, v18
	v_cndmask_b32_e32 v18, v18, v19, vcc
	v_cmp_class_f32_e32 vcc, v17, v221
	s_nop 1
	v_cndmask_b32_e32 v17, v18, v17, vcc
	v_div_scale_f32 v18, s[8:9], v17, v17, 1.0
	v_rcp_f32_e32 v19, v18
	s_nop 0
	v_fma_f32 v20, -v18, v19, 1.0
	v_fmac_f32_e32 v19, v20, v19
	v_div_scale_f32 v20, vcc, 1.0, v17, 1.0
	v_mul_f32_e32 v21, v20, v19
	v_fma_f32 v23, -v18, v21, v20
	v_fmac_f32_e32 v21, v23, v19
	v_fma_f32 v18, -v18, v21, v20
	v_div_fmas_f32 v18, v18, v19, v21
	v_div_fixup_f32 v17, v18, v17, 1.0
	v_mul_f32_e32 v15, v15, v17
	s_waitcnt vmcnt(0)
	s_nop 0
	v_mov_b32_e32 v17, v148
	s_nop 1
	s_waitcnt vmcnt(0)
	s_nop 0
	v_mov_b32_e32 v18, v149
	s_nop 1
	s_waitcnt vmcnt(0)
	s_nop 0
	v_mov_b32_e32 v19, v150
	s_nop 1
	v_cmp_lt_i32_e32 vcc, 3, v3
	s_or_b64 s[18:19], vcc, s[18:19]
	s_waitcnt vmcnt(0) lgkmcnt(0)
	v_mul_f32_e32 v15, v17, v15
	ds_bpermute_b32 v17, v110, v15
	s_waitcnt lgkmcnt(0)
	v_mul_f32_e32 v17, v19, v17
	v_cndmask_b32_e64 v17, v17, -v17, s[6:7]
	v_fmac_f32_e32 v17, v18, v15
	v_mul_f32_e32 v15, 0x3e000000, v17
	ds_write_b32 v7, v15
	v_add_u32_e32 v7, 0x800, v7
	s_andn2_b64 exec, exec, s[18:19]
	s_cbranch_execnz .LBB0_443
.LBB0_444:
	s_or_b64 exec, exec, s[16:17]
	v_cmp_gt_i32_e32 vcc, 4, v2
	s_and_saveexec_b64 s[8:9], vcc
	s_cbranch_execz .LBB0_447
	s_nop 1
	v_and_b32_e32 v152, 0xffffffc0, v78
	v_or_b32_e32 v148, v152, v22
	v_add_u32_e32 v150, 0x500, v148
	v_ashrrev_i32_e32 v151, 31, v150
	v_lshl_add_u64 v[150:151], v[150:151], 2, s[10:11]
	global_load_dword v149, v[150:151], off
	v_and_b32_e32 v8, 0xffffffc0, v78
	v_or_b32_e32 v3, v8, v22
	v_add_u32_e32 v10, 0x400, v3
	v_ashrrev_i32_e32 v11, 31, v10
	v_lshl_add_u64 v[10:11], v[10:11], 2, s[10:11]
	global_load_dword v9, v[10:11], off
	v_readlane_b32 s6, v254, 15
	s_nop 1
	v_mov_b32_e32 v7, s6
	ds_read_b64 v[10:11], v7
	v_mov_b32_e32 v7, v1
	s_waitcnt lgkmcnt(0)
	v_readfirstlane_b32 s6, v10
	v_readfirstlane_b32 s7, v11
	s_nop 1
	v_lshl_add_u64 v[10:11], s[6:7], 0, v[0:1]
	global_load_dword v12, v[10:11], off
	v_lshl_add_u64 v[10:11], s[12:13], 0, v[6:7]
	v_lshl_add_u64 v[6:7], s[14:15], 0, v[6:7]
	global_load_dword v10, v[10:11], off
	s_nop 0
	global_load_dword v11, v[6:7], off
	v_add_u32_e32 v6, 0x500, v3
	v_ashrrev_i32_e32 v7, 31, v6
	v_lshl_add_u64 v[6:7], v[6:7], 2, s[10:11]
	s_waitcnt vmcnt(0)
	v_mul_f32_e32 v3, v9, v9
	ds_bpermute_b32 v13, v5, v3
	s_waitcnt vmcnt(0)
	s_nop 0
	v_mov_b32_e32 v3, v149
	s_nop 1
	s_waitcnt lgkmcnt(0)
	v_fmac_f32_e32 v13, v9, v9
	ds_bpermute_b32 v6, v106, v13
	s_waitcnt lgkmcnt(0)
	v_add_f32_e32 v6, v13, v6
	ds_bpermute_b32 v7, v107, v6
	s_waitcnt lgkmcnt(0)
	v_add_f32_e32 v6, v6, v7
	ds_bpermute_b32 v7, v108, v6
	s_waitcnt lgkmcnt(0)
	v_add_f32_e32 v6, v6, v7
	ds_bpermute_b32 v7, v109, v6
	s_waitcnt lgkmcnt(0)
	v_add_f32_e32 v6, v6, v7
	ds_bpermute_b32 v7, v110, v6
	s_waitcnt lgkmcnt(0)
	v_add_f32_e32 v6, v6, v7
	v_fmamk_f32 v6, v6, 0x3c800000, v219
	v_mul_f32_e32 v7, 0x4f800000, v6
	v_cmp_gt_f32_e32 vcc, s85, v6
	s_nop 1
	v_cndmask_b32_e32 v6, v6, v7, vcc
	v_sqrt_f32_e32 v7, v6
	s_nop 0
	v_add_u32_e32 v13, -1, v7
	v_add_u32_e32 v14, 1, v7
	v_fma_f32 v15, -v13, v7, v6
	v_fma_f32 v17, -v14, v7, v6
	v_cmp_ge_f32_e64 s[6:7], 0, v15
	s_nop 1
	v_cndmask_b32_e64 v7, v7, v13, s[6:7]
	v_cmp_lt_f32_e64 s[6:7], 0, v17
	s_nop 1
	v_cndmask_b32_e64 v7, v7, v14, s[6:7]
	v_mul_f32_e32 v13, 0x37800000, v7
	v_cndmask_b32_e32 v7, v7, v13, vcc
	v_cmp_class_f32_e32 vcc, v6, v221
	s_nop 1
	v_cndmask_b32_e32 v6, v7, v6, vcc
	v_div_scale_f32 v7, s[6:7], v6, v6, 1.0
	v_rcp_f32_e32 v13, v7
	v_div_scale_f32 v14, vcc, 1.0, v6, 1.0
	v_readlane_b32 s6, v254, 49
	v_fma_f32 v15, -v7, v13, 1.0
	v_fmac_f32_e32 v13, v15, v13
	v_mul_f32_e32 v15, v14, v13
	v_fma_f32 v17, -v7, v15, v14
	v_fmac_f32_e32 v15, v17, v13
	v_fma_f32 v7, -v7, v15, v14
	v_div_fmas_f32 v7, v7, v13, v15
	v_div_fixup_f32 v6, v7, v6, 1.0
	v_mul_f32_e32 v6, v9, v6
	v_mul_f32_e32 v7, v12, v6
	ds_bpermute_b32 v6, v110, v7
	v_cmp_gt_u32_e32 vcc, 32, v22
	v_lshl_add_u32 v9, v78, 2, 0
	v_readlane_b32 s7, v254, 50
	v_add_u32_e32 v9, 0xc0, v9
	s_waitcnt lgkmcnt(0)
	v_mul_f32_e32 v6, v11, v6
	v_cndmask_b32_e64 v6, v6, -v6, vcc
	v_fmac_f32_e32 v6, v10, v7
	s_andn2_b64 vcc, exec, s[6:7]
	s_waitcnt vmcnt(0)
	ds_write2st64_b32 v9, v6, v3 offset0:60 offset1:64
	s_cbranch_vccnz .LBB0_447
	v_readlane_b32 s6, v254, 8
	v_ashrrev_i32_e32 v9, 31, v8
	s_nop 0
	v_mov_b32_e32 v7, s6
	ds_read_b64 v[10:11], v7
	s_lshl_b64 s[6:7], s[94:95], 10
	s_waitcnt lgkmcnt(0)
	v_readfirstlane_b32 s10, v10
	v_readfirstlane_b32 s11, v11
	s_add_u32 s6, s10, s6
	s_addc_u32 s7, s11, s7
	v_lshl_add_u64 v[8:9], v[8:9], 2, s[6:7]
	v_lshl_add_u64 v[8:9], v[8:9], 0, v[0:1]
	v_add_co_u32_e32 v10, vcc, 0x6558000, v8
	s_nop 1
	v_addc_co_u32_e32 v11, vcc, 0, v9, vcc
	global_store_dword v[10:11], v6, off
	v_add_co_u32_e32 v6, vcc, 0x6578000, v8
	s_nop 1
	v_addc_co_u32_e32 v7, vcc, 0, v9, vcc
	global_store_dword v[6:7], v3, off

.LBB0_459:
	v_add_u32_e32 v28, s4, v30
	v_mad_i64_i32 v[6:7], s[4:5], s14, v28, 0
	v_lshl_add_u64 v[10:11], v[6:7], 1, v[2:3]
	v_mov_b32_e32 v14, s9
	global_load_dwordx4 v[6:9], v[10:11], off nt
	s_nop 0
	global_load_dwordx4 v[10:13], v[10:11], off offset:64 nt
	ds_read_b64 v[14:15], v14
	s_lshl_b64 s[4:5], s[12:13], 2
	v_ashrrev_i32_e32 v29, 31, v28
	s_waitcnt lgkmcnt(0)
	v_readfirstlane_b32 s6, v14
	v_readfirstlane_b32 s7, v15
	s_add_u32 s4, s6, s4
	s_addc_u32 s5, s7, s5
	s_nop 1
	v_lshl_add_u64 v[160:161], s[4:5], 0, v[0:1]
	global_load_dwordx4 v[162:165], v[160:161], off offset:144
	s_nop 1
	v_lshl_add_u64 v[154:155], s[4:5], 0, v[0:1]
	global_load_dwordx4 v[156:159], v[154:155], off offset:16
	s_nop 1
	v_lshl_add_u64 v[148:149], s[4:5], 0, v[0:1]
	global_load_dwordx4 v[150:153], v[148:149], off
	v_lshl_add_u64 v[18:19], s[4:5], 0, v[0:1]
	global_load_dwordx4 v[14:17], v[18:19], off offset:128
	s_waitcnt vmcnt(0)
	v_lshlrev_b32_e32 v37, 16, v7
	v_lshlrev_b32_e32 v21, 16, v11
	v_lshlrev_b32_e32 v20, 16, v10
	v_and_b32_e32 v23, 0xffff0000, v11
	v_and_b32_e32 v22, 0xffff0000, v10
	v_and_b32_e32 v35, 0xffff0000, v13
	v_and_b32_e32 v34, 0xffff0000, v12
	v_lshlrev_b32_e32 v36, 16, v6
	v_and_b32_e32 v39, 0xffff0000, v7
	v_and_b32_e32 v38, 0xffff0000, v6
	v_mov_b32_e32 v6, v23
	v_mov_b32_e32 v7, v21
	s_waitcnt lgkmcnt(0)
	v_mov_b32_e32 v24, v14
	v_mov_b32_e32 v25, v16
	v_mov_b32_e32 v16, v15
	v_lshlrev_b32_e32 v15, 16, v13
	v_lshlrev_b32_e32 v14, 16, v12
	s_waitcnt vmcnt(0)
	s_nop 0
	v_mov_b32_e32 v10, v150
	v_mov_b32_e32 v11, v151
	v_mov_b32_e32 v12, v152
	v_mov_b32_e32 v13, v153
	s_nop 1
	v_pk_mul_f32 v[6:7], v[6:7], v[6:7]
	v_mov_b32_e32 v40, v39
	v_mov_b32_e32 v41, v37
	v_pk_fma_f32 v[40:41], v[40:41], v[40:41], v[6:7]
	v_and_b32_e32 v45, 0xffff0000, v9
	v_and_b32_e32 v44, 0xffff0000, v8
	v_mul_f32_e32 v27, v38, v38
	v_mul_f32_e32 v33, v36, v36
	v_fmac_f32_e32 v27, v22, v22
	v_fmac_f32_e32 v33, v20, v20
	v_mov_b32_e32 v46, v34
	v_mov_b32_e32 v47, v14
	v_add_f32_e32 v27, v33, v27
	v_pk_mul_f32 v[46:47], v[46:47], v[46:47]
	v_mov_b32_e32 v48, v44
	v_add_f32_e32 v27, v41, v27
	v_add_f32_e32 v27, v40, v27
	v_mov_b32_e32 v50, v45
	s_waitcnt vmcnt(0) lgkmcnt(0)
	v_mov_b32_e32 v42, v10
	v_mov_b32_e32 v43, v12
	v_mov_b32_e32 v12, v11
	v_lshlrev_b32_e32 v11, 16, v9
	v_lshlrev_b32_e32 v10, 16, v8
	s_waitcnt vmcnt(0)
	s_nop 0
	v_mov_b32_e32 v6, v156
	v_mov_b32_e32 v7, v157
	v_mov_b32_e32 v8, v158
	v_mov_b32_e32 v9, v159
	s_nop 1
	v_mov_b32_e32 v49, v10
	v_pk_fma_f32 v[46:47], v[48:49], v[48:49], v[46:47]
	v_mov_b32_e32 v48, v35
	v_mov_b32_e32 v49, v15
	v_pk_mul_f32 v[48:49], v[48:49], v[48:49]
	v_mov_b32_e32 v51, v11
	v_add_f32_e32 v27, v47, v27
	v_pk_fma_f32 v[48:49], v[50:51], v[50:51], v[48:49]
	v_add_f32_e32 v27, v46, v27
	v_add_f32_e32 v27, v49, v27
	v_add_f32_e32 v27, v48, v27
	ds_bpermute_b32 v33, v109, v27
	s_waitcnt lgkmcnt(0)
	v_add_f32_e32 v27, v27, v33
	ds_bpermute_b32 v33, v110, v27
	s_waitcnt lgkmcnt(0)
	v_add_f32_e32 v27, v27, v33
	v_fmamk_f32 v27, v27, 0x3c800000, v219
	v_cmp_gt_f32_e32 vcc, s85, v27
	v_mul_f32_e32 v33, 0x4f800000, v27
	s_nop 0
	v_cndmask_b32_e32 v27, v27, v33, vcc
	v_sqrt_f32_e32 v33, v27
	s_nop 0
	v_add_u32_e32 v40, -1, v33
	v_fma_f32 v41, -v40, v33, v27
	v_cmp_ge_f32_e64 s[4:5], 0, v41
	v_add_u32_e32 v41, 1, v33
	s_nop 0
	v_cndmask_b32_e64 v40, v33, v40, s[4:5]
	v_fma_f32 v33, -v41, v33, v27
	v_cmp_lt_f32_e64 s[4:5], 0, v33
	s_nop 1
	v_cndmask_b32_e64 v33, v40, v41, s[4:5]
	v_mul_f32_e32 v40, 0x37800000, v33
	v_cndmask_b32_e32 v33, v33, v40, vcc
	v_cmp_class_f32_e32 vcc, v27, v221
	s_nop 1
	v_cndmask_b32_e32 v27, v33, v27, vcc
	v_div_scale_f32 v33, s[4:5], v27, v27, s86
	v_rcp_f32_e32 v40, v33
	s_nop 0
	v_fma_f32 v41, -v33, v40, 1.0
	v_fmac_f32_e32 v40, v41, v40
	v_div_scale_f32 v41, vcc, s86, v27, s86
	v_mul_f32_e32 v46, v41, v40
	v_fma_f32 v47, -v33, v46, v41
	v_fmac_f32_e32 v46, v47, v40
	v_fma_f32 v33, -v33, v46, v41
	v_div_fmas_f32 v33, v33, v40, v46
	v_div_fixup_f32 v40, v33, v27, s86
	v_pk_mul_f32 v[38:39], v[40:41], v[38:39] op_sel_hi:[0,1]
	v_pk_mul_f32 v[12:13], v[12:13], v[38:39]
	v_pk_mul_f32 v[10:11], v[40:41], v[10:11] op_sel_hi:[0,1]
	v_pk_mul_f32 v[36:37], v[40:41], v[36:37] op_sel_hi:[0,1]
	v_pk_mul_f32 v[36:37], v[42:43], v[36:37]
	v_bfe_u32 v27, v13, 16, 1
	v_bfe_u32 v33, v12, 16, 1
	v_add3_u32 v12, v12, v33, s91
	v_add3_u32 v13, v13, v27, s91
	v_pk_mul_f32 v[14:15], v[40:41], v[14:15] op_sel_hi:[0,1]
	s_waitcnt vmcnt(0)
	v_mov_b32_e32 v38, v6
	v_mov_b32_e32 v39, v8
	v_pk_mul_f32 v[10:11], v[38:39], v[10:11]
	v_pk_mul_f32 v[38:39], v[40:41], v[44:45] op_sel_hi:[0,1]
	v_mov_b32_e32 v8, v7
	v_pk_mul_f32 v[6:7], v[8:9], v[38:39]
	v_bfe_u32 v27, v10, 16, 1
	v_bfe_u32 v8, v7, 16, 1
	v_bfe_u32 v9, v6, 16, 1
	v_add3_u32 v6, v6, v9, s91
	v_add3_u32 v7, v7, v8, s91
	v_bfe_u32 v8, v36, 16, 1
	v_bfe_u32 v9, v37, 16, 1
	v_bfe_u32 v33, v11, 16, 1
	v_add3_u32 v11, v11, v33, s91
	v_add3_u32 v10, v10, v27, s91
	v_add3_u32 v9, v37, v9, s91
	v_add3_u32 v8, v36, v8, s91
	v_lshrrev_b32_e32 v27, 16, v8
	v_lshrrev_b32_e32 v33, 16, v9
	v_lshrrev_b32_e32 v8, 16, v10
	v_lshrrev_b32_e32 v9, 16, v11
	v_pk_mul_f32 v[10:11], v[40:41], v[20:21] op_sel_hi:[0,1]
	v_pk_mul_f32 v[20:21], v[24:25], v[10:11]
	v_pk_mul_f32 v[10:11], v[40:41], v[22:23] op_sel_hi:[0,1]
	v_and_or_b32 v9, v7, s33, v9
	v_and_or_b32 v8, v6, s33, v8
	v_and_or_b32 v7, v13, s33, v33
	v_and_or_b32 v6, v12, s33, v27
	v_pk_mul_f32 v[16:17], v[16:17], v[10:11]
	s_waitcnt vmcnt(0)
	s_nop 0
	v_mov_b32_e32 v10, v162
	v_mov_b32_e32 v11, v163
	v_mov_b32_e32 v12, v164
	v_mov_b32_e32 v13, v165
	s_nop 1
	s_waitcnt vmcnt(0) lgkmcnt(0)
	v_mov_b32_e32 v18, v10
	v_mov_b32_e32 v19, v12
	v_pk_mul_f32 v[14:15], v[18:19], v[14:15]
	v_pk_mul_f32 v[18:19], v[40:41], v[34:35] op_sel_hi:[0,1]
	v_mov_b32_e32 v12, v11
	v_pk_mul_f32 v[10:11], v[18:19], v[12:13]
	v_bfe_u32 v18, v17, 16, 1
	v_bfe_u32 v12, v11, 16, 1
	v_bfe_u32 v13, v10, 16, 1
	v_bfe_u32 v19, v16, 16, 1
	v_add3_u32 v16, v16, v19, s91
	v_add3_u32 v17, v17, v18, s91
	v_add3_u32 v10, v10, v13, s91
	v_add3_u32 v11, v11, v12, s91
	v_bfe_u32 v12, v20, 16, 1
	v_bfe_u32 v13, v21, 16, 1
	v_bfe_u32 v18, v14, 16, 1
	v_bfe_u32 v19, v15, 16, 1
	v_add3_u32 v15, v15, v19, s91
	v_add3_u32 v14, v14, v18, s91
	v_add3_u32 v13, v21, v13, s91
	v_add3_u32 v12, v20, v12, s91
	v_lshrrev_b32_e32 v18, 16, v12
	v_lshrrev_b32_e32 v19, 16, v13
	v_lshrrev_b32_e32 v12, 16, v14
	v_lshrrev_b32_e32 v13, 16, v15
	v_and_or_b32 v13, v11, s33, v13
	v_and_or_b32 v12, v10, s33, v12
	v_and_or_b32 v11, v17, s33, v19
	v_and_or_b32 v10, v16, s33, v18
	ds_read_b128 v[14:17], v31
	ds_read_b128 v[18:21], v31 offset:64
	s_waitcnt lgkmcnt(1)
	v_mfma_f32_16x16x32_bf16 v[14:17], v[14:17], v[6:9], 0
	s_waitcnt lgkmcnt(0)
	v_mfma_f32_16x16x32_bf16 v[34:37], v[18:21], v[10:13], v[14:17]
	ds_read_b128 v[18:21], v31 offset:2368
	s_nop 4
	ds_read_b128 v[14:17], v31 offset:2304
	s_waitcnt lgkmcnt(0)
	v_mfma_f32_16x16x32_bf16 v[14:17], v[14:17], v[6:9], 0
	v_mfma_f32_16x16x32_bf16 v[38:41], v[18:21], v[10:13], v[14:17]
	ds_read_b128 v[18:21], v31 offset:4672
	s_nop 5
	ds_read_b128 v[14:17], v31 offset:4608
	s_waitcnt lgkmcnt(0)
	v_mfma_f32_16x16x32_bf16 v[14:17], v[14:17], v[6:9], 0
	v_mfma_f32_16x16x32_bf16 v[42:45], v[18:21], v[10:13], v[14:17]
	ds_read_b128 v[18:21], v31 offset:6976
	s_nop 5
	ds_read_b128 v[14:17], v31 offset:6912
	s_waitcnt lgkmcnt(0)
	v_mfma_f32_16x16x32_bf16 v[14:17], v[14:17], v[6:9], 0
	v_mfma_f32_16x16x32_bf16 v[50:53], v[18:21], v[10:13], v[14:17]
	ds_read_b128 v[18:21], v31 offset:9280
	s_nop 5
	ds_read_b128 v[14:17], v31 offset:9216
	s_waitcnt lgkmcnt(0)
	v_mfma_f32_16x16x32_bf16 v[14:17], v[14:17], v[6:9], 0
	v_mfma_f32_16x16x32_bf16 v[56:59], v[18:21], v[10:13], v[14:17]
	ds_read_b128 v[18:21], v31 offset:11584
	s_nop 5
	ds_read_b128 v[14:17], v31 offset:11520
	s_waitcnt lgkmcnt(0)
	v_mfma_f32_16x16x32_bf16 v[14:17], v[14:17], v[6:9], 0
	v_mfma_f32_16x16x32_bf16 v[66:69], v[18:21], v[10:13], v[14:17]
	ds_read_b128 v[18:21], v31 offset:13888
	s_nop 5
	ds_read_b128 v[14:17], v31 offset:13824
	s_waitcnt lgkmcnt(0)
	v_mfma_f32_16x16x32_bf16 v[14:17], v[14:17], v[6:9], 0
	v_mfma_f32_16x16x32_bf16 v[74:77], v[18:21], v[10:13], v[14:17]
	ds_read_b128 v[18:21], v31 offset:16192
	s_nop 5
	ds_read_b128 v[14:17], v31 offset:16128
	s_waitcnt lgkmcnt(0)
	v_mfma_f32_16x16x32_bf16 v[14:17], v[14:17], v[6:9], 0
	v_mfma_f32_16x16x32_bf16 v[80:83], v[18:21], v[10:13], v[14:17]
	ds_read_b128 v[18:21], v31 offset:18496
	s_nop 5
	ds_read_b128 v[14:17], v31 offset:18432
	s_waitcnt lgkmcnt(0)
	v_mfma_f32_16x16x32_bf16 v[14:17], v[14:17], v[6:9], 0
	v_mfma_f32_16x16x32_bf16 v[84:87], v[18:21], v[10:13], v[14:17]
	ds_read_b128 v[18:21], v31 offset:20800
	s_nop 5
	ds_read_b128 v[14:17], v31 offset:20736
	s_waitcnt lgkmcnt(0)
	v_mfma_f32_16x16x32_bf16 v[14:17], v[14:17], v[6:9], 0
	v_mfma_f32_16x16x32_bf16 v[88:91], v[18:21], v[10:13], v[14:17]
	ds_read_b128 v[18:21], v31 offset:23104
	s_nop 5
	ds_read_b128 v[14:17], v31 offset:23040
	s_waitcnt lgkmcnt(0)
	v_mfma_f32_16x16x32_bf16 v[14:17], v[14:17], v[6:9], 0
	v_mfma_f32_16x16x32_bf16 v[92:95], v[18:21], v[10:13], v[14:17]
	ds_read_b128 v[18:21], v31 offset:25408
	s_nop 5
	ds_read_b128 v[14:17], v31 offset:25344
	s_waitcnt lgkmcnt(0)
	v_mfma_f32_16x16x32_bf16 v[14:17], v[14:17], v[6:9], 0
	v_mfma_f32_16x16x32_bf16 v[96:99], v[18:21], v[10:13], v[14:17]
	ds_read_b128 v[18:21], v31 offset:27712
	s_nop 5
	ds_read_b128 v[14:17], v31 offset:27648
	s_waitcnt lgkmcnt(0)
	v_mfma_f32_16x16x32_bf16 v[14:17], v[14:17], v[6:9], 0
	v_mfma_f32_16x16x32_bf16 v[22:25], v[18:21], v[10:13], v[14:17]
	ds_read_b128 v[18:21], v31 offset:30016
	s_nop 5
	ds_read_b128 v[14:17], v31 offset:29952
	s_waitcnt lgkmcnt(0)
	v_mfma_f32_16x16x32_bf16 v[14:17], v[14:17], v[6:9], 0
	ds_read_b128 v[46:49], v31 offset:32320
	v_mfma_f32_16x16x32_bf16 v[18:21], v[18:21], v[10:13], v[14:17]
	s_nop 5
	ds_read_b128 v[14:17], v31 offset:32256
	s_waitcnt lgkmcnt(0)
	v_mfma_f32_16x16x32_bf16 v[14:17], v[14:17], v[6:9], 0
	v_mfma_f32_16x16x32_bf16 v[14:17], v[46:49], v[10:13], v[14:17]
	ds_read_b128 v[46:49], v31 offset:34560
	s_waitcnt lgkmcnt(0)
	v_mfma_f32_16x16x32_bf16 v[6:9], v[46:49], v[6:9], 0
	ds_read_b128 v[46:49], v31 offset:34624
	s_waitcnt lgkmcnt(0)
	v_mfma_f32_16x16x32_bf16 v[6:9], v[46:49], v[10:13], v[6:9]
	v_max3_f32 v10, v34, s89, v35
	v_max3_f32 v10, v10, v36, v37
	v_max3_f32 v10, v10, v38, v39
	v_max3_f32 v10, v10, v40, v41
	v_max3_f32 v10, v10, v42, v43
	v_max3_f32 v10, v10, v44, v45
	v_max3_f32 v10, v10, v50, v51
	v_max3_f32 v10, v10, v52, v53
	v_max3_f32 v10, v10, v56, v57
	v_max3_f32 v10, v10, v58, v59
	v_max3_f32 v10, v10, v66, v67
	v_max3_f32 v10, v10, v68, v69
	v_max3_f32 v10, v10, v74, v75
	v_max3_f32 v10, v10, v76, v77
	v_max3_f32 v10, v10, v80, v81
	v_max3_f32 v10, v10, v82, v83
	v_max3_f32 v10, v10, v84, v85
	v_max3_f32 v10, v10, v86, v87
	v_max3_f32 v10, v10, v88, v89
	v_max3_f32 v10, v10, v90, v91
	v_max3_f32 v10, v10, v92, v93
	v_max3_f32 v10, v10, v94, v95
	v_max3_f32 v10, v10, v96, v97
	v_max3_f32 v10, v10, v98, v99
	v_max3_f32 v10, v10, v22, v23
	v_max3_f32 v10, v10, v24, v25
	v_max3_f32 v10, v10, v18, v19
	v_max3_f32 v10, v10, v20, v21
	v_max3_f32 v10, v10, v14, v15
	v_max3_f32 v10, v10, v16, v17
	v_max3_f32 v10, v10, v6, v7
	v_max3_f32 v10, v10, v8, v9
	ds_bpermute_b32 v11, v109, v10
	s_waitcnt lgkmcnt(0)
	v_max_f32_e32 v11, v11, v11
	v_max_f32_e32 v10, v10, v11
	ds_bpermute_b32 v11, v110, v10
	s_waitcnt lgkmcnt(0)
	v_max_f32_e32 v11, v11, v11
	v_max_f32_e32 v73, v10, v11
	v_sub_f32_e32 v11, v35, v73
	v_mul_f32_e32 v11, 0x3fb8aa3b, v11
	v_exp_f32_e32 v100, v11
	v_sub_f32_e32 v11, v36, v73
	v_mul_f32_e32 v11, 0x3fb8aa3b, v11
	v_exp_f32_e32 v101, v11
	v_sub_f32_e32 v11, v37, v73
	v_mul_f32_e32 v11, 0x3fb8aa3b, v11
	v_exp_f32_e32 v102, v11
	v_sub_f32_e32 v11, v38, v73
	v_mul_f32_e32 v11, 0x3fb8aa3b, v11
	v_exp_f32_e32 v103, v11
	v_sub_f32_e32 v11, v39, v73
	v_mul_f32_e32 v11, 0x3fb8aa3b, v11
	v_exp_f32_e32 v104, v11
	v_sub_f32_e32 v11, v40, v73
	v_mul_f32_e32 v11, 0x3fb8aa3b, v11
	v_exp_f32_e32 v105, v11
	v_sub_f32_e32 v11, v41, v73
	v_mul_f32_e32 v11, 0x3fb8aa3b, v11
	v_exp_f32_e32 v111, v11
	v_sub_f32_e32 v11, v42, v73
	v_mul_f32_e32 v11, 0x3fb8aa3b, v11
	v_sub_f32_e32 v10, v34, v73
	v_exp_f32_e32 v34, v11
	v_sub_f32_e32 v11, v43, v73
	v_mul_f32_e32 v11, 0x3fb8aa3b, v11
	v_exp_f32_e32 v46, v11
	v_sub_f32_e32 v11, v44, v73
	v_mul_f32_e32 v11, 0x3fb8aa3b, v11
	v_exp_f32_e32 v39, v11
	v_sub_f32_e32 v11, v45, v73
	v_mul_f32_e32 v11, 0x3fb8aa3b, v11
	v_exp_f32_e32 v55, v11
	v_sub_f32_e32 v11, v50, v73
	v_mul_f32_e32 v11, 0x3fb8aa3b, v11
	v_exp_f32_e32 v50, v11
	v_sub_f32_e32 v11, v51, v73
	v_mul_f32_e32 v11, 0x3fb8aa3b, v11
	v_exp_f32_e32 v65, v11
	v_sub_f32_e32 v11, v52, v73
	v_mul_f32_e32 v11, 0x3fb8aa3b, v11
	v_exp_f32_e32 v62, v11
	v_sub_f32_e32 v11, v53, v73
	v_mul_f32_e32 v11, 0x3fb8aa3b, v11
	v_exp_f32_e32 v72, v11
	v_sub_f32_e32 v11, v56, v73
	v_mul_f32_e32 v11, 0x3fb8aa3b, v11
	v_exp_f32_e32 v33, v11
	v_sub_f32_e32 v11, v57, v73
	v_mul_f32_e32 v11, 0x3fb8aa3b, v11
	v_exp_f32_e32 v44, v11
	v_sub_f32_e32 v11, v58, v73
	v_mul_f32_e32 v11, 0x3fb8aa3b, v11
	v_exp_f32_e32 v38, v11
	v_sub_f32_e32 v11, v59, v73
	v_mul_f32_e32 v11, 0x3fb8aa3b, v11
	v_exp_f32_e32 v54, v11
	v_sub_f32_e32 v11, v66, v73
	v_mul_f32_e32 v11, 0x3fb8aa3b, v11
	v_exp_f32_e32 v49, v11
	v_sub_f32_e32 v11, v67, v73
	v_mul_f32_e32 v11, 0x3fb8aa3b, v11
	v_exp_f32_e32 v64, v11
	v_sub_f32_e32 v11, v68, v73
	v_mul_f32_e32 v11, 0x3fb8aa3b, v11
	v_exp_f32_e32 v60, v11
	v_sub_f32_e32 v11, v69, v73
	v_mul_f32_e32 v11, 0x3fb8aa3b, v11
	v_exp_f32_e32 v71, v11
	v_sub_f32_e32 v11, v74, v73
	v_mul_f32_e32 v11, 0x3fb8aa3b, v11
	v_mul_f32_e32 v10, 0x3fb8aa3b, v10
	v_exp_f32_e32 v27, v11
	v_sub_f32_e32 v11, v75, v73
	v_exp_f32_e32 v79, v10
	v_mul_f32_e32 v11, 0x3fb8aa3b, v11
	v_exp_f32_e32 v43, v11
	v_sub_f32_e32 v11, v76, v73
	v_mul_f32_e32 v11, 0x3fb8aa3b, v11
	v_exp_f32_e32 v37, v11
	v_sub_f32_e32 v11, v77, v73
	v_add_f32_e32 v10, 0, v79
	v_mul_f32_e32 v11, 0x3fb8aa3b, v11
	v_add_f32_e32 v10, v100, v10
	v_exp_f32_e32 v53, v11
	v_sub_f32_e32 v11, v80, v73
	v_add_f32_e32 v10, v101, v10
	v_mul_f32_e32 v11, 0x3fb8aa3b, v11
	v_add_f32_e32 v10, v102, v10
	v_exp_f32_e32 v48, v11
	v_sub_f32_e32 v11, v81, v73
	v_add_f32_e32 v10, v103, v10
	v_mul_f32_e32 v11, 0x3fb8aa3b, v11
	v_add_f32_e32 v10, v104, v10
	v_exp_f32_e32 v63, v11
	v_sub_f32_e32 v11, v82, v73
	v_add_f32_e32 v10, v105, v10
	v_mul_f32_e32 v11, 0x3fb8aa3b, v11
	v_add_f32_e32 v10, v111, v10
	v_exp_f32_e32 v58, v11
	v_sub_f32_e32 v11, v83, v73
	v_add_f32_e32 v10, v34, v10
	v_mul_f32_e32 v11, 0x3fb8aa3b, v11
	v_add_f32_e32 v10, v46, v10
	v_exp_f32_e32 v70, v11
	v_sub_f32_e32 v11, v84, v73
	v_add_f32_e32 v10, v39, v10
	v_mul_f32_e32 v11, 0x3fb8aa3b, v11
	v_add_f32_e32 v10, v55, v10
	v_exp_f32_e32 v13, v11
	v_sub_f32_e32 v11, v85, v73
	v_add_f32_e32 v10, v50, v10
	v_mul_f32_e32 v11, 0x3fb8aa3b, v11
	v_add_f32_e32 v10, v65, v10
	v_exp_f32_e32 v42, v11
	v_sub_f32_e32 v11, v86, v73
	v_add_f32_e32 v10, v62, v10
	v_mul_f32_e32 v11, 0x3fb8aa3b, v11
	v_add_f32_e32 v10, v72, v10
	v_exp_f32_e32 v36, v11
	v_sub_f32_e32 v11, v87, v73
	v_add_f32_e32 v10, v33, v10
	v_mul_f32_e32 v11, 0x3fb8aa3b, v11
	v_add_f32_e32 v10, v44, v10
	v_exp_f32_e32 v52, v11
	v_sub_f32_e32 v11, v88, v73
	v_add_f32_e32 v10, v38, v10
	v_mul_f32_e32 v11, 0x3fb8aa3b, v11
	v_add_f32_e32 v10, v54, v10
	v_exp_f32_e32 v47, v11
	v_sub_f32_e32 v11, v89, v73
	v_add_f32_e32 v10, v49, v10
	v_mul_f32_e32 v11, 0x3fb8aa3b, v11
	v_add_f32_e32 v10, v64, v10
	v_exp_f32_e32 v61, v11
	v_sub_f32_e32 v11, v90, v73
	v_add_f32_e32 v10, v60, v10
	v_mul_f32_e32 v11, 0x3fb8aa3b, v11
	v_add_f32_e32 v10, v71, v10
	v_exp_f32_e32 v57, v11
	v_sub_f32_e32 v11, v91, v73
	v_add_f32_e32 v10, v27, v10
	v_mul_f32_e32 v11, 0x3fb8aa3b, v11
	v_add_f32_e32 v10, v43, v10
	v_exp_f32_e32 v69, v11
	v_sub_f32_e32 v11, v92, v73
	v_add_f32_e32 v10, v37, v10
	v_mul_f32_e32 v11, 0x3fb8aa3b, v11
	v_add_f32_e32 v10, v53, v10
	v_exp_f32_e32 v12, v11
	v_sub_f32_e32 v11, v93, v73
	v_add_f32_e32 v10, v48, v10
	v_mul_f32_e32 v11, 0x3fb8aa3b, v11
	v_add_f32_e32 v10, v63, v10
	v_exp_f32_e32 v41, v11
	v_sub_f32_e32 v11, v94, v73
	v_add_f32_e32 v10, v58, v10
	v_mul_f32_e32 v11, 0x3fb8aa3b, v11
	v_add_f32_e32 v10, v70, v10
	v_exp_f32_e32 v35, v11
	v_sub_f32_e32 v11, v95, v73
	v_add_f32_e32 v10, v13, v10
	v_mul_f32_e32 v11, 0x3fb8aa3b, v11
	v_add_f32_e32 v10, v42, v10
	v_exp_f32_e32 v51, v11
	v_sub_f32_e32 v11, v96, v73
	v_add_f32_e32 v10, v36, v10
	v_mul_f32_e32 v11, 0x3fb8aa3b, v11
	v_add_f32_e32 v10, v52, v10
	v_exp_f32_e32 v45, v11
	v_sub_f32_e32 v11, v97, v73
	v_add_f32_e32 v10, v47, v10
	v_mul_f32_e32 v11, 0x3fb8aa3b, v11
	v_add_f32_e32 v10, v61, v10
	v_exp_f32_e32 v59, v11
	v_sub_f32_e32 v11, v98, v73
	v_add_f32_e32 v10, v57, v10
	v_mul_f32_e32 v11, 0x3fb8aa3b, v11
	v_add_f32_e32 v10, v69, v10
	v_exp_f32_e32 v56, v11
	v_sub_f32_e32 v11, v99, v73
	v_add_f32_e32 v10, v12, v10
	v_mul_f32_e32 v11, 0x3fb8aa3b, v11
	v_add_f32_e32 v10, v41, v10
	v_exp_f32_e32 v68, v11
	v_sub_f32_e32 v11, v22, v73
	v_sub_f32_e32 v22, v23, v73
	v_add_f32_e32 v10, v35, v10
	v_mul_f32_e32 v22, 0x3fb8aa3b, v22
	v_add_f32_e32 v10, v51, v10
	v_mul_f32_e32 v11, 0x3fb8aa3b, v11
	v_exp_f32_e32 v40, v22
	v_sub_f32_e32 v22, v24, v73
	v_add_f32_e32 v10, v45, v10
	v_exp_f32_e32 v11, v11
	v_mul_f32_e32 v22, 0x3fb8aa3b, v22
	v_add_f32_e32 v10, v59, v10
	v_exp_f32_e32 v23, v22
	v_sub_f32_e32 v22, v25, v73
	v_sub_f32_e32 v19, v19, v73
	v_add_f32_e32 v10, v56, v10
	v_mul_f32_e32 v22, 0x3fb8aa3b, v22
	v_sub_f32_e32 v18, v18, v73
	v_mul_f32_e32 v19, 0x3fb8aa3b, v19
	v_add_f32_e32 v10, v68, v10
	v_exp_f32_e32 v24, v22
	v_mul_f32_e32 v18, 0x3fb8aa3b, v18
	v_exp_f32_e32 v25, v19
	v_sub_f32_e32 v19, v20, v73
	v_add_f32_e32 v10, v11, v10
	v_exp_f32_e32 v18, v18
	v_mul_f32_e32 v19, 0x3fb8aa3b, v19
	v_add_f32_e32 v10, v40, v10
	v_exp_f32_e32 v20, v19
	v_sub_f32_e32 v19, v21, v73
	v_add_f32_e32 v10, v23, v10
	v_mul_f32_e32 v19, 0x3fb8aa3b, v19
	v_add_f32_e32 v10, v24, v10
	v_exp_f32_e32 v67, v19
	v_add_f32_e32 v10, v18, v10
	v_add_f32_e32 v10, v25, v10
	v_add_f32_e32 v10, v20, v10
	v_add_f32_e32 v19, v67, v10
	v_sub_f32_e32 v10, v14, v73
	v_mul_f32_e32 v10, 0x3fb8aa3b, v10
	v_sub_f32_e32 v15, v15, v73
	v_exp_f32_e32 v10, v10
	v_mul_f32_e32 v15, 0x3fb8aa3b, v15
	v_exp_f32_e32 v15, v15
	v_sub_f32_e32 v17, v17, v73
	v_add_f32_e32 v14, v10, v19
	v_mul_f32_e32 v17, 0x3fb8aa3b, v17
	v_add_f32_e32 v19, v15, v14
	v_sub_f32_e32 v14, v16, v73
	v_mul_f32_e32 v14, 0x3fb8aa3b, v14
	v_exp_f32_e32 v14, v14
	v_exp_f32_e32 v17, v17
	v_sub_f32_e32 v6, v6, v73
	v_mul_f32_e32 v6, 0x3fb8aa3b, v6
	v_add_f32_e32 v16, v14, v19
	v_add_f32_e32 v19, v17, v16
	v_exp_f32_e32 v16, v6
	v_sub_f32_e32 v7, v7, v73
	v_mul_f32_e32 v7, 0x3fb8aa3b, v7
	v_exp_f32_e32 v21, v7
	v_sub_f32_e32 v7, v8, v73
	v_mul_f32_e32 v7, 0x3fb8aa3b, v7
	v_add_f32_e32 v6, v16, v19
	v_exp_f32_e32 v19, v7
	v_sub_f32_e32 v7, v9, v73
	v_mul_f32_e32 v7, 0x3fb8aa3b, v7
	v_exp_f32_e32 v66, v7
	v_add_f32_e32 v6, v21, v6
	v_add_f32_e32 v6, v19, v6
	v_bfe_u32 v8, v102, 16, 1
	v_add_f32_e32 v6, v66, v6
	ds_bpermute_b32 v7, v109, v6
	v_bfe_u32 v9, v100, 16, 1
	v_add3_u32 v73, v100, v9, s91
	v_add3_u32 v74, v102, v8, s91
	v_bfe_u32 v8, v79, 16, 1
	s_waitcnt lgkmcnt(0)
	v_add_f32_e32 v6, v6, v7
	ds_bpermute_b32 v7, v110, v6
	v_bfe_u32 v9, v101, 16, 1
	v_bfe_u32 v75, v103, 16, 1
	v_bfe_u32 v76, v105, 16, 1
	v_add3_u32 v75, v103, v75, s91
	s_waitcnt lgkmcnt(0)
	v_add_f32_e32 v22, v6, v7
	v_bfe_u32 v7, v104, 16, 1
	v_add3_u32 v9, v101, v9, s91
	v_add3_u32 v8, v79, v8, s91
	v_bfe_u32 v6, v111, 16, 1
	v_add3_u32 v7, v104, v7, s91
	v_add3_u32 v76, v105, v76, s91
	v_lshrrev_b32_e32 v77, 16, v8
	v_lshrrev_b32_e32 v79, 16, v9
	v_lshrrev_b32_e32 v8, 16, v75
	v_add3_u32 v6, v111, v6, s91
	v_lshrrev_b32_e32 v9, 16, v76
	v_and_or_b32 v8, v7, s33, v8
	v_and_or_b32 v7, v74, s33, v79
	v_add_u32_e32 v79, 0x9000, v32
	v_add_u32_e32 v96, 0xb000, v32
	v_add_u32_e32 v97, 0xd000, v32
	v_add_u32_e32 v98, 0xf000, v32
	v_and_or_b32 v9, v6, s33, v9
	v_and_or_b32 v6, v73, s33, v77
	ds_read2_b64 v[74:77], v79 offset1:4
	ds_read2_b64 v[80:83], v96 offset0:32 offset1:36
	ds_read2_b64 v[84:87], v97 offset0:64 offset1:68
	ds_read2_b64 v[88:91], v98 offset0:96 offset1:100
	ds_read2_b64 v[92:95], v79 offset0:8 offset1:12
	s_waitcnt lgkmcnt(4)
	v_mfma_f32_16x16x32_bf16 v[74:77], v[74:77], v[6:9], 0
	v_bfe_u32 v73, v72, 16, 1
	v_add3_u32 v72, v72, v73, s91
	v_bfe_u32 v73, v34, 16, 1
	s_waitcnt lgkmcnt(3)
	v_mfma_f32_16x16x32_bf16 v[80:83], v[80:83], v[6:9], 0
	v_add3_u32 v34, v34, v73, s91
	v_lshrrev_b32_e32 v34, 16, v34
	s_waitcnt lgkmcnt(2)
	v_mfma_f32_16x16x32_bf16 v[84:87], v[84:87], v[6:9], 0
	s_waitcnt lgkmcnt(1)
	v_mfma_f32_16x16x32_bf16 v[6:9], v[88:91], v[6:9], 0
	v_bfe_u32 v88, v65, 16, 1
	v_bfe_u32 v89, v55, 16, 1
	v_bfe_u32 v90, v46, 16, 1
	v_add3_u32 v46, v46, v90, s91
	v_add3_u32 v55, v55, v89, s91
	v_add3_u32 v65, v65, v88, s91
	v_bfe_u32 v88, v39, 16, 1
	v_bfe_u32 v89, v50, 16, 1
	v_bfe_u32 v90, v62, 16, 1
	v_add3_u32 v62, v62, v90, s91
	v_add3_u32 v50, v50, v89, s91
	v_add3_u32 v39, v39, v88, s91
	v_lshrrev_b32_e32 v39, 16, v39
	v_lshrrev_b32_e32 v50, 16, v50
	v_lshrrev_b32_e32 v62, 16, v62
	v_and_or_b32 v91, v72, s33, v62
	v_and_or_b32 v90, v65, s33, v50
	v_and_or_b32 v89, v55, s33, v39
	v_and_or_b32 v88, v46, s33, v34
	v_bfe_u32 v46, v54, 16, 1
	v_bfe_u32 v50, v44, 16, 1
	s_waitcnt lgkmcnt(0)
	v_mfma_f32_16x16x32_bf16 v[72:75], v[92:95], v[88:91], v[74:77]
	ds_read2_b64 v[92:95], v96 offset0:40 offset1:44
	v_add3_u32 v44, v44, v50, s91
	v_add3_u32 v46, v54, v46, s91
	s_waitcnt lgkmcnt(0)
	v_mfma_f32_16x16x32_bf16 v[80:83], v[92:95], v[88:91], v[80:83]
	ds_read2_b64 v[92:95], v97 offset0:72 offset1:76
	v_bfe_u32 v50, v33, 16, 1
	v_bfe_u32 v54, v38, 16, 1
	s_waitcnt lgkmcnt(0)
	v_mfma_f32_16x16x32_bf16 v[84:87], v[92:95], v[88:91], v[84:87]
	ds_read2_b64 v[92:95], v98 offset0:104 offset1:108
	v_bfe_u32 v55, v49, 16, 1
	s_waitcnt lgkmcnt(0)
	v_mfma_f32_16x16x32_bf16 v[6:9], v[92:95], v[88:91], v[6:9]
	ds_read2_b64 v[92:95], v79 offset0:16 offset1:20
	v_bfe_u32 v62, v60, 16, 1
	v_bfe_u32 v34, v71, 16, 1
	v_bfe_u32 v39, v64, 16, 1
	v_add3_u32 v60, v60, v62, s91
	v_add3_u32 v49, v49, v55, s91
	v_add3_u32 v38, v38, v54, s91
	v_add3_u32 v33, v33, v50, s91
	v_add3_u32 v39, v64, v39, s91
	v_add3_u32 v34, v71, v34, s91
	v_lshrrev_b32_e32 v33, 16, v33
	v_lshrrev_b32_e32 v38, 16, v38
	v_lshrrev_b32_e32 v49, 16, v49
	v_lshrrev_b32_e32 v50, 16, v60
	v_and_or_b32 v91, v34, s33, v50
	v_and_or_b32 v90, v39, s33, v49
	v_and_or_b32 v89, v46, s33, v38
	v_and_or_b32 v88, v44, s33, v33
	v_bfe_u32 v39, v43, 16, 1
	v_add3_u32 v39, v43, v39, s91
	s_waitcnt lgkmcnt(0)
	v_mfma_f32_16x16x32_bf16 v[72:75], v[92:95], v[88:91], v[72:75]
	ds_read2_b64 v[92:95], v96 offset0:48 offset1:52
	v_bfe_u32 v43, v27, 16, 1
	v_bfe_u32 v44, v37, 16, 1
	s_waitcnt lgkmcnt(0)
	v_mfma_f32_16x16x32_bf16 v[80:83], v[92:95], v[88:91], v[80:83]
	ds_read2_b64 v[92:95], v97 offset0:80 offset1:84
	v_bfe_u32 v46, v48, 16, 1
	v_bfe_u32 v49, v58, 16, 1
	s_waitcnt lgkmcnt(0)
	v_mfma_f32_16x16x32_bf16 v[84:87], v[92:95], v[88:91], v[84:87]
	ds_read2_b64 v[92:95], v98 offset0:112 offset1:116
	v_bfe_u32 v33, v70, 16, 1
	s_waitcnt lgkmcnt(0)
	v_mfma_f32_16x16x32_bf16 v[6:9], v[92:95], v[88:91], v[6:9]
	ds_read2_b64 v[88:91], v79 offset0:24 offset1:28
	v_bfe_u32 v34, v63, 16, 1
	v_bfe_u32 v38, v53, 16, 1
	v_add3_u32 v49, v58, v49, s91
	v_add3_u32 v46, v48, v46, s91
	v_add3_u32 v37, v37, v44, s91
	v_add3_u32 v27, v27, v43, s91
	v_add3_u32 v38, v53, v38, s91
	v_add3_u32 v34, v63, v34, s91
	v_add3_u32 v33, v70, v33, s91
	v_lshrrev_b32_e32 v27, 16, v27
	v_lshrrev_b32_e32 v37, 16, v37
	v_lshrrev_b32_e32 v43, 16, v46
	v_lshrrev_b32_e32 v44, 16, v49
	v_and_or_b32 v65, v33, s33, v44
	v_and_or_b32 v64, v34, s33, v43
	v_and_or_b32 v63, v38, s33, v37
	v_and_or_b32 v62, v39, s33, v27
	v_bfe_u32 v39, v47, 16, 1
	v_add3_u32 v39, v47, v39, s91
	s_waitcnt lgkmcnt(0)
	v_mfma_f32_16x16x32_bf16 v[70:73], v[88:91], v[62:65], v[72:75]
	v_bfe_u32 v37, v42, 16, 1
	v_add3_u32 v42, v42, v37, s91
	v_bfe_u32 v37, v13, 16, 1
	ds_read2_b64 v[74:77], v96 offset0:56 offset1:60
	s_waitcnt lgkmcnt(0)
	v_mfma_f32_16x16x32_bf16 v[74:77], v[74:77], v[62:65], v[80:83]
	s_nop 2
	ds_read2_b64 v[80:83], v97 offset0:88 offset1:92
	v_bfe_u32 v38, v36, 16, 1
	v_bfe_u32 v43, v57, 16, 1
	s_waitcnt lgkmcnt(0)
	v_mfma_f32_16x16x32_bf16 v[80:83], v[80:83], v[62:65], v[84:87]
	s_nop 2
	ds_read2_b64 v[84:87], v98 offset0:120 offset1:124
	ds_read2_b64 v[46:49], v79 offset0:32 offset1:36
	v_bfe_u32 v27, v69, 16, 1
	v_bfe_u32 v33, v61, 16, 1
	v_bfe_u32 v34, v52, 16, 1
	v_add3_u32 v43, v57, v43, s91
	v_add3_u32 v36, v36, v38, s91
	v_add3_u32 v13, v13, v37, s91
	v_add3_u32 v34, v52, v34, s91
	v_add3_u32 v33, v61, v33, s91
	v_add3_u32 v27, v69, v27, s91
	v_lshrrev_b32_e32 v13, 16, v13
	v_lshrrev_b32_e32 v36, 16, v36
	v_lshrrev_b32_e32 v37, 16, v39
	v_lshrrev_b32_e32 v38, 16, v43
	v_and_or_b32 v39, v27, s33, v38
	v_and_or_b32 v38, v33, s33, v37
	v_and_or_b32 v37, v34, s33, v36
	v_and_or_b32 v36, v42, s33, v13
	s_waitcnt lgkmcnt(1)
	v_mfma_f32_16x16x32_bf16 v[6:9], v[84:87], v[62:65], v[6:9]
	ds_read2_b64 v[52:55], v96 offset0:64 offset1:68
	ds_read2_b64 v[60:63], v97 offset0:96 offset1:100
	v_bfe_u32 v13, v68, 16, 1
	s_waitcnt lgkmcnt(2)
	v_mfma_f32_16x16x32_bf16 v[46:49], v[46:49], v[36:39], v[70:73]
	v_bfe_u32 v27, v59, 16, 1
	v_bfe_u32 v33, v51, 16, 1
	v_bfe_u32 v34, v41, 16, 1
	ds_read2_b64 v[70:73], v98 offset0:128 offset1:132
	s_waitcnt lgkmcnt(2)
	v_mfma_f32_16x16x32_bf16 v[52:55], v[52:55], v[36:39], v[74:77]
	v_add3_u32 v34, v41, v34, s91
	v_add3_u32 v33, v51, v33, s91
	s_waitcnt lgkmcnt(1)
	v_mfma_f32_16x16x32_bf16 v[60:63], v[60:63], v[36:39], v[80:83]
	v_add3_u32 v27, v59, v27, s91
	v_add3_u32 v13, v68, v13, s91
	s_waitcnt lgkmcnt(0)
	v_mfma_f32_16x16x32_bf16 v[6:9], v[70:73], v[36:39], v[6:9]
	v_bfe_u32 v38, v45, 16, 1
	v_add3_u32 v38, v45, v38, s91
	ds_read2_b64 v[42:45], v79 offset0:40 offset1:44
	v_bfe_u32 v36, v12, 16, 1
	v_bfe_u32 v37, v35, 16, 1
	v_bfe_u32 v39, v56, 16, 1
	v_add3_u32 v39, v56, v39, s91
	v_add3_u32 v35, v35, v37, s91
	v_add3_u32 v12, v12, v36, s91
	v_lshrrev_b32_e32 v12, 16, v12
	v_lshrrev_b32_e32 v35, 16, v35
	v_lshrrev_b32_e32 v36, 16, v38
	v_lshrrev_b32_e32 v37, 16, v39
	v_and_or_b32 v37, v13, s33, v37
	v_and_or_b32 v36, v27, s33, v36
	v_and_or_b32 v35, v33, s33, v35
	v_and_or_b32 v34, v34, s33, v12
	v_bfe_u32 v33, v40, 16, 1
	v_add3_u32 v33, v40, v33, s91
	s_waitcnt lgkmcnt(0)
	v_mfma_f32_16x16x32_bf16 v[42:45], v[42:45], v[34:37], v[46:49]
	v_bfe_u32 v13, v25, 16, 1
	v_bfe_u32 v27, v24, 16, 1
	v_add3_u32 v24, v24, v27, s91
	ds_read2_b64 v[46:49], v96 offset0:72 offset1:76
	s_waitcnt lgkmcnt(0)
	v_mfma_f32_16x16x32_bf16 v[46:49], v[46:49], v[34:37], v[52:55]
	s_nop 2
	ds_read2_b64 v[50:53], v97 offset0:104 offset1:108
	ds_read2_b64 v[54:57], v98 offset0:136 offset1:140
	ds_read2_b64 v[38:41], v79 offset0:48 offset1:52
	s_waitcnt lgkmcnt(2)
	v_mfma_f32_16x16x32_bf16 v[50:53], v[50:53], v[34:37], v[60:63]
	v_add3_u32 v13, v25, v13, s91
	v_bfe_u32 v25, v11, 16, 1
	v_bfe_u32 v27, v23, 16, 1
	s_waitcnt lgkmcnt(1)
	v_mfma_f32_16x16x32_bf16 v[6:9], v[54:57], v[34:37], v[6:9]
	v_bfe_u32 v34, v18, 16, 1
	v_bfe_u32 v35, v20, 16, 1
	v_bfe_u32 v12, v67, 16, 1
	v_add3_u32 v20, v20, v35, s91
	v_add3_u32 v18, v18, v34, s91
	v_add3_u32 v23, v23, v27, s91
	v_add3_u32 v11, v11, v25, s91
	v_add3_u32 v12, v67, v12, s91
	v_lshrrev_b32_e32 v11, 16, v11
	v_lshrrev_b32_e32 v23, 16, v23
	v_lshrrev_b32_e32 v18, 16, v18
	v_lshrrev_b32_e32 v20, 16, v20
	v_and_or_b32 v37, v12, s33, v20
	v_and_or_b32 v36, v13, s33, v18
	v_and_or_b32 v35, v24, s33, v23
	v_and_or_b32 v34, v33, s33, v11
	v_bfe_u32 v12, v21, 16, 1
	v_bfe_u32 v13, v17, 16, 1
	s_waitcnt lgkmcnt(0)
	v_mfma_f32_16x16x32_bf16 v[38:41], v[38:41], v[34:37], v[42:45]
	v_bfe_u32 v18, v15, 16, 1
	v_add3_u32 v15, v15, v18, s91
	v_add3_u32 v13, v17, v13, s91
	ds_read2_b64 v[42:45], v96 offset0:80 offset1:84
	s_waitcnt lgkmcnt(0)
	v_mfma_f32_16x16x32_bf16 v[42:45], v[42:45], v[34:37], v[46:49]
	s_nop 2
	ds_read2_b64 v[46:49], v97 offset0:112 offset1:116
	v_add3_u32 v12, v21, v12, s91
	v_bfe_u32 v17, v10, 16, 1
	s_waitcnt lgkmcnt(0)
	v_mfma_f32_16x16x32_bf16 v[46:49], v[46:49], v[34:37], v[50:53]
	s_nop 2
	ds_read2_b64 v[50:53], v98 offset0:144 offset1:148
	v_bfe_u32 v18, v14, 16, 1
	v_bfe_u32 v20, v16, 16, 1
	v_bfe_u32 v21, v19, 16, 1
	v_bfe_u32 v11, v66, 16, 1
	v_add3_u32 v19, v19, v21, s91
	v_add3_u32 v16, v16, v20, s91
	v_add3_u32 v14, v14, v18, s91
	v_add3_u32 v10, v10, v17, s91
	v_add3_u32 v11, v66, v11, s91
	v_lshrrev_b32_e32 v10, 16, v10
	v_lshrrev_b32_e32 v14, 16, v14
	v_lshrrev_b32_e32 v16, 16, v16
	v_lshrrev_b32_e32 v17, 16, v19
	s_waitcnt lgkmcnt(0)
	v_mfma_f32_16x16x32_bf16 v[6:9], v[50:53], v[34:37], v[6:9]
	v_and_or_b32 v37, v11, s33, v17
	v_and_or_b32 v36, v12, s33, v16
	v_and_or_b32 v35, v13, s33, v14
	v_and_or_b32 v34, v15, s33, v10
	ds_read2_b64 v[10:13], v79 offset0:56 offset1:60
	v_div_scale_f32 v23, s[4:5], v22, v22, 1.0
	s_waitcnt lgkmcnt(0)
	v_mfma_f32_16x16x32_bf16 v[18:21], v[10:13], v[34:37], v[38:41]
	ds_read2_b64 v[10:13], v96 offset0:88 offset1:92
	v_rcp_f32_e32 v27, v23
	s_nop 0
	ds_read2_b64 v[38:41], v98 offset0:152 offset1:156
	s_waitcnt lgkmcnt(1)
	v_mfma_f32_16x16x32_bf16 v[14:17], v[10:13], v[34:37], v[42:45]
	ds_read2_b64 v[10:13], v97 offset0:120 offset1:124
	v_lshlrev_b64 v[24:25], 11, v[28:29]
	v_fma_f32 v28, -v23, v27, 1.0
	v_fmac_f32_e32 v27, v28, v27
	v_div_scale_f32 v28, vcc, 1.0, v22, 1.0
	v_mul_f32_e32 v29, v28, v27
	v_fma_f32 v33, -v23, v29, v28
	v_fmac_f32_e32 v29, v33, v27
	v_fma_f32 v23, -v23, v29, v28
	v_div_fmas_f32 v23, v23, v27, v29
	s_waitcnt lgkmcnt(0)
	v_mfma_f32_16x16x32_bf16 v[10:13], v[10:13], v[34:37], v[46:49]
	v_div_fixup_f32 v22, v23, v22, 1.0
	v_lshl_add_u64 v[24:25], s[0:1], 0, v[24:25]
	v_lshl_add_u64 v[24:25], v[24:25], 0, s[94:95]
	v_mfma_f32_16x16x32_bf16 v[6:9], v[38:41], v[34:37], v[6:9]
	v_mov_b32_e32 v35, v20
	v_mov_b32_e32 v20, v19
	v_mov_b32_e32 v34, v18
	v_pk_mul_f32 v[18:19], v[22:23], v[20:21] op_sel_hi:[0,1]
	v_mov_b32_e32 v27, v1
	v_pk_mul_f32 v[34:35], v[22:23], v[34:35] op_sel_hi:[0,1]
	v_and_b32_sdwa v23, v19, v218 dst_sel:DWORD dst_unused:UNUSED_PAD src0_sel:WORD_1 src1_sel:DWORD
	v_lshl_add_u64 v[24:25], v[24:25], 0, v[26:27]
	v_and_b32_sdwa v20, v35, v218 dst_sel:DWORD dst_unused:UNUSED_PAD src0_sel:WORD_1 src1_sel:DWORD
	v_and_b32_sdwa v27, v18, v218 dst_sel:DWORD dst_unused:UNUSED_PAD src0_sel:WORD_1 src1_sel:DWORD
	v_add3_u32 v19, v19, v23, s91
	v_and_b32_sdwa v21, v34, v218 dst_sel:DWORD dst_unused:UNUSED_PAD src0_sel:WORD_1 src1_sel:DWORD
	v_add3_u32 v20, v35, v20, s91
	v_add3_u32 v18, v18, v27, s91
	v_and_b32_e32 v19, 0xffff0000, v19
	v_add3_u32 v21, v34, v21, s91
	v_and_b32_e32 v18, 0xffff0000, v18
	v_or_b32_sdwa v19, v19, v20 dst_sel:DWORD dst_unused:UNUSED_PAD src0_sel:DWORD src1_sel:WORD_1
	v_add_co_u32_e32 v20, vcc, s8, v24
	v_or_b32_sdwa v18, v18, v21 dst_sel:DWORD dst_unused:UNUSED_PAD src0_sel:DWORD src1_sel:WORD_1
	s_nop 0
	v_addc_co_u32_e32 v21, vcc, 0, v25, vcc
	global_store_dwordx2 v[20:21], v[18:19], off offset:1536
	v_mov_b32_e32 v18, v14
	v_mov_b32_e32 v19, v16
	v_pk_mul_f32 v[18:19], v[22:23], v[18:19] op_sel_hi:[0,1]
	v_mov_b32_e32 v16, v15
	v_pk_mul_f32 v[14:15], v[22:23], v[16:17] op_sel_hi:[0,1]
	v_and_b32_sdwa v16, v19, v218 dst_sel:DWORD dst_unused:UNUSED_PAD src0_sel:WORD_1 src1_sel:DWORD
	v_and_b32_sdwa v17, v18, v218 dst_sel:DWORD dst_unused:UNUSED_PAD src0_sel:WORD_1 src1_sel:DWORD
	v_add3_u32 v17, v18, v17, s91
	v_add3_u32 v16, v19, v16, s91
	v_and_b32_sdwa v18, v15, v218 dst_sel:DWORD dst_unused:UNUSED_PAD src0_sel:WORD_1 src1_sel:DWORD
	v_and_b32_sdwa v19, v14, v218 dst_sel:DWORD dst_unused:UNUSED_PAD src0_sel:WORD_1 src1_sel:DWORD
	v_add3_u32 v15, v15, v18, s91
	v_add3_u32 v14, v14, v19, s91
	v_and_b32_e32 v15, 0xffff0000, v15
	v_and_b32_e32 v14, 0xffff0000, v14
	v_lshl_add_u64 v[28:29], v[24:25], 0, s[10:11]
	v_or_b32_sdwa v15, v15, v16 dst_sel:DWORD dst_unused:UNUSED_PAD src0_sel:DWORD src1_sel:WORD_1
	v_or_b32_sdwa v14, v14, v17 dst_sel:DWORD dst_unused:UNUSED_PAD src0_sel:DWORD src1_sel:WORD_1
	global_store_dwordx2 v[28:29], v[14:15], off offset:32
	v_mov_b32_e32 v14, v10
	v_mov_b32_e32 v15, v12
	v_pk_mul_f32 v[14:15], v[22:23], v[14:15] op_sel_hi:[0,1]
	v_mov_b32_e32 v12, v11
	v_pk_mul_f32 v[10:11], v[22:23], v[12:13] op_sel_hi:[0,1]
	v_and_b32_sdwa v12, v15, v218 dst_sel:DWORD dst_unused:UNUSED_PAD src0_sel:WORD_1 src1_sel:DWORD
	v_and_b32_sdwa v13, v14, v218 dst_sel:DWORD dst_unused:UNUSED_PAD src0_sel:WORD_1 src1_sel:DWORD
	v_add3_u32 v13, v14, v13, s91
	v_add3_u32 v12, v15, v12, s91
	v_and_b32_sdwa v14, v11, v218 dst_sel:DWORD dst_unused:UNUSED_PAD src0_sel:WORD_1 src1_sel:DWORD
	v_and_b32_sdwa v15, v10, v218 dst_sel:DWORD dst_unused:UNUSED_PAD src0_sel:WORD_1 src1_sel:DWORD
	v_add3_u32 v11, v11, v14, s91
	v_add3_u32 v10, v10, v15, s91
	v_and_b32_e32 v11, 0xffff0000, v11
	v_and_b32_e32 v10, 0xffff0000, v10
	v_or_b32_sdwa v11, v11, v12 dst_sel:DWORD dst_unused:UNUSED_PAD src0_sel:DWORD src1_sel:WORD_1
	v_or_b32_sdwa v10, v10, v13 dst_sel:DWORD dst_unused:UNUSED_PAD src0_sel:DWORD src1_sel:WORD_1
	global_store_dwordx2 v[28:29], v[10:11], off offset:64
	v_mov_b32_e32 v10, v6
	v_mov_b32_e32 v11, v8
	v_pk_mul_f32 v[10:11], v[22:23], v[10:11] op_sel_hi:[0,1]
	v_mov_b32_e32 v8, v7
	v_pk_mul_f32 v[6:7], v[22:23], v[8:9] op_sel_hi:[0,1]
	v_and_b32_sdwa v8, v11, v218 dst_sel:DWORD dst_unused:UNUSED_PAD src0_sel:WORD_1 src1_sel:DWORD
	v_and_b32_sdwa v9, v10, v218 dst_sel:DWORD dst_unused:UNUSED_PAD src0_sel:WORD_1 src1_sel:DWORD
	v_add3_u32 v9, v10, v9, s91
	v_add3_u32 v8, v11, v8, s91
	v_and_b32_sdwa v10, v7, v218 dst_sel:DWORD dst_unused:UNUSED_PAD src0_sel:WORD_1 src1_sel:DWORD
	v_and_b32_sdwa v11, v6, v218 dst_sel:DWORD dst_unused:UNUSED_PAD src0_sel:WORD_1 src1_sel:DWORD
	v_add3_u32 v7, v7, v10, s91
	v_add3_u32 v6, v6, v11, s91
	v_and_b32_e32 v7, 0xffff0000, v7
	v_and_b32_e32 v6, 0xffff0000, v6
	v_or_b32_sdwa v7, v7, v8 dst_sel:DWORD dst_unused:UNUSED_PAD src0_sel:DWORD src1_sel:WORD_1
	v_or_b32_sdwa v6, v6, v9 dst_sel:DWORD dst_unused:UNUSED_PAD src0_sel:DWORD src1_sel:WORD_1
	s_movk_i32 s4, 0x80
	s_and_b64 vcc, exec, s[2:3]
	s_mov_b64 s[2:3], 0
	global_store_dwordx2 v[28:29], v[6:7], off offset:96
	s_cbranch_vccnz .LBB0_459
	s_waitcnt lgkmcnt(0)
	s_barrier

.LBB0_462:
	s_andn2_b64 vcc, exec, s[0:1]
	s_cbranch_vccnz .LBB0_400
	v_readlane_b32 s0, v254, 4
	v_readlane_b32 s3, v254, 61
	s_bfe_u32 s13, s3, 0x50002
	v_mov_b32_e32 v0, s0
	ds_read_b64 v[2:3], v0
	v_readfirstlane_b32 s0, v78
	s_ashr_i32 s12, s0, 6
	v_and_b32_e32 v75, 15, v78
	v_bfe_u32 v79, v78, 4, 2
	s_waitcnt lgkmcnt(0)
	v_readfirstlane_b32 s0, v2
	v_readfirstlane_b32 s1, v3
	s_add_u32 s8, s0, 0x9800000
	s_addc_u32 s9, s1, 0
	s_add_u32 s10, s0, 0x9900000
	s_addc_u32 s11, s1, 0
	s_lshl_b32 s19, s13, 7
	s_lshl_b32 s14, s12, 4
	s_add_i32 s2, s14, s19
	v_or_b32_e32 v22, s2, v75
	v_lshlrev_b32_e32 v2, 5, v22
	s_lshl_b32 s2, s20, 5
	v_ashrrev_i32_e32 v3, 31, v2
	s_and_b32 s18, s2, 0xfffff000
	v_lshlrev_b64 v[2:3], 2, v[2:3]
	s_and_b32 s6, s3, 3
	v_lshl_add_u64 v[6:7], s[8:9], 0, v[2:3]
	v_lshlrev_b32_e32 v0, 5, v79
	v_lshl_add_u64 v[2:3], s[10:11], 0, v[2:3]
	s_add_u32 s2, s0, 0xc400000
	v_lshl_add_u64 v[6:7], v[6:7], 0, v[0:1]
	v_lshl_add_u64 v[2:3], v[2:3], 0, v[0:1]
	s_addc_u32 s3, s1, 0
	global_load_dwordx4 v[10:13], v[6:7], off
	s_nop 0
	global_load_dwordx4 v[6:9], v[6:7], off offset:16
	s_nop 0
	global_load_dwordx4 v[18:21], v[2:3], off
	global_load_dwordx4 v[14:17], v[2:3], off offset:16
	v_add_u32_e32 v2, s18, v22
	v_mov_b64_e32 v[22:23], s[2:3]
	s_movk_i32 s4, 0xc00
	v_mad_i64_i32 v[22:23], s[4:5], v2, s4, v[22:23]
	s_mul_i32 s48, s6, 3
	v_lshlrev_b32_e32 v0, 4, v79
	s_mul_i32 s4, s6, 0xc0
	v_lshl_add_u64 v[22:23], v[22:23], 0, v[0:1]
	s_lshl_b32 s92, s4, 1
	s_mov_b32 s93, s95
	s_add_i32 s16, s48, 1
	v_lshl_add_u64 v[24:25], v[22:23], 0, s[92:93]
	s_lshl_b32 s94, s16, 7
	s_add_i32 s17, s48, 2
	global_load_dwordx4 v[42:45], v[24:25], off nt
	global_load_dwordx4 v[38:41], v[24:25], off offset:64 nt
	v_lshl_add_u64 v[24:25], v[22:23], 0, s[94:95]
	s_lshl_b32 s94, s17, 7
	v_lshl_add_u64 v[22:23], v[22:23], 0, s[94:95]
	global_load_dwordx4 v[34:37], v[24:25], off nt
	global_load_dwordx4 v[30:33], v[24:25], off offset:64 nt
	global_load_dwordx4 v[26:29], v[22:23], off nt
	s_nop 0
	global_load_dwordx4 v[22:25], v[22:23], off offset:64 nt
	s_addk_i32 s19, 0xff80
	v_lshlrev_b32_e32 v0, 3, v78
	v_ashrrev_i32_e32 v82, 2, v78
	v_and_b32_e32 v3, 24, v0
	v_add_u32_e32 v54, s19, v82
	v_mov_b32_e32 v64, 0
	s_lshl_b32 s15, s6, 6
	v_cmp_lt_i32_e32 vcc, -1, v54
	v_lshlrev_b32_e32 v68, 1, v3
	v_mov_b32_e32 v65, v64
	v_mov_b32_e32 v58, v64
	v_mov_b32_e32 v59, v64
	v_mov_b32_e32 v70, v64
	v_mov_b32_e32 v71, v64
	v_mov_b32_e32 v72, v64
	v_mov_b32_e32 v73, v64
	v_mov_b32_e32 v46, v64
	v_mov_b32_e32 v47, v64
	v_mov_b32_e32 v50, v64
	v_mov_b32_e32 v51, v64
	v_mov_b32_e32 v48, v64
	v_mov_b32_e32 v49, v64
	v_mov_b32_e32 v52, v64
	v_mov_b32_e32 v53, v64
	s_and_saveexec_b64 s[4:5], vcc
	s_cbranch_execz .LBB0_465
	v_add_u32_e32 v0, s18, v54
	v_mov_b64_e32 v[46:47], s[2:3]
	s_movk_i32 s6, 0xc00
	v_mad_i64_i32 v[46:47], s[6:7], v0, s6, v[46:47]
	s_lshl_b32 s94, s15, 1
	v_lshl_add_u64 v[46:47], v[46:47], 0, s[94:95]
	v_mov_b32_e32 v69, v1
	v_lshl_add_u64 v[46:47], v[46:47], 0, v[68:69]
	global_load_dwordx4 v[58:61], v[46:47], off offset:2048
	global_load_dwordx4 v[64:67], v[46:47], off offset:2112
	s_waitcnt vmcnt(0) lgkmcnt(0)
	v_lshlrev_b32_e32 v46, 16, v58
	v_and_b32_e32 v47, 0xffff0000, v58
	v_lshlrev_b32_e32 v50, 16, v64
	v_and_b32_e32 v51, 0xffff0000, v64
	v_lshlrev_b32_e32 v48, 16, v59
	v_and_b32_e32 v49, 0xffff0000, v59
	v_lshlrev_b32_e32 v52, 16, v65
	v_and_b32_e32 v53, 0xffff0000, v65
	v_lshlrev_b32_e32 v64, 16, v60
	v_and_b32_e32 v65, 0xffff0000, v60
	v_lshlrev_b32_e32 v58, 16, v66
	v_and_b32_e32 v59, 0xffff0000, v66
	v_lshlrev_b32_e32 v70, 16, v61
	v_and_b32_e32 v71, 0xffff0000, v61
	v_lshlrev_b32_e32 v72, 16, v67
	v_and_b32_e32 v73, 0xffff0000, v67
.LBB0_465:
	s_or_b64 exec, exec, s[4:5]
	v_pk_mul_f32 v[56:57], v[50:51], v[50:51]
	v_pk_mul_f32 v[60:61], v[52:53], v[52:53]
	v_pk_fma_f32 v[56:57], v[46:47], v[46:47], v[56:57]
	v_pk_fma_f32 v[60:61], v[48:49], v[48:49], v[60:61]
	v_add_f32_e32 v0, v57, v56
	v_pk_mul_f32 v[62:63], v[58:59], v[58:59]
	v_add_f32_e32 v0, v60, v0
	v_pk_fma_f32 v[62:63], v[64:65], v[64:65], v[62:63]
	v_add_f32_e32 v0, v61, v0
	v_pk_mul_f32 v[66:67], v[72:73], v[72:73]
	v_add_f32_e32 v0, v62, v0
	v_pk_fma_f32 v[66:67], v[70:71], v[70:71], v[66:67]
	v_add_f32_e32 v0, v63, v0
	v_add_f32_e32 v0, v66, v0
	v_add_f32_e32 v0, v67, v0
	ds_bpermute_b32 v55, v5, v0
	s_cmp_eq_u32 s13, 31
	v_readlane_b32 s6, v254, 49
	s_cselect_b64 s[4:5], -1, 0
	v_readlane_b32 s7, v254, 50
	s_waitcnt lgkmcnt(0)
	v_add_f32_e32 v0, v0, v55
	ds_bpermute_b32 v55, v106, v0
	s_and_b64 s[6:7], s[6:7], s[4:5]
	v_max_i32_e32 v54, 0, v54
	s_nop 1
	v_lshl_or_b32 v191, v54, 5, v3
	v_or_b32_e32 v196, 4, v191
	v_ashrrev_i32_e32 v197, 31, v196
	v_lshlrev_b64 v[196:197], 2, v[196:197]
	v_lshl_add_u64 v[200:201], s[10:11], 0, v[196:197]
	global_load_dwordx4 v[202:205], v[200:201], off
	s_nop 1
	v_lshl_or_b32 v190, v54, 5, v3
	v_or_b32_e32 v186, 4, v190
	v_ashrrev_i32_e32 v187, 31, v186
	v_lshlrev_b64 v[186:187], 2, v[186:187]
	v_lshl_add_u64 v[188:189], s[8:9], 0, v[186:187]
	global_load_dwordx4 v[192:195], v[188:189], off
	s_nop 1
	v_lshl_or_b32 v162, v54, 5, v3
	v_ashrrev_i32_e32 v163, 31, v162
	v_lshlrev_b64 v[158:159], 2, v[162:163]
	v_lshl_add_u64 v[160:161], s[8:9], 0, v[158:159]
	global_load_dwordx4 v[164:167], v[160:161], off
	s_nop 1
	v_lshl_or_b32 v150, v54, 5, v3
	v_ashrrev_i32_e32 v151, 31, v150
	v_lshlrev_b64 v[148:149], 2, v[150:151]
	v_lshl_add_u64 v[152:153], s[10:11], 0, v[148:149]
	global_load_dwordx4 v[154:157], v[152:153], off
	v_lshl_or_b32 v76, v54, 5, v3
	v_ashrrev_i32_e32 v77, 31, v76
	s_waitcnt lgkmcnt(0)
	v_add_f32_e32 v0, v0, v55
	v_fmamk_f32 v0, v0, 0x3c800000, v219
	v_cmp_gt_f32_e32 vcc, s85, v0
	v_mul_f32_e32 v55, 0x4f800000, v0
	s_and_b32 s20, s20, 0xffffff80
	v_cndmask_b32_e32 v0, v0, v55, vcc
	v_sqrt_f32_e32 v55, v0
	s_addk_i32 s20, 0xff80
	v_add_u32_e32 v56, -1, v55
	v_fma_f32 v57, -v56, v55, v0
	v_cmp_ge_f32_e64 s[4:5], 0, v57
	v_add_u32_e32 v57, 1, v55
	s_nop 0
	v_cndmask_b32_e64 v56, v55, v56, s[4:5]
	v_fma_f32 v55, -v57, v55, v0
	v_cmp_lt_f32_e64 s[4:5], 0, v55
	s_nop 1
	v_cndmask_b32_e64 v55, v56, v57, s[4:5]
	v_mul_f32_e32 v56, 0x37800000, v55
	v_cndmask_b32_e32 v55, v55, v56, vcc
	v_cmp_class_f32_e32 vcc, v0, v221
	s_nop 1
	v_cndmask_b32_e32 v0, v55, v0, vcc
	v_div_scale_f32 v55, s[4:5], v0, v0, 1.0
	v_rcp_f32_e32 v56, v55
	v_readlane_b32 s4, v254, 15
	v_fma_f32 v57, -v55, v56, 1.0
	v_fmac_f32_e32 v56, v57, v56
	v_div_scale_f32 v57, vcc, 1.0, v0, 1.0
	v_mul_f32_e32 v60, v57, v56
	v_fma_f32 v61, -v55, v60, v57
	v_fmac_f32_e32 v60, v61, v56
	v_fma_f32 v55, -v55, v60, v57
	v_div_fmas_f32 v55, v55, v56, v60
	v_div_fixup_f32 v74, v55, v0, 1.0
	v_mov_b32_e32 v0, s4
	ds_read_b64 v[56:57], v0
	v_lshlrev_b32_e32 v0, 2, v3
	v_lshlrev_b64 v[54:55], 2, v[76:77]
	v_lshl_add_u64 v[80:81], s[10:11], 0, v[54:55]
	s_waitcnt vmcnt(0)
	s_nop 0
	v_mov_b32_e32 v84, v154
	v_mov_b32_e32 v85, v155
	v_mov_b32_e32 v86, v156
	v_mov_b32_e32 v87, v157
	s_nop 1
	s_waitcnt lgkmcnt(0)
	v_readfirstlane_b32 s4, v56
	v_readfirstlane_b32 s5, v57
	s_nop 1
	v_lshl_add_u64 v[206:207], s[4:5], 0, v[0:1]
	global_load_dwordx4 v[208:211], v[206:207], off offset:16
	s_nop 1
	v_lshl_add_u64 v[180:181], s[4:5], 0, v[0:1]
	global_load_dwordx4 v[182:185], v[180:181], off offset:144
	s_nop 1
	v_lshl_add_u64 v[174:175], s[4:5], 0, v[0:1]
	global_load_dwordx4 v[176:179], v[174:175], off
	s_nop 1
	v_lshl_add_u64 v[168:169], s[4:5], 0, v[0:1]
	global_load_dwordx4 v[170:173], v[168:169], off offset:128
	v_lshl_add_u64 v[56:57], s[8:9], 0, v[54:55]
	s_waitcnt vmcnt(0)
	s_nop 0
	v_mov_b32_e32 v54, v164
	v_mov_b32_e32 v55, v165
	v_mov_b32_e32 v56, v166
	v_mov_b32_e32 v57, v167
	s_nop 1
	v_lshl_add_u64 v[66:67], s[4:5], 0, v[0:1]
	s_waitcnt vmcnt(0)
	s_nop 0
	v_mov_b32_e32 v60, v170
	v_mov_b32_e32 v61, v171
	v_mov_b32_e32 v62, v172
	v_mov_b32_e32 v63, v173
	s_nop 1
	s_waitcnt vmcnt(0)
	s_nop 0
	v_mov_b32_e32 v88, v176
	v_mov_b32_e32 v89, v177
	v_mov_b32_e32 v90, v178
	v_mov_b32_e32 v91, v179
	s_nop 1
	v_pk_mul_f32 v[50:51], v[50:51], v[74:75] op_sel_hi:[1,0]
	v_pk_mul_f32 v[46:47], v[46:47], v[74:75] op_sel_hi:[1,0]
	v_pk_mul_f32 v[52:53], v[52:53], v[74:75] op_sel_hi:[1,0]
	v_pk_mul_f32 v[48:49], v[48:49], v[74:75] op_sel_hi:[1,0]
	v_pk_mul_f32 v[58:59], v[58:59], v[74:75] op_sel_hi:[1,0]
	s_movk_i32 s4, 0x7f
	v_cmp_lt_i32_e32 vcc, s4, v82
	s_and_b64 s[22:23], s[6:7], vcc
	s_waitcnt vmcnt(0) lgkmcnt(0)
	v_pk_mul_f32 v[60:61], v[60:61], v[50:51]
	v_pk_mul_f32 v[46:47], v[88:89], v[46:47]
	v_pk_mul_f32 v[50:51], v[84:85], v[60:61]
	v_pk_mul_f32 v[48:49], v[48:49], v[90:91]
	v_pk_fma_f32 v[50:51], v[54:55], v[46:47], v[50:51] neg_lo:[0,0,1] neg_hi:[0,0,1]
	v_pk_mul_f32 v[54:55], v[54:55], v[60:61]
	v_bfe_u32 v69, v50, 16, 1
	v_pk_fma_f32 v[46:47], v[84:85], v[46:47], v[54:55]
	v_pk_mul_f32 v[54:55], v[52:53], v[62:63]
	s_waitcnt vmcnt(0)
	s_nop 0
	v_mov_b32_e32 v60, v182
	v_mov_b32_e32 v61, v183
	v_mov_b32_e32 v62, v184
	v_mov_b32_e32 v63, v185
	s_nop 1
	v_pk_mul_f32 v[52:53], v[86:87], v[54:55]
	v_pk_mul_f32 v[54:55], v[56:57], v[54:55]
	v_pk_fma_f32 v[52:53], v[56:57], v[48:49], v[52:53] neg_lo:[0,0,1] neg_hi:[0,0,1]
	v_pk_fma_f32 v[48:49], v[86:87], v[48:49], v[54:55]
	v_or_b32_e32 v54, 4, v76
	v_ashrrev_i32_e32 v55, 31, v54
	v_lshlrev_b64 v[54:55], 2, v[54:55]
	v_lshl_add_u64 v[80:81], s[10:11], 0, v[54:55]
	v_lshl_add_u64 v[56:57], s[8:9], 0, v[54:55]
	s_waitcnt vmcnt(0)
	s_nop 0
	v_mov_b32_e32 v54, v192
	v_mov_b32_e32 v55, v193
	v_mov_b32_e32 v56, v194
	v_mov_b32_e32 v57, v195
	s_nop 1
	v_add3_u32 v69, v50, v69, s91
	v_lshrrev_b32_e32 v69, 16, v69
	s_waitcnt vmcnt(0) lgkmcnt(0)
	v_pk_mul_f32 v[76:77], v[58:59], v[60:61]
	s_waitcnt vmcnt(0)
	s_nop 0
	v_mov_b32_e32 v58, v202
	v_mov_b32_e32 v59, v203
	v_mov_b32_e32 v60, v204
	v_mov_b32_e32 v61, v205
	s_nop 1
	v_pk_mul_f32 v[80:81], v[64:65], v[74:75] op_sel_hi:[1,0]
	s_waitcnt vmcnt(0)
	s_nop 0
	v_mov_b32_e32 v64, v208
	v_mov_b32_e32 v65, v209
	v_mov_b32_e32 v66, v210
	v_mov_b32_e32 v67, v211
	s_nop 1
	s_waitcnt vmcnt(0) lgkmcnt(0)
	v_pk_mul_f32 v[80:81], v[80:81], v[64:65]
	v_pk_mul_f32 v[64:65], v[58:59], v[76:77]
	s_nop 0
	v_pk_fma_f32 v[64:65], v[54:55], v[80:81], v[64:65] neg_lo:[0,0,1] neg_hi:[0,0,1]
	v_pk_mul_f32 v[54:55], v[54:55], v[76:77]
	s_nop 0
	v_pk_fma_f32 v[54:55], v[58:59], v[80:81], v[54:55]
	v_pk_mul_f32 v[58:59], v[72:73], v[74:75] op_sel_hi:[1,0]
	s_nop 0
	v_pk_mul_f32 v[58:59], v[58:59], v[62:63]
	v_pk_mul_f32 v[62:63], v[70:71], v[74:75] op_sel_hi:[1,0]
	v_bfe_u32 v70, v64, 16, 1
	v_pk_mul_f32 v[62:63], v[62:63], v[66:67]
	v_pk_mul_f32 v[66:67], v[60:61], v[58:59]
	v_add3_u32 v70, v64, v70, s91
	v_pk_fma_f32 v[66:67], v[56:57], v[62:63], v[66:67] neg_lo:[0,0,1] neg_hi:[0,0,1]
	v_pk_mul_f32 v[56:57], v[56:57], v[58:59]
	v_bfe_u32 v58, v65, 16, 1
	v_pk_fma_f32 v[56:57], v[60:61], v[62:63], v[56:57]
	v_bfe_u32 v60, v67, 16, 1
	v_bfe_u32 v61, v53, 16, 1
	v_add3_u32 v62, v53, v61, s91
	v_add3_u32 v61, v67, v60, s91
	v_bfe_u32 v60, v52, 16, 1
	v_bfe_u32 v59, v51, 16, 1
	v_bfe_u32 v63, v66, 16, 1
	v_add3_u32 v60, v52, v60, s91
	v_add3_u32 v59, v51, v59, s91
	v_add3_u32 v58, v65, v58, s91
	v_add3_u32 v63, v66, v63, s91
	v_lshrrev_b32_e32 v71, 16, v60
	v_lshrrev_b32_e32 v60, 16, v70
	v_lshrrev_b32_e32 v63, 16, v63
	v_and_or_b32 v60, v58, s33, v60
	v_and_or_b32 v58, v59, s33, v69
	v_and_or_b32 v59, v62, s33, v71
	v_mul_lo_u32 v62, v82, s88
	v_and_or_b32 v61, v61, s33, v63
	v_add3_u32 v62, 0, v62, v68
	ds_write_b128 v62, v[58:61]
	v_bfe_u32 v60, v57, 16, 1
	v_bfe_u32 v61, v49, 16, 1
	v_add3_u32 v63, v49, v61, s91
	v_add3_u32 v61, v57, v60, s91
	v_bfe_u32 v60, v48, 16, 1
	v_bfe_u32 v69, v56, 16, 1
	v_bfe_u32 v70, v46, 16, 1
	v_bfe_u32 v71, v54, 16, 1
	v_bfe_u32 v58, v55, 16, 1
	v_bfe_u32 v59, v47, 16, 1
	v_add3_u32 v71, v54, v71, s91
	v_add3_u32 v70, v46, v70, s91
	v_add3_u32 v69, v56, v69, s91
	v_add3_u32 v60, v48, v60, s91
	v_add3_u32 v59, v47, v59, s91
	v_add3_u32 v58, v55, v58, s91
	v_lshrrev_b32_e32 v72, 16, v60
	v_lshrrev_b32_e32 v69, 16, v69
	v_lshrrev_b32_e32 v70, 16, v70
	v_lshrrev_b32_e32 v60, 16, v71
	v_and_or_b32 v60, v58, s33, v60
	v_and_or_b32 v58, v59, s33, v70
	v_and_or_b32 v61, v61, s33, v69
	v_and_or_b32 v59, v63, s33, v72
	ds_write_b128 v62, v[58:61] offset:64
	s_and_saveexec_b64 s[4:5], s[22:23]
	s_cbranch_execz .LBB0_467
	v_readlane_b32 s21, v254, 8
	s_lshl_b32 s94, s15, 2
	s_nop 0
	v_mov_b32_e32 v58, s21
	ds_read_b64 v[58:59], v58
	s_mov_b32 s21, 0x4158000
	s_waitcnt lgkmcnt(0)
	v_readfirstlane_b32 s22, v58
	v_add_u32_e32 v58, s20, v82
	v_readfirstlane_b32 s23, v59
	v_ashrrev_i32_e32 v59, 31, v58
	v_lshlrev_b64 v[58:59], 10, v[58:59]
	v_lshl_add_u64 v[58:59], s[22:23], 0, v[58:59]
	v_lshl_add_u64 v[58:59], v[58:59], 0, s[94:95]
	v_lshl_add_u64 v[58:59], v[58:59], 0, v[0:1]
	s_mov_b64 s[22:23], 0x4158000
	v_lshl_add_u64 v[60:61], v[58:59], 0, s[22:23]
	v_add_co_u32_e32 v58, vcc, s21, v58
	s_nop 1
	v_addc_co_u32_e32 v59, vcc, 0, v59, vcc
	global_store_dwordx4 v[58:59], v[50:53], off
	global_store_dwordx4 v[60:61], v[64:67], off offset:16
	global_store_dwordx4 v[60:61], v[46:49], off offset:128
	global_store_dwordx4 v[60:61], v[54:57], off offset:144
.LBB0_467:
	s_or_b64 exec, exec, s[4:5]
	v_add_u32_e32 v46, 0x200, v78
	v_ashrrev_i32_e32 v82, 2, v46
	v_add_u32_e32 v54, s19, v82
	v_cmp_lt_i32_e32 vcc, -1, v54
	v_mov_b32_e32 v64, 0
	v_mov_b32_e32 v65, 0
	v_mov_b32_e32 v58, 0
	v_mov_b32_e32 v59, 0
	v_mov_b32_e32 v70, 0
	v_mov_b32_e32 v71, 0
	v_mov_b32_e32 v72, 0
	v_mov_b32_e32 v73, 0
	v_mov_b32_e32 v46, 0
	v_mov_b32_e32 v47, 0
	v_mov_b32_e32 v50, 0
	v_mov_b32_e32 v51, 0
	v_mov_b32_e32 v48, 0
	v_mov_b32_e32 v49, 0
	v_mov_b32_e32 v52, 0
	v_mov_b32_e32 v53, 0
	s_and_saveexec_b64 s[4:5], vcc
	s_cbranch_execz .LBB0_469
	v_add_u32_e32 v48, s18, v54
	v_mov_b64_e32 v[46:47], s[2:3]
	s_movk_i32 s21, 0xc00
	v_mad_i64_i32 v[46:47], s[22:23], v48, s21, v[46:47]
	s_lshl_b32 s94, s15, 1
	v_lshl_add_u64 v[46:47], v[46:47], 0, s[94:95]
	v_mov_b32_e32 v69, v1
	v_lshl_add_u64 v[46:47], v[46:47], 0, v[68:69]
	global_load_dwordx4 v[58:61], v[46:47], off offset:2048
	global_load_dwordx4 v[64:67], v[46:47], off offset:2112
	s_waitcnt vmcnt(0) lgkmcnt(0)
	v_lshlrev_b32_e32 v46, 16, v58
	v_and_b32_e32 v47, 0xffff0000, v58
	v_lshlrev_b32_e32 v50, 16, v64
	v_and_b32_e32 v51, 0xffff0000, v64
	v_lshlrev_b32_e32 v48, 16, v59
	v_and_b32_e32 v49, 0xffff0000, v59
	v_lshlrev_b32_e32 v52, 16, v65
	v_and_b32_e32 v53, 0xffff0000, v65
	v_lshlrev_b32_e32 v64, 16, v60
	v_and_b32_e32 v65, 0xffff0000, v60
	v_lshlrev_b32_e32 v58, 16, v66
	v_and_b32_e32 v59, 0xffff0000, v66
	v_lshlrev_b32_e32 v70, 16, v61
	v_and_b32_e32 v71, 0xffff0000, v61
	v_lshlrev_b32_e32 v72, 16, v67
	v_and_b32_e32 v73, 0xffff0000, v67
.LBB0_469:
	s_or_b64 exec, exec, s[4:5]
	v_pk_mul_f32 v[56:57], v[50:51], v[50:51]
	v_pk_mul_f32 v[60:61], v[52:53], v[52:53]
	v_pk_fma_f32 v[56:57], v[46:47], v[46:47], v[56:57]
	v_pk_fma_f32 v[60:61], v[48:49], v[48:49], v[60:61]
	v_add_f32_e32 v55, v57, v56
	v_pk_mul_f32 v[62:63], v[58:59], v[58:59]
	v_add_f32_e32 v55, v60, v55
	v_pk_fma_f32 v[62:63], v[64:65], v[64:65], v[62:63]
	v_add_f32_e32 v55, v61, v55
	v_pk_mul_f32 v[66:67], v[72:73], v[72:73]
	v_add_f32_e32 v55, v62, v55
	v_pk_fma_f32 v[66:67], v[70:71], v[70:71], v[66:67]
	v_add_f32_e32 v55, v63, v55
	v_add_f32_e32 v55, v66, v55
	v_add_f32_e32 v55, v67, v55
	ds_bpermute_b32 v56, v5, v55
	v_max_i32_e32 v54, 0, v54
	s_nop 1
	v_lshl_or_b32 v191, v54, 5, v3
	v_or_b32_e32 v196, 4, v191
	v_ashrrev_i32_e32 v197, 31, v196
	v_lshlrev_b64 v[196:197], 2, v[196:197]
	v_lshl_add_u64 v[200:201], s[10:11], 0, v[196:197]
	global_load_dwordx4 v[202:205], v[200:201], off
	s_nop 1
	v_lshl_or_b32 v190, v54, 5, v3
	v_or_b32_e32 v186, 4, v190
	v_ashrrev_i32_e32 v187, 31, v186
	v_lshlrev_b64 v[186:187], 2, v[186:187]
	v_lshl_add_u64 v[188:189], s[8:9], 0, v[186:187]
	global_load_dwordx4 v[192:195], v[188:189], off
	s_nop 1
	v_lshl_or_b32 v162, v54, 5, v3
	v_ashrrev_i32_e32 v163, 31, v162
	v_lshlrev_b64 v[158:159], 2, v[162:163]
	v_lshl_add_u64 v[160:161], s[8:9], 0, v[158:159]
	global_load_dwordx4 v[164:167], v[160:161], off
	s_nop 1
	v_lshl_or_b32 v150, v54, 5, v3
	v_ashrrev_i32_e32 v151, 31, v150
	v_lshlrev_b64 v[148:149], 2, v[150:151]
	v_lshl_add_u64 v[152:153], s[10:11], 0, v[148:149]
	global_load_dwordx4 v[154:157], v[152:153], off
	v_lshl_or_b32 v76, v54, 5, v3
	v_ashrrev_i32_e32 v77, 31, v76
	s_waitcnt lgkmcnt(0)
	v_add_f32_e32 v55, v55, v56
	ds_bpermute_b32 v56, v106, v55
	s_waitcnt lgkmcnt(0)
	v_add_f32_e32 v55, v55, v56
	v_fmamk_f32 v55, v55, 0x3c800000, v219
	v_cmp_gt_f32_e32 vcc, s85, v55
	v_mul_f32_e32 v56, 0x4f800000, v55
	s_nop 0
	v_cndmask_b32_e32 v55, v55, v56, vcc
	v_sqrt_f32_e32 v56, v55
	s_nop 0
	v_add_u32_e32 v57, -1, v56
	v_fma_f32 v60, -v57, v56, v55
	v_cmp_ge_f32_e64 s[4:5], 0, v60
	v_add_u32_e32 v60, 1, v56
	s_nop 0
	v_cndmask_b32_e64 v57, v56, v57, s[4:5]
	v_fma_f32 v56, -v60, v56, v55
	v_cmp_lt_f32_e64 s[4:5], 0, v56
	s_nop 1
	v_cndmask_b32_e64 v56, v57, v60, s[4:5]
	v_mul_f32_e32 v57, 0x37800000, v56
	v_cndmask_b32_e32 v56, v56, v57, vcc
	v_cmp_class_f32_e32 vcc, v55, v221
	s_nop 1
	v_cndmask_b32_e32 v55, v56, v55, vcc
	v_div_scale_f32 v56, s[4:5], v55, v55, 1.0
	v_rcp_f32_e32 v57, v56
	v_readlane_b32 s4, v254, 15
	v_fma_f32 v60, -v56, v57, 1.0
	v_fmac_f32_e32 v57, v60, v57
	v_div_scale_f32 v60, vcc, 1.0, v55, 1.0
	v_mul_f32_e32 v61, v60, v57
	v_fma_f32 v62, -v56, v61, v60
	v_fmac_f32_e32 v61, v62, v57
	v_fma_f32 v56, -v56, v61, v60
	v_div_fmas_f32 v56, v56, v57, v61
	v_div_fixup_f32 v74, v56, v55, 1.0
	v_mov_b32_e32 v55, s4
	ds_read_b64 v[56:57], v55
	v_lshlrev_b64 v[54:55], 2, v[76:77]
	v_lshl_add_u64 v[80:81], s[10:11], 0, v[54:55]
	s_waitcnt vmcnt(0)
	s_nop 0
	v_mov_b32_e32 v84, v154
	v_mov_b32_e32 v85, v155
	v_mov_b32_e32 v86, v156
	v_mov_b32_e32 v87, v157
	s_nop 1
	v_pk_mul_f32 v[50:51], v[50:51], v[74:75] op_sel_hi:[1,0]
	s_waitcnt lgkmcnt(0)
	v_readfirstlane_b32 s4, v56
	v_readfirstlane_b32 s5, v57
	s_nop 1
	v_lshl_add_u64 v[206:207], s[4:5], 0, v[0:1]
	global_load_dwordx4 v[208:211], v[206:207], off offset:16
	s_nop 1
	v_lshl_add_u64 v[180:181], s[4:5], 0, v[0:1]
	global_load_dwordx4 v[182:185], v[180:181], off offset:144
	s_nop 1
	v_lshl_add_u64 v[174:175], s[4:5], 0, v[0:1]
	global_load_dwordx4 v[176:179], v[174:175], off
	s_nop 1
	v_lshl_add_u64 v[168:169], s[4:5], 0, v[0:1]
	global_load_dwordx4 v[170:173], v[168:169], off offset:128
	v_lshl_add_u64 v[56:57], s[8:9], 0, v[54:55]
	s_waitcnt vmcnt(0)
	s_nop 0
	v_mov_b32_e32 v54, v164
	v_mov_b32_e32 v55, v165
	v_mov_b32_e32 v56, v166
	v_mov_b32_e32 v57, v167
	s_nop 1
	v_lshl_add_u64 v[66:67], s[4:5], 0, v[0:1]
	s_waitcnt vmcnt(0)
	s_nop 0
	v_mov_b32_e32 v60, v170
	v_mov_b32_e32 v61, v171
	v_mov_b32_e32 v62, v172
	v_mov_b32_e32 v63, v173
	s_nop 1
	s_waitcnt vmcnt(0)
	s_nop 0
	v_mov_b32_e32 v88, v176
	v_mov_b32_e32 v89, v177
	v_mov_b32_e32 v90, v178
	v_mov_b32_e32 v91, v179
	s_nop 1
	v_pk_mul_f32 v[46:47], v[46:47], v[74:75] op_sel_hi:[1,0]
	v_pk_mul_f32 v[52:53], v[52:53], v[74:75] op_sel_hi:[1,0]
	v_pk_mul_f32 v[48:49], v[48:49], v[74:75] op_sel_hi:[1,0]
	v_pk_mul_f32 v[58:59], v[58:59], v[74:75] op_sel_hi:[1,0]
	s_movk_i32 s4, 0x7f
	v_cmp_lt_i32_e32 vcc, s4, v82
	s_waitcnt vmcnt(0) lgkmcnt(0)
	v_pk_mul_f32 v[60:61], v[60:61], v[50:51]
	v_pk_mul_f32 v[46:47], v[88:89], v[46:47]
	v_pk_mul_f32 v[50:51], v[84:85], v[60:61]
	v_pk_mul_f32 v[48:49], v[48:49], v[90:91]
	v_pk_fma_f32 v[50:51], v[54:55], v[46:47], v[50:51] neg_lo:[0,0,1] neg_hi:[0,0,1]
	v_pk_mul_f32 v[54:55], v[54:55], v[60:61]
	s_nop 0
	v_pk_fma_f32 v[46:47], v[84:85], v[46:47], v[54:55]
	v_pk_mul_f32 v[54:55], v[52:53], v[62:63]
	s_waitcnt vmcnt(0)
	s_nop 0
	v_mov_b32_e32 v60, v182
	v_mov_b32_e32 v61, v183
	v_mov_b32_e32 v62, v184
	v_mov_b32_e32 v63, v185
	s_nop 1
	v_pk_mul_f32 v[52:53], v[86:87], v[54:55]
	v_pk_mul_f32 v[54:55], v[56:57], v[54:55]
	v_pk_fma_f32 v[52:53], v[56:57], v[48:49], v[52:53] neg_lo:[0,0,1] neg_hi:[0,0,1]
	v_pk_fma_f32 v[48:49], v[86:87], v[48:49], v[54:55]
	v_or_b32_e32 v54, 4, v76
	v_ashrrev_i32_e32 v55, 31, v54
	v_lshlrev_b64 v[54:55], 2, v[54:55]
	v_lshl_add_u64 v[80:81], s[10:11], 0, v[54:55]
	v_lshl_add_u64 v[56:57], s[8:9], 0, v[54:55]
	s_waitcnt vmcnt(0)
	s_nop 0
	v_mov_b32_e32 v54, v192
	v_mov_b32_e32 v55, v193
	v_mov_b32_e32 v56, v194
	v_mov_b32_e32 v57, v195
	s_nop 1
	s_and_b64 s[8:9], s[6:7], vcc
	s_waitcnt vmcnt(0) lgkmcnt(0)
	v_pk_mul_f32 v[76:77], v[58:59], v[60:61]
	s_waitcnt vmcnt(0)
	s_nop 0
	v_mov_b32_e32 v58, v202
	v_mov_b32_e32 v59, v203
	v_mov_b32_e32 v60, v204
	v_mov_b32_e32 v61, v205
	s_nop 1
	v_pk_mul_f32 v[80:81], v[64:65], v[74:75] op_sel_hi:[1,0]
	s_waitcnt vmcnt(0)
	s_nop 0
	v_mov_b32_e32 v64, v208
	v_mov_b32_e32 v65, v209
	v_mov_b32_e32 v66, v210
	v_mov_b32_e32 v67, v211
	s_nop 1
	s_waitcnt vmcnt(0) lgkmcnt(0)
	v_pk_mul_f32 v[80:81], v[80:81], v[64:65]
	v_pk_mul_f32 v[64:65], v[58:59], v[76:77]
	s_nop 0
	v_pk_fma_f32 v[64:65], v[54:55], v[80:81], v[64:65] neg_lo:[0,0,1] neg_hi:[0,0,1]
	v_pk_mul_f32 v[54:55], v[54:55], v[76:77]
	v_bfe_u32 v69, v64, 16, 1
	v_pk_fma_f32 v[54:55], v[58:59], v[80:81], v[54:55]
	v_pk_mul_f32 v[58:59], v[72:73], v[74:75] op_sel_hi:[1,0]
	v_bfe_u32 v3, v65, 16, 1
	v_pk_mul_f32 v[58:59], v[58:59], v[62:63]
	v_pk_mul_f32 v[62:63], v[70:71], v[74:75] op_sel_hi:[1,0]
	v_add3_u32 v69, v64, v69, s91
	v_pk_mul_f32 v[62:63], v[62:63], v[66:67]
	v_pk_mul_f32 v[66:67], v[60:61], v[58:59]
	v_add3_u32 v3, v65, v3, s91
	v_pk_fma_f32 v[66:67], v[56:57], v[62:63], v[66:67] neg_lo:[0,0,1] neg_hi:[0,0,1]
	v_pk_mul_f32 v[56:57], v[56:57], v[58:59]
	v_bfe_u32 v58, v51, 16, 1
	v_pk_fma_f32 v[56:57], v[60:61], v[62:63], v[56:57]
	v_bfe_u32 v60, v53, 16, 1
	v_add3_u32 v62, v53, v60, s91
	v_bfe_u32 v60, v52, 16, 1
	v_bfe_u32 v61, v66, 16, 1
	v_bfe_u32 v63, v50, 16, 1
	v_add3_u32 v60, v52, v60, s91
	v_bfe_u32 v59, v67, 16, 1
	v_add3_u32 v63, v50, v63, s91
	v_add3_u32 v61, v66, v61, s91
	v_lshrrev_b32_e32 v70, 16, v60
	v_lshrrev_b32_e32 v60, 16, v69
	v_add3_u32 v59, v67, v59, s91
	v_add3_u32 v58, v51, v58, s91
	v_lshrrev_b32_e32 v61, 16, v61
	v_lshrrev_b32_e32 v63, 16, v63
	v_and_or_b32 v60, v3, s33, v60
	v_mul_lo_u32 v3, v82, s88
	v_and_or_b32 v58, v58, s33, v63
	v_and_or_b32 v61, v59, s33, v61
	v_and_or_b32 v59, v62, s33, v70
	v_add3_u32 v3, 0, v3, v68
	ds_write_b128 v3, v[58:61]
	v_bfe_u32 v60, v57, 16, 1
	v_bfe_u32 v61, v49, 16, 1
	v_add3_u32 v62, v49, v61, s91
	v_add3_u32 v61, v57, v60, s91
	v_bfe_u32 v60, v48, 16, 1
	v_bfe_u32 v63, v56, 16, 1
	v_bfe_u32 v68, v46, 16, 1
	v_bfe_u32 v69, v54, 16, 1
	v_bfe_u32 v58, v55, 16, 1
	v_bfe_u32 v59, v47, 16, 1
	v_add3_u32 v69, v54, v69, s91
	v_add3_u32 v68, v46, v68, s91
	v_add3_u32 v63, v56, v63, s91
	v_add3_u32 v60, v48, v60, s91
	v_add3_u32 v59, v47, v59, s91
	v_add3_u32 v58, v55, v58, s91
	v_lshrrev_b32_e32 v70, 16, v60
	v_lshrrev_b32_e32 v63, 16, v63
	v_lshrrev_b32_e32 v68, 16, v68
	v_lshrrev_b32_e32 v60, 16, v69
	v_and_or_b32 v60, v58, s33, v60
	v_and_or_b32 v58, v59, s33, v68
	v_and_or_b32 v61, v61, s33, v63
	v_and_or_b32 v59, v62, s33, v70
	ds_write_b128 v3, v[58:61] offset:64
	s_and_saveexec_b64 s[4:5], s[8:9]
	s_cbranch_execz .LBB0_471
	v_readlane_b32 s8, v254, 8
	s_lshl_b32 s94, s15, 2
	s_nop 0
	v_mov_b32_e32 v3, s8
	ds_read_b64 v[58:59], v3
	s_waitcnt lgkmcnt(0)
	v_readfirstlane_b32 s8, v58
	v_add_u32_e32 v58, s20, v82
	v_readfirstlane_b32 s9, v59
	v_ashrrev_i32_e32 v59, 31, v58
	v_lshlrev_b64 v[58:59], 10, v[58:59]
	v_lshl_add_u64 v[58:59], s[8:9], 0, v[58:59]
	v_lshl_add_u64 v[58:59], v[58:59], 0, s[94:95]
	v_lshl_add_u64 v[58:59], v[58:59], 0, v[0:1]
	s_mov_b64 s[8:9], 0x4158000
	v_lshl_add_u64 v[60:61], v[58:59], 0, s[8:9]
	s_mov_b32 s8, 0x4158000
	v_add_co_u32_e32 v58, vcc, s8, v58
	s_nop 1
	v_addc_co_u32_e32 v59, vcc, 0, v59, vcc
	global_store_dwordx4 v[58:59], v[50:53], off
	global_store_dwordx4 v[60:61], v[64:67], off offset:16
	global_store_dwordx4 v[60:61], v[46:49], off offset:128
	global_store_dwordx4 v[60:61], v[54:57], off offset:144
.LBB0_471:
	s_or_b64 exec, exec, s[4:5]
	s_nop 0
	v_and_b32_e32 v56, 0xff, v78
	v_add_u32_e32 v0, s19, v56
	v_cmp_lt_i32_e64 s[4:5], -1, v0
	v_ashrrev_i32_e32 v3, 3, v78
	v_add_u32_e32 v0, s18, v0
	v_mov_b64_e32 v[46:47], s[2:3]
	s_movk_i32 s2, 0xc00
	v_and_b32_e32 v54, 0xffffffe0, v3
	v_mad_i64_i32 v[46:47], s[2:3], v0, s2, v[46:47]
	s_lshl_b32 s94, s15, 1
	v_lshl_add_u64 v[46:47], v[46:47], 0, s[94:95]
	v_ashrrev_i32_e32 v55, 31, v54
	v_lshl_add_u64 v[58:59], v[54:55], 1, v[46:47]
	v_mov_b32_e32 v46, 0
	v_mov_b32_e32 v47, 0
	v_mov_b32_e32 v48, 0
	v_mov_b32_e32 v49, 0
	v_mov_b32_e32 v50, 0
	v_mov_b32_e32 v51, 0
	v_mov_b32_e32 v52, 0
	v_mov_b32_e32 v53, 0
	s_and_saveexec_b64 s[2:3], s[4:5]
	s_cbranch_execz .LBB0_473
	global_load_dwordx4 v[50:53], v[58:59], off offset:2560
	s_waitcnt vmcnt(0) lgkmcnt(0)
	v_lshlrev_b32_e32 v46, 16, v50
	v_and_b32_e32 v47, 0xffff0000, v50
	v_lshlrev_b32_e32 v48, 16, v51
	v_and_b32_e32 v49, 0xffff0000, v51
	v_lshlrev_b32_e32 v50, 16, v52
	v_and_b32_e32 v51, 0xffff0000, v52
	v_lshlrev_b32_e32 v52, 16, v53
	v_and_b32_e32 v53, 0xffff0000, v53
.LBB0_473:
	s_or_b64 exec, exec, s[2:3]
	s_movk_i32 s2, 0x7f
	v_cmp_lt_u32_e32 vcc, s2, v56
	s_and_b64 s[2:3], s[6:7], vcc
	v_bfe_u32 v60, v46, 16, 1
	s_movk_i32 s6, 0x210
	v_lshl_add_u32 v0, v56, 1, 0
	v_add3_u32 v61, v46, v60, s91
	v_mul_lo_u32 v60, v54, s6
	v_add_u32_e32 v60, v0, v60
	ds_write_b16_d16_hi v60, v61 offset:36864
	v_bfe_u32 v61, v47, 16, 1
	v_add3_u32 v61, v47, v61, s91
	ds_write_b16_d16_hi v60, v61 offset:37392
	v_bfe_u32 v61, v48, 16, 1
	v_add3_u32 v61, v48, v61, s91
	ds_write_b16_d16_hi v60, v61 offset:37920
	v_bfe_u32 v61, v49, 16, 1
	v_add3_u32 v61, v49, v61, s91
	ds_write_b16_d16_hi v60, v61 offset:38448
	v_bfe_u32 v61, v50, 16, 1
	v_add3_u32 v61, v50, v61, s91
	ds_write_b16_d16_hi v60, v61 offset:38976
	v_bfe_u32 v61, v51, 16, 1
	v_add3_u32 v61, v51, v61, s91
	ds_write_b16_d16_hi v60, v61 offset:39504
	v_bfe_u32 v61, v52, 16, 1
	v_add_u32_e32 v56, s20, v56
	v_add3_u32 v61, v52, v61, s91
	v_ashrrev_i32_e32 v57, 31, v56
	ds_write_b16_d16_hi v60, v61 offset:40032
	v_bfe_u32 v61, v53, 16, 1
	v_lshlrev_b64 v[56:57], 10, v[56:57]
	v_add3_u32 v61, v53, v61, s91
	ds_write_b16_d16_hi v60, v61 offset:40560
	s_and_saveexec_b64 s[6:7], s[2:3]
	s_cbranch_execz .LBB0_475
	v_readlane_b32 s8, v254, 8
	s_lshl_b32 s94, s15, 2
	s_nop 0
	v_mov_b32_e32 v61, s8
	ds_read_b64 v[62:63], v61
	s_waitcnt lgkmcnt(0)
	v_readfirstlane_b32 s8, v62
	v_readfirstlane_b32 s9, v63
	s_nop 1
	v_lshl_add_u64 v[62:63], s[8:9], 0, v[56:57]
	v_lshl_add_u64 v[62:63], v[62:63], 0, s[94:95]
	v_lshl_add_u64 v[62:63], v[54:55], 2, v[62:63]
	s_mov_b64 s[8:9], 0x41d8000
	v_lshl_add_u64 v[64:65], v[62:63], 0, s[8:9]
	v_add_co_u32_e32 v62, vcc, 0x41d8000, v62
	s_nop 1
	v_addc_co_u32_e32 v63, vcc, 0, v63, vcc
	global_store_dwordx4 v[62:63], v[46:49], off
	global_store_dwordx4 v[64:65], v[50:53], off offset:16
.LBB0_475:
	s_or_b64 exec, exec, s[6:7]
	v_mov_b32_e32 v46, 0
	v_mov_b32_e32 v47, 0
	v_mov_b32_e32 v48, 0
	v_mov_b32_e32 v49, 0
	v_mov_b32_e32 v50, 0
	v_mov_b32_e32 v51, 0
	v_mov_b32_e32 v52, 0
	v_mov_b32_e32 v53, 0
	s_and_saveexec_b64 s[6:7], s[4:5]
	s_cbranch_execz .LBB0_477
	global_load_dwordx4 v[50:53], v[58:59], off offset:2576
	s_waitcnt vmcnt(0) lgkmcnt(0)
	v_lshlrev_b32_e32 v46, 16, v50
	v_and_b32_e32 v47, 0xffff0000, v50
	v_lshlrev_b32_e32 v48, 16, v51
	v_and_b32_e32 v49, 0xffff0000, v51
	v_lshlrev_b32_e32 v50, 16, v52
	v_and_b32_e32 v51, 0xffff0000, v52
	v_lshlrev_b32_e32 v52, 16, v53
	v_and_b32_e32 v53, 0xffff0000, v53
.LBB0_477:
	s_or_b64 exec, exec, s[6:7]
	v_bfe_u32 v61, v46, 16, 1
	v_add3_u32 v61, v46, v61, s91
	ds_write_b16_d16_hi v60, v61 offset:41088
	v_bfe_u32 v61, v47, 16, 1
	v_add3_u32 v61, v47, v61, s91
	ds_write_b16_d16_hi v60, v61 offset:41616
	v_bfe_u32 v61, v48, 16, 1
	v_add3_u32 v61, v48, v61, s91
	ds_write_b16_d16_hi v60, v61 offset:42144
	v_bfe_u32 v61, v49, 16, 1
	v_add3_u32 v61, v49, v61, s91
	ds_write_b16_d16_hi v60, v61 offset:42672
	v_bfe_u32 v61, v50, 16, 1
	v_add3_u32 v61, v50, v61, s91
	ds_write_b16_d16_hi v60, v61 offset:43200
	v_bfe_u32 v61, v51, 16, 1
	v_add3_u32 v61, v51, v61, s91
	ds_write_b16_d16_hi v60, v61 offset:43728
	v_bfe_u32 v61, v52, 16, 1
	v_add3_u32 v61, v52, v61, s91
	ds_write_b16_d16_hi v60, v61 offset:44256
	v_bfe_u32 v61, v53, 16, 1
	v_add3_u32 v61, v53, v61, s91
	ds_write_b16_d16_hi v60, v61 offset:44784
	s_and_saveexec_b64 s[6:7], s[2:3]
	s_cbranch_execz .LBB0_479
	v_readlane_b32 s8, v254, 8
	s_lshl_b32 s94, s15, 2
	s_nop 0
	v_mov_b32_e32 v61, s8
	ds_read_b64 v[62:63], v61
	s_waitcnt lgkmcnt(0)
	v_readfirstlane_b32 s8, v62
	v_readfirstlane_b32 s9, v63
	s_nop 1
	v_lshl_add_u64 v[62:63], s[8:9], 0, v[56:57]
	v_lshl_add_u64 v[62:63], v[62:63], 0, s[94:95]
	v_lshl_add_u64 v[62:63], v[54:55], 2, v[62:63]
	v_add_co_u32_e32 v62, vcc, 0x41d8000, v62
	s_nop 1
	v_addc_co_u32_e32 v63, vcc, 0, v63, vcc
	global_store_dwordx4 v[62:63], v[46:49], off offset:32
	global_store_dwordx4 v[62:63], v[50:53], off offset:48
.LBB0_479:
	s_or_b64 exec, exec, s[6:7]
	v_mov_b32_e32 v46, 0
	v_mov_b32_e32 v47, 0
	v_mov_b32_e32 v48, 0
	v_mov_b32_e32 v49, 0
	v_mov_b32_e32 v50, 0
	v_mov_b32_e32 v51, 0
	v_mov_b32_e32 v52, 0
	v_mov_b32_e32 v53, 0
	s_and_saveexec_b64 s[6:7], s[4:5]
	s_cbranch_execz .LBB0_481
	global_load_dwordx4 v[50:53], v[58:59], off offset:2592
	s_waitcnt vmcnt(0) lgkmcnt(0)
	v_lshlrev_b32_e32 v46, 16, v50
	v_and_b32_e32 v47, 0xffff0000, v50
	v_lshlrev_b32_e32 v48, 16, v51
	v_and_b32_e32 v49, 0xffff0000, v51
	v_lshlrev_b32_e32 v50, 16, v52
	v_and_b32_e32 v51, 0xffff0000, v52
	v_lshlrev_b32_e32 v52, 16, v53
	v_and_b32_e32 v53, 0xffff0000, v53
.LBB0_481:
	s_or_b64 exec, exec, s[6:7]
	v_bfe_u32 v61, v46, 16, 1
	v_add3_u32 v61, v46, v61, s91
	ds_write_b16_d16_hi v60, v61 offset:45312
	v_bfe_u32 v61, v47, 16, 1
	v_add3_u32 v61, v47, v61, s91
	ds_write_b16_d16_hi v60, v61 offset:45840
	v_bfe_u32 v61, v48, 16, 1
	v_add3_u32 v61, v48, v61, s91
	ds_write_b16_d16_hi v60, v61 offset:46368
	v_bfe_u32 v61, v49, 16, 1
	v_add3_u32 v61, v49, v61, s91
	ds_write_b16_d16_hi v60, v61 offset:46896
	v_bfe_u32 v61, v50, 16, 1
	v_add3_u32 v61, v50, v61, s91
	ds_write_b16_d16_hi v60, v61 offset:47424
	v_bfe_u32 v61, v51, 16, 1
	v_add3_u32 v61, v51, v61, s91
	ds_write_b16_d16_hi v60, v61 offset:47952
	v_bfe_u32 v61, v52, 16, 1
	v_add3_u32 v61, v52, v61, s91
	ds_write_b16_d16_hi v60, v61 offset:48480
	v_bfe_u32 v61, v53, 16, 1
	v_add3_u32 v61, v53, v61, s91
	ds_write_b16_d16_hi v60, v61 offset:49008
	s_and_saveexec_b64 s[6:7], s[2:3]
	s_cbranch_execz .LBB0_483
	v_readlane_b32 s8, v254, 8
	s_lshl_b32 s94, s15, 2
	s_nop 0
	v_mov_b32_e32 v61, s8
	ds_read_b64 v[62:63], v61
	s_waitcnt lgkmcnt(0)
	v_readfirstlane_b32 s8, v62
	v_readfirstlane_b32 s9, v63
	s_nop 1
	v_lshl_add_u64 v[62:63], s[8:9], 0, v[56:57]
	v_lshl_add_u64 v[62:63], v[62:63], 0, s[94:95]
	v_lshl_add_u64 v[62:63], v[54:55], 2, v[62:63]
	v_add_co_u32_e32 v62, vcc, 0x41d8000, v62
	s_nop 1
	v_addc_co_u32_e32 v63, vcc, 0, v63, vcc
	global_store_dwordx4 v[62:63], v[46:49], off offset:64
	global_store_dwordx4 v[62:63], v[50:53], off offset:80
.LBB0_483:
	s_or_b64 exec, exec, s[6:7]
	v_mov_b32_e32 v46, 0
	v_mov_b32_e32 v47, 0
	v_mov_b32_e32 v48, 0
	v_mov_b32_e32 v49, 0
	v_mov_b32_e32 v50, 0
	v_mov_b32_e32 v51, 0
	v_mov_b32_e32 v52, 0
	v_mov_b32_e32 v53, 0
	s_and_saveexec_b64 s[6:7], s[4:5]
	s_cbranch_execz .LBB0_485
	global_load_dwordx4 v[50:53], v[58:59], off offset:2608
	s_waitcnt vmcnt(0) lgkmcnt(0)
	v_lshlrev_b32_e32 v46, 16, v50
	v_and_b32_e32 v47, 0xffff0000, v50
	v_lshlrev_b32_e32 v48, 16, v51
	v_and_b32_e32 v49, 0xffff0000, v51
	v_lshlrev_b32_e32 v50, 16, v52
	v_and_b32_e32 v51, 0xffff0000, v52
	v_lshlrev_b32_e32 v52, 16, v53
	v_and_b32_e32 v53, 0xffff0000, v53
.LBB0_485:
	s_mov_b32 s93, s40
	s_or_b64 exec, exec, s[6:7]
	v_bfe_u32 v58, v46, 16, 1
	v_add3_u32 v58, v46, v58, s91
	ds_write_b16_d16_hi v60, v58 offset:49536
	v_bfe_u32 v58, v47, 16, 1
	v_add3_u32 v58, v47, v58, s91
	ds_write_b16_d16_hi v60, v58 offset:50064
	v_bfe_u32 v58, v48, 16, 1
	v_add3_u32 v58, v48, v58, s91
	ds_write_b16_d16_hi v60, v58 offset:50592
	v_bfe_u32 v58, v49, 16, 1
	v_add3_u32 v58, v49, v58, s91
	ds_write_b16_d16_hi v60, v58 offset:51120
	v_bfe_u32 v58, v50, 16, 1
	v_add3_u32 v58, v50, v58, s91
	ds_write_b16_d16_hi v60, v58 offset:51648
	v_bfe_u32 v58, v51, 16, 1
	v_add3_u32 v58, v51, v58, s91
	s_lshl_b32 s4, s16, 6
	ds_write_b16_d16_hi v60, v58 offset:52176
	v_bfe_u32 v58, v52, 16, 1
	v_writelane_b32 v254, s4, 62
	s_lshl_b32 s4, s17, 6
	v_add3_u32 v58, v52, v58, s91
	v_writelane_b32 v254, s4, 63
	ds_write_b16_d16_hi v60, v58 offset:52704
	v_bfe_u32 v58, v53, 16, 1
	v_or_b32_e32 v3, 31, v3
	s_movk_i32 s4, 0x210
	v_add3_u32 v60, v53, v58, s91
	v_mad_u64_u32 v[58:59], s[4:5], v3, s4, v[0:1]
	ds_write_b16_d16_hi v58, v60 offset:36864
	s_and_saveexec_b64 s[4:5], s[2:3]
	s_cbranch_execz .LBB0_399
	v_readlane_b32 s2, v254, 8
	s_lshl_b32 s94, s15, 2
	s_nop 0
	v_mov_b32_e32 v0, s2
	ds_read_b64 v[58:59], v0
	s_waitcnt lgkmcnt(0)
	v_readfirstlane_b32 s2, v58
	v_readfirstlane_b32 s3, v59
	s_nop 1
	v_lshl_add_u64 v[56:57], s[2:3], 0, v[56:57]
	v_lshl_add_u64 v[56:57], v[56:57], 0, s[94:95]
	v_lshl_add_u64 v[54:55], v[54:55], 2, v[56:57]
	v_add_co_u32_e32 v54, vcc, 0x41d8000, v54
	s_nop 1
	v_addc_co_u32_e32 v55, vcc, 0, v55, vcc
	global_store_dwordx4 v[54:55], v[46:49], off offset:96
	global_store_dwordx4 v[54:55], v[50:53], off offset:112
	s_branch .LBB0_399

.LBB0_505:
	global_load_dwordx4 v[30:33], v[18:19], off nt
	ds_read_b32 v34, v11
	v_add_co_u32_e32 v21, vcc, 1, v21
	v_add_u32_e32 v20, 4, v20
	v_lshl_add_u64 v[18:19], v[18:19], 0, s[6:7]
	s_or_b64 s[4:5], vcc, s[4:5]
	s_waitcnt vmcnt(0) lgkmcnt(0)
	v_pk_fma_f32 v[14:15], v[32:33], v[34:35], v[14:15] op_sel_hi:[1,0,1]
	v_pk_fma_f32 v[16:17], v[30:31], v[34:35], v[16:17] op_sel_hi:[1,0,1]
	ds_read_b32 v34, v11 offset:1040
	s_waitcnt lgkmcnt(0)
	v_pk_fma_f32 v[8:9], v[32:33], v[34:35], v[8:9] op_sel_hi:[1,0,1]
	v_pk_fma_f32 v[12:13], v[30:31], v[34:35], v[12:13] op_sel_hi:[1,0,1]
	ds_read_b32 v34, v11 offset:2080
	v_add_u32_e32 v11, 16, v11
	s_waitcnt lgkmcnt(0)
	v_pk_fma_f32 v[2:3], v[32:33], v[34:35], v[2:3] op_sel_hi:[1,0,1]
	v_pk_fma_f32 v[6:7], v[30:31], v[34:35], v[6:7] op_sel_hi:[1,0,1]
	s_andn2_b64 exec, exec, s[4:5]
	s_cbranch_execnz .LBB0_505
	s_or_b64 exec, exec, s[4:5]

.LBB0_520:
	v_and_b32_e32 v13, 0xffffffc0, v2
	v_and_b32_e32 v12, 0xffffffc0, v3
	v_lshl_add_u32 v13, v13, 2, v0
	ds_read2st64_b32 v[10:11], v6 offset1:8
	v_lshl_add_u32 v14, v12, 2, v0
	ds_read_b32 v12, v13 offset:20672
	ds_read_b32 v13, v14 offset:20672
	v_ashrrev_i32_e32 v14, 6, v2
	v_ashrrev_i32_e32 v15, 6, v3
	v_add_u32_e32 v9, -2, v9
	v_cmp_eq_u32_e32 vcc, 0, v9
	s_waitcnt lgkmcnt(0)
	v_pk_add_f32 v[10:11], v[10:11], v[12:13]
	v_mul_lo_u32 v12, v15, s8
	v_mul_lo_u32 v13, v14, s8
	v_add_u32_e32 v13, 0, v13
	v_add_u32_e32 v16, 0, v12
	v_mul_hi_i32 v14, v14, s9
	ds_read_b32 v12, v13 offset:3584
	ds_read_b32 v13, v16 offset:3584
	v_lshrrev_b32_e32 v16, 31, v14
	v_mul_hi_i32 v15, v15, s9
	v_add_u32_e32 v14, v14, v16
	v_lshrrev_b32_e32 v16, 31, v15
	v_add_u32_e32 v15, v15, v16
	v_lshl_add_u32 v14, v14, 8, v0
	v_lshl_add_u32 v15, v15, 8, v0
	ds_read_b32 v14, v14 offset:16576
	ds_read_b32 v15, v15 offset:16576
	v_add_u32_e32 v6, 0x1000, v6
	s_or_b64 s[6:7], vcc, s[6:7]
	s_waitcnt lgkmcnt(0)
	v_pk_fma_f32 v[10:11], v[12:13], v[14:15], v[10:11]
	s_nop 0
	v_and_b32_sdwa v12, v11, v218 dst_sel:DWORD dst_unused:UNUSED_PAD src0_sel:WORD_1 src1_sel:DWORD
	v_and_b32_sdwa v13, v10, v218 dst_sel:DWORD dst_unused:UNUSED_PAD src0_sel:WORD_1 src1_sel:DWORD
	v_add3_u32 v14, v11, v12, s91
	v_add3_u32 v15, v10, v13, s91
	v_ashrrev_i32_e32 v13, 31, v2
	v_mov_b32_e32 v12, v2
	v_ashrrev_i32_e32 v11, 31, v3
	v_mov_b32_e32 v10, v3
	v_lshl_add_u64 v[12:13], v[12:13], 1, s[4:5]
	v_add_u32_e32 v3, 0x400, v3
	v_add_u32_e32 v2, 0x400, v2
	v_lshl_add_u64 v[10:11], v[10:11], 1, s[4:5]
	global_store_short_d16_hi v[12:13], v15, off
	global_store_short_d16_hi v[10:11], v14, off
	s_andn2_b64 exec, exec, s[6:7]
	s_cbranch_execnz .LBB0_520
	s_or_b64 exec, exec, s[6:7]
	v_cmp_ne_u32_e32 vcc, v7, v8
	v_lshl_add_u32 v6, v8, 9, v78
	s_orn2_b64 s[4:5], vcc, exec

.LBB0_524:
	v_and_b32_e32 v9, 0x3fffffc0, v6
	v_lshl_add_u32 v9, v9, 2, v0
	ds_read_b32 v7, v8
	ds_read_b32 v9, v9 offset:20672
	v_cmp_lt_i32_e32 vcc, s4, v6
	v_add_u32_e32 v8, 0x800, v8
	s_or_b64 s[2:3], vcc, s[2:3]
	s_waitcnt lgkmcnt(0)
	v_add_f32_e32 v7, v7, v9
	v_ashrrev_i32_e32 v9, 6, v6
	v_mul_lo_u32 v10, v9, s5
	v_mul_hi_i32 v9, v9, s6
	v_lshrrev_b32_e32 v11, 31, v9
	v_add_u32_e32 v9, v9, v11
	v_add_u32_e32 v10, 0, v10
	v_lshl_add_u32 v9, v9, 8, v0
	ds_read_b32 v10, v10 offset:3584
	ds_read_b32 v9, v9 offset:16576
	s_waitcnt lgkmcnt(0)
	v_fmac_f32_e32 v7, v10, v9
	v_bfe_u32 v9, v7, 16, 1
	v_add3_u32 v7, v7, v9, s91
	global_store_short_d16_hi v[2:3], v7, off
	v_add_u32_e32 v7, 0x200, v6
	v_lshl_add_u64 v[2:3], v[2:3], 0, s[8:9]
	v_mov_b32_e32 v6, v7
	s_andn2_b64 exec, exec, s[2:3]
	s_cbranch_execnz .LBB0_524

.LBB0_536:
	v_add_u32_e32 v28, s4, v5
	v_mad_i64_i32 v[6:7], s[4:5], s11, v28, 0
	v_lshl_add_u64 v[10:11], v[6:7], 1, v[2:3]
	v_mov_b32_e32 v14, s9
	global_load_dwordx4 v[6:9], v[10:11], off nt
	s_nop 0
	global_load_dwordx4 v[10:13], v[10:11], off offset:64 nt
	ds_read_b64 v[14:15], v14
	v_ashrrev_i32_e32 v29, 31, v28
	s_waitcnt lgkmcnt(0)
	v_readfirstlane_b32 s4, v14
	v_readfirstlane_b32 s5, v15
	s_add_u32 s4, s4, s6
	s_addc_u32 s5, s5, s7
	s_nop 1
	v_lshl_add_u64 v[126:127], s[4:5], 0, v[0:1]
	global_load_dwordx4 v[128:131], v[126:127], off offset:144
	s_nop 1
	v_lshl_add_u64 v[120:121], s[4:5], 0, v[0:1]
	global_load_dwordx4 v[122:125], v[120:121], off offset:16
	s_nop 1
	v_lshl_add_u64 v[114:115], s[4:5], 0, v[0:1]
	global_load_dwordx4 v[116:119], v[114:115], off
	v_lshl_add_u64 v[18:19], s[4:5], 0, v[0:1]
	global_load_dwordx4 v[14:17], v[18:19], off offset:128
	s_waitcnt vmcnt(0)
	v_lshlrev_b32_e32 v35, 16, v7
	v_lshlrev_b32_e32 v21, 16, v11
	v_lshlrev_b32_e32 v20, 16, v10
	v_and_b32_e32 v23, 0xffff0000, v11
	v_and_b32_e32 v22, 0xffff0000, v10
	v_and_b32_e32 v33, 0xffff0000, v13
	v_and_b32_e32 v32, 0xffff0000, v12
	v_lshlrev_b32_e32 v34, 16, v6
	v_and_b32_e32 v37, 0xffff0000, v7
	v_and_b32_e32 v36, 0xffff0000, v6
	v_mov_b32_e32 v6, v23
	v_mov_b32_e32 v7, v21
	s_waitcnt lgkmcnt(0)
	v_mov_b32_e32 v24, v14
	v_mov_b32_e32 v25, v16
	v_mov_b32_e32 v16, v15
	v_lshlrev_b32_e32 v15, 16, v13
	v_lshlrev_b32_e32 v14, 16, v12
	s_waitcnt vmcnt(0)
	s_nop 0
	v_mov_b32_e32 v10, v116
	v_mov_b32_e32 v11, v117
	v_mov_b32_e32 v12, v118
	v_mov_b32_e32 v13, v119
	s_nop 1
	v_pk_mul_f32 v[6:7], v[6:7], v[6:7]
	v_mov_b32_e32 v38, v37
	v_mov_b32_e32 v39, v35
	v_pk_fma_f32 v[38:39], v[38:39], v[38:39], v[6:7]
	v_and_b32_e32 v43, 0xffff0000, v9
	v_and_b32_e32 v42, 0xffff0000, v8
	v_mov_b32_e32 v44, v32
	v_mov_b32_e32 v45, v14
	v_pk_mul_f32 v[44:45], v[44:45], v[44:45]
	v_mov_b32_e32 v46, v42
	v_mov_b32_e32 v48, v43
	v_mul_f32_e32 v27, v36, v36
	v_fmac_f32_e32 v27, v22, v22
	s_waitcnt vmcnt(0) lgkmcnt(0)
	v_mov_b32_e32 v40, v10
	v_mov_b32_e32 v41, v12
	v_mov_b32_e32 v12, v11
	v_lshlrev_b32_e32 v11, 16, v9
	v_lshlrev_b32_e32 v10, 16, v8
	s_waitcnt vmcnt(0)
	s_nop 0
	v_mov_b32_e32 v6, v122
	v_mov_b32_e32 v7, v123
	v_mov_b32_e32 v8, v124
	v_mov_b32_e32 v9, v125
	s_nop 1
	v_mov_b32_e32 v47, v10
	v_pk_fma_f32 v[44:45], v[46:47], v[46:47], v[44:45]
	v_mov_b32_e32 v46, v33
	v_mov_b32_e32 v47, v15
	v_pk_mul_f32 v[46:47], v[46:47], v[46:47]
	v_mov_b32_e32 v49, v11
	v_pk_fma_f32 v[46:47], v[48:49], v[48:49], v[46:47]
	v_mul_f32_e32 v48, v34, v34
	v_fmac_f32_e32 v48, v20, v20
	v_add_f32_e32 v27, v48, v27
	v_add_f32_e32 v27, v39, v27
	v_add_f32_e32 v27, v38, v27
	v_add_f32_e32 v27, v45, v27
	v_add_f32_e32 v27, v44, v27
	v_add_f32_e32 v27, v47, v27
	v_add_f32_e32 v27, v46, v27
	ds_bpermute_b32 v38, v98, v27
	s_waitcnt lgkmcnt(0)
	v_add_f32_e32 v27, v27, v38
	ds_bpermute_b32 v38, v99, v27
	s_waitcnt lgkmcnt(0)
	v_add_f32_e32 v27, v27, v38
	v_fmamk_f32 v27, v27, 0x3c800000, v219
	v_cmp_gt_f32_e32 vcc, s85, v27
	v_mul_f32_e32 v38, 0x4f800000, v27
	s_nop 0
	v_cndmask_b32_e32 v27, v27, v38, vcc
	v_sqrt_f32_e32 v38, v27
	s_nop 0
	v_add_u32_e32 v39, -1, v38
	v_fma_f32 v44, -v39, v38, v27
	v_cmp_ge_f32_e64 s[4:5], 0, v44
	v_add_u32_e32 v44, 1, v38
	s_nop 0
	v_cndmask_b32_e64 v39, v38, v39, s[4:5]
	v_fma_f32 v38, -v44, v38, v27
	v_cmp_lt_f32_e64 s[4:5], 0, v38
	s_nop 1
	v_cndmask_b32_e64 v38, v39, v44, s[4:5]
	v_mul_f32_e32 v39, 0x37800000, v38
	v_cndmask_b32_e32 v38, v38, v39, vcc
	v_cmp_class_f32_e32 vcc, v27, v221
	s_nop 1
	v_cndmask_b32_e32 v27, v38, v27, vcc
	v_div_scale_f32 v38, s[4:5], v27, v27, s86
	v_rcp_f32_e32 v39, v38
	s_nop 0
	v_fma_f32 v44, -v38, v39, 1.0
	v_fmac_f32_e32 v39, v44, v39
	v_div_scale_f32 v44, vcc, s86, v27, s86
	v_mul_f32_e32 v45, v44, v39
	v_fma_f32 v46, -v38, v45, v44
	v_fmac_f32_e32 v45, v46, v39
	v_fma_f32 v38, -v38, v45, v44
	v_div_fmas_f32 v38, v38, v39, v45
	v_div_fixup_f32 v38, v38, v27, s86
	v_pk_mul_f32 v[36:37], v[38:39], v[36:37] op_sel_hi:[0,1]
	v_pk_mul_f32 v[12:13], v[12:13], v[36:37]
	v_pk_mul_f32 v[10:11], v[38:39], v[10:11] op_sel_hi:[0,1]
	v_pk_mul_f32 v[34:35], v[38:39], v[34:35] op_sel_hi:[0,1]
	v_pk_mul_f32 v[34:35], v[40:41], v[34:35]
	v_bfe_u32 v27, v13, 16, 1
	v_add3_u32 v13, v13, v27, s91
	v_pk_mul_f32 v[14:15], v[38:39], v[14:15] op_sel_hi:[0,1]
	s_waitcnt vmcnt(0)
	v_mov_b32_e32 v36, v6
	v_mov_b32_e32 v37, v8
	v_pk_mul_f32 v[10:11], v[36:37], v[10:11]
	v_pk_mul_f32 v[36:37], v[38:39], v[42:43] op_sel_hi:[0,1]
	v_mov_b32_e32 v8, v7
	v_pk_mul_f32 v[6:7], v[8:9], v[36:37]
	v_bfe_u32 v36, v12, 16, 1
	v_bfe_u32 v8, v7, 16, 1
	v_bfe_u32 v9, v6, 16, 1
	v_add3_u32 v12, v12, v36, s91
	v_add3_u32 v6, v6, v9, s91
	v_add3_u32 v7, v7, v8, s91
	v_bfe_u32 v8, v34, 16, 1
	v_bfe_u32 v9, v35, 16, 1
	v_bfe_u32 v27, v10, 16, 1
	v_bfe_u32 v36, v11, 16, 1
	v_add3_u32 v11, v11, v36, s91
	v_add3_u32 v10, v10, v27, s91
	v_add3_u32 v9, v35, v9, s91
	v_add3_u32 v8, v34, v8, s91
	v_lshrrev_b32_e32 v27, 16, v8
	v_lshrrev_b32_e32 v34, 16, v9
	v_lshrrev_b32_e32 v8, 16, v10
	v_lshrrev_b32_e32 v9, 16, v11
	v_pk_mul_f32 v[10:11], v[38:39], v[20:21] op_sel_hi:[0,1]
	v_pk_mul_f32 v[20:21], v[24:25], v[10:11]
	v_pk_mul_f32 v[10:11], v[38:39], v[22:23] op_sel_hi:[0,1]
	v_and_or_b32 v9, v7, s33, v9
	v_and_or_b32 v8, v6, s33, v8
	v_and_or_b32 v7, v13, s33, v34
	v_and_or_b32 v6, v12, s33, v27
	v_pk_mul_f32 v[16:17], v[16:17], v[10:11]
	s_waitcnt vmcnt(0)
	s_nop 0
	v_mov_b32_e32 v10, v128
	v_mov_b32_e32 v11, v129
	v_mov_b32_e32 v12, v130
	v_mov_b32_e32 v13, v131
	s_nop 1
	s_waitcnt vmcnt(0) lgkmcnt(0)
	v_mov_b32_e32 v18, v10
	v_mov_b32_e32 v19, v12
	v_pk_mul_f32 v[14:15], v[18:19], v[14:15]
	v_pk_mul_f32 v[18:19], v[38:39], v[32:33] op_sel_hi:[0,1]
	v_mov_b32_e32 v12, v11
	v_pk_mul_f32 v[10:11], v[18:19], v[12:13]
	v_bfe_u32 v18, v17, 16, 1
	v_bfe_u32 v12, v11, 16, 1
	v_bfe_u32 v13, v10, 16, 1
	v_bfe_u32 v19, v16, 16, 1
	v_add3_u32 v16, v16, v19, s91
	v_add3_u32 v17, v17, v18, s91
	v_add3_u32 v10, v10, v13, s91
	v_add3_u32 v11, v11, v12, s91
	v_bfe_u32 v12, v20, 16, 1
	v_bfe_u32 v13, v21, 16, 1
	v_bfe_u32 v18, v14, 16, 1
	v_bfe_u32 v19, v15, 16, 1
	v_add3_u32 v15, v15, v19, s91
	v_add3_u32 v14, v14, v18, s91
	v_add3_u32 v13, v21, v13, s91
	v_add3_u32 v12, v20, v12, s91
	v_lshrrev_b32_e32 v18, 16, v12
	v_lshrrev_b32_e32 v19, 16, v13
	v_lshrrev_b32_e32 v12, 16, v14
	v_lshrrev_b32_e32 v13, 16, v15
	v_and_or_b32 v13, v11, s33, v13
	v_and_or_b32 v12, v10, s33, v12
	v_and_or_b32 v11, v17, s33, v19
	v_and_or_b32 v10, v16, s33, v18
	ds_read_b128 v[14:17], v30
	ds_read_b128 v[18:21], v30 offset:64
	s_waitcnt lgkmcnt(1)
	v_mfma_f32_16x16x32_bf16 v[14:17], v[14:17], v[6:9], 0
	s_waitcnt lgkmcnt(0)
	v_mfma_f32_16x16x32_bf16 v[32:35], v[18:21], v[10:13], v[14:17]
	ds_read_b128 v[18:21], v30 offset:2368
	s_nop 4
	ds_read_b128 v[14:17], v30 offset:2304
	s_waitcnt lgkmcnt(0)
	v_mfma_f32_16x16x32_bf16 v[14:17], v[14:17], v[6:9], 0
	v_mfma_f32_16x16x32_bf16 v[36:39], v[18:21], v[10:13], v[14:17]
	ds_read_b128 v[18:21], v30 offset:4672
	s_nop 5
	ds_read_b128 v[14:17], v30 offset:4608
	s_waitcnt lgkmcnt(0)
	v_mfma_f32_16x16x32_bf16 v[14:17], v[14:17], v[6:9], 0
	v_mfma_f32_16x16x32_bf16 v[40:43], v[18:21], v[10:13], v[14:17]
	ds_read_b128 v[18:21], v30 offset:6976
	s_nop 5
	ds_read_b128 v[14:17], v30 offset:6912
	s_waitcnt lgkmcnt(0)
	v_mfma_f32_16x16x32_bf16 v[14:17], v[14:17], v[6:9], 0
	v_mfma_f32_16x16x32_bf16 v[50:53], v[18:21], v[10:13], v[14:17]
	ds_read_b128 v[18:21], v30 offset:9280
	s_nop 5
	ds_read_b128 v[14:17], v30 offset:9216
	s_waitcnt lgkmcnt(0)
	v_mfma_f32_16x16x32_bf16 v[14:17], v[14:17], v[6:9], 0
	v_mfma_f32_16x16x32_bf16 v[56:59], v[18:21], v[10:13], v[14:17]
	ds_read_b128 v[18:21], v30 offset:11584
	s_nop 5
	ds_read_b128 v[14:17], v30 offset:11520
	s_waitcnt lgkmcnt(0)
	v_mfma_f32_16x16x32_bf16 v[14:17], v[14:17], v[6:9], 0
	v_mfma_f32_16x16x32_bf16 v[66:69], v[18:21], v[10:13], v[14:17]
	ds_read_b128 v[18:21], v30 offset:13888
	s_nop 5
	ds_read_b128 v[14:17], v30 offset:13824
	s_waitcnt lgkmcnt(0)
	v_mfma_f32_16x16x32_bf16 v[14:17], v[14:17], v[6:9], 0
	v_mfma_f32_16x16x32_bf16 v[72:75], v[18:21], v[10:13], v[14:17]
	ds_read_b128 v[18:21], v30 offset:16192
	s_nop 5
	ds_read_b128 v[14:17], v30 offset:16128
	s_waitcnt lgkmcnt(0)
	v_mfma_f32_16x16x32_bf16 v[14:17], v[14:17], v[6:9], 0
	v_mfma_f32_16x16x32_bf16 v[76:79], v[18:21], v[10:13], v[14:17]
	ds_read_b128 v[18:21], v30 offset:18496
	s_nop 5
	ds_read_b128 v[14:17], v30 offset:18432
	s_waitcnt lgkmcnt(0)
	v_mfma_f32_16x16x32_bf16 v[14:17], v[14:17], v[6:9], 0
	v_mfma_f32_16x16x32_bf16 v[84:87], v[18:21], v[10:13], v[14:17]
	ds_read_b128 v[18:21], v30 offset:20800
	s_nop 5
	ds_read_b128 v[14:17], v30 offset:20736
	s_waitcnt lgkmcnt(0)
	v_mfma_f32_16x16x32_bf16 v[14:17], v[14:17], v[6:9], 0
	v_mfma_f32_16x16x32_bf16 v[88:91], v[18:21], v[10:13], v[14:17]
	ds_read_b128 v[18:21], v30 offset:23104
	s_nop 5
	ds_read_b128 v[14:17], v30 offset:23040
	s_waitcnt lgkmcnt(0)
	v_mfma_f32_16x16x32_bf16 v[14:17], v[14:17], v[6:9], 0
	v_mfma_f32_16x16x32_bf16 v[92:95], v[18:21], v[10:13], v[14:17]
	ds_read_b128 v[18:21], v30 offset:25408
	s_nop 5
	ds_read_b128 v[14:17], v30 offset:25344
	s_waitcnt lgkmcnt(0)
	v_mfma_f32_16x16x32_bf16 v[14:17], v[14:17], v[6:9], 0
	v_mfma_f32_16x16x32_bf16 v[102:105], v[18:21], v[10:13], v[14:17]
	ds_read_b128 v[18:21], v30 offset:27712
	s_nop 5
	ds_read_b128 v[14:17], v30 offset:27648
	s_waitcnt lgkmcnt(0)
	v_mfma_f32_16x16x32_bf16 v[14:17], v[14:17], v[6:9], 0
	v_mfma_f32_16x16x32_bf16 v[22:25], v[18:21], v[10:13], v[14:17]
	ds_read_b128 v[18:21], v30 offset:30016
	s_nop 5
	ds_read_b128 v[14:17], v30 offset:29952
	s_waitcnt lgkmcnt(0)
	v_mfma_f32_16x16x32_bf16 v[14:17], v[14:17], v[6:9], 0
	ds_read_b128 v[44:47], v30 offset:32320
	v_mfma_f32_16x16x32_bf16 v[18:21], v[18:21], v[10:13], v[14:17]
	s_nop 5
	ds_read_b128 v[14:17], v30 offset:32256
	s_waitcnt lgkmcnt(0)
	v_mfma_f32_16x16x32_bf16 v[14:17], v[14:17], v[6:9], 0
	v_mfma_f32_16x16x32_bf16 v[14:17], v[44:47], v[10:13], v[14:17]
	ds_read_b128 v[44:47], v30 offset:34560
	s_waitcnt lgkmcnt(0)
	v_mfma_f32_16x16x32_bf16 v[6:9], v[44:47], v[6:9], 0
	ds_read_b128 v[44:47], v30 offset:34624
	s_waitcnt lgkmcnt(0)
	v_mfma_f32_16x16x32_bf16 v[6:9], v[44:47], v[10:13], v[6:9]
	v_max3_f32 v10, v32, s89, v33
	v_max3_f32 v10, v10, v34, v35
	v_max3_f32 v10, v10, v36, v37
	v_max3_f32 v10, v10, v38, v39
	v_max3_f32 v10, v10, v40, v41
	v_max3_f32 v10, v10, v42, v43
	v_max3_f32 v10, v10, v50, v51
	v_max3_f32 v10, v10, v52, v53
	v_max3_f32 v10, v10, v56, v57
	v_max3_f32 v10, v10, v58, v59
	v_max3_f32 v10, v10, v66, v67
	v_max3_f32 v10, v10, v68, v69
	v_max3_f32 v10, v10, v72, v73
	v_max3_f32 v10, v10, v74, v75
	v_max3_f32 v10, v10, v76, v77
	v_max3_f32 v10, v10, v78, v79
	v_max3_f32 v10, v10, v84, v85
	v_max3_f32 v10, v10, v86, v87
	v_max3_f32 v10, v10, v88, v89
	v_max3_f32 v10, v10, v90, v91
	v_max3_f32 v10, v10, v92, v93
	v_max3_f32 v10, v10, v94, v95
	v_max3_f32 v10, v10, v102, v103
	v_max3_f32 v10, v10, v104, v105
	v_max3_f32 v10, v10, v22, v23
	v_max3_f32 v10, v10, v24, v25
	v_max3_f32 v10, v10, v18, v19
	v_max3_f32 v10, v10, v20, v21
	v_max3_f32 v10, v10, v14, v15
	v_max3_f32 v10, v10, v16, v17
	v_max3_f32 v10, v10, v6, v7
	v_max3_f32 v10, v10, v8, v9
	ds_bpermute_b32 v11, v98, v10
	s_waitcnt lgkmcnt(0)
	v_max_f32_e32 v11, v11, v11
	v_max_f32_e32 v10, v10, v11
	ds_bpermute_b32 v11, v99, v10
	s_waitcnt lgkmcnt(0)
	v_max_f32_e32 v11, v11, v11
	v_max_f32_e32 v65, v10, v11
	v_sub_f32_e32 v11, v33, v65
	v_mul_f32_e32 v11, 0x3fb8aa3b, v11
	v_exp_f32_e32 v81, v11
	v_sub_f32_e32 v11, v34, v65
	v_mul_f32_e32 v11, 0x3fb8aa3b, v11
	v_exp_f32_e32 v82, v11
	v_sub_f32_e32 v11, v35, v65
	v_mul_f32_e32 v11, 0x3fb8aa3b, v11
	v_exp_f32_e32 v96, v11
	v_sub_f32_e32 v11, v36, v65
	v_mul_f32_e32 v11, 0x3fb8aa3b, v11
	v_exp_f32_e32 v97, v11
	v_sub_f32_e32 v11, v37, v65
	v_mul_f32_e32 v11, 0x3fb8aa3b, v11
	v_exp_f32_e32 v101, v11
	v_sub_f32_e32 v11, v38, v65
	v_mul_f32_e32 v11, 0x3fb8aa3b, v11
	v_exp_f32_e32 v106, v11
	v_sub_f32_e32 v11, v39, v65
	v_mul_f32_e32 v11, 0x3fb8aa3b, v11
	v_exp_f32_e32 v107, v11
	v_sub_f32_e32 v11, v40, v65
	v_mul_f32_e32 v11, 0x3fb8aa3b, v11
	v_exp_f32_e32 v33, v11
	v_sub_f32_e32 v11, v41, v65
	v_mul_f32_e32 v11, 0x3fb8aa3b, v11
	v_exp_f32_e32 v45, v11
	v_sub_f32_e32 v11, v42, v65
	v_mul_f32_e32 v11, 0x3fb8aa3b, v11
	v_exp_f32_e32 v38, v11
	v_sub_f32_e32 v11, v43, v65
	v_mul_f32_e32 v11, 0x3fb8aa3b, v11
	v_exp_f32_e32 v54, v11
	v_sub_f32_e32 v11, v50, v65
	v_mul_f32_e32 v11, 0x3fb8aa3b, v11
	v_exp_f32_e32 v49, v11
	v_sub_f32_e32 v11, v51, v65
	v_mul_f32_e32 v11, 0x3fb8aa3b, v11
	v_exp_f32_e32 v64, v11
	v_sub_f32_e32 v11, v52, v65
	v_mul_f32_e32 v11, 0x3fb8aa3b, v11
	v_exp_f32_e32 v61, v11
	v_sub_f32_e32 v11, v53, v65
	v_mul_f32_e32 v11, 0x3fb8aa3b, v11
	v_exp_f32_e32 v71, v11
	v_sub_f32_e32 v11, v56, v65
	v_mul_f32_e32 v11, 0x3fb8aa3b, v11
	v_sub_f32_e32 v10, v32, v65
	v_exp_f32_e32 v32, v11
	v_sub_f32_e32 v11, v57, v65
	v_mul_f32_e32 v11, 0x3fb8aa3b, v11
	v_exp_f32_e32 v43, v11
	v_sub_f32_e32 v11, v58, v65
	v_mul_f32_e32 v11, 0x3fb8aa3b, v11
	v_exp_f32_e32 v37, v11
	v_sub_f32_e32 v11, v59, v65
	v_mul_f32_e32 v11, 0x3fb8aa3b, v11
	v_exp_f32_e32 v53, v11
	v_sub_f32_e32 v11, v66, v65
	v_mul_f32_e32 v11, 0x3fb8aa3b, v11
	v_exp_f32_e32 v48, v11
	v_sub_f32_e32 v11, v67, v65
	v_mul_f32_e32 v11, 0x3fb8aa3b, v11
	v_exp_f32_e32 v63, v11
	v_sub_f32_e32 v11, v68, v65
	v_mul_f32_e32 v11, 0x3fb8aa3b, v11
	v_exp_f32_e32 v59, v11
	v_sub_f32_e32 v11, v69, v65
	v_mul_f32_e32 v11, 0x3fb8aa3b, v11
	v_exp_f32_e32 v70, v11
	v_sub_f32_e32 v11, v72, v65
	v_mul_f32_e32 v11, 0x3fb8aa3b, v11
	v_mul_f32_e32 v10, 0x3fb8aa3b, v10
	v_exp_f32_e32 v27, v11
	v_sub_f32_e32 v11, v73, v65
	v_exp_f32_e32 v80, v10
	v_mul_f32_e32 v11, 0x3fb8aa3b, v11
	v_exp_f32_e32 v42, v11
	v_sub_f32_e32 v11, v74, v65
	v_mul_f32_e32 v11, 0x3fb8aa3b, v11
	v_exp_f32_e32 v36, v11
	v_sub_f32_e32 v11, v75, v65
	v_add_f32_e32 v10, 0, v80
	v_mul_f32_e32 v11, 0x3fb8aa3b, v11
	v_add_f32_e32 v10, v81, v10
	v_exp_f32_e32 v52, v11
	v_sub_f32_e32 v11, v76, v65
	v_add_f32_e32 v10, v82, v10
	v_mul_f32_e32 v11, 0x3fb8aa3b, v11
	v_add_f32_e32 v10, v96, v10
	v_exp_f32_e32 v47, v11
	v_sub_f32_e32 v11, v77, v65
	v_add_f32_e32 v10, v97, v10
	v_mul_f32_e32 v11, 0x3fb8aa3b, v11
	v_add_f32_e32 v10, v101, v10
	v_exp_f32_e32 v62, v11
	v_sub_f32_e32 v11, v78, v65
	v_add_f32_e32 v10, v106, v10
	v_mul_f32_e32 v11, 0x3fb8aa3b, v11
	v_add_f32_e32 v10, v107, v10
	v_exp_f32_e32 v57, v11
	v_sub_f32_e32 v11, v79, v65
	v_add_f32_e32 v10, v33, v10
	v_mul_f32_e32 v11, 0x3fb8aa3b, v11
	v_add_f32_e32 v10, v45, v10
	v_exp_f32_e32 v69, v11
	v_sub_f32_e32 v11, v84, v65
	v_add_f32_e32 v10, v38, v10
	v_mul_f32_e32 v11, 0x3fb8aa3b, v11
	v_add_f32_e32 v10, v54, v10
	v_exp_f32_e32 v13, v11
	v_sub_f32_e32 v11, v85, v65
	v_add_f32_e32 v10, v49, v10
	v_mul_f32_e32 v11, 0x3fb8aa3b, v11
	v_add_f32_e32 v10, v64, v10
	v_exp_f32_e32 v41, v11
	v_sub_f32_e32 v11, v86, v65
	v_add_f32_e32 v10, v61, v10
	v_mul_f32_e32 v11, 0x3fb8aa3b, v11
	v_add_f32_e32 v10, v71, v10
	v_exp_f32_e32 v35, v11
	v_sub_f32_e32 v11, v87, v65
	v_add_f32_e32 v10, v32, v10
	v_mul_f32_e32 v11, 0x3fb8aa3b, v11
	v_add_f32_e32 v10, v43, v10
	v_exp_f32_e32 v51, v11
	v_sub_f32_e32 v11, v88, v65
	v_add_f32_e32 v10, v37, v10
	v_mul_f32_e32 v11, 0x3fb8aa3b, v11
	v_add_f32_e32 v10, v53, v10
	v_exp_f32_e32 v46, v11
	v_sub_f32_e32 v11, v89, v65
	v_add_f32_e32 v10, v48, v10
	v_mul_f32_e32 v11, 0x3fb8aa3b, v11
	v_add_f32_e32 v10, v63, v10
	v_exp_f32_e32 v60, v11
	v_sub_f32_e32 v11, v90, v65
	v_add_f32_e32 v10, v59, v10
	v_mul_f32_e32 v11, 0x3fb8aa3b, v11
	v_add_f32_e32 v10, v70, v10
	v_exp_f32_e32 v56, v11
	v_sub_f32_e32 v11, v91, v65
	v_add_f32_e32 v10, v27, v10
	v_mul_f32_e32 v11, 0x3fb8aa3b, v11
	v_add_f32_e32 v10, v42, v10
	v_exp_f32_e32 v68, v11
	v_sub_f32_e32 v11, v92, v65
	v_add_f32_e32 v10, v36, v10
	v_mul_f32_e32 v11, 0x3fb8aa3b, v11
	v_add_f32_e32 v10, v52, v10
	v_exp_f32_e32 v12, v11
	v_sub_f32_e32 v11, v93, v65
	v_add_f32_e32 v10, v47, v10
	v_mul_f32_e32 v11, 0x3fb8aa3b, v11
	v_add_f32_e32 v10, v62, v10
	v_exp_f32_e32 v40, v11
	v_sub_f32_e32 v11, v94, v65
	v_add_f32_e32 v10, v57, v10
	v_mul_f32_e32 v11, 0x3fb8aa3b, v11
	v_add_f32_e32 v10, v69, v10
	v_exp_f32_e32 v34, v11
	v_sub_f32_e32 v11, v95, v65
	v_add_f32_e32 v10, v13, v10
	v_mul_f32_e32 v11, 0x3fb8aa3b, v11
	v_add_f32_e32 v10, v41, v10
	v_exp_f32_e32 v50, v11
	v_sub_f32_e32 v11, v102, v65
	v_add_f32_e32 v10, v35, v10
	v_mul_f32_e32 v11, 0x3fb8aa3b, v11
	v_add_f32_e32 v10, v51, v10
	v_exp_f32_e32 v44, v11
	v_sub_f32_e32 v11, v103, v65
	v_add_f32_e32 v10, v46, v10
	v_mul_f32_e32 v11, 0x3fb8aa3b, v11
	v_add_f32_e32 v10, v60, v10
	v_exp_f32_e32 v58, v11
	v_sub_f32_e32 v11, v104, v65
	v_add_f32_e32 v10, v56, v10
	v_mul_f32_e32 v11, 0x3fb8aa3b, v11
	v_add_f32_e32 v10, v68, v10
	v_exp_f32_e32 v55, v11
	v_sub_f32_e32 v11, v105, v65
	v_add_f32_e32 v10, v12, v10
	v_mul_f32_e32 v11, 0x3fb8aa3b, v11
	v_add_f32_e32 v10, v40, v10
	v_exp_f32_e32 v67, v11
	v_sub_f32_e32 v11, v22, v65
	v_sub_f32_e32 v22, v23, v65
	v_add_f32_e32 v10, v34, v10
	v_mul_f32_e32 v22, 0x3fb8aa3b, v22
	v_add_f32_e32 v10, v50, v10
	v_mul_f32_e32 v11, 0x3fb8aa3b, v11
	v_exp_f32_e32 v39, v22
	v_sub_f32_e32 v22, v24, v65
	v_add_f32_e32 v10, v44, v10
	v_exp_f32_e32 v11, v11
	v_mul_f32_e32 v22, 0x3fb8aa3b, v22
	v_add_f32_e32 v10, v58, v10
	v_exp_f32_e32 v23, v22
	v_sub_f32_e32 v22, v25, v65
	v_sub_f32_e32 v19, v19, v65
	v_add_f32_e32 v10, v55, v10
	v_mul_f32_e32 v22, 0x3fb8aa3b, v22
	v_sub_f32_e32 v18, v18, v65
	v_mul_f32_e32 v19, 0x3fb8aa3b, v19
	v_add_f32_e32 v10, v67, v10
	v_exp_f32_e32 v24, v22
	v_mul_f32_e32 v18, 0x3fb8aa3b, v18
	v_exp_f32_e32 v25, v19
	v_sub_f32_e32 v19, v20, v65
	v_add_f32_e32 v10, v11, v10
	v_exp_f32_e32 v18, v18
	v_mul_f32_e32 v19, 0x3fb8aa3b, v19
	v_add_f32_e32 v10, v39, v10
	v_exp_f32_e32 v20, v19
	v_sub_f32_e32 v19, v21, v65
	v_add_f32_e32 v10, v23, v10
	v_mul_f32_e32 v19, 0x3fb8aa3b, v19
	v_add_f32_e32 v10, v24, v10
	v_exp_f32_e32 v66, v19
	v_add_f32_e32 v10, v18, v10
	v_add_f32_e32 v10, v25, v10
	v_add_f32_e32 v10, v20, v10
	v_add_f32_e32 v19, v66, v10
	v_sub_f32_e32 v10, v14, v65
	v_mul_f32_e32 v10, 0x3fb8aa3b, v10
	v_sub_f32_e32 v15, v15, v65
	v_exp_f32_e32 v10, v10
	v_mul_f32_e32 v15, 0x3fb8aa3b, v15
	v_exp_f32_e32 v15, v15
	v_sub_f32_e32 v17, v17, v65
	v_add_f32_e32 v14, v10, v19
	v_mul_f32_e32 v17, 0x3fb8aa3b, v17
	v_add_f32_e32 v19, v15, v14
	v_sub_f32_e32 v14, v16, v65
	v_mul_f32_e32 v14, 0x3fb8aa3b, v14
	v_exp_f32_e32 v14, v14
	v_exp_f32_e32 v17, v17
	v_sub_f32_e32 v6, v6, v65
	v_mul_f32_e32 v6, 0x3fb8aa3b, v6
	v_add_f32_e32 v16, v14, v19
	v_add_f32_e32 v19, v17, v16
	v_exp_f32_e32 v16, v6
	v_sub_f32_e32 v7, v7, v65
	v_mul_f32_e32 v7, 0x3fb8aa3b, v7
	v_exp_f32_e32 v21, v7
	v_sub_f32_e32 v7, v8, v65
	v_mul_f32_e32 v7, 0x3fb8aa3b, v7
	v_add_f32_e32 v6, v16, v19
	v_exp_f32_e32 v19, v7
	v_sub_f32_e32 v7, v9, v65
	v_mul_f32_e32 v7, 0x3fb8aa3b, v7
	v_exp_f32_e32 v65, v7
	v_add_f32_e32 v6, v21, v6
	v_add_f32_e32 v6, v19, v6
	v_bfe_u32 v8, v96, 16, 1
	v_add_f32_e32 v6, v65, v6
	ds_bpermute_b32 v7, v98, v6
	v_bfe_u32 v9, v81, 16, 1
	v_add3_u32 v72, v81, v9, s91
	v_add3_u32 v73, v96, v8, s91
	v_bfe_u32 v8, v80, 16, 1
	s_waitcnt lgkmcnt(0)
	v_add_f32_e32 v6, v6, v7
	ds_bpermute_b32 v7, v99, v6
	v_bfe_u32 v9, v82, 16, 1
	v_bfe_u32 v74, v97, 16, 1
	v_bfe_u32 v75, v106, 16, 1
	v_add3_u32 v75, v106, v75, s91
	s_waitcnt lgkmcnt(0)
	v_add_f32_e32 v22, v6, v7
	v_bfe_u32 v6, v107, 16, 1
	v_bfe_u32 v7, v101, 16, 1
	v_add3_u32 v74, v97, v74, s91
	v_add3_u32 v9, v82, v9, s91
	v_add3_u32 v8, v80, v8, s91
	v_add3_u32 v7, v101, v7, s91
	v_add3_u32 v6, v107, v6, s91
	v_lshrrev_b32_e32 v76, 16, v8
	v_lshrrev_b32_e32 v77, 16, v9
	v_lshrrev_b32_e32 v8, 16, v74
	v_lshrrev_b32_e32 v9, 16, v75
	v_add_u32_e32 v82, 0x9000, v31
	v_add_u32_e32 v96, 0xb000, v31
	v_add_u32_e32 v97, 0xd000, v31
	v_add_u32_e32 v101, 0xf000, v31
	v_and_or_b32 v9, v6, s33, v9
	v_and_or_b32 v8, v7, s33, v8
	v_and_or_b32 v7, v73, s33, v77
	v_and_or_b32 v6, v72, s33, v76
	ds_read2_b64 v[72:75], v82 offset1:4
	ds_read2_b64 v[76:79], v96 offset0:32 offset1:36
	ds_read2_b64 v[84:87], v97 offset0:64 offset1:68
	ds_read2_b64 v[88:91], v101 offset0:96 offset1:100
	ds_read2_b64 v[92:95], v82 offset0:8 offset1:12
	s_waitcnt lgkmcnt(4)
	v_mfma_f32_16x16x32_bf16 v[72:75], v[72:75], v[6:9], 0
	v_bfe_u32 v80, v71, 16, 1
	v_bfe_u32 v81, v64, 16, 1
	v_add3_u32 v64, v64, v81, s91
	s_waitcnt lgkmcnt(3)
	v_mfma_f32_16x16x32_bf16 v[76:79], v[76:79], v[6:9], 0
	v_add3_u32 v71, v71, v80, s91
	v_bfe_u32 v80, v33, 16, 1
	v_bfe_u32 v81, v38, 16, 1
	s_waitcnt lgkmcnt(2)
	v_mfma_f32_16x16x32_bf16 v[84:87], v[84:87], v[6:9], 0
	v_add3_u32 v38, v38, v81, s91
	v_add3_u32 v33, v33, v80, s91
	v_lshrrev_b32_e32 v33, 16, v33
	s_waitcnt lgkmcnt(1)
	v_mfma_f32_16x16x32_bf16 v[6:9], v[88:91], v[6:9], 0
	v_bfe_u32 v88, v54, 16, 1
	v_bfe_u32 v89, v45, 16, 1
	v_add3_u32 v45, v45, v89, s91
	v_add3_u32 v54, v54, v88, s91
	v_bfe_u32 v88, v49, 16, 1
	v_bfe_u32 v89, v61, 16, 1
	v_add3_u32 v61, v61, v89, s91
	v_add3_u32 v49, v49, v88, s91
	v_lshrrev_b32_e32 v38, 16, v38
	v_lshrrev_b32_e32 v49, 16, v49
	v_lshrrev_b32_e32 v61, 16, v61
	v_and_or_b32 v91, v71, s33, v61
	v_and_or_b32 v90, v64, s33, v49
	v_and_or_b32 v89, v54, s33, v38
	v_and_or_b32 v88, v45, s33, v33
	v_bfe_u32 v45, v53, 16, 1
	v_bfe_u32 v49, v43, 16, 1
	s_waitcnt lgkmcnt(0)
	v_mfma_f32_16x16x32_bf16 v[72:75], v[92:95], v[88:91], v[72:75]
	ds_read2_b64 v[92:95], v96 offset0:40 offset1:44
	v_add3_u32 v43, v43, v49, s91
	v_add3_u32 v45, v53, v45, s91
	s_waitcnt lgkmcnt(0)
	v_mfma_f32_16x16x32_bf16 v[76:79], v[92:95], v[88:91], v[76:79]
	ds_read2_b64 v[92:95], v97 offset0:72 offset1:76
	v_bfe_u32 v49, v32, 16, 1
	v_bfe_u32 v53, v37, 16, 1
	s_waitcnt lgkmcnt(0)
	v_mfma_f32_16x16x32_bf16 v[84:87], v[92:95], v[88:91], v[84:87]
	ds_read2_b64 v[92:95], v101 offset0:104 offset1:108
	v_bfe_u32 v54, v48, 16, 1
	s_waitcnt lgkmcnt(0)
	v_mfma_f32_16x16x32_bf16 v[6:9], v[92:95], v[88:91], v[6:9]
	ds_read2_b64 v[92:95], v82 offset0:16 offset1:20
	v_bfe_u32 v61, v59, 16, 1
	v_bfe_u32 v33, v70, 16, 1
	v_bfe_u32 v38, v63, 16, 1
	v_add3_u32 v59, v59, v61, s91
	v_add3_u32 v48, v48, v54, s91
	v_add3_u32 v37, v37, v53, s91
	v_add3_u32 v32, v32, v49, s91
	v_add3_u32 v38, v63, v38, s91
	v_add3_u32 v33, v70, v33, s91
	v_lshrrev_b32_e32 v32, 16, v32
	v_lshrrev_b32_e32 v37, 16, v37
	v_lshrrev_b32_e32 v48, 16, v48
	v_lshrrev_b32_e32 v49, 16, v59
	v_and_or_b32 v91, v33, s33, v49
	v_and_or_b32 v90, v38, s33, v48
	v_and_or_b32 v89, v45, s33, v37
	v_and_or_b32 v88, v43, s33, v32
	v_bfe_u32 v38, v42, 16, 1
	v_add3_u32 v38, v42, v38, s91
	s_waitcnt lgkmcnt(0)
	v_mfma_f32_16x16x32_bf16 v[70:73], v[92:95], v[88:91], v[72:75]
	ds_read2_b64 v[92:95], v96 offset0:48 offset1:52
	v_bfe_u32 v42, v27, 16, 1
	v_bfe_u32 v43, v36, 16, 1
	s_waitcnt lgkmcnt(0)
	v_mfma_f32_16x16x32_bf16 v[74:77], v[92:95], v[88:91], v[76:79]
	s_nop 2
	ds_read2_b64 v[78:81], v97 offset0:80 offset1:84
	v_bfe_u32 v45, v47, 16, 1
	v_bfe_u32 v48, v57, 16, 1
	s_waitcnt lgkmcnt(0)
	v_mfma_f32_16x16x32_bf16 v[78:81], v[78:81], v[88:91], v[84:87]
	s_nop 2
	ds_read2_b64 v[84:87], v101 offset0:112 offset1:116
	v_bfe_u32 v32, v69, 16, 1
	s_waitcnt lgkmcnt(0)
	v_mfma_f32_16x16x32_bf16 v[6:9], v[84:87], v[88:91], v[6:9]
	ds_read2_b64 v[88:91], v82 offset0:24 offset1:28
	v_bfe_u32 v33, v62, 16, 1
	v_bfe_u32 v37, v52, 16, 1
	v_add3_u32 v48, v57, v48, s91
	v_add3_u32 v45, v47, v45, s91
	v_add3_u32 v36, v36, v43, s91
	v_add3_u32 v27, v27, v42, s91
	v_add3_u32 v37, v52, v37, s91
	v_add3_u32 v33, v62, v33, s91
	v_add3_u32 v32, v69, v32, s91
	v_lshrrev_b32_e32 v27, 16, v27
	v_lshrrev_b32_e32 v36, 16, v36
	v_lshrrev_b32_e32 v42, 16, v45
	v_lshrrev_b32_e32 v43, 16, v48
	v_and_or_b32 v87, v32, s33, v43
	v_and_or_b32 v86, v33, s33, v42
	v_and_or_b32 v85, v37, s33, v36
	v_and_or_b32 v84, v38, s33, v27
	v_bfe_u32 v32, v60, 16, 1
	v_add3_u32 v32, v60, v32, s91
	s_waitcnt lgkmcnt(0)
	v_mfma_f32_16x16x32_bf16 v[70:73], v[88:91], v[84:87], v[70:73]
	ds_read2_b64 v[88:91], v96 offset0:56 offset1:60
	v_bfe_u32 v36, v41, 16, 1
	v_add3_u32 v36, v41, v36, s91
	s_waitcnt lgkmcnt(0)
	v_mfma_f32_16x16x32_bf16 v[74:77], v[88:91], v[84:87], v[74:77]
	ds_read2_b64 v[88:91], v97 offset0:88 offset1:92
	v_bfe_u32 v37, v13, 16, 1
	v_bfe_u32 v38, v35, 16, 1
	s_waitcnt lgkmcnt(0)
	v_mfma_f32_16x16x32_bf16 v[78:81], v[88:91], v[84:87], v[78:81]
	ds_read2_b64 v[88:91], v101 offset0:120 offset1:124
	ds_read2_b64 v[60:63], v82 offset0:32 offset1:36
	v_bfe_u32 v41, v46, 16, 1
	v_bfe_u32 v42, v56, 16, 1
	v_bfe_u32 v27, v68, 16, 1
	v_bfe_u32 v33, v51, 16, 1
	v_add3_u32 v42, v56, v42, s91
	v_add3_u32 v41, v46, v41, s91
	v_add3_u32 v35, v35, v38, s91
	v_add3_u32 v13, v13, v37, s91
	v_add3_u32 v33, v51, v33, s91
	v_add3_u32 v27, v68, v27, s91
	v_lshrrev_b32_e32 v13, 16, v13
	v_lshrrev_b32_e32 v35, 16, v35
	v_lshrrev_b32_e32 v37, 16, v41
	v_lshrrev_b32_e32 v38, 16, v42
	v_and_or_b32 v49, v27, s33, v38
	v_and_or_b32 v48, v32, s33, v37
	v_and_or_b32 v47, v33, s33, v35
	v_and_or_b32 v46, v36, s33, v13
	s_waitcnt lgkmcnt(1)
	v_mfma_f32_16x16x32_bf16 v[6:9], v[88:91], v[84:87], v[6:9]
	v_bfe_u32 v32, v50, 16, 1
	v_bfe_u32 v33, v40, 16, 1
	v_bfe_u32 v37, v44, 16, 1
	s_waitcnt lgkmcnt(0)
	v_mfma_f32_16x16x32_bf16 v[60:63], v[60:63], v[46:49], v[70:73]
	v_bfe_u32 v38, v55, 16, 1
	v_add3_u32 v36, v40, v33, s91
	v_add3_u32 v32, v50, v32, s91
	ds_read2_b64 v[68:71], v96 offset0:64 offset1:68
	s_waitcnt lgkmcnt(0)
	v_mfma_f32_16x16x32_bf16 v[68:71], v[68:71], v[46:49], v[74:77]
	s_nop 2
	ds_read2_b64 v[72:75], v97 offset0:96 offset1:100
	v_add3_u32 v38, v55, v38, s91
	v_add3_u32 v37, v44, v37, s91
	s_waitcnt lgkmcnt(0)
	v_mfma_f32_16x16x32_bf16 v[72:75], v[72:75], v[46:49], v[78:81]
	s_nop 2
	ds_read2_b64 v[76:79], v101 offset0:128 offset1:132
	ds_read2_b64 v[40:43], v82 offset0:40 offset1:44
	s_waitcnt lgkmcnt(1)
	v_mfma_f32_16x16x32_bf16 v[6:9], v[76:79], v[46:49], v[6:9]
	ds_read2_b64 v[44:47], v96 offset0:72 offset1:76
	ds_read2_b64 v[48:51], v97 offset0:104 offset1:108
	ds_read2_b64 v[52:55], v101 offset0:136 offset1:140
	v_bfe_u32 v33, v12, 16, 1
	v_bfe_u32 v35, v34, 16, 1
	v_bfe_u32 v13, v67, 16, 1
	v_bfe_u32 v27, v58, 16, 1
	v_add3_u32 v34, v34, v35, s91
	v_add3_u32 v12, v12, v33, s91
	v_add3_u32 v27, v58, v27, s91
	v_add3_u32 v13, v67, v13, s91
	v_lshrrev_b32_e32 v12, 16, v12
	v_lshrrev_b32_e32 v33, 16, v34
	v_lshrrev_b32_e32 v34, 16, v37
	v_lshrrev_b32_e32 v35, 16, v38
	v_and_or_b32 v35, v13, s33, v35
	v_and_or_b32 v34, v27, s33, v34
	v_and_or_b32 v33, v32, s33, v33
	v_and_or_b32 v32, v36, s33, v12
	v_bfe_u32 v13, v25, 16, 1
	v_bfe_u32 v27, v24, 16, 1
	s_waitcnt lgkmcnt(3)
	v_mfma_f32_16x16x32_bf16 v[40:43], v[40:43], v[32:35], v[60:63]
	v_add3_u32 v24, v24, v27, s91
	v_add3_u32 v13, v25, v13, s91
	v_bfe_u32 v25, v11, 16, 1
	s_waitcnt lgkmcnt(2)
	v_mfma_f32_16x16x32_bf16 v[44:47], v[44:47], v[32:35], v[68:71]
	v_bfe_u32 v27, v23, 16, 1
	v_bfe_u32 v12, v66, 16, 1
	v_add3_u32 v23, v23, v27, s91
	s_waitcnt lgkmcnt(1)
	v_mfma_f32_16x16x32_bf16 v[48:51], v[48:51], v[32:35], v[72:75]
	v_add3_u32 v11, v11, v25, s91
	v_add3_u32 v12, v66, v12, s91
	v_lshrrev_b32_e32 v11, 16, v11
	s_waitcnt lgkmcnt(0)
	v_mfma_f32_16x16x32_bf16 v[6:9], v[52:55], v[32:35], v[6:9]
	v_bfe_u32 v32, v39, 16, 1
	v_add3_u32 v32, v39, v32, s91
	ds_read2_b64 v[36:39], v82 offset0:48 offset1:52
	v_bfe_u32 v33, v18, 16, 1
	v_bfe_u32 v34, v20, 16, 1
	v_add3_u32 v20, v20, v34, s91
	v_add3_u32 v18, v18, v33, s91
	v_lshrrev_b32_e32 v23, 16, v23
	v_lshrrev_b32_e32 v18, 16, v18
	v_lshrrev_b32_e32 v20, 16, v20
	v_and_or_b32 v35, v12, s33, v20
	v_and_or_b32 v34, v13, s33, v18
	v_and_or_b32 v33, v24, s33, v23
	v_and_or_b32 v32, v32, s33, v11
	v_bfe_u32 v12, v21, 16, 1
	v_bfe_u32 v13, v17, 16, 1
	s_waitcnt lgkmcnt(0)
	v_mfma_f32_16x16x32_bf16 v[36:39], v[36:39], v[32:35], v[40:43]
	v_bfe_u32 v18, v15, 16, 1
	v_add3_u32 v15, v15, v18, s91
	v_add3_u32 v13, v17, v13, s91
	ds_read2_b64 v[40:43], v96 offset0:80 offset1:84
	s_waitcnt lgkmcnt(0)
	v_mfma_f32_16x16x32_bf16 v[40:43], v[40:43], v[32:35], v[44:47]
	s_nop 2
	ds_read2_b64 v[44:47], v97 offset0:112 offset1:116
	v_add3_u32 v12, v21, v12, s91
	v_bfe_u32 v17, v10, 16, 1
	s_waitcnt lgkmcnt(0)
	v_mfma_f32_16x16x32_bf16 v[44:47], v[44:47], v[32:35], v[48:51]
	s_nop 2
	ds_read2_b64 v[48:51], v101 offset0:144 offset1:148
	v_bfe_u32 v18, v14, 16, 1
	v_bfe_u32 v20, v16, 16, 1
	v_bfe_u32 v21, v19, 16, 1
	v_bfe_u32 v11, v65, 16, 1
	v_add3_u32 v19, v19, v21, s91
	v_add3_u32 v16, v16, v20, s91
	v_add3_u32 v14, v14, v18, s91
	v_add3_u32 v10, v10, v17, s91
	v_add3_u32 v11, v65, v11, s91
	v_lshrrev_b32_e32 v10, 16, v10
	v_lshrrev_b32_e32 v14, 16, v14
	v_lshrrev_b32_e32 v16, 16, v16
	v_lshrrev_b32_e32 v17, 16, v19
	s_waitcnt lgkmcnt(0)
	v_mfma_f32_16x16x32_bf16 v[6:9], v[48:51], v[32:35], v[6:9]
	v_and_or_b32 v35, v11, s33, v17
	v_and_or_b32 v34, v12, s33, v16
	v_and_or_b32 v33, v13, s33, v14
	v_and_or_b32 v32, v15, s33, v10
	ds_read2_b64 v[10:13], v82 offset0:56 offset1:60
	v_div_scale_f32 v23, s[4:5], v22, v22, 1.0
	s_waitcnt lgkmcnt(0)
	v_mfma_f32_16x16x32_bf16 v[18:21], v[10:13], v[32:35], v[36:39]
	ds_read2_b64 v[10:13], v96 offset0:88 offset1:92
	s_nop 1
	ds_read2_b64 v[36:39], v101 offset0:152 offset1:156
	v_rcp_f32_e32 v27, v23
	s_waitcnt lgkmcnt(1)
	v_mfma_f32_16x16x32_bf16 v[14:17], v[10:13], v[32:35], v[40:43]
	ds_read2_b64 v[10:13], v97 offset0:120 offset1:124
	v_lshlrev_b64 v[24:25], 11, v[28:29]
	v_fma_f32 v28, -v23, v27, 1.0
	v_fmac_f32_e32 v27, v28, v27
	v_div_scale_f32 v28, vcc, 1.0, v22, 1.0
	v_mul_f32_e32 v29, v28, v27
	s_waitcnt lgkmcnt(0)
	v_mfma_f32_16x16x32_bf16 v[10:13], v[10:13], v[32:35], v[44:47]
	v_lshl_add_u64 v[24:25], s[0:1], 0, v[24:25]
	v_lshl_add_u64 v[24:25], v[24:25], 0, s[94:95]
	v_mfma_f32_16x16x32_bf16 v[6:9], v[36:39], v[32:35], v[6:9]
	v_fma_f32 v32, -v23, v29, v28
	v_fmac_f32_e32 v29, v32, v27
	v_fma_f32 v23, -v23, v29, v28
	v_div_fmas_f32 v23, v23, v27, v29
	v_div_fixup_f32 v22, v23, v22, 1.0
	v_mov_b32_e32 v33, v20
	v_mov_b32_e32 v20, v19
	v_mov_b32_e32 v32, v18
	v_pk_mul_f32 v[18:19], v[22:23], v[20:21] op_sel_hi:[0,1]
	v_mov_b32_e32 v27, v1
	v_pk_mul_f32 v[32:33], v[22:23], v[32:33] op_sel_hi:[0,1]
	v_and_b32_sdwa v23, v19, v218 dst_sel:DWORD dst_unused:UNUSED_PAD src0_sel:WORD_1 src1_sel:DWORD
	v_lshl_add_u64 v[24:25], v[24:25], 0, v[26:27]
	v_and_b32_sdwa v20, v33, v218 dst_sel:DWORD dst_unused:UNUSED_PAD src0_sel:WORD_1 src1_sel:DWORD
	v_and_b32_sdwa v27, v18, v218 dst_sel:DWORD dst_unused:UNUSED_PAD src0_sel:WORD_1 src1_sel:DWORD
	v_add3_u32 v19, v19, v23, s91
	v_and_b32_sdwa v21, v32, v218 dst_sel:DWORD dst_unused:UNUSED_PAD src0_sel:WORD_1 src1_sel:DWORD
	v_add3_u32 v20, v33, v20, s91
	v_add3_u32 v18, v18, v27, s91
	v_and_b32_e32 v19, 0xffff0000, v19
	v_add3_u32 v21, v32, v21, s91
	v_and_b32_e32 v18, 0xffff0000, v18
	v_or_b32_sdwa v19, v19, v20 dst_sel:DWORD dst_unused:UNUSED_PAD src0_sel:DWORD src1_sel:WORD_1
	v_add_co_u32_e32 v20, vcc, s8, v24
	v_or_b32_sdwa v18, v18, v21 dst_sel:DWORD dst_unused:UNUSED_PAD src0_sel:DWORD src1_sel:WORD_1
	s_nop 0
	v_addc_co_u32_e32 v21, vcc, 0, v25, vcc
	global_store_dwordx2 v[20:21], v[18:19], off offset:1536
	v_mov_b32_e32 v18, v14
	v_mov_b32_e32 v19, v16
	v_pk_mul_f32 v[18:19], v[22:23], v[18:19] op_sel_hi:[0,1]
	v_mov_b32_e32 v16, v15
	v_pk_mul_f32 v[14:15], v[22:23], v[16:17] op_sel_hi:[0,1]
	v_and_b32_sdwa v16, v19, v218 dst_sel:DWORD dst_unused:UNUSED_PAD src0_sel:WORD_1 src1_sel:DWORD
	v_and_b32_sdwa v17, v18, v218 dst_sel:DWORD dst_unused:UNUSED_PAD src0_sel:WORD_1 src1_sel:DWORD
	v_add3_u32 v17, v18, v17, s91
	v_add3_u32 v16, v19, v16, s91
	v_and_b32_sdwa v18, v15, v218 dst_sel:DWORD dst_unused:UNUSED_PAD src0_sel:WORD_1 src1_sel:DWORD
	v_and_b32_sdwa v19, v14, v218 dst_sel:DWORD dst_unused:UNUSED_PAD src0_sel:WORD_1 src1_sel:DWORD
	v_add3_u32 v15, v15, v18, s91
	v_add3_u32 v14, v14, v19, s91
	v_and_b32_e32 v15, 0xffff0000, v15
	v_and_b32_e32 v14, 0xffff0000, v14
	v_lshl_add_u64 v[28:29], v[24:25], 0, s[16:17]
	v_or_b32_sdwa v15, v15, v16 dst_sel:DWORD dst_unused:UNUSED_PAD src0_sel:DWORD src1_sel:WORD_1
	v_or_b32_sdwa v14, v14, v17 dst_sel:DWORD dst_unused:UNUSED_PAD src0_sel:DWORD src1_sel:WORD_1
	global_store_dwordx2 v[28:29], v[14:15], off offset:32
	v_mov_b32_e32 v14, v10
	v_mov_b32_e32 v15, v12
	v_pk_mul_f32 v[14:15], v[22:23], v[14:15] op_sel_hi:[0,1]
	v_mov_b32_e32 v12, v11
	v_pk_mul_f32 v[10:11], v[22:23], v[12:13] op_sel_hi:[0,1]
	v_and_b32_sdwa v12, v15, v218 dst_sel:DWORD dst_unused:UNUSED_PAD src0_sel:WORD_1 src1_sel:DWORD
	v_and_b32_sdwa v13, v14, v218 dst_sel:DWORD dst_unused:UNUSED_PAD src0_sel:WORD_1 src1_sel:DWORD
	v_add3_u32 v13, v14, v13, s91
	v_add3_u32 v12, v15, v12, s91
	v_and_b32_sdwa v14, v11, v218 dst_sel:DWORD dst_unused:UNUSED_PAD src0_sel:WORD_1 src1_sel:DWORD
	v_and_b32_sdwa v15, v10, v218 dst_sel:DWORD dst_unused:UNUSED_PAD src0_sel:WORD_1 src1_sel:DWORD
	v_add3_u32 v11, v11, v14, s91
	v_add3_u32 v10, v10, v15, s91
	v_and_b32_e32 v11, 0xffff0000, v11
	v_and_b32_e32 v10, 0xffff0000, v10
	v_or_b32_sdwa v11, v11, v12 dst_sel:DWORD dst_unused:UNUSED_PAD src0_sel:DWORD src1_sel:WORD_1
	v_or_b32_sdwa v10, v10, v13 dst_sel:DWORD dst_unused:UNUSED_PAD src0_sel:DWORD src1_sel:WORD_1
	global_store_dwordx2 v[28:29], v[10:11], off offset:64
	v_mov_b32_e32 v10, v6
	v_mov_b32_e32 v11, v8
	v_pk_mul_f32 v[10:11], v[22:23], v[10:11] op_sel_hi:[0,1]
	v_mov_b32_e32 v8, v7
	v_pk_mul_f32 v[6:7], v[22:23], v[8:9] op_sel_hi:[0,1]
	v_and_b32_sdwa v8, v11, v218 dst_sel:DWORD dst_unused:UNUSED_PAD src0_sel:WORD_1 src1_sel:DWORD
	v_and_b32_sdwa v9, v10, v218 dst_sel:DWORD dst_unused:UNUSED_PAD src0_sel:WORD_1 src1_sel:DWORD
	v_add3_u32 v9, v10, v9, s91
	v_add3_u32 v8, v11, v8, s91
	v_and_b32_sdwa v10, v7, v218 dst_sel:DWORD dst_unused:UNUSED_PAD src0_sel:WORD_1 src1_sel:DWORD
	v_and_b32_sdwa v11, v6, v218 dst_sel:DWORD dst_unused:UNUSED_PAD src0_sel:WORD_1 src1_sel:DWORD
	v_add3_u32 v7, v7, v10, s91
	v_add3_u32 v6, v6, v11, s91
	v_and_b32_e32 v7, 0xffff0000, v7
	v_and_b32_e32 v6, 0xffff0000, v6
	v_or_b32_sdwa v7, v7, v8 dst_sel:DWORD dst_unused:UNUSED_PAD src0_sel:DWORD src1_sel:WORD_1
	v_or_b32_sdwa v6, v6, v9 dst_sel:DWORD dst_unused:UNUSED_PAD src0_sel:DWORD src1_sel:WORD_1
	s_movk_i32 s4, 0x80
	s_and_b64 vcc, exec, s[2:3]
	s_mov_b64 s[2:3], 0
	global_store_dwordx2 v[28:29], v[6:7], off offset:96
	s_cbranch_vccnz .LBB0_536
	s_waitcnt lgkmcnt(0)
	s_barrier
	s_branch .LBB0_533
.LBB0_538:
	s_and_b64 vcc, exec, s[0:1]
	s_cbranch_vccz .LBB0_533
	v_readlane_b32 s0, v254, 4
	v_ashrrev_i32_e32 v85, 8, v100
	s_mov_b32 s2, 0x2aaaaaab
	v_mov_b32_e32 v0, s0
	ds_read_b64 v[2:3], v0
	v_lshl_add_u32 v0, s14, 1, v85
	v_bfe_u32 v102, v100, 4, 4
	s_movk_i32 s15, 0x300
	v_lshlrev_b32_e32 v89, 1, v102
	s_waitcnt lgkmcnt(0)
	v_readfirstlane_b32 s0, v2
	v_mul_hi_i32 v2, v0, s2
	v_readfirstlane_b32 s1, v3
	v_lshrrev_b32_e32 v3, 31, v2
	v_ashrrev_i32_e32 v2, 1, v2
	v_add_u32_e32 v5, v2, v3
	v_mul_lo_u32 v2, v5, 12
	v_sub_u32_e32 v0, v0, v2
	v_and_b32_e32 v103, 31, v5
	v_ashrrev_i32_e32 v101, 5, v5
	v_lshlrev_b32_e32 v2, 2, v83
	v_lshl_or_b32 v80, v0, 6, v2
	v_lshlrev_b32_e32 v0, 12, v101
	v_lshlrev_b32_e32 v2, 7, v103
	v_lshlrev_b32_e32 v3, 3, v102
	s_add_u32 s2, s0, 0x16400000
	v_or3_b32 v96, v0, v2, v3
	s_addc_u32 s3, s1, 0
	v_ashrrev_i32_e32 v81, 31, v80
	s_add_u32 s4, s0, 0x19400000
	v_mad_i64_i32 v[2:3], s[8:9], v96, s15, v[80:81]
	s_addc_u32 s5, s1, 0
	v_lshlrev_b64 v[2:3], 2, v[2:3]
	v_lshl_add_u64 v[6:7], s[2:3], 0, v[2:3]
	v_lshl_add_u64 v[2:3], s[4:5], 0, v[2:3]
	v_or_b32_e32 v94, 1, v96
	global_load_dwordx4 v[64:67], v[6:7], off nt
	global_load_dwordx4 v[68:71], v[2:3], off nt
	v_mad_i64_i32 v[2:3], s[8:9], v94, s15, v[80:81]
	v_lshlrev_b64 v[2:3], 2, v[2:3]
	v_lshl_add_u64 v[6:7], s[2:3], 0, v[2:3]
	v_lshl_add_u64 v[2:3], s[4:5], 0, v[2:3]
	v_or_b32_e32 v92, 2, v96
	global_load_dwordx4 v[56:59], v[6:7], off nt
	global_load_dwordx4 v[60:63], v[2:3], off nt
	v_mad_i64_i32 v[2:3], s[8:9], v92, s15, v[80:81]
	v_lshlrev_b64 v[2:3], 2, v[2:3]
	v_lshl_add_u64 v[6:7], s[2:3], 0, v[2:3]
	v_lshl_add_u64 v[2:3], s[4:5], 0, v[2:3]
	v_or_b32_e32 v90, 3, v96
	global_load_dwordx4 v[48:51], v[6:7], off nt
	global_load_dwordx4 v[52:55], v[2:3], off nt
	v_mad_i64_i32 v[2:3], s[8:9], v90, s15, v[80:81]
	v_lshlrev_b64 v[2:3], 2, v[2:3]
	v_lshl_add_u64 v[6:7], s[2:3], 0, v[2:3]
	v_lshl_add_u64 v[2:3], s[4:5], 0, v[2:3]
	v_or_b32_e32 v88, 4, v96
	global_load_dwordx4 v[40:43], v[6:7], off nt
	global_load_dwordx4 v[44:47], v[2:3], off nt
	v_mad_i64_i32 v[2:3], s[8:9], v88, s15, v[80:81]
	v_lshlrev_b64 v[2:3], 2, v[2:3]
	v_lshl_add_u64 v[6:7], s[2:3], 0, v[2:3]
	v_lshl_add_u64 v[2:3], s[4:5], 0, v[2:3]
	v_or_b32_e32 v86, 5, v96
	global_load_dwordx4 v[32:35], v[6:7], off nt
	global_load_dwordx4 v[36:39], v[2:3], off nt
	v_mad_i64_i32 v[2:3], s[8:9], v86, s15, v[80:81]
	v_lshlrev_b64 v[2:3], 2, v[2:3]
	v_lshl_add_u64 v[6:7], s[2:3], 0, v[2:3]
	v_lshl_add_u64 v[2:3], s[4:5], 0, v[2:3]
	v_or_b32_e32 v84, 6, v96
	global_load_dwordx4 v[24:27], v[6:7], off nt
	global_load_dwordx4 v[28:31], v[2:3], off nt
	v_mad_i64_i32 v[2:3], s[8:9], v84, s15, v[80:81]
	v_lshlrev_b64 v[2:3], 2, v[2:3]
	v_lshl_add_u64 v[6:7], s[2:3], 0, v[2:3]
	v_lshl_add_u64 v[2:3], s[4:5], 0, v[2:3]
	v_or_b32_e32 v82, 7, v96
	global_load_dwordx4 v[16:19], v[6:7], off nt
	global_load_dwordx4 v[20:23], v[2:3], off nt
	v_mad_i64_i32 v[2:3], s[8:9], v82, s15, v[80:81]
	v_lshlrev_b64 v[2:3], 2, v[2:3]
	v_lshl_add_u64 v[6:7], s[2:3], 0, v[2:3]
	v_lshl_add_u64 v[2:3], s[4:5], 0, v[2:3]
	global_load_dwordx4 v[8:11], v[6:7], off nt
	global_load_dwordx4 v[12:15], v[2:3], off nt
	s_add_u32 s2, s0, 0x9a00000
	s_addc_u32 s3, s1, 0
	v_mov_b32_e32 v6, v4
	v_mov_b32_e32 v7, v4
	v_mov_b32_e32 v2, v1
	v_mov_b32_e32 v3, v1
	s_add_u32 s4, s0, 0x9b00000
	v_and_b32_e32 v87, 0xffffffe0, v5
	v_mov_b32_e32 v5, v4
	v_mov_b32_e32 v0, v1
	v_mov_b64_e32 v[78:79], v[2:3]
	v_mov_b64_e32 v[74:75], v[6:7]
	s_addc_u32 s5, s1, 0
	v_cmp_lt_u32_e32 vcc, v89, v103
	v_mov_b64_e32 v[76:77], v[0:1]
	v_mov_b64_e32 v[72:73], v[4:5]
	s_and_saveexec_b64 s[8:9], vcc
	s_cbranch_execz .LBB0_541
	v_or_b32_e32 v0, v87, v89
	v_mad_i64_i32 v[2:3], s[16:17], v0, s15, v[80:81]
	v_lshlrev_b64 v[2:3], 2, v[2:3]
	v_lshl_add_u64 v[6:7], s[2:3], 0, v[2:3]
	v_lshl_add_u64 v[2:3], s[4:5], 0, v[2:3]
	global_load_dwordx4 v[72:75], v[6:7], off
	global_load_dwordx4 v[76:79], v[2:3], off
	s_waitcnt vmcnt(0) lgkmcnt(0)
	v_pk_fma_f32 v[78:79], v[74:75], 0, v[78:79] op_sel_hi:[1,0,1]
	v_pk_fma_f32 v[76:77], v[72:73], 0, v[76:77] op_sel_hi:[1,0,1]
.LBB0_541:
	s_or_b64 exec, exec, s[8:9]
	v_or_b32_e32 v0, 1, v89
	v_cmp_lt_u32_e32 vcc, v0, v103
	s_and_saveexec_b64 s[8:9], vcc
	s_cbranch_execz .LBB0_543
	v_or_b32_e32 v0, v0, v87
	v_mad_i64_i32 v[2:3], s[16:17], v0, s15, v[80:81]
	v_lshlrev_b64 v[2:3], 2, v[2:3]
	v_lshl_add_u64 v[6:7], s[2:3], 0, v[2:3]
	v_lshl_add_u64 v[2:3], s[4:5], 0, v[2:3]
	global_load_dwordx4 v[104:107], v[6:7], off
	global_load_dwordx4 v[108:111], v[2:3], off
	s_waitcnt vmcnt(0) lgkmcnt(0)
	v_pk_mul_f32 v[74:75], v[74:75], v[106:107]
	v_pk_fma_f32 v[78:79], v[78:79], v[106:107], v[110:111]
	v_pk_fma_f32 v[76:77], v[76:77], v[104:105], v[108:109]
	v_pk_mul_f32 v[72:73], v[72:73], v[104:105]

.LBB0_547:
	s_or_b64 exec, exec, s[2:3]
	v_lshl_add_u64 v[2:3], v[80:81], 1, s[0:1]
	s_mov_b64 s[0:1], 0xc400000
	v_lshl_add_u64 v[6:7], v[2:3], 0, s[0:1]
	s_mov_b64 s[0:1], 0xa000000
	s_movk_i32 s2, 0xe00
	v_lshl_add_u64 v[2:3], v[2:3], 0, s[0:1]
	v_pk_fma_f32 v[64:65], v[64:65], v[72:73], v[68:69]
	v_mad_i64_i32 v[68:69], s[0:1], v96, s2, v[6:7]
	global_load_dwordx2 v[68:69], v[68:69], off nt
	v_pk_fma_f32 v[66:67], v[66:67], v[74:75], v[70:71]
	v_ashrrev_i32_e32 v97, 31, v96
	v_pk_fma_f32 v[56:57], v[56:57], v[64:65], v[60:61]
	v_mad_i64_i32 v[60:61], s[0:1], v94, s2, v[6:7]
	v_pk_fma_f32 v[58:59], v[58:59], v[66:67], v[62:63]
	v_ashrrev_i32_e32 v95, 31, v94
	v_pk_fma_f32 v[48:49], v[48:49], v[56:57], v[52:53]
	v_mad_i64_i32 v[52:53], s[0:1], v92, s2, v[6:7]
	v_pk_fma_f32 v[50:51], v[50:51], v[58:59], v[54:55]
	v_ashrrev_i32_e32 v93, 31, v92
	v_pk_fma_f32 v[40:41], v[40:41], v[48:49], v[44:45]
	v_mad_i64_i32 v[44:45], s[0:1], v90, s2, v[6:7]
	v_pk_fma_f32 v[42:43], v[42:43], v[50:51], v[46:47]
	v_ashrrev_i32_e32 v91, 31, v90
	v_pk_fma_f32 v[32:33], v[32:33], v[40:41], v[36:37]
	v_mad_i64_i32 v[36:37], s[0:1], v88, s2, v[6:7]
	v_pk_fma_f32 v[34:35], v[34:35], v[42:43], v[38:39]
	v_ashrrev_i32_e32 v89, 31, v88
	v_pk_fma_f32 v[24:25], v[24:25], v[32:33], v[28:29]
	v_mad_i64_i32 v[28:29], s[0:1], v86, s2, v[6:7]
	v_pk_fma_f32 v[26:27], v[26:27], v[34:35], v[30:31]
	v_ashrrev_i32_e32 v87, 31, v86
	v_pk_fma_f32 v[16:17], v[16:17], v[24:25], v[20:21]
	v_mad_i64_i32 v[20:21], s[0:1], v84, s2, v[6:7]
	v_pk_fma_f32 v[18:19], v[18:19], v[26:27], v[22:23]
	v_ashrrev_i32_e32 v85, 31, v84
	v_mad_i64_i32 v[6:7], s[0:1], v82, s2, v[6:7]
	v_pk_fma_f32 v[8:9], v[8:9], v[16:17], v[12:13]
	v_pk_fma_f32 v[10:11], v[10:11], v[18:19], v[14:15]
	v_ashrrev_i32_e32 v83, 31, v82
	v_cmp_eq_u32_e32 vcc, 31, v103
	v_cmp_eq_u32_e64 s[4:5], 15, v102
	s_and_b64 s[2:3], s[4:5], vcc
	s_waitcnt vmcnt(0) lgkmcnt(0)
	v_lshlrev_b32_e32 v71, 16, v69
	v_lshlrev_b32_e32 v70, 16, v68
	v_pk_mul_f32 v[72:73], v[70:71], v[70:71]
	v_and_b32_e32 v69, 0xffff0000, v69
	v_fmamk_f32 v0, v72, 0xbdd2d3e2, v220
	v_mul_f32_e32 v0, v0, v70
	v_exp_f32_e32 v0, v0
	v_and_b32_e32 v68, 0xffff0000, v68
	v_pk_mul_f32 v[74:75], v[68:69], v[68:69]
	v_add_f32_e32 v0, 1.0, v0
	v_rcp_f32_e32 v72, v0
	v_fmamk_f32 v0, v74, 0xbdd2d3e2, v220
	v_mul_f32_e32 v0, v0, v68
	v_exp_f32_e32 v0, v0
	s_nop 0
	v_add_f32_e32 v0, 1.0, v0
	v_rcp_f32_e32 v74, v0
	v_fmamk_f32 v0, v73, 0xbdd2d3e2, v220
	v_mul_f32_e32 v0, v0, v71
	v_exp_f32_e32 v0, v0
	s_nop 0
	v_add_f32_e32 v0, 1.0, v0
	v_rcp_f32_e32 v73, v0
	v_fmamk_f32 v0, v75, 0xbdd2d3e2, v220
	v_mul_f32_e32 v0, v0, v69
	v_exp_f32_e32 v0, v0
	v_pk_mul_f32 v[70:71], v[72:73], v[70:71]
	v_mov_b32_e32 v72, v64
	v_mov_b32_e32 v73, v66
	v_add_f32_e32 v0, 1.0, v0
	v_rcp_f32_e32 v75, v0
	v_pk_mul_f32 v[70:71], v[72:73], v[70:71]
	v_mov_b32_e32 v72, v65
	v_mov_b32_e32 v73, v67
	v_pk_mul_f32 v[68:69], v[74:75], v[68:69]
	v_and_b32_sdwa v0, v71, v218 dst_sel:DWORD dst_unused:UNUSED_PAD src0_sel:WORD_1 src1_sel:DWORD
	v_pk_mul_f32 v[68:69], v[72:73], v[68:69]
	v_and_b32_sdwa v5, v70, v218 dst_sel:DWORD dst_unused:UNUSED_PAD src0_sel:WORD_1 src1_sel:DWORD
	v_add3_u32 v5, v70, v5, s91
	v_add3_u32 v0, v71, v0, s91
	v_and_b32_sdwa v70, v69, v218 dst_sel:DWORD dst_unused:UNUSED_PAD src0_sel:WORD_1 src1_sel:DWORD
	v_and_b32_sdwa v71, v68, v218 dst_sel:DWORD dst_unused:UNUSED_PAD src0_sel:WORD_1 src1_sel:DWORD
	v_add3_u32 v69, v69, v70, s91
	v_add3_u32 v68, v68, v71, s91
	v_and_b32_e32 v69, 0xffff0000, v69
	v_and_b32_e32 v68, 0xffff0000, v68
	v_lshlrev_b64 v[70:71], 11, v[96:97]
	v_or_b32_sdwa v69, v69, v0 dst_sel:DWORD dst_unused:UNUSED_PAD src0_sel:DWORD src1_sel:WORD_1
	v_or_b32_sdwa v68, v68, v5 dst_sel:DWORD dst_unused:UNUSED_PAD src0_sel:DWORD src1_sel:WORD_1
	v_lshl_add_u64 v[70:71], v[2:3], 0, v[70:71]
	global_store_dwordx2 v[70:71], v[68:69], off
	global_load_dwordx2 v[60:61], v[60:61], off nt
	s_waitcnt vmcnt(0) lgkmcnt(0)
	v_lshlrev_b32_e32 v63, 16, v61
	v_lshlrev_b32_e32 v62, 16, v60
	v_pk_mul_f32 v[64:65], v[62:63], v[62:63]
	v_and_b32_e32 v61, 0xffff0000, v61
	v_fmamk_f32 v0, v64, 0xbdd2d3e2, v220
	v_mul_f32_e32 v0, v0, v62
	v_exp_f32_e32 v0, v0
	v_and_b32_e32 v60, 0xffff0000, v60
	v_pk_mul_f32 v[66:67], v[60:61], v[60:61]
	v_add_f32_e32 v0, 1.0, v0
	v_rcp_f32_e32 v64, v0
	v_fmamk_f32 v0, v66, 0xbdd2d3e2, v220
	v_mul_f32_e32 v0, v0, v60
	v_exp_f32_e32 v0, v0
	s_nop 0
	v_add_f32_e32 v0, 1.0, v0
	v_rcp_f32_e32 v66, v0
	v_fmamk_f32 v0, v65, 0xbdd2d3e2, v220
	v_mul_f32_e32 v0, v0, v63
	v_exp_f32_e32 v0, v0
	s_nop 0
	v_add_f32_e32 v0, 1.0, v0
	v_rcp_f32_e32 v65, v0
	v_fmamk_f32 v0, v67, 0xbdd2d3e2, v220
	v_mul_f32_e32 v0, v0, v61
	v_exp_f32_e32 v0, v0
	v_pk_mul_f32 v[62:63], v[64:65], v[62:63]
	v_mov_b32_e32 v64, v56
	v_mov_b32_e32 v65, v58
	v_add_f32_e32 v0, 1.0, v0
	v_rcp_f32_e32 v67, v0
	v_pk_mul_f32 v[62:63], v[64:65], v[62:63]
	v_mov_b32_e32 v64, v57
	v_mov_b32_e32 v65, v59
	v_pk_mul_f32 v[60:61], v[66:67], v[60:61]
	v_and_b32_sdwa v0, v63, v218 dst_sel:DWORD dst_unused:UNUSED_PAD src0_sel:WORD_1 src1_sel:DWORD
	v_pk_mul_f32 v[60:61], v[64:65], v[60:61]
	v_and_b32_sdwa v5, v62, v218 dst_sel:DWORD dst_unused:UNUSED_PAD src0_sel:WORD_1 src1_sel:DWORD
	v_add3_u32 v5, v62, v5, s91
	v_add3_u32 v0, v63, v0, s91
	v_and_b32_sdwa v62, v61, v218 dst_sel:DWORD dst_unused:UNUSED_PAD src0_sel:WORD_1 src1_sel:DWORD
	v_and_b32_sdwa v63, v60, v218 dst_sel:DWORD dst_unused:UNUSED_PAD src0_sel:WORD_1 src1_sel:DWORD
	v_add3_u32 v61, v61, v62, s91
	v_add3_u32 v60, v60, v63, s91
	v_and_b32_e32 v61, 0xffff0000, v61
	v_and_b32_e32 v60, 0xffff0000, v60
	v_lshlrev_b64 v[62:63], 11, v[94:95]
	v_or_b32_sdwa v61, v61, v0 dst_sel:DWORD dst_unused:UNUSED_PAD src0_sel:DWORD src1_sel:WORD_1
	v_or_b32_sdwa v60, v60, v5 dst_sel:DWORD dst_unused:UNUSED_PAD src0_sel:DWORD src1_sel:WORD_1
	v_lshl_add_u64 v[62:63], v[2:3], 0, v[62:63]
	global_store_dwordx2 v[62:63], v[60:61], off
	global_load_dwordx2 v[52:53], v[52:53], off nt
	s_waitcnt vmcnt(0) lgkmcnt(0)
	v_lshlrev_b32_e32 v55, 16, v53
	v_lshlrev_b32_e32 v54, 16, v52
	v_pk_mul_f32 v[56:57], v[54:55], v[54:55]
	v_and_b32_e32 v53, 0xffff0000, v53
	v_fmamk_f32 v0, v56, 0xbdd2d3e2, v220
	v_mul_f32_e32 v0, v0, v54
	v_exp_f32_e32 v0, v0
	v_and_b32_e32 v52, 0xffff0000, v52
	v_pk_mul_f32 v[58:59], v[52:53], v[52:53]
	v_add_f32_e32 v0, 1.0, v0
	v_rcp_f32_e32 v56, v0
	v_fmamk_f32 v0, v58, 0xbdd2d3e2, v220
	v_mul_f32_e32 v0, v0, v52
	v_exp_f32_e32 v0, v0
	s_nop 0
	v_add_f32_e32 v0, 1.0, v0
	v_rcp_f32_e32 v58, v0
	v_fmamk_f32 v0, v57, 0xbdd2d3e2, v220
	v_mul_f32_e32 v0, v0, v55
	v_exp_f32_e32 v0, v0
	s_nop 0
	v_add_f32_e32 v0, 1.0, v0
	v_rcp_f32_e32 v57, v0
	v_fmamk_f32 v0, v59, 0xbdd2d3e2, v220
	v_mul_f32_e32 v0, v0, v53
	v_exp_f32_e32 v0, v0
	v_pk_mul_f32 v[54:55], v[56:57], v[54:55]
	v_mov_b32_e32 v56, v48
	v_mov_b32_e32 v57, v50
	v_add_f32_e32 v0, 1.0, v0
	v_rcp_f32_e32 v59, v0
	v_pk_mul_f32 v[54:55], v[56:57], v[54:55]
	v_mov_b32_e32 v56, v49
	v_mov_b32_e32 v57, v51
	v_pk_mul_f32 v[52:53], v[58:59], v[52:53]
	v_and_b32_sdwa v0, v55, v218 dst_sel:DWORD dst_unused:UNUSED_PAD src0_sel:WORD_1 src1_sel:DWORD
	v_pk_mul_f32 v[52:53], v[56:57], v[52:53]
	v_and_b32_sdwa v5, v54, v218 dst_sel:DWORD dst_unused:UNUSED_PAD src0_sel:WORD_1 src1_sel:DWORD
	v_add3_u32 v5, v54, v5, s91
	v_add3_u32 v0, v55, v0, s91
	v_and_b32_sdwa v54, v53, v218 dst_sel:DWORD dst_unused:UNUSED_PAD src0_sel:WORD_1 src1_sel:DWORD
	v_and_b32_sdwa v55, v52, v218 dst_sel:DWORD dst_unused:UNUSED_PAD src0_sel:WORD_1 src1_sel:DWORD
	v_add3_u32 v53, v53, v54, s91
	v_add3_u32 v52, v52, v55, s91
	v_and_b32_e32 v53, 0xffff0000, v53
	v_and_b32_e32 v52, 0xffff0000, v52
	v_lshlrev_b64 v[54:55], 11, v[92:93]
	v_or_b32_sdwa v53, v53, v0 dst_sel:DWORD dst_unused:UNUSED_PAD src0_sel:DWORD src1_sel:WORD_1
	v_or_b32_sdwa v52, v52, v5 dst_sel:DWORD dst_unused:UNUSED_PAD src0_sel:DWORD src1_sel:WORD_1
	v_lshl_add_u64 v[54:55], v[2:3], 0, v[54:55]
	global_store_dwordx2 v[54:55], v[52:53], off
	global_load_dwordx2 v[44:45], v[44:45], off nt
	s_waitcnt vmcnt(0) lgkmcnt(0)
	v_lshlrev_b32_e32 v47, 16, v45
	v_lshlrev_b32_e32 v46, 16, v44
	v_pk_mul_f32 v[48:49], v[46:47], v[46:47]
	v_and_b32_e32 v45, 0xffff0000, v45
	v_fmamk_f32 v0, v48, 0xbdd2d3e2, v220
	v_mul_f32_e32 v0, v0, v46
	v_exp_f32_e32 v0, v0
	v_and_b32_e32 v44, 0xffff0000, v44
	v_pk_mul_f32 v[50:51], v[44:45], v[44:45]
	v_add_f32_e32 v0, 1.0, v0
	v_rcp_f32_e32 v48, v0
	v_fmamk_f32 v0, v50, 0xbdd2d3e2, v220
	v_mul_f32_e32 v0, v0, v44
	v_exp_f32_e32 v0, v0
	s_nop 0
	v_add_f32_e32 v0, 1.0, v0
	v_rcp_f32_e32 v50, v0
	v_fmamk_f32 v0, v49, 0xbdd2d3e2, v220
	v_mul_f32_e32 v0, v0, v47
	v_exp_f32_e32 v0, v0
	s_nop 0
	v_add_f32_e32 v0, 1.0, v0
	v_rcp_f32_e32 v49, v0
	v_fmamk_f32 v0, v51, 0xbdd2d3e2, v220
	v_mul_f32_e32 v0, v0, v45
	v_exp_f32_e32 v0, v0
	v_pk_mul_f32 v[46:47], v[48:49], v[46:47]
	v_mov_b32_e32 v48, v40
	v_mov_b32_e32 v49, v42
	v_add_f32_e32 v0, 1.0, v0
	v_rcp_f32_e32 v51, v0
	v_pk_mul_f32 v[46:47], v[48:49], v[46:47]
	v_mov_b32_e32 v48, v41
	v_mov_b32_e32 v49, v43
	v_pk_mul_f32 v[44:45], v[50:51], v[44:45]
	v_and_b32_sdwa v0, v47, v218 dst_sel:DWORD dst_unused:UNUSED_PAD src0_sel:WORD_1 src1_sel:DWORD
	v_pk_mul_f32 v[44:45], v[48:49], v[44:45]
	v_and_b32_sdwa v5, v46, v218 dst_sel:DWORD dst_unused:UNUSED_PAD src0_sel:WORD_1 src1_sel:DWORD
	v_add3_u32 v5, v46, v5, s91
	v_add3_u32 v0, v47, v0, s91
	v_and_b32_sdwa v46, v45, v218 dst_sel:DWORD dst_unused:UNUSED_PAD src0_sel:WORD_1 src1_sel:DWORD
	v_and_b32_sdwa v47, v44, v218 dst_sel:DWORD dst_unused:UNUSED_PAD src0_sel:WORD_1 src1_sel:DWORD
	v_add3_u32 v45, v45, v46, s91
	v_add3_u32 v44, v44, v47, s91
	v_and_b32_e32 v45, 0xffff0000, v45
	v_and_b32_e32 v44, 0xffff0000, v44
	v_lshlrev_b64 v[46:47], 11, v[90:91]
	v_or_b32_sdwa v45, v45, v0 dst_sel:DWORD dst_unused:UNUSED_PAD src0_sel:DWORD src1_sel:WORD_1
	v_or_b32_sdwa v44, v44, v5 dst_sel:DWORD dst_unused:UNUSED_PAD src0_sel:DWORD src1_sel:WORD_1
	v_lshl_add_u64 v[46:47], v[2:3], 0, v[46:47]
	global_store_dwordx2 v[46:47], v[44:45], off
	global_load_dwordx2 v[36:37], v[36:37], off nt
	s_waitcnt vmcnt(0) lgkmcnt(0)
	v_lshlrev_b32_e32 v39, 16, v37
	v_lshlrev_b32_e32 v38, 16, v36
	v_pk_mul_f32 v[40:41], v[38:39], v[38:39]
	v_and_b32_e32 v37, 0xffff0000, v37
	v_fmamk_f32 v0, v40, 0xbdd2d3e2, v220
	v_mul_f32_e32 v0, v0, v38
	v_exp_f32_e32 v0, v0
	v_and_b32_e32 v36, 0xffff0000, v36
	v_pk_mul_f32 v[42:43], v[36:37], v[36:37]
	v_add_f32_e32 v0, 1.0, v0
	v_rcp_f32_e32 v40, v0
	v_fmamk_f32 v0, v42, 0xbdd2d3e2, v220
	v_mul_f32_e32 v0, v0, v36
	v_exp_f32_e32 v0, v0
	s_nop 0
	v_add_f32_e32 v0, 1.0, v0
	v_rcp_f32_e32 v42, v0
	v_fmamk_f32 v0, v41, 0xbdd2d3e2, v220
	v_mul_f32_e32 v0, v0, v39
	v_exp_f32_e32 v0, v0
	s_nop 0
	v_add_f32_e32 v0, 1.0, v0
	v_rcp_f32_e32 v41, v0
	v_fmamk_f32 v0, v43, 0xbdd2d3e2, v220
	v_mul_f32_e32 v0, v0, v37
	v_exp_f32_e32 v0, v0
	v_pk_mul_f32 v[38:39], v[40:41], v[38:39]
	v_mov_b32_e32 v40, v32
	v_mov_b32_e32 v41, v34
	v_add_f32_e32 v0, 1.0, v0
	v_rcp_f32_e32 v43, v0
	v_pk_mul_f32 v[38:39], v[40:41], v[38:39]
	v_mov_b32_e32 v40, v33
	v_mov_b32_e32 v41, v35
	v_pk_mul_f32 v[36:37], v[42:43], v[36:37]
	v_and_b32_sdwa v0, v39, v218 dst_sel:DWORD dst_unused:UNUSED_PAD src0_sel:WORD_1 src1_sel:DWORD
	v_pk_mul_f32 v[36:37], v[40:41], v[36:37]
	v_and_b32_sdwa v5, v38, v218 dst_sel:DWORD dst_unused:UNUSED_PAD src0_sel:WORD_1 src1_sel:DWORD
	v_add3_u32 v5, v38, v5, s91
	v_add3_u32 v0, v39, v0, s91
	v_and_b32_sdwa v38, v37, v218 dst_sel:DWORD dst_unused:UNUSED_PAD src0_sel:WORD_1 src1_sel:DWORD
	v_and_b32_sdwa v39, v36, v218 dst_sel:DWORD dst_unused:UNUSED_PAD src0_sel:WORD_1 src1_sel:DWORD
	v_add3_u32 v37, v37, v38, s91
	v_add3_u32 v36, v36, v39, s91
	v_and_b32_e32 v37, 0xffff0000, v37
	v_and_b32_e32 v36, 0xffff0000, v36
	v_lshlrev_b64 v[38:39], 11, v[88:89]
	v_or_b32_sdwa v37, v37, v0 dst_sel:DWORD dst_unused:UNUSED_PAD src0_sel:DWORD src1_sel:WORD_1
	v_or_b32_sdwa v36, v36, v5 dst_sel:DWORD dst_unused:UNUSED_PAD src0_sel:DWORD src1_sel:WORD_1
	v_lshl_add_u64 v[38:39], v[2:3], 0, v[38:39]
	global_store_dwordx2 v[38:39], v[36:37], off
	global_load_dwordx2 v[28:29], v[28:29], off nt
	s_waitcnt vmcnt(0) lgkmcnt(0)
	v_lshlrev_b32_e32 v31, 16, v29
	v_lshlrev_b32_e32 v30, 16, v28
	v_pk_mul_f32 v[32:33], v[30:31], v[30:31]
	v_and_b32_e32 v29, 0xffff0000, v29
	v_fmamk_f32 v0, v32, 0xbdd2d3e2, v220
	v_mul_f32_e32 v0, v0, v30
	v_exp_f32_e32 v0, v0
	v_and_b32_e32 v28, 0xffff0000, v28
	v_pk_mul_f32 v[34:35], v[28:29], v[28:29]
	v_add_f32_e32 v0, 1.0, v0
	v_rcp_f32_e32 v32, v0
	v_fmamk_f32 v0, v34, 0xbdd2d3e2, v220
	v_mul_f32_e32 v0, v0, v28
	v_exp_f32_e32 v0, v0
	s_nop 0
	v_add_f32_e32 v0, 1.0, v0
	v_rcp_f32_e32 v34, v0
	v_fmamk_f32 v0, v33, 0xbdd2d3e2, v220
	v_mul_f32_e32 v0, v0, v31
	v_exp_f32_e32 v0, v0
	s_nop 0
	v_add_f32_e32 v0, 1.0, v0
	v_rcp_f32_e32 v33, v0
	v_fmamk_f32 v0, v35, 0xbdd2d3e2, v220
	v_mul_f32_e32 v0, v0, v29
	v_exp_f32_e32 v0, v0
	v_pk_mul_f32 v[30:31], v[32:33], v[30:31]
	v_mov_b32_e32 v32, v24
	v_mov_b32_e32 v33, v26
	v_add_f32_e32 v0, 1.0, v0
	v_rcp_f32_e32 v35, v0
	v_pk_mul_f32 v[30:31], v[32:33], v[30:31]
	v_mov_b32_e32 v32, v25
	v_mov_b32_e32 v33, v27
	v_pk_mul_f32 v[28:29], v[34:35], v[28:29]
	v_and_b32_sdwa v0, v31, v218 dst_sel:DWORD dst_unused:UNUSED_PAD src0_sel:WORD_1 src1_sel:DWORD
	v_pk_mul_f32 v[28:29], v[32:33], v[28:29]
	v_and_b32_sdwa v5, v30, v218 dst_sel:DWORD dst_unused:UNUSED_PAD src0_sel:WORD_1 src1_sel:DWORD
	v_add3_u32 v5, v30, v5, s91
	v_add3_u32 v0, v31, v0, s91
	v_and_b32_sdwa v30, v29, v218 dst_sel:DWORD dst_unused:UNUSED_PAD src0_sel:WORD_1 src1_sel:DWORD
	v_and_b32_sdwa v31, v28, v218 dst_sel:DWORD dst_unused:UNUSED_PAD src0_sel:WORD_1 src1_sel:DWORD
	v_add3_u32 v29, v29, v30, s91
	v_add3_u32 v28, v28, v31, s91
	v_and_b32_e32 v29, 0xffff0000, v29
	v_and_b32_e32 v28, 0xffff0000, v28
	v_lshlrev_b64 v[30:31], 11, v[86:87]
	v_or_b32_sdwa v29, v29, v0 dst_sel:DWORD dst_unused:UNUSED_PAD src0_sel:DWORD src1_sel:WORD_1
	v_or_b32_sdwa v28, v28, v5 dst_sel:DWORD dst_unused:UNUSED_PAD src0_sel:DWORD src1_sel:WORD_1
	v_lshl_add_u64 v[30:31], v[2:3], 0, v[30:31]
	global_store_dwordx2 v[30:31], v[28:29], off
	global_load_dwordx2 v[20:21], v[20:21], off nt
	s_waitcnt vmcnt(0) lgkmcnt(0)
	v_lshlrev_b32_e32 v23, 16, v21
	v_lshlrev_b32_e32 v22, 16, v20
	v_pk_mul_f32 v[24:25], v[22:23], v[22:23]
	v_and_b32_e32 v21, 0xffff0000, v21
	v_fmamk_f32 v0, v24, 0xbdd2d3e2, v220
	v_mul_f32_e32 v0, v0, v22
	v_exp_f32_e32 v0, v0
	v_and_b32_e32 v20, 0xffff0000, v20
	v_pk_mul_f32 v[26:27], v[20:21], v[20:21]
	v_add_f32_e32 v0, 1.0, v0
	v_rcp_f32_e32 v24, v0
	v_fmamk_f32 v0, v26, 0xbdd2d3e2, v220
	v_mul_f32_e32 v0, v0, v20
	v_exp_f32_e32 v0, v0
	s_nop 0
	v_add_f32_e32 v0, 1.0, v0
	v_rcp_f32_e32 v26, v0
	v_fmamk_f32 v0, v25, 0xbdd2d3e2, v220
	v_mul_f32_e32 v0, v0, v23
	v_exp_f32_e32 v0, v0
	s_nop 0
	v_add_f32_e32 v0, 1.0, v0
	v_rcp_f32_e32 v25, v0
	v_fmamk_f32 v0, v27, 0xbdd2d3e2, v220
	v_mul_f32_e32 v0, v0, v21
	v_exp_f32_e32 v0, v0
	v_pk_mul_f32 v[22:23], v[24:25], v[22:23]
	v_mov_b32_e32 v24, v16
	v_mov_b32_e32 v25, v18
	v_add_f32_e32 v0, 1.0, v0
	v_rcp_f32_e32 v27, v0
	v_pk_mul_f32 v[22:23], v[24:25], v[22:23]
	v_mov_b32_e32 v24, v17
	v_mov_b32_e32 v25, v19
	v_pk_mul_f32 v[20:21], v[26:27], v[20:21]
	v_and_b32_sdwa v0, v23, v218 dst_sel:DWORD dst_unused:UNUSED_PAD src0_sel:WORD_1 src1_sel:DWORD
	v_pk_mul_f32 v[20:21], v[24:25], v[20:21]
	v_and_b32_sdwa v5, v22, v218 dst_sel:DWORD dst_unused:UNUSED_PAD src0_sel:WORD_1 src1_sel:DWORD
	v_add3_u32 v5, v22, v5, s91
	v_add3_u32 v0, v23, v0, s91
	v_and_b32_sdwa v22, v21, v218 dst_sel:DWORD dst_unused:UNUSED_PAD src0_sel:WORD_1 src1_sel:DWORD
	v_and_b32_sdwa v23, v20, v218 dst_sel:DWORD dst_unused:UNUSED_PAD src0_sel:WORD_1 src1_sel:DWORD
	v_add3_u32 v21, v21, v22, s91
	v_add3_u32 v20, v20, v23, s91
	v_and_b32_e32 v21, 0xffff0000, v21
	v_and_b32_e32 v20, 0xffff0000, v20
	v_lshlrev_b64 v[22:23], 11, v[84:85]
	v_or_b32_sdwa v21, v21, v0 dst_sel:DWORD dst_unused:UNUSED_PAD src0_sel:DWORD src1_sel:WORD_1
	v_or_b32_sdwa v20, v20, v5 dst_sel:DWORD dst_unused:UNUSED_PAD src0_sel:DWORD src1_sel:WORD_1
	v_lshl_add_u64 v[22:23], v[2:3], 0, v[22:23]
	global_store_dwordx2 v[22:23], v[20:21], off
	global_load_dwordx2 v[6:7], v[6:7], off nt
	s_waitcnt vmcnt(0) lgkmcnt(0)
	v_lshlrev_b32_e32 v13, 16, v7
	v_lshlrev_b32_e32 v12, 16, v6
	v_pk_mul_f32 v[14:15], v[12:13], v[12:13]
	v_and_b32_e32 v7, 0xffff0000, v7
	v_fmamk_f32 v0, v14, 0xbdd2d3e2, v220
	v_mul_f32_e32 v0, v0, v12
	v_exp_f32_e32 v0, v0
	v_and_b32_e32 v6, 0xffff0000, v6
	v_pk_mul_f32 v[16:17], v[6:7], v[6:7]
	v_add_f32_e32 v0, 1.0, v0
	v_rcp_f32_e32 v14, v0
	v_fmamk_f32 v0, v16, 0xbdd2d3e2, v220
	v_mul_f32_e32 v0, v0, v6
	v_exp_f32_e32 v0, v0
	s_nop 0
	v_add_f32_e32 v0, 1.0, v0
	v_rcp_f32_e32 v16, v0
	v_fmamk_f32 v0, v15, 0xbdd2d3e2, v220
	v_mul_f32_e32 v0, v0, v13
	v_exp_f32_e32 v0, v0
	s_nop 0
	v_add_f32_e32 v0, 1.0, v0
	v_rcp_f32_e32 v15, v0
	v_fmamk_f32 v0, v17, 0xbdd2d3e2, v220
	v_mul_f32_e32 v0, v0, v7
	v_exp_f32_e32 v0, v0
	v_pk_mul_f32 v[12:13], v[14:15], v[12:13]
	v_mov_b32_e32 v14, v8
	v_mov_b32_e32 v15, v10
	v_add_f32_e32 v0, 1.0, v0
	v_rcp_f32_e32 v17, v0
	v_pk_mul_f32 v[12:13], v[14:15], v[12:13]
	v_mov_b32_e32 v14, v9
	v_mov_b32_e32 v15, v11
	v_pk_mul_f32 v[6:7], v[16:17], v[6:7]
	v_and_b32_sdwa v0, v13, v218 dst_sel:DWORD dst_unused:UNUSED_PAD src0_sel:WORD_1 src1_sel:DWORD
	v_pk_mul_f32 v[6:7], v[14:15], v[6:7]
	v_and_b32_sdwa v5, v12, v218 dst_sel:DWORD dst_unused:UNUSED_PAD src0_sel:WORD_1 src1_sel:DWORD
	v_add3_u32 v5, v12, v5, s91
	v_add3_u32 v0, v13, v0, s91
	v_and_b32_sdwa v12, v7, v218 dst_sel:DWORD dst_unused:UNUSED_PAD src0_sel:WORD_1 src1_sel:DWORD
	v_and_b32_sdwa v13, v6, v218 dst_sel:DWORD dst_unused:UNUSED_PAD src0_sel:WORD_1 src1_sel:DWORD
	v_add3_u32 v7, v7, v12, s91
	v_add3_u32 v6, v6, v13, s91
	v_and_b32_e32 v7, 0xffff0000, v7
	v_and_b32_e32 v6, 0xffff0000, v6
	v_lshlrev_b64 v[12:13], 11, v[82:83]
	v_or_b32_sdwa v7, v7, v0 dst_sel:DWORD dst_unused:UNUSED_PAD src0_sel:DWORD src1_sel:WORD_1
	v_or_b32_sdwa v6, v6, v5 dst_sel:DWORD dst_unused:UNUSED_PAD src0_sel:DWORD src1_sel:WORD_1
	v_lshl_add_u64 v[2:3], v[2:3], 0, v[12:13]
	global_store_dwordx2 v[2:3], v[6:7], off
	s_and_saveexec_b64 s[0:1], s[2:3]
	s_cbranch_execz .LBB0_532
	v_readlane_b32 s2, v254, 8
	s_nop 1
	v_mov_b32_e32 v0, s2
	ds_read_b64 v[2:3], v0
	v_add_u32_e32 v0, s12, v101
	s_waitcnt lgkmcnt(0)
	v_readfirstlane_b32 s2, v2
	v_readfirstlane_b32 s3, v3
	s_nop 0
	v_mov_b32_e32 v2, s2
	s_movk_i32 s2, 0xc00
	v_mov_b32_e32 v3, s3
	v_mad_i64_i32 v[2:3], s[2:3], v0, s2, v[2:3]
	v_lshl_add_u64 v[2:3], v[80:81], 2, v[2:3]
	v_add_co_u32_e32 v2, vcc, 0x4080000, v2
	s_nop 1
	v_addc_co_u32_e32 v3, vcc, 0, v3, vcc
	global_store_dwordx4 v[2:3], v[8:11], off
	s_branch .LBB0_532

.LBB0_556:
	global_load_dwordx4 v[14:17], v[20:21], off
	s_bfe_u32 s3, s2, 0x20008
	s_ashr_i32 s9, s2, 10
	s_and_b32 s1, s2, 0xff
	s_waitcnt vmcnt(0) lgkmcnt(0)
	v_lshlrev_b32_e32 v6, 16, v14
	v_and_b32_e32 v7, 0xffff0000, v14
	v_lshlrev_b32_e32 v8, 16, v15
	v_and_b32_e32 v9, 0xffff0000, v15
	v_pk_mul_f32 v[30:31], v[6:7], v[6:7]
	v_pk_mul_f32 v[32:33], v[8:9], v[8:9]
	v_add_f32_e32 v0, v30, v31
	v_lshlrev_b32_e32 v10, 16, v16
	v_and_b32_e32 v11, 0xffff0000, v16
	v_add_f32_e32 v0, v32, v0
	v_pk_mul_f32 v[34:35], v[10:11], v[10:11]
	v_add_f32_e32 v0, v33, v0
	v_lshlrev_b32_e32 v12, 16, v17
	v_and_b32_e32 v13, 0xffff0000, v17
	v_add_f32_e32 v0, v34, v0
	v_pk_mul_f32 v[36:37], v[12:13], v[12:13]
	v_add_f32_e32 v0, v35, v0
	v_add_f32_e32 v0, v36, v0
	v_add_f32_e32 v0, v37, v0
	ds_bpermute_b32 v23, v3, v0
	s_waitcnt lgkmcnt(0)
	v_add_f32_e32 v0, v0, v23
	ds_bpermute_b32 v23, v5, v0
	s_waitcnt lgkmcnt(0)
	v_add_f32_e32 v23, v0, v23
	ds_bpermute_b32 v25, v26, v23
	v_lshlrev_b32_e32 v0, 2, v2
	s_and_saveexec_b64 s[6:7], s[4:5]
	s_xor_b64 s[6:7], exec, s[6:7]
	s_cbranch_execz .LBB0_558
	v_readlane_b32 s14, v254, 8
	s_nop 1
	v_mov_b32_e32 v23, s14
	ds_read_b64 v[30:31], v23
	s_lshl_b32 s14, s9, 2
	s_or_b32 s14, s14, s3
	s_ashr_i32 s15, s14, 31
	s_lshl_b64 s[16:17], s[14:15], 18
	s_waitcnt lgkmcnt(0)
	v_readfirstlane_b32 s18, v30
	v_readfirstlane_b32 s19, v31
	s_add_u32 s15, s18, s16
	s_addc_u32 s17, s19, s17
	s_lshl_b32 s16, s1, 10
	s_add_u32 s16, s15, s16
	s_addc_u32 s17, s17, 0
	v_mov_b32_e32 v23, v1
	v_lshl_add_u64 v[30:31], s[16:17], 0, v[22:23]
	v_lshl_add_u64 v[30:31], v[30:31], 0, v[0:1]
	s_mov_b64 s[16:17], 0x4658000
	s_mov_b32 s15, 0x4658000
	v_lshl_add_u64 v[32:33], v[30:31], 0, s[16:17]
	v_add_co_u32_e32 v30, vcc, s15, v30
	s_lshl_b32 s94, s1, 1
	s_nop 0
	v_addc_co_u32_e32 v31, vcc, 0, v31, vcc
	global_store_dwordx4 v[30:31], v[6:9], off
	global_store_dwordx4 v[32:33], v[10:13], off offset:16
	s_nop 0
	v_lshl_or_b32 v6, s14, 2, v28
	v_ashrrev_i32_e32 v7, 31, v6
	v_lshlrev_b64 v[6:7], 15, v[6:7]
	v_lshl_add_u64 v[6:7], v[18:19], 0, v[6:7]
	v_lshl_add_u64 v[6:7], v[6:7], 0, s[94:95]
	global_store_short v[6:7], v14, off
	global_store_short_d16_hi v[6:7], v14, off offset:512
	global_store_short v[6:7], v15, off offset:1024
	global_store_short_d16_hi v[6:7], v15, off offset:1536
	global_store_short v[6:7], v16, off offset:2048
	global_store_short_d16_hi v[6:7], v16, off offset:2560
	global_store_short v[6:7], v17, off offset:3072
	global_store_short_d16_hi v[6:7], v17, off offset:3584
.LBB0_558:
	s_andn2_saveexec_b64 s[14:15], s[6:7]
	s_cbranch_execz .LBB0_555
	s_waitcnt lgkmcnt(0)
	v_add_f32_e32 v14, v23, v25
	v_fmamk_f32 v14, v14, 0x3c800000, v219
	v_cmp_gt_f32_e32 vcc, s85, v14
	v_mul_f32_e32 v15, 0x4f800000, v14
	s_nop 0
	v_cndmask_b32_e32 v14, v14, v15, vcc
	v_sqrt_f32_e32 v15, v14
	s_nop 0
	v_add_u32_e32 v16, -1, v15
	v_fma_f32 v17, -v16, v15, v14
	v_cmp_ge_f32_e64 s[6:7], 0, v17
	v_add_u32_e32 v17, 1, v15
	s_nop 0
	v_cndmask_b32_e64 v16, v15, v16, s[6:7]
	v_fma_f32 v15, -v17, v15, v14
	v_cmp_lt_f32_e64 s[6:7], 0, v15
	s_nop 1
	v_cndmask_b32_e64 v15, v16, v17, s[6:7]
	v_mul_f32_e32 v16, 0x37800000, v15
	v_cndmask_b32_e32 v15, v15, v16, vcc
	v_cmp_class_f32_e32 vcc, v14, v221
	s_nop 1
	v_cndmask_b32_e32 v14, v15, v14, vcc
	v_div_scale_f32 v15, s[6:7], v14, v14, 1.0
	v_rcp_f32_e32 v16, v15
	v_readlane_b32 s6, v254, 18
	v_fma_f32 v17, -v15, v16, 1.0
	v_fmac_f32_e32 v16, v17, v16
	v_div_scale_f32 v17, vcc, 1.0, v14, 1.0
	v_mul_f32_e32 v23, v17, v16
	v_fma_f32 v25, -v15, v23, v17
	v_fmac_f32_e32 v23, v25, v16
	v_fma_f32 v15, -v15, v23, v17
	v_div_fmas_f32 v15, v15, v16, v23
	v_div_fixup_f32 v30, v15, v14, 1.0
	v_mov_b32_e32 v14, s6
	ds_read_b64 v[14:15], v14
	s_lshl_b32 s6, s9, 6
	s_ashr_i32 s7, s6, 31
	s_lshl_b64 s[6:7], s[6:7], 2
	v_pk_mul_f32 v[6:7], v[30:31], v[6:7] op_sel_hi:[0,1]
	s_waitcnt lgkmcnt(0)
	v_readfirstlane_b32 s16, v14
	v_readfirstlane_b32 s17, v15
	s_add_u32 s6, s16, s6
	s_addc_u32 s7, s17, s7
	s_nop 1
	v_lshl_add_u64 v[102:103], s[6:7], 0, v[0:1]
	global_load_dwordx4 v[104:107], v[102:103], off offset:16
	v_lshl_add_u64 v[32:33], s[6:7], 0, v[0:1]
	global_load_dwordx4 v[14:17], v[32:33], off
	v_pk_mul_f32 v[8:9], v[30:31], v[8:9] op_sel_hi:[0,1]
	v_pk_mul_f32 v[10:11], v[30:31], v[10:11] op_sel_hi:[0,1]
	v_readlane_b32 s6, v254, 8
	v_mov_b32_e32 v25, v1
	v_pk_mul_f32 v[12:13], v[30:31], v[12:13] op_sel_hi:[0,1]
	s_waitcnt vmcnt(0) lgkmcnt(0)
	v_pk_mul_f32 v[6:7], v[6:7], v[14:15]
	v_pk_mul_f32 v[8:9], v[8:9], v[16:17]
	s_waitcnt vmcnt(0)
	s_nop 0
	v_mov_b32_e32 v14, v104
	v_mov_b32_e32 v15, v105
	v_mov_b32_e32 v16, v106
	v_mov_b32_e32 v17, v107
	s_nop 1
	s_waitcnt vmcnt(0) lgkmcnt(0)
	v_pk_mul_f32 v[10:11], v[10:11], v[14:15]
	v_mov_b32_e32 v14, s6
	ds_read_b64 v[14:15], v14
	s_lshl_b32 s6, s9, 2
	s_or_b32 s6, s6, s3
	s_ashr_i32 s7, s6, 31
	s_lshl_b64 s[16:17], s[6:7], 18
	s_waitcnt lgkmcnt(0)
	v_readfirstlane_b32 s18, v14
	v_readfirstlane_b32 s19, v15
	s_add_u32 s3, s18, s16
	s_addc_u32 s7, s19, s17
	s_lshl_b32 s9, s1, 10
	s_add_u32 s16, s3, s9
	s_addc_u32 s17, s7, 0
	v_lshl_add_u64 v[14:15], s[16:17], 0, v[24:25]
	v_lshl_add_u64 v[14:15], v[14:15], 0, v[0:1]
	s_mov_b64 s[16:17], 0x4258000
	s_mov_b32 s3, 0x4258000
	v_pk_mul_f32 v[12:13], v[12:13], v[16:17]
	v_lshl_add_u64 v[16:17], v[14:15], 0, s[16:17]
	v_add_co_u32_e32 v14, vcc, s3, v14
	v_bfe_u32 v0, v11, 16, 1
	s_nop 0
	v_addc_co_u32_e32 v15, vcc, 0, v15, vcc
	global_store_dwordx4 v[14:15], v[6:9], off
	global_store_dwordx4 v[16:17], v[10:13], off offset:16
	v_bfe_u32 v14, v7, 16, 1
	v_bfe_u32 v15, v13, 16, 1
	v_bfe_u32 v16, v9, 16, 1
	v_add3_u32 v16, v9, v16, s91
	v_add3_u32 v9, v13, v15, s91
	v_add3_u32 v7, v7, v14, s91
	v_add3_u32 v0, v11, v0, s91
	v_bfe_u32 v11, v8, 16, 1
	v_bfe_u32 v14, v6, 16, 1
	v_bfe_u32 v15, v10, 16, 1
	v_add3_u32 v10, v10, v15, s91
	v_add3_u32 v6, v6, v14, s91
	v_add3_u32 v8, v8, v11, s91
	v_lshrrev_b32_e32 v11, 16, v8
	v_lshrrev_b32_e32 v6, 16, v6
	v_lshrrev_b32_e32 v8, 16, v10
	v_lshl_or_b32 v10, s6, 2, v27
	v_and_or_b32 v6, v7, s33, v6
	v_and_or_b32 v7, v16, s33, v11
	v_ashrrev_i32_e32 v11, 31, v10
	v_bfe_u32 v13, v12, 16, 1
	v_lshlrev_b64 v[10:11], 15, v[10:11]
	v_add3_u32 v12, v12, v13, s91
	v_lshl_add_u64 v[10:11], s[10:11], 0, v[10:11]
	s_lshl_b32 s94, s1, 7
	v_lshrrev_b32_e32 v12, 16, v12
	v_and_or_b32 v8, v0, s33, v8
	v_lshl_add_u64 v[10:11], v[10:11], 0, s[94:95]
	v_lshlrev_b32_e32 v0, 1, v2
	v_and_or_b32 v9, v9, s33, v12
	v_lshl_add_u64 v[10:11], v[10:11], 0, v[0:1]
	global_store_dwordx4 v[10:11], v[6:9], off
	s_branch .LBB0_555

.LBB0_568:
	s_nop 1
	global_load_dword v102, v[8:9], off
	v_ashrrev_i32_e32 v11, 31, v10
	v_lshl_add_u64 v[14:15], v[10:11], 2, s[2:3]
	global_load_dword v11, v[14:15], off
	v_add_u32_e32 v7, 8, v7
	v_add_u32_e32 v10, 0x200, v10
	s_waitcnt vmcnt(0) lgkmcnt(0)
	v_mul_f32_e32 v14, v11, v11
	ds_bpermute_b32 v14, v5, v14
	s_waitcnt lgkmcnt(0)
	v_fmac_f32_e32 v14, v11, v11
	ds_bpermute_b32 v15, v88, v14
	s_waitcnt lgkmcnt(0)
	v_add_f32_e32 v14, v14, v15
	ds_bpermute_b32 v15, v89, v14
	s_waitcnt lgkmcnt(0)
	v_add_f32_e32 v14, v14, v15
	ds_bpermute_b32 v15, v90, v14
	s_waitcnt lgkmcnt(0)
	v_add_f32_e32 v14, v14, v15
	ds_bpermute_b32 v15, v91, v14
	s_waitcnt lgkmcnt(0)
	v_add_f32_e32 v14, v14, v15
	ds_bpermute_b32 v15, v92, v14
	s_waitcnt lgkmcnt(0)
	v_add_f32_e32 v14, v14, v15
	v_fmamk_f32 v14, v14, 0x3c800000, v219
	v_cmp_gt_f32_e32 vcc, s85, v14
	v_mul_f32_e32 v15, 0x4f800000, v14
	s_nop 0
	v_cndmask_b32_e32 v14, v14, v15, vcc
	v_sqrt_f32_e32 v15, v14
	s_nop 0
	v_add_u32_e32 v16, -1, v15
	v_fma_f32 v17, -v16, v15, v14
	v_cmp_ge_f32_e64 s[6:7], 0, v17
	v_add_u32_e32 v17, 1, v15
	s_nop 0
	v_cndmask_b32_e64 v16, v15, v16, s[6:7]
	v_fma_f32 v15, -v17, v15, v14
	v_cmp_lt_f32_e64 s[6:7], 0, v15
	s_nop 1
	v_cndmask_b32_e64 v15, v16, v17, s[6:7]
	v_mul_f32_e32 v16, 0x37800000, v15
	v_cndmask_b32_e32 v15, v15, v16, vcc
	v_cmp_class_f32_e32 vcc, v14, v221
	s_nop 1
	v_cndmask_b32_e32 v14, v15, v14, vcc
	v_div_scale_f32 v15, s[6:7], v14, v14, 1.0
	v_rcp_f32_e32 v16, v15
	s_nop 0
	v_fma_f32 v17, -v15, v16, 1.0
	v_fmac_f32_e32 v16, v17, v16
	v_div_scale_f32 v17, vcc, 1.0, v14, 1.0
	v_mul_f32_e32 v18, v17, v16
	v_fma_f32 v19, -v15, v18, v17
	v_fmac_f32_e32 v18, v19, v16
	v_fma_f32 v15, -v15, v18, v17
	v_div_fmas_f32 v15, v15, v16, v18
	v_div_fixup_f32 v14, v15, v14, 1.0
	v_mul_f32_e32 v11, v11, v14
	s_waitcnt vmcnt(0)
	s_nop 0
	v_mov_b32_e32 v14, v102
	s_nop 1
	v_cmp_lt_i32_e32 vcc, -5, v7
	s_or_b64 s[20:21], vcc, s[20:21]
	s_waitcnt vmcnt(0) lgkmcnt(0)
	v_mul_f32_e32 v11, v14, v11
	v_mul_f32_e32 v11, 0x3e000000, v11
	ds_write_b32 v13, v11
	v_add_u32_e32 v13, 0x800, v13
	s_andn2_b64 exec, exec, s[20:21]
	s_cbranch_execnz .LBB0_568

.LBB0_585:
	global_load_dwordx4 v[22:25], v[12:13], off nt
	ds_read_b32 v26, v21
	v_add_co_u32_e32 v9, vcc, 1, v9
	v_add_u32_e32 v16, 4, v16
	v_add_u32_e32 v21, 16, v21
	v_lshl_add_u64 v[12:13], v[12:13], 0, s[6:7]
	s_or_b64 s[4:5], vcc, s[4:5]
	s_waitcnt vmcnt(0) lgkmcnt(0)
	v_pk_fma_f32 v[6:7], v[24:25], v[26:27], v[6:7] op_sel_hi:[1,0,1]
	v_pk_fma_f32 v[10:11], v[22:23], v[26:27], v[10:11] op_sel_hi:[1,0,1]
	s_andn2_b64 exec, exec, s[4:5]
	s_cbranch_execnz .LBB0_585
	s_or_b64 exec, exec, s[4:5]

.LBB0_596:
	v_and_b32_e32 v14, 0xffffffc0, v6
	v_and_b32_e32 v3, 0xffffffc0, v7
	v_lshl_add_u32 v14, v14, 2, v0
	ds_read2st64_b32 v[12:13], v10 offset1:8
	v_lshl_add_u32 v3, v3, 2, v0
	ds_read_b32 v14, v14 offset:20672
	ds_read_b32 v15, v3 offset:20672
	v_add_u32_e32 v11, -2, v11
	v_cmp_eq_u32_e32 vcc, 0, v11
	v_add_u32_e32 v10, 0x1000, v10
	s_or_b64 s[6:7], vcc, s[6:7]
	s_waitcnt lgkmcnt(0)
	v_pk_add_f32 v[12:13], v[12:13], v[14:15]
	v_ashrrev_i32_e32 v15, 31, v6
	v_and_b32_sdwa v14, v12, v218 dst_sel:DWORD dst_unused:UNUSED_PAD src0_sel:WORD_1 src1_sel:DWORD
	v_and_b32_sdwa v3, v13, v218 dst_sel:DWORD dst_unused:UNUSED_PAD src0_sel:WORD_1 src1_sel:DWORD
	v_add3_u32 v16, v12, v14, s91
	v_mov_b32_e32 v14, v6
	v_add3_u32 v3, v13, v3, s91
	v_ashrrev_i32_e32 v13, 31, v7
	v_mov_b32_e32 v12, v7
	v_lshl_add_u64 v[14:15], v[14:15], 1, s[4:5]
	v_add_u32_e32 v7, 0x400, v7
	v_add_u32_e32 v6, 0x400, v6
	v_lshl_add_u64 v[12:13], v[12:13], 1, s[4:5]
	global_store_short_d16_hi v[14:15], v16, off
	global_store_short_d16_hi v[12:13], v3, off
	s_andn2_b64 exec, exec, s[6:7]
	s_cbranch_execnz .LBB0_596
	s_or_b64 exec, exec, s[6:7]
	v_cmp_ne_u32_e32 vcc, v8, v9
	v_lshl_add_u32 v6, v9, 9, v2
	s_orn2_b64 s[4:5], vcc, exec

.LBB0_600:
	v_and_b32_e32 v10, 0x3fffffc0, v6
	v_lshl_add_u32 v10, v10, 2, v0
	ds_read_b32 v7, v3
	ds_read_b32 v10, v10 offset:20672
	v_cmp_lt_i32_e32 vcc, s5, v6
	v_add_u32_e32 v3, 0x800, v3
	s_or_b64 s[2:3], vcc, s[2:3]
	s_waitcnt lgkmcnt(0)
	v_add_f32_e32 v7, v7, v10
	v_bfe_u32 v10, v7, 16, 1
	v_add3_u32 v7, v7, v10, s91
	global_store_short_d16_hi v[8:9], v7, off
	v_add_u32_e32 v7, 0x200, v6
	v_lshl_add_u64 v[8:9], v[8:9], 0, s[6:7]
	v_mov_b32_e32 v6, v7
	s_andn2_b64 exec, exec, s[2:3]
	s_cbranch_execnz .LBB0_600

.LBB0_602:
	s_and_b64 vcc, exec, s[0:1]
	s_cbranch_vccz .LBB0_633
	v_readlane_b32 s0, v254, 4
	v_readlane_b32 s1, v254, 19
	v_bfe_u32 v3, v2, 3, 6
	v_mov_b32_e32 v0, s0
	ds_read_b64 v[10:11], v0
	s_add_i32 s0, s28, 0xfffffa00
	s_lshl_b32 s94, s0, 6
	s_add_i32 s0, s0, s24
	v_mov_b32_e32 v0, s1
	s_ashr_i32 s1, s0, 31
	s_waitcnt lgkmcnt(0)
	v_readfirstlane_b32 s15, v10
	s_lshl_b64 s[0:1], s[0:1], 14
	v_readfirstlane_b32 s17, v11
	s_add_u32 s0, s15, s0
	ds_read2_b64 v[6:9], v0 offset1:1
	s_addc_u32 s1, s17, s1
	v_lshlrev_b32_e32 v0, 7, v3
	v_lshl_add_u64 v[10:11], s[0:1], 0, v[0:1]
	v_lshlrev_b32_e32 v0, 4, v2
	v_and_b32_e32 v0, 0x70, v0
	v_lshl_add_u64 v[10:11], v[10:11], 0, v[0:1]
	s_mov_b64 s[0:1], 0x9d00000
	s_nop 1
	v_lshl_add_u64 v[102:103], v[10:11], 0, s[0:1]
	v_add_u32_e32 v104, 0x200, v2
	v_ashrrev_i32_e32 v106, 9, v104
	v_lshlrev_b32_e32 v104, 12, v106
	v_ashrrev_i32_e32 v105, 31, v104
	v_lshl_add_u64 v[102:103], v[104:105], 1, v[102:103]
	global_load_dwordx4 v[108:111], v[102:103], off
	v_ashrrev_i32_e32 v18, 9, v2
	v_lshl_add_u64 v[14:15], v[10:11], 0, s[0:1]
	v_lshlrev_b32_e32 v10, 12, v18
	v_ashrrev_i32_e32 v11, 31, v10
	v_lshl_add_u64 v[10:11], v[10:11], 1, v[14:15]
	global_load_dwordx4 v[10:13], v[10:11], off
	v_add_u32_e32 v16, 0x200, v2
	v_mul_u32_u24_e32 v3, 0x90, v3
	v_ashrrev_i32_e32 v19, 9, v16
	v_readlane_b32 s0, v254, 20
	v_lshlrev_b32_e32 v16, 12, v19
	v_ashrrev_i32_e32 v17, 31, v16
	v_add3_u32 v0, s0, v3, v0
	s_movk_i32 s0, 0x2400
	v_mad_i32_i24 v3, v18, s0, v0
	v_lshl_add_u64 v[14:15], v[16:17], 1, v[14:15]
	s_waitcnt lgkmcnt(0)
	v_readfirstlane_b32 s2, v6
	v_readfirstlane_b32 s3, v7
	v_readfirstlane_b32 s6, v8
	v_readfirstlane_b32 s7, v9
	v_mad_i32_i24 v0, v19, s0, v0
	v_cmp_gt_i32_e32 vcc, 64, v2
	s_waitcnt vmcnt(0)
	ds_write_b128 v3, v[10:13]
	s_waitcnt vmcnt(0)
	s_nop 0
	v_mov_b32_e32 v10, v108
	v_mov_b32_e32 v11, v109
	v_mov_b32_e32 v12, v110
	v_mov_b32_e32 v13, v111
	s_nop 1
	s_waitcnt vmcnt(0) lgkmcnt(0)
	ds_write_b128 v0, v[10:13]
	s_and_saveexec_b64 s[0:1], vcc
	s_cbranch_execz .LBB0_605
	v_readlane_b32 s4, v254, 21
	s_add_i32 s20, s94, s10
	s_nop 0
	v_mov_b32_e32 v0, s4
	ds_read_b128 v[6:9], v0
	s_waitcnt lgkmcnt(0)
	v_readfirstlane_b32 s4, v8
	v_add_u32_e32 v8, s20, v2
	v_readfirstlane_b32 s5, v9
	v_ashrrev_i32_e32 v9, 31, v8
	v_lshlrev_b64 v[8:9], 2, v[8:9]
	v_lshl_add_u64 v[10:11], s[4:5], 0, v[8:9]
	global_load_dword v0, v[10:11], off
	s_mov_b32 s4, 0xbfb8aa3b
	s_waitcnt vmcnt(0) lgkmcnt(0)
	v_mul_f32_e32 v3, 0xbfb8aa3b, v0
	v_fma_f32 v10, v0, s4, -v3
	v_rndne_f32_e32 v11, v3
	v_fmac_f32_e32 v10, 0xb2a5705f, v0
	v_sub_f32_e32 v3, v3, v11
	v_add_f32_e32 v3, v3, v10
	v_exp_f32_e32 v3, v3
	v_cvt_i32_f32_e32 v10, v11
	s_mov_b32 s4, 0x42ce8ed0
	v_cmp_nlt_f32_e32 vcc, s4, v0
	s_mov_b32 s4, 0xc2b17218
	v_ldexp_f32 v3, v3, v10
	v_cndmask_b32_e32 v3, 0, v3, vcc
	v_cmp_ngt_f32_e32 vcc, s4, v0
	s_mov_b32 s4, 0x3f2aaaab
	s_nop 0
	v_cndmask_b32_e32 v0, v228, v3, vcc
	v_add_f32_e32 v3, 1.0, v0
	v_add_f32_e32 v10, -1.0, v3
	v_sub_f32_e32 v11, v10, v3
	v_add_f32_e32 v11, 1.0, v11
	v_sub_f32_e32 v10, v0, v10
	v_add_f32_e32 v12, v10, v11
	v_frexp_mant_f32_e32 v10, v3
	v_cmp_gt_f32_e32 vcc, s4, v10
	v_cvt_f64_f32_e32 v[10:11], v3
	v_frexp_exp_i32_f64_e32 v10, v[10:11]
	v_subbrev_co_u32_e32 v10, vcc, 0, v10, vcc
	v_sub_u32_e32 v11, 0, v10
	v_ldexp_f32 v3, v3, v11
	v_ldexp_f32 v11, v12, v11
	v_add_f32_e32 v12, -1.0, v3
	v_add_f32_e32 v13, 1.0, v12
	v_sub_f32_e32 v13, v3, v13
	v_add_f32_e32 v13, v11, v13
	v_add_f32_e32 v14, v12, v13
	v_sub_f32_e32 v12, v12, v14
	v_add_f32_e32 v12, v13, v12
	v_add_f32_e32 v13, 1.0, v3
	v_add_f32_e32 v15, -1.0, v13
	v_sub_f32_e32 v3, v3, v15
	v_add_f32_e32 v3, v11, v3
	v_add_f32_e32 v11, v13, v3
	v_sub_f32_e32 v13, v13, v11
	v_add_f32_e32 v3, v3, v13
	v_rcp_f32_e32 v13, v11
	v_cvt_f32_i32_e32 v10, v10
	s_mov_b32 s4, 0x3f317218
	v_mul_f32_e32 v15, v14, v13
	v_mul_f32_e32 v16, v11, v15
	v_fma_f32 v17, v15, v11, -v16
	v_fmac_f32_e32 v17, v15, v3
	v_add_f32_e32 v18, v16, v17
	v_sub_f32_e32 v19, v14, v18
	v_sub_f32_e32 v14, v14, v19
	v_sub_f32_e32 v16, v18, v16
	v_sub_f32_e32 v14, v14, v18
	v_add_f32_e32 v12, v12, v14
	v_sub_f32_e32 v14, v16, v17
	v_add_f32_e32 v12, v14, v12
	v_add_f32_e32 v14, v19, v12
	v_mul_f32_e32 v16, v13, v14
	v_mul_f32_e32 v17, v11, v16
	v_fma_f32 v11, v16, v11, -v17
	v_fmac_f32_e32 v11, v16, v3
	v_sub_f32_e32 v3, v19, v14
	v_add_f32_e32 v3, v12, v3
	v_add_f32_e32 v12, v17, v11
	v_sub_f32_e32 v18, v14, v12
	v_sub_f32_e32 v14, v14, v18
	v_sub_f32_e32 v17, v12, v17
	v_sub_f32_e32 v12, v14, v12
	v_add_f32_e32 v3, v3, v12
	v_sub_f32_e32 v11, v17, v11
	v_add_f32_e32 v3, v11, v3
	v_add_f32_e32 v11, v15, v16
	v_add_f32_e32 v3, v18, v3
	v_sub_f32_e32 v12, v11, v15
	v_mul_f32_e32 v3, v13, v3
	v_sub_f32_e32 v12, v16, v12
	v_add_f32_e32 v3, v12, v3
	v_mul_f32_e32 v15, 0x3f317218, v10
	v_add_f32_e32 v12, v11, v3
	v_fma_f32 v16, v10, s4, -v15
	v_mul_f32_e32 v13, v12, v12
	v_fmac_f32_e32 v16, 0xb102e308, v10
	v_sub_f32_e32 v10, v12, v11
	v_fmamk_f32 v14, v13, 0x3e9b6dac, v222
	v_sub_f32_e32 v3, v3, v10
	v_add_f32_e32 v10, v15, v16
	v_fmaak_f32 v14, v13, v14, 0x3f2aaada
	v_sub_f32_e32 v11, v10, v15
	v_ldexp_f32 v15, v12, 1
	v_mul_f32_e32 v12, v12, v13
	v_mul_f32_e32 v12, v12, v14
	v_add_f32_e32 v13, v15, v12
	v_sub_f32_e32 v14, v13, v15
	v_ldexp_f32 v3, v3, 1
	v_sub_f32_e32 v12, v12, v14
	v_add_f32_e32 v3, v3, v12
	v_add_f32_e32 v12, v13, v3
	v_sub_f32_e32 v13, v12, v13
	v_sub_f32_e32 v3, v3, v13
	v_add_f32_e32 v13, v10, v12
	v_sub_f32_e32 v14, v13, v10
	v_sub_f32_e32 v15, v13, v14
	v_sub_f32_e32 v11, v16, v11
	v_sub_f32_e32 v10, v10, v15
	v_sub_f32_e32 v12, v12, v14
	v_add_f32_e32 v10, v12, v10
	v_add_f32_e32 v12, v11, v3
	v_sub_f32_e32 v14, v12, v11
	v_sub_f32_e32 v15, v12, v14
	v_sub_f32_e32 v11, v11, v15
	v_sub_f32_e32 v3, v3, v14
	v_add_f32_e32 v10, v12, v10
	v_add_f32_e32 v3, v3, v11
	v_add_f32_e32 v11, v13, v10
	v_sub_f32_e32 v12, v11, v13
	v_sub_f32_e32 v10, v10, v12
	v_add_f32_e32 v3, v3, v10
	s_mov_b32 s4, 0x7f800000
	v_add_f32_e32 v3, v11, v3
	v_cmp_neq_f32_e32 vcc, s4, v0
	s_mov_b32 s4, 0x33800000
	s_nop 0
	v_cndmask_b32_e32 v3, v228, v3, vcc
	v_cmp_lt_f32_e64 vcc, |v0|, s4
	v_readlane_b32 s4, v254, 22
	s_nop 0
	v_cndmask_b32_e32 v0, v3, v0, vcc
	v_xor_b32_e32 v3, 0x80000000, v0
	v_lshl_add_u32 v0, v2, 2, 0
	v_add_u32_e32 v0, 0x22500, v0
	ds_write_b32 v0, v3
	v_mov_b32_e32 v3, s4
	ds_read_b64 v[10:11], v3
	s_waitcnt lgkmcnt(0)
	v_readfirstlane_b32 s4, v10
	v_readfirstlane_b32 s5, v11
	s_nop 1
	v_lshl_add_u64 v[10:11], s[4:5], 0, v[8:9]
	global_load_dword v3, v[10:11], off
	v_readfirstlane_b32 s4, v6
	v_readfirstlane_b32 s5, v7
	s_nop 1
	v_lshl_add_u64 v[102:103], s[4:5], 0, v[8:9]
	global_load_dword v104, v[102:103], off
	s_waitcnt vmcnt(0) lgkmcnt(0)
	ds_write_b32 v0, v3 offset:256
	v_lshl_add_u64 v[6:7], s[4:5], 0, v[8:9]
	s_waitcnt vmcnt(0)
	s_nop 0
	v_mov_b32_e32 v3, v104
	s_nop 1
	s_waitcnt vmcnt(0) lgkmcnt(0)
	ds_write_b32 v0, v3 offset:512

.LBB0_607:
	s_nop 1
	global_load_dword v106, v[16:17], off
	s_nop 1
	global_load_dword v105, v[14:15], off
	s_nop 1
	global_load_dword v104, v[12:13], off offset:3072
	s_nop 1
	global_load_dword v103, v[12:13], off
	s_nop 1
	global_load_dword v102, v[10:11], off
	v_ashrrev_i32_e32 v24, 6, v19
	s_waitcnt lgkmcnt(0)
	v_readfirstlane_b32 s29, v6
	v_readfirstlane_b32 s30, v7
	v_add_u32_e32 v25, s25, v24
	v_mov_b32_e32 v22, s29
	v_mov_b32_e32 v23, s30
	v_mad_i64_i32 v[22:23], s[30:31], v25, s35, v[22:23]
	v_lshl_add_u64 v[22:23], v[22:23], 0, s[2:3]
	v_lshl_add_u64 v[22:23], v[22:23], 0, v[0:1]
	s_movk_i32 s29, 0x1000
	global_load_dword v26, v[22:23], off
	global_load_dword v28, v[22:23], off offset:3072
	v_add_co_u32_e32 v22, vcc, s29, v22
	s_waitcnt lgkmcnt(0)
	v_readfirstlane_b32 s29, v8
	v_addc_co_u32_e32 v23, vcc, 0, v23, vcc
	global_load_dword v29, v[22:23], off offset:2048
	v_mad_i64_i32 v[22:23], s[30:31], v24, s34, v[20:21]
	global_load_dword v30, v[22:23], off offset:3072
	s_nop 0
	s_waitcnt vmcnt(0)
	s_nop 0
	v_mov_b32_e32 v22, v102
	s_nop 1
	s_waitcnt vmcnt(0)
	s_nop 0
	v_mov_b32_e32 v23, v103
	s_nop 1
	s_waitcnt vmcnt(0) lgkmcnt(0)
	v_fmac_f32_e32 v22, v26, v23
	s_waitcnt vmcnt(0)
	s_nop 0
	v_mov_b32_e32 v23, v104
	s_nop 1
	s_waitcnt vmcnt(0) lgkmcnt(0)
	v_fmac_f32_e32 v22, v28, v23
	s_waitcnt vmcnt(0)
	s_nop 0
	v_mov_b32_e32 v23, v105
	s_nop 1
	s_waitcnt vmcnt(0) lgkmcnt(0)
	v_fmac_f32_e32 v22, v29, v23
	s_waitcnt vmcnt(0)
	s_nop 0
	v_mov_b32_e32 v23, v106
	s_nop 1
	s_waitcnt vmcnt(0) lgkmcnt(0)
	v_fmac_f32_e32 v22, v30, v23
	v_bfe_u32 v23, v22, 16, 1
	ds_write_b32 v3, v22
	v_add3_u32 v26, v22, v23, s91
	v_mad_u64_u32 v[22:23], s[30:31], v24, s88, v[18:19]
	v_readfirstlane_b32 s30, v9
	ds_write_b16_d16_hi v22, v26
	v_mov_b32_e32 v22, s29
	v_mov_b32_e32 v23, s30
	v_mad_i64_i32 v[22:23], s[30:31], v25, s35, v[22:23]
	v_lshl_add_u64 v[22:23], v[22:23], 0, s[2:3]
	v_lshl_add_u64 v[22:23], v[22:23], 0, v[0:1]
	v_add_co_u32_e32 v26, vcc, 0x4b18000, v22
	s_mov_b64 s[30:31], 0x4b18000
	s_nop 0
	v_addc_co_u32_e32 v27, vcc, 0, v23, vcc
	v_lshl_add_u64 v[24:25], v[22:23], 0, s[30:31]
	v_add_co_u32_e32 v22, vcc, 0x4b19000, v22
	global_store_dword v[26:27], v28, off
	global_store_dword v[24:25], v29, off offset:3072
	v_addc_co_u32_e32 v23, vcc, 0, v23, vcc
	global_store_dword v[22:23], v30, off offset:2048
	v_add_u32_e32 v22, 0x200, v19
	v_cmp_lt_i32_e32 vcc, s36, v19
	v_add_u32_e32 v3, 0x800, v3
	s_or_b64 s[6:7], vcc, s[6:7]
	v_mov_b32_e32 v19, v22
	s_andn2_b64 exec, exec, s[6:7]
	s_cbranch_execnz .LBB0_607

.LBB0_610:
	v_ashrrev_i32_e32 v16, 6, v14
	s_waitcnt lgkmcnt(0)
	v_readfirstlane_b32 s6, v6
	v_readfirstlane_b32 s7, v7
	v_add_u32_e32 v15, s25, v16
	v_mov_b32_e32 v18, s6
	v_mov_b32_e32 v19, s7
	v_mad_i64_i32 v[18:19], s[6:7], v15, s29, v[18:19]
	v_lshl_add_u64 v[18:19], v[18:19], 0, s[2:3]
	v_lshl_add_u64 v[18:19], v[18:19], 0, v[0:1]
	global_load_dword v17, v[18:19], off
	v_add_u32_e32 v18, 0x10400, v3
	ds_read_b32 v18, v18
	ds_read_b32 v20, v3
	v_add_u32_e32 v3, 0x800, v3
	s_waitcnt vmcnt(0) lgkmcnt(0)
	v_fmac_f32_e32 v20, v17, v18
	v_mad_i64_i32 v[18:19], s[6:7], v16, s30, v[10:11]
	global_load_dword v18, v[18:19], off
	v_ashrrev_i32_e32 v17, 31, v16
	v_lshlrev_b64 v[16:17], 11, v[16:17]
	v_lshl_add_u64 v[16:17], v[12:13], 0, v[16:17]
	s_brev_b32 s6, 64
	v_add_co_u32_e32 v16, vcc, s6, v16
	v_readfirstlane_b32 s6, v8
	s_nop 0
	v_addc_co_u32_e32 v17, vcc, 0, v17, vcc
	v_readfirstlane_b32 s7, v9
	s_waitcnt vmcnt(0) lgkmcnt(0)
	v_mul_f32_e32 v19, v18, v18
	v_fmamk_f32 v19, v19, 0xbdd2d3e2, v220
	v_mul_f32_e32 v19, v18, v19
	v_exp_f32_e32 v19, v19
	s_nop 0
	v_add_f32_e32 v19, 1.0, v19
	v_rcp_f32_e32 v19, v19
	s_nop 0
	v_mul_f32_e32 v18, v18, v19
	v_mul_f32_e32 v18, v20, v18
	v_bfe_u32 v19, v18, 16, 1
	v_add3_u32 v18, v18, v19, s91
	global_store_short_d16_hi v[16:17], v18, off
	v_mov_b32_e32 v16, s6
	v_mov_b32_e32 v17, s7
	v_mad_i64_i32 v[16:17], s[6:7], v15, s29, v[16:17]
	v_lshl_add_u64 v[16:17], v[16:17], 0, s[2:3]
	v_lshl_add_u64 v[16:17], v[16:17], 0, v[0:1]
	v_add_co_u32_e32 v16, vcc, 0x4a58000, v16
	v_add_u32_e32 v15, 0x200, v14
	s_nop 0
	v_addc_co_u32_e32 v17, vcc, 0, v17, vcc
	v_cmp_lt_i32_e32 vcc, s31, v14
	s_or_b64 s[4:5], vcc, s[4:5]
	v_mov_b32_e32 v14, v15
	global_store_dword v[16:17], v20, off
	s_andn2_b64 exec, exec, s[4:5]
	s_cbranch_execnz .LBB0_610

.LBB0_613:
	v_readlane_b32 s0, v254, 4
	s_mul_hi_i32 s2, s28, 0x2aaaaaab
	s_lshr_b32 s3, s2, 31
	v_mov_b32_e32 v0, s0
	s_ashr_i32 s15, s2, 1
	ds_read_b64 v[10:11], v0
	s_add_i32 s15, s15, s3
	s_mul_i32 s2, s15, 12
	s_sub_i32 s4, s28, s2
	s_lshl_b32 s2, s4, 6
	s_add_i32 s4, s4, s24
	v_readlane_b32 s0, v254, 19
	s_ashr_i32 s5, s4, 31
	s_ashr_i32 s3, s2, 31
	v_mov_b32_e32 v0, s0
	s_waitcnt lgkmcnt(0)
	v_readfirstlane_b32 s0, v10
	s_lshl_b64 s[4:5], s[4:5], 14
	v_readfirstlane_b32 s1, v11
	s_add_u32 s4, s0, s4
	v_bfe_u32 v16, v2, 3, 6
	ds_read2_b64 v[6:9], v0 offset1:1
	s_addc_u32 s5, s1, s5
	v_lshlrev_b32_e32 v0, 7, v16
	v_lshl_add_u64 v[10:11], s[4:5], 0, v[0:1]
	v_lshlrev_b32_e32 v0, 3, v2
	v_and_b32_e32 v3, 56, v0
	v_lshlrev_b32_e32 v62, 1, v3
	v_mov_b32_e32 v63, v1
	v_lshl_add_u64 v[10:11], v[10:11], 0, v[62:63]
	s_mov_b64 s[4:5], 0x9d00000
	s_nop 1
	v_lshl_add_u64 v[102:103], v[10:11], 0, s[4:5]
	v_add_u32_e32 v105, 0x200, v2
	v_ashrrev_i32_e32 v106, 9, v105
	v_lshlrev_b32_e32 v104, 12, v106
	v_ashrrev_i32_e32 v105, 31, v104
	v_lshl_add_u64 v[102:103], v[104:105], 1, v[102:103]
	global_load_dwordx4 v[108:111], v[102:103], off
	v_ashrrev_i32_e32 v0, 9, v2
	v_lshl_add_u64 v[14:15], v[10:11], 0, s[4:5]
	v_lshlrev_b32_e32 v10, 12, v0
	v_ashrrev_i32_e32 v11, 31, v10
	v_lshl_add_u64 v[10:11], v[10:11], 1, v[14:15]
	global_load_dwordx4 v[10:13], v[10:11], off
	v_add_u32_e32 v17, 0x200, v2
	v_mul_u32_u24_e32 v18, 0x90, v16
	v_ashrrev_i32_e32 v19, 9, v17
	v_readlane_b32 s4, v254, 20
	v_lshlrev_b32_e32 v16, 12, v19
	v_ashrrev_i32_e32 v17, 31, v16
	v_add3_u32 v18, s4, v18, v62
	s_movk_i32 s4, 0x2400
	v_mad_i32_i24 v0, v0, s4, v18
	v_lshl_add_u64 v[14:15], v[16:17], 1, v[14:15]
	s_waitcnt lgkmcnt(0)
	v_readfirstlane_b32 s17, v6
	v_readfirstlane_b32 s20, v7
	v_readfirstlane_b32 s21, v8
	v_readfirstlane_b32 s29, v9
	v_cmp_gt_i32_e32 vcc, 64, v2
	s_waitcnt vmcnt(0)
	ds_write_b128 v0, v[10:13]
	s_waitcnt vmcnt(0)
	s_nop 0
	v_mov_b32_e32 v10, v108
	v_mov_b32_e32 v11, v109
	v_mov_b32_e32 v12, v110
	v_mov_b32_e32 v13, v111
	s_nop 1
	v_mad_i32_i24 v0, v19, s4, v18
	s_waitcnt vmcnt(0) lgkmcnt(0)
	ds_write_b128 v0, v[10:13]
	s_and_saveexec_b64 s[4:5], vcc
	s_cbranch_execz .LBB0_615
	v_readlane_b32 s6, v254, 21
	s_add_i32 s30, s2, s10
	s_nop 0
	v_mov_b32_e32 v0, s6
	ds_read_b128 v[6:9], v0
	s_waitcnt lgkmcnt(0)
	v_readfirstlane_b32 s6, v8
	v_add_u32_e32 v8, s30, v2
	v_readfirstlane_b32 s7, v9
	v_ashrrev_i32_e32 v9, 31, v8
	v_lshlrev_b64 v[8:9], 2, v[8:9]
	v_lshl_add_u64 v[10:11], s[6:7], 0, v[8:9]
	global_load_dword v0, v[10:11], off
	s_mov_b32 s6, 0xbfb8aa3b
	s_waitcnt vmcnt(0) lgkmcnt(0)
	v_mul_f32_e32 v10, 0xbfb8aa3b, v0
	v_fma_f32 v11, v0, s6, -v10
	v_rndne_f32_e32 v12, v10
	v_fmac_f32_e32 v11, 0xb2a5705f, v0
	v_sub_f32_e32 v10, v10, v12
	v_add_f32_e32 v10, v10, v11
	v_exp_f32_e32 v10, v10
	v_cvt_i32_f32_e32 v11, v12
	s_mov_b32 s6, 0x42ce8ed0
	v_cmp_nlt_f32_e32 vcc, s6, v0
	s_mov_b32 s6, 0xc2b17218
	v_ldexp_f32 v10, v10, v11
	v_cndmask_b32_e32 v10, 0, v10, vcc
	v_cmp_ngt_f32_e32 vcc, s6, v0
	s_mov_b32 s6, 0x3f2aaaab
	s_nop 0
	v_cndmask_b32_e32 v0, v228, v10, vcc
	v_add_f32_e32 v12, 1.0, v0
	v_add_f32_e32 v10, -1.0, v12
	v_sub_f32_e32 v11, v10, v12
	v_add_f32_e32 v11, 1.0, v11
	v_sub_f32_e32 v10, v0, v10
	v_add_f32_e32 v13, v10, v11
	v_frexp_mant_f32_e32 v10, v12
	v_cmp_gt_f32_e32 vcc, s6, v10
	v_cvt_f64_f32_e32 v[10:11], v12
	v_frexp_exp_i32_f64_e32 v10, v[10:11]
	v_subbrev_co_u32_e32 v10, vcc, 0, v10, vcc
	v_sub_u32_e32 v11, 0, v10
	v_ldexp_f32 v12, v12, v11
	v_ldexp_f32 v11, v13, v11
	v_add_f32_e32 v13, -1.0, v12
	v_add_f32_e32 v14, 1.0, v13
	v_sub_f32_e32 v14, v12, v14
	v_add_f32_e32 v14, v11, v14
	v_add_f32_e32 v15, v13, v14
	v_sub_f32_e32 v13, v13, v15
	v_add_f32_e32 v13, v14, v13
	v_add_f32_e32 v14, 1.0, v12
	v_add_f32_e32 v16, -1.0, v14
	v_sub_f32_e32 v12, v12, v16
	v_add_f32_e32 v11, v11, v12
	v_add_f32_e32 v12, v14, v11
	v_sub_f32_e32 v14, v14, v12
	v_add_f32_e32 v11, v11, v14
	v_rcp_f32_e32 v14, v12
	v_cvt_f32_i32_e32 v10, v10
	s_mov_b32 s6, 0x3f317218
	v_mul_f32_e32 v16, v15, v14
	v_mul_f32_e32 v17, v12, v16
	v_fma_f32 v18, v16, v12, -v17
	v_fmac_f32_e32 v18, v16, v11
	v_add_f32_e32 v19, v17, v18
	v_sub_f32_e32 v20, v15, v19
	v_sub_f32_e32 v15, v15, v20
	v_sub_f32_e32 v17, v19, v17
	v_sub_f32_e32 v15, v15, v19
	v_add_f32_e32 v13, v13, v15
	v_sub_f32_e32 v15, v17, v18
	v_add_f32_e32 v13, v15, v13
	v_add_f32_e32 v15, v20, v13
	v_mul_f32_e32 v17, v14, v15
	v_mul_f32_e32 v18, v12, v17
	v_fma_f32 v12, v17, v12, -v18
	v_fmac_f32_e32 v12, v17, v11
	v_sub_f32_e32 v11, v20, v15
	v_add_f32_e32 v11, v13, v11
	v_add_f32_e32 v13, v18, v12
	v_sub_f32_e32 v19, v15, v13
	v_sub_f32_e32 v15, v15, v19
	v_sub_f32_e32 v18, v13, v18
	v_sub_f32_e32 v13, v15, v13
	v_add_f32_e32 v11, v11, v13
	v_sub_f32_e32 v12, v18, v12
	v_add_f32_e32 v11, v12, v11
	v_add_f32_e32 v12, v16, v17
	v_add_f32_e32 v11, v19, v11
	v_sub_f32_e32 v13, v12, v16
	v_mul_f32_e32 v11, v14, v11
	v_sub_f32_e32 v13, v17, v13
	v_add_f32_e32 v11, v13, v11
	v_mul_f32_e32 v16, 0x3f317218, v10
	v_add_f32_e32 v13, v12, v11
	v_fma_f32 v17, v10, s6, -v16
	v_mul_f32_e32 v14, v13, v13
	v_fmac_f32_e32 v17, 0xb102e308, v10
	v_sub_f32_e32 v10, v13, v12
	v_fmamk_f32 v15, v14, 0x3e9b6dac, v222
	v_sub_f32_e32 v10, v11, v10
	v_add_f32_e32 v11, v16, v17
	v_fmaak_f32 v15, v14, v15, 0x3f2aaada
	v_sub_f32_e32 v12, v11, v16
	v_ldexp_f32 v16, v13, 1
	v_mul_f32_e32 v13, v13, v14
	v_mul_f32_e32 v13, v13, v15
	v_add_f32_e32 v14, v16, v13
	v_sub_f32_e32 v15, v14, v16
	v_ldexp_f32 v10, v10, 1
	v_sub_f32_e32 v13, v13, v15
	v_add_f32_e32 v10, v10, v13
	v_add_f32_e32 v13, v14, v10
	v_sub_f32_e32 v14, v13, v14
	v_sub_f32_e32 v10, v10, v14
	v_add_f32_e32 v14, v11, v13
	v_sub_f32_e32 v15, v14, v11
	v_sub_f32_e32 v16, v14, v15
	v_sub_f32_e32 v12, v17, v12
	v_sub_f32_e32 v11, v11, v16
	v_sub_f32_e32 v13, v13, v15
	v_add_f32_e32 v11, v13, v11
	v_add_f32_e32 v13, v12, v10
	v_sub_f32_e32 v15, v13, v12
	v_sub_f32_e32 v16, v13, v15
	v_sub_f32_e32 v12, v12, v16
	v_sub_f32_e32 v10, v10, v15
	v_add_f32_e32 v11, v13, v11
	v_add_f32_e32 v10, v10, v12
	v_add_f32_e32 v12, v14, v11
	v_sub_f32_e32 v13, v12, v14
	v_sub_f32_e32 v11, v11, v13
	v_add_f32_e32 v10, v10, v11
	s_mov_b32 s6, 0x7f800000
	v_add_f32_e32 v10, v12, v10
	v_cmp_neq_f32_e32 vcc, s6, v0
	s_mov_b32 s6, 0x33800000
	s_nop 0
	v_cndmask_b32_e32 v10, v228, v10, vcc
	v_cmp_lt_f32_e64 vcc, |v0|, s6
	v_readlane_b32 s6, v254, 22
	s_nop 0
	v_cndmask_b32_e32 v0, v10, v0, vcc
	v_xor_b32_e32 v10, 0x80000000, v0
	v_lshl_add_u32 v0, v2, 2, 0
	v_add_u32_e32 v0, 0x22500, v0
	ds_write_b32 v0, v10
	v_mov_b32_e32 v10, s6
	ds_read_b64 v[10:11], v10
	s_waitcnt lgkmcnt(0)
	v_readfirstlane_b32 s6, v10
	v_readfirstlane_b32 s7, v11
	s_nop 1
	v_lshl_add_u64 v[10:11], s[6:7], 0, v[8:9]
	global_load_dword v10, v[10:11], off
	v_readfirstlane_b32 s6, v6
	v_readfirstlane_b32 s7, v7
	s_nop 1
	v_lshl_add_u64 v[102:103], s[6:7], 0, v[8:9]
	global_load_dword v104, v[102:103], off
	s_waitcnt vmcnt(0) lgkmcnt(0)
	ds_write_b32 v0, v10 offset:256
	v_lshl_add_u64 v[6:7], s[6:7], 0, v[8:9]
	s_waitcnt vmcnt(0)
	s_nop 0
	v_mov_b32_e32 v6, v104
	s_nop 1
	s_waitcnt vmcnt(0) lgkmcnt(0)
	ds_write_b32 v0, v6 offset:512
.LBB0_615:
	s_or_b64 exec, exec, s[4:5]
	s_ashr_i32 s31, s15, 5
	s_and_b32 s34, s15, 31
	s_lshl_b32 s30, s31, 12
	s_add_u32 s6, s0, 0xc400000
	s_addc_u32 s7, s1, 0
	s_lshl_b64 s[4:5], s[10:11], 2
	s_add_u32 s35, s21, s4
	s_addc_u32 s37, s29, s5
	s_lshl_b32 s29, s34, 7
	s_add_u32 s17, s17, s23
	s_addc_u32 s21, s20, s22
	s_lshl_b64 s[4:5], s[2:3], 2
	s_add_u32 s20, s17, s4
	s_addc_u32 s21, s21, s5
	v_lshlrev_b32_e32 v0, 2, v3
	v_lshl_add_u64 v[30:31], s[20:21], 0, v[0:1]
	v_add_co_u32_e32 v22, vcc, 0x1000, v30
	s_add_u32 s36, s35, s4
	s_nop 0
	v_addc_co_u32_e32 v23, vcc, 0, v31, vcc
	s_addc_u32 s37, s37, s5
	global_load_dwordx4 v[14:17], v[30:31], off
	global_load_dwordx4 v[6:9], v[30:31], off offset:16
	global_load_dwordx4 v[18:21], v[30:31], off offset:3072
	global_load_dwordx4 v[10:13], v[30:31], off offset:3088
	v_add_co_u32_e32 v30, vcc, 0x2000, v30
	v_lshl_add_u64 v[34:35], s[36:37], 0, v[0:1]
	s_nop 0
	v_addc_co_u32_e32 v31, vcc, 0, v31, vcc
	global_load_dwordx4 v[26:29], v[22:23], off offset:2048
	s_nop 0
	global_load_dwordx4 v[22:25], v[22:23], off offset:2064
	s_nop 0
	global_load_dwordx4 v[38:41], v[30:31], off offset:1024
	s_nop 0
	global_load_dwordx4 v[30:33], v[30:31], off offset:1040
	s_nop 0
	global_load_dwordx4 v[42:45], v[34:35], off
	s_nop 0
	global_load_dwordx4 v[34:37], v[34:35], off offset:16
	v_ashrrev_i32_e32 v94, 3, v2
	v_lshlrev_b32_e32 v93, 1, v94
	v_add3_u32 v95, s29, -3, v93
	v_cmp_lt_i32_e32 vcc, -1, v95
	v_mov_b32_e32 v64, 0
	v_mov_b32_e32 v78, 0
	v_mov_b32_e32 v79, 0
	v_mov_b32_e32 v74, 0
	v_mov_b32_e32 v75, 0
	v_mov_b32_e32 v76, 0
	v_mov_b32_e32 v77, 0
	v_mov_b32_e32 v72, 0
	v_mov_b32_e32 v73, 0
	s_and_saveexec_b64 s[20:21], vcc
	s_cbranch_execz .LBB0_617
	v_add_u32_e32 v48, s30, v95
	v_mov_b64_e32 v[46:47], s[6:7]
	s_movk_i32 s17, 0xe00
	v_mad_i64_i32 v[46:47], s[36:37], v48, s17, v[46:47]
	v_lshl_add_u64 v[46:47], s[2:3], 1, v[46:47]
	v_mov_b32_e32 v63, v1
	v_lshl_add_u64 v[46:47], v[46:47], 0, v[62:63]
	global_load_dwordx4 v[46:49], v[46:47], off offset:1536
	s_waitcnt vmcnt(0) lgkmcnt(0)
	v_lshlrev_b32_e32 v78, 16, v46
	v_and_b32_e32 v79, 0xffff0000, v46
	v_lshlrev_b32_e32 v74, 16, v47
	v_and_b32_e32 v75, 0xffff0000, v47
	v_lshlrev_b32_e32 v76, 16, v48
	v_and_b32_e32 v77, 0xffff0000, v48
	v_lshlrev_b32_e32 v72, 16, v49
	v_and_b32_e32 v73, 0xffff0000, v49
.LBB0_617:
	s_or_b64 exec, exec, s[20:21]
	v_cmp_lt_i32_e32 vcc, -2, v95
	v_mov_b32_e32 v65, 0
	v_mov_b32_e32 v66, 0
	v_mov_b32_e32 v67, 0
	v_mov_b32_e32 v68, 0
	v_mov_b32_e32 v69, 0
	v_mov_b32_e32 v70, 0
	v_mov_b32_e32 v71, 0
	s_and_saveexec_b64 s[20:21], vcc
	s_cbranch_execz .LBB0_619
	v_add3_u32 v48, v95, s30, 1
	v_mov_b64_e32 v[46:47], s[6:7]
	s_movk_i32 s17, 0xe00
	v_mad_i64_i32 v[46:47], s[36:37], v48, s17, v[46:47]
	v_lshl_add_u64 v[46:47], s[2:3], 1, v[46:47]
	v_mov_b32_e32 v63, v1
	v_lshl_add_u64 v[46:47], v[46:47], 0, v[62:63]
	global_load_dwordx4 v[46:49], v[46:47], off offset:1536
	s_waitcnt vmcnt(0) lgkmcnt(0)
	v_lshlrev_b32_e32 v64, 16, v46
	v_and_b32_e32 v65, 0xffff0000, v46
	v_lshlrev_b32_e32 v66, 16, v47
	v_and_b32_e32 v67, 0xffff0000, v47
	v_lshlrev_b32_e32 v68, 16, v48
	v_and_b32_e32 v69, 0xffff0000, v48
	v_lshlrev_b32_e32 v70, 16, v49
	v_and_b32_e32 v71, 0xffff0000, v49
.LBB0_619:
	s_or_b64 exec, exec, s[20:21]
	v_cmp_lt_i32_e32 vcc, -3, v95
	v_mov_b32_e32 v46, 0
	v_mov_b32_e32 v80, 0
	v_mov_b32_e32 v81, 0
	v_mov_b32_e32 v82, 0
	v_mov_b32_e32 v83, 0
	v_mov_b32_e32 v84, 0
	v_mov_b32_e32 v85, 0
	v_mov_b32_e32 v86, 0
	v_mov_b32_e32 v87, 0
	s_and_saveexec_b64 s[20:21], vcc
	s_cbranch_execz .LBB0_621
	v_add3_u32 v47, v95, s30, 2
	v_mov_b64_e32 v[48:49], s[6:7]
	s_movk_i32 s17, 0xe00
	v_mad_i64_i32 v[48:49], s[36:37], v47, s17, v[48:49]
	v_lshl_add_u64 v[48:49], s[2:3], 1, v[48:49]
	v_mov_b32_e32 v63, v1
	v_lshl_add_u64 v[48:49], v[48:49], 0, v[62:63]
	global_load_dwordx4 v[48:51], v[48:49], off offset:1536
	s_waitcnt vmcnt(0) lgkmcnt(0)
	v_lshlrev_b32_e32 v80, 16, v48
	v_and_b32_e32 v81, 0xffff0000, v48
	v_lshlrev_b32_e32 v82, 16, v49
	v_and_b32_e32 v83, 0xffff0000, v49
	v_lshlrev_b32_e32 v84, 16, v50
	v_and_b32_e32 v85, 0xffff0000, v50
	v_lshlrev_b32_e32 v86, 16, v51
	v_and_b32_e32 v87, 0xffff0000, v51
.LBB0_621:
	s_or_b64 exec, exec, s[20:21]
	v_add_u32_e32 v54, s29, v93
	v_cmp_lt_i32_e32 vcc, -1, v54
	v_mov_b32_e32 v47, 0
	v_mov_b32_e32 v48, 0
	v_mov_b32_e32 v49, 0
	v_mov_b32_e32 v50, 0
	v_mov_b32_e32 v51, 0
	v_mov_b32_e32 v52, 0
	v_mov_b32_e32 v53, 0
	s_and_saveexec_b64 s[20:21], vcc
	s_cbranch_execz .LBB0_623
	v_add_u32_e32 v48, s30, v54
	v_mov_b64_e32 v[46:47], s[6:7]
	s_movk_i32 s17, 0xe00
	v_mad_i64_i32 v[46:47], s[36:37], v48, s17, v[46:47]
	v_lshl_add_u64 v[46:47], s[2:3], 1, v[46:47]
	v_mov_b32_e32 v63, v1
	v_lshl_add_u64 v[46:47], v[46:47], 0, v[62:63]
	global_load_dwordx4 v[50:53], v[46:47], off offset:1536
	s_waitcnt vmcnt(0) lgkmcnt(0)
	v_lshlrev_b32_e32 v46, 16, v50
	v_and_b32_e32 v47, 0xffff0000, v50
	v_lshlrev_b32_e32 v48, 16, v51
	v_and_b32_e32 v49, 0xffff0000, v51
	v_lshlrev_b32_e32 v50, 16, v52
	v_and_b32_e32 v51, 0xffff0000, v52
	v_lshlrev_b32_e32 v52, 16, v53
	v_and_b32_e32 v53, 0xffff0000, v53
.LBB0_623:
	s_or_b64 exec, exec, s[20:21]
	v_cmp_lt_i32_e32 vcc, -5, v95
	v_mov_b32_e32 v54, 0
	v_mov_b32_e32 v55, 0
	v_mov_b32_e32 v56, 0
	v_mov_b32_e32 v57, 0
	v_mov_b32_e32 v58, 0
	v_mov_b32_e32 v59, 0
	v_mov_b32_e32 v60, 0
	v_mov_b32_e32 v61, 0
	s_and_saveexec_b64 s[20:21], vcc
	s_cbranch_execz .LBB0_625
	v_add3_u32 v56, v95, s30, 4
	v_mov_b64_e32 v[54:55], s[6:7]
	s_movk_i32 s6, 0xe00
	v_mad_i64_i32 v[54:55], s[6:7], v56, s6, v[54:55]
	v_lshl_add_u64 v[54:55], s[2:3], 1, v[54:55]
	v_mov_b32_e32 v63, v1
	v_lshl_add_u64 v[54:55], v[54:55], 0, v[62:63]
	global_load_dwordx4 v[58:61], v[54:55], off offset:1536
	s_waitcnt vmcnt(0) lgkmcnt(0)
	v_lshlrev_b32_e32 v54, 16, v58
	v_and_b32_e32 v55, 0xffff0000, v58
	v_lshlrev_b32_e32 v56, 16, v59
	v_and_b32_e32 v57, 0xffff0000, v59
	v_lshlrev_b32_e32 v58, 16, v60
	v_and_b32_e32 v59, 0xffff0000, v60
	v_lshlrev_b32_e32 v60, 16, v61
	v_and_b32_e32 v61, 0xffff0000, v61
.LBB0_625:
	s_or_b64 exec, exec, s[20:21]
	s_waitcnt vmcnt(0) lgkmcnt(0)
	v_pk_fma_f32 v[74:75], v[16:17], v[74:75], v[44:45]
	v_pk_fma_f32 v[78:79], v[14:15], v[78:79], v[42:43]
	v_pk_fma_f32 v[74:75], v[20:21], v[66:67], v[74:75]
	v_pk_fma_f32 v[78:79], v[18:19], v[64:65], v[78:79]
	v_pk_fma_f32 v[74:75], v[28:29], v[82:83], v[74:75]
	v_pk_fma_f32 v[72:73], v[8:9], v[72:73], v[36:37]
	v_pk_fma_f32 v[98:99], v[40:41], v[48:49], v[74:75]
	v_pk_fma_f32 v[74:75], v[6:7], v[76:77], v[34:35]
	v_pk_fma_f32 v[78:79], v[26:27], v[80:81], v[78:79]
	v_pk_fma_f32 v[74:75], v[10:11], v[68:69], v[74:75]
	v_pk_fma_f32 v[72:73], v[12:13], v[70:71], v[72:73]
	v_lshl_add_u32 v63, v3, 2, 0
	v_readlane_b32 s6, v254, 24
	v_pk_fma_f32 v[96:97], v[38:39], v[46:47], v[78:79]
	v_pk_fma_f32 v[74:75], v[22:23], v[84:85], v[74:75]
	v_pk_fma_f32 v[72:73], v[24:25], v[86:87], v[72:73]
	v_lshl_add_u32 v62, v3, 1, s6
	v_pk_fma_f32 v[74:75], v[30:31], v[50:51], v[74:75]
	v_pk_fma_f32 v[76:77], v[32:33], v[52:53], v[72:73]
	v_lshl_add_u32 v3, v94, 9, v63
	v_bfe_u32 v73, v96, 16, 1
	ds_write_b128 v3, v[96:99] offset:33792
	ds_write_b128 v3, v[74:77] offset:33808
	v_bfe_u32 v3, v98, 16, 1
	v_bfe_u32 v72, v76, 16, 1
	v_bfe_u32 v78, v74, 16, 1
	v_add3_u32 v73, v96, v73, s91
	v_add3_u32 v72, v76, v72, s91
	v_add3_u32 v3, v98, v3, s91
	v_add3_u32 v74, v74, v78, s91
	v_lshrrev_b32_e32 v76, 16, v73
	v_bfe_u32 v73, v77, 16, 1
	v_bfe_u32 v78, v99, 16, 1
	v_pk_fma_f32 v[14:15], v[14:15], v[64:65], v[42:43]
	v_pk_fma_f32 v[16:17], v[16:17], v[66:67], v[44:45]
	v_pk_fma_f32 v[6:7], v[6:7], v[68:69], v[34:35]
	v_pk_fma_f32 v[8:9], v[8:9], v[70:71], v[36:37]
	v_lshrrev_b32_e32 v3, 16, v3
	v_lshrrev_b32_e32 v72, 16, v72
	v_bfe_u32 v79, v75, 16, 1
	v_bfe_u32 v95, v97, 16, 1
	v_add3_u32 v78, v99, v78, s91
	v_add3_u32 v73, v77, v73, s91
	v_pk_fma_f32 v[14:15], v[18:19], v[80:81], v[14:15]
	v_pk_fma_f32 v[16:17], v[20:21], v[82:83], v[16:17]
	v_pk_fma_f32 v[6:7], v[10:11], v[84:85], v[6:7]
	v_pk_fma_f32 v[8:9], v[12:13], v[86:87], v[8:9]
	v_lshrrev_b32_e32 v74, 16, v74
	v_add3_u32 v77, v97, v95, s91
	v_add3_u32 v79, v75, v79, s91
	v_and_or_b32 v75, v73, s33, v72
	v_and_or_b32 v73, v78, s33, v3
	s_movk_i32 s6, 0x120
	v_pk_fma_f32 v[14:15], v[26:27], v[46:47], v[14:15]
	v_pk_fma_f32 v[16:17], v[28:29], v[48:49], v[16:17]
	v_pk_fma_f32 v[6:7], v[22:23], v[50:51], v[6:7]
	v_pk_fma_f32 v[8:9], v[24:25], v[52:53], v[8:9]
	v_or_b32_e32 v3, 1, v93
	v_and_or_b32 v74, v79, s33, v74
	v_and_or_b32 v72, v77, s33, v76
	v_mad_u64_u32 v[76:77], s[6:7], v94, s6, v[62:63]
	v_pk_fma_f32 v[14:15], v[38:39], v[54:55], v[14:15]
	v_pk_fma_f32 v[16:17], v[40:41], v[56:57], v[16:17]
	v_pk_fma_f32 v[6:7], v[30:31], v[58:59], v[6:7]
	v_pk_fma_f32 v[8:9], v[32:33], v[60:61], v[8:9]
	v_lshl_add_u32 v10, v3, 8, v63
	ds_write_b128 v76, v[72:75]
	ds_write_b128 v10, v[14:17] offset:33792
	ds_write_b128 v10, v[6:9] offset:33808
	v_bfe_u32 v10, v16, 16, 1
	v_bfe_u32 v11, v8, 16, 1
	v_bfe_u32 v12, v14, 16, 1
	v_bfe_u32 v13, v6, 16, 1
	v_add3_u32 v8, v8, v11, s91
	v_add3_u32 v10, v16, v10, s91
	v_add3_u32 v6, v6, v13, s91
	v_add3_u32 v11, v14, v12, s91
	v_bfe_u32 v12, v9, 16, 1
	v_bfe_u32 v13, v17, 16, 1
	v_bfe_u32 v14, v7, 16, 1
	v_bfe_u32 v16, v15, 16, 1
	v_lshrrev_b32_e32 v10, 16, v10
	v_lshrrev_b32_e32 v8, 16, v8
	v_lshrrev_b32_e32 v11, 16, v11
	v_lshrrev_b32_e32 v6, 16, v6
	v_add3_u32 v13, v17, v13, s91
	v_add3_u32 v9, v9, v12, s91
	v_add3_u32 v12, v15, v16, s91
	v_add3_u32 v14, v7, v14, s91
	v_and_or_b32 v9, v9, s33, v8
	v_and_or_b32 v7, v13, s33, v10
	v_and_or_b32 v8, v14, s33, v6
	v_and_or_b32 v6, v12, s33, v11
	v_mad_u64_u32 v[10:11], s[6:7], v3, s88, v[62:63]
	s_cmp_eq_u32 s34, 31
	s_cselect_b64 s[6:7], -1, 0
	v_cmp_lt_i32_e32 vcc, 61, v94
	s_and_b64 s[20:21], s[6:7], vcc
	ds_write_b128 v10, v[6:9]
	s_and_saveexec_b64 s[6:7], s[20:21]
	s_cbranch_execz .LBB0_629
	v_readlane_b32 s17, v254, 8
	v_cmp_lt_u32_e32 vcc, 62, v94
	s_nop 0
	v_mov_b32_e32 v3, s17
	ds_read_b64 v[6:7], v3
	s_add_i32 s17, s31, s26
	s_mul_hi_i32 s20, s17, 0x2400
	s_mulk_i32 s17, 0x2400
	s_waitcnt lgkmcnt(0)
	v_readfirstlane_b32 s21, v6
	v_readfirstlane_b32 s31, v7
	s_add_u32 s17, s21, s17
	s_addc_u32 s21, s31, s20
	s_add_u32 s20, s17, s4
	s_addc_u32 s21, s21, s5
	v_lshl_add_u64 v[6:7], s[20:21], 0, v[0:1]
	s_mov_b64 s[20:21], 0x4086000
	v_lshl_add_u64 v[6:7], v[6:7], 0, s[20:21]
	s_and_saveexec_b64 s[20:21], vcc
	s_cbranch_execz .LBB0_628
	v_add_u32_e32 v0, 0xffffff83, v93
	s_movk_i32 s17, 0xc00
	v_mad_u64_u32 v[8:9], s[34:35], v0, s17, v[6:7]
	global_store_dwordx4 v[8:9], v[46:49], off
	global_store_dwordx4 v[8:9], v[50:53], off offset:16
.LBB0_628:
	s_or_b64 exec, exec, s[20:21]
	v_add_u32_e32 v0, 0xffffff84, v93
	s_movk_i32 s17, 0xc00
	v_mad_u64_u32 v[6:7], s[20:21], v0, s17, v[6:7]
	global_store_dwordx4 v[6:7], v[54:57], off
	global_store_dwordx4 v[6:7], v[58:61], off offset:16
.LBB0_629:
	s_or_b64 exec, exec, s[6:7]
	v_ashrrev_i32_e32 v3, 2, v2
	v_and_b32_e32 v14, 15, v2
	v_bfi_b32 v18, -16, v3, v2
	v_mul_lo_u32 v6, v18, s88
	v_and_b32_e32 v0, 48, v2
	v_readlane_b32 s6, v254, 24
	v_mul_u32_u24_e32 v14, 0x90, v14
	v_readlane_b32 s20, v254, 20
	v_add3_u32 v6, s6, v6, v0
	v_lshlrev_b32_e32 v15, 8, v18
	v_readlane_b32 s6, v254, 26
	v_add_u32_e32 v24, 0, v0
	v_add3_u32 v47, s20, v0, v14
	s_waitcnt lgkmcnt(0)
	s_barrier
	ds_read_b128 v[10:13], v6
	ds_read_b128 v[6:9], v6 offset:64
	v_add3_u32 v45, s6, v15, v0
	v_add_u32_e32 v44, v24, v15
	ds_read_b128 v[14:17], v47 offset:9216
	s_or_b32 s17, s29, s30
	v_add_u32_e32 v42, s17, v18
	ds_read_b128 v[18:21], v47 offset:9280
	s_waitcnt lgkmcnt(0)
	v_mfma_f32_16x16x32_bf16 v[14:17], v[14:17], v[10:13], 0
	v_add_u32_e32 v46, 0x22500, v24
	ds_read_b128 v[32:35], v47
	ds_read_b128 v[24:27], v46 offset:512
	v_mfma_f32_16x16x32_bf16 v[28:31], v[18:21], v[6:9], v[14:17]
	s_add_u32 s6, s0, s4
	s_addc_u32 s7, s1, s5
	ds_read_b128 v[36:39], v47 offset:64
	s_add_u32 s4, s6, 0x16400000
	s_addc_u32 s5, s7, 0
	s_waitcnt lgkmcnt(0)
	s_nop 1
	v_add_f32_e32 v14, v28, v24
	v_mul_f32_e32 v14, 0xbfb8aa3b, v14
	v_exp_f32_e32 v20, v14
	v_mov_b64_e32 v[22:23], s[4:5]
	s_movk_i32 s17, 0xc00
	v_mad_i64_i32 v[22:23], s[4:5], v42, s17, v[22:23]
	v_add_f32_e32 v20, 1.0, v20
	v_lshl_add_u64 v[40:41], v[22:23], 0, v[0:1]
	v_mfma_f32_16x16x32_bf16 v[14:17], v[32:35], v[10:13], 0
	v_rcp_f32_e32 v24, v20
	ds_read_b128 v[20:23], v46
	s_add_u32 s6, s6, 0x19400000
	s_addc_u32 s7, s7, 0
	v_mov_b64_e32 v[18:19], s[6:7]
	v_mad_i64_i32 v[42:43], s[4:5], v42, s17, v[18:19]
	ds_read_b128 v[32:35], v46 offset:256
	v_mfma_f32_16x16x32_bf16 v[16:19], v[36:39], v[6:9], v[14:17]
	ds_read_b128 v[36:39], v44 offset:33792
	v_lshl_add_u64 v[42:43], v[42:43], 0, v[0:1]
	v_add_f32_e32 v25, v29, v25
	v_mul_f32_e32 v14, 0x41000000, v24
	s_waitcnt lgkmcnt(0)
	v_mul_f32_e32 v14, v20, v14
	v_mul_f32_e32 v14, 0x3fb8aa3b, v14
	v_exp_f32_e32 v14, v14
	v_add_f32_e32 v15, v16, v32
	v_mul_f32_e32 v15, 0xbfb8aa3b, v15
	v_exp_f32_e32 v15, v15
	v_fma_f32 v16, -v14, v14, 1.0
	v_max_f32_e32 v16, 0, v16
	v_cmp_gt_f32_e32 vcc, s85, v16
	v_mul_f32_e32 v20, 0x4f800000, v16
	v_add_f32_e32 v0, 1.0, v15
	v_cndmask_b32_e32 v16, v16, v20, vcc
	v_sqrt_f32_e32 v24, v16
	v_rcp_f32_e32 v20, v0
	v_mul_f32_e32 v25, 0xbfb8aa3b, v25
	v_exp_f32_e32 v25, v25
	v_add_u32_e32 v0, -1, v24
	v_fma_f32 v15, -v0, v24, v16
	v_cmp_ge_f32_e64 s[4:5], 0, v15
	v_add_u32_e32 v15, 1, v24
	v_add_f32_e32 v17, v17, v33
	v_cndmask_b32_e64 v0, v24, v0, s[4:5]
	v_fma_f32 v24, -v15, v24, v16
	v_cmp_lt_f32_e64 s[4:5], 0, v24
	v_mul_f32_e32 v17, 0xbfb8aa3b, v17
	v_exp_f32_e32 v17, v17
	v_cndmask_b32_e64 v0, v0, v15, s[4:5]
	v_add_f32_e32 v15, 1.0, v25
	v_rcp_f32_e32 v15, v15
	v_mul_f32_e32 v24, 0x37800000, v0
	v_cndmask_b32_e32 v0, v0, v24, vcc
	v_cmp_class_f32_e32 vcc, v16, v221
	v_mul_f32_e32 v15, 0x41000000, v15
	v_mul_f32_e32 v15, v21, v15
	v_mul_f32_e32 v15, 0x3fb8aa3b, v15
	v_exp_f32_e32 v15, v15
	v_add_f32_e32 v26, v30, v26
	v_mul_f32_e32 v26, 0xbfb8aa3b, v26
	v_exp_f32_e32 v26, v26
	v_fma_f32 v21, -v15, v15, 1.0
	v_max_f32_e32 v21, 0, v21
	v_cmp_gt_f32_e64 s[4:5], s85, v21
	v_mul_f32_e32 v24, 0x4f800000, v21
	v_add_f32_e32 v27, v31, v27
	v_cndmask_b32_e64 v25, v21, v24, s[4:5]
	v_sqrt_f32_e32 v28, v25
	v_cndmask_b32_e32 v24, v0, v16, vcc
	v_add_f32_e32 v0, 1.0, v17
	v_rcp_f32_e32 v21, v0
	v_add_u32_e32 v0, -1, v28
	v_fma_f32 v16, -v0, v28, v25
	v_cmp_ge_f32_e32 vcc, 0, v16
	v_add_u32_e32 v16, 1, v28
	v_fma_f32 v17, -v16, v28, v25
	v_cndmask_b32_e32 v0, v28, v0, vcc
	v_cmp_lt_f32_e32 vcc, 0, v17
	v_add_f32_e32 v17, 1.0, v26
	v_rcp_f32_e32 v17, v17
	v_cndmask_b32_e32 v0, v0, v16, vcc
	v_mul_f32_e32 v16, 0x37800000, v0
	v_cndmask_b32_e64 v0, v0, v16, s[4:5]
	v_cmp_class_f32_e32 vcc, v25, v221
	v_mul_f32_e32 v27, 0xbfb8aa3b, v27
	v_exp_f32_e32 v27, v27
	v_cndmask_b32_e32 v25, v0, v25, vcc
	v_mul_f32_e32 v0, 0x41000000, v17
	v_mul_f32_e32 v0, v22, v0
	v_mul_f32_e32 v0, 0x3fb8aa3b, v0
	v_exp_f32_e32 v16, v0
	v_add_f32_e32 v0, v18, v34
	v_mul_f32_e32 v0, 0xbfb8aa3b, v0
	v_exp_f32_e32 v18, v0
	v_fma_f32 v0, -v16, v16, 1.0
	v_max_f32_e32 v0, 0, v0
	v_cmp_gt_f32_e32 vcc, s85, v0
	v_mul_f32_e32 v17, 0x4f800000, v0
	v_add_f32_e32 v19, v19, v35
	v_cndmask_b32_e32 v0, v0, v17, vcc
	v_sqrt_f32_e32 v17, v0
	v_mul_f32_e32 v19, 0xbfb8aa3b, v19
	v_exp_f32_e32 v19, v19
	v_add_f32_e32 v18, 1.0, v18
	v_add_u32_e32 v22, -1, v17
	v_fma_f32 v26, -v22, v17, v0
	v_cmp_ge_f32_e64 s[4:5], 0, v26
	v_add_u32_e32 v26, 1, v17
	v_rcp_f32_e32 v18, v18
	v_cndmask_b32_e64 v22, v17, v22, s[4:5]
	v_fma_f32 v17, -v26, v17, v0
	v_cmp_lt_f32_e64 s[4:5], 0, v17
	v_pk_mul_f32 v[20:21], v[20:21], v[24:25]
	s_nop 0
	v_cndmask_b32_e64 v17, v22, v26, s[4:5]
	v_add_f32_e32 v22, 1.0, v27
	v_rcp_f32_e32 v22, v22
	v_mul_f32_e32 v26, 0x37800000, v17
	v_cndmask_b32_e32 v26, v17, v26, vcc
	v_cmp_class_f32_e32 vcc, v0, v221
	v_mul_f32_e32 v17, 0x41000000, v22
	v_mul_f32_e32 v17, v23, v17
	v_mul_f32_e32 v17, 0x3fb8aa3b, v17
	v_exp_f32_e32 v17, v17
	s_nop 0
	v_fma_f32 v22, -v17, v17, 1.0
	v_max_f32_e32 v22, 0, v22
	v_cmp_gt_f32_e64 s[4:5], s85, v22
	v_mul_f32_e32 v23, 0x4f800000, v22
	s_nop 0
	v_cndmask_b32_e64 v23, v22, v23, s[4:5]
	v_sqrt_f32_e32 v27, v23
	v_cndmask_b32_e32 v22, v26, v0, vcc
	v_add_f32_e32 v0, 1.0, v19
	v_rcp_f32_e32 v19, v0
	v_add_u32_e32 v0, -1, v27
	v_fma_f32 v26, -v0, v27, v23
	v_cmp_ge_f32_e32 vcc, 0, v26
	v_add_u32_e32 v26, 1, v27
	s_nop 0
	v_cndmask_b32_e32 v0, v27, v0, vcc
	v_fma_f32 v27, -v26, v27, v23
	v_cmp_lt_f32_e32 vcc, 0, v27
	s_nop 1
	v_cndmask_b32_e32 v0, v0, v26, vcc
	v_mul_f32_e32 v26, 0x37800000, v0
	v_cndmask_b32_e64 v0, v0, v26, s[4:5]
	v_cmp_class_f32_e32 vcc, v23, v221
	s_nop 1
	v_cndmask_b32_e32 v23, v0, v23, vcc
	v_pk_mul_f32 v[22:23], v[18:19], v[22:23]
	v_pk_mul_f32 v[18:19], v[36:37], v[20:21]
	v_pk_mul_f32 v[20:21], v[38:39], v[22:23]
	ds_write_b128 v45, v[14:17]
	ds_write_b128 v44, v[18:21]
	global_store_dwordx4 v[40:41], v[14:17], off nt
	global_store_dwordx4 v[42:43], v[18:21], off nt
	ds_read_b128 v[14:17], v47 offset:11520
	ds_read_b128 v[18:21], v47 offset:11584
	s_waitcnt lgkmcnt(0)
	v_mfma_f32_16x16x32_bf16 v[14:17], v[14:17], v[10:13], 0
	ds_read_b128 v[22:25], v47 offset:2304
	ds_read_b128 v[36:39], v47 offset:2368
	ds_read_b128 v[28:31], v46 offset:576
	v_mfma_f32_16x16x32_bf16 v[32:35], v[18:21], v[6:9], v[14:17]
	s_waitcnt lgkmcnt(0)
	v_mfma_f32_16x16x32_bf16 v[14:17], v[22:25], v[10:13], 0
	ds_read_b128 v[20:23], v46 offset:64
	s_nop 4
	v_add_f32_e32 v0, v32, v28
	v_mul_f32_e32 v0, 0xbfb8aa3b, v0
	v_exp_f32_e32 v0, v0
	v_mfma_f32_16x16x32_bf16 v[16:19], v[36:39], v[6:9], v[14:17]
	ds_read_b128 v[36:39], v44 offset:33856
	ds_read_b128 v[24:27], v46 offset:320
	v_add_f32_e32 v0, 1.0, v0
	v_rcp_f32_e32 v0, v0
	v_add_f32_e32 v28, v33, v29
	v_mul_f32_e32 v28, 0xbfb8aa3b, v28
	v_exp_f32_e32 v28, v28
	v_mul_f32_e32 v0, 0x41000000, v0
	s_waitcnt lgkmcnt(0)
	v_mul_f32_e32 v0, v20, v0
	v_mul_f32_e32 v0, 0x3fb8aa3b, v0
	v_exp_f32_e32 v14, v0
	v_add_f32_e32 v0, v16, v24
	v_mul_f32_e32 v0, 0xbfb8aa3b, v0
	v_exp_f32_e32 v0, v0
	v_fma_f32 v15, -v14, v14, 1.0
	v_max_f32_e32 v15, 0, v15
	v_cmp_gt_f32_e32 vcc, s85, v15
	v_mul_f32_e32 v16, 0x4f800000, v15
	v_add_f32_e32 v0, 1.0, v0
	v_cndmask_b32_e32 v16, v15, v16, vcc
	v_sqrt_f32_e32 v15, v16
	v_rcp_f32_e32 v20, v0
	v_add_f32_e32 v17, v17, v25
	v_mul_f32_e32 v17, 0xbfb8aa3b, v17
	v_add_u32_e32 v0, -1, v15
	v_fma_f32 v24, -v0, v15, v16
	v_cmp_ge_f32_e64 s[4:5], 0, v24
	v_add_u32_e32 v24, 1, v15
	v_exp_f32_e32 v17, v17
	v_cndmask_b32_e64 v0, v15, v0, s[4:5]
	v_fma_f32 v15, -v24, v15, v16
	v_cmp_lt_f32_e64 s[4:5], 0, v15
	v_add_f32_e32 v15, 1.0, v28
	v_rcp_f32_e32 v15, v15
	v_cndmask_b32_e64 v0, v0, v24, s[4:5]
	v_mul_f32_e32 v24, 0x37800000, v0
	v_cndmask_b32_e32 v0, v0, v24, vcc
	v_mul_f32_e32 v15, 0x41000000, v15
	v_mul_f32_e32 v15, v21, v15
	v_mul_f32_e32 v15, 0x3fb8aa3b, v15
	v_exp_f32_e32 v15, v15
	v_cmp_class_f32_e32 vcc, v16, v221
	v_add_f32_e32 v19, v19, v27
	v_mul_f32_e32 v19, 0xbfb8aa3b, v19
	v_fma_f32 v21, -v15, v15, 1.0
	v_max_f32_e32 v21, 0, v21
	v_cmp_gt_f32_e64 s[4:5], s85, v21
	v_mul_f32_e32 v24, 0x4f800000, v21
	v_exp_f32_e32 v19, v19
	v_cndmask_b32_e64 v25, v21, v24, s[4:5]
	v_sqrt_f32_e32 v28, v25
	v_cndmask_b32_e32 v24, v0, v16, vcc
	v_add_f32_e32 v0, 1.0, v17
	v_rcp_f32_e32 v21, v0
	v_add_u32_e32 v0, -1, v28
	v_fma_f32 v16, -v0, v28, v25
	v_cmp_ge_f32_e32 vcc, 0, v16
	v_add_u32_e32 v16, 1, v28
	v_fma_f32 v17, -v16, v28, v25
	v_cndmask_b32_e32 v0, v28, v0, vcc
	v_add_f32_e32 v28, v34, v30
	v_mul_f32_e32 v28, 0xbfb8aa3b, v28
	v_exp_f32_e32 v28, v28
	v_cmp_lt_f32_e32 vcc, 0, v17
	v_add_f32_e32 v17, 1.0, v28
	v_rcp_f32_e32 v17, v17
	v_cndmask_b32_e32 v0, v0, v16, vcc
	v_mul_f32_e32 v16, 0x37800000, v0
	v_cndmask_b32_e64 v0, v0, v16, s[4:5]
	v_cmp_class_f32_e32 vcc, v25, v221
	v_add_f32_e32 v28, v35, v31
	v_mul_f32_e32 v28, 0xbfb8aa3b, v28
	v_cndmask_b32_e32 v25, v0, v25, vcc
	v_mul_f32_e32 v0, 0x41000000, v17
	v_mul_f32_e32 v0, v22, v0
	v_mul_f32_e32 v0, 0x3fb8aa3b, v0
	v_exp_f32_e32 v16, v0
	v_add_f32_e32 v0, v18, v26
	v_mul_f32_e32 v0, 0xbfb8aa3b, v0
	v_exp_f32_e32 v18, v0
	v_fma_f32 v0, -v16, v16, 1.0
	v_max_f32_e32 v0, 0, v0
	v_cmp_gt_f32_e32 vcc, s85, v0
	v_mul_f32_e32 v17, 0x4f800000, v0
	v_exp_f32_e32 v28, v28
	v_cndmask_b32_e32 v0, v0, v17, vcc
	v_sqrt_f32_e32 v17, v0
	v_add_f32_e32 v18, 1.0, v18
	v_rcp_f32_e32 v18, v18
	v_pk_mul_f32 v[20:21], v[20:21], v[24:25]
	v_add_u32_e32 v22, -1, v17
	v_fma_f32 v26, -v22, v17, v0
	v_cmp_ge_f32_e64 s[4:5], 0, v26
	v_add_u32_e32 v26, 1, v17
	s_nop 0
	v_cndmask_b32_e64 v22, v17, v22, s[4:5]
	v_fma_f32 v17, -v26, v17, v0
	v_cmp_lt_f32_e64 s[4:5], 0, v17
	s_nop 1
	v_cndmask_b32_e64 v17, v22, v26, s[4:5]
	v_add_f32_e32 v22, 1.0, v28
	v_rcp_f32_e32 v22, v22
	v_mul_f32_e32 v26, 0x37800000, v17
	v_cndmask_b32_e32 v26, v17, v26, vcc
	v_cmp_class_f32_e32 vcc, v0, v221
	v_mul_f32_e32 v17, 0x41000000, v22
	v_mul_f32_e32 v17, v23, v17
	v_mul_f32_e32 v17, 0x3fb8aa3b, v17
	v_exp_f32_e32 v17, v17
	s_nop 0
	v_fma_f32 v22, -v17, v17, 1.0
	v_max_f32_e32 v22, 0, v22
	v_cmp_gt_f32_e64 s[4:5], s85, v22
	v_mul_f32_e32 v23, 0x4f800000, v22
	s_nop 0
	v_cndmask_b32_e64 v23, v22, v23, s[4:5]
	v_sqrt_f32_e32 v27, v23
	v_cndmask_b32_e32 v22, v26, v0, vcc
	v_add_f32_e32 v0, 1.0, v19
	v_rcp_f32_e32 v19, v0
	v_add_u32_e32 v0, -1, v27
	v_fma_f32 v26, -v0, v27, v23
	v_cmp_ge_f32_e32 vcc, 0, v26
	v_add_u32_e32 v26, 1, v27
	s_nop 0
	v_cndmask_b32_e32 v0, v27, v0, vcc
	v_fma_f32 v27, -v26, v27, v23
	v_cmp_lt_f32_e32 vcc, 0, v27
	s_nop 1
	v_cndmask_b32_e32 v0, v0, v26, vcc
	v_mul_f32_e32 v26, 0x37800000, v0
	v_cndmask_b32_e64 v0, v0, v26, s[4:5]
	v_cmp_class_f32_e32 vcc, v23, v221
	s_nop 1
	v_cndmask_b32_e32 v23, v0, v23, vcc
	v_pk_mul_f32 v[22:23], v[18:19], v[22:23]
	v_pk_mul_f32 v[18:19], v[36:37], v[20:21]
	v_pk_mul_f32 v[20:21], v[38:39], v[22:23]
	ds_write_b128 v45, v[14:17] offset:64
	ds_write_b128 v44, v[18:21] offset:64
	global_store_dwordx4 v[40:41], v[14:17], off offset:64 nt
	global_store_dwordx4 v[42:43], v[18:21], off offset:64 nt
	ds_read_b128 v[14:17], v47 offset:13824
	ds_read_b128 v[18:21], v47 offset:13888
	s_waitcnt lgkmcnt(0)
	v_mfma_f32_16x16x32_bf16 v[14:17], v[14:17], v[10:13], 0
	ds_read_b128 v[22:25], v47 offset:4608
	ds_read_b128 v[36:39], v47 offset:4672
	ds_read_b128 v[28:31], v46 offset:640
	v_mfma_f32_16x16x32_bf16 v[32:35], v[18:21], v[6:9], v[14:17]
	s_waitcnt lgkmcnt(0)
	v_mfma_f32_16x16x32_bf16 v[14:17], v[22:25], v[10:13], 0
	ds_read_b128 v[20:23], v46 offset:128
	s_nop 4
	v_add_f32_e32 v0, v32, v28
	v_mul_f32_e32 v0, 0xbfb8aa3b, v0
	v_exp_f32_e32 v0, v0
	v_mfma_f32_16x16x32_bf16 v[16:19], v[36:39], v[6:9], v[14:17]
	ds_read_b128 v[36:39], v44 offset:33920
	ds_read_b128 v[24:27], v46 offset:384
	v_add_f32_e32 v0, 1.0, v0
	v_rcp_f32_e32 v0, v0
	v_add_f32_e32 v28, v33, v29
	v_mul_f32_e32 v28, 0xbfb8aa3b, v28
	v_exp_f32_e32 v28, v28
	v_mul_f32_e32 v0, 0x41000000, v0
	s_waitcnt lgkmcnt(0)
	v_mul_f32_e32 v0, v20, v0
	v_mul_f32_e32 v0, 0x3fb8aa3b, v0
	v_exp_f32_e32 v14, v0
	v_add_f32_e32 v0, v16, v24
	v_mul_f32_e32 v0, 0xbfb8aa3b, v0
	v_exp_f32_e32 v0, v0
	v_fma_f32 v15, -v14, v14, 1.0
	v_max_f32_e32 v15, 0, v15
	v_cmp_gt_f32_e32 vcc, s85, v15
	v_mul_f32_e32 v16, 0x4f800000, v15
	v_add_f32_e32 v0, 1.0, v0
	v_cndmask_b32_e32 v16, v15, v16, vcc
	v_sqrt_f32_e32 v15, v16
	v_rcp_f32_e32 v20, v0
	v_add_f32_e32 v17, v17, v25
	v_mul_f32_e32 v17, 0xbfb8aa3b, v17
	v_add_u32_e32 v0, -1, v15
	v_fma_f32 v24, -v0, v15, v16
	v_cmp_ge_f32_e64 s[4:5], 0, v24
	v_add_u32_e32 v24, 1, v15
	v_exp_f32_e32 v17, v17
	v_cndmask_b32_e64 v0, v15, v0, s[4:5]
	v_fma_f32 v15, -v24, v15, v16
	v_cmp_lt_f32_e64 s[4:5], 0, v15
	v_add_f32_e32 v15, 1.0, v28
	v_rcp_f32_e32 v15, v15
	v_cndmask_b32_e64 v0, v0, v24, s[4:5]
	v_mul_f32_e32 v24, 0x37800000, v0
	v_cndmask_b32_e32 v0, v0, v24, vcc
	v_mul_f32_e32 v15, 0x41000000, v15
	v_mul_f32_e32 v15, v21, v15
	v_mul_f32_e32 v15, 0x3fb8aa3b, v15
	v_exp_f32_e32 v15, v15
	v_cmp_class_f32_e32 vcc, v16, v221
	v_add_f32_e32 v19, v19, v27
	v_mul_f32_e32 v19, 0xbfb8aa3b, v19
	v_fma_f32 v21, -v15, v15, 1.0
	v_max_f32_e32 v21, 0, v21
	v_cmp_gt_f32_e64 s[4:5], s85, v21
	v_mul_f32_e32 v24, 0x4f800000, v21
	v_exp_f32_e32 v19, v19
	v_cndmask_b32_e64 v25, v21, v24, s[4:5]
	v_sqrt_f32_e32 v28, v25
	v_cndmask_b32_e32 v24, v0, v16, vcc
	v_add_f32_e32 v0, 1.0, v17
	v_rcp_f32_e32 v21, v0
	v_add_u32_e32 v0, -1, v28
	v_fma_f32 v16, -v0, v28, v25
	v_cmp_ge_f32_e32 vcc, 0, v16
	v_add_u32_e32 v16, 1, v28
	v_fma_f32 v17, -v16, v28, v25
	v_cndmask_b32_e32 v0, v28, v0, vcc
	v_add_f32_e32 v28, v34, v30
	v_mul_f32_e32 v28, 0xbfb8aa3b, v28
	v_exp_f32_e32 v28, v28
	v_cmp_lt_f32_e32 vcc, 0, v17
	v_add_f32_e32 v17, 1.0, v28
	v_rcp_f32_e32 v17, v17
	v_cndmask_b32_e32 v0, v0, v16, vcc
	v_mul_f32_e32 v16, 0x37800000, v0
	v_cndmask_b32_e64 v0, v0, v16, s[4:5]
	v_cmp_class_f32_e32 vcc, v25, v221
	v_add_f32_e32 v28, v35, v31
	v_mul_f32_e32 v28, 0xbfb8aa3b, v28
	v_cndmask_b32_e32 v25, v0, v25, vcc
	v_mul_f32_e32 v0, 0x41000000, v17
	v_mul_f32_e32 v0, v22, v0
	v_mul_f32_e32 v0, 0x3fb8aa3b, v0
	v_exp_f32_e32 v16, v0
	v_add_f32_e32 v0, v18, v26
	v_mul_f32_e32 v0, 0xbfb8aa3b, v0
	v_exp_f32_e32 v18, v0
	v_fma_f32 v0, -v16, v16, 1.0
	v_max_f32_e32 v0, 0, v0
	v_cmp_gt_f32_e32 vcc, s85, v0
	v_mul_f32_e32 v17, 0x4f800000, v0
	v_exp_f32_e32 v28, v28
	v_cndmask_b32_e32 v0, v0, v17, vcc
	v_sqrt_f32_e32 v17, v0
	v_add_f32_e32 v18, 1.0, v18
	v_rcp_f32_e32 v18, v18
	v_pk_mul_f32 v[20:21], v[20:21], v[24:25]
	v_add_u32_e32 v22, -1, v17
	v_fma_f32 v26, -v22, v17, v0
	v_cmp_ge_f32_e64 s[4:5], 0, v26
	v_add_u32_e32 v26, 1, v17
	s_nop 0
	v_cndmask_b32_e64 v22, v17, v22, s[4:5]
	v_fma_f32 v17, -v26, v17, v0
	v_cmp_lt_f32_e64 s[4:5], 0, v17
	s_nop 1
	v_cndmask_b32_e64 v17, v22, v26, s[4:5]
	v_add_f32_e32 v22, 1.0, v28
	v_rcp_f32_e32 v22, v22
	v_mul_f32_e32 v26, 0x37800000, v17
	v_cndmask_b32_e32 v26, v17, v26, vcc
	v_cmp_class_f32_e32 vcc, v0, v221
	v_mul_f32_e32 v17, 0x41000000, v22
	v_mul_f32_e32 v17, v23, v17
	v_mul_f32_e32 v17, 0x3fb8aa3b, v17
	v_exp_f32_e32 v17, v17
	s_nop 0
	v_fma_f32 v22, -v17, v17, 1.0
	v_max_f32_e32 v22, 0, v22
	v_cmp_gt_f32_e64 s[4:5], s85, v22
	v_mul_f32_e32 v23, 0x4f800000, v22
	s_nop 0
	v_cndmask_b32_e64 v23, v22, v23, s[4:5]
	v_sqrt_f32_e32 v27, v23
	v_cndmask_b32_e32 v22, v26, v0, vcc
	v_add_f32_e32 v0, 1.0, v19
	v_rcp_f32_e32 v19, v0
	v_add_u32_e32 v0, -1, v27
	v_fma_f32 v26, -v0, v27, v23
	v_cmp_ge_f32_e32 vcc, 0, v26
	v_add_u32_e32 v26, 1, v27
	s_nop 0
	v_cndmask_b32_e32 v0, v27, v0, vcc
	v_fma_f32 v27, -v26, v27, v23
	v_cmp_lt_f32_e32 vcc, 0, v27
	s_nop 1
	v_cndmask_b32_e32 v0, v0, v26, vcc
	v_mul_f32_e32 v26, 0x37800000, v0
	v_cndmask_b32_e64 v0, v0, v26, s[4:5]
	v_cmp_class_f32_e32 vcc, v23, v221
	s_nop 1
	v_cndmask_b32_e32 v23, v0, v23, vcc
	v_pk_mul_f32 v[22:23], v[18:19], v[22:23]
	v_pk_mul_f32 v[18:19], v[36:37], v[20:21]
	v_pk_mul_f32 v[20:21], v[38:39], v[22:23]
	ds_write_b128 v45, v[14:17] offset:128
	ds_write_b128 v44, v[18:21] offset:128
	global_store_dwordx4 v[40:41], v[14:17], off offset:128 nt
	global_store_dwordx4 v[42:43], v[18:21], off offset:128 nt
	ds_read_b128 v[14:17], v47 offset:16128
	ds_read_b128 v[24:27], v47 offset:16192
	s_waitcnt lgkmcnt(0)
	v_mfma_f32_16x16x32_bf16 v[14:17], v[14:17], v[10:13], 0
	ds_read_b128 v[28:31], v47 offset:6912
	ds_read_b128 v[32:35], v47 offset:6976
	ds_read_b128 v[20:23], v46 offset:704
	v_mfma_f32_16x16x32_bf16 v[24:27], v[24:27], v[6:9], v[14:17]
	s_waitcnt lgkmcnt(0)
	v_mfma_f32_16x16x32_bf16 v[16:19], v[28:31], v[10:13], 0
	s_nop 1
	ds_read_b128 v[12:15], v46 offset:192
	ds_read_b128 v[28:31], v44 offset:33984
	s_nop 1
	v_add_f32_e32 v0, v24, v20
	v_mul_f32_e32 v0, 0xbfb8aa3b, v0
	v_exp_f32_e32 v0, v0
	v_mfma_f32_16x16x32_bf16 v[8:11], v[32:35], v[6:9], v[16:19]
	v_add_f32_e32 v21, v25, v21
	v_mul_f32_e32 v21, 0xbfb8aa3b, v21
	v_add_f32_e32 v0, 1.0, v0
	v_rcp_f32_e32 v20, v0
	ds_read_b128 v[16:19], v46 offset:448
	v_exp_f32_e32 v21, v21
	v_add_f32_e32 v22, v26, v22
	v_mul_f32_e32 v6, 0x41000000, v20
	s_waitcnt lgkmcnt(0)
	v_mul_f32_e32 v6, v12, v6
	v_mul_f32_e32 v6, 0x3fb8aa3b, v6
	v_exp_f32_e32 v6, v6
	v_add_f32_e32 v7, v8, v16
	v_mul_f32_e32 v7, 0xbfb8aa3b, v7
	v_exp_f32_e32 v7, v7
	v_fma_f32 v8, -v6, v6, 1.0
	v_max_f32_e32 v8, 0, v8
	v_cmp_gt_f32_e32 vcc, s85, v8
	v_mul_f32_e32 v12, 0x4f800000, v8
	v_add_f32_e32 v7, 1.0, v7
	v_cndmask_b32_e32 v8, v8, v12, vcc
	v_sqrt_f32_e32 v16, v8
	v_rcp_f32_e32 v12, v7
	v_add_f32_e32 v9, v9, v17
	v_mul_f32_e32 v9, 0xbfb8aa3b, v9
	v_add_u32_e32 v7, -1, v16
	v_fma_f32 v24, -v7, v16, v8
	v_cmp_ge_f32_e64 s[4:5], 0, v24
	v_add_u32_e32 v24, 1, v16
	v_exp_f32_e32 v9, v9
	v_cndmask_b32_e64 v7, v16, v7, s[4:5]
	v_fma_f32 v16, -v24, v16, v8
	v_cmp_lt_f32_e64 s[4:5], 0, v16
	v_add_f32_e32 v16, 1.0, v21
	v_rcp_f32_e32 v16, v16
	v_cndmask_b32_e64 v7, v7, v24, s[4:5]
	v_mul_f32_e32 v21, 0x37800000, v7
	v_cndmask_b32_e32 v21, v7, v21, vcc
	v_mul_f32_e32 v7, 0x41000000, v16
	v_mul_f32_e32 v7, v13, v7
	v_mul_f32_e32 v7, 0x3fb8aa3b, v7
	v_exp_f32_e32 v7, v7
	v_cmp_class_f32_e32 vcc, v8, v221
	v_mul_f32_e32 v22, 0xbfb8aa3b, v22
	v_exp_f32_e32 v22, v22
	v_fma_f32 v13, -v7, v7, 1.0
	v_max_f32_e32 v13, 0, v13
	v_cmp_gt_f32_e64 s[4:5], s85, v13
	v_mul_f32_e32 v16, 0x4f800000, v13
	v_add_f32_e32 v11, v11, v19
	v_cndmask_b32_e64 v17, v13, v16, s[4:5]
	v_sqrt_f32_e32 v24, v17
	v_cndmask_b32_e32 v16, v21, v8, vcc
	v_add_f32_e32 v8, 1.0, v9
	v_rcp_f32_e32 v13, v8
	v_add_u32_e32 v8, -1, v24
	v_fma_f32 v9, -v8, v24, v17
	v_cmp_ge_f32_e32 vcc, 0, v9
	v_add_u32_e32 v9, 1, v24
	v_fma_f32 v21, -v9, v24, v17
	v_cndmask_b32_e32 v8, v24, v8, vcc
	v_cmp_lt_f32_e32 vcc, 0, v21
	v_add_f32_e32 v21, 1.0, v22
	v_rcp_f32_e32 v21, v21
	v_cndmask_b32_e32 v8, v8, v9, vcc
	v_mul_f32_e32 v9, 0x37800000, v8
	v_cndmask_b32_e64 v8, v8, v9, s[4:5]
	v_cmp_class_f32_e32 vcc, v17, v221
	v_add_f32_e32 v9, v10, v18
	v_mul_f32_e32 v9, 0xbfb8aa3b, v9
	v_cndmask_b32_e32 v17, v8, v17, vcc
	v_mul_f32_e32 v8, 0x41000000, v21
	v_mul_f32_e32 v8, v14, v8
	v_mul_f32_e32 v8, 0x3fb8aa3b, v8
	v_exp_f32_e32 v8, v8
	v_exp_f32_e32 v14, v9
	v_add_f32_e32 v22, v27, v23
	v_mul_f32_e32 v22, 0xbfb8aa3b, v22
	v_fma_f32 v9, -v8, v8, 1.0
	v_max_f32_e32 v9, 0, v9
	v_cmp_gt_f32_e32 vcc, s85, v9
	v_mul_f32_e32 v10, 0x4f800000, v9
	v_exp_f32_e32 v22, v22
	v_cndmask_b32_e32 v10, v9, v10, vcc
	v_sqrt_f32_e32 v9, v10
	v_mul_f32_e32 v11, 0xbfb8aa3b, v11
	v_exp_f32_e32 v11, v11
	v_add_f32_e32 v14, 1.0, v14
	v_add_u32_e32 v18, -1, v9
	v_fma_f32 v21, -v18, v9, v10
	v_cmp_ge_f32_e64 s[4:5], 0, v21
	v_add_u32_e32 v21, 1, v9
	v_add_f32_e32 v11, 1.0, v11
	v_cndmask_b32_e64 v18, v9, v18, s[4:5]
	v_fma_f32 v9, -v21, v9, v10
	v_cmp_lt_f32_e64 s[4:5], 0, v9
	v_rcp_f32_e32 v14, v14
	v_and_b32_e32 v0, 63, v2
	v_cndmask_b32_e64 v9, v18, v21, s[4:5]
	v_add_f32_e32 v18, 1.0, v22
	v_rcp_f32_e32 v18, v18
	v_mul_f32_e32 v21, 0x37800000, v9
	v_cndmask_b32_e32 v21, v9, v21, vcc
	v_cmp_class_f32_e32 vcc, v10, v221
	v_mul_f32_e32 v9, 0x41000000, v18
	v_mul_f32_e32 v9, v15, v9
	v_mul_f32_e32 v9, 0x3fb8aa3b, v9
	v_exp_f32_e32 v9, v9
	v_cndmask_b32_e32 v10, v21, v10, vcc
	v_pk_mul_f32 v[12:13], v[12:13], v[16:17]
	v_and_b32_e32 v20, -16, v3
	v_fma_f32 v15, -v9, v9, 1.0
	v_max_f32_e32 v15, 0, v15
	v_cmp_gt_f32_e64 s[4:5], s85, v15
	v_mul_f32_e32 v18, 0x4f800000, v15
	v_lshlrev_b32_e32 v0, 2, v0
	v_cndmask_b32_e64 v18, v15, v18, s[4:5]
	v_sqrt_f32_e32 v19, v18
	v_rcp_f32_e32 v15, v11
	v_add_u32_e32 v11, -1, v19
	v_fma_f32 v21, -v11, v19, v18
	v_cmp_ge_f32_e32 vcc, 0, v21
	v_add_u32_e32 v21, 1, v19
	s_nop 0
	v_cndmask_b32_e32 v11, v19, v11, vcc
	v_fma_f32 v19, -v21, v19, v18
	v_cmp_lt_f32_e32 vcc, 0, v19
	s_nop 1
	v_cndmask_b32_e32 v11, v11, v21, vcc
	v_mul_f32_e32 v19, 0x37800000, v11
	v_cndmask_b32_e64 v11, v11, v19, s[4:5]
	v_cmp_class_f32_e32 vcc, v18, v221
	s_movk_i32 s4, 0xf000
	s_nop 0
	v_cndmask_b32_e32 v11, v11, v18, vcc
	v_pk_mul_f32 v[14:15], v[14:15], v[10:11]
	v_pk_mul_f32 v[10:11], v[28:29], v[12:13]
	v_pk_mul_f32 v[12:13], v[30:31], v[14:15]
	ds_write_b128 v45, v[6:9] offset:192
	ds_write_b128 v44, v[10:13] offset:192
	global_store_dwordx4 v[40:41], v[6:9], off offset:192 nt
	global_store_dwordx4 v[42:43], v[10:13], off offset:192 nt
	s_waitcnt lgkmcnt(0)
	v_or_b32_e32 v6, 15, v3
	v_lshlrev_b32_e32 v3, 8, v3
	v_and_or_b32 v3, v3, s4, v0
	v_sub_u32_e32 v6, v6, v20
	v_add_u32_e32 v3, 0, v3
	v_add_u32_e32 v10, 1, v6
	v_mov_b32_e32 v7, 1.0
	v_mov_b32_e32 v8, 0
	s_mov_b64 s[4:5], 0
	s_barrier
.LBB0_630:
	v_add_u32_e32 v6, 0x10400, v3
	ds_read_b32 v9, v6
	ds_read2st64_b32 v[12:13], v3 offset1:1
	v_add_u32_e32 v10, -4, v10
	v_cmp_eq_u32_e32 vcc, 0, v10
	s_or_b64 s[4:5], vcc, s[4:5]
	s_waitcnt lgkmcnt(0)
	v_fma_f32 v6, v8, v9, v12
	v_add_u32_e32 v8, 0x10500, v3
	ds_read_b32 v15, v8
	s_waitcnt lgkmcnt(0)
	v_fmac_f32_e32 v13, v6, v15
	v_add_u32_e32 v6, 0x10600, v3
	ds_read_b32 v8, v6
	ds_read2st64_b32 v[16:17], v3 offset0:2 offset1:3
	v_add_u32_e32 v6, 0x10700, v3
	ds_read_b32 v12, v6
	v_mov_b32_e32 v6, v13
	s_waitcnt lgkmcnt(0)
	v_pk_mul_f32 v[18:19], v[6:7], v[8:9]
	v_mov_b32_e32 v14, v16
	v_pk_fma_f32 v[6:7], v[6:7], v[8:9], v[16:17]
	v_pk_mul_f32 v[14:15], v[18:19], v[14:15]
	v_mov_b32_e32 v13, v8
	v_mov_b32_e32 v7, v15
	v_pk_mul_f32 v[14:15], v[6:7], v[12:13]
	v_mov_b32_e32 v16, v17
	v_mov_b32_e32 v17, v12
	v_pk_fma_f32 v[8:9], v[6:7], v[12:13], v[16:17]
	v_pk_mul_f32 v[6:7], v[14:15], v[16:17]
	v_add_u32_e32 v3, 0x400, v3
	s_andn2_b64 exec, exec, s[4:5]
	s_cbranch_execnz .LBB0_630
	s_or_b64 exec, exec, s[4:5]
	v_and_b32_e32 v6, 0x3fffffc0, v2
	v_readlane_b32 s4, v254, 28
	v_lshlrev_b32_e32 v6, 2, v6
	v_cmp_gt_u32_e32 vcc, 64, v2
	v_lshl_add_u32 v3, v2, 2, s4
	v_add3_u32 v0, s4, v6, v0
	ds_write_b32 v3, v7
	ds_write_b32 v0, v8 offset:2048
	s_waitcnt lgkmcnt(0)
	s_barrier
	s_and_saveexec_b64 s[4:5], vcc
	s_cbranch_execz .LBB0_562
	ds_read2st64_b32 v[6:7], v3 offset1:1
	ds_read2st64_b32 v[8:9], v3 offset0:8 offset1:9
	s_mul_hi_i32 s6, s15, 0x300
	s_mulk_i32 s15, 0x300
	s_add_u32 s2, s15, s2
	s_addc_u32 s3, s6, s3
	s_waitcnt lgkmcnt(0)
	v_fma_f32 v0, 0, v6, v8
	v_fmac_f32_e32 v9, v0, v7
	v_mul_f32_e32 v0, v6, v7
	ds_read2st64_b32 v[6:7], v3 offset0:2 offset1:3
	ds_read2st64_b32 v[10:11], v3 offset0:10 offset1:11
	s_waitcnt lgkmcnt(0)
	v_mul_f32_e32 v0, v0, v6
	v_fma_f32 v8, v9, v6, v10
	v_fmac_f32_e32 v11, v8, v7
	v_mul_f32_e32 v0, v0, v7
	ds_read2st64_b32 v[6:7], v3 offset0:4 offset1:5
	ds_read2st64_b32 v[8:9], v3 offset0:12 offset1:13
	s_waitcnt lgkmcnt(0)
	v_mul_f32_e32 v0, v0, v6
	v_fma_f32 v8, v11, v6, v8
	v_fmac_f32_e32 v9, v8, v7
	v_mul_f32_e32 v0, v0, v7
	ds_read2st64_b32 v[6:7], v3 offset0:6 offset1:7
	ds_read2st64_b32 v[10:11], v3 offset0:14 offset1:15
	s_waitcnt lgkmcnt(0)
	v_mul_f32_e32 v0, v0, v6
	v_fma_f32 v3, v9, v6, v10
	v_fmac_f32_e32 v11, v3, v7
	v_mul_f32_e32 v0, v0, v7
	v_or_b32_e32 v6, s2, v2
	v_mov_b32_e32 v7, s3
	v_lshl_add_u64 v[6:7], v[6:7], 2, s[0:1]
	v_add_co_u32_e32 v8, vcc, 0x9a00000, v6
	s_nop 1
	v_addc_co_u32_e32 v9, vcc, 0, v7, vcc
	v_add_co_u32_e32 v6, vcc, 0x9b00000, v6
	global_store_dword v[8:9], v0, off
	s_nop 0
	v_addc_co_u32_e32 v7, vcc, 0, v7, vcc
	global_store_dword v[6:7], v11, off
	s_branch .LBB0_562

.LBB0_662:
	v_lshl_add_u32 v183, s44, 8, v179
	v_lshl_or_b32 v0, v183, 6, v177
	v_lshl_add_u64 v[102:103], s[24:25], 0, v[0:1]
	global_load_dwordx4 v[184:187], v[102:103], off
	global_load_dwordx4 v[158:161], v[102:103], off offset:1024
	global_load_dwordx4 v[154:157], v[102:103], off offset:2048
	global_load_dwordx4 v[134:137], v[102:103], off offset:3072
	v_add_u32_e32 v102, 0x2000, v0
	v_mov_b32_e32 v103, v1
	v_lshl_add_u64 v[102:103], s[24:25], 0, v[102:103]
	global_load_dwordx4 v[114:117], v[102:103], off
	v_add_u32_e32 v102, 0x2400, v0
	v_mov_b32_e32 v103, v1
	v_lshl_add_u64 v[102:103], s[24:25], 0, v[102:103]
	global_load_dwordx4 v[110:113], v[102:103], off
	v_add_u32_e32 v102, 0x2800, v0
	v_mov_b32_e32 v103, v1
	v_lshl_add_u64 v[102:103], s[24:25], 0, v[102:103]
	v_add_u32_e32 v0, 0x2c00, v0
	global_load_dwordx4 v[106:109], v[102:103], off
	v_lshl_add_u64 v[102:103], s[24:25], 0, v[0:1]
	v_lshl_or_b32 v0, s42, 8, v181
	global_load_dwordx4 v[102:105], v[102:103], off
	s_andn2_b64 vcc, exec, s[4:5]
	s_waitcnt vmcnt(0) lgkmcnt(0)
	v_mov_b32_e32 v172, v185
	v_mov_b32_e32 v173, v186
	v_mov_b32_e32 v185, v187
	v_pk_add_f32 v[172:173], v[172:173], v[184:185]
	s_nop 0
	v_add_f32_e32 v172, v172, v173
	ds_bpermute_b32 v173, v174, v172
	s_waitcnt lgkmcnt(0)
	v_add_f32_e32 v172, v172, v173
	ds_bpermute_b32 v173, v175, v172
	s_waitcnt lgkmcnt(0)
	v_add_f32_e32 v172, v172, v173
	v_fmamk_f32 v172, v172, 0x3a800000, v219
	v_rsq_f32_e32 v184, v172
	v_mad_u64_u32 v[172:173], s[42:43], s22, v183, 0
	v_lshl_add_u64 v[186:187], v[172:173], 1, s[20:21]
	v_lshlrev_b64 v[172:173], 1, v[0:1]
	v_lshl_add_u64 v[186:187], v[186:187], 0, v[172:173]
	v_pk_mul_f32 v[152:153], v[152:153], v[184:185] op_sel_hi:[1,0]
	v_pk_mul_f32 v[150:151], v[150:151], v[184:185] op_sel_hi:[1,0]
	v_pk_mul_f32 v[188:189], v[148:149], v[184:185] op_sel_hi:[1,0]
	v_pk_mul_f32 v[148:149], v[146:147], v[184:185] op_sel_hi:[1,0]
	v_cvt_pk_bf16_f32 v146, v150, v151
	v_cvt_pk_bf16_f32 v147, v152, v153
	v_pk_mul_f32 v[144:145], v[144:145], v[184:185] op_sel_hi:[1,0]
	v_cvt_pk_bf16_f32 v148, v148, v149
	v_cvt_pk_bf16_f32 v149, v188, v189
	global_store_dwordx4 v[186:187], v[146:149], off
	v_pk_mul_f32 v[142:143], v[142:143], v[184:185] op_sel_hi:[1,0]
	s_nop 0
	v_pk_mul_f32 v[146:147], v[140:141], v[184:185] op_sel_hi:[1,0]
	v_pk_mul_f32 v[140:141], v[138:139], v[184:185] op_sel_hi:[1,0]
	v_cvt_pk_bf16_f32 v138, v142, v143
	v_cvt_pk_bf16_f32 v139, v144, v145
	s_nop 0
	v_cvt_pk_bf16_f32 v140, v140, v141
	v_cvt_pk_bf16_f32 v141, v146, v147
	global_store_dwordx4 v[186:187], v[138:141], off offset:256
	s_nop 1
	v_mov_b32_e32 v138, v159
	v_mov_b32_e32 v139, v160
	v_mov_b32_e32 v159, v161
	v_pk_add_f32 v[138:139], v[138:139], v[158:159]
	v_or_b32_e32 v140, 16, v183
	v_add_f32_e32 v0, v138, v139
	ds_bpermute_b32 v138, v174, v0
	s_waitcnt lgkmcnt(0)
	v_add_f32_e32 v0, v0, v138
	ds_bpermute_b32 v138, v175, v0
	s_waitcnt lgkmcnt(0)
	v_add_f32_e32 v0, v0, v138
	v_fmamk_f32 v0, v0, 0x3a800000, v219
	v_rsq_f32_e32 v0, v0
	v_mad_u64_u32 v[138:139], s[42:43], s22, v140, 0
	v_lshl_add_u64 v[138:139], v[138:139], 1, s[20:21]
	v_lshl_add_u64 v[138:139], v[138:139], 0, v[172:173]
	v_pk_mul_f32 v[132:133], v[132:133], v[0:1] op_sel_hi:[1,0]
	v_pk_mul_f32 v[130:131], v[130:131], v[0:1] op_sel_hi:[1,0]
	v_pk_mul_f32 v[140:141], v[128:129], v[0:1] op_sel_hi:[1,0]
	v_pk_mul_f32 v[128:129], v[126:127], v[0:1] op_sel_hi:[1,0]
	v_cvt_pk_bf16_f32 v126, v130, v131
	v_cvt_pk_bf16_f32 v127, v132, v133
	v_pk_mul_f32 v[124:125], v[124:125], v[0:1] op_sel_hi:[1,0]
	v_cvt_pk_bf16_f32 v128, v128, v129
	v_cvt_pk_bf16_f32 v129, v140, v141
	global_store_dwordx4 v[138:139], v[126:129], off
	v_pk_mul_f32 v[122:123], v[122:123], v[0:1] op_sel_hi:[1,0]
	s_nop 0
	v_pk_mul_f32 v[126:127], v[120:121], v[0:1] op_sel_hi:[1,0]
	v_pk_mul_f32 v[120:121], v[118:119], v[0:1] op_sel_hi:[1,0]
	v_cvt_pk_bf16_f32 v118, v122, v123
	v_cvt_pk_bf16_f32 v119, v124, v125
	s_nop 0
	v_cvt_pk_bf16_f32 v120, v120, v121
	v_cvt_pk_bf16_f32 v121, v126, v127
	global_store_dwordx4 v[138:139], v[118:121], off offset:256
	s_nop 1
	v_mov_b32_e32 v118, v155
	v_mov_b32_e32 v119, v156
	v_mov_b32_e32 v155, v157
	v_pk_add_f32 v[118:119], v[118:119], v[154:155]
	v_or_b32_e32 v120, 32, v183
	v_add_f32_e32 v0, v118, v119
	ds_bpermute_b32 v118, v174, v0
	s_waitcnt lgkmcnt(0)
	v_add_f32_e32 v0, v0, v118
	ds_bpermute_b32 v118, v175, v0
	s_waitcnt lgkmcnt(0)
	v_add_f32_e32 v0, v0, v118
	v_fmamk_f32 v0, v0, 0x3a800000, v219
	v_rsq_f32_e32 v0, v0
	v_mad_u64_u32 v[118:119], s[42:43], s22, v120, 0
	v_lshl_add_u64 v[118:119], v[118:119], 1, s[20:21]
	v_lshl_add_u64 v[118:119], v[118:119], 0, v[172:173]
	v_pk_mul_f32 v[100:101], v[100:101], v[0:1] op_sel_hi:[1,0]
	v_pk_mul_f32 v[98:99], v[98:99], v[0:1] op_sel_hi:[1,0]
	v_pk_mul_f32 v[120:121], v[96:97], v[0:1] op_sel_hi:[1,0]
	v_pk_mul_f32 v[96:97], v[94:95], v[0:1] op_sel_hi:[1,0]
	v_cvt_pk_bf16_f32 v94, v98, v99
	v_cvt_pk_bf16_f32 v95, v100, v101
	v_pk_mul_f32 v[92:93], v[92:93], v[0:1] op_sel_hi:[1,0]
	v_cvt_pk_bf16_f32 v96, v96, v97
	v_cvt_pk_bf16_f32 v97, v120, v121
	global_store_dwordx4 v[118:119], v[94:97], off
	v_pk_mul_f32 v[90:91], v[90:91], v[0:1] op_sel_hi:[1,0]
	s_nop 0
	v_pk_mul_f32 v[94:95], v[88:89], v[0:1] op_sel_hi:[1,0]
	v_pk_mul_f32 v[88:89], v[86:87], v[0:1] op_sel_hi:[1,0]
	v_cvt_pk_bf16_f32 v86, v90, v91
	v_cvt_pk_bf16_f32 v87, v92, v93
	s_nop 0
	v_cvt_pk_bf16_f32 v88, v88, v89
	v_cvt_pk_bf16_f32 v89, v94, v95
	global_store_dwordx4 v[118:119], v[86:89], off offset:256
	s_nop 1
	v_mov_b32_e32 v86, v135
	v_mov_b32_e32 v87, v136
	v_mov_b32_e32 v135, v137
	v_pk_add_f32 v[86:87], v[86:87], v[134:135]
	v_or_b32_e32 v88, 48, v183
	v_add_f32_e32 v0, v86, v87
	ds_bpermute_b32 v86, v174, v0
	s_waitcnt lgkmcnt(0)
	v_add_f32_e32 v0, v0, v86
	ds_bpermute_b32 v86, v175, v0
	s_waitcnt lgkmcnt(0)
	v_add_f32_e32 v0, v0, v86
	v_fmamk_f32 v0, v0, 0x3a800000, v219
	v_rsq_f32_e32 v0, v0
	v_mad_u64_u32 v[86:87], s[42:43], s22, v88, 0
	v_lshl_add_u64 v[86:87], v[86:87], 1, s[20:21]
	v_lshl_add_u64 v[86:87], v[86:87], 0, v[172:173]
	v_pk_mul_f32 v[84:85], v[84:85], v[0:1] op_sel_hi:[1,0]
	v_pk_mul_f32 v[82:83], v[82:83], v[0:1] op_sel_hi:[1,0]
	v_pk_mul_f32 v[88:89], v[80:81], v[0:1] op_sel_hi:[1,0]
	v_pk_mul_f32 v[80:81], v[78:79], v[0:1] op_sel_hi:[1,0]
	v_cvt_pk_bf16_f32 v78, v82, v83
	v_cvt_pk_bf16_f32 v79, v84, v85
	v_pk_mul_f32 v[76:77], v[76:77], v[0:1] op_sel_hi:[1,0]
	v_cvt_pk_bf16_f32 v80, v80, v81
	v_cvt_pk_bf16_f32 v81, v88, v89
	global_store_dwordx4 v[86:87], v[78:81], off
	v_pk_mul_f32 v[74:75], v[74:75], v[0:1] op_sel_hi:[1,0]
	s_nop 0
	v_pk_mul_f32 v[78:79], v[72:73], v[0:1] op_sel_hi:[1,0]
	v_pk_mul_f32 v[72:73], v[70:71], v[0:1] op_sel_hi:[1,0]
	v_cvt_pk_bf16_f32 v70, v74, v75
	v_cvt_pk_bf16_f32 v71, v76, v77
	s_nop 0
	v_cvt_pk_bf16_f32 v72, v72, v73
	v_cvt_pk_bf16_f32 v73, v78, v79
	global_store_dwordx4 v[86:87], v[70:73], off offset:256
	s_nop 1
	v_mov_b32_e32 v70, v115
	v_mov_b32_e32 v71, v116
	v_mov_b32_e32 v115, v117
	v_pk_add_f32 v[70:71], v[70:71], v[114:115]
	v_add_u32_e32 v72, 0x80, v183
	v_add_f32_e32 v0, v70, v71
	ds_bpermute_b32 v70, v174, v0
	s_waitcnt lgkmcnt(0)
	v_add_f32_e32 v0, v0, v70
	ds_bpermute_b32 v70, v175, v0
	s_waitcnt lgkmcnt(0)
	v_add_f32_e32 v0, v0, v70
	v_fmamk_f32 v0, v0, 0x3a800000, v219
	v_rsq_f32_e32 v0, v0
	v_mad_u64_u32 v[70:71], s[42:43], s22, v72, 0
	v_lshl_add_u64 v[70:71], v[70:71], 1, s[20:21]
	v_lshl_add_u64 v[70:71], v[70:71], 0, v[172:173]
	v_pk_mul_f32 v[68:69], v[68:69], v[0:1] op_sel_hi:[1,0]
	v_pk_mul_f32 v[66:67], v[66:67], v[0:1] op_sel_hi:[1,0]
	v_pk_mul_f32 v[72:73], v[64:65], v[0:1] op_sel_hi:[1,0]
	v_pk_mul_f32 v[64:65], v[62:63], v[0:1] op_sel_hi:[1,0]
	v_cvt_pk_bf16_f32 v62, v66, v67
	v_cvt_pk_bf16_f32 v63, v68, v69
	v_pk_mul_f32 v[60:61], v[60:61], v[0:1] op_sel_hi:[1,0]
	v_cvt_pk_bf16_f32 v64, v64, v65
	v_cvt_pk_bf16_f32 v65, v72, v73
	global_store_dwordx4 v[70:71], v[62:65], off
	v_pk_mul_f32 v[58:59], v[58:59], v[0:1] op_sel_hi:[1,0]
	s_nop 0
	v_pk_mul_f32 v[62:63], v[56:57], v[0:1] op_sel_hi:[1,0]
	v_pk_mul_f32 v[56:57], v[54:55], v[0:1] op_sel_hi:[1,0]
	v_cvt_pk_bf16_f32 v54, v58, v59
	v_cvt_pk_bf16_f32 v55, v60, v61
	s_nop 0
	v_cvt_pk_bf16_f32 v56, v56, v57
	v_cvt_pk_bf16_f32 v57, v62, v63
	global_store_dwordx4 v[70:71], v[54:57], off offset:256
	s_nop 1
	v_mov_b32_e32 v54, v111
	v_mov_b32_e32 v55, v112
	v_mov_b32_e32 v111, v113
	v_pk_add_f32 v[54:55], v[54:55], v[110:111]
	v_add_u32_e32 v56, 0x90, v183
	v_add_f32_e32 v0, v54, v55
	ds_bpermute_b32 v54, v174, v0
	s_waitcnt lgkmcnt(0)
	v_add_f32_e32 v0, v0, v54
	ds_bpermute_b32 v54, v175, v0
	s_waitcnt lgkmcnt(0)
	v_add_f32_e32 v0, v0, v54
	v_fmamk_f32 v0, v0, 0x3a800000, v219
	v_rsq_f32_e32 v0, v0
	v_mad_u64_u32 v[54:55], s[42:43], s22, v56, 0
	v_lshl_add_u64 v[54:55], v[54:55], 1, s[20:21]
	v_lshl_add_u64 v[54:55], v[54:55], 0, v[172:173]
	v_pk_mul_f32 v[52:53], v[52:53], v[0:1] op_sel_hi:[1,0]
	v_pk_mul_f32 v[50:51], v[50:51], v[0:1] op_sel_hi:[1,0]
	v_pk_mul_f32 v[56:57], v[48:49], v[0:1] op_sel_hi:[1,0]
	v_pk_mul_f32 v[48:49], v[46:47], v[0:1] op_sel_hi:[1,0]
	v_cvt_pk_bf16_f32 v46, v50, v51
	v_cvt_pk_bf16_f32 v47, v52, v53
	v_pk_mul_f32 v[44:45], v[44:45], v[0:1] op_sel_hi:[1,0]
	v_cvt_pk_bf16_f32 v48, v48, v49
	v_cvt_pk_bf16_f32 v49, v56, v57
	global_store_dwordx4 v[54:55], v[46:49], off
	v_pk_mul_f32 v[42:43], v[42:43], v[0:1] op_sel_hi:[1,0]
	s_nop 0
	v_pk_mul_f32 v[46:47], v[40:41], v[0:1] op_sel_hi:[1,0]
	v_pk_mul_f32 v[40:41], v[38:39], v[0:1] op_sel_hi:[1,0]
	v_cvt_pk_bf16_f32 v38, v42, v43
	v_cvt_pk_bf16_f32 v39, v44, v45
	s_nop 0
	v_cvt_pk_bf16_f32 v40, v40, v41
	v_cvt_pk_bf16_f32 v41, v46, v47
	global_store_dwordx4 v[54:55], v[38:41], off offset:256
	s_nop 1
	v_mov_b32_e32 v38, v107
	v_mov_b32_e32 v39, v108
	v_mov_b32_e32 v107, v109
	v_pk_add_f32 v[38:39], v[38:39], v[106:107]
	v_add_u32_e32 v40, 0xa0, v183
	v_add_f32_e32 v0, v38, v39
	ds_bpermute_b32 v38, v174, v0
	s_waitcnt lgkmcnt(0)
	v_add_f32_e32 v0, v0, v38
	ds_bpermute_b32 v38, v175, v0
	s_waitcnt lgkmcnt(0)
	v_add_f32_e32 v0, v0, v38
	v_fmamk_f32 v0, v0, 0x3a800000, v219
	v_rsq_f32_e32 v0, v0
	v_mad_u64_u32 v[38:39], s[42:43], s22, v40, 0
	v_lshl_add_u64 v[38:39], v[38:39], 1, s[20:21]
	v_lshl_add_u64 v[38:39], v[38:39], 0, v[172:173]
	v_pk_mul_f32 v[36:37], v[36:37], v[0:1] op_sel_hi:[1,0]
	v_pk_mul_f32 v[34:35], v[34:35], v[0:1] op_sel_hi:[1,0]
	v_pk_mul_f32 v[40:41], v[32:33], v[0:1] op_sel_hi:[1,0]
	v_pk_mul_f32 v[32:33], v[30:31], v[0:1] op_sel_hi:[1,0]
	v_cvt_pk_bf16_f32 v30, v34, v35
	v_cvt_pk_bf16_f32 v31, v36, v37
	v_pk_mul_f32 v[28:29], v[28:29], v[0:1] op_sel_hi:[1,0]
	v_cvt_pk_bf16_f32 v32, v32, v33
	v_cvt_pk_bf16_f32 v33, v40, v41
	global_store_dwordx4 v[38:39], v[30:33], off
	v_pk_mul_f32 v[26:27], v[26:27], v[0:1] op_sel_hi:[1,0]
	s_nop 0
	v_pk_mul_f32 v[30:31], v[24:25], v[0:1] op_sel_hi:[1,0]
	v_pk_mul_f32 v[24:25], v[22:23], v[0:1] op_sel_hi:[1,0]
	v_cvt_pk_bf16_f32 v22, v26, v27
	v_cvt_pk_bf16_f32 v23, v28, v29
	s_nop 0
	v_cvt_pk_bf16_f32 v24, v24, v25
	v_cvt_pk_bf16_f32 v25, v30, v31
	global_store_dwordx4 v[38:39], v[22:25], off offset:256
	s_nop 1
	v_mov_b32_e32 v22, v103
	v_mov_b32_e32 v23, v104
	v_mov_b32_e32 v103, v105
	v_pk_add_f32 v[22:23], v[22:23], v[102:103]
	v_add_u32_e32 v24, 0xb0, v183
	v_add_f32_e32 v0, v22, v23
	ds_bpermute_b32 v22, v174, v0
	s_waitcnt lgkmcnt(0)
	v_add_f32_e32 v0, v0, v22
	ds_bpermute_b32 v22, v175, v0
	s_waitcnt lgkmcnt(0)
	v_add_f32_e32 v0, v0, v22
	v_fmamk_f32 v0, v0, 0x3a800000, v219
	v_rsq_f32_e32 v0, v0
	v_mad_u64_u32 v[22:23], s[42:43], s22, v24, 0
	v_lshl_add_u64 v[22:23], v[22:23], 1, s[20:21]
	v_lshl_add_u64 v[22:23], v[22:23], 0, v[172:173]
	v_pk_mul_f32 v[20:21], v[20:21], v[0:1] op_sel_hi:[1,0]
	v_pk_mul_f32 v[18:19], v[18:19], v[0:1] op_sel_hi:[1,0]
	v_pk_mul_f32 v[24:25], v[16:17], v[0:1] op_sel_hi:[1,0]
	v_pk_mul_f32 v[16:17], v[14:15], v[0:1] op_sel_hi:[1,0]
	v_cvt_pk_bf16_f32 v14, v18, v19
	v_cvt_pk_bf16_f32 v15, v20, v21
	s_mov_b64 s[42:43], -1
	v_cvt_pk_bf16_f32 v16, v16, v17
	v_cvt_pk_bf16_f32 v17, v24, v25
	global_store_dwordx4 v[22:23], v[14:17], off
	v_pk_mul_f32 v[12:13], v[12:13], v[0:1] op_sel_hi:[1,0]
	v_pk_mul_f32 v[10:11], v[10:11], v[0:1] op_sel_hi:[1,0]
	v_pk_mul_f32 v[14:15], v[8:9], v[0:1] op_sel_hi:[1,0]
	v_pk_mul_f32 v[8:9], v[6:7], v[0:1] op_sel_hi:[1,0]
	v_cvt_pk_bf16_f32 v6, v10, v11
	v_cvt_pk_bf16_f32 v7, v12, v13
	s_nop 0
	v_cvt_pk_bf16_f32 v8, v8, v9
	v_cvt_pk_bf16_f32 v9, v14, v15
	global_store_dwordx4 v[22:23], v[6:9], off offset:256
	s_cbranch_vccnz .LBB0_655
	s_andn2_b64 vcc, exec, s[28:29]
	s_cbranch_vccnz .LBB0_654
	s_barrier
	s_branch .LBB0_654

.LBB0_673:
	s_and_b32 s6, s14, 0xffffffe0
	v_or_b32_e32 v6, s6, v5
	v_ashrrev_i32_e32 v7, 31, v6
	s_and_b32 s4, s12, 0x70
	v_lshlrev_b64 v[6:7], 11, v[6:7]
	v_or_b32_e32 v19, s4, v5
	v_lshl_add_u64 v[40:41], v[14:15], 0, v[6:7]
	s_mov_b32 s4, 0x8000
	v_lshlrev_b32_e32 v0, 11, v19
	v_add_co_u32_e32 v42, vcc, s4, v40
	v_lshl_add_u64 v[38:39], v[2:3], 0, v[0:1]
	s_nop 0
	v_addc_co_u32_e32 v43, vcc, 0, v41, vcc
	global_load_dwordx4 v[6:9], v[38:39], off
	global_load_dwordx4 v[10:13], v[40:41], off
	s_waitcnt lgkmcnt(0)
	global_load_dwordx4 v[22:25], v[42:43], off
	global_load_dwordx4 v[26:29], v[40:41], off offset:64
	global_load_dwordx4 v[30:33], v[38:39], off offset:64
	v_add_u32_e32 v0, s11, v21
	s_andn2_b64 vcc, exec, s[2:3]
	s_waitcnt vmcnt(0)
	v_mfma_f32_16x16x32_bf16 v[10:13], v[10:13], v[6:9], 0
	s_waitcnt lgkmcnt(0)
	v_mfma_f32_16x16x32_bf16 v[6:9], v[22:25], v[6:9], 0
	global_load_dwordx4 v[22:25], v[42:43], off offset:64
	v_mfma_f32_16x16x32_bf16 v[10:13], v[26:29], v[30:33], v[10:13]
	global_load_dwordx4 v[26:29], v[40:41], off offset:128
	global_load_dwordx4 v[34:37], v[38:39], off offset:128
	s_waitcnt vmcnt(0) lgkmcnt(0)
	v_mfma_f32_16x16x32_bf16 v[10:13], v[26:29], v[34:37], v[10:13]
	v_mfma_f32_16x16x32_bf16 v[6:9], v[22:25], v[30:33], v[6:9]
	global_load_dwordx4 v[22:25], v[42:43], off offset:128
	global_load_dwordx4 v[26:29], v[40:41], off offset:192
	global_load_dwordx4 v[30:33], v[42:43], off offset:192
	s_waitcnt vmcnt(0) lgkmcnt(0)
	v_mfma_f32_16x16x32_bf16 v[22:25], v[22:25], v[34:37], v[6:9]
	global_load_dwordx4 v[34:37], v[38:39], off offset:192
	s_waitcnt vmcnt(0) lgkmcnt(0)
	v_mfma_f32_16x16x32_bf16 v[6:9], v[26:29], v[34:37], v[10:13]
	v_mfma_f32_16x16x32_bf16 v[10:13], v[30:33], v[34:37], v[22:25]
	s_nop 6
	ds_write_b128 v0, v[6:9]
	ds_write_b128 v0, v[10:13] offset:1024
	s_waitcnt lgkmcnt(0)
	s_barrier
	s_cbranch_vccnz .LBB0_672
	ds_read_b128 v[22:25], v21 offset:2048
	v_lshlrev_b32_e32 v0, 7, v19
	s_ashr_i32 s7, s6, 31
	s_waitcnt lgkmcnt(0)
	v_pk_add_f32 v[24:25], v[8:9], v[24:25]
	v_pk_add_f32 v[22:23], v[6:7], v[22:23]
	ds_read_b128 v[6:9], v21 offset:3072
	s_waitcnt lgkmcnt(0)
	v_pk_add_f32 v[12:13], v[12:13], v[8:9]
	v_pk_add_f32 v[10:11], v[10:11], v[6:7]
	ds_read_b128 v[6:9], v21 offset:4096
	s_waitcnt lgkmcnt(0)
	v_pk_add_f32 v[24:25], v[24:25], v[8:9]
	v_pk_add_f32 v[22:23], v[22:23], v[6:7]
	ds_read_b128 v[6:9], v21 offset:5120
	s_waitcnt lgkmcnt(0)
	v_pk_add_f32 v[12:13], v[12:13], v[8:9]
	v_pk_add_f32 v[10:11], v[10:11], v[6:7]
	ds_read_b128 v[6:9], v21 offset:6144
	s_waitcnt lgkmcnt(0)
	v_pk_add_f32 v[24:25], v[24:25], v[8:9]
	v_pk_add_f32 v[22:23], v[22:23], v[6:7]
	ds_read_b128 v[6:9], v21 offset:7168
	s_waitcnt lgkmcnt(0)
	v_pk_add_f32 v[12:13], v[12:13], v[8:9]
	v_pk_add_f32 v[10:11], v[10:11], v[6:7]
	ds_read_b128 v[6:9], v21 offset:8192
	s_waitcnt lgkmcnt(0)
	v_pk_add_f32 v[24:25], v[24:25], v[8:9]
	v_pk_add_f32 v[22:23], v[22:23], v[6:7]
	ds_read_b128 v[6:9], v21 offset:9216
	s_waitcnt lgkmcnt(0)
	v_pk_add_f32 v[12:13], v[12:13], v[8:9]
	v_pk_add_f32 v[10:11], v[10:11], v[6:7]
	ds_read_b128 v[6:9], v21 offset:10240
	s_waitcnt lgkmcnt(0)
	v_pk_add_f32 v[24:25], v[24:25], v[8:9]
	v_pk_add_f32 v[22:23], v[22:23], v[6:7]
	ds_read_b128 v[6:9], v21 offset:11264
	s_waitcnt lgkmcnt(0)
	v_pk_add_f32 v[12:13], v[12:13], v[8:9]
	v_pk_add_f32 v[10:11], v[10:11], v[6:7]
	ds_read_b128 v[6:9], v21 offset:12288
	s_waitcnt lgkmcnt(0)
	v_pk_add_f32 v[24:25], v[24:25], v[8:9]
	v_pk_add_f32 v[22:23], v[22:23], v[6:7]
	ds_read_b128 v[6:9], v21 offset:13312
	s_waitcnt lgkmcnt(0)
	v_pk_add_f32 v[12:13], v[12:13], v[8:9]
	v_pk_add_f32 v[26:27], v[10:11], v[6:7]
	ds_read_b128 v[6:9], v21 offset:14336
	s_waitcnt lgkmcnt(0)
	v_pk_add_f32 v[28:29], v[24:25], v[8:9]
	v_pk_add_f32 v[30:31], v[22:23], v[6:7]
	ds_read_b128 v[6:9], v21 offset:15360
	v_lshl_add_u64 v[22:23], v[16:17], 0, v[0:1]
	s_waitcnt lgkmcnt(0)
	v_pk_add_f32 v[10:11], v[12:13], v[8:9]
	v_pk_add_f32 v[12:13], v[26:27], v[6:7]
	global_load_dwordx4 v[6:9], v[22:23], off
	s_nop 0
	global_load_dwordx4 v[22:25], v[22:23], off offset:16
	s_waitcnt vmcnt(0) lgkmcnt(0)
	v_mov_b32_e32 v26, v6
	v_mov_b32_e32 v27, v22
	v_mov_b32_e32 v22, v7
	v_pk_add_f32 v[6:7], v[26:27], v[22:23]
	v_mov_b32_e32 v22, v8
	v_mov_b32_e32 v23, v24
	v_mov_b32_e32 v24, v9
	v_pk_add_f32 v[8:9], v[22:23], v[24:25]
	s_nop 0
	v_pk_add_f32 v[6:7], v[6:7], v[8:9]
	s_nop 0
	v_add_f32_e32 v0, v6, v7
	ds_bpermute_b32 v6, v174, v0
	s_waitcnt lgkmcnt(0)
	v_add_f32_e32 v0, v0, v6
	ds_bpermute_b32 v6, v175, v0
	s_waitcnt lgkmcnt(0)
	v_add_f32_e32 v0, v0, v6
	v_fmamk_f32 v0, v0, 0x3a800000, v219
	v_cmp_gt_f32_e32 vcc, s85, v0
	v_mul_f32_e32 v6, 0x4f800000, v0
	s_nop 0
	v_cndmask_b32_e32 v0, v0, v6, vcc
	v_sqrt_f32_e32 v6, v0
	s_nop 0
	v_add_u32_e32 v7, -1, v6
	v_fma_f32 v8, -v7, v6, v0
	v_cmp_ge_f32_e64 s[4:5], 0, v8
	v_add_u32_e32 v8, 1, v6
	s_nop 0
	v_cndmask_b32_e64 v7, v6, v7, s[4:5]
	v_fma_f32 v6, -v8, v6, v0
	v_cmp_lt_f32_e64 s[4:5], 0, v6
	s_nop 1
	v_cndmask_b32_e64 v6, v7, v8, s[4:5]
	v_mul_f32_e32 v7, 0x37800000, v6
	v_cndmask_b32_e32 v6, v6, v7, vcc
	v_cmp_class_f32_e32 vcc, v0, v221
	s_nop 1
	v_cndmask_b32_e32 v0, v6, v0, vcc
	v_div_scale_f32 v6, s[4:5], v0, v0, 1.0
	v_rcp_f32_e32 v7, v6
	s_nop 0
	v_fma_f32 v8, -v6, v7, 1.0
	v_fmac_f32_e32 v7, v8, v7
	v_div_scale_f32 v8, vcc, 1.0, v0, 1.0
	v_mul_f32_e32 v9, v8, v7
	v_fma_f32 v20, -v6, v9, v8
	v_fmac_f32_e32 v9, v20, v7
	v_fma_f32 v6, -v6, v9, v8
	v_div_fmas_f32 v6, v6, v7, v9
	v_div_fixup_f32 v20, v6, v0, 1.0
	v_mul_u32_u24_e32 v0, 0x700, v19
	v_lshlrev_b32_e32 v0, 2, v0
	v_lshl_add_u64 v[22:23], s[0:1], 0, v[0:1]
	v_lshl_add_u64 v[22:23], s[6:7], 2, v[22:23]
	v_mov_b32_e32 v19, v1
	v_pk_mul_f32 v[8:9], v[28:29], v[20:21] op_sel_hi:[1,0]
	v_pk_mul_f32 v[6:7], v[30:31], v[20:21] op_sel_hi:[1,0]
	v_lshl_add_u64 v[22:23], v[22:23], 0, v[18:19]
	global_store_dwordx4 v[22:23], v[6:9], off
	s_nop 1
	v_pk_mul_f32 v[8:9], v[10:11], v[20:21] op_sel_hi:[1,0]
	v_pk_mul_f32 v[6:7], v[12:13], v[20:21] op_sel_hi:[1,0]
	global_store_dwordx4 v[22:23], v[6:9], off offset:64
	s_branch .LBB0_672
